# dead DPP zero-inits removed in all GEMM and attention epilogues (wait states re-derived); on top of conv+gelu epilogue trim, pipelined prep/final-norm loops, NA score-modifier rewrite
# baseline (speedup 1.0000x reference)
; __device__ __forceinline__ unsigned cvt_pk_bf16(float lo, float hi) { unsigned r; asm volatile("v_cvt_pk_bf16_f32 %0, %1, %2" : "=v"(r) : "v"(lo), "v"(hi)); return r; }
; __device__ __forceinline__ unsigned dpp_xor1(unsigned v) { return (unsigned)__builtin_amdgcn_update_dpp(0, (int)v, 0xB1, 0xf, 0xf, false); }
; __device__ __forceinline__ float dpp_xor1(float v) { return __int_as_float(__builtin_amdgcn_update_dpp(0, __float_as_int(v), 0xB1, 0xf, 0xf, false)); }
; __device__ __forceinline__ void store_pair_rows(bf16_t* O, size_t ldc, int row, int col0, int fr, u32x4 p0, u32x4 p1) {
;     const bool odd = (fr & 1) != 0;
;     const u32x4 snd = odd ? p0 : p1; u32x4 rcv;
;     rcv.x = dpp_xor1(snd.x); rcv.y = dpp_xor1(snd.y); rcv.z = dpp_xor1(snd.z); rcv.w = dpp_xor1(snd.w);
;     bf16_t* pa = O + (size_t)(row - (odd ? 1 : 0)) * ldc + col0 + (odd ? 8 : 0);
;     *(u32x4*)pa = odd ? rcv : p0;
;     *(u32x4*)(pa + ldc) = odd ? p1 : rcv;
; }
;     __device__ __forceinline__ void operator()(const f32x4 (&acc)[2][2][4][2], const Unit& u, int wr, int wc, int fr, int fq) const {
;     ...
;         const int lr0 = wr * 64 + fr, row0 = u.pm * BM + lr0, col0 = u.pn * BM + wc * 64 + 16 * fq;
; #pragma unroll
;         for (int ai = 0; ai < 2; ++ai)
; #pragma unroll
;             for (int m = 0; m < 4; ++m) {
;                 const int row = row0 + ai * HALF + m * 16;
;                 float rs = 1.0f; if constexpr (SCALE) rs = RS[lr0 + ai * HALF + m * 16];
;                 u32x4 pw[2];
; #pragma unroll
;                 for (int bj = 0; bj < 2; ++bj) { const f32x4 v0 = acc[ai][bj][m][0] * rs, v1 = acc[ai][bj][m][1] * rs;
;                     pw[bj].x = cvt_pk_bf16(v0[0], v0[1]); pw[bj].y = cvt_pk_bf16(v0[2], v0[3]); pw[bj].z = cvt_pk_bf16(v1[0], v1[1]); pw[bj].w = cvt_pk_bf16(v1[2], v1[3]); }
;                 store_pair_rows(O, (size_t)ldc, row, col0, fr, pw[0], pw[1]);
;             }
.LBB0_150:
	v_readlane_b32 s26, v254, 15
	v_lshl_or_b32 v156, s45, 8, v152
	v_cvt_pk_bf16_f32 v124, v124, v125
	v_cvt_pk_bf16_f32 v125, v126, v127
	v_cvt_pk_bf16_f32 v126, v120, v121
	v_cvt_pk_bf16_f32 v122, v122, v123
	v_cvt_pk_bf16_f32 v123, v116, v117
	v_cvt_pk_bf16_f32 v127, v118, v119
	v_cvt_pk_bf16_f32 v159, v112, v113
	v_cvt_pk_bf16_f32 v160, v114, v115
	v_cndmask_b32_e64 v112, v122, v160, s[0:1]
	v_cndmask_b32_e64 v113, v126, v159, s[0:1]
	v_readlane_b32 s27, v254, 16
	v_lshl_add_u32 v158, s24, 8, v151
	v_ashrrev_i32_e32 v157, 31, v156
	v_cndmask_b32_e64 v114, v125, v127, s[0:1]
	v_cndmask_b32_e64 v115, v124, v123, s[0:1]
	v_mov_b32_dpp v163, v113 quad_perm:[1,0,3,2] row_mask:0xf bank_mask:0xf
	v_mov_b32_dpp v164, v112 quad_perm:[1,0,3,2] row_mask:0xf bank_mask:0xf
	v_mov_b64_e32 v[112:113], s[26:27]
	v_mov_b32_dpp v161, v115 quad_perm:[1,0,3,2] row_mask:0xf bank_mask:0xf
	v_mov_b32_dpp v162, v114 quad_perm:[1,0,3,2] row_mask:0xf bank_mask:0xf
	v_mad_i64_i32 v[116:117], s[26:27], v158, s44, v[112:113]
	v_lshlrev_b64 v[114:115], 1, v[156:157]
	v_lshl_add_u64 v[116:117], v[116:117], 0, v[114:115]
	v_lshl_add_u64 v[120:121], v[116:117], 0, v[140:141]
	v_cndmask_b32_e64 v116, v161, v124, s[0:1]
	v_cndmask_b32_e64 v117, v162, v125, s[0:1]
	v_cndmask_b32_e64 v118, v163, v126, s[0:1]
	v_cndmask_b32_e64 v119, v164, v122, s[0:1]
	global_store_dwordx4 v[120:121], v[116:119], off
	v_add_co_u32_e32 v120, vcc, s38, v120
	s_nop 0
	v_cndmask_b32_e64 v116, v123, v161, s[0:1]
	v_cndmask_b32_e64 v117, v127, v162, s[0:1]
	v_cndmask_b32_e64 v118, v159, v163, s[0:1]
	v_cndmask_b32_e64 v119, v160, v164, s[0:1]
	v_addc_co_u32_e32 v121, vcc, 0, v121, vcc
	global_store_dwordx4 v[120:121], v[116:119], off offset:128
	v_cvt_pk_bf16_f32 v108, v108, v109
	v_cvt_pk_bf16_f32 v109, v110, v111
	v_cvt_pk_bf16_f32 v104, v104, v105
	v_cvt_pk_bf16_f32 v105, v106, v107
	v_cvt_pk_bf16_f32 v106, v100, v101
	v_cvt_pk_bf16_f32 v102, v102, v103
	v_cvt_pk_bf16_f32 v103, v96, v97
	v_cvt_pk_bf16_f32 v107, v98, v99
	s_nop 1
	v_cndmask_b32_e64 v96, v105, v107, s[0:1]
	v_cndmask_b32_e64 v97, v104, v103, s[0:1]
	s_nop 1
	v_mov_b32_dpp v117, v96 quad_perm:[1,0,3,2] row_mask:0xf bank_mask:0xf
	v_or_b32_e32 v96, 16, v158
	v_cndmask_b32_e64 v98, v109, v102, s[0:1]
	v_cndmask_b32_e64 v99, v108, v106, s[0:1]
	v_mov_b32_dpp v116, v97 quad_perm:[1,0,3,2] row_mask:0xf bank_mask:0xf
	v_mad_i64_i32 v[96:97], s[26:27], v96, s44, v[112:113]
	v_mov_b32_dpp v110, v99 quad_perm:[1,0,3,2] row_mask:0xf bank_mask:0xf
	v_mov_b32_dpp v111, v98 quad_perm:[1,0,3,2] row_mask:0xf bank_mask:0xf
	v_lshl_add_u64 v[96:97], v[96:97], 0, v[114:115]
	v_lshl_add_u64 v[100:101], v[96:97], 0, v[140:141]
	v_cndmask_b32_e64 v96, v110, v108, s[0:1]
	v_cndmask_b32_e64 v97, v111, v109, s[0:1]
	v_cndmask_b32_e64 v98, v116, v104, s[0:1]
	v_cndmask_b32_e64 v99, v117, v105, s[0:1]
	global_store_dwordx4 v[100:101], v[96:99], off
	v_add_co_u32_e32 v100, vcc, s38, v100
	s_nop 0
	v_cndmask_b32_e64 v96, v106, v110, s[0:1]
	v_cndmask_b32_e64 v97, v102, v111, s[0:1]
	v_cndmask_b32_e64 v98, v103, v116, s[0:1]
	v_cndmask_b32_e64 v99, v107, v117, s[0:1]
	v_addc_co_u32_e32 v101, vcc, 0, v101, vcc
	global_store_dwordx4 v[100:101], v[96:99], off offset:128
	v_cvt_pk_bf16_f32 v92, v92, v93
	v_cvt_pk_bf16_f32 v93, v94, v95
	v_cvt_pk_bf16_f32 v88, v88, v89
	v_cvt_pk_bf16_f32 v89, v90, v91
	v_cvt_pk_bf16_f32 v90, v84, v85
	v_cvt_pk_bf16_f32 v86, v86, v87
	v_cvt_pk_bf16_f32 v87, v80, v81
	v_cvt_pk_bf16_f32 v91, v82, v83
	s_nop 1
	v_cndmask_b32_e64 v80, v89, v91, s[0:1]
	v_cndmask_b32_e64 v81, v88, v87, s[0:1]
	s_nop 1
	v_mov_b32_dpp v97, v80 quad_perm:[1,0,3,2] row_mask:0xf bank_mask:0xf
	v_or_b32_e32 v80, 32, v158
	v_cndmask_b32_e64 v82, v93, v86, s[0:1]
	v_cndmask_b32_e64 v83, v92, v90, s[0:1]
	v_mov_b32_dpp v96, v81 quad_perm:[1,0,3,2] row_mask:0xf bank_mask:0xf
	v_mad_i64_i32 v[80:81], s[26:27], v80, s44, v[112:113]
	v_mov_b32_dpp v94, v83 quad_perm:[1,0,3,2] row_mask:0xf bank_mask:0xf
	v_mov_b32_dpp v95, v82 quad_perm:[1,0,3,2] row_mask:0xf bank_mask:0xf
	v_lshl_add_u64 v[80:81], v[80:81], 0, v[114:115]
	v_lshl_add_u64 v[84:85], v[80:81], 0, v[140:141]
	v_cndmask_b32_e64 v80, v94, v92, s[0:1]
	v_cndmask_b32_e64 v81, v95, v93, s[0:1]
	v_cndmask_b32_e64 v82, v96, v88, s[0:1]
	v_cndmask_b32_e64 v83, v97, v89, s[0:1]
	global_store_dwordx4 v[84:85], v[80:83], off
	v_add_co_u32_e32 v84, vcc, s38, v84
	s_nop 0
	v_cndmask_b32_e64 v80, v90, v94, s[0:1]
	v_cndmask_b32_e64 v81, v86, v95, s[0:1]
	v_cndmask_b32_e64 v82, v87, v96, s[0:1]
	v_cndmask_b32_e64 v83, v91, v97, s[0:1]
	v_addc_co_u32_e32 v85, vcc, 0, v85, vcc
	global_store_dwordx4 v[84:85], v[80:83], off offset:128
	v_cvt_pk_bf16_f32 v76, v76, v77
	v_cvt_pk_bf16_f32 v77, v78, v79
	v_cvt_pk_bf16_f32 v72, v72, v73
	v_cvt_pk_bf16_f32 v73, v74, v75
	v_cvt_pk_bf16_f32 v74, v68, v69
	v_cvt_pk_bf16_f32 v70, v70, v71
	v_cvt_pk_bf16_f32 v71, v64, v65
	v_cvt_pk_bf16_f32 v75, v66, v67
	s_nop 1
	v_cndmask_b32_e64 v64, v73, v75, s[0:1]
	v_cndmask_b32_e64 v65, v72, v71, s[0:1]
	s_nop 1
	v_mov_b32_dpp v81, v64 quad_perm:[1,0,3,2] row_mask:0xf bank_mask:0xf
	v_or_b32_e32 v64, 48, v158
	v_cndmask_b32_e64 v66, v77, v70, s[0:1]
	v_cndmask_b32_e64 v67, v76, v74, s[0:1]
	v_mov_b32_dpp v80, v65 quad_perm:[1,0,3,2] row_mask:0xf bank_mask:0xf
	v_mad_i64_i32 v[64:65], s[26:27], v64, s44, v[112:113]
	v_mov_b32_dpp v78, v67 quad_perm:[1,0,3,2] row_mask:0xf bank_mask:0xf
	v_mov_b32_dpp v79, v66 quad_perm:[1,0,3,2] row_mask:0xf bank_mask:0xf
	v_lshl_add_u64 v[64:65], v[64:65], 0, v[114:115]
	v_lshl_add_u64 v[68:69], v[64:65], 0, v[140:141]
	v_cndmask_b32_e64 v64, v78, v76, s[0:1]
	v_cndmask_b32_e64 v65, v79, v77, s[0:1]
; __device__ __forceinline__ unsigned cvt_pk_bf16(float lo, float hi) { unsigned r; asm volatile("v_cvt_pk_bf16_f32 %0, %1, %2" : "=v"(r) : "v"(lo), "v"(hi)); return r; }
; __device__ __forceinline__ unsigned dpp_xor1(unsigned v) { return (unsigned)__builtin_amdgcn_update_dpp(0, (int)v, 0xB1, 0xf, 0xf, false); }
; __device__ __forceinline__ float dpp_xor1(float v) { return __int_as_float(__builtin_amdgcn_update_dpp(0, __float_as_int(v), 0xB1, 0xf, 0xf, false)); }
; __device__ __forceinline__ void store_pair_rows(bf16_t* O, size_t ldc, int row, int col0, int fr, u32x4 p0, u32x4 p1) {
;     const bool odd = (fr & 1) != 0;
;     const u32x4 snd = odd ? p0 : p1; u32x4 rcv;
;     rcv.x = dpp_xor1(snd.x); rcv.y = dpp_xor1(snd.y); rcv.z = dpp_xor1(snd.z); rcv.w = dpp_xor1(snd.w);
;     bf16_t* pa = O + (size_t)(row - (odd ? 1 : 0)) * ldc + col0 + (odd ? 8 : 0);
;     *(u32x4*)pa = odd ? rcv : p0;
;     *(u32x4*)(pa + ldc) = odd ? p1 : rcv;
; }
;     __device__ __forceinline__ void operator()(const f32x4 (&acc)[2][2][4][2], const Unit& u, int wr, int wc, int fr, int fq) const {
;     ...
;         const int lr0 = wr * 64 + fr, row0 = u.pm * BM + lr0, col0 = u.pn * BM + wc * 64 + 16 * fq;
; #pragma unroll
;         for (int ai = 0; ai < 2; ++ai)
; #pragma unroll
;             for (int m = 0; m < 4; ++m) {
;                 const int row = row0 + ai * HALF + m * 16;
;                 float rs = 1.0f; if constexpr (SCALE) rs = RS[lr0 + ai * HALF + m * 16];
;                 u32x4 pw[2];
; #pragma unroll
;                 for (int bj = 0; bj < 2; ++bj) { const f32x4 v0 = acc[ai][bj][m][0] * rs, v1 = acc[ai][bj][m][1] * rs;
;                     pw[bj].x = cvt_pk_bf16(v0[0], v0[1]); pw[bj].y = cvt_pk_bf16(v0[2], v0[3]); pw[bj].z = cvt_pk_bf16(v1[0], v1[1]); pw[bj].w = cvt_pk_bf16(v1[2], v1[3]); }
;                 store_pair_rows(O, (size_t)ldc, row, col0, fr, pw[0], pw[1]);
;             }
	v_cndmask_b32_e64 v66, v80, v72, s[0:1]
	v_cndmask_b32_e64 v67, v81, v73, s[0:1]
	global_store_dwordx4 v[68:69], v[64:67], off
	v_add_co_u32_e32 v68, vcc, s38, v68
	s_nop 0
	v_cndmask_b32_e64 v64, v74, v78, s[0:1]
	v_cndmask_b32_e64 v65, v70, v79, s[0:1]
	v_cndmask_b32_e64 v66, v71, v80, s[0:1]
	v_cndmask_b32_e64 v67, v75, v81, s[0:1]
	v_addc_co_u32_e32 v69, vcc, 0, v69, vcc
	global_store_dwordx4 v[68:69], v[64:67], off offset:128
	v_cvt_pk_bf16_f32 v60, v60, v61
	v_cvt_pk_bf16_f32 v61, v62, v63
	v_cvt_pk_bf16_f32 v56, v56, v57
	v_cvt_pk_bf16_f32 v57, v58, v59
	v_cvt_pk_bf16_f32 v58, v52, v53
	s_nop 1
	v_add_u32_e32 v64, 0x80, v158
	v_cvt_pk_bf16_f32 v54, v54, v55
	v_cvt_pk_bf16_f32 v55, v48, v49
	v_cvt_pk_bf16_f32 v59, v50, v51
	v_cndmask_b32_e64 v48, v57, v59, s[0:1]
	v_cndmask_b32_e64 v49, v56, v55, s[0:1]
	v_cndmask_b32_e64 v50, v61, v54, s[0:1]
	v_cndmask_b32_e64 v51, v60, v58, s[0:1]
	v_mov_b32_dpp v65, v49 quad_perm:[1,0,3,2] row_mask:0xf bank_mask:0xf
	v_mov_b32_dpp v66, v48 quad_perm:[1,0,3,2] row_mask:0xf bank_mask:0xf
	v_mad_i64_i32 v[48:49], s[26:27], v64, s44, v[112:113]
	v_mov_b32_dpp v62, v51 quad_perm:[1,0,3,2] row_mask:0xf bank_mask:0xf
	v_mov_b32_dpp v63, v50 quad_perm:[1,0,3,2] row_mask:0xf bank_mask:0xf
	v_lshl_add_u64 v[48:49], v[48:49], 0, v[114:115]
	v_lshl_add_u64 v[52:53], v[48:49], 0, v[140:141]
	v_cndmask_b32_e64 v48, v62, v60, s[0:1]
	v_cndmask_b32_e64 v49, v63, v61, s[0:1]
	v_cndmask_b32_e64 v50, v65, v56, s[0:1]
	v_cndmask_b32_e64 v51, v66, v57, s[0:1]
	global_store_dwordx4 v[52:53], v[48:51], off
	v_add_co_u32_e32 v52, vcc, s38, v52
	s_nop 0
	v_cndmask_b32_e64 v48, v58, v62, s[0:1]
	v_cndmask_b32_e64 v49, v54, v63, s[0:1]
	v_cndmask_b32_e64 v50, v55, v65, s[0:1]
	v_cndmask_b32_e64 v51, v59, v66, s[0:1]
	v_addc_co_u32_e32 v53, vcc, 0, v53, vcc
	global_store_dwordx4 v[52:53], v[48:51], off offset:128
	v_cvt_pk_bf16_f32 v44, v44, v45
	v_cvt_pk_bf16_f32 v45, v46, v47
	v_cvt_pk_bf16_f32 v40, v40, v41
	v_cvt_pk_bf16_f32 v41, v42, v43
	v_cvt_pk_bf16_f32 v42, v36, v37
	v_cvt_pk_bf16_f32 v38, v38, v39
	v_cvt_pk_bf16_f32 v39, v32, v33
	v_cvt_pk_bf16_f32 v43, v34, v35
	s_nop 1
	v_cndmask_b32_e64 v32, v41, v43, s[0:1]
	v_cndmask_b32_e64 v33, v40, v39, s[0:1]
	s_nop 1
	v_mov_b32_dpp v49, v32 quad_perm:[1,0,3,2] row_mask:0xf bank_mask:0xf
	v_add_u32_e32 v32, 0x90, v158
	v_cndmask_b32_e64 v34, v45, v38, s[0:1]
	v_cndmask_b32_e64 v35, v44, v42, s[0:1]
	v_mov_b32_dpp v48, v33 quad_perm:[1,0,3,2] row_mask:0xf bank_mask:0xf
	v_mad_i64_i32 v[32:33], s[26:27], v32, s44, v[112:113]
	v_mov_b32_dpp v46, v35 quad_perm:[1,0,3,2] row_mask:0xf bank_mask:0xf
	v_mov_b32_dpp v47, v34 quad_perm:[1,0,3,2] row_mask:0xf bank_mask:0xf
	v_lshl_add_u64 v[32:33], v[32:33], 0, v[114:115]
	v_lshl_add_u64 v[36:37], v[32:33], 0, v[140:141]
	v_cndmask_b32_e64 v32, v46, v44, s[0:1]
	v_cndmask_b32_e64 v33, v47, v45, s[0:1]
	v_cndmask_b32_e64 v34, v48, v40, s[0:1]
	v_cndmask_b32_e64 v35, v49, v41, s[0:1]
	global_store_dwordx4 v[36:37], v[32:35], off
	v_add_co_u32_e32 v36, vcc, s38, v36
	s_nop 0
	v_cndmask_b32_e64 v32, v42, v46, s[0:1]
	v_cndmask_b32_e64 v33, v38, v47, s[0:1]
	v_cndmask_b32_e64 v34, v39, v48, s[0:1]
	v_cndmask_b32_e64 v35, v43, v49, s[0:1]
	v_addc_co_u32_e32 v37, vcc, 0, v37, vcc
	global_store_dwordx4 v[36:37], v[32:35], off offset:128
	v_cvt_pk_bf16_f32 v28, v28, v29
	v_cvt_pk_bf16_f32 v29, v30, v31
	v_cvt_pk_bf16_f32 v24, v24, v25
	v_cvt_pk_bf16_f32 v25, v26, v27
	v_cvt_pk_bf16_f32 v26, v20, v21
	v_cvt_pk_bf16_f32 v22, v22, v23
	v_cvt_pk_bf16_f32 v23, v16, v17
	v_cvt_pk_bf16_f32 v27, v18, v19
	s_nop 1
	v_cndmask_b32_e64 v16, v25, v27, s[0:1]
	v_cndmask_b32_e64 v17, v24, v23, s[0:1]
	s_nop 1
	v_mov_b32_dpp v33, v16 quad_perm:[1,0,3,2] row_mask:0xf bank_mask:0xf
	v_add_u32_e32 v16, 0xa0, v158
	v_cndmask_b32_e64 v18, v29, v22, s[0:1]
	v_cndmask_b32_e64 v19, v28, v26, s[0:1]
	v_mov_b32_dpp v32, v17 quad_perm:[1,0,3,2] row_mask:0xf bank_mask:0xf
	v_mad_i64_i32 v[16:17], s[26:27], v16, s44, v[112:113]
	v_mov_b32_dpp v30, v19 quad_perm:[1,0,3,2] row_mask:0xf bank_mask:0xf
	v_mov_b32_dpp v31, v18 quad_perm:[1,0,3,2] row_mask:0xf bank_mask:0xf
	v_lshl_add_u64 v[16:17], v[16:17], 0, v[114:115]
	v_lshl_add_u64 v[20:21], v[16:17], 0, v[140:141]
	v_cndmask_b32_e64 v16, v30, v28, s[0:1]
	v_cndmask_b32_e64 v17, v31, v29, s[0:1]
	v_cndmask_b32_e64 v18, v32, v24, s[0:1]
	v_cndmask_b32_e64 v19, v33, v25, s[0:1]
	global_store_dwordx4 v[20:21], v[16:19], off
	v_add_co_u32_e32 v20, vcc, s38, v20
	s_nop 0
	v_cndmask_b32_e64 v16, v26, v30, s[0:1]
	v_cndmask_b32_e64 v17, v22, v31, s[0:1]
	v_cndmask_b32_e64 v18, v23, v32, s[0:1]
	v_cndmask_b32_e64 v19, v27, v33, s[0:1]
	v_addc_co_u32_e32 v21, vcc, 0, v21, vcc
	global_store_dwordx4 v[20:21], v[16:19], off offset:128
	v_cvt_pk_bf16_f32 v12, v12, v13
	v_cvt_pk_bf16_f32 v13, v14, v15
	v_cvt_pk_bf16_f32 v8, v8, v9
	v_cvt_pk_bf16_f32 v9, v10, v11
	v_cvt_pk_bf16_f32 v10, v4, v5
	v_cvt_pk_bf16_f32 v6, v6, v7
	v_cvt_pk_bf16_f32 v7, v0, v1
	v_cvt_pk_bf16_f32 v11, v2, v3
	s_nop 1
	v_cndmask_b32_e64 v0, v9, v11, s[0:1]
	v_cndmask_b32_e64 v1, v8, v7, s[0:1]
	s_nop 1
	v_mov_b32_dpp v17, v0 quad_perm:[1,0,3,2] row_mask:0xf bank_mask:0xf
	v_add_u32_e32 v0, 0xb0, v158
	v_cndmask_b32_e64 v2, v13, v6, s[0:1]
	v_cndmask_b32_e64 v3, v12, v10, s[0:1]
	v_mov_b32_dpp v16, v1 quad_perm:[1,0,3,2] row_mask:0xf bank_mask:0xf
	v_mad_i64_i32 v[0:1], s[26:27], v0, s44, v[112:113]
	v_mov_b32_dpp v14, v3 quad_perm:[1,0,3,2] row_mask:0xf bank_mask:0xf
	v_mov_b32_dpp v15, v2 quad_perm:[1,0,3,2] row_mask:0xf bank_mask:0xf
	v_lshl_add_u64 v[0:1], v[0:1], 0, v[114:115]
	v_lshl_add_u64 v[4:5], v[0:1], 0, v[140:141]
	v_cndmask_b32_e64 v0, v14, v12, s[0:1]
	v_cndmask_b32_e64 v1, v15, v13, s[0:1]
	v_cndmask_b32_e64 v2, v16, v8, s[0:1]
	v_cndmask_b32_e64 v3, v17, v9, s[0:1]
	global_store_dwordx4 v[4:5], v[0:3], off
	v_add_co_u32_e32 v4, vcc, 0x6000, v4
	s_nop 0
	v_cndmask_b32_e64 v0, v10, v14, s[0:1]
	v_addc_co_u32_e32 v5, vcc, 0, v5, vcc
	v_cndmask_b32_e64 v1, v6, v15, s[0:1]
	v_cndmask_b32_e64 v2, v7, v16, s[0:1]
	v_cndmask_b32_e64 v3, v11, v17, s[0:1]
	s_andn2_b64 vcc, exec, s[2:3]
	s_mov_b64 s[2:3], -1
	global_store_dwordx4 v[4:5], v[0:3], off offset:128
	s_cbranch_vccnz .LBB0_143
	s_andn2_b64 vcc, exec, s[6:7]
	s_cbranch_vccnz .LBB0_142
	s_barrier
	s_branch .LBB0_142

;     ...
;     float mnC = (cb - mn) * C;
; #pragma unroll
;     for (int r = 0; r < 16; ++r) p0[r] = fmaf(p0[r], C, mnC);
; #pragma unroll
;     for (int r = 0; r < 16; ++r) p1[r] = fmaf(p1[r], C, mnC);
; #pragma unroll
;     for (int r = 0; r < 16; ++r) p0[r] = __builtin_amdgcn_exp2f(p0[r]);
; }
; __device__ __forceinline__ void finishSM(f32x16& p0, f32x16& p1, float alpha, float& l_reg, bf16x8& pa0, bf16x8& pa1, bf16x8& pa2, bf16x8& pa3) {
; #pragma unroll
;     for (int r = 0; r < 16; ++r) p1[r] = __builtin_amdgcn_exp2f(p1[r]);
;     float ps = 0;
; #pragma unroll
;     for (int r = 0; r < 16; ++r) ps += p0[r];
; #pragma unroll
;     for (int r = 0; r < 16; ++r) ps += p1[r];
;     { auto rr = __builtin_amdgcn_permlane32_swap(__float_as_uint(ps), __float_as_uint(ps), false, false);
;       ps = __uint_as_float(rr[0]) + __uint_as_float(rr[1]); }
;     l_reg = l_reg * alpha + ps;
;     ...
;     PK4(p0, 0, pa0); PK4(p0, 8, pa1); PK4(p1, 0, pa2); PK4(p1, 8, pa3);
.LBB0_246:
	v_cndmask_b32_e64 v170, v188, v225, s[2:3]
	v_sub_f32_e32 v170, s22, v170
	v_mul_f32_e32 v170, 0x3e0293ee, v170
	v_fmamk_f32 v144, v144, 0x3e0293ee, v170
	v_fmamk_f32 v145, v145, 0x3e0293ee, v170
	v_fmamk_f32 v146, v146, 0x3e0293ee, v170
	v_fmamk_f32 v147, v147, 0x3e0293ee, v170
	v_fmamk_f32 v148, v148, 0x3e0293ee, v170
	v_fmamk_f32 v149, v149, 0x3e0293ee, v170
	v_fmamk_f32 v150, v150, 0x3e0293ee, v170
	v_fmamk_f32 v151, v151, 0x3e0293ee, v170
	v_fmamk_f32 v152, v152, 0x3e0293ee, v170
	v_fmamk_f32 v153, v153, 0x3e0293ee, v170
	v_fmamk_f32 v154, v154, 0x3e0293ee, v170
	v_fmamk_f32 v155, v155, 0x3e0293ee, v170
	v_fmamk_f32 v156, v156, 0x3e0293ee, v170
	v_fmamk_f32 v157, v157, 0x3e0293ee, v170
	v_fmamk_f32 v158, v158, 0x3e0293ee, v170
	v_fmamk_f32 v159, v159, 0x3e0293ee, v170
	v_fmamk_f32 v128, v128, 0x3e0293ee, v170
	v_fmamk_f32 v129, v129, 0x3e0293ee, v170
	v_fmamk_f32 v130, v130, 0x3e0293ee, v170
	v_fmamk_f32 v131, v131, 0x3e0293ee, v170
	v_fmamk_f32 v132, v132, 0x3e0293ee, v170
	v_fmamk_f32 v133, v133, 0x3e0293ee, v170
	v_fmamk_f32 v134, v134, 0x3e0293ee, v170
	v_fmamk_f32 v135, v135, 0x3e0293ee, v170
	v_fmamk_f32 v136, v136, 0x3e0293ee, v170
	v_fmamk_f32 v137, v137, 0x3e0293ee, v170
	v_fmamk_f32 v138, v138, 0x3e0293ee, v170
	v_fmamk_f32 v139, v139, 0x3e0293ee, v170
	v_fmamk_f32 v140, v140, 0x3e0293ee, v170
	v_fmamk_f32 v141, v141, 0x3e0293ee, v170
	v_fmamk_f32 v142, v142, 0x3e0293ee, v170
	v_fmac_f32_e32 v170, 0x3e0293ee, v143
	v_exp_f32_e32 v143, v144
	v_exp_f32_e32 v171, v145
	v_exp_f32_e32 v146, v146
	v_exp_f32_e32 v147, v147
	v_exp_f32_e32 v148, v148
	v_exp_f32_e32 v172, v128
	v_add_f32_e32 v128, 0, v143
	v_exp_f32_e32 v149, v149
	v_add_f32_e32 v128, v171, v128
	v_exp_f32_e32 v150, v150
	v_add_f32_e32 v128, v146, v128
	v_exp_f32_e32 v151, v151
	v_add_f32_e32 v128, v147, v128
	v_exp_f32_e32 v152, v152
	v_add_f32_e32 v128, v148, v128
	v_exp_f32_e32 v153, v153
	v_add_f32_e32 v128, v149, v128
	v_exp_f32_e32 v154, v154
	v_add_f32_e32 v128, v150, v128
	v_exp_f32_e32 v155, v155
	v_add_f32_e32 v128, v151, v128
	v_exp_f32_e32 v156, v156
	v_add_f32_e32 v128, v152, v128
	v_exp_f32_e32 v157, v157
	v_add_f32_e32 v128, v153, v128
	v_exp_f32_e32 v158, v158
	v_add_f32_e32 v128, v154, v128
	v_exp_f32_e32 v159, v159
	v_add_f32_e32 v128, v155, v128
	v_add_f32_e32 v128, v156, v128
	v_exp_f32_e32 v173, v129
	v_add_f32_e32 v128, v157, v128
	v_exp_f32_e32 v174, v130
	v_add_f32_e32 v128, v158, v128
	v_exp_f32_e32 v175, v131
	v_add_f32_e32 v128, v159, v128
	v_exp_f32_e32 v176, v132
	v_add_f32_e32 v128, v172, v128
	v_exp_f32_e32 v177, v133
	v_add_f32_e32 v128, v173, v128
	v_exp_f32_e32 v178, v134
	v_add_f32_e32 v128, v174, v128
	v_exp_f32_e32 v179, v135
	v_add_f32_e32 v128, v175, v128
	v_exp_f32_e32 v180, v136
	v_add_f32_e32 v128, v176, v128
	v_exp_f32_e32 v181, v137
	v_add_f32_e32 v128, v177, v128
	v_exp_f32_e32 v182, v138
	v_add_f32_e32 v128, v178, v128
	v_exp_f32_e32 v183, v139
	v_add_f32_e32 v128, v179, v128
	v_exp_f32_e32 v184, v140
	v_add_f32_e32 v128, v180, v128
	v_exp_f32_e32 v185, v141
	v_add_f32_e32 v128, v181, v128
	v_exp_f32_e32 v188, v142
	v_add_f32_e32 v128, v182, v128
	v_exp_f32_e32 v170, v170
	v_add_f32_e32 v128, v183, v128
	v_add_f32_e32 v128, v184, v128
	v_add_f32_e32 v128, v185, v128
	v_add_f32_e32 v128, v188, v128
	v_add_f32_e32 v144, v170, v128
	v_mov_b32_e32 v145, v144
	s_nop 1
	v_permlane32_swap_b32_e32 v144, v145
	v_cvt_pk_bf16_f32 v128, v143, v171
	v_cvt_pk_bf16_f32 v129, v146, v147
	v_cvt_pk_bf16_f32 v130, v148, v149
	v_cvt_pk_bf16_f32 v131, v150, v151
	v_cvt_pk_bf16_f32 v132, v152, v153
	v_cvt_pk_bf16_f32 v133, v154, v155
	v_cvt_pk_bf16_f32 v134, v156, v157
	v_cvt_pk_bf16_f32 v135, v158, v159
	v_cvt_pk_bf16_f32 v136, v172, v173
	v_cvt_pk_bf16_f32 v137, v174, v175
	v_cvt_pk_bf16_f32 v138, v176, v177
	v_cvt_pk_bf16_f32 v139, v178, v179
	v_cvt_pk_bf16_f32 v140, v180, v181
	v_cvt_pk_bf16_f32 v141, v182, v183
	v_cvt_pk_bf16_f32 v142, v184, v185
	v_cvt_pk_bf16_f32 v143, v188, v170
	s_nop 0
	v_permlane32_swap_b32_e32 v128, v130
	v_permlane32_swap_b32_e32 v129, v131
	v_permlane32_swap_b32_e32 v132, v134
	v_permlane32_swap_b32_e32 v133, v135
	v_permlane32_swap_b32_e32 v136, v138
	v_permlane32_swap_b32_e32 v137, v139
	v_permlane32_swap_b32_e32 v140, v142
	v_permlane32_swap_b32_e32 v141, v143
	v_add_u32_e32 v158, 0x8000, v224
	ds_read_b64_tr_b16 v[146:147], v158 offset:0
	ds_read_b64_tr_b16 v[148:149], v158 offset:0x800
	ds_read_b64_tr_b16 v[150:151], v158 offset:0x1000
	ds_read_b64_tr_b16 v[152:153], v158 offset:0x1800
	ds_read_b64_tr_b16 v[154:155], v158 offset:0x2000
	ds_read_b64_tr_b16 v[156:157], v158 offset:0x2800
	ds_read_b64_tr_b16 v[170:171], v158 offset:0x3000
	ds_read_b64_tr_b16 v[172:173], v158 offset:0x3800
	s_waitcnt lgkmcnt(0)
	s_nop 0
	v_mfma_f32_32x32x16_bf16 v[112:127], v[128:131], v[146:149], v[112:127]
	ds_read_b64_tr_b16 v[146:147], v158 offset:0x200
	ds_read_b64_tr_b16 v[148:149], v158 offset:0xa00
	v_mfma_f32_32x32x16_bf16 v[112:127], v[132:135], v[150:153], v[112:127]
	ds_read_b64_tr_b16 v[150:151], v158 offset:0x1200
	ds_read_b64_tr_b16 v[152:153], v158 offset:0x1a00
	v_mfma_f32_32x32x16_bf16 v[112:127], v[136:139], v[154:157], v[112:127]
	ds_read_b64_tr_b16 v[154:155], v158 offset:0x2200
	ds_read_b64_tr_b16 v[156:157], v158 offset:0x2a00
	v_mfma_f32_32x32x16_bf16 v[112:127], v[140:143], v[170:173], v[112:127]
	ds_read_b64_tr_b16 v[170:171], v158 offset:0x3200
	ds_read_b64_tr_b16 v[172:173], v158 offset:0x3a00
	s_waitcnt lgkmcnt(0)
; #define SBAR() __builtin_amdgcn_sched_barrier(0)
; template <int D0> __device__ __forceinline__ void pv_one(f32x16& od, int vb, bf16x8 pa0, bf16x8 pa1, bf16x8 pa2, bf16x8 pa3) {
;     const s16x4 l0 = tr_read<v_rd_off(D0, 0, 0)>(vb), h0 = tr_read<v_rd_off(D0, 0, 1)>(vb), l1 = tr_read<v_rd_off(D0, 1, 0)>(vb), h1 = tr_read<v_rd_off(D0, 1, 1)>(vb);
;     const s16x4 l2 = tr_read<v_rd_off(D0, 2, 0)>(vb), h2 = tr_read<v_rd_off(D0, 2, 1)>(vb), l3 = tr_read<v_rd_off(D0, 3, 0)>(vb), h3 = tr_read<v_rd_off(D0, 3, 1)>(vb);
;     asm volatile("s_waitcnt lgkmcnt(0)" ::: "memory"); SBAR();
;     ...
;     od = __builtin_amdgcn_mfma_f32_32x32x16_bf16(pa0, PK(l0, h0), od, 0, 0, 0);
;     od = __builtin_amdgcn_mfma_f32_32x32x16_bf16(pa1, PK(l1, h1), od, 0, 0, 0);
;     od = __builtin_amdgcn_mfma_f32_32x32x16_bf16(pa2, PK(l2, h2), od, 0, 0, 0);
;     od = __builtin_amdgcn_mfma_f32_32x32x16_bf16(pa3, PK(l3, h3), od, 0, 0, 0);
;     ...
; }
; __device__ __forceinline__ void pv_d0(f32x16* o, int vb, bf16x8 pa0, bf16x8 pa1, bf16x8 pa2, bf16x8 pa3) {
;     pv_one<0>(o[0], vb, pa0, pa1, pa2, pa3); pv_one<1>(o[1], vb, pa0, pa1, pa2, pa3); pv_one<2>(o[2], vb, pa0, pa1, pa2, pa3); pv_one<3>(o[3], vb, pa0, pa1, pa2, pa3);
; template <int MODE, int VW>
; __device__ __forceinline__ void attn_unit_s(const AttnP& P, char* lds, const int tid) {
;     ...
;     if (hi == 0) li_l[r32] = l_reg; asm volatile("s_waitcnt lgkmcnt(0)" ::: "memory");
;     if (P.lse != nullptr && hi == 0) P.lse[(long)(wid * QBLK + r32) * P.lse_ld] = m_reg * SCALE + __logf(l_reg);
;     float rli[16];
; #pragma unroll
;     for (int r = 0; r < 16; ++r) rli[r] = __builtin_amdgcn_rcpf(li_l[crow(r, hi)]);
;     {
;         char* st = lds + wid * 10240;
;         const bool odd = (r32 & 1) != 0;
;         const int sbase = (crow(0, hi) + (odd ? 1 : 0)) * 320 + (r32 & ~1) * 2;
;         bf16_t* Ow = P.O + (long)(wid * QBLK) * P.ldo;
; #pragma unroll
;         for (int hv = 0; hv < VW; ++hv) {
; #pragma unroll
;             for (int d0 = 0; d0 < 4; ++d0)
; #pragma unroll
;                 for (int rp = 0; rp < 8; ++rp) { const int r = 2 * rp;
;                     const float a = o[hv * 4 + d0][r] * rli[r], bb = o[hv * 4 + d0][r + 1] * rli[r + 1];
;                     const float t = odd ? a : bb; const float rcv = dpp_xor1(t);
;                     const unsigned w = odd ? cvt_pk_bf16(rcv, bb) : cvt_pk_bf16(a, rcv);
	v_mfma_f32_32x32x16_bf16 v[96:111], v[128:131], v[146:149], v[96:111]
	ds_read_b64_tr_b16 v[146:147], v158 offset:0x400
	ds_read_b64_tr_b16 v[148:149], v158 offset:0xc00
	v_mfma_f32_32x32x16_bf16 v[96:111], v[132:135], v[150:153], v[96:111]
	ds_read_b64_tr_b16 v[150:151], v158 offset:0x1400
	ds_read_b64_tr_b16 v[152:153], v158 offset:0x1c00
	v_mfma_f32_32x32x16_bf16 v[96:111], v[136:139], v[154:157], v[96:111]
	ds_read_b64_tr_b16 v[154:155], v158 offset:0x2400
	ds_read_b64_tr_b16 v[156:157], v158 offset:0x2c00
	v_mfma_f32_32x32x16_bf16 v[96:111], v[140:143], v[170:173], v[96:111]
	ds_read_b64_tr_b16 v[170:171], v158 offset:0x3400
	ds_read_b64_tr_b16 v[172:173], v158 offset:0x3c00
	s_waitcnt lgkmcnt(0)
	v_mfma_f32_32x32x16_bf16 v[80:95], v[128:131], v[146:149], v[80:95]
	ds_read_b64_tr_b16 v[146:147], v158 offset:0x600
	ds_read_b64_tr_b16 v[148:149], v158 offset:0xe00
	v_mfma_f32_32x32x16_bf16 v[80:95], v[132:135], v[150:153], v[80:95]
	ds_read_b64_tr_b16 v[150:151], v158 offset:0x1600
	ds_read_b64_tr_b16 v[152:153], v158 offset:0x1e00
	v_mfma_f32_32x32x16_bf16 v[80:95], v[136:139], v[154:157], v[80:95]
	ds_read_b64_tr_b16 v[154:155], v158 offset:0x2600
	ds_read_b64_tr_b16 v[156:157], v158 offset:0x2e00
	v_mfma_f32_32x32x16_bf16 v[80:95], v[140:143], v[170:173], v[80:95]
	ds_read_b64_tr_b16 v[170:171], v158 offset:0x3600
	ds_read_b64_tr_b16 v[172:173], v158 offset:0x3e00
	s_waitcnt lgkmcnt(0)
	v_mfma_f32_32x32x16_bf16 v[64:79], v[128:131], v[146:149], v[64:79]
	v_add_u32_e32 v158, 0xc000, v224
	ds_read_b64_tr_b16 v[146:147], v158 offset:0
	ds_read_b64_tr_b16 v[148:149], v158 offset:0x800
	v_mfma_f32_32x32x16_bf16 v[64:79], v[132:135], v[150:153], v[64:79]
	ds_read_b64_tr_b16 v[150:151], v158 offset:0x1000
	ds_read_b64_tr_b16 v[152:153], v158 offset:0x1800
	v_mfma_f32_32x32x16_bf16 v[64:79], v[136:139], v[154:157], v[64:79]
	ds_read_b64_tr_b16 v[154:155], v158 offset:0x2000
	ds_read_b64_tr_b16 v[156:157], v158 offset:0x2800
	v_mfma_f32_32x32x16_bf16 v[64:79], v[140:143], v[170:173], v[64:79]
	ds_read_b64_tr_b16 v[170:171], v158 offset:0x3000
	ds_read_b64_tr_b16 v[172:173], v158 offset:0x3800
	s_waitcnt lgkmcnt(0)
	v_mfma_f32_32x32x16_bf16 v[48:63], v[128:131], v[146:149], v[48:63]
	ds_read_b64_tr_b16 v[146:147], v158 offset:0x200
	ds_read_b64_tr_b16 v[148:149], v158 offset:0xa00
	v_mfma_f32_32x32x16_bf16 v[48:63], v[132:135], v[150:153], v[48:63]
	ds_read_b64_tr_b16 v[150:151], v158 offset:0x1200
	ds_read_b64_tr_b16 v[152:153], v158 offset:0x1a00
	v_mfma_f32_32x32x16_bf16 v[48:63], v[136:139], v[154:157], v[48:63]
	ds_read_b64_tr_b16 v[154:155], v158 offset:0x2200
	ds_read_b64_tr_b16 v[156:157], v158 offset:0x2a00
	v_mfma_f32_32x32x16_bf16 v[48:63], v[140:143], v[170:173], v[48:63]
	ds_read_b64_tr_b16 v[170:171], v158 offset:0x3200
	ds_read_b64_tr_b16 v[172:173], v158 offset:0x3a00
	s_waitcnt lgkmcnt(0)
	v_mfma_f32_32x32x16_bf16 v[32:47], v[128:131], v[146:149], v[32:47]
	ds_read_b64_tr_b16 v[146:147], v158 offset:0x400
	ds_read_b64_tr_b16 v[148:149], v158 offset:0xc00
	v_mfma_f32_32x32x16_bf16 v[32:47], v[132:135], v[150:153], v[32:47]
	ds_read_b64_tr_b16 v[150:151], v158 offset:0x1400
	ds_read_b64_tr_b16 v[152:153], v158 offset:0x1c00
	v_mfma_f32_32x32x16_bf16 v[32:47], v[136:139], v[154:157], v[32:47]
	ds_read_b64_tr_b16 v[154:155], v158 offset:0x2400
	ds_read_b64_tr_b16 v[156:157], v158 offset:0x2c00
	v_mfma_f32_32x32x16_bf16 v[32:47], v[140:143], v[170:173], v[32:47]
	ds_read_b64_tr_b16 v[170:171], v158 offset:0x3400
	ds_read_b64_tr_b16 v[172:173], v158 offset:0x3c00
	s_waitcnt lgkmcnt(0)
	v_mfma_f32_32x32x16_bf16 v[16:31], v[128:131], v[146:149], v[16:31]
	ds_read_b64_tr_b16 v[146:147], v158 offset:0x600
	ds_read_b64_tr_b16 v[148:149], v158 offset:0xe00
	v_mfma_f32_32x32x16_bf16 v[16:31], v[132:135], v[150:153], v[16:31]
	ds_read_b64_tr_b16 v[150:151], v158 offset:0x1600
	ds_read_b64_tr_b16 v[152:153], v158 offset:0x1e00
	v_mfma_f32_32x32x16_bf16 v[16:31], v[136:139], v[154:157], v[16:31]
	ds_read_b64_tr_b16 v[154:155], v158 offset:0x2600
	ds_read_b64_tr_b16 v[156:157], v158 offset:0x2e00
	v_mfma_f32_32x32x16_bf16 v[16:31], v[140:143], v[170:173], v[16:31]
	ds_read_b64_tr_b16 v[170:171], v158 offset:0x3600
	ds_read_b64_tr_b16 v[172:173], v158 offset:0x3e00
	s_waitcnt lgkmcnt(0)
	v_mfma_f32_32x32x16_bf16 v[0:15], v[128:131], v[146:149], v[0:15]
	s_waitcnt vmcnt(0)
	s_barrier
	v_mfma_f32_32x32x16_bf16 v[0:15], v[132:135], v[150:153], v[0:15]
	v_mfma_f32_32x32x16_bf16 v[0:15], v[136:139], v[154:157], v[0:15]
	v_mfma_f32_32x32x16_bf16 v[0:15], v[140:143], v[170:173], v[0:15]
	s_and_saveexec_b64 s[2:3], s[0:1]
	v_add_f32_e32 v128, v144, v145
	v_fmac_f32_e32 v128, v186, v187
	ds_write_b32 v223, v128
	s_or_b64 exec, exec, s[2:3]
	s_waitcnt lgkmcnt(0)
	ds_read_b128 v[140:143], v222
	ds_read_b128 v[136:139], v222 offset:32
	ds_read_b128 v[132:135], v222 offset:64
	ds_read_b128 v[128:131], v222 offset:96
	v_and_b32_e32 v144, 1, v219
	v_cmp_eq_u32_e64 s[0:1], 0, v144
	s_waitcnt lgkmcnt(3)
	v_rcp_f32_e32 v140, v140
	v_rcp_f32_e32 v141, v141
	v_cmp_eq_u32_e32 vcc, 1, v144
	v_mul_f32_e32 v112, v112, v140
	v_mul_f32_e32 v146, v113, v141
	v_cndmask_b32_e64 v145, v112, v146, s[0:1]
	s_nop 1
	v_mov_b32_dpp v113, v145 quad_perm:[1,0,3,2] row_mask:0xf bank_mask:0xf
	s_and_saveexec_b64 s[2:3], vcc
	s_xor_b64 s[2:3], exec, s[2:3]
	s_cbranch_execz .LBB0_250
	v_cvt_pk_bf16_f32 v145, v113, v146

; __device__ __forceinline__ unsigned cvt_pk_bf16(float lo, float hi) { unsigned r; asm volatile("v_cvt_pk_bf16_f32 %0, %1, %2" : "=v"(r) : "v"(lo), "v"(hi)); return r; }
; __device__ __forceinline__ unsigned dpp_xor1(unsigned v) { return (unsigned)__builtin_amdgcn_update_dpp(0, (int)v, 0xB1, 0xf, 0xf, false); }
; __device__ __forceinline__ float dpp_xor1(float v) { return __int_as_float(__builtin_amdgcn_update_dpp(0, __float_as_int(v), 0xB1, 0xf, 0xf, false)); }
; __device__ __forceinline__ int crow(int r, int hi) { return (r & 3) + 8 * (r >> 2) + 4 * hi; }
; template <int MODE, int VW>
; __device__ __forceinline__ void attn_unit_s(const AttnP& P, char* lds, const int tid) {
;     ...
;     for (int r = 0; r < 16; ++r) rli[r] = __builtin_amdgcn_rcpf(li_l[crow(r, hi)]);
;     {
;         char* st = lds + wid * 10240;
;         const bool odd = (r32 & 1) != 0;
;         const int sbase = (crow(0, hi) + (odd ? 1 : 0)) * 320 + (r32 & ~1) * 2;
;         bf16_t* Ow = P.O + (long)(wid * QBLK) * P.ldo;
; #pragma unroll
;         for (int hv = 0; hv < VW; ++hv) {
; #pragma unroll
;             for (int d0 = 0; d0 < 4; ++d0)
; #pragma unroll
;                 for (int rp = 0; rp < 8; ++rp) { const int r = 2 * rp;
;                     const float a = o[hv * 4 + d0][r] * rli[r], bb = o[hv * 4 + d0][r + 1] * rli[r + 1];
;                     const float t = odd ? a : bb; const float rcv = dpp_xor1(t);
;                     const unsigned w = odd ? cvt_pk_bf16(rcv, bb) : cvt_pk_bf16(a, rcv);
;                     *(unsigned*)(st + sbase + (crow(r, 0)) * 320 + d0 * 64) = w; }
.LBB0_252:
	s_or_b64 exec, exec, s[2:3]
	v_rcp_f32_e32 v113, v142
	v_rcp_f32_e32 v142, v143
	s_mulk_i32 s57, 0x2800
	s_add_i32 s22, s57, 0
	v_or_b32_e32 v112, v221, v144
	v_mov_b32_e32 v144, s22
	v_and_b32_e32 v143, 60, v220
	v_mad_u32_u24 v112, v112, s73, v144
	v_mul_f32_e32 v114, v114, v113
	v_mul_f32_e32 v144, v115, v142
	v_add_u32_e32 v112, v112, v143
	v_cndmask_b32_e64 v143, v114, v144, s[0:1]
	ds_write_b32 v112, v145
	s_nop 0
	v_mov_b32_dpp v115, v143 quad_perm:[1,0,3,2] row_mask:0xf bank_mask:0xf
	s_and_saveexec_b64 s[2:3], vcc
	s_xor_b64 s[2:3], exec, s[2:3]
	s_cbranch_execz .LBB0_254
	v_cvt_pk_bf16_f32 v143, v115, v144

; __device__ __forceinline__ unsigned cvt_pk_bf16(float lo, float hi) { unsigned r; asm volatile("v_cvt_pk_bf16_f32 %0, %1, %2" : "=v"(r) : "v"(lo), "v"(hi)); return r; }
; __device__ __forceinline__ unsigned dpp_xor1(unsigned v) { return (unsigned)__builtin_amdgcn_update_dpp(0, (int)v, 0xB1, 0xf, 0xf, false); }
; __device__ __forceinline__ float dpp_xor1(float v) { return __int_as_float(__builtin_amdgcn_update_dpp(0, __float_as_int(v), 0xB1, 0xf, 0xf, false)); }
; __device__ __forceinline__ int crow(int r, int hi) { return (r & 3) + 8 * (r >> 2) + 4 * hi; }
; template <int MODE, int VW>
; __device__ __forceinline__ void attn_unit_s(const AttnP& P, char* lds, const int tid) {
;     ...
;         for (int hv = 0; hv < VW; ++hv) {
; #pragma unroll
;             for (int d0 = 0; d0 < 4; ++d0)
; #pragma unroll
;                 for (int rp = 0; rp < 8; ++rp) { const int r = 2 * rp;
;                     const float a = o[hv * 4 + d0][r] * rli[r], bb = o[hv * 4 + d0][r + 1] * rli[r + 1];
;                     const float t = odd ? a : bb; const float rcv = dpp_xor1(t);
;                     const unsigned w = odd ? cvt_pk_bf16(rcv, bb) : cvt_pk_bf16(a, rcv);
;                     *(unsigned*)(st + sbase + (crow(r, 0)) * 320 + d0 * 64) = w; }
.LBB0_256:
	s_or_b64 exec, exec, s[2:3]
	s_waitcnt lgkmcnt(3)
	v_rcp_f32_e32 v114, v136
	v_rcp_f32_e32 v115, v137
	ds_write_b32 v112, v143 offset:640
	v_mul_f32_e32 v116, v116, v114
	v_mul_f32_e32 v137, v117, v115
	v_cndmask_b32_e64 v136, v116, v137, s[0:1]
	s_nop 1
	v_mov_b32_dpp v117, v136 quad_perm:[1,0,3,2] row_mask:0xf bank_mask:0xf
	s_and_saveexec_b64 s[2:3], vcc
	s_xor_b64 s[2:3], exec, s[2:3]
	s_cbranch_execz .LBB0_258
	v_cvt_pk_bf16_f32 v136, v117, v137

; __device__ __forceinline__ unsigned cvt_pk_bf16(float lo, float hi) { unsigned r; asm volatile("v_cvt_pk_bf16_f32 %0, %1, %2" : "=v"(r) : "v"(lo), "v"(hi)); return r; }
; __device__ __forceinline__ unsigned dpp_xor1(unsigned v) { return (unsigned)__builtin_amdgcn_update_dpp(0, (int)v, 0xB1, 0xf, 0xf, false); }
; __device__ __forceinline__ float dpp_xor1(float v) { return __int_as_float(__builtin_amdgcn_update_dpp(0, __float_as_int(v), 0xB1, 0xf, 0xf, false)); }
; __device__ __forceinline__ int crow(int r, int hi) { return (r & 3) + 8 * (r >> 2) + 4 * hi; }
; template <int MODE, int VW>
; __device__ __forceinline__ void attn_unit_s(const AttnP& P, char* lds, const int tid) {
;     ...
;         for (int hv = 0; hv < VW; ++hv) {
; #pragma unroll
;             for (int d0 = 0; d0 < 4; ++d0)
; #pragma unroll
;                 for (int rp = 0; rp < 8; ++rp) { const int r = 2 * rp;
;                     const float a = o[hv * 4 + d0][r] * rli[r], bb = o[hv * 4 + d0][r + 1] * rli[r + 1];
;                     const float t = odd ? a : bb; const float rcv = dpp_xor1(t);
;                     const unsigned w = odd ? cvt_pk_bf16(rcv, bb) : cvt_pk_bf16(a, rcv);
;                     *(unsigned*)(st + sbase + (crow(r, 0)) * 320 + d0 * 64) = w; }
.LBB0_260:
	s_or_b64 exec, exec, s[2:3]
	v_rcp_f32_e32 v116, v138
	v_rcp_f32_e32 v117, v139
	ds_write_b32 v112, v136 offset:2560
	v_mul_f32_e32 v118, v118, v116
	v_mul_f32_e32 v137, v119, v117
	v_cndmask_b32_e64 v136, v118, v137, s[0:1]
	s_nop 1
	v_mov_b32_dpp v119, v136 quad_perm:[1,0,3,2] row_mask:0xf bank_mask:0xf
	s_and_saveexec_b64 s[2:3], vcc
	s_xor_b64 s[2:3], exec, s[2:3]
	s_cbranch_execz .LBB0_262
	v_cvt_pk_bf16_f32 v136, v119, v137

; __device__ __forceinline__ unsigned cvt_pk_bf16(float lo, float hi) { unsigned r; asm volatile("v_cvt_pk_bf16_f32 %0, %1, %2" : "=v"(r) : "v"(lo), "v"(hi)); return r; }
; __device__ __forceinline__ unsigned dpp_xor1(unsigned v) { return (unsigned)__builtin_amdgcn_update_dpp(0, (int)v, 0xB1, 0xf, 0xf, false); }
; __device__ __forceinline__ float dpp_xor1(float v) { return __int_as_float(__builtin_amdgcn_update_dpp(0, __float_as_int(v), 0xB1, 0xf, 0xf, false)); }
; __device__ __forceinline__ int crow(int r, int hi) { return (r & 3) + 8 * (r >> 2) + 4 * hi; }
; template <int MODE, int VW>
; __device__ __forceinline__ void attn_unit_s(const AttnP& P, char* lds, const int tid) {
;     ...
;         for (int hv = 0; hv < VW; ++hv) {
; #pragma unroll
;             for (int d0 = 0; d0 < 4; ++d0)
; #pragma unroll
;                 for (int rp = 0; rp < 8; ++rp) { const int r = 2 * rp;
;                     const float a = o[hv * 4 + d0][r] * rli[r], bb = o[hv * 4 + d0][r + 1] * rli[r + 1];
;                     const float t = odd ? a : bb; const float rcv = dpp_xor1(t);
;                     const unsigned w = odd ? cvt_pk_bf16(rcv, bb) : cvt_pk_bf16(a, rcv);
;                     *(unsigned*)(st + sbase + (crow(r, 0)) * 320 + d0 * 64) = w; }
.LBB0_264:
	s_or_b64 exec, exec, s[2:3]
	s_waitcnt lgkmcnt(4)
	v_rcp_f32_e32 v118, v132
	v_rcp_f32_e32 v119, v133
	ds_write_b32 v112, v136 offset:3200
	v_mul_f32_e32 v120, v120, v118
	v_mul_f32_e32 v133, v121, v119
	v_cndmask_b32_e64 v132, v120, v133, s[0:1]
	s_nop 1
	v_mov_b32_dpp v121, v132 quad_perm:[1,0,3,2] row_mask:0xf bank_mask:0xf
	s_and_saveexec_b64 s[2:3], vcc
	s_xor_b64 s[2:3], exec, s[2:3]
	s_cbranch_execz .LBB0_266
	v_cvt_pk_bf16_f32 v132, v121, v133

; __device__ __forceinline__ unsigned cvt_pk_bf16(float lo, float hi) { unsigned r; asm volatile("v_cvt_pk_bf16_f32 %0, %1, %2" : "=v"(r) : "v"(lo), "v"(hi)); return r; }
; __device__ __forceinline__ unsigned dpp_xor1(unsigned v) { return (unsigned)__builtin_amdgcn_update_dpp(0, (int)v, 0xB1, 0xf, 0xf, false); }
; __device__ __forceinline__ float dpp_xor1(float v) { return __int_as_float(__builtin_amdgcn_update_dpp(0, __float_as_int(v), 0xB1, 0xf, 0xf, false)); }
; __device__ __forceinline__ int crow(int r, int hi) { return (r & 3) + 8 * (r >> 2) + 4 * hi; }
; template <int MODE, int VW>
; __device__ __forceinline__ void attn_unit_s(const AttnP& P, char* lds, const int tid) {
;     ...
;         for (int hv = 0; hv < VW; ++hv) {
; #pragma unroll
;             for (int d0 = 0; d0 < 4; ++d0)
; #pragma unroll
;                 for (int rp = 0; rp < 8; ++rp) { const int r = 2 * rp;
;                     const float a = o[hv * 4 + d0][r] * rli[r], bb = o[hv * 4 + d0][r + 1] * rli[r + 1];
;                     const float t = odd ? a : bb; const float rcv = dpp_xor1(t);
;                     const unsigned w = odd ? cvt_pk_bf16(rcv, bb) : cvt_pk_bf16(a, rcv);
;                     *(unsigned*)(st + sbase + (crow(r, 0)) * 320 + d0 * 64) = w; }
.LBB0_268:
	s_or_b64 exec, exec, s[2:3]
	v_rcp_f32_e32 v120, v134
	v_rcp_f32_e32 v121, v135
	ds_write_b32 v112, v132 offset:5120
	v_mul_f32_e32 v122, v122, v120
	v_mul_f32_e32 v133, v123, v121
	v_cndmask_b32_e64 v132, v122, v133, s[0:1]
	s_nop 1
	v_mov_b32_dpp v123, v132 quad_perm:[1,0,3,2] row_mask:0xf bank_mask:0xf
	s_and_saveexec_b64 s[2:3], vcc
	s_xor_b64 s[2:3], exec, s[2:3]
	s_cbranch_execz .LBB0_270
	v_cvt_pk_bf16_f32 v132, v123, v133

; __device__ __forceinline__ unsigned cvt_pk_bf16(float lo, float hi) { unsigned r; asm volatile("v_cvt_pk_bf16_f32 %0, %1, %2" : "=v"(r) : "v"(lo), "v"(hi)); return r; }
; __device__ __forceinline__ unsigned dpp_xor1(unsigned v) { return (unsigned)__builtin_amdgcn_update_dpp(0, (int)v, 0xB1, 0xf, 0xf, false); }
; __device__ __forceinline__ float dpp_xor1(float v) { return __int_as_float(__builtin_amdgcn_update_dpp(0, __float_as_int(v), 0xB1, 0xf, 0xf, false)); }
; __device__ __forceinline__ int crow(int r, int hi) { return (r & 3) + 8 * (r >> 2) + 4 * hi; }
; template <int MODE, int VW>
; __device__ __forceinline__ void attn_unit_s(const AttnP& P, char* lds, const int tid) {
;     ...
;         for (int hv = 0; hv < VW; ++hv) {
; #pragma unroll
;             for (int d0 = 0; d0 < 4; ++d0)
; #pragma unroll
;                 for (int rp = 0; rp < 8; ++rp) { const int r = 2 * rp;
;                     const float a = o[hv * 4 + d0][r] * rli[r], bb = o[hv * 4 + d0][r + 1] * rli[r + 1];
;                     const float t = odd ? a : bb; const float rcv = dpp_xor1(t);
;                     const unsigned w = odd ? cvt_pk_bf16(rcv, bb) : cvt_pk_bf16(a, rcv);
;                     *(unsigned*)(st + sbase + (crow(r, 0)) * 320 + d0 * 64) = w; }
.LBB0_272:
	s_or_b64 exec, exec, s[2:3]
	s_waitcnt lgkmcnt(5)
	v_rcp_f32_e32 v122, v128
	v_rcp_f32_e32 v123, v129
	ds_write_b32 v112, v132 offset:5760
	v_mul_f32_e32 v124, v124, v122
	v_mul_f32_e32 v129, v125, v123
	v_cndmask_b32_e64 v128, v124, v129, s[0:1]
	s_nop 1
	v_mov_b32_dpp v125, v128 quad_perm:[1,0,3,2] row_mask:0xf bank_mask:0xf
	s_and_saveexec_b64 s[2:3], vcc
	s_xor_b64 s[2:3], exec, s[2:3]
	s_cbranch_execz .LBB0_274
	v_cvt_pk_bf16_f32 v128, v125, v129

; __device__ __forceinline__ unsigned cvt_pk_bf16(float lo, float hi) { unsigned r; asm volatile("v_cvt_pk_bf16_f32 %0, %1, %2" : "=v"(r) : "v"(lo), "v"(hi)); return r; }
; __device__ __forceinline__ unsigned dpp_xor1(unsigned v) { return (unsigned)__builtin_amdgcn_update_dpp(0, (int)v, 0xB1, 0xf, 0xf, false); }
; __device__ __forceinline__ float dpp_xor1(float v) { return __int_as_float(__builtin_amdgcn_update_dpp(0, __float_as_int(v), 0xB1, 0xf, 0xf, false)); }
; __device__ __forceinline__ int crow(int r, int hi) { return (r & 3) + 8 * (r >> 2) + 4 * hi; }
; template <int MODE, int VW>
; __device__ __forceinline__ void attn_unit_s(const AttnP& P, char* lds, const int tid) {
;     ...
;         for (int hv = 0; hv < VW; ++hv) {
; #pragma unroll
;             for (int d0 = 0; d0 < 4; ++d0)
; #pragma unroll
;                 for (int rp = 0; rp < 8; ++rp) { const int r = 2 * rp;
;                     const float a = o[hv * 4 + d0][r] * rli[r], bb = o[hv * 4 + d0][r + 1] * rli[r + 1];
;                     const float t = odd ? a : bb; const float rcv = dpp_xor1(t);
;                     const unsigned w = odd ? cvt_pk_bf16(rcv, bb) : cvt_pk_bf16(a, rcv);
;                     *(unsigned*)(st + sbase + (crow(r, 0)) * 320 + d0 * 64) = w; }
.LBB0_276:
	s_or_b64 exec, exec, s[2:3]
	v_rcp_f32_e32 v124, v130
	v_rcp_f32_e32 v125, v131
	ds_write_b32 v112, v128 offset:7680
	v_mul_f32_e32 v128, v126, v124
	v_mul_f32_e32 v129, v127, v125
	v_cndmask_b32_e64 v126, v128, v129, s[0:1]
	s_nop 1
	v_mov_b32_dpp v127, v126 quad_perm:[1,0,3,2] row_mask:0xf bank_mask:0xf
	s_and_saveexec_b64 s[2:3], vcc
	s_xor_b64 s[2:3], exec, s[2:3]
	s_cbranch_execz .LBB0_278
	v_cvt_pk_bf16_f32 v126, v127, v129

; __device__ __forceinline__ unsigned cvt_pk_bf16(float lo, float hi) { unsigned r; asm volatile("v_cvt_pk_bf16_f32 %0, %1, %2" : "=v"(r) : "v"(lo), "v"(hi)); return r; }
; __device__ __forceinline__ unsigned dpp_xor1(unsigned v) { return (unsigned)__builtin_amdgcn_update_dpp(0, (int)v, 0xB1, 0xf, 0xf, false); }
; __device__ __forceinline__ float dpp_xor1(float v) { return __int_as_float(__builtin_amdgcn_update_dpp(0, __float_as_int(v), 0xB1, 0xf, 0xf, false)); }
; __device__ __forceinline__ int crow(int r, int hi) { return (r & 3) + 8 * (r >> 2) + 4 * hi; }
; template <int MODE, int VW>
; __device__ __forceinline__ void attn_unit_s(const AttnP& P, char* lds, const int tid) {
;     ...
;         for (int hv = 0; hv < VW; ++hv) {
; #pragma unroll
;             for (int d0 = 0; d0 < 4; ++d0)
; #pragma unroll
;                 for (int rp = 0; rp < 8; ++rp) { const int r = 2 * rp;
;                     const float a = o[hv * 4 + d0][r] * rli[r], bb = o[hv * 4 + d0][r + 1] * rli[r + 1];
;                     const float t = odd ? a : bb; const float rcv = dpp_xor1(t);
;                     const unsigned w = odd ? cvt_pk_bf16(rcv, bb) : cvt_pk_bf16(a, rcv);
;                     *(unsigned*)(st + sbase + (crow(r, 0)) * 320 + d0 * 64) = w; }
.LBB0_280:
	s_or_b64 exec, exec, s[2:3]
	ds_write_b32 v112, v126 offset:8320
	v_mul_f32_e32 v126, v96, v140
	v_mul_f32_e32 v127, v97, v141
	v_cndmask_b32_e64 v96, v126, v127, s[0:1]
	s_nop 1
	v_mov_b32_dpp v97, v96 quad_perm:[1,0,3,2] row_mask:0xf bank_mask:0xf
	s_and_saveexec_b64 s[2:3], vcc
	s_xor_b64 s[2:3], exec, s[2:3]
	s_cbranch_execz .LBB0_282
	v_cvt_pk_bf16_f32 v96, v97, v127

; __device__ __forceinline__ unsigned cvt_pk_bf16(float lo, float hi) { unsigned r; asm volatile("v_cvt_pk_bf16_f32 %0, %1, %2" : "=v"(r) : "v"(lo), "v"(hi)); return r; }
; __device__ __forceinline__ unsigned dpp_xor1(unsigned v) { return (unsigned)__builtin_amdgcn_update_dpp(0, (int)v, 0xB1, 0xf, 0xf, false); }
; __device__ __forceinline__ float dpp_xor1(float v) { return __int_as_float(__builtin_amdgcn_update_dpp(0, __float_as_int(v), 0xB1, 0xf, 0xf, false)); }
; __device__ __forceinline__ int crow(int r, int hi) { return (r & 3) + 8 * (r >> 2) + 4 * hi; }
; template <int MODE, int VW>
; __device__ __forceinline__ void attn_unit_s(const AttnP& P, char* lds, const int tid) {
;     ...
;         for (int hv = 0; hv < VW; ++hv) {
; #pragma unroll
;             for (int d0 = 0; d0 < 4; ++d0)
; #pragma unroll
;                 for (int rp = 0; rp < 8; ++rp) { const int r = 2 * rp;
;                     const float a = o[hv * 4 + d0][r] * rli[r], bb = o[hv * 4 + d0][r + 1] * rli[r + 1];
;                     const float t = odd ? a : bb; const float rcv = dpp_xor1(t);
;                     const unsigned w = odd ? cvt_pk_bf16(rcv, bb) : cvt_pk_bf16(a, rcv);
;                     *(unsigned*)(st + sbase + (crow(r, 0)) * 320 + d0 * 64) = w; }
.LBB0_284:
	s_or_b64 exec, exec, s[2:3]
	v_mul_f32_e32 v97, v98, v113
	v_mul_f32_e32 v99, v99, v142
	ds_write_b32 v112, v96 offset:64
	v_cndmask_b32_e64 v96, v97, v99, s[0:1]
	s_nop 1
	v_mov_b32_dpp v98, v96 quad_perm:[1,0,3,2] row_mask:0xf bank_mask:0xf
	s_and_saveexec_b64 s[2:3], vcc
	s_xor_b64 s[2:3], exec, s[2:3]
	s_cbranch_execz .LBB0_286
	v_cvt_pk_bf16_f32 v96, v98, v99

; __device__ __forceinline__ unsigned cvt_pk_bf16(float lo, float hi) { unsigned r; asm volatile("v_cvt_pk_bf16_f32 %0, %1, %2" : "=v"(r) : "v"(lo), "v"(hi)); return r; }
; __device__ __forceinline__ unsigned dpp_xor1(unsigned v) { return (unsigned)__builtin_amdgcn_update_dpp(0, (int)v, 0xB1, 0xf, 0xf, false); }
; __device__ __forceinline__ float dpp_xor1(float v) { return __int_as_float(__builtin_amdgcn_update_dpp(0, __float_as_int(v), 0xB1, 0xf, 0xf, false)); }
; __device__ __forceinline__ int crow(int r, int hi) { return (r & 3) + 8 * (r >> 2) + 4 * hi; }
; template <int MODE, int VW>
; __device__ __forceinline__ void attn_unit_s(const AttnP& P, char* lds, const int tid) {
;     ...
;         for (int hv = 0; hv < VW; ++hv) {
; #pragma unroll
;             for (int d0 = 0; d0 < 4; ++d0)
; #pragma unroll
;                 for (int rp = 0; rp < 8; ++rp) { const int r = 2 * rp;
;                     const float a = o[hv * 4 + d0][r] * rli[r], bb = o[hv * 4 + d0][r + 1] * rli[r + 1];
;                     const float t = odd ? a : bb; const float rcv = dpp_xor1(t);
;                     const unsigned w = odd ? cvt_pk_bf16(rcv, bb) : cvt_pk_bf16(a, rcv);
;                     *(unsigned*)(st + sbase + (crow(r, 0)) * 320 + d0 * 64) = w; }
.LBB0_288:
	s_or_b64 exec, exec, s[2:3]
	v_mul_f32_e32 v97, v100, v114
	v_mul_f32_e32 v99, v101, v115
	ds_write_b32 v112, v96 offset:704
	v_cndmask_b32_e64 v96, v97, v99, s[0:1]
	s_nop 1
	v_mov_b32_dpp v98, v96 quad_perm:[1,0,3,2] row_mask:0xf bank_mask:0xf
	s_and_saveexec_b64 s[2:3], vcc
	s_xor_b64 s[2:3], exec, s[2:3]
	s_cbranch_execz .LBB0_290
	v_cvt_pk_bf16_f32 v96, v98, v99

; __device__ __forceinline__ unsigned cvt_pk_bf16(float lo, float hi) { unsigned r; asm volatile("v_cvt_pk_bf16_f32 %0, %1, %2" : "=v"(r) : "v"(lo), "v"(hi)); return r; }
; __device__ __forceinline__ unsigned dpp_xor1(unsigned v) { return (unsigned)__builtin_amdgcn_update_dpp(0, (int)v, 0xB1, 0xf, 0xf, false); }
; __device__ __forceinline__ float dpp_xor1(float v) { return __int_as_float(__builtin_amdgcn_update_dpp(0, __float_as_int(v), 0xB1, 0xf, 0xf, false)); }
; __device__ __forceinline__ int crow(int r, int hi) { return (r & 3) + 8 * (r >> 2) + 4 * hi; }
; template <int MODE, int VW>
; __device__ __forceinline__ void attn_unit_s(const AttnP& P, char* lds, const int tid) {
;     ...
;         for (int hv = 0; hv < VW; ++hv) {
; #pragma unroll
;             for (int d0 = 0; d0 < 4; ++d0)
; #pragma unroll
;                 for (int rp = 0; rp < 8; ++rp) { const int r = 2 * rp;
;                     const float a = o[hv * 4 + d0][r] * rli[r], bb = o[hv * 4 + d0][r + 1] * rli[r + 1];
;                     const float t = odd ? a : bb; const float rcv = dpp_xor1(t);
;                     const unsigned w = odd ? cvt_pk_bf16(rcv, bb) : cvt_pk_bf16(a, rcv);
;                     *(unsigned*)(st + sbase + (crow(r, 0)) * 320 + d0 * 64) = w; }
.LBB0_292:
	s_or_b64 exec, exec, s[2:3]
	v_mul_f32_e32 v97, v102, v116
	v_mul_f32_e32 v99, v103, v117
	ds_write_b32 v112, v96 offset:2624
	v_cndmask_b32_e64 v96, v97, v99, s[0:1]
	s_nop 1
	v_mov_b32_dpp v98, v96 quad_perm:[1,0,3,2] row_mask:0xf bank_mask:0xf
	s_and_saveexec_b64 s[2:3], vcc
	s_xor_b64 s[2:3], exec, s[2:3]
	s_cbranch_execz .LBB0_294
	v_cvt_pk_bf16_f32 v96, v98, v99

; __device__ __forceinline__ unsigned cvt_pk_bf16(float lo, float hi) { unsigned r; asm volatile("v_cvt_pk_bf16_f32 %0, %1, %2" : "=v"(r) : "v"(lo), "v"(hi)); return r; }
; __device__ __forceinline__ unsigned dpp_xor1(unsigned v) { return (unsigned)__builtin_amdgcn_update_dpp(0, (int)v, 0xB1, 0xf, 0xf, false); }
; __device__ __forceinline__ float dpp_xor1(float v) { return __int_as_float(__builtin_amdgcn_update_dpp(0, __float_as_int(v), 0xB1, 0xf, 0xf, false)); }
; __device__ __forceinline__ int crow(int r, int hi) { return (r & 3) + 8 * (r >> 2) + 4 * hi; }
; template <int MODE, int VW>
; __device__ __forceinline__ void attn_unit_s(const AttnP& P, char* lds, const int tid) {
;     ...
;         for (int hv = 0; hv < VW; ++hv) {
; #pragma unroll
;             for (int d0 = 0; d0 < 4; ++d0)
; #pragma unroll
;                 for (int rp = 0; rp < 8; ++rp) { const int r = 2 * rp;
;                     const float a = o[hv * 4 + d0][r] * rli[r], bb = o[hv * 4 + d0][r + 1] * rli[r + 1];
;                     const float t = odd ? a : bb; const float rcv = dpp_xor1(t);
;                     const unsigned w = odd ? cvt_pk_bf16(rcv, bb) : cvt_pk_bf16(a, rcv);
;                     *(unsigned*)(st + sbase + (crow(r, 0)) * 320 + d0 * 64) = w; }
.LBB0_296:
	s_or_b64 exec, exec, s[2:3]
	v_mul_f32_e32 v97, v104, v118
	v_mul_f32_e32 v99, v105, v119
	ds_write_b32 v112, v96 offset:3264
	v_cndmask_b32_e64 v96, v97, v99, s[0:1]
	s_nop 1
	v_mov_b32_dpp v98, v96 quad_perm:[1,0,3,2] row_mask:0xf bank_mask:0xf
	s_and_saveexec_b64 s[2:3], vcc
	s_xor_b64 s[2:3], exec, s[2:3]
	s_cbranch_execz .LBB0_298
	v_cvt_pk_bf16_f32 v96, v98, v99

; __device__ __forceinline__ unsigned cvt_pk_bf16(float lo, float hi) { unsigned r; asm volatile("v_cvt_pk_bf16_f32 %0, %1, %2" : "=v"(r) : "v"(lo), "v"(hi)); return r; }
; __device__ __forceinline__ unsigned dpp_xor1(unsigned v) { return (unsigned)__builtin_amdgcn_update_dpp(0, (int)v, 0xB1, 0xf, 0xf, false); }
; __device__ __forceinline__ float dpp_xor1(float v) { return __int_as_float(__builtin_amdgcn_update_dpp(0, __float_as_int(v), 0xB1, 0xf, 0xf, false)); }
; __device__ __forceinline__ int crow(int r, int hi) { return (r & 3) + 8 * (r >> 2) + 4 * hi; }
; template <int MODE, int VW>
; __device__ __forceinline__ void attn_unit_s(const AttnP& P, char* lds, const int tid) {
;     ...
;         for (int hv = 0; hv < VW; ++hv) {
; #pragma unroll
;             for (int d0 = 0; d0 < 4; ++d0)
; #pragma unroll
;                 for (int rp = 0; rp < 8; ++rp) { const int r = 2 * rp;
;                     const float a = o[hv * 4 + d0][r] * rli[r], bb = o[hv * 4 + d0][r + 1] * rli[r + 1];
;                     const float t = odd ? a : bb; const float rcv = dpp_xor1(t);
;                     const unsigned w = odd ? cvt_pk_bf16(rcv, bb) : cvt_pk_bf16(a, rcv);
;                     *(unsigned*)(st + sbase + (crow(r, 0)) * 320 + d0 * 64) = w; }
.LBB0_300:
	s_or_b64 exec, exec, s[2:3]
	v_mul_f32_e32 v97, v106, v120
	v_mul_f32_e32 v99, v107, v121
	ds_write_b32 v112, v96 offset:5184
	v_cndmask_b32_e64 v96, v97, v99, s[0:1]
	s_nop 1
	v_mov_b32_dpp v98, v96 quad_perm:[1,0,3,2] row_mask:0xf bank_mask:0xf
	s_and_saveexec_b64 s[2:3], vcc
	s_xor_b64 s[2:3], exec, s[2:3]
	s_cbranch_execz .LBB0_302
	v_cvt_pk_bf16_f32 v96, v98, v99

; __device__ __forceinline__ unsigned cvt_pk_bf16(float lo, float hi) { unsigned r; asm volatile("v_cvt_pk_bf16_f32 %0, %1, %2" : "=v"(r) : "v"(lo), "v"(hi)); return r; }
; __device__ __forceinline__ unsigned dpp_xor1(unsigned v) { return (unsigned)__builtin_amdgcn_update_dpp(0, (int)v, 0xB1, 0xf, 0xf, false); }
; __device__ __forceinline__ float dpp_xor1(float v) { return __int_as_float(__builtin_amdgcn_update_dpp(0, __float_as_int(v), 0xB1, 0xf, 0xf, false)); }
; __device__ __forceinline__ int crow(int r, int hi) { return (r & 3) + 8 * (r >> 2) + 4 * hi; }
; template <int MODE, int VW>
; __device__ __forceinline__ void attn_unit_s(const AttnP& P, char* lds, const int tid) {
;     ...
;         for (int hv = 0; hv < VW; ++hv) {
; #pragma unroll
;             for (int d0 = 0; d0 < 4; ++d0)
; #pragma unroll
;                 for (int rp = 0; rp < 8; ++rp) { const int r = 2 * rp;
;                     const float a = o[hv * 4 + d0][r] * rli[r], bb = o[hv * 4 + d0][r + 1] * rli[r + 1];
;                     const float t = odd ? a : bb; const float rcv = dpp_xor1(t);
;                     const unsigned w = odd ? cvt_pk_bf16(rcv, bb) : cvt_pk_bf16(a, rcv);
;                     *(unsigned*)(st + sbase + (crow(r, 0)) * 320 + d0 * 64) = w; }
.LBB0_304:
	s_or_b64 exec, exec, s[2:3]
	v_mul_f32_e32 v97, v108, v122
	v_mul_f32_e32 v99, v109, v123
	ds_write_b32 v112, v96 offset:5824
	v_cndmask_b32_e64 v96, v97, v99, s[0:1]
	s_nop 1
	v_mov_b32_dpp v98, v96 quad_perm:[1,0,3,2] row_mask:0xf bank_mask:0xf
	s_and_saveexec_b64 s[2:3], vcc
	s_xor_b64 s[2:3], exec, s[2:3]
	s_cbranch_execz .LBB0_306
	v_cvt_pk_bf16_f32 v96, v98, v99

; __device__ __forceinline__ unsigned cvt_pk_bf16(float lo, float hi) { unsigned r; asm volatile("v_cvt_pk_bf16_f32 %0, %1, %2" : "=v"(r) : "v"(lo), "v"(hi)); return r; }
; __device__ __forceinline__ unsigned dpp_xor1(unsigned v) { return (unsigned)__builtin_amdgcn_update_dpp(0, (int)v, 0xB1, 0xf, 0xf, false); }
; __device__ __forceinline__ float dpp_xor1(float v) { return __int_as_float(__builtin_amdgcn_update_dpp(0, __float_as_int(v), 0xB1, 0xf, 0xf, false)); }
; __device__ __forceinline__ int crow(int r, int hi) { return (r & 3) + 8 * (r >> 2) + 4 * hi; }
; template <int MODE, int VW>
; __device__ __forceinline__ void attn_unit_s(const AttnP& P, char* lds, const int tid) {
;     ...
;         for (int hv = 0; hv < VW; ++hv) {
; #pragma unroll
;             for (int d0 = 0; d0 < 4; ++d0)
; #pragma unroll
;                 for (int rp = 0; rp < 8; ++rp) { const int r = 2 * rp;
;                     const float a = o[hv * 4 + d0][r] * rli[r], bb = o[hv * 4 + d0][r + 1] * rli[r + 1];
;                     const float t = odd ? a : bb; const float rcv = dpp_xor1(t);
;                     const unsigned w = odd ? cvt_pk_bf16(rcv, bb) : cvt_pk_bf16(a, rcv);
;                     *(unsigned*)(st + sbase + (crow(r, 0)) * 320 + d0 * 64) = w; }
.LBB0_308:
	s_or_b64 exec, exec, s[2:3]
	v_mul_f32_e32 v97, v110, v124
	v_mul_f32_e32 v99, v111, v125
	ds_write_b32 v112, v96 offset:7744
	v_cndmask_b32_e64 v96, v97, v99, s[0:1]
	s_nop 1
	v_mov_b32_dpp v98, v96 quad_perm:[1,0,3,2] row_mask:0xf bank_mask:0xf
	s_and_saveexec_b64 s[2:3], vcc
	s_xor_b64 s[2:3], exec, s[2:3]
	s_cbranch_execz .LBB0_310
	v_cvt_pk_bf16_f32 v96, v98, v99

; __device__ __forceinline__ unsigned cvt_pk_bf16(float lo, float hi) { unsigned r; asm volatile("v_cvt_pk_bf16_f32 %0, %1, %2" : "=v"(r) : "v"(lo), "v"(hi)); return r; }
; __device__ __forceinline__ unsigned dpp_xor1(unsigned v) { return (unsigned)__builtin_amdgcn_update_dpp(0, (int)v, 0xB1, 0xf, 0xf, false); }
; __device__ __forceinline__ float dpp_xor1(float v) { return __int_as_float(__builtin_amdgcn_update_dpp(0, __float_as_int(v), 0xB1, 0xf, 0xf, false)); }
; __device__ __forceinline__ int crow(int r, int hi) { return (r & 3) + 8 * (r >> 2) + 4 * hi; }
; template <int MODE, int VW>
; __device__ __forceinline__ void attn_unit_s(const AttnP& P, char* lds, const int tid) {
;     ...
;         for (int hv = 0; hv < VW; ++hv) {
; #pragma unroll
;             for (int d0 = 0; d0 < 4; ++d0)
; #pragma unroll
;                 for (int rp = 0; rp < 8; ++rp) { const int r = 2 * rp;
;                     const float a = o[hv * 4 + d0][r] * rli[r], bb = o[hv * 4 + d0][r + 1] * rli[r + 1];
;                     const float t = odd ? a : bb; const float rcv = dpp_xor1(t);
;                     const unsigned w = odd ? cvt_pk_bf16(rcv, bb) : cvt_pk_bf16(a, rcv);
;                     *(unsigned*)(st + sbase + (crow(r, 0)) * 320 + d0 * 64) = w; }
.LBB0_312:
	s_or_b64 exec, exec, s[2:3]
	ds_write_b32 v112, v96 offset:8384
	v_mul_f32_e32 v96, v80, v140
	v_mul_f32_e32 v97, v81, v141
	v_cndmask_b32_e64 v80, v96, v97, s[0:1]
	s_nop 1
	v_mov_b32_dpp v81, v80 quad_perm:[1,0,3,2] row_mask:0xf bank_mask:0xf
	s_and_saveexec_b64 s[2:3], vcc
	s_xor_b64 s[2:3], exec, s[2:3]
	s_cbranch_execz .LBB0_314
	v_cvt_pk_bf16_f32 v80, v81, v97

; __device__ __forceinline__ unsigned cvt_pk_bf16(float lo, float hi) { unsigned r; asm volatile("v_cvt_pk_bf16_f32 %0, %1, %2" : "=v"(r) : "v"(lo), "v"(hi)); return r; }
; __device__ __forceinline__ unsigned dpp_xor1(unsigned v) { return (unsigned)__builtin_amdgcn_update_dpp(0, (int)v, 0xB1, 0xf, 0xf, false); }
; __device__ __forceinline__ float dpp_xor1(float v) { return __int_as_float(__builtin_amdgcn_update_dpp(0, __float_as_int(v), 0xB1, 0xf, 0xf, false)); }
; __device__ __forceinline__ int crow(int r, int hi) { return (r & 3) + 8 * (r >> 2) + 4 * hi; }
; template <int MODE, int VW>
; __device__ __forceinline__ void attn_unit_s(const AttnP& P, char* lds, const int tid) {
;     ...
;         for (int hv = 0; hv < VW; ++hv) {
; #pragma unroll
;             for (int d0 = 0; d0 < 4; ++d0)
; #pragma unroll
;                 for (int rp = 0; rp < 8; ++rp) { const int r = 2 * rp;
;                     const float a = o[hv * 4 + d0][r] * rli[r], bb = o[hv * 4 + d0][r + 1] * rli[r + 1];
;                     const float t = odd ? a : bb; const float rcv = dpp_xor1(t);
;                     const unsigned w = odd ? cvt_pk_bf16(rcv, bb) : cvt_pk_bf16(a, rcv);
;                     *(unsigned*)(st + sbase + (crow(r, 0)) * 320 + d0 * 64) = w; }
.LBB0_316:
	s_or_b64 exec, exec, s[2:3]
	v_mul_f32_e32 v81, v82, v113
	v_mul_f32_e32 v83, v83, v142
	ds_write_b32 v112, v80 offset:128
	v_cndmask_b32_e64 v80, v81, v83, s[0:1]
	s_nop 1
	v_mov_b32_dpp v82, v80 quad_perm:[1,0,3,2] row_mask:0xf bank_mask:0xf
	s_and_saveexec_b64 s[2:3], vcc
	s_xor_b64 s[2:3], exec, s[2:3]
	s_cbranch_execz .LBB0_318
	v_cvt_pk_bf16_f32 v80, v82, v83

; __device__ __forceinline__ unsigned cvt_pk_bf16(float lo, float hi) { unsigned r; asm volatile("v_cvt_pk_bf16_f32 %0, %1, %2" : "=v"(r) : "v"(lo), "v"(hi)); return r; }
; __device__ __forceinline__ unsigned dpp_xor1(unsigned v) { return (unsigned)__builtin_amdgcn_update_dpp(0, (int)v, 0xB1, 0xf, 0xf, false); }
; __device__ __forceinline__ float dpp_xor1(float v) { return __int_as_float(__builtin_amdgcn_update_dpp(0, __float_as_int(v), 0xB1, 0xf, 0xf, false)); }
; __device__ __forceinline__ int crow(int r, int hi) { return (r & 3) + 8 * (r >> 2) + 4 * hi; }
; template <int MODE, int VW>
; __device__ __forceinline__ void attn_unit_s(const AttnP& P, char* lds, const int tid) {
;     ...
;         for (int hv = 0; hv < VW; ++hv) {
; #pragma unroll
;             for (int d0 = 0; d0 < 4; ++d0)
; #pragma unroll
;                 for (int rp = 0; rp < 8; ++rp) { const int r = 2 * rp;
;                     const float a = o[hv * 4 + d0][r] * rli[r], bb = o[hv * 4 + d0][r + 1] * rli[r + 1];
;                     const float t = odd ? a : bb; const float rcv = dpp_xor1(t);
;                     const unsigned w = odd ? cvt_pk_bf16(rcv, bb) : cvt_pk_bf16(a, rcv);
;                     *(unsigned*)(st + sbase + (crow(r, 0)) * 320 + d0 * 64) = w; }
.LBB0_320:
	s_or_b64 exec, exec, s[2:3]
	v_mul_f32_e32 v81, v84, v114
	v_mul_f32_e32 v83, v85, v115
	ds_write_b32 v112, v80 offset:768
	v_cndmask_b32_e64 v80, v81, v83, s[0:1]
	s_nop 1
	v_mov_b32_dpp v82, v80 quad_perm:[1,0,3,2] row_mask:0xf bank_mask:0xf
	s_and_saveexec_b64 s[2:3], vcc
	s_xor_b64 s[2:3], exec, s[2:3]
	s_cbranch_execz .LBB0_322
	v_cvt_pk_bf16_f32 v80, v82, v83

; __device__ __forceinline__ unsigned cvt_pk_bf16(float lo, float hi) { unsigned r; asm volatile("v_cvt_pk_bf16_f32 %0, %1, %2" : "=v"(r) : "v"(lo), "v"(hi)); return r; }
; __device__ __forceinline__ unsigned dpp_xor1(unsigned v) { return (unsigned)__builtin_amdgcn_update_dpp(0, (int)v, 0xB1, 0xf, 0xf, false); }
; __device__ __forceinline__ float dpp_xor1(float v) { return __int_as_float(__builtin_amdgcn_update_dpp(0, __float_as_int(v), 0xB1, 0xf, 0xf, false)); }
; __device__ __forceinline__ int crow(int r, int hi) { return (r & 3) + 8 * (r >> 2) + 4 * hi; }
; template <int MODE, int VW>
; __device__ __forceinline__ void attn_unit_s(const AttnP& P, char* lds, const int tid) {
;     ...
;         for (int hv = 0; hv < VW; ++hv) {
; #pragma unroll
;             for (int d0 = 0; d0 < 4; ++d0)
; #pragma unroll
;                 for (int rp = 0; rp < 8; ++rp) { const int r = 2 * rp;
;                     const float a = o[hv * 4 + d0][r] * rli[r], bb = o[hv * 4 + d0][r + 1] * rli[r + 1];
;                     const float t = odd ? a : bb; const float rcv = dpp_xor1(t);
;                     const unsigned w = odd ? cvt_pk_bf16(rcv, bb) : cvt_pk_bf16(a, rcv);
;                     *(unsigned*)(st + sbase + (crow(r, 0)) * 320 + d0 * 64) = w; }
.LBB0_324:
	s_or_b64 exec, exec, s[2:3]
	v_mul_f32_e32 v81, v86, v116
	v_mul_f32_e32 v83, v87, v117
	ds_write_b32 v112, v80 offset:2688
	v_cndmask_b32_e64 v80, v81, v83, s[0:1]
	s_nop 1
	v_mov_b32_dpp v82, v80 quad_perm:[1,0,3,2] row_mask:0xf bank_mask:0xf
	s_and_saveexec_b64 s[2:3], vcc
	s_xor_b64 s[2:3], exec, s[2:3]
	s_cbranch_execz .LBB0_326
	v_cvt_pk_bf16_f32 v80, v82, v83

; __device__ __forceinline__ unsigned cvt_pk_bf16(float lo, float hi) { unsigned r; asm volatile("v_cvt_pk_bf16_f32 %0, %1, %2" : "=v"(r) : "v"(lo), "v"(hi)); return r; }
; __device__ __forceinline__ unsigned dpp_xor1(unsigned v) { return (unsigned)__builtin_amdgcn_update_dpp(0, (int)v, 0xB1, 0xf, 0xf, false); }
; __device__ __forceinline__ float dpp_xor1(float v) { return __int_as_float(__builtin_amdgcn_update_dpp(0, __float_as_int(v), 0xB1, 0xf, 0xf, false)); }
; __device__ __forceinline__ int crow(int r, int hi) { return (r & 3) + 8 * (r >> 2) + 4 * hi; }
; template <int MODE, int VW>
; __device__ __forceinline__ void attn_unit_s(const AttnP& P, char* lds, const int tid) {
;     ...
;         for (int hv = 0; hv < VW; ++hv) {
; #pragma unroll
;             for (int d0 = 0; d0 < 4; ++d0)
; #pragma unroll
;                 for (int rp = 0; rp < 8; ++rp) { const int r = 2 * rp;
;                     const float a = o[hv * 4 + d0][r] * rli[r], bb = o[hv * 4 + d0][r + 1] * rli[r + 1];
;                     const float t = odd ? a : bb; const float rcv = dpp_xor1(t);
;                     const unsigned w = odd ? cvt_pk_bf16(rcv, bb) : cvt_pk_bf16(a, rcv);
;                     *(unsigned*)(st + sbase + (crow(r, 0)) * 320 + d0 * 64) = w; }
.LBB0_328:
	s_or_b64 exec, exec, s[2:3]
	v_mul_f32_e32 v81, v88, v118
	v_mul_f32_e32 v83, v89, v119
	ds_write_b32 v112, v80 offset:3328
	v_cndmask_b32_e64 v80, v81, v83, s[0:1]
	s_nop 1
	v_mov_b32_dpp v82, v80 quad_perm:[1,0,3,2] row_mask:0xf bank_mask:0xf
	s_and_saveexec_b64 s[2:3], vcc
	s_xor_b64 s[2:3], exec, s[2:3]
	s_cbranch_execz .LBB0_330
	v_cvt_pk_bf16_f32 v80, v82, v83

; __device__ __forceinline__ unsigned cvt_pk_bf16(float lo, float hi) { unsigned r; asm volatile("v_cvt_pk_bf16_f32 %0, %1, %2" : "=v"(r) : "v"(lo), "v"(hi)); return r; }
; __device__ __forceinline__ unsigned dpp_xor1(unsigned v) { return (unsigned)__builtin_amdgcn_update_dpp(0, (int)v, 0xB1, 0xf, 0xf, false); }
; __device__ __forceinline__ float dpp_xor1(float v) { return __int_as_float(__builtin_amdgcn_update_dpp(0, __float_as_int(v), 0xB1, 0xf, 0xf, false)); }
; __device__ __forceinline__ int crow(int r, int hi) { return (r & 3) + 8 * (r >> 2) + 4 * hi; }
; template <int MODE, int VW>
; __device__ __forceinline__ void attn_unit_s(const AttnP& P, char* lds, const int tid) {
;     ...
;         for (int hv = 0; hv < VW; ++hv) {
; #pragma unroll
;             for (int d0 = 0; d0 < 4; ++d0)
; #pragma unroll
;                 for (int rp = 0; rp < 8; ++rp) { const int r = 2 * rp;
;                     const float a = o[hv * 4 + d0][r] * rli[r], bb = o[hv * 4 + d0][r + 1] * rli[r + 1];
;                     const float t = odd ? a : bb; const float rcv = dpp_xor1(t);
;                     const unsigned w = odd ? cvt_pk_bf16(rcv, bb) : cvt_pk_bf16(a, rcv);
;                     *(unsigned*)(st + sbase + (crow(r, 0)) * 320 + d0 * 64) = w; }
.LBB0_332:
	s_or_b64 exec, exec, s[2:3]
	v_mul_f32_e32 v81, v90, v120
	v_mul_f32_e32 v83, v91, v121
	ds_write_b32 v112, v80 offset:5248
	v_cndmask_b32_e64 v80, v81, v83, s[0:1]
	s_nop 1
	v_mov_b32_dpp v82, v80 quad_perm:[1,0,3,2] row_mask:0xf bank_mask:0xf
	s_and_saveexec_b64 s[2:3], vcc
	s_xor_b64 s[2:3], exec, s[2:3]
	s_cbranch_execz .LBB0_334
	v_cvt_pk_bf16_f32 v80, v82, v83

; __device__ __forceinline__ unsigned cvt_pk_bf16(float lo, float hi) { unsigned r; asm volatile("v_cvt_pk_bf16_f32 %0, %1, %2" : "=v"(r) : "v"(lo), "v"(hi)); return r; }
; __device__ __forceinline__ unsigned dpp_xor1(unsigned v) { return (unsigned)__builtin_amdgcn_update_dpp(0, (int)v, 0xB1, 0xf, 0xf, false); }
; __device__ __forceinline__ float dpp_xor1(float v) { return __int_as_float(__builtin_amdgcn_update_dpp(0, __float_as_int(v), 0xB1, 0xf, 0xf, false)); }
; __device__ __forceinline__ int crow(int r, int hi) { return (r & 3) + 8 * (r >> 2) + 4 * hi; }
; template <int MODE, int VW>
; __device__ __forceinline__ void attn_unit_s(const AttnP& P, char* lds, const int tid) {
;     ...
;         for (int hv = 0; hv < VW; ++hv) {
; #pragma unroll
;             for (int d0 = 0; d0 < 4; ++d0)
; #pragma unroll
;                 for (int rp = 0; rp < 8; ++rp) { const int r = 2 * rp;
;                     const float a = o[hv * 4 + d0][r] * rli[r], bb = o[hv * 4 + d0][r + 1] * rli[r + 1];
;                     const float t = odd ? a : bb; const float rcv = dpp_xor1(t);
;                     const unsigned w = odd ? cvt_pk_bf16(rcv, bb) : cvt_pk_bf16(a, rcv);
;                     *(unsigned*)(st + sbase + (crow(r, 0)) * 320 + d0 * 64) = w; }
.LBB0_336:
	s_or_b64 exec, exec, s[2:3]
	v_mul_f32_e32 v81, v92, v122
	v_mul_f32_e32 v83, v93, v123
	ds_write_b32 v112, v80 offset:5888
	v_cndmask_b32_e64 v80, v81, v83, s[0:1]
	s_nop 1
	v_mov_b32_dpp v82, v80 quad_perm:[1,0,3,2] row_mask:0xf bank_mask:0xf
	s_and_saveexec_b64 s[2:3], vcc
	s_xor_b64 s[2:3], exec, s[2:3]
	s_cbranch_execz .LBB0_338
	v_cvt_pk_bf16_f32 v80, v82, v83

; __device__ __forceinline__ unsigned cvt_pk_bf16(float lo, float hi) { unsigned r; asm volatile("v_cvt_pk_bf16_f32 %0, %1, %2" : "=v"(r) : "v"(lo), "v"(hi)); return r; }
; __device__ __forceinline__ unsigned dpp_xor1(unsigned v) { return (unsigned)__builtin_amdgcn_update_dpp(0, (int)v, 0xB1, 0xf, 0xf, false); }
; __device__ __forceinline__ float dpp_xor1(float v) { return __int_as_float(__builtin_amdgcn_update_dpp(0, __float_as_int(v), 0xB1, 0xf, 0xf, false)); }
; __device__ __forceinline__ int crow(int r, int hi) { return (r & 3) + 8 * (r >> 2) + 4 * hi; }
; template <int MODE, int VW>
; __device__ __forceinline__ void attn_unit_s(const AttnP& P, char* lds, const int tid) {
;     ...
;         for (int hv = 0; hv < VW; ++hv) {
; #pragma unroll
;             for (int d0 = 0; d0 < 4; ++d0)
; #pragma unroll
;                 for (int rp = 0; rp < 8; ++rp) { const int r = 2 * rp;
;                     const float a = o[hv * 4 + d0][r] * rli[r], bb = o[hv * 4 + d0][r + 1] * rli[r + 1];
;                     const float t = odd ? a : bb; const float rcv = dpp_xor1(t);
;                     const unsigned w = odd ? cvt_pk_bf16(rcv, bb) : cvt_pk_bf16(a, rcv);
;                     *(unsigned*)(st + sbase + (crow(r, 0)) * 320 + d0 * 64) = w; }
.LBB0_340:
	s_or_b64 exec, exec, s[2:3]
	v_mul_f32_e32 v81, v94, v124
	v_mul_f32_e32 v83, v95, v125
	ds_write_b32 v112, v80 offset:7808
	v_cndmask_b32_e64 v80, v81, v83, s[0:1]
	s_nop 1
	v_mov_b32_dpp v82, v80 quad_perm:[1,0,3,2] row_mask:0xf bank_mask:0xf
	s_and_saveexec_b64 s[2:3], vcc
	s_xor_b64 s[2:3], exec, s[2:3]
	s_cbranch_execz .LBB0_342
	v_cvt_pk_bf16_f32 v80, v82, v83

; __device__ __forceinline__ unsigned cvt_pk_bf16(float lo, float hi) { unsigned r; asm volatile("v_cvt_pk_bf16_f32 %0, %1, %2" : "=v"(r) : "v"(lo), "v"(hi)); return r; }
; __device__ __forceinline__ unsigned dpp_xor1(unsigned v) { return (unsigned)__builtin_amdgcn_update_dpp(0, (int)v, 0xB1, 0xf, 0xf, false); }
; __device__ __forceinline__ float dpp_xor1(float v) { return __int_as_float(__builtin_amdgcn_update_dpp(0, __float_as_int(v), 0xB1, 0xf, 0xf, false)); }
; __device__ __forceinline__ int crow(int r, int hi) { return (r & 3) + 8 * (r >> 2) + 4 * hi; }
; template <int MODE, int VW>
; __device__ __forceinline__ void attn_unit_s(const AttnP& P, char* lds, const int tid) {
;     ...
;         for (int hv = 0; hv < VW; ++hv) {
; #pragma unroll
;             for (int d0 = 0; d0 < 4; ++d0)
; #pragma unroll
;                 for (int rp = 0; rp < 8; ++rp) { const int r = 2 * rp;
;                     const float a = o[hv * 4 + d0][r] * rli[r], bb = o[hv * 4 + d0][r + 1] * rli[r + 1];
;                     const float t = odd ? a : bb; const float rcv = dpp_xor1(t);
;                     const unsigned w = odd ? cvt_pk_bf16(rcv, bb) : cvt_pk_bf16(a, rcv);
;                     *(unsigned*)(st + sbase + (crow(r, 0)) * 320 + d0 * 64) = w; }
.LBB0_344:
	s_or_b64 exec, exec, s[2:3]
	ds_write_b32 v112, v80 offset:8448
	v_mul_f32_e32 v80, v64, v140
	v_mul_f32_e32 v81, v65, v141
	v_cndmask_b32_e64 v64, v80, v81, s[0:1]
	s_nop 1
	v_mov_b32_dpp v65, v64 quad_perm:[1,0,3,2] row_mask:0xf bank_mask:0xf
	s_and_saveexec_b64 s[2:3], vcc
	s_xor_b64 s[2:3], exec, s[2:3]
	s_cbranch_execz .LBB0_346
	v_cvt_pk_bf16_f32 v64, v65, v81

; __device__ __forceinline__ unsigned cvt_pk_bf16(float lo, float hi) { unsigned r; asm volatile("v_cvt_pk_bf16_f32 %0, %1, %2" : "=v"(r) : "v"(lo), "v"(hi)); return r; }
; __device__ __forceinline__ unsigned dpp_xor1(unsigned v) { return (unsigned)__builtin_amdgcn_update_dpp(0, (int)v, 0xB1, 0xf, 0xf, false); }
; __device__ __forceinline__ float dpp_xor1(float v) { return __int_as_float(__builtin_amdgcn_update_dpp(0, __float_as_int(v), 0xB1, 0xf, 0xf, false)); }
; __device__ __forceinline__ int crow(int r, int hi) { return (r & 3) + 8 * (r >> 2) + 4 * hi; }
; template <int MODE, int VW>
; __device__ __forceinline__ void attn_unit_s(const AttnP& P, char* lds, const int tid) {
;     ...
;         for (int hv = 0; hv < VW; ++hv) {
; #pragma unroll
;             for (int d0 = 0; d0 < 4; ++d0)
; #pragma unroll
;                 for (int rp = 0; rp < 8; ++rp) { const int r = 2 * rp;
;                     const float a = o[hv * 4 + d0][r] * rli[r], bb = o[hv * 4 + d0][r + 1] * rli[r + 1];
;                     const float t = odd ? a : bb; const float rcv = dpp_xor1(t);
;                     const unsigned w = odd ? cvt_pk_bf16(rcv, bb) : cvt_pk_bf16(a, rcv);
;                     *(unsigned*)(st + sbase + (crow(r, 0)) * 320 + d0 * 64) = w; }
.LBB0_348:
	s_or_b64 exec, exec, s[2:3]
	v_mul_f32_e32 v65, v66, v113
	v_mul_f32_e32 v67, v67, v142
	ds_write_b32 v112, v64 offset:192
	v_cndmask_b32_e64 v64, v65, v67, s[0:1]
	s_nop 1
	v_mov_b32_dpp v66, v64 quad_perm:[1,0,3,2] row_mask:0xf bank_mask:0xf
	s_and_saveexec_b64 s[2:3], vcc
	s_xor_b64 s[2:3], exec, s[2:3]
	s_cbranch_execz .LBB0_350
	v_cvt_pk_bf16_f32 v64, v66, v67

; __device__ __forceinline__ unsigned cvt_pk_bf16(float lo, float hi) { unsigned r; asm volatile("v_cvt_pk_bf16_f32 %0, %1, %2" : "=v"(r) : "v"(lo), "v"(hi)); return r; }
; __device__ __forceinline__ unsigned dpp_xor1(unsigned v) { return (unsigned)__builtin_amdgcn_update_dpp(0, (int)v, 0xB1, 0xf, 0xf, false); }
; __device__ __forceinline__ float dpp_xor1(float v) { return __int_as_float(__builtin_amdgcn_update_dpp(0, __float_as_int(v), 0xB1, 0xf, 0xf, false)); }
; __device__ __forceinline__ int crow(int r, int hi) { return (r & 3) + 8 * (r >> 2) + 4 * hi; }
; template <int MODE, int VW>
; __device__ __forceinline__ void attn_unit_s(const AttnP& P, char* lds, const int tid) {
;     ...
;         for (int hv = 0; hv < VW; ++hv) {
; #pragma unroll
;             for (int d0 = 0; d0 < 4; ++d0)
; #pragma unroll
;                 for (int rp = 0; rp < 8; ++rp) { const int r = 2 * rp;
;                     const float a = o[hv * 4 + d0][r] * rli[r], bb = o[hv * 4 + d0][r + 1] * rli[r + 1];
;                     const float t = odd ? a : bb; const float rcv = dpp_xor1(t);
;                     const unsigned w = odd ? cvt_pk_bf16(rcv, bb) : cvt_pk_bf16(a, rcv);
;                     *(unsigned*)(st + sbase + (crow(r, 0)) * 320 + d0 * 64) = w; }
.LBB0_352:
	s_or_b64 exec, exec, s[2:3]
	v_mul_f32_e32 v65, v68, v114
	v_mul_f32_e32 v67, v69, v115
	ds_write_b32 v112, v64 offset:832
	v_cndmask_b32_e64 v64, v65, v67, s[0:1]
	s_nop 1
	v_mov_b32_dpp v66, v64 quad_perm:[1,0,3,2] row_mask:0xf bank_mask:0xf
	s_and_saveexec_b64 s[2:3], vcc
	s_xor_b64 s[2:3], exec, s[2:3]
	s_cbranch_execz .LBB0_354
	v_cvt_pk_bf16_f32 v64, v66, v67

; __device__ __forceinline__ unsigned cvt_pk_bf16(float lo, float hi) { unsigned r; asm volatile("v_cvt_pk_bf16_f32 %0, %1, %2" : "=v"(r) : "v"(lo), "v"(hi)); return r; }
; __device__ __forceinline__ unsigned dpp_xor1(unsigned v) { return (unsigned)__builtin_amdgcn_update_dpp(0, (int)v, 0xB1, 0xf, 0xf, false); }
; __device__ __forceinline__ float dpp_xor1(float v) { return __int_as_float(__builtin_amdgcn_update_dpp(0, __float_as_int(v), 0xB1, 0xf, 0xf, false)); }
; __device__ __forceinline__ int crow(int r, int hi) { return (r & 3) + 8 * (r >> 2) + 4 * hi; }
; template <int MODE, int VW>
; __device__ __forceinline__ void attn_unit_s(const AttnP& P, char* lds, const int tid) {
;     ...
;         for (int hv = 0; hv < VW; ++hv) {
; #pragma unroll
;             for (int d0 = 0; d0 < 4; ++d0)
; #pragma unroll
;                 for (int rp = 0; rp < 8; ++rp) { const int r = 2 * rp;
;                     const float a = o[hv * 4 + d0][r] * rli[r], bb = o[hv * 4 + d0][r + 1] * rli[r + 1];
;                     const float t = odd ? a : bb; const float rcv = dpp_xor1(t);
;                     const unsigned w = odd ? cvt_pk_bf16(rcv, bb) : cvt_pk_bf16(a, rcv);
;                     *(unsigned*)(st + sbase + (crow(r, 0)) * 320 + d0 * 64) = w; }
.LBB0_356:
	s_or_b64 exec, exec, s[2:3]
	v_mul_f32_e32 v65, v70, v116
	v_mul_f32_e32 v67, v71, v117
	ds_write_b32 v112, v64 offset:2752
	v_cndmask_b32_e64 v64, v65, v67, s[0:1]
	s_nop 1
	v_mov_b32_dpp v66, v64 quad_perm:[1,0,3,2] row_mask:0xf bank_mask:0xf
	s_and_saveexec_b64 s[2:3], vcc
	s_xor_b64 s[2:3], exec, s[2:3]
	s_cbranch_execz .LBB0_358
	v_cvt_pk_bf16_f32 v64, v66, v67

; __device__ __forceinline__ unsigned cvt_pk_bf16(float lo, float hi) { unsigned r; asm volatile("v_cvt_pk_bf16_f32 %0, %1, %2" : "=v"(r) : "v"(lo), "v"(hi)); return r; }
; __device__ __forceinline__ unsigned dpp_xor1(unsigned v) { return (unsigned)__builtin_amdgcn_update_dpp(0, (int)v, 0xB1, 0xf, 0xf, false); }
; __device__ __forceinline__ float dpp_xor1(float v) { return __int_as_float(__builtin_amdgcn_update_dpp(0, __float_as_int(v), 0xB1, 0xf, 0xf, false)); }
; __device__ __forceinline__ int crow(int r, int hi) { return (r & 3) + 8 * (r >> 2) + 4 * hi; }
; template <int MODE, int VW>
; __device__ __forceinline__ void attn_unit_s(const AttnP& P, char* lds, const int tid) {
;     ...
;         for (int hv = 0; hv < VW; ++hv) {
; #pragma unroll
;             for (int d0 = 0; d0 < 4; ++d0)
; #pragma unroll
;                 for (int rp = 0; rp < 8; ++rp) { const int r = 2 * rp;
;                     const float a = o[hv * 4 + d0][r] * rli[r], bb = o[hv * 4 + d0][r + 1] * rli[r + 1];
;                     const float t = odd ? a : bb; const float rcv = dpp_xor1(t);
;                     const unsigned w = odd ? cvt_pk_bf16(rcv, bb) : cvt_pk_bf16(a, rcv);
;                     *(unsigned*)(st + sbase + (crow(r, 0)) * 320 + d0 * 64) = w; }
.LBB0_360:
	s_or_b64 exec, exec, s[2:3]
	v_mul_f32_e32 v65, v72, v118
	v_mul_f32_e32 v67, v73, v119
	ds_write_b32 v112, v64 offset:3392
	v_cndmask_b32_e64 v64, v65, v67, s[0:1]
	s_nop 1
	v_mov_b32_dpp v66, v64 quad_perm:[1,0,3,2] row_mask:0xf bank_mask:0xf
	s_and_saveexec_b64 s[2:3], vcc
	s_xor_b64 s[2:3], exec, s[2:3]
	s_cbranch_execz .LBB0_362
	v_cvt_pk_bf16_f32 v64, v66, v67

; __device__ __forceinline__ unsigned cvt_pk_bf16(float lo, float hi) { unsigned r; asm volatile("v_cvt_pk_bf16_f32 %0, %1, %2" : "=v"(r) : "v"(lo), "v"(hi)); return r; }
; __device__ __forceinline__ unsigned dpp_xor1(unsigned v) { return (unsigned)__builtin_amdgcn_update_dpp(0, (int)v, 0xB1, 0xf, 0xf, false); }
; __device__ __forceinline__ float dpp_xor1(float v) { return __int_as_float(__builtin_amdgcn_update_dpp(0, __float_as_int(v), 0xB1, 0xf, 0xf, false)); }
; __device__ __forceinline__ int crow(int r, int hi) { return (r & 3) + 8 * (r >> 2) + 4 * hi; }
; template <int MODE, int VW>
; __device__ __forceinline__ void attn_unit_s(const AttnP& P, char* lds, const int tid) {
;     ...
;         for (int hv = 0; hv < VW; ++hv) {
; #pragma unroll
;             for (int d0 = 0; d0 < 4; ++d0)
; #pragma unroll
;                 for (int rp = 0; rp < 8; ++rp) { const int r = 2 * rp;
;                     const float a = o[hv * 4 + d0][r] * rli[r], bb = o[hv * 4 + d0][r + 1] * rli[r + 1];
;                     const float t = odd ? a : bb; const float rcv = dpp_xor1(t);
;                     const unsigned w = odd ? cvt_pk_bf16(rcv, bb) : cvt_pk_bf16(a, rcv);
;                     *(unsigned*)(st + sbase + (crow(r, 0)) * 320 + d0 * 64) = w; }
.LBB0_364:
	s_or_b64 exec, exec, s[2:3]
	v_mul_f32_e32 v65, v74, v120
	v_mul_f32_e32 v67, v75, v121
	ds_write_b32 v112, v64 offset:5312
	v_cndmask_b32_e64 v64, v65, v67, s[0:1]
	s_nop 1
	v_mov_b32_dpp v66, v64 quad_perm:[1,0,3,2] row_mask:0xf bank_mask:0xf
	s_and_saveexec_b64 s[2:3], vcc
	s_xor_b64 s[2:3], exec, s[2:3]
	s_cbranch_execz .LBB0_366
	v_cvt_pk_bf16_f32 v64, v66, v67

; __device__ __forceinline__ unsigned cvt_pk_bf16(float lo, float hi) { unsigned r; asm volatile("v_cvt_pk_bf16_f32 %0, %1, %2" : "=v"(r) : "v"(lo), "v"(hi)); return r; }
; __device__ __forceinline__ unsigned dpp_xor1(unsigned v) { return (unsigned)__builtin_amdgcn_update_dpp(0, (int)v, 0xB1, 0xf, 0xf, false); }
; __device__ __forceinline__ float dpp_xor1(float v) { return __int_as_float(__builtin_amdgcn_update_dpp(0, __float_as_int(v), 0xB1, 0xf, 0xf, false)); }
; __device__ __forceinline__ int crow(int r, int hi) { return (r & 3) + 8 * (r >> 2) + 4 * hi; }
; template <int MODE, int VW>
; __device__ __forceinline__ void attn_unit_s(const AttnP& P, char* lds, const int tid) {
;     ...
;         for (int hv = 0; hv < VW; ++hv) {
; #pragma unroll
;             for (int d0 = 0; d0 < 4; ++d0)
; #pragma unroll
;                 for (int rp = 0; rp < 8; ++rp) { const int r = 2 * rp;
;                     const float a = o[hv * 4 + d0][r] * rli[r], bb = o[hv * 4 + d0][r + 1] * rli[r + 1];
;                     const float t = odd ? a : bb; const float rcv = dpp_xor1(t);
;                     const unsigned w = odd ? cvt_pk_bf16(rcv, bb) : cvt_pk_bf16(a, rcv);
;                     *(unsigned*)(st + sbase + (crow(r, 0)) * 320 + d0 * 64) = w; }
.LBB0_368:
	s_or_b64 exec, exec, s[2:3]
	v_mul_f32_e32 v65, v76, v122
	v_mul_f32_e32 v67, v77, v123
	ds_write_b32 v112, v64 offset:5952
	v_cndmask_b32_e64 v64, v65, v67, s[0:1]
	s_nop 1
	v_mov_b32_dpp v66, v64 quad_perm:[1,0,3,2] row_mask:0xf bank_mask:0xf
	s_and_saveexec_b64 s[2:3], vcc
	s_xor_b64 s[2:3], exec, s[2:3]
	s_cbranch_execz .LBB0_370
	v_cvt_pk_bf16_f32 v64, v66, v67

; __device__ __forceinline__ unsigned cvt_pk_bf16(float lo, float hi) { unsigned r; asm volatile("v_cvt_pk_bf16_f32 %0, %1, %2" : "=v"(r) : "v"(lo), "v"(hi)); return r; }
; __device__ __forceinline__ unsigned dpp_xor1(unsigned v) { return (unsigned)__builtin_amdgcn_update_dpp(0, (int)v, 0xB1, 0xf, 0xf, false); }
; __device__ __forceinline__ float dpp_xor1(float v) { return __int_as_float(__builtin_amdgcn_update_dpp(0, __float_as_int(v), 0xB1, 0xf, 0xf, false)); }
; __device__ __forceinline__ int crow(int r, int hi) { return (r & 3) + 8 * (r >> 2) + 4 * hi; }
; template <int MODE, int VW>
; __device__ __forceinline__ void attn_unit_s(const AttnP& P, char* lds, const int tid) {
;     ...
;         for (int hv = 0; hv < VW; ++hv) {
; #pragma unroll
;             for (int d0 = 0; d0 < 4; ++d0)
; #pragma unroll
;                 for (int rp = 0; rp < 8; ++rp) { const int r = 2 * rp;
;                     const float a = o[hv * 4 + d0][r] * rli[r], bb = o[hv * 4 + d0][r + 1] * rli[r + 1];
;                     const float t = odd ? a : bb; const float rcv = dpp_xor1(t);
;                     const unsigned w = odd ? cvt_pk_bf16(rcv, bb) : cvt_pk_bf16(a, rcv);
;                     *(unsigned*)(st + sbase + (crow(r, 0)) * 320 + d0 * 64) = w; }
.LBB0_372:
	s_or_b64 exec, exec, s[2:3]
	v_mul_f32_e32 v65, v78, v124
	v_mul_f32_e32 v67, v79, v125
	ds_write_b32 v112, v64 offset:7872
	v_cndmask_b32_e64 v64, v65, v67, s[0:1]
	s_nop 1
	v_mov_b32_dpp v66, v64 quad_perm:[1,0,3,2] row_mask:0xf bank_mask:0xf
	s_and_saveexec_b64 s[2:3], vcc
	s_xor_b64 s[2:3], exec, s[2:3]
	s_cbranch_execz .LBB0_374
	v_cvt_pk_bf16_f32 v64, v66, v67

; __device__ __forceinline__ unsigned cvt_pk_bf16(float lo, float hi) { unsigned r; asm volatile("v_cvt_pk_bf16_f32 %0, %1, %2" : "=v"(r) : "v"(lo), "v"(hi)); return r; }
; __device__ __forceinline__ unsigned dpp_xor1(unsigned v) { return (unsigned)__builtin_amdgcn_update_dpp(0, (int)v, 0xB1, 0xf, 0xf, false); }
; __device__ __forceinline__ float dpp_xor1(float v) { return __int_as_float(__builtin_amdgcn_update_dpp(0, __float_as_int(v), 0xB1, 0xf, 0xf, false)); }
; __device__ __forceinline__ int crow(int r, int hi) { return (r & 3) + 8 * (r >> 2) + 4 * hi; }
; template <int MODE, int VW>
; __device__ __forceinline__ void attn_unit_s(const AttnP& P, char* lds, const int tid) {
;     ...
;             for (int d0 = 0; d0 < 4; ++d0)
; #pragma unroll
;                 for (int rp = 0; rp < 8; ++rp) { const int r = 2 * rp;
;                     const float a = o[hv * 4 + d0][r] * rli[r], bb = o[hv * 4 + d0][r + 1] * rli[r + 1];
;                     const float t = odd ? a : bb; const float rcv = dpp_xor1(t);
;                     const unsigned w = odd ? cvt_pk_bf16(rcv, bb) : cvt_pk_bf16(a, rcv);
;                     *(unsigned*)(st + sbase + (crow(r, 0)) * 320 + d0 * 64) = w; }
;             asm volatile("s_waitcnt lgkmcnt(0)" ::: "memory");
; #pragma unroll
;             for (int i = 0; i < 8; ++i) { const int chunk = i * 64 + lane, row = chunk >> 4, c16 = chunk & 15;
;                 const u32x4 v = *(const u32x4*)(st + row * 320 + c16 * 16);
;                 *(u32x4*)(Ow + (long)row * P.ldo + hv * 128 + c16 * 8) = v; }
.LBB0_376:
	s_or_b64 exec, exec, s[2:3]
	s_lshl_b64 s[2:3], s[6:7], 12
	s_lshl_b32 s5, s5, 14
	s_add_u32 s2, s2, s5
	s_addc_u32 s3, s3, 0
	s_or_b32 s2, s2, s56
	s_lshl_b64 s[2:3], s[2:3], 11
	v_readlane_b32 s6, v254, 25
	v_readlane_b32 s7, v254, 26
	s_add_u32 s2, s6, s2
	s_addc_u32 s3, s7, s3
	s_lshl_b32 s5, s49, 1
	v_lshlrev_b32_e32 v202, 4, v218
	s_add_u32 s5, s2, s5
	v_add_u32_e32 v80, s22, v202
	v_lshrrev_b32_e32 v81, 4, v161
	ds_write_b32 v112, v64 offset:8512
	s_addc_u32 s6, s3, 0
	s_ashr_i32 s49, s48, 31
	s_waitcnt lgkmcnt(0)
	v_mad_u32_u24 v88, v81, s73, v80
	s_lshl_b64 s[2:3], s[48:49], 11
	ds_read_b128 v[66:69], v88
	ds_read_b128 v[70:73], v88 offset:1280
	s_add_u32 s2, s5, s2
	s_addc_u32 s3, s6, s3
	v_lshl_add_u64 v[86:87], s[2:3], 0, v[202:203]
	v_lshlrev_b32_e32 v202, 11, v81
	v_lshl_add_u64 v[64:65], v[86:87], 0, v[202:203]
	s_waitcnt lgkmcnt(1)
	global_store_dwordx4 v[64:65], v[66:69], off
	ds_read_b128 v[82:85], v88 offset:7680
	s_nop 0
	v_or_b32_e32 v66, 0x2000, v202
	v_mov_b32_e32 v67, v203
	v_lshl_add_u64 v[68:69], v[86:87], 0, v[66:67]
	s_waitcnt lgkmcnt(1)
	global_store_dwordx4 v[68:69], v[70:73], off
	ds_read_b128 v[72:75], v88 offset:2560
	v_or_b32_e32 v66, 0x4000, v202
	v_lshl_add_u64 v[70:71], v[86:87], 0, v[66:67]
	v_or_b32_e32 v66, 0x6000, v202
	s_waitcnt lgkmcnt(0)
	global_store_dwordx4 v[70:71], v[72:75], off
	ds_read_b128 v[74:77], v88 offset:3840
	s_nop 0
	v_lshl_add_u64 v[72:73], v[86:87], 0, v[66:67]
	v_or_b32_e32 v66, 0x8000, v202
	v_lshl_add_u64 v[66:67], v[86:87], 0, v[66:67]
	s_waitcnt lgkmcnt(0)
	global_store_dwordx4 v[72:73], v[74:77], off
	ds_read_b128 v[74:77], v88 offset:5120
	s_waitcnt lgkmcnt(0)
	global_store_dwordx4 v[66:67], v[74:77], off
	ds_read_b128 v[76:79], v88 offset:6400
	s_nop 0
	v_or_b32_e32 v74, 0xa000, v202
	v_mov_b32_e32 v75, v203
	v_lshl_add_u64 v[74:75], v[86:87], 0, v[74:75]
	s_waitcnt lgkmcnt(0)
	global_store_dwordx4 v[74:75], v[76:79], off
	s_nop 1
	v_or_b32_e32 v76, 0xc000, v202
	v_mov_b32_e32 v77, v203
	v_lshl_add_u64 v[76:77], v[86:87], 0, v[76:77]
	global_store_dwordx4 v[76:77], v[82:85], off
	ds_read_b128 v[82:85], v88 offset:8960
	v_or_b32_e32 v202, 0xe000, v202
	v_lshl_add_u64 v[78:79], v[86:87], 0, v[202:203]
	s_waitcnt lgkmcnt(0)
	global_store_dwordx4 v[78:79], v[82:85], off
	s_waitcnt lgkmcnt(0)
	s_nop 1
	v_mul_f32_e32 v82, v48, v140
	v_mul_f32_e32 v83, v49, v141
	v_cndmask_b32_e64 v48, v82, v83, s[0:1]
	s_nop 1
	v_mov_b32_dpp v49, v48 quad_perm:[1,0,3,2] row_mask:0xf bank_mask:0xf
	s_and_saveexec_b64 s[2:3], vcc
	s_xor_b64 s[2:3], exec, s[2:3]
	s_cbranch_execz .LBB0_378
	v_cvt_pk_bf16_f32 v48, v49, v83

; __device__ __forceinline__ unsigned cvt_pk_bf16(float lo, float hi) { unsigned r; asm volatile("v_cvt_pk_bf16_f32 %0, %1, %2" : "=v"(r) : "v"(lo), "v"(hi)); return r; }
; __device__ __forceinline__ unsigned dpp_xor1(unsigned v) { return (unsigned)__builtin_amdgcn_update_dpp(0, (int)v, 0xB1, 0xf, 0xf, false); }
; __device__ __forceinline__ float dpp_xor1(float v) { return __int_as_float(__builtin_amdgcn_update_dpp(0, __float_as_int(v), 0xB1, 0xf, 0xf, false)); }
; __device__ __forceinline__ int crow(int r, int hi) { return (r & 3) + 8 * (r >> 2) + 4 * hi; }
; template <int MODE, int VW>
; __device__ __forceinline__ void attn_unit_s(const AttnP& P, char* lds, const int tid) {
;     ...
;         for (int hv = 0; hv < VW; ++hv) {
; #pragma unroll
;             for (int d0 = 0; d0 < 4; ++d0)
; #pragma unroll
;                 for (int rp = 0; rp < 8; ++rp) { const int r = 2 * rp;
;                     const float a = o[hv * 4 + d0][r] * rli[r], bb = o[hv * 4 + d0][r + 1] * rli[r + 1];
;                     const float t = odd ? a : bb; const float rcv = dpp_xor1(t);
;                     const unsigned w = odd ? cvt_pk_bf16(rcv, bb) : cvt_pk_bf16(a, rcv);
;                     *(unsigned*)(st + sbase + (crow(r, 0)) * 320 + d0 * 64) = w; }
.LBB0_380:
	s_or_b64 exec, exec, s[2:3]
	v_mul_f32_e32 v49, v50, v113
	v_mul_f32_e32 v51, v51, v142
	ds_write_b32 v112, v48
	v_cndmask_b32_e64 v48, v49, v51, s[0:1]
	s_nop 1
	v_mov_b32_dpp v50, v48 quad_perm:[1,0,3,2] row_mask:0xf bank_mask:0xf
	s_and_saveexec_b64 s[2:3], vcc
	s_xor_b64 s[2:3], exec, s[2:3]
	s_cbranch_execz .LBB0_382
	v_cvt_pk_bf16_f32 v48, v50, v51

; __device__ __forceinline__ unsigned cvt_pk_bf16(float lo, float hi) { unsigned r; asm volatile("v_cvt_pk_bf16_f32 %0, %1, %2" : "=v"(r) : "v"(lo), "v"(hi)); return r; }
; __device__ __forceinline__ unsigned dpp_xor1(unsigned v) { return (unsigned)__builtin_amdgcn_update_dpp(0, (int)v, 0xB1, 0xf, 0xf, false); }
; __device__ __forceinline__ float dpp_xor1(float v) { return __int_as_float(__builtin_amdgcn_update_dpp(0, __float_as_int(v), 0xB1, 0xf, 0xf, false)); }
; __device__ __forceinline__ int crow(int r, int hi) { return (r & 3) + 8 * (r >> 2) + 4 * hi; }
; template <int MODE, int VW>
; __device__ __forceinline__ void attn_unit_s(const AttnP& P, char* lds, const int tid) {
;     ...
;         for (int hv = 0; hv < VW; ++hv) {
; #pragma unroll
;             for (int d0 = 0; d0 < 4; ++d0)
; #pragma unroll
;                 for (int rp = 0; rp < 8; ++rp) { const int r = 2 * rp;
;                     const float a = o[hv * 4 + d0][r] * rli[r], bb = o[hv * 4 + d0][r + 1] * rli[r + 1];
;                     const float t = odd ? a : bb; const float rcv = dpp_xor1(t);
;                     const unsigned w = odd ? cvt_pk_bf16(rcv, bb) : cvt_pk_bf16(a, rcv);
;                     *(unsigned*)(st + sbase + (crow(r, 0)) * 320 + d0 * 64) = w; }
.LBB0_384:
	s_or_b64 exec, exec, s[2:3]
	v_mul_f32_e32 v49, v52, v114
	v_mul_f32_e32 v51, v53, v115
	ds_write_b32 v112, v48 offset:640
	v_cndmask_b32_e64 v48, v49, v51, s[0:1]
	s_nop 1
	v_mov_b32_dpp v50, v48 quad_perm:[1,0,3,2] row_mask:0xf bank_mask:0xf
	s_and_saveexec_b64 s[2:3], vcc
	s_xor_b64 s[2:3], exec, s[2:3]
	s_cbranch_execz .LBB0_386
	v_cvt_pk_bf16_f32 v48, v50, v51

; __device__ __forceinline__ unsigned cvt_pk_bf16(float lo, float hi) { unsigned r; asm volatile("v_cvt_pk_bf16_f32 %0, %1, %2" : "=v"(r) : "v"(lo), "v"(hi)); return r; }
; __device__ __forceinline__ unsigned dpp_xor1(unsigned v) { return (unsigned)__builtin_amdgcn_update_dpp(0, (int)v, 0xB1, 0xf, 0xf, false); }
; __device__ __forceinline__ float dpp_xor1(float v) { return __int_as_float(__builtin_amdgcn_update_dpp(0, __float_as_int(v), 0xB1, 0xf, 0xf, false)); }
; __device__ __forceinline__ int crow(int r, int hi) { return (r & 3) + 8 * (r >> 2) + 4 * hi; }
; template <int MODE, int VW>
; __device__ __forceinline__ void attn_unit_s(const AttnP& P, char* lds, const int tid) {
;     ...
;         for (int hv = 0; hv < VW; ++hv) {
; #pragma unroll
;             for (int d0 = 0; d0 < 4; ++d0)
; #pragma unroll
;                 for (int rp = 0; rp < 8; ++rp) { const int r = 2 * rp;
;                     const float a = o[hv * 4 + d0][r] * rli[r], bb = o[hv * 4 + d0][r + 1] * rli[r + 1];
;                     const float t = odd ? a : bb; const float rcv = dpp_xor1(t);
;                     const unsigned w = odd ? cvt_pk_bf16(rcv, bb) : cvt_pk_bf16(a, rcv);
;                     *(unsigned*)(st + sbase + (crow(r, 0)) * 320 + d0 * 64) = w; }
.LBB0_388:
	s_or_b64 exec, exec, s[2:3]
	v_mul_f32_e32 v49, v54, v116
	v_mul_f32_e32 v51, v55, v117
	ds_write_b32 v112, v48 offset:2560
	v_cndmask_b32_e64 v48, v49, v51, s[0:1]
	s_nop 1
	v_mov_b32_dpp v50, v48 quad_perm:[1,0,3,2] row_mask:0xf bank_mask:0xf
	s_and_saveexec_b64 s[2:3], vcc
	s_xor_b64 s[2:3], exec, s[2:3]
	s_cbranch_execz .LBB0_390
	v_cvt_pk_bf16_f32 v48, v50, v51

; __device__ __forceinline__ unsigned cvt_pk_bf16(float lo, float hi) { unsigned r; asm volatile("v_cvt_pk_bf16_f32 %0, %1, %2" : "=v"(r) : "v"(lo), "v"(hi)); return r; }
; __device__ __forceinline__ unsigned dpp_xor1(unsigned v) { return (unsigned)__builtin_amdgcn_update_dpp(0, (int)v, 0xB1, 0xf, 0xf, false); }
; __device__ __forceinline__ float dpp_xor1(float v) { return __int_as_float(__builtin_amdgcn_update_dpp(0, __float_as_int(v), 0xB1, 0xf, 0xf, false)); }
; __device__ __forceinline__ int crow(int r, int hi) { return (r & 3) + 8 * (r >> 2) + 4 * hi; }
; template <int MODE, int VW>
; __device__ __forceinline__ void attn_unit_s(const AttnP& P, char* lds, const int tid) {
;     ...
;         for (int hv = 0; hv < VW; ++hv) {
; #pragma unroll
;             for (int d0 = 0; d0 < 4; ++d0)
; #pragma unroll
;                 for (int rp = 0; rp < 8; ++rp) { const int r = 2 * rp;
;                     const float a = o[hv * 4 + d0][r] * rli[r], bb = o[hv * 4 + d0][r + 1] * rli[r + 1];
;                     const float t = odd ? a : bb; const float rcv = dpp_xor1(t);
;                     const unsigned w = odd ? cvt_pk_bf16(rcv, bb) : cvt_pk_bf16(a, rcv);
;                     *(unsigned*)(st + sbase + (crow(r, 0)) * 320 + d0 * 64) = w; }
.LBB0_392:
	s_or_b64 exec, exec, s[2:3]
	v_mul_f32_e32 v49, v56, v118
	v_mul_f32_e32 v51, v57, v119
	ds_write_b32 v112, v48 offset:3200
	v_cndmask_b32_e64 v48, v49, v51, s[0:1]
	s_nop 1
	v_mov_b32_dpp v50, v48 quad_perm:[1,0,3,2] row_mask:0xf bank_mask:0xf
	s_and_saveexec_b64 s[2:3], vcc
	s_xor_b64 s[2:3], exec, s[2:3]
	s_cbranch_execz .LBB0_394
	v_cvt_pk_bf16_f32 v48, v50, v51

; __device__ __forceinline__ unsigned cvt_pk_bf16(float lo, float hi) { unsigned r; asm volatile("v_cvt_pk_bf16_f32 %0, %1, %2" : "=v"(r) : "v"(lo), "v"(hi)); return r; }
; __device__ __forceinline__ unsigned dpp_xor1(unsigned v) { return (unsigned)__builtin_amdgcn_update_dpp(0, (int)v, 0xB1, 0xf, 0xf, false); }
; __device__ __forceinline__ float dpp_xor1(float v) { return __int_as_float(__builtin_amdgcn_update_dpp(0, __float_as_int(v), 0xB1, 0xf, 0xf, false)); }
; __device__ __forceinline__ int crow(int r, int hi) { return (r & 3) + 8 * (r >> 2) + 4 * hi; }
; template <int MODE, int VW>
; __device__ __forceinline__ void attn_unit_s(const AttnP& P, char* lds, const int tid) {
;     ...
;         for (int hv = 0; hv < VW; ++hv) {
; #pragma unroll
;             for (int d0 = 0; d0 < 4; ++d0)
; #pragma unroll
;                 for (int rp = 0; rp < 8; ++rp) { const int r = 2 * rp;
;                     const float a = o[hv * 4 + d0][r] * rli[r], bb = o[hv * 4 + d0][r + 1] * rli[r + 1];
;                     const float t = odd ? a : bb; const float rcv = dpp_xor1(t);
;                     const unsigned w = odd ? cvt_pk_bf16(rcv, bb) : cvt_pk_bf16(a, rcv);
;                     *(unsigned*)(st + sbase + (crow(r, 0)) * 320 + d0 * 64) = w; }
.LBB0_396:
	s_or_b64 exec, exec, s[2:3]
	v_mul_f32_e32 v49, v58, v120
	v_mul_f32_e32 v51, v59, v121
	ds_write_b32 v112, v48 offset:5120
	v_cndmask_b32_e64 v48, v49, v51, s[0:1]
	s_nop 1
	v_mov_b32_dpp v50, v48 quad_perm:[1,0,3,2] row_mask:0xf bank_mask:0xf
	s_and_saveexec_b64 s[2:3], vcc
	s_xor_b64 s[2:3], exec, s[2:3]
	s_cbranch_execz .LBB0_398
	v_cvt_pk_bf16_f32 v48, v50, v51

; __device__ __forceinline__ unsigned cvt_pk_bf16(float lo, float hi) { unsigned r; asm volatile("v_cvt_pk_bf16_f32 %0, %1, %2" : "=v"(r) : "v"(lo), "v"(hi)); return r; }
; __device__ __forceinline__ unsigned dpp_xor1(unsigned v) { return (unsigned)__builtin_amdgcn_update_dpp(0, (int)v, 0xB1, 0xf, 0xf, false); }
; __device__ __forceinline__ float dpp_xor1(float v) { return __int_as_float(__builtin_amdgcn_update_dpp(0, __float_as_int(v), 0xB1, 0xf, 0xf, false)); }
; __device__ __forceinline__ int crow(int r, int hi) { return (r & 3) + 8 * (r >> 2) + 4 * hi; }
; template <int MODE, int VW>
; __device__ __forceinline__ void attn_unit_s(const AttnP& P, char* lds, const int tid) {
;     ...
;         for (int hv = 0; hv < VW; ++hv) {
; #pragma unroll
;             for (int d0 = 0; d0 < 4; ++d0)
; #pragma unroll
;                 for (int rp = 0; rp < 8; ++rp) { const int r = 2 * rp;
;                     const float a = o[hv * 4 + d0][r] * rli[r], bb = o[hv * 4 + d0][r + 1] * rli[r + 1];
;                     const float t = odd ? a : bb; const float rcv = dpp_xor1(t);
;                     const unsigned w = odd ? cvt_pk_bf16(rcv, bb) : cvt_pk_bf16(a, rcv);
;                     *(unsigned*)(st + sbase + (crow(r, 0)) * 320 + d0 * 64) = w; }
.LBB0_400:
	s_or_b64 exec, exec, s[2:3]
	v_mul_f32_e32 v49, v60, v122
	v_mul_f32_e32 v51, v61, v123
	ds_write_b32 v112, v48 offset:5760
	v_cndmask_b32_e64 v48, v49, v51, s[0:1]
	s_nop 1
	v_mov_b32_dpp v50, v48 quad_perm:[1,0,3,2] row_mask:0xf bank_mask:0xf
	s_and_saveexec_b64 s[2:3], vcc
	s_xor_b64 s[2:3], exec, s[2:3]
	s_cbranch_execz .LBB0_402
	v_cvt_pk_bf16_f32 v48, v50, v51

; __device__ __forceinline__ unsigned cvt_pk_bf16(float lo, float hi) { unsigned r; asm volatile("v_cvt_pk_bf16_f32 %0, %1, %2" : "=v"(r) : "v"(lo), "v"(hi)); return r; }
; __device__ __forceinline__ unsigned dpp_xor1(unsigned v) { return (unsigned)__builtin_amdgcn_update_dpp(0, (int)v, 0xB1, 0xf, 0xf, false); }
; __device__ __forceinline__ float dpp_xor1(float v) { return __int_as_float(__builtin_amdgcn_update_dpp(0, __float_as_int(v), 0xB1, 0xf, 0xf, false)); }
; __device__ __forceinline__ int crow(int r, int hi) { return (r & 3) + 8 * (r >> 2) + 4 * hi; }
; template <int MODE, int VW>
; __device__ __forceinline__ void attn_unit_s(const AttnP& P, char* lds, const int tid) {
;     ...
;         for (int hv = 0; hv < VW; ++hv) {
; #pragma unroll
;             for (int d0 = 0; d0 < 4; ++d0)
; #pragma unroll
;                 for (int rp = 0; rp < 8; ++rp) { const int r = 2 * rp;
;                     const float a = o[hv * 4 + d0][r] * rli[r], bb = o[hv * 4 + d0][r + 1] * rli[r + 1];
;                     const float t = odd ? a : bb; const float rcv = dpp_xor1(t);
;                     const unsigned w = odd ? cvt_pk_bf16(rcv, bb) : cvt_pk_bf16(a, rcv);
;                     *(unsigned*)(st + sbase + (crow(r, 0)) * 320 + d0 * 64) = w; }
.LBB0_404:
	s_or_b64 exec, exec, s[2:3]
	v_mul_f32_e32 v49, v62, v124
	v_mul_f32_e32 v51, v63, v125
	ds_write_b32 v112, v48 offset:7680
	v_cndmask_b32_e64 v48, v49, v51, s[0:1]
	s_nop 1
	v_mov_b32_dpp v50, v48 quad_perm:[1,0,3,2] row_mask:0xf bank_mask:0xf
	s_and_saveexec_b64 s[2:3], vcc
	s_xor_b64 s[2:3], exec, s[2:3]
	s_cbranch_execz .LBB0_406
	v_cvt_pk_bf16_f32 v48, v50, v51

; __device__ __forceinline__ unsigned cvt_pk_bf16(float lo, float hi) { unsigned r; asm volatile("v_cvt_pk_bf16_f32 %0, %1, %2" : "=v"(r) : "v"(lo), "v"(hi)); return r; }
; __device__ __forceinline__ unsigned dpp_xor1(unsigned v) { return (unsigned)__builtin_amdgcn_update_dpp(0, (int)v, 0xB1, 0xf, 0xf, false); }
; __device__ __forceinline__ float dpp_xor1(float v) { return __int_as_float(__builtin_amdgcn_update_dpp(0, __float_as_int(v), 0xB1, 0xf, 0xf, false)); }
; __device__ __forceinline__ int crow(int r, int hi) { return (r & 3) + 8 * (r >> 2) + 4 * hi; }
; template <int MODE, int VW>
; __device__ __forceinline__ void attn_unit_s(const AttnP& P, char* lds, const int tid) {
;     ...
;         for (int hv = 0; hv < VW; ++hv) {
; #pragma unroll
;             for (int d0 = 0; d0 < 4; ++d0)
; #pragma unroll
;                 for (int rp = 0; rp < 8; ++rp) { const int r = 2 * rp;
;                     const float a = o[hv * 4 + d0][r] * rli[r], bb = o[hv * 4 + d0][r + 1] * rli[r + 1];
;                     const float t = odd ? a : bb; const float rcv = dpp_xor1(t);
;                     const unsigned w = odd ? cvt_pk_bf16(rcv, bb) : cvt_pk_bf16(a, rcv);
;                     *(unsigned*)(st + sbase + (crow(r, 0)) * 320 + d0 * 64) = w; }
.LBB0_408:
	s_or_b64 exec, exec, s[2:3]
	ds_write_b32 v112, v48 offset:8320
	v_mul_f32_e32 v48, v32, v140
	v_mul_f32_e32 v49, v33, v141
	v_cndmask_b32_e64 v32, v48, v49, s[0:1]
	s_nop 1
	v_mov_b32_dpp v33, v32 quad_perm:[1,0,3,2] row_mask:0xf bank_mask:0xf
	s_and_saveexec_b64 s[2:3], vcc
	s_xor_b64 s[2:3], exec, s[2:3]
	s_cbranch_execz .LBB0_410
	v_cvt_pk_bf16_f32 v32, v33, v49

; __device__ __forceinline__ unsigned cvt_pk_bf16(float lo, float hi) { unsigned r; asm volatile("v_cvt_pk_bf16_f32 %0, %1, %2" : "=v"(r) : "v"(lo), "v"(hi)); return r; }
; __device__ __forceinline__ unsigned dpp_xor1(unsigned v) { return (unsigned)__builtin_amdgcn_update_dpp(0, (int)v, 0xB1, 0xf, 0xf, false); }
; __device__ __forceinline__ float dpp_xor1(float v) { return __int_as_float(__builtin_amdgcn_update_dpp(0, __float_as_int(v), 0xB1, 0xf, 0xf, false)); }
; __device__ __forceinline__ int crow(int r, int hi) { return (r & 3) + 8 * (r >> 2) + 4 * hi; }
; template <int MODE, int VW>
; __device__ __forceinline__ void attn_unit_s(const AttnP& P, char* lds, const int tid) {
;     ...
;         for (int hv = 0; hv < VW; ++hv) {
; #pragma unroll
;             for (int d0 = 0; d0 < 4; ++d0)
; #pragma unroll
;                 for (int rp = 0; rp < 8; ++rp) { const int r = 2 * rp;
;                     const float a = o[hv * 4 + d0][r] * rli[r], bb = o[hv * 4 + d0][r + 1] * rli[r + 1];
;                     const float t = odd ? a : bb; const float rcv = dpp_xor1(t);
;                     const unsigned w = odd ? cvt_pk_bf16(rcv, bb) : cvt_pk_bf16(a, rcv);
;                     *(unsigned*)(st + sbase + (crow(r, 0)) * 320 + d0 * 64) = w; }
.LBB0_412:
	s_or_b64 exec, exec, s[2:3]
	v_mul_f32_e32 v33, v34, v113
	v_mul_f32_e32 v35, v35, v142
	ds_write_b32 v112, v32 offset:64
	v_cndmask_b32_e64 v32, v33, v35, s[0:1]
	s_nop 1
	v_mov_b32_dpp v34, v32 quad_perm:[1,0,3,2] row_mask:0xf bank_mask:0xf
	s_and_saveexec_b64 s[2:3], vcc
	s_xor_b64 s[2:3], exec, s[2:3]
	s_cbranch_execz .LBB0_414
	v_cvt_pk_bf16_f32 v32, v34, v35

; __device__ __forceinline__ unsigned cvt_pk_bf16(float lo, float hi) { unsigned r; asm volatile("v_cvt_pk_bf16_f32 %0, %1, %2" : "=v"(r) : "v"(lo), "v"(hi)); return r; }
; __device__ __forceinline__ unsigned dpp_xor1(unsigned v) { return (unsigned)__builtin_amdgcn_update_dpp(0, (int)v, 0xB1, 0xf, 0xf, false); }
; __device__ __forceinline__ float dpp_xor1(float v) { return __int_as_float(__builtin_amdgcn_update_dpp(0, __float_as_int(v), 0xB1, 0xf, 0xf, false)); }
; __device__ __forceinline__ int crow(int r, int hi) { return (r & 3) + 8 * (r >> 2) + 4 * hi; }
; template <int MODE, int VW>
; __device__ __forceinline__ void attn_unit_s(const AttnP& P, char* lds, const int tid) {
;     ...
;         for (int hv = 0; hv < VW; ++hv) {
; #pragma unroll
;             for (int d0 = 0; d0 < 4; ++d0)
; #pragma unroll
;                 for (int rp = 0; rp < 8; ++rp) { const int r = 2 * rp;
;                     const float a = o[hv * 4 + d0][r] * rli[r], bb = o[hv * 4 + d0][r + 1] * rli[r + 1];
;                     const float t = odd ? a : bb; const float rcv = dpp_xor1(t);
;                     const unsigned w = odd ? cvt_pk_bf16(rcv, bb) : cvt_pk_bf16(a, rcv);
;                     *(unsigned*)(st + sbase + (crow(r, 0)) * 320 + d0 * 64) = w; }
.LBB0_416:
	s_or_b64 exec, exec, s[2:3]
	v_mul_f32_e32 v33, v36, v114
	v_mul_f32_e32 v35, v37, v115
	ds_write_b32 v112, v32 offset:704
	v_cndmask_b32_e64 v32, v33, v35, s[0:1]
	s_nop 1
	v_mov_b32_dpp v34, v32 quad_perm:[1,0,3,2] row_mask:0xf bank_mask:0xf
	s_and_saveexec_b64 s[2:3], vcc
	s_xor_b64 s[2:3], exec, s[2:3]
	s_cbranch_execz .LBB0_418
	v_cvt_pk_bf16_f32 v32, v34, v35

; __device__ __forceinline__ unsigned cvt_pk_bf16(float lo, float hi) { unsigned r; asm volatile("v_cvt_pk_bf16_f32 %0, %1, %2" : "=v"(r) : "v"(lo), "v"(hi)); return r; }
; __device__ __forceinline__ unsigned dpp_xor1(unsigned v) { return (unsigned)__builtin_amdgcn_update_dpp(0, (int)v, 0xB1, 0xf, 0xf, false); }
; __device__ __forceinline__ float dpp_xor1(float v) { return __int_as_float(__builtin_amdgcn_update_dpp(0, __float_as_int(v), 0xB1, 0xf, 0xf, false)); }
; __device__ __forceinline__ int crow(int r, int hi) { return (r & 3) + 8 * (r >> 2) + 4 * hi; }
; template <int MODE, int VW>
; __device__ __forceinline__ void attn_unit_s(const AttnP& P, char* lds, const int tid) {
;     ...
;         for (int hv = 0; hv < VW; ++hv) {
; #pragma unroll
;             for (int d0 = 0; d0 < 4; ++d0)
; #pragma unroll
;                 for (int rp = 0; rp < 8; ++rp) { const int r = 2 * rp;
;                     const float a = o[hv * 4 + d0][r] * rli[r], bb = o[hv * 4 + d0][r + 1] * rli[r + 1];
;                     const float t = odd ? a : bb; const float rcv = dpp_xor1(t);
;                     const unsigned w = odd ? cvt_pk_bf16(rcv, bb) : cvt_pk_bf16(a, rcv);
;                     *(unsigned*)(st + sbase + (crow(r, 0)) * 320 + d0 * 64) = w; }
.LBB0_420:
	s_or_b64 exec, exec, s[2:3]
	v_mul_f32_e32 v33, v38, v116
	v_mul_f32_e32 v35, v39, v117
	ds_write_b32 v112, v32 offset:2624
	v_cndmask_b32_e64 v32, v33, v35, s[0:1]
	s_nop 1
	v_mov_b32_dpp v34, v32 quad_perm:[1,0,3,2] row_mask:0xf bank_mask:0xf
	s_and_saveexec_b64 s[2:3], vcc
	s_xor_b64 s[2:3], exec, s[2:3]
	s_cbranch_execz .LBB0_422
	v_cvt_pk_bf16_f32 v32, v34, v35

; __device__ __forceinline__ unsigned cvt_pk_bf16(float lo, float hi) { unsigned r; asm volatile("v_cvt_pk_bf16_f32 %0, %1, %2" : "=v"(r) : "v"(lo), "v"(hi)); return r; }
; __device__ __forceinline__ unsigned dpp_xor1(unsigned v) { return (unsigned)__builtin_amdgcn_update_dpp(0, (int)v, 0xB1, 0xf, 0xf, false); }
; __device__ __forceinline__ float dpp_xor1(float v) { return __int_as_float(__builtin_amdgcn_update_dpp(0, __float_as_int(v), 0xB1, 0xf, 0xf, false)); }
; __device__ __forceinline__ int crow(int r, int hi) { return (r & 3) + 8 * (r >> 2) + 4 * hi; }
; template <int MODE, int VW>
; __device__ __forceinline__ void attn_unit_s(const AttnP& P, char* lds, const int tid) {
;     ...
;         for (int hv = 0; hv < VW; ++hv) {
; #pragma unroll
;             for (int d0 = 0; d0 < 4; ++d0)
; #pragma unroll
;                 for (int rp = 0; rp < 8; ++rp) { const int r = 2 * rp;
;                     const float a = o[hv * 4 + d0][r] * rli[r], bb = o[hv * 4 + d0][r + 1] * rli[r + 1];
;                     const float t = odd ? a : bb; const float rcv = dpp_xor1(t);
;                     const unsigned w = odd ? cvt_pk_bf16(rcv, bb) : cvt_pk_bf16(a, rcv);
;                     *(unsigned*)(st + sbase + (crow(r, 0)) * 320 + d0 * 64) = w; }
.LBB0_424:
	s_or_b64 exec, exec, s[2:3]
	v_mul_f32_e32 v33, v40, v118
	v_mul_f32_e32 v35, v41, v119
	ds_write_b32 v112, v32 offset:3264
	v_cndmask_b32_e64 v32, v33, v35, s[0:1]
	s_nop 1
	v_mov_b32_dpp v34, v32 quad_perm:[1,0,3,2] row_mask:0xf bank_mask:0xf
	s_and_saveexec_b64 s[2:3], vcc
	s_xor_b64 s[2:3], exec, s[2:3]
	s_cbranch_execz .LBB0_426
	v_cvt_pk_bf16_f32 v32, v34, v35

; __device__ __forceinline__ unsigned cvt_pk_bf16(float lo, float hi) { unsigned r; asm volatile("v_cvt_pk_bf16_f32 %0, %1, %2" : "=v"(r) : "v"(lo), "v"(hi)); return r; }
; __device__ __forceinline__ unsigned dpp_xor1(unsigned v) { return (unsigned)__builtin_amdgcn_update_dpp(0, (int)v, 0xB1, 0xf, 0xf, false); }
; __device__ __forceinline__ float dpp_xor1(float v) { return __int_as_float(__builtin_amdgcn_update_dpp(0, __float_as_int(v), 0xB1, 0xf, 0xf, false)); }
; __device__ __forceinline__ int crow(int r, int hi) { return (r & 3) + 8 * (r >> 2) + 4 * hi; }
; template <int MODE, int VW>
; __device__ __forceinline__ void attn_unit_s(const AttnP& P, char* lds, const int tid) {
;     ...
;         for (int hv = 0; hv < VW; ++hv) {
; #pragma unroll
;             for (int d0 = 0; d0 < 4; ++d0)
; #pragma unroll
;                 for (int rp = 0; rp < 8; ++rp) { const int r = 2 * rp;
;                     const float a = o[hv * 4 + d0][r] * rli[r], bb = o[hv * 4 + d0][r + 1] * rli[r + 1];
;                     const float t = odd ? a : bb; const float rcv = dpp_xor1(t);
;                     const unsigned w = odd ? cvt_pk_bf16(rcv, bb) : cvt_pk_bf16(a, rcv);
;                     *(unsigned*)(st + sbase + (crow(r, 0)) * 320 + d0 * 64) = w; }
.LBB0_428:
	s_or_b64 exec, exec, s[2:3]
	v_mul_f32_e32 v33, v42, v120
	v_mul_f32_e32 v35, v43, v121
	ds_write_b32 v112, v32 offset:5184
	v_cndmask_b32_e64 v32, v33, v35, s[0:1]
	s_nop 1
	v_mov_b32_dpp v34, v32 quad_perm:[1,0,3,2] row_mask:0xf bank_mask:0xf
	s_and_saveexec_b64 s[2:3], vcc
	s_xor_b64 s[2:3], exec, s[2:3]
	s_cbranch_execz .LBB0_430
	v_cvt_pk_bf16_f32 v32, v34, v35

; __device__ __forceinline__ unsigned cvt_pk_bf16(float lo, float hi) { unsigned r; asm volatile("v_cvt_pk_bf16_f32 %0, %1, %2" : "=v"(r) : "v"(lo), "v"(hi)); return r; }
; __device__ __forceinline__ unsigned dpp_xor1(unsigned v) { return (unsigned)__builtin_amdgcn_update_dpp(0, (int)v, 0xB1, 0xf, 0xf, false); }
; __device__ __forceinline__ float dpp_xor1(float v) { return __int_as_float(__builtin_amdgcn_update_dpp(0, __float_as_int(v), 0xB1, 0xf, 0xf, false)); }
; __device__ __forceinline__ int crow(int r, int hi) { return (r & 3) + 8 * (r >> 2) + 4 * hi; }
; template <int MODE, int VW>
; __device__ __forceinline__ void attn_unit_s(const AttnP& P, char* lds, const int tid) {
;     ...
;         for (int hv = 0; hv < VW; ++hv) {
; #pragma unroll
;             for (int d0 = 0; d0 < 4; ++d0)
; #pragma unroll
;                 for (int rp = 0; rp < 8; ++rp) { const int r = 2 * rp;
;                     const float a = o[hv * 4 + d0][r] * rli[r], bb = o[hv * 4 + d0][r + 1] * rli[r + 1];
;                     const float t = odd ? a : bb; const float rcv = dpp_xor1(t);
;                     const unsigned w = odd ? cvt_pk_bf16(rcv, bb) : cvt_pk_bf16(a, rcv);
;                     *(unsigned*)(st + sbase + (crow(r, 0)) * 320 + d0 * 64) = w; }
.LBB0_432:
	s_or_b64 exec, exec, s[2:3]
	v_mul_f32_e32 v33, v44, v122
	v_mul_f32_e32 v35, v45, v123
	ds_write_b32 v112, v32 offset:5824
	v_cndmask_b32_e64 v32, v33, v35, s[0:1]
	s_nop 1
	v_mov_b32_dpp v34, v32 quad_perm:[1,0,3,2] row_mask:0xf bank_mask:0xf
	s_and_saveexec_b64 s[2:3], vcc
	s_xor_b64 s[2:3], exec, s[2:3]
	s_cbranch_execz .LBB0_434
	v_cvt_pk_bf16_f32 v32, v34, v35

; __device__ __forceinline__ unsigned cvt_pk_bf16(float lo, float hi) { unsigned r; asm volatile("v_cvt_pk_bf16_f32 %0, %1, %2" : "=v"(r) : "v"(lo), "v"(hi)); return r; }
; __device__ __forceinline__ unsigned dpp_xor1(unsigned v) { return (unsigned)__builtin_amdgcn_update_dpp(0, (int)v, 0xB1, 0xf, 0xf, false); }
; __device__ __forceinline__ float dpp_xor1(float v) { return __int_as_float(__builtin_amdgcn_update_dpp(0, __float_as_int(v), 0xB1, 0xf, 0xf, false)); }
; __device__ __forceinline__ int crow(int r, int hi) { return (r & 3) + 8 * (r >> 2) + 4 * hi; }
; template <int MODE, int VW>
; __device__ __forceinline__ void attn_unit_s(const AttnP& P, char* lds, const int tid) {
;     ...
;         for (int hv = 0; hv < VW; ++hv) {
; #pragma unroll
;             for (int d0 = 0; d0 < 4; ++d0)
; #pragma unroll
;                 for (int rp = 0; rp < 8; ++rp) { const int r = 2 * rp;
;                     const float a = o[hv * 4 + d0][r] * rli[r], bb = o[hv * 4 + d0][r + 1] * rli[r + 1];
;                     const float t = odd ? a : bb; const float rcv = dpp_xor1(t);
;                     const unsigned w = odd ? cvt_pk_bf16(rcv, bb) : cvt_pk_bf16(a, rcv);
;                     *(unsigned*)(st + sbase + (crow(r, 0)) * 320 + d0 * 64) = w; }
.LBB0_436:
	s_or_b64 exec, exec, s[2:3]
	v_mul_f32_e32 v33, v46, v124
	v_mul_f32_e32 v35, v47, v125
	ds_write_b32 v112, v32 offset:7744
	v_cndmask_b32_e64 v32, v33, v35, s[0:1]
	s_nop 1
	v_mov_b32_dpp v34, v32 quad_perm:[1,0,3,2] row_mask:0xf bank_mask:0xf
	s_and_saveexec_b64 s[2:3], vcc
	s_xor_b64 s[2:3], exec, s[2:3]
	s_cbranch_execz .LBB0_438
	v_cvt_pk_bf16_f32 v32, v34, v35

; __device__ __forceinline__ unsigned cvt_pk_bf16(float lo, float hi) { unsigned r; asm volatile("v_cvt_pk_bf16_f32 %0, %1, %2" : "=v"(r) : "v"(lo), "v"(hi)); return r; }
; __device__ __forceinline__ unsigned dpp_xor1(unsigned v) { return (unsigned)__builtin_amdgcn_update_dpp(0, (int)v, 0xB1, 0xf, 0xf, false); }
; __device__ __forceinline__ float dpp_xor1(float v) { return __int_as_float(__builtin_amdgcn_update_dpp(0, __float_as_int(v), 0xB1, 0xf, 0xf, false)); }
; __device__ __forceinline__ int crow(int r, int hi) { return (r & 3) + 8 * (r >> 2) + 4 * hi; }
; template <int MODE, int VW>
; __device__ __forceinline__ void attn_unit_s(const AttnP& P, char* lds, const int tid) {
;     ...
;         for (int hv = 0; hv < VW; ++hv) {
; #pragma unroll
;             for (int d0 = 0; d0 < 4; ++d0)
; #pragma unroll
;                 for (int rp = 0; rp < 8; ++rp) { const int r = 2 * rp;
;                     const float a = o[hv * 4 + d0][r] * rli[r], bb = o[hv * 4 + d0][r + 1] * rli[r + 1];
;                     const float t = odd ? a : bb; const float rcv = dpp_xor1(t);
;                     const unsigned w = odd ? cvt_pk_bf16(rcv, bb) : cvt_pk_bf16(a, rcv);
;                     *(unsigned*)(st + sbase + (crow(r, 0)) * 320 + d0 * 64) = w; }
.LBB0_440:
	s_or_b64 exec, exec, s[2:3]
	ds_write_b32 v112, v32 offset:8384
	v_mul_f32_e32 v32, v16, v140
	v_mul_f32_e32 v33, v17, v141
	v_cndmask_b32_e64 v16, v32, v33, s[0:1]
	s_nop 1
	v_mov_b32_dpp v17, v16 quad_perm:[1,0,3,2] row_mask:0xf bank_mask:0xf
	s_and_saveexec_b64 s[2:3], vcc
	s_xor_b64 s[2:3], exec, s[2:3]
	s_cbranch_execz .LBB0_442
	v_cvt_pk_bf16_f32 v16, v17, v33

; __device__ __forceinline__ unsigned cvt_pk_bf16(float lo, float hi) { unsigned r; asm volatile("v_cvt_pk_bf16_f32 %0, %1, %2" : "=v"(r) : "v"(lo), "v"(hi)); return r; }
; __device__ __forceinline__ unsigned dpp_xor1(unsigned v) { return (unsigned)__builtin_amdgcn_update_dpp(0, (int)v, 0xB1, 0xf, 0xf, false); }
; __device__ __forceinline__ float dpp_xor1(float v) { return __int_as_float(__builtin_amdgcn_update_dpp(0, __float_as_int(v), 0xB1, 0xf, 0xf, false)); }
; __device__ __forceinline__ int crow(int r, int hi) { return (r & 3) + 8 * (r >> 2) + 4 * hi; }
; template <int MODE, int VW>
; __device__ __forceinline__ void attn_unit_s(const AttnP& P, char* lds, const int tid) {
;     ...
;         for (int hv = 0; hv < VW; ++hv) {
; #pragma unroll
;             for (int d0 = 0; d0 < 4; ++d0)
; #pragma unroll
;                 for (int rp = 0; rp < 8; ++rp) { const int r = 2 * rp;
;                     const float a = o[hv * 4 + d0][r] * rli[r], bb = o[hv * 4 + d0][r + 1] * rli[r + 1];
;                     const float t = odd ? a : bb; const float rcv = dpp_xor1(t);
;                     const unsigned w = odd ? cvt_pk_bf16(rcv, bb) : cvt_pk_bf16(a, rcv);
;                     *(unsigned*)(st + sbase + (crow(r, 0)) * 320 + d0 * 64) = w; }
.LBB0_444:
	s_or_b64 exec, exec, s[2:3]
	v_mul_f32_e32 v17, v18, v113
	v_mul_f32_e32 v19, v19, v142
	ds_write_b32 v112, v16 offset:128
	v_cndmask_b32_e64 v16, v17, v19, s[0:1]
	s_nop 1
	v_mov_b32_dpp v18, v16 quad_perm:[1,0,3,2] row_mask:0xf bank_mask:0xf
	s_and_saveexec_b64 s[2:3], vcc
	s_xor_b64 s[2:3], exec, s[2:3]
	s_cbranch_execz .LBB0_446
	v_cvt_pk_bf16_f32 v16, v18, v19

; __device__ __forceinline__ unsigned cvt_pk_bf16(float lo, float hi) { unsigned r; asm volatile("v_cvt_pk_bf16_f32 %0, %1, %2" : "=v"(r) : "v"(lo), "v"(hi)); return r; }
; __device__ __forceinline__ unsigned dpp_xor1(unsigned v) { return (unsigned)__builtin_amdgcn_update_dpp(0, (int)v, 0xB1, 0xf, 0xf, false); }
; __device__ __forceinline__ float dpp_xor1(float v) { return __int_as_float(__builtin_amdgcn_update_dpp(0, __float_as_int(v), 0xB1, 0xf, 0xf, false)); }
; __device__ __forceinline__ int crow(int r, int hi) { return (r & 3) + 8 * (r >> 2) + 4 * hi; }
; template <int MODE, int VW>
; __device__ __forceinline__ void attn_unit_s(const AttnP& P, char* lds, const int tid) {
;     ...
;         for (int hv = 0; hv < VW; ++hv) {
; #pragma unroll
;             for (int d0 = 0; d0 < 4; ++d0)
; #pragma unroll
;                 for (int rp = 0; rp < 8; ++rp) { const int r = 2 * rp;
;                     const float a = o[hv * 4 + d0][r] * rli[r], bb = o[hv * 4 + d0][r + 1] * rli[r + 1];
;                     const float t = odd ? a : bb; const float rcv = dpp_xor1(t);
;                     const unsigned w = odd ? cvt_pk_bf16(rcv, bb) : cvt_pk_bf16(a, rcv);
;                     *(unsigned*)(st + sbase + (crow(r, 0)) * 320 + d0 * 64) = w; }
.LBB0_448:
	s_or_b64 exec, exec, s[2:3]
	v_mul_f32_e32 v17, v20, v114
	v_mul_f32_e32 v19, v21, v115
	ds_write_b32 v112, v16 offset:768
	v_cndmask_b32_e64 v16, v17, v19, s[0:1]
	s_nop 1
	v_mov_b32_dpp v18, v16 quad_perm:[1,0,3,2] row_mask:0xf bank_mask:0xf
	s_and_saveexec_b64 s[2:3], vcc
	s_xor_b64 s[2:3], exec, s[2:3]
	s_cbranch_execz .LBB0_450
	v_cvt_pk_bf16_f32 v16, v18, v19

; __device__ __forceinline__ unsigned cvt_pk_bf16(float lo, float hi) { unsigned r; asm volatile("v_cvt_pk_bf16_f32 %0, %1, %2" : "=v"(r) : "v"(lo), "v"(hi)); return r; }
; __device__ __forceinline__ unsigned dpp_xor1(unsigned v) { return (unsigned)__builtin_amdgcn_update_dpp(0, (int)v, 0xB1, 0xf, 0xf, false); }
; __device__ __forceinline__ float dpp_xor1(float v) { return __int_as_float(__builtin_amdgcn_update_dpp(0, __float_as_int(v), 0xB1, 0xf, 0xf, false)); }
; __device__ __forceinline__ int crow(int r, int hi) { return (r & 3) + 8 * (r >> 2) + 4 * hi; }
; template <int MODE, int VW>
; __device__ __forceinline__ void attn_unit_s(const AttnP& P, char* lds, const int tid) {
;     ...
;         for (int hv = 0; hv < VW; ++hv) {
; #pragma unroll
;             for (int d0 = 0; d0 < 4; ++d0)
; #pragma unroll
;                 for (int rp = 0; rp < 8; ++rp) { const int r = 2 * rp;
;                     const float a = o[hv * 4 + d0][r] * rli[r], bb = o[hv * 4 + d0][r + 1] * rli[r + 1];
;                     const float t = odd ? a : bb; const float rcv = dpp_xor1(t);
;                     const unsigned w = odd ? cvt_pk_bf16(rcv, bb) : cvt_pk_bf16(a, rcv);
;                     *(unsigned*)(st + sbase + (crow(r, 0)) * 320 + d0 * 64) = w; }
.LBB0_452:
	s_or_b64 exec, exec, s[2:3]
	v_mul_f32_e32 v17, v22, v116
	v_mul_f32_e32 v19, v23, v117
	ds_write_b32 v112, v16 offset:2688
	v_cndmask_b32_e64 v16, v17, v19, s[0:1]
	s_nop 1
	v_mov_b32_dpp v18, v16 quad_perm:[1,0,3,2] row_mask:0xf bank_mask:0xf
	s_and_saveexec_b64 s[2:3], vcc
	s_xor_b64 s[2:3], exec, s[2:3]
	s_cbranch_execz .LBB0_454
	v_cvt_pk_bf16_f32 v16, v18, v19

; __device__ __forceinline__ unsigned cvt_pk_bf16(float lo, float hi) { unsigned r; asm volatile("v_cvt_pk_bf16_f32 %0, %1, %2" : "=v"(r) : "v"(lo), "v"(hi)); return r; }
; __device__ __forceinline__ unsigned dpp_xor1(unsigned v) { return (unsigned)__builtin_amdgcn_update_dpp(0, (int)v, 0xB1, 0xf, 0xf, false); }
; __device__ __forceinline__ float dpp_xor1(float v) { return __int_as_float(__builtin_amdgcn_update_dpp(0, __float_as_int(v), 0xB1, 0xf, 0xf, false)); }
; __device__ __forceinline__ int crow(int r, int hi) { return (r & 3) + 8 * (r >> 2) + 4 * hi; }
; template <int MODE, int VW>
; __device__ __forceinline__ void attn_unit_s(const AttnP& P, char* lds, const int tid) {
;     ...
;         for (int hv = 0; hv < VW; ++hv) {
; #pragma unroll
;             for (int d0 = 0; d0 < 4; ++d0)
; #pragma unroll
;                 for (int rp = 0; rp < 8; ++rp) { const int r = 2 * rp;
;                     const float a = o[hv * 4 + d0][r] * rli[r], bb = o[hv * 4 + d0][r + 1] * rli[r + 1];
;                     const float t = odd ? a : bb; const float rcv = dpp_xor1(t);
;                     const unsigned w = odd ? cvt_pk_bf16(rcv, bb) : cvt_pk_bf16(a, rcv);
;                     *(unsigned*)(st + sbase + (crow(r, 0)) * 320 + d0 * 64) = w; }
.LBB0_456:
	s_or_b64 exec, exec, s[2:3]
	v_mul_f32_e32 v17, v24, v118
	v_mul_f32_e32 v19, v25, v119
	ds_write_b32 v112, v16 offset:3328
	v_cndmask_b32_e64 v16, v17, v19, s[0:1]
	s_nop 1
	v_mov_b32_dpp v18, v16 quad_perm:[1,0,3,2] row_mask:0xf bank_mask:0xf
	s_and_saveexec_b64 s[2:3], vcc
	s_xor_b64 s[2:3], exec, s[2:3]
	s_cbranch_execz .LBB0_458
	v_cvt_pk_bf16_f32 v16, v18, v19

; __device__ __forceinline__ unsigned cvt_pk_bf16(float lo, float hi) { unsigned r; asm volatile("v_cvt_pk_bf16_f32 %0, %1, %2" : "=v"(r) : "v"(lo), "v"(hi)); return r; }
; __device__ __forceinline__ unsigned dpp_xor1(unsigned v) { return (unsigned)__builtin_amdgcn_update_dpp(0, (int)v, 0xB1, 0xf, 0xf, false); }
; __device__ __forceinline__ float dpp_xor1(float v) { return __int_as_float(__builtin_amdgcn_update_dpp(0, __float_as_int(v), 0xB1, 0xf, 0xf, false)); }
; __device__ __forceinline__ int crow(int r, int hi) { return (r & 3) + 8 * (r >> 2) + 4 * hi; }
; template <int MODE, int VW>
; __device__ __forceinline__ void attn_unit_s(const AttnP& P, char* lds, const int tid) {
;     ...
;         for (int hv = 0; hv < VW; ++hv) {
; #pragma unroll
;             for (int d0 = 0; d0 < 4; ++d0)
; #pragma unroll
;                 for (int rp = 0; rp < 8; ++rp) { const int r = 2 * rp;
;                     const float a = o[hv * 4 + d0][r] * rli[r], bb = o[hv * 4 + d0][r + 1] * rli[r + 1];
;                     const float t = odd ? a : bb; const float rcv = dpp_xor1(t);
;                     const unsigned w = odd ? cvt_pk_bf16(rcv, bb) : cvt_pk_bf16(a, rcv);
;                     *(unsigned*)(st + sbase + (crow(r, 0)) * 320 + d0 * 64) = w; }
.LBB0_460:
	s_or_b64 exec, exec, s[2:3]
	v_mul_f32_e32 v17, v26, v120
	v_mul_f32_e32 v19, v27, v121
	ds_write_b32 v112, v16 offset:5248
	v_cndmask_b32_e64 v16, v17, v19, s[0:1]
	s_nop 1
	v_mov_b32_dpp v18, v16 quad_perm:[1,0,3,2] row_mask:0xf bank_mask:0xf
	s_and_saveexec_b64 s[2:3], vcc
	s_xor_b64 s[2:3], exec, s[2:3]
	s_cbranch_execz .LBB0_462
	v_cvt_pk_bf16_f32 v16, v18, v19

; __device__ __forceinline__ unsigned cvt_pk_bf16(float lo, float hi) { unsigned r; asm volatile("v_cvt_pk_bf16_f32 %0, %1, %2" : "=v"(r) : "v"(lo), "v"(hi)); return r; }
; __device__ __forceinline__ unsigned dpp_xor1(unsigned v) { return (unsigned)__builtin_amdgcn_update_dpp(0, (int)v, 0xB1, 0xf, 0xf, false); }
; __device__ __forceinline__ float dpp_xor1(float v) { return __int_as_float(__builtin_amdgcn_update_dpp(0, __float_as_int(v), 0xB1, 0xf, 0xf, false)); }
; __device__ __forceinline__ int crow(int r, int hi) { return (r & 3) + 8 * (r >> 2) + 4 * hi; }
; template <int MODE, int VW>
; __device__ __forceinline__ void attn_unit_s(const AttnP& P, char* lds, const int tid) {
;     ...
;         for (int hv = 0; hv < VW; ++hv) {
; #pragma unroll
;             for (int d0 = 0; d0 < 4; ++d0)
; #pragma unroll
;                 for (int rp = 0; rp < 8; ++rp) { const int r = 2 * rp;
;                     const float a = o[hv * 4 + d0][r] * rli[r], bb = o[hv * 4 + d0][r + 1] * rli[r + 1];
;                     const float t = odd ? a : bb; const float rcv = dpp_xor1(t);
;                     const unsigned w = odd ? cvt_pk_bf16(rcv, bb) : cvt_pk_bf16(a, rcv);
;                     *(unsigned*)(st + sbase + (crow(r, 0)) * 320 + d0 * 64) = w; }
.LBB0_464:
	s_or_b64 exec, exec, s[2:3]
	v_mul_f32_e32 v17, v28, v122
	v_mul_f32_e32 v19, v29, v123
	ds_write_b32 v112, v16 offset:5888
	v_cndmask_b32_e64 v16, v17, v19, s[0:1]
	s_nop 1
	v_mov_b32_dpp v18, v16 quad_perm:[1,0,3,2] row_mask:0xf bank_mask:0xf
	s_and_saveexec_b64 s[2:3], vcc
	s_xor_b64 s[2:3], exec, s[2:3]
	s_cbranch_execz .LBB0_466
	v_cvt_pk_bf16_f32 v16, v18, v19

; __device__ __forceinline__ unsigned cvt_pk_bf16(float lo, float hi) { unsigned r; asm volatile("v_cvt_pk_bf16_f32 %0, %1, %2" : "=v"(r) : "v"(lo), "v"(hi)); return r; }
; __device__ __forceinline__ unsigned dpp_xor1(unsigned v) { return (unsigned)__builtin_amdgcn_update_dpp(0, (int)v, 0xB1, 0xf, 0xf, false); }
; __device__ __forceinline__ float dpp_xor1(float v) { return __int_as_float(__builtin_amdgcn_update_dpp(0, __float_as_int(v), 0xB1, 0xf, 0xf, false)); }
; __device__ __forceinline__ int crow(int r, int hi) { return (r & 3) + 8 * (r >> 2) + 4 * hi; }
; template <int MODE, int VW>
; __device__ __forceinline__ void attn_unit_s(const AttnP& P, char* lds, const int tid) {
;     ...
;             for (int d0 = 0; d0 < 4; ++d0)
; #pragma unroll
;                 for (int rp = 0; rp < 8; ++rp) { const int r = 2 * rp;
;                     const float a = o[hv * 4 + d0][r] * rli[r], bb = o[hv * 4 + d0][r + 1] * rli[r + 1];
;                     const float t = odd ? a : bb; const float rcv = dpp_xor1(t);
;                     const unsigned w = odd ? cvt_pk_bf16(rcv, bb) : cvt_pk_bf16(a, rcv);
;                     *(unsigned*)(st + sbase + (crow(r, 0)) * 320 + d0 * 64) = w; }
.LBB0_468:
	s_or_b64 exec, exec, s[2:3]
	v_mul_f32_e32 v17, v30, v124
	v_mul_f32_e32 v19, v31, v125
	ds_write_b32 v112, v16 offset:7808
	v_cndmask_b32_e64 v16, v17, v19, s[0:1]
	s_nop 1
	v_mov_b32_dpp v18, v16 quad_perm:[1,0,3,2] row_mask:0xf bank_mask:0xf
	s_and_saveexec_b64 s[2:3], vcc
	s_xor_b64 s[2:3], exec, s[2:3]
	s_cbranch_execz .LBB0_470
	v_cvt_pk_bf16_f32 v16, v18, v19

; __device__ __forceinline__ unsigned cvt_pk_bf16(float lo, float hi) { unsigned r; asm volatile("v_cvt_pk_bf16_f32 %0, %1, %2" : "=v"(r) : "v"(lo), "v"(hi)); return r; }
; __device__ __forceinline__ unsigned dpp_xor1(unsigned v) { return (unsigned)__builtin_amdgcn_update_dpp(0, (int)v, 0xB1, 0xf, 0xf, false); }
; __device__ __forceinline__ float dpp_xor1(float v) { return __int_as_float(__builtin_amdgcn_update_dpp(0, __float_as_int(v), 0xB1, 0xf, 0xf, false)); }
; __device__ __forceinline__ int crow(int r, int hi) { return (r & 3) + 8 * (r >> 2) + 4 * hi; }
; template <int MODE, int VW>
; __device__ __forceinline__ void attn_unit_s(const AttnP& P, char* lds, const int tid) {
;     ...
;             for (int d0 = 0; d0 < 4; ++d0)
; #pragma unroll
;                 for (int rp = 0; rp < 8; ++rp) { const int r = 2 * rp;
;                     const float a = o[hv * 4 + d0][r] * rli[r], bb = o[hv * 4 + d0][r + 1] * rli[r + 1];
;                     const float t = odd ? a : bb; const float rcv = dpp_xor1(t);
;                     const unsigned w = odd ? cvt_pk_bf16(rcv, bb) : cvt_pk_bf16(a, rcv);
;                     *(unsigned*)(st + sbase + (crow(r, 0)) * 320 + d0 * 64) = w; }
.LBB0_472:
	s_or_b64 exec, exec, s[2:3]
	ds_write_b32 v112, v16 offset:8448
	v_mul_f32_e32 v16, v0, v140
	v_mul_f32_e32 v17, v1, v141
	v_cndmask_b32_e64 v0, v16, v17, s[0:1]
	s_nop 1
	v_mov_b32_dpp v1, v0 quad_perm:[1,0,3,2] row_mask:0xf bank_mask:0xf
	s_and_saveexec_b64 s[2:3], vcc
	s_xor_b64 s[2:3], exec, s[2:3]
	s_cbranch_execz .LBB0_474
	v_cvt_pk_bf16_f32 v0, v1, v17

; __device__ __forceinline__ unsigned cvt_pk_bf16(float lo, float hi) { unsigned r; asm volatile("v_cvt_pk_bf16_f32 %0, %1, %2" : "=v"(r) : "v"(lo), "v"(hi)); return r; }
; __device__ __forceinline__ unsigned dpp_xor1(unsigned v) { return (unsigned)__builtin_amdgcn_update_dpp(0, (int)v, 0xB1, 0xf, 0xf, false); }
; __device__ __forceinline__ float dpp_xor1(float v) { return __int_as_float(__builtin_amdgcn_update_dpp(0, __float_as_int(v), 0xB1, 0xf, 0xf, false)); }
; __device__ __forceinline__ int crow(int r, int hi) { return (r & 3) + 8 * (r >> 2) + 4 * hi; }
; template <int MODE, int VW>
; __device__ __forceinline__ void attn_unit_s(const AttnP& P, char* lds, const int tid) {
;     ...
;             for (int d0 = 0; d0 < 4; ++d0)
; #pragma unroll
;                 for (int rp = 0; rp < 8; ++rp) { const int r = 2 * rp;
;                     const float a = o[hv * 4 + d0][r] * rli[r], bb = o[hv * 4 + d0][r + 1] * rli[r + 1];
;                     const float t = odd ? a : bb; const float rcv = dpp_xor1(t);
;                     const unsigned w = odd ? cvt_pk_bf16(rcv, bb) : cvt_pk_bf16(a, rcv);
;                     *(unsigned*)(st + sbase + (crow(r, 0)) * 320 + d0 * 64) = w; }
.LBB0_476:
	s_or_b64 exec, exec, s[2:3]
	v_mul_f32_e32 v1, v2, v113
	v_mul_f32_e32 v3, v3, v142
	ds_write_b32 v112, v0 offset:192
	v_cndmask_b32_e64 v0, v1, v3, s[0:1]
	s_nop 1
	v_mov_b32_dpp v2, v0 quad_perm:[1,0,3,2] row_mask:0xf bank_mask:0xf
	s_and_saveexec_b64 s[2:3], vcc
	s_xor_b64 s[2:3], exec, s[2:3]
	s_cbranch_execz .LBB0_478
	v_cvt_pk_bf16_f32 v0, v2, v3

; __device__ __forceinline__ unsigned cvt_pk_bf16(float lo, float hi) { unsigned r; asm volatile("v_cvt_pk_bf16_f32 %0, %1, %2" : "=v"(r) : "v"(lo), "v"(hi)); return r; }
; __device__ __forceinline__ unsigned dpp_xor1(unsigned v) { return (unsigned)__builtin_amdgcn_update_dpp(0, (int)v, 0xB1, 0xf, 0xf, false); }
; __device__ __forceinline__ float dpp_xor1(float v) { return __int_as_float(__builtin_amdgcn_update_dpp(0, __float_as_int(v), 0xB1, 0xf, 0xf, false)); }
; __device__ __forceinline__ int crow(int r, int hi) { return (r & 3) + 8 * (r >> 2) + 4 * hi; }
; template <int MODE, int VW>
; __device__ __forceinline__ void attn_unit_s(const AttnP& P, char* lds, const int tid) {
;     ...
;             for (int d0 = 0; d0 < 4; ++d0)
; #pragma unroll
;                 for (int rp = 0; rp < 8; ++rp) { const int r = 2 * rp;
;                     const float a = o[hv * 4 + d0][r] * rli[r], bb = o[hv * 4 + d0][r + 1] * rli[r + 1];
;                     const float t = odd ? a : bb; const float rcv = dpp_xor1(t);
;                     const unsigned w = odd ? cvt_pk_bf16(rcv, bb) : cvt_pk_bf16(a, rcv);
;                     *(unsigned*)(st + sbase + (crow(r, 0)) * 320 + d0 * 64) = w; }
.LBB0_480:
	s_or_b64 exec, exec, s[2:3]
	v_mul_f32_e32 v1, v4, v114
	v_mul_f32_e32 v3, v5, v115
	ds_write_b32 v112, v0 offset:832
	v_cndmask_b32_e64 v0, v1, v3, s[0:1]
	s_nop 1
	v_mov_b32_dpp v2, v0 quad_perm:[1,0,3,2] row_mask:0xf bank_mask:0xf
	s_and_saveexec_b64 s[2:3], vcc
	s_xor_b64 s[2:3], exec, s[2:3]
	s_cbranch_execz .LBB0_482
	v_cvt_pk_bf16_f32 v0, v2, v3

; __device__ __forceinline__ unsigned cvt_pk_bf16(float lo, float hi) { unsigned r; asm volatile("v_cvt_pk_bf16_f32 %0, %1, %2" : "=v"(r) : "v"(lo), "v"(hi)); return r; }
; __device__ __forceinline__ unsigned dpp_xor1(unsigned v) { return (unsigned)__builtin_amdgcn_update_dpp(0, (int)v, 0xB1, 0xf, 0xf, false); }
; __device__ __forceinline__ float dpp_xor1(float v) { return __int_as_float(__builtin_amdgcn_update_dpp(0, __float_as_int(v), 0xB1, 0xf, 0xf, false)); }
; __device__ __forceinline__ int crow(int r, int hi) { return (r & 3) + 8 * (r >> 2) + 4 * hi; }
; template <int MODE, int VW>
; __device__ __forceinline__ void attn_unit_s(const AttnP& P, char* lds, const int tid) {
;     ...
;             for (int d0 = 0; d0 < 4; ++d0)
; #pragma unroll
;                 for (int rp = 0; rp < 8; ++rp) { const int r = 2 * rp;
;                     const float a = o[hv * 4 + d0][r] * rli[r], bb = o[hv * 4 + d0][r + 1] * rli[r + 1];
;                     const float t = odd ? a : bb; const float rcv = dpp_xor1(t);
;                     const unsigned w = odd ? cvt_pk_bf16(rcv, bb) : cvt_pk_bf16(a, rcv);
;                     *(unsigned*)(st + sbase + (crow(r, 0)) * 320 + d0 * 64) = w; }
.LBB0_484:
	s_or_b64 exec, exec, s[2:3]
	v_mul_f32_e32 v1, v6, v116
	v_mul_f32_e32 v3, v7, v117
	ds_write_b32 v112, v0 offset:2752
	v_cndmask_b32_e64 v0, v1, v3, s[0:1]
	s_nop 1
	v_mov_b32_dpp v2, v0 quad_perm:[1,0,3,2] row_mask:0xf bank_mask:0xf
	s_and_saveexec_b64 s[2:3], vcc
	s_xor_b64 s[2:3], exec, s[2:3]
	s_cbranch_execz .LBB0_486
	v_cvt_pk_bf16_f32 v0, v2, v3

; __device__ __forceinline__ unsigned cvt_pk_bf16(float lo, float hi) { unsigned r; asm volatile("v_cvt_pk_bf16_f32 %0, %1, %2" : "=v"(r) : "v"(lo), "v"(hi)); return r; }
; __device__ __forceinline__ unsigned dpp_xor1(unsigned v) { return (unsigned)__builtin_amdgcn_update_dpp(0, (int)v, 0xB1, 0xf, 0xf, false); }
; __device__ __forceinline__ float dpp_xor1(float v) { return __int_as_float(__builtin_amdgcn_update_dpp(0, __float_as_int(v), 0xB1, 0xf, 0xf, false)); }
; __device__ __forceinline__ int crow(int r, int hi) { return (r & 3) + 8 * (r >> 2) + 4 * hi; }
; template <int MODE, int VW>
; __device__ __forceinline__ void attn_unit_s(const AttnP& P, char* lds, const int tid) {
;     ...
;             for (int d0 = 0; d0 < 4; ++d0)
; #pragma unroll
;                 for (int rp = 0; rp < 8; ++rp) { const int r = 2 * rp;
;                     const float a = o[hv * 4 + d0][r] * rli[r], bb = o[hv * 4 + d0][r + 1] * rli[r + 1];
;                     const float t = odd ? a : bb; const float rcv = dpp_xor1(t);
;                     const unsigned w = odd ? cvt_pk_bf16(rcv, bb) : cvt_pk_bf16(a, rcv);
;                     *(unsigned*)(st + sbase + (crow(r, 0)) * 320 + d0 * 64) = w; }
.LBB0_488:
	s_or_b64 exec, exec, s[2:3]
	v_mul_f32_e32 v1, v8, v118
	v_mul_f32_e32 v3, v9, v119
	ds_write_b32 v112, v0 offset:3392
	v_cndmask_b32_e64 v0, v1, v3, s[0:1]
	s_nop 1
	v_mov_b32_dpp v2, v0 quad_perm:[1,0,3,2] row_mask:0xf bank_mask:0xf
	s_and_saveexec_b64 s[2:3], vcc
	s_xor_b64 s[2:3], exec, s[2:3]
	s_cbranch_execz .LBB0_490
	v_cvt_pk_bf16_f32 v0, v2, v3

; __device__ __forceinline__ unsigned cvt_pk_bf16(float lo, float hi) { unsigned r; asm volatile("v_cvt_pk_bf16_f32 %0, %1, %2" : "=v"(r) : "v"(lo), "v"(hi)); return r; }
; __device__ __forceinline__ unsigned dpp_xor1(unsigned v) { return (unsigned)__builtin_amdgcn_update_dpp(0, (int)v, 0xB1, 0xf, 0xf, false); }
; __device__ __forceinline__ float dpp_xor1(float v) { return __int_as_float(__builtin_amdgcn_update_dpp(0, __float_as_int(v), 0xB1, 0xf, 0xf, false)); }
; __device__ __forceinline__ int crow(int r, int hi) { return (r & 3) + 8 * (r >> 2) + 4 * hi; }
; template <int MODE, int VW>
; __device__ __forceinline__ void attn_unit_s(const AttnP& P, char* lds, const int tid) {
;     ...
;             for (int d0 = 0; d0 < 4; ++d0)
; #pragma unroll
;                 for (int rp = 0; rp < 8; ++rp) { const int r = 2 * rp;
;                     const float a = o[hv * 4 + d0][r] * rli[r], bb = o[hv * 4 + d0][r + 1] * rli[r + 1];
;                     const float t = odd ? a : bb; const float rcv = dpp_xor1(t);
;                     const unsigned w = odd ? cvt_pk_bf16(rcv, bb) : cvt_pk_bf16(a, rcv);
;                     *(unsigned*)(st + sbase + (crow(r, 0)) * 320 + d0 * 64) = w; }
.LBB0_492:
	s_or_b64 exec, exec, s[2:3]
	v_mul_f32_e32 v1, v10, v120
	v_mul_f32_e32 v3, v11, v121
	ds_write_b32 v112, v0 offset:5312
	v_cndmask_b32_e64 v0, v1, v3, s[0:1]
	s_nop 1
	v_mov_b32_dpp v2, v0 quad_perm:[1,0,3,2] row_mask:0xf bank_mask:0xf
	s_and_saveexec_b64 s[2:3], vcc
	s_xor_b64 s[2:3], exec, s[2:3]
	s_cbranch_execz .LBB0_494
	v_cvt_pk_bf16_f32 v0, v2, v3

; __device__ __forceinline__ unsigned cvt_pk_bf16(float lo, float hi) { unsigned r; asm volatile("v_cvt_pk_bf16_f32 %0, %1, %2" : "=v"(r) : "v"(lo), "v"(hi)); return r; }
; __device__ __forceinline__ unsigned dpp_xor1(unsigned v) { return (unsigned)__builtin_amdgcn_update_dpp(0, (int)v, 0xB1, 0xf, 0xf, false); }
; __device__ __forceinline__ float dpp_xor1(float v) { return __int_as_float(__builtin_amdgcn_update_dpp(0, __float_as_int(v), 0xB1, 0xf, 0xf, false)); }
; __device__ __forceinline__ int crow(int r, int hi) { return (r & 3) + 8 * (r >> 2) + 4 * hi; }
; template <int MODE, int VW>
; __device__ __forceinline__ void attn_unit_s(const AttnP& P, char* lds, const int tid) {
;     ...
;             for (int d0 = 0; d0 < 4; ++d0)
; #pragma unroll
;                 for (int rp = 0; rp < 8; ++rp) { const int r = 2 * rp;
;                     const float a = o[hv * 4 + d0][r] * rli[r], bb = o[hv * 4 + d0][r + 1] * rli[r + 1];
;                     const float t = odd ? a : bb; const float rcv = dpp_xor1(t);
;                     const unsigned w = odd ? cvt_pk_bf16(rcv, bb) : cvt_pk_bf16(a, rcv);
;                     *(unsigned*)(st + sbase + (crow(r, 0)) * 320 + d0 * 64) = w; }
.LBB0_496:
	s_or_b64 exec, exec, s[2:3]
	v_mul_f32_e32 v1, v12, v122
	v_mul_f32_e32 v3, v13, v123
	ds_write_b32 v112, v0 offset:5952
	v_cndmask_b32_e64 v0, v1, v3, s[0:1]
	s_nop 1
	v_mov_b32_dpp v2, v0 quad_perm:[1,0,3,2] row_mask:0xf bank_mask:0xf
	s_and_saveexec_b64 s[2:3], vcc
	s_xor_b64 s[2:3], exec, s[2:3]
	s_cbranch_execz .LBB0_498
	v_cvt_pk_bf16_f32 v0, v2, v3

; __device__ __forceinline__ unsigned cvt_pk_bf16(float lo, float hi) { unsigned r; asm volatile("v_cvt_pk_bf16_f32 %0, %1, %2" : "=v"(r) : "v"(lo), "v"(hi)); return r; }
; __device__ __forceinline__ unsigned dpp_xor1(unsigned v) { return (unsigned)__builtin_amdgcn_update_dpp(0, (int)v, 0xB1, 0xf, 0xf, false); }
; __device__ __forceinline__ float dpp_xor1(float v) { return __int_as_float(__builtin_amdgcn_update_dpp(0, __float_as_int(v), 0xB1, 0xf, 0xf, false)); }
; __device__ __forceinline__ int crow(int r, int hi) { return (r & 3) + 8 * (r >> 2) + 4 * hi; }
; template <int MODE, int VW>
; __device__ __forceinline__ void attn_unit_s(const AttnP& P, char* lds, const int tid) {
;     ...
;             for (int d0 = 0; d0 < 4; ++d0)
; #pragma unroll
;                 for (int rp = 0; rp < 8; ++rp) { const int r = 2 * rp;
;                     const float a = o[hv * 4 + d0][r] * rli[r], bb = o[hv * 4 + d0][r + 1] * rli[r + 1];
;                     const float t = odd ? a : bb; const float rcv = dpp_xor1(t);
;                     const unsigned w = odd ? cvt_pk_bf16(rcv, bb) : cvt_pk_bf16(a, rcv);
;                     *(unsigned*)(st + sbase + (crow(r, 0)) * 320 + d0 * 64) = w; }
.LBB0_500:
	s_or_b64 exec, exec, s[2:3]
	v_mul_f32_e32 v1, v14, v124
	v_mul_f32_e32 v3, v15, v125
	ds_write_b32 v112, v0 offset:7872
	v_cndmask_b32_e64 v0, v1, v3, s[0:1]
	s_nop 1
	v_mov_b32_dpp v2, v0 quad_perm:[1,0,3,2] row_mask:0xf bank_mask:0xf
	s_and_saveexec_b64 s[0:1], vcc
	s_xor_b64 s[0:1], exec, s[0:1]
	s_cbranch_execz .LBB0_502
	v_cvt_pk_bf16_f32 v0, v2, v3

; __device__ __forceinline__ unsigned cvt_pk_bf16(float lo, float hi) { unsigned r; asm volatile("v_cvt_pk_bf16_f32 %0, %1, %2" : "=v"(r) : "v"(lo), "v"(hi)); return r; }
; __device__ __forceinline__ unsigned dpp_xor1(unsigned v) { return (unsigned)__builtin_amdgcn_update_dpp(0, (int)v, 0xB1, 0xf, 0xf, false); }
; __device__ __forceinline__ float dpp_xor1(float v) { return __int_as_float(__builtin_amdgcn_update_dpp(0, __float_as_int(v), 0xB1, 0xf, 0xf, false)); }
; __device__ __forceinline__ int crow(int r, int hi) { return (r & 3) + 8 * (r >> 2) + 4 * hi; }
; template <int MODE, int VW>
; __device__ __forceinline__ void attn_unit_s(const AttnP& P, char* lds, const int tid) {
;     ...
;     float rli[16];
; #pragma unroll
;     for (int r = 0; r < 16; ++r) rli[r] = __builtin_amdgcn_rcpf(li_l[crow(r, hi)]);
;     {
;         char* st = lds + wid * 10240;
;         const bool odd = (r32 & 1) != 0;
;         const int sbase = (crow(0, hi) + (odd ? 1 : 0)) * 320 + (r32 & ~1) * 2;
;         bf16_t* Ow = P.O + (long)(wid * QBLK) * P.ldo;
; #pragma unroll
;         for (int hv = 0; hv < VW; ++hv) {
; #pragma unroll
;             for (int d0 = 0; d0 < 4; ++d0)
; #pragma unroll
;                 for (int rp = 0; rp < 8; ++rp) { const int r = 2 * rp;
;                     const float a = o[hv * 4 + d0][r] * rli[r], bb = o[hv * 4 + d0][r + 1] * rli[r + 1];
;                     const float t = odd ? a : bb; const float rcv = dpp_xor1(t);
;                     const unsigned w = odd ? cvt_pk_bf16(rcv, bb) : cvt_pk_bf16(a, rcv);
;                     *(unsigned*)(st + sbase + (crow(r, 0)) * 320 + d0 * 64) = w; }
.LBB0_610:
	s_or_b64 exec, exec, s[2:3]
	ds_read_b128 v[78:81], v165
	ds_read_b128 v[74:77], v165 offset:32
	ds_read_b128 v[70:73], v165 offset:64
	ds_read_b128 v[66:69], v165 offset:96
	v_and_b32_e32 v82, 1, v162
	s_waitcnt lgkmcnt(3)
	v_rcp_f32_e32 v0, v78
	v_rcp_f32_e32 v78, v79
	v_cmp_eq_u32_e64 s[0:1], 0, v82
	v_cmp_eq_u32_e32 vcc, 1, v82
	v_mul_f32_e32 v50, v50, v0
	v_mul_f32_e32 v79, v51, v78
	v_cndmask_b32_e64 v83, v50, v79, s[0:1]
	s_nop 1
	v_mov_b32_dpp v51, v83 quad_perm:[1,0,3,2] row_mask:0xf bank_mask:0xf
	s_and_saveexec_b64 s[2:3], vcc
	s_xor_b64 s[2:3], exec, s[2:3]
	s_cbranch_execz .LBB0_612
	v_cvt_pk_bf16_f32 v83, v51, v79

; __device__ __forceinline__ unsigned cvt_pk_bf16(float lo, float hi) { unsigned r; asm volatile("v_cvt_pk_bf16_f32 %0, %1, %2" : "=v"(r) : "v"(lo), "v"(hi)); return r; }
; __device__ __forceinline__ unsigned dpp_xor1(unsigned v) { return (unsigned)__builtin_amdgcn_update_dpp(0, (int)v, 0xB1, 0xf, 0xf, false); }
; __device__ __forceinline__ float dpp_xor1(float v) { return __int_as_float(__builtin_amdgcn_update_dpp(0, __float_as_int(v), 0xB1, 0xf, 0xf, false)); }
; __device__ __forceinline__ int crow(int r, int hi) { return (r & 3) + 8 * (r >> 2) + 4 * hi; }
; template <int MODE, int VW>
; __device__ __forceinline__ void attn_unit_s(const AttnP& P, char* lds, const int tid) {
;     ...
;     float rli[16];
; #pragma unroll
;     for (int r = 0; r < 16; ++r) rli[r] = __builtin_amdgcn_rcpf(li_l[crow(r, hi)]);
;     {
;         char* st = lds + wid * 10240;
;         const bool odd = (r32 & 1) != 0;
;         const int sbase = (crow(0, hi) + (odd ? 1 : 0)) * 320 + (r32 & ~1) * 2;
;         bf16_t* Ow = P.O + (long)(wid * QBLK) * P.ldo;
; #pragma unroll
;         for (int hv = 0; hv < VW; ++hv) {
; #pragma unroll
;             for (int d0 = 0; d0 < 4; ++d0)
; #pragma unroll
;                 for (int rp = 0; rp < 8; ++rp) { const int r = 2 * rp;
;                     const float a = o[hv * 4 + d0][r] * rli[r], bb = o[hv * 4 + d0][r + 1] * rli[r + 1];
;                     const float t = odd ? a : bb; const float rcv = dpp_xor1(t);
;                     const unsigned w = odd ? cvt_pk_bf16(rcv, bb) : cvt_pk_bf16(a, rcv);
;                     *(unsigned*)(st + sbase + (crow(r, 0)) * 320 + d0 * 64) = w; }
.LBB0_614:
	s_or_b64 exec, exec, s[2:3]
	v_rcp_f32_e32 v51, v80
	v_rcp_f32_e32 v79, v81
	s_mulk_i32 s23, 0x2800
	s_add_i32 s22, s23, 0
	v_or_b32_e32 v50, v163, v82
	v_lshlrev_b32_e32 v80, 1, v162
	v_mov_b32_e32 v81, s22
	s_movk_i32 s2, 0x140
	v_and_b32_e32 v80, 60, v80
	v_mad_u32_u24 v50, v50, s2, v81
	v_mul_f32_e32 v52, v52, v51
	v_mul_f32_e32 v81, v53, v79
	v_add_u32_e32 v50, v50, v80
	v_cndmask_b32_e64 v80, v52, v81, s[0:1]
	ds_write_b32 v50, v83
	s_nop 0
	v_mov_b32_dpp v53, v80 quad_perm:[1,0,3,2] row_mask:0xf bank_mask:0xf
	s_and_saveexec_b64 s[2:3], vcc
	s_xor_b64 s[2:3], exec, s[2:3]
	s_cbranch_execz .LBB0_616
	v_cvt_pk_bf16_f32 v80, v53, v81

; __device__ __forceinline__ unsigned cvt_pk_bf16(float lo, float hi) { unsigned r; asm volatile("v_cvt_pk_bf16_f32 %0, %1, %2" : "=v"(r) : "v"(lo), "v"(hi)); return r; }
; __device__ __forceinline__ unsigned dpp_xor1(unsigned v) { return (unsigned)__builtin_amdgcn_update_dpp(0, (int)v, 0xB1, 0xf, 0xf, false); }
; __device__ __forceinline__ float dpp_xor1(float v) { return __int_as_float(__builtin_amdgcn_update_dpp(0, __float_as_int(v), 0xB1, 0xf, 0xf, false)); }
; __device__ __forceinline__ int crow(int r, int hi) { return (r & 3) + 8 * (r >> 2) + 4 * hi; }
; template <int MODE, int VW>
; __device__ __forceinline__ void attn_unit_s(const AttnP& P, char* lds, const int tid) {
;     ...
;     float rli[16];
; #pragma unroll
;     for (int r = 0; r < 16; ++r) rli[r] = __builtin_amdgcn_rcpf(li_l[crow(r, hi)]);
;     {
;         char* st = lds + wid * 10240;
;         const bool odd = (r32 & 1) != 0;
;         const int sbase = (crow(0, hi) + (odd ? 1 : 0)) * 320 + (r32 & ~1) * 2;
;         bf16_t* Ow = P.O + (long)(wid * QBLK) * P.ldo;
; #pragma unroll
;         for (int hv = 0; hv < VW; ++hv) {
; #pragma unroll
;             for (int d0 = 0; d0 < 4; ++d0)
; #pragma unroll
;                 for (int rp = 0; rp < 8; ++rp) { const int r = 2 * rp;
;                     const float a = o[hv * 4 + d0][r] * rli[r], bb = o[hv * 4 + d0][r + 1] * rli[r + 1];
;                     const float t = odd ? a : bb; const float rcv = dpp_xor1(t);
;                     const unsigned w = odd ? cvt_pk_bf16(rcv, bb) : cvt_pk_bf16(a, rcv);
;                     *(unsigned*)(st + sbase + (crow(r, 0)) * 320 + d0 * 64) = w; }
.LBB0_618:
	s_or_b64 exec, exec, s[2:3]
	s_waitcnt lgkmcnt(3)
	v_rcp_f32_e32 v52, v74
	v_rcp_f32_e32 v53, v75
	ds_write_b32 v50, v80 offset:640
	v_mul_f32_e32 v54, v54, v52
	v_mul_f32_e32 v75, v55, v53
	v_cndmask_b32_e64 v74, v54, v75, s[0:1]
	s_nop 1
	v_mov_b32_dpp v55, v74 quad_perm:[1,0,3,2] row_mask:0xf bank_mask:0xf
	s_and_saveexec_b64 s[2:3], vcc
	s_xor_b64 s[2:3], exec, s[2:3]
	s_cbranch_execz .LBB0_620
	v_cvt_pk_bf16_f32 v74, v55, v75

; __device__ __forceinline__ unsigned cvt_pk_bf16(float lo, float hi) { unsigned r; asm volatile("v_cvt_pk_bf16_f32 %0, %1, %2" : "=v"(r) : "v"(lo), "v"(hi)); return r; }
; __device__ __forceinline__ unsigned dpp_xor1(unsigned v) { return (unsigned)__builtin_amdgcn_update_dpp(0, (int)v, 0xB1, 0xf, 0xf, false); }
; __device__ __forceinline__ float dpp_xor1(float v) { return __int_as_float(__builtin_amdgcn_update_dpp(0, __float_as_int(v), 0xB1, 0xf, 0xf, false)); }
; __device__ __forceinline__ int crow(int r, int hi) { return (r & 3) + 8 * (r >> 2) + 4 * hi; }
; template <int MODE, int VW>
; __device__ __forceinline__ void attn_unit_s(const AttnP& P, char* lds, const int tid) {
;     ...
;     float rli[16];
; #pragma unroll
;     for (int r = 0; r < 16; ++r) rli[r] = __builtin_amdgcn_rcpf(li_l[crow(r, hi)]);
;     {
;         char* st = lds + wid * 10240;
;         const bool odd = (r32 & 1) != 0;
;         const int sbase = (crow(0, hi) + (odd ? 1 : 0)) * 320 + (r32 & ~1) * 2;
;         bf16_t* Ow = P.O + (long)(wid * QBLK) * P.ldo;
; #pragma unroll
;         for (int hv = 0; hv < VW; ++hv) {
; #pragma unroll
;             for (int d0 = 0; d0 < 4; ++d0)
; #pragma unroll
;                 for (int rp = 0; rp < 8; ++rp) { const int r = 2 * rp;
;                     const float a = o[hv * 4 + d0][r] * rli[r], bb = o[hv * 4 + d0][r + 1] * rli[r + 1];
;                     const float t = odd ? a : bb; const float rcv = dpp_xor1(t);
;                     const unsigned w = odd ? cvt_pk_bf16(rcv, bb) : cvt_pk_bf16(a, rcv);
;                     *(unsigned*)(st + sbase + (crow(r, 0)) * 320 + d0 * 64) = w; }
.LBB0_622:
	s_or_b64 exec, exec, s[2:3]
	v_rcp_f32_e32 v54, v76
	v_rcp_f32_e32 v55, v77
	ds_write_b32 v50, v74 offset:2560
	v_mul_f32_e32 v56, v56, v54
	v_mul_f32_e32 v75, v57, v55
	v_cndmask_b32_e64 v74, v56, v75, s[0:1]
	s_nop 1
	v_mov_b32_dpp v57, v74 quad_perm:[1,0,3,2] row_mask:0xf bank_mask:0xf
	s_and_saveexec_b64 s[2:3], vcc
	s_xor_b64 s[2:3], exec, s[2:3]
	s_cbranch_execz .LBB0_624
	v_cvt_pk_bf16_f32 v74, v57, v75

; __device__ __forceinline__ unsigned cvt_pk_bf16(float lo, float hi) { unsigned r; asm volatile("v_cvt_pk_bf16_f32 %0, %1, %2" : "=v"(r) : "v"(lo), "v"(hi)); return r; }
; __device__ __forceinline__ unsigned dpp_xor1(unsigned v) { return (unsigned)__builtin_amdgcn_update_dpp(0, (int)v, 0xB1, 0xf, 0xf, false); }
; __device__ __forceinline__ float dpp_xor1(float v) { return __int_as_float(__builtin_amdgcn_update_dpp(0, __float_as_int(v), 0xB1, 0xf, 0xf, false)); }
; __device__ __forceinline__ int crow(int r, int hi) { return (r & 3) + 8 * (r >> 2) + 4 * hi; }
; template <int MODE, int VW>
; __device__ __forceinline__ void attn_unit_s(const AttnP& P, char* lds, const int tid) {
;     ...
;     float rli[16];
; #pragma unroll
;     for (int r = 0; r < 16; ++r) rli[r] = __builtin_amdgcn_rcpf(li_l[crow(r, hi)]);
;     {
;         char* st = lds + wid * 10240;
;         const bool odd = (r32 & 1) != 0;
;         const int sbase = (crow(0, hi) + (odd ? 1 : 0)) * 320 + (r32 & ~1) * 2;
;         bf16_t* Ow = P.O + (long)(wid * QBLK) * P.ldo;
; #pragma unroll
;         for (int hv = 0; hv < VW; ++hv) {
; #pragma unroll
;             for (int d0 = 0; d0 < 4; ++d0)
; #pragma unroll
;                 for (int rp = 0; rp < 8; ++rp) { const int r = 2 * rp;
;                     const float a = o[hv * 4 + d0][r] * rli[r], bb = o[hv * 4 + d0][r + 1] * rli[r + 1];
;                     const float t = odd ? a : bb; const float rcv = dpp_xor1(t);
;                     const unsigned w = odd ? cvt_pk_bf16(rcv, bb) : cvt_pk_bf16(a, rcv);
;                     *(unsigned*)(st + sbase + (crow(r, 0)) * 320 + d0 * 64) = w; }
.LBB0_626:
	s_or_b64 exec, exec, s[2:3]
	s_waitcnt lgkmcnt(4)
	v_rcp_f32_e32 v56, v70
	v_rcp_f32_e32 v57, v71
	ds_write_b32 v50, v74 offset:3200
	v_mul_f32_e32 v58, v58, v56
	v_mul_f32_e32 v71, v59, v57
	v_cndmask_b32_e64 v70, v58, v71, s[0:1]
	s_nop 1
	v_mov_b32_dpp v59, v70 quad_perm:[1,0,3,2] row_mask:0xf bank_mask:0xf
	s_and_saveexec_b64 s[2:3], vcc
	s_xor_b64 s[2:3], exec, s[2:3]
	s_cbranch_execz .LBB0_628
	v_cvt_pk_bf16_f32 v70, v59, v71

; __device__ __forceinline__ unsigned cvt_pk_bf16(float lo, float hi) { unsigned r; asm volatile("v_cvt_pk_bf16_f32 %0, %1, %2" : "=v"(r) : "v"(lo), "v"(hi)); return r; }
; __device__ __forceinline__ unsigned dpp_xor1(unsigned v) { return (unsigned)__builtin_amdgcn_update_dpp(0, (int)v, 0xB1, 0xf, 0xf, false); }
; __device__ __forceinline__ float dpp_xor1(float v) { return __int_as_float(__builtin_amdgcn_update_dpp(0, __float_as_int(v), 0xB1, 0xf, 0xf, false)); }
; __device__ __forceinline__ int crow(int r, int hi) { return (r & 3) + 8 * (r >> 2) + 4 * hi; }
; template <int MODE, int VW>
; __device__ __forceinline__ void attn_unit_s(const AttnP& P, char* lds, const int tid) {
;     ...
;     float rli[16];
; #pragma unroll
;     for (int r = 0; r < 16; ++r) rli[r] = __builtin_amdgcn_rcpf(li_l[crow(r, hi)]);
;     {
;         char* st = lds + wid * 10240;
;         const bool odd = (r32 & 1) != 0;
;         const int sbase = (crow(0, hi) + (odd ? 1 : 0)) * 320 + (r32 & ~1) * 2;
;         bf16_t* Ow = P.O + (long)(wid * QBLK) * P.ldo;
; #pragma unroll
;         for (int hv = 0; hv < VW; ++hv) {
; #pragma unroll
;             for (int d0 = 0; d0 < 4; ++d0)
; #pragma unroll
;                 for (int rp = 0; rp < 8; ++rp) { const int r = 2 * rp;
;                     const float a = o[hv * 4 + d0][r] * rli[r], bb = o[hv * 4 + d0][r + 1] * rli[r + 1];
;                     const float t = odd ? a : bb; const float rcv = dpp_xor1(t);
;                     const unsigned w = odd ? cvt_pk_bf16(rcv, bb) : cvt_pk_bf16(a, rcv);
;                     *(unsigned*)(st + sbase + (crow(r, 0)) * 320 + d0 * 64) = w; }
.LBB0_630:
	s_or_b64 exec, exec, s[2:3]
	v_rcp_f32_e32 v58, v72
	v_rcp_f32_e32 v59, v73
	ds_write_b32 v50, v70 offset:5120
	v_mul_f32_e32 v60, v60, v58
	v_mul_f32_e32 v71, v61, v59
	v_cndmask_b32_e64 v70, v60, v71, s[0:1]
	s_nop 1
	v_mov_b32_dpp v61, v70 quad_perm:[1,0,3,2] row_mask:0xf bank_mask:0xf
	s_and_saveexec_b64 s[2:3], vcc
	s_xor_b64 s[2:3], exec, s[2:3]
	s_cbranch_execz .LBB0_632
	v_cvt_pk_bf16_f32 v70, v61, v71

; __device__ __forceinline__ unsigned cvt_pk_bf16(float lo, float hi) { unsigned r; asm volatile("v_cvt_pk_bf16_f32 %0, %1, %2" : "=v"(r) : "v"(lo), "v"(hi)); return r; }
; __device__ __forceinline__ unsigned dpp_xor1(unsigned v) { return (unsigned)__builtin_amdgcn_update_dpp(0, (int)v, 0xB1, 0xf, 0xf, false); }
; __device__ __forceinline__ float dpp_xor1(float v) { return __int_as_float(__builtin_amdgcn_update_dpp(0, __float_as_int(v), 0xB1, 0xf, 0xf, false)); }
; __device__ __forceinline__ int crow(int r, int hi) { return (r & 3) + 8 * (r >> 2) + 4 * hi; }
; template <int MODE, int VW>
; __device__ __forceinline__ void attn_unit_s(const AttnP& P, char* lds, const int tid) {
;     ...
;     float rli[16];
; #pragma unroll
;     for (int r = 0; r < 16; ++r) rli[r] = __builtin_amdgcn_rcpf(li_l[crow(r, hi)]);
;     {
;         char* st = lds + wid * 10240;
;         const bool odd = (r32 & 1) != 0;
;         const int sbase = (crow(0, hi) + (odd ? 1 : 0)) * 320 + (r32 & ~1) * 2;
;         bf16_t* Ow = P.O + (long)(wid * QBLK) * P.ldo;
; #pragma unroll
;         for (int hv = 0; hv < VW; ++hv) {
; #pragma unroll
;             for (int d0 = 0; d0 < 4; ++d0)
; #pragma unroll
;                 for (int rp = 0; rp < 8; ++rp) { const int r = 2 * rp;
;                     const float a = o[hv * 4 + d0][r] * rli[r], bb = o[hv * 4 + d0][r + 1] * rli[r + 1];
;                     const float t = odd ? a : bb; const float rcv = dpp_xor1(t);
;                     const unsigned w = odd ? cvt_pk_bf16(rcv, bb) : cvt_pk_bf16(a, rcv);
;                     *(unsigned*)(st + sbase + (crow(r, 0)) * 320 + d0 * 64) = w; }
.LBB0_634:
	s_or_b64 exec, exec, s[2:3]
	s_waitcnt lgkmcnt(5)
	v_rcp_f32_e32 v60, v66
	v_rcp_f32_e32 v61, v67
	ds_write_b32 v50, v70 offset:5760
	v_mul_f32_e32 v62, v62, v60
	v_mul_f32_e32 v67, v63, v61
	v_cndmask_b32_e64 v66, v62, v67, s[0:1]
	s_nop 1
	v_mov_b32_dpp v63, v66 quad_perm:[1,0,3,2] row_mask:0xf bank_mask:0xf
	s_and_saveexec_b64 s[2:3], vcc
	s_xor_b64 s[2:3], exec, s[2:3]
	s_cbranch_execz .LBB0_636
	v_cvt_pk_bf16_f32 v66, v63, v67

; __device__ __forceinline__ unsigned cvt_pk_bf16(float lo, float hi) { unsigned r; asm volatile("v_cvt_pk_bf16_f32 %0, %1, %2" : "=v"(r) : "v"(lo), "v"(hi)); return r; }
; __device__ __forceinline__ unsigned dpp_xor1(unsigned v) { return (unsigned)__builtin_amdgcn_update_dpp(0, (int)v, 0xB1, 0xf, 0xf, false); }
; __device__ __forceinline__ float dpp_xor1(float v) { return __int_as_float(__builtin_amdgcn_update_dpp(0, __float_as_int(v), 0xB1, 0xf, 0xf, false)); }
; __device__ __forceinline__ int crow(int r, int hi) { return (r & 3) + 8 * (r >> 2) + 4 * hi; }
; template <int MODE, int VW>
; __device__ __forceinline__ void attn_unit_s(const AttnP& P, char* lds, const int tid) {
;     ...
;     float rli[16];
; #pragma unroll
;     for (int r = 0; r < 16; ++r) rli[r] = __builtin_amdgcn_rcpf(li_l[crow(r, hi)]);
;     {
;         char* st = lds + wid * 10240;
;         const bool odd = (r32 & 1) != 0;
;         const int sbase = (crow(0, hi) + (odd ? 1 : 0)) * 320 + (r32 & ~1) * 2;
;         bf16_t* Ow = P.O + (long)(wid * QBLK) * P.ldo;
; #pragma unroll
;         for (int hv = 0; hv < VW; ++hv) {
; #pragma unroll
;             for (int d0 = 0; d0 < 4; ++d0)
; #pragma unroll
;                 for (int rp = 0; rp < 8; ++rp) { const int r = 2 * rp;
;                     const float a = o[hv * 4 + d0][r] * rli[r], bb = o[hv * 4 + d0][r + 1] * rli[r + 1];
;                     const float t = odd ? a : bb; const float rcv = dpp_xor1(t);
;                     const unsigned w = odd ? cvt_pk_bf16(rcv, bb) : cvt_pk_bf16(a, rcv);
;                     *(unsigned*)(st + sbase + (crow(r, 0)) * 320 + d0 * 64) = w; }
.LBB0_638:
	s_or_b64 exec, exec, s[2:3]
	v_rcp_f32_e32 v62, v68
	v_rcp_f32_e32 v63, v69
	ds_write_b32 v50, v66 offset:7680
	v_mul_f32_e32 v66, v64, v62
	v_mul_f32_e32 v67, v65, v63
	v_cndmask_b32_e64 v64, v66, v67, s[0:1]
	s_nop 1
	v_mov_b32_dpp v65, v64 quad_perm:[1,0,3,2] row_mask:0xf bank_mask:0xf
	s_and_saveexec_b64 s[2:3], vcc
	s_xor_b64 s[2:3], exec, s[2:3]
	s_cbranch_execz .LBB0_640
	v_cvt_pk_bf16_f32 v64, v65, v67

; __device__ __forceinline__ unsigned cvt_pk_bf16(float lo, float hi) { unsigned r; asm volatile("v_cvt_pk_bf16_f32 %0, %1, %2" : "=v"(r) : "v"(lo), "v"(hi)); return r; }
; __device__ __forceinline__ unsigned dpp_xor1(unsigned v) { return (unsigned)__builtin_amdgcn_update_dpp(0, (int)v, 0xB1, 0xf, 0xf, false); }
; __device__ __forceinline__ float dpp_xor1(float v) { return __int_as_float(__builtin_amdgcn_update_dpp(0, __float_as_int(v), 0xB1, 0xf, 0xf, false)); }
; __device__ __forceinline__ int crow(int r, int hi) { return (r & 3) + 8 * (r >> 2) + 4 * hi; }
; template <int MODE, int VW>
; __device__ __forceinline__ void attn_unit_s(const AttnP& P, char* lds, const int tid) {
;     ...
;             for (int d0 = 0; d0 < 4; ++d0)
; #pragma unroll
;                 for (int rp = 0; rp < 8; ++rp) { const int r = 2 * rp;
;                     const float a = o[hv * 4 + d0][r] * rli[r], bb = o[hv * 4 + d0][r + 1] * rli[r + 1];
;                     const float t = odd ? a : bb; const float rcv = dpp_xor1(t);
;                     const unsigned w = odd ? cvt_pk_bf16(rcv, bb) : cvt_pk_bf16(a, rcv);
;                     *(unsigned*)(st + sbase + (crow(r, 0)) * 320 + d0 * 64) = w; }
.LBB0_642:
	s_or_b64 exec, exec, s[2:3]
	ds_write_b32 v50, v64 offset:8320
	v_mul_f32_e32 v64, v34, v0
	v_mul_f32_e32 v65, v35, v78
	v_cndmask_b32_e64 v34, v64, v65, s[0:1]
	s_nop 1
	v_mov_b32_dpp v35, v34 quad_perm:[1,0,3,2] row_mask:0xf bank_mask:0xf
	s_and_saveexec_b64 s[2:3], vcc
	s_xor_b64 s[2:3], exec, s[2:3]
	s_cbranch_execz .LBB0_644
	v_cvt_pk_bf16_f32 v34, v35, v65

; __device__ __forceinline__ unsigned cvt_pk_bf16(float lo, float hi) { unsigned r; asm volatile("v_cvt_pk_bf16_f32 %0, %1, %2" : "=v"(r) : "v"(lo), "v"(hi)); return r; }
; __device__ __forceinline__ unsigned dpp_xor1(unsigned v) { return (unsigned)__builtin_amdgcn_update_dpp(0, (int)v, 0xB1, 0xf, 0xf, false); }
; __device__ __forceinline__ float dpp_xor1(float v) { return __int_as_float(__builtin_amdgcn_update_dpp(0, __float_as_int(v), 0xB1, 0xf, 0xf, false)); }
; __device__ __forceinline__ int crow(int r, int hi) { return (r & 3) + 8 * (r >> 2) + 4 * hi; }
; template <int MODE, int VW>
; __device__ __forceinline__ void attn_unit_s(const AttnP& P, char* lds, const int tid) {
;     ...
;             for (int d0 = 0; d0 < 4; ++d0)
; #pragma unroll
;                 for (int rp = 0; rp < 8; ++rp) { const int r = 2 * rp;
;                     const float a = o[hv * 4 + d0][r] * rli[r], bb = o[hv * 4 + d0][r + 1] * rli[r + 1];
;                     const float t = odd ? a : bb; const float rcv = dpp_xor1(t);
;                     const unsigned w = odd ? cvt_pk_bf16(rcv, bb) : cvt_pk_bf16(a, rcv);
;                     *(unsigned*)(st + sbase + (crow(r, 0)) * 320 + d0 * 64) = w; }
.LBB0_646:
	s_or_b64 exec, exec, s[2:3]
	v_mul_f32_e32 v35, v36, v51
	v_mul_f32_e32 v37, v37, v79
	ds_write_b32 v50, v34 offset:64
	v_cndmask_b32_e64 v34, v35, v37, s[0:1]
	s_nop 1
	v_mov_b32_dpp v36, v34 quad_perm:[1,0,3,2] row_mask:0xf bank_mask:0xf
	s_and_saveexec_b64 s[2:3], vcc
	s_xor_b64 s[2:3], exec, s[2:3]
	s_cbranch_execz .LBB0_648
	v_cvt_pk_bf16_f32 v34, v36, v37

; __device__ __forceinline__ unsigned cvt_pk_bf16(float lo, float hi) { unsigned r; asm volatile("v_cvt_pk_bf16_f32 %0, %1, %2" : "=v"(r) : "v"(lo), "v"(hi)); return r; }
; __device__ __forceinline__ unsigned dpp_xor1(unsigned v) { return (unsigned)__builtin_amdgcn_update_dpp(0, (int)v, 0xB1, 0xf, 0xf, false); }
; __device__ __forceinline__ float dpp_xor1(float v) { return __int_as_float(__builtin_amdgcn_update_dpp(0, __float_as_int(v), 0xB1, 0xf, 0xf, false)); }
; __device__ __forceinline__ int crow(int r, int hi) { return (r & 3) + 8 * (r >> 2) + 4 * hi; }
; template <int MODE, int VW>
; __device__ __forceinline__ void attn_unit_s(const AttnP& P, char* lds, const int tid) {
;     ...
;             for (int d0 = 0; d0 < 4; ++d0)
; #pragma unroll
;                 for (int rp = 0; rp < 8; ++rp) { const int r = 2 * rp;
;                     const float a = o[hv * 4 + d0][r] * rli[r], bb = o[hv * 4 + d0][r + 1] * rli[r + 1];
;                     const float t = odd ? a : bb; const float rcv = dpp_xor1(t);
;                     const unsigned w = odd ? cvt_pk_bf16(rcv, bb) : cvt_pk_bf16(a, rcv);
;                     *(unsigned*)(st + sbase + (crow(r, 0)) * 320 + d0 * 64) = w; }
.LBB0_650:
	s_or_b64 exec, exec, s[2:3]
	v_mul_f32_e32 v35, v38, v52
	v_mul_f32_e32 v37, v39, v53
	ds_write_b32 v50, v34 offset:704
	v_cndmask_b32_e64 v34, v35, v37, s[0:1]
	s_nop 1
	v_mov_b32_dpp v36, v34 quad_perm:[1,0,3,2] row_mask:0xf bank_mask:0xf
	s_and_saveexec_b64 s[2:3], vcc
	s_xor_b64 s[2:3], exec, s[2:3]
	s_cbranch_execz .LBB0_652
	v_cvt_pk_bf16_f32 v34, v36, v37

; __device__ __forceinline__ unsigned cvt_pk_bf16(float lo, float hi) { unsigned r; asm volatile("v_cvt_pk_bf16_f32 %0, %1, %2" : "=v"(r) : "v"(lo), "v"(hi)); return r; }
; __device__ __forceinline__ unsigned dpp_xor1(unsigned v) { return (unsigned)__builtin_amdgcn_update_dpp(0, (int)v, 0xB1, 0xf, 0xf, false); }
; __device__ __forceinline__ float dpp_xor1(float v) { return __int_as_float(__builtin_amdgcn_update_dpp(0, __float_as_int(v), 0xB1, 0xf, 0xf, false)); }
; __device__ __forceinline__ int crow(int r, int hi) { return (r & 3) + 8 * (r >> 2) + 4 * hi; }
; template <int MODE, int VW>
; __device__ __forceinline__ void attn_unit_s(const AttnP& P, char* lds, const int tid) {
;     ...
;             for (int d0 = 0; d0 < 4; ++d0)
; #pragma unroll
;                 for (int rp = 0; rp < 8; ++rp) { const int r = 2 * rp;
;                     const float a = o[hv * 4 + d0][r] * rli[r], bb = o[hv * 4 + d0][r + 1] * rli[r + 1];
;                     const float t = odd ? a : bb; const float rcv = dpp_xor1(t);
;                     const unsigned w = odd ? cvt_pk_bf16(rcv, bb) : cvt_pk_bf16(a, rcv);
;                     *(unsigned*)(st + sbase + (crow(r, 0)) * 320 + d0 * 64) = w; }
.LBB0_654:
	s_or_b64 exec, exec, s[2:3]
	v_mul_f32_e32 v35, v40, v54
	v_mul_f32_e32 v37, v41, v55
	ds_write_b32 v50, v34 offset:2624
	v_cndmask_b32_e64 v34, v35, v37, s[0:1]
	s_nop 1
	v_mov_b32_dpp v36, v34 quad_perm:[1,0,3,2] row_mask:0xf bank_mask:0xf
	s_and_saveexec_b64 s[2:3], vcc
	s_xor_b64 s[2:3], exec, s[2:3]
	s_cbranch_execz .LBB0_656
	v_cvt_pk_bf16_f32 v34, v36, v37

; __device__ __forceinline__ unsigned cvt_pk_bf16(float lo, float hi) { unsigned r; asm volatile("v_cvt_pk_bf16_f32 %0, %1, %2" : "=v"(r) : "v"(lo), "v"(hi)); return r; }
; __device__ __forceinline__ unsigned dpp_xor1(unsigned v) { return (unsigned)__builtin_amdgcn_update_dpp(0, (int)v, 0xB1, 0xf, 0xf, false); }
; __device__ __forceinline__ float dpp_xor1(float v) { return __int_as_float(__builtin_amdgcn_update_dpp(0, __float_as_int(v), 0xB1, 0xf, 0xf, false)); }
; __device__ __forceinline__ int crow(int r, int hi) { return (r & 3) + 8 * (r >> 2) + 4 * hi; }
; template <int MODE, int VW>
; __device__ __forceinline__ void attn_unit_s(const AttnP& P, char* lds, const int tid) {
;     ...
;             for (int d0 = 0; d0 < 4; ++d0)
; #pragma unroll
;                 for (int rp = 0; rp < 8; ++rp) { const int r = 2 * rp;
;                     const float a = o[hv * 4 + d0][r] * rli[r], bb = o[hv * 4 + d0][r + 1] * rli[r + 1];
;                     const float t = odd ? a : bb; const float rcv = dpp_xor1(t);
;                     const unsigned w = odd ? cvt_pk_bf16(rcv, bb) : cvt_pk_bf16(a, rcv);
;                     *(unsigned*)(st + sbase + (crow(r, 0)) * 320 + d0 * 64) = w; }
.LBB0_658:
	s_or_b64 exec, exec, s[2:3]
	v_mul_f32_e32 v35, v42, v56
	v_mul_f32_e32 v37, v43, v57
	ds_write_b32 v50, v34 offset:3264
	v_cndmask_b32_e64 v34, v35, v37, s[0:1]
	s_nop 1
	v_mov_b32_dpp v36, v34 quad_perm:[1,0,3,2] row_mask:0xf bank_mask:0xf
	s_and_saveexec_b64 s[2:3], vcc
	s_xor_b64 s[2:3], exec, s[2:3]
	s_cbranch_execz .LBB0_660
	v_cvt_pk_bf16_f32 v34, v36, v37

; __device__ __forceinline__ unsigned cvt_pk_bf16(float lo, float hi) { unsigned r; asm volatile("v_cvt_pk_bf16_f32 %0, %1, %2" : "=v"(r) : "v"(lo), "v"(hi)); return r; }
; __device__ __forceinline__ unsigned dpp_xor1(unsigned v) { return (unsigned)__builtin_amdgcn_update_dpp(0, (int)v, 0xB1, 0xf, 0xf, false); }
; __device__ __forceinline__ float dpp_xor1(float v) { return __int_as_float(__builtin_amdgcn_update_dpp(0, __float_as_int(v), 0xB1, 0xf, 0xf, false)); }
; __device__ __forceinline__ int crow(int r, int hi) { return (r & 3) + 8 * (r >> 2) + 4 * hi; }
; template <int MODE, int VW>
; __device__ __forceinline__ void attn_unit_s(const AttnP& P, char* lds, const int tid) {
;     ...
;             for (int d0 = 0; d0 < 4; ++d0)
; #pragma unroll
;                 for (int rp = 0; rp < 8; ++rp) { const int r = 2 * rp;
;                     const float a = o[hv * 4 + d0][r] * rli[r], bb = o[hv * 4 + d0][r + 1] * rli[r + 1];
;                     const float t = odd ? a : bb; const float rcv = dpp_xor1(t);
;                     const unsigned w = odd ? cvt_pk_bf16(rcv, bb) : cvt_pk_bf16(a, rcv);
;                     *(unsigned*)(st + sbase + (crow(r, 0)) * 320 + d0 * 64) = w; }
.LBB0_662:
	s_or_b64 exec, exec, s[2:3]
	v_mul_f32_e32 v35, v44, v58
	v_mul_f32_e32 v37, v45, v59
	ds_write_b32 v50, v34 offset:5184
	v_cndmask_b32_e64 v34, v35, v37, s[0:1]
	s_nop 1
	v_mov_b32_dpp v36, v34 quad_perm:[1,0,3,2] row_mask:0xf bank_mask:0xf
	s_and_saveexec_b64 s[2:3], vcc
	s_xor_b64 s[2:3], exec, s[2:3]
	s_cbranch_execz .LBB0_664
	v_cvt_pk_bf16_f32 v34, v36, v37

; __device__ __forceinline__ unsigned cvt_pk_bf16(float lo, float hi) { unsigned r; asm volatile("v_cvt_pk_bf16_f32 %0, %1, %2" : "=v"(r) : "v"(lo), "v"(hi)); return r; }
; __device__ __forceinline__ unsigned dpp_xor1(unsigned v) { return (unsigned)__builtin_amdgcn_update_dpp(0, (int)v, 0xB1, 0xf, 0xf, false); }
; __device__ __forceinline__ float dpp_xor1(float v) { return __int_as_float(__builtin_amdgcn_update_dpp(0, __float_as_int(v), 0xB1, 0xf, 0xf, false)); }
; __device__ __forceinline__ int crow(int r, int hi) { return (r & 3) + 8 * (r >> 2) + 4 * hi; }
; template <int MODE, int VW>
; __device__ __forceinline__ void attn_unit_s(const AttnP& P, char* lds, const int tid) {
;     ...
;             for (int d0 = 0; d0 < 4; ++d0)
; #pragma unroll
;                 for (int rp = 0; rp < 8; ++rp) { const int r = 2 * rp;
;                     const float a = o[hv * 4 + d0][r] * rli[r], bb = o[hv * 4 + d0][r + 1] * rli[r + 1];
;                     const float t = odd ? a : bb; const float rcv = dpp_xor1(t);
;                     const unsigned w = odd ? cvt_pk_bf16(rcv, bb) : cvt_pk_bf16(a, rcv);
;                     *(unsigned*)(st + sbase + (crow(r, 0)) * 320 + d0 * 64) = w; }
.LBB0_666:
	s_or_b64 exec, exec, s[2:3]
	v_mul_f32_e32 v35, v46, v60
	v_mul_f32_e32 v37, v47, v61
	ds_write_b32 v50, v34 offset:5824
	v_cndmask_b32_e64 v34, v35, v37, s[0:1]
	s_nop 1
	v_mov_b32_dpp v36, v34 quad_perm:[1,0,3,2] row_mask:0xf bank_mask:0xf
	s_and_saveexec_b64 s[2:3], vcc
	s_xor_b64 s[2:3], exec, s[2:3]
	s_cbranch_execz .LBB0_668
	v_cvt_pk_bf16_f32 v34, v36, v37

; __device__ __forceinline__ unsigned cvt_pk_bf16(float lo, float hi) { unsigned r; asm volatile("v_cvt_pk_bf16_f32 %0, %1, %2" : "=v"(r) : "v"(lo), "v"(hi)); return r; }
; __device__ __forceinline__ unsigned dpp_xor1(unsigned v) { return (unsigned)__builtin_amdgcn_update_dpp(0, (int)v, 0xB1, 0xf, 0xf, false); }
; __device__ __forceinline__ float dpp_xor1(float v) { return __int_as_float(__builtin_amdgcn_update_dpp(0, __float_as_int(v), 0xB1, 0xf, 0xf, false)); }
; __device__ __forceinline__ int crow(int r, int hi) { return (r & 3) + 8 * (r >> 2) + 4 * hi; }
; template <int MODE, int VW>
; __device__ __forceinline__ void attn_unit_s(const AttnP& P, char* lds, const int tid) {
;     ...
;             for (int d0 = 0; d0 < 4; ++d0)
; #pragma unroll
;                 for (int rp = 0; rp < 8; ++rp) { const int r = 2 * rp;
;                     const float a = o[hv * 4 + d0][r] * rli[r], bb = o[hv * 4 + d0][r + 1] * rli[r + 1];
;                     const float t = odd ? a : bb; const float rcv = dpp_xor1(t);
;                     const unsigned w = odd ? cvt_pk_bf16(rcv, bb) : cvt_pk_bf16(a, rcv);
;                     *(unsigned*)(st + sbase + (crow(r, 0)) * 320 + d0 * 64) = w; }
.LBB0_670:
	s_or_b64 exec, exec, s[2:3]
	v_mul_f32_e32 v35, v48, v62
	v_mul_f32_e32 v37, v49, v63
	ds_write_b32 v50, v34 offset:7744
	v_cndmask_b32_e64 v34, v35, v37, s[0:1]
	s_nop 1
	v_mov_b32_dpp v36, v34 quad_perm:[1,0,3,2] row_mask:0xf bank_mask:0xf
	s_and_saveexec_b64 s[2:3], vcc
	s_xor_b64 s[2:3], exec, s[2:3]
	s_cbranch_execz .LBB0_672
	v_cvt_pk_bf16_f32 v34, v36, v37

; __device__ __forceinline__ unsigned cvt_pk_bf16(float lo, float hi) { unsigned r; asm volatile("v_cvt_pk_bf16_f32 %0, %1, %2" : "=v"(r) : "v"(lo), "v"(hi)); return r; }
; __device__ __forceinline__ unsigned dpp_xor1(unsigned v) { return (unsigned)__builtin_amdgcn_update_dpp(0, (int)v, 0xB1, 0xf, 0xf, false); }
; __device__ __forceinline__ float dpp_xor1(float v) { return __int_as_float(__builtin_amdgcn_update_dpp(0, __float_as_int(v), 0xB1, 0xf, 0xf, false)); }
; __device__ __forceinline__ int crow(int r, int hi) { return (r & 3) + 8 * (r >> 2) + 4 * hi; }
; template <int MODE, int VW>
; __device__ __forceinline__ void attn_unit_s(const AttnP& P, char* lds, const int tid) {
;     ...
;             for (int d0 = 0; d0 < 4; ++d0)
; #pragma unroll
;                 for (int rp = 0; rp < 8; ++rp) { const int r = 2 * rp;
;                     const float a = o[hv * 4 + d0][r] * rli[r], bb = o[hv * 4 + d0][r + 1] * rli[r + 1];
;                     const float t = odd ? a : bb; const float rcv = dpp_xor1(t);
;                     const unsigned w = odd ? cvt_pk_bf16(rcv, bb) : cvt_pk_bf16(a, rcv);
;                     *(unsigned*)(st + sbase + (crow(r, 0)) * 320 + d0 * 64) = w; }
.LBB0_674:
	s_or_b64 exec, exec, s[2:3]
	ds_write_b32 v50, v34 offset:8384
	v_mul_f32_e32 v34, v18, v0
	v_mul_f32_e32 v35, v19, v78
	v_cndmask_b32_e64 v18, v34, v35, s[0:1]
	s_nop 1
	v_mov_b32_dpp v19, v18 quad_perm:[1,0,3,2] row_mask:0xf bank_mask:0xf
	s_and_saveexec_b64 s[2:3], vcc
	s_xor_b64 s[2:3], exec, s[2:3]
	s_cbranch_execz .LBB0_676
	v_cvt_pk_bf16_f32 v18, v19, v35

; __device__ __forceinline__ unsigned cvt_pk_bf16(float lo, float hi) { unsigned r; asm volatile("v_cvt_pk_bf16_f32 %0, %1, %2" : "=v"(r) : "v"(lo), "v"(hi)); return r; }
; __device__ __forceinline__ unsigned dpp_xor1(unsigned v) { return (unsigned)__builtin_amdgcn_update_dpp(0, (int)v, 0xB1, 0xf, 0xf, false); }
; __device__ __forceinline__ float dpp_xor1(float v) { return __int_as_float(__builtin_amdgcn_update_dpp(0, __float_as_int(v), 0xB1, 0xf, 0xf, false)); }
; __device__ __forceinline__ int crow(int r, int hi) { return (r & 3) + 8 * (r >> 2) + 4 * hi; }
; template <int MODE, int VW>
; __device__ __forceinline__ void attn_unit_s(const AttnP& P, char* lds, const int tid) {
;     ...
;             for (int d0 = 0; d0 < 4; ++d0)
; #pragma unroll
;                 for (int rp = 0; rp < 8; ++rp) { const int r = 2 * rp;
;                     const float a = o[hv * 4 + d0][r] * rli[r], bb = o[hv * 4 + d0][r + 1] * rli[r + 1];
;                     const float t = odd ? a : bb; const float rcv = dpp_xor1(t);
;                     const unsigned w = odd ? cvt_pk_bf16(rcv, bb) : cvt_pk_bf16(a, rcv);
;                     *(unsigned*)(st + sbase + (crow(r, 0)) * 320 + d0 * 64) = w; }
.LBB0_678:
	s_or_b64 exec, exec, s[2:3]
	v_mul_f32_e32 v19, v20, v51
	v_mul_f32_e32 v21, v21, v79
	ds_write_b32 v50, v18 offset:128
	v_cndmask_b32_e64 v18, v19, v21, s[0:1]
	s_nop 1
	v_mov_b32_dpp v20, v18 quad_perm:[1,0,3,2] row_mask:0xf bank_mask:0xf
	s_and_saveexec_b64 s[2:3], vcc
	s_xor_b64 s[2:3], exec, s[2:3]
	s_cbranch_execz .LBB0_680
	v_cvt_pk_bf16_f32 v18, v20, v21

; __device__ __forceinline__ unsigned cvt_pk_bf16(float lo, float hi) { unsigned r; asm volatile("v_cvt_pk_bf16_f32 %0, %1, %2" : "=v"(r) : "v"(lo), "v"(hi)); return r; }
; __device__ __forceinline__ unsigned dpp_xor1(unsigned v) { return (unsigned)__builtin_amdgcn_update_dpp(0, (int)v, 0xB1, 0xf, 0xf, false); }
; __device__ __forceinline__ float dpp_xor1(float v) { return __int_as_float(__builtin_amdgcn_update_dpp(0, __float_as_int(v), 0xB1, 0xf, 0xf, false)); }
; __device__ __forceinline__ int crow(int r, int hi) { return (r & 3) + 8 * (r >> 2) + 4 * hi; }
; template <int MODE, int VW>
; __device__ __forceinline__ void attn_unit_s(const AttnP& P, char* lds, const int tid) {
;     ...
;             for (int d0 = 0; d0 < 4; ++d0)
; #pragma unroll
;                 for (int rp = 0; rp < 8; ++rp) { const int r = 2 * rp;
;                     const float a = o[hv * 4 + d0][r] * rli[r], bb = o[hv * 4 + d0][r + 1] * rli[r + 1];
;                     const float t = odd ? a : bb; const float rcv = dpp_xor1(t);
;                     const unsigned w = odd ? cvt_pk_bf16(rcv, bb) : cvt_pk_bf16(a, rcv);
;                     *(unsigned*)(st + sbase + (crow(r, 0)) * 320 + d0 * 64) = w; }
.LBB0_682:
	s_or_b64 exec, exec, s[2:3]
	v_mul_f32_e32 v19, v22, v52
	v_mul_f32_e32 v21, v23, v53
	ds_write_b32 v50, v18 offset:768
	v_cndmask_b32_e64 v18, v19, v21, s[0:1]
	s_nop 1
	v_mov_b32_dpp v20, v18 quad_perm:[1,0,3,2] row_mask:0xf bank_mask:0xf
	s_and_saveexec_b64 s[2:3], vcc
	s_xor_b64 s[2:3], exec, s[2:3]
	s_cbranch_execz .LBB0_684
	v_cvt_pk_bf16_f32 v18, v20, v21

; __device__ __forceinline__ unsigned cvt_pk_bf16(float lo, float hi) { unsigned r; asm volatile("v_cvt_pk_bf16_f32 %0, %1, %2" : "=v"(r) : "v"(lo), "v"(hi)); return r; }
; __device__ __forceinline__ unsigned dpp_xor1(unsigned v) { return (unsigned)__builtin_amdgcn_update_dpp(0, (int)v, 0xB1, 0xf, 0xf, false); }
; __device__ __forceinline__ float dpp_xor1(float v) { return __int_as_float(__builtin_amdgcn_update_dpp(0, __float_as_int(v), 0xB1, 0xf, 0xf, false)); }
; __device__ __forceinline__ int crow(int r, int hi) { return (r & 3) + 8 * (r >> 2) + 4 * hi; }
; template <int MODE, int VW>
; __device__ __forceinline__ void attn_unit_s(const AttnP& P, char* lds, const int tid) {
;     ...
;             for (int d0 = 0; d0 < 4; ++d0)
; #pragma unroll
;                 for (int rp = 0; rp < 8; ++rp) { const int r = 2 * rp;
;                     const float a = o[hv * 4 + d0][r] * rli[r], bb = o[hv * 4 + d0][r + 1] * rli[r + 1];
;                     const float t = odd ? a : bb; const float rcv = dpp_xor1(t);
;                     const unsigned w = odd ? cvt_pk_bf16(rcv, bb) : cvt_pk_bf16(a, rcv);
;                     *(unsigned*)(st + sbase + (crow(r, 0)) * 320 + d0 * 64) = w; }
.LBB0_686:
	s_or_b64 exec, exec, s[2:3]
	v_mul_f32_e32 v19, v24, v54
	v_mul_f32_e32 v21, v25, v55
	ds_write_b32 v50, v18 offset:2688
	v_cndmask_b32_e64 v18, v19, v21, s[0:1]
	s_nop 1
	v_mov_b32_dpp v20, v18 quad_perm:[1,0,3,2] row_mask:0xf bank_mask:0xf
	s_and_saveexec_b64 s[2:3], vcc
	s_xor_b64 s[2:3], exec, s[2:3]
	s_cbranch_execz .LBB0_688
	v_cvt_pk_bf16_f32 v18, v20, v21

; __device__ __forceinline__ unsigned cvt_pk_bf16(float lo, float hi) { unsigned r; asm volatile("v_cvt_pk_bf16_f32 %0, %1, %2" : "=v"(r) : "v"(lo), "v"(hi)); return r; }
; __device__ __forceinline__ unsigned dpp_xor1(unsigned v) { return (unsigned)__builtin_amdgcn_update_dpp(0, (int)v, 0xB1, 0xf, 0xf, false); }
; __device__ __forceinline__ float dpp_xor1(float v) { return __int_as_float(__builtin_amdgcn_update_dpp(0, __float_as_int(v), 0xB1, 0xf, 0xf, false)); }
; __device__ __forceinline__ int crow(int r, int hi) { return (r & 3) + 8 * (r >> 2) + 4 * hi; }
; template <int MODE, int VW>
; __device__ __forceinline__ void attn_unit_s(const AttnP& P, char* lds, const int tid) {
;     ...
;             for (int d0 = 0; d0 < 4; ++d0)
; #pragma unroll
;                 for (int rp = 0; rp < 8; ++rp) { const int r = 2 * rp;
;                     const float a = o[hv * 4 + d0][r] * rli[r], bb = o[hv * 4 + d0][r + 1] * rli[r + 1];
;                     const float t = odd ? a : bb; const float rcv = dpp_xor1(t);
;                     const unsigned w = odd ? cvt_pk_bf16(rcv, bb) : cvt_pk_bf16(a, rcv);
;                     *(unsigned*)(st + sbase + (crow(r, 0)) * 320 + d0 * 64) = w; }
.LBB0_690:
	s_or_b64 exec, exec, s[2:3]
	v_mul_f32_e32 v19, v26, v56
	v_mul_f32_e32 v21, v27, v57
	ds_write_b32 v50, v18 offset:3328
	v_cndmask_b32_e64 v18, v19, v21, s[0:1]
	s_nop 1
	v_mov_b32_dpp v20, v18 quad_perm:[1,0,3,2] row_mask:0xf bank_mask:0xf
	s_and_saveexec_b64 s[2:3], vcc
	s_xor_b64 s[2:3], exec, s[2:3]
	s_cbranch_execz .LBB0_692
	v_cvt_pk_bf16_f32 v18, v20, v21

; __device__ __forceinline__ unsigned cvt_pk_bf16(float lo, float hi) { unsigned r; asm volatile("v_cvt_pk_bf16_f32 %0, %1, %2" : "=v"(r) : "v"(lo), "v"(hi)); return r; }
; __device__ __forceinline__ unsigned dpp_xor1(unsigned v) { return (unsigned)__builtin_amdgcn_update_dpp(0, (int)v, 0xB1, 0xf, 0xf, false); }
; __device__ __forceinline__ float dpp_xor1(float v) { return __int_as_float(__builtin_amdgcn_update_dpp(0, __float_as_int(v), 0xB1, 0xf, 0xf, false)); }
; __device__ __forceinline__ int crow(int r, int hi) { return (r & 3) + 8 * (r >> 2) + 4 * hi; }
; template <int MODE, int VW>
; __device__ __forceinline__ void attn_unit_s(const AttnP& P, char* lds, const int tid) {
;     ...
;             for (int d0 = 0; d0 < 4; ++d0)
; #pragma unroll
;                 for (int rp = 0; rp < 8; ++rp) { const int r = 2 * rp;
;                     const float a = o[hv * 4 + d0][r] * rli[r], bb = o[hv * 4 + d0][r + 1] * rli[r + 1];
;                     const float t = odd ? a : bb; const float rcv = dpp_xor1(t);
;                     const unsigned w = odd ? cvt_pk_bf16(rcv, bb) : cvt_pk_bf16(a, rcv);
;                     *(unsigned*)(st + sbase + (crow(r, 0)) * 320 + d0 * 64) = w; }
.LBB0_694:
	s_or_b64 exec, exec, s[2:3]
	v_mul_f32_e32 v19, v28, v58
	v_mul_f32_e32 v21, v29, v59
	ds_write_b32 v50, v18 offset:5248
	v_cndmask_b32_e64 v18, v19, v21, s[0:1]
	s_nop 1
	v_mov_b32_dpp v20, v18 quad_perm:[1,0,3,2] row_mask:0xf bank_mask:0xf
	s_and_saveexec_b64 s[2:3], vcc
	s_xor_b64 s[2:3], exec, s[2:3]
	s_cbranch_execz .LBB0_696
	v_cvt_pk_bf16_f32 v18, v20, v21

; __device__ __forceinline__ unsigned cvt_pk_bf16(float lo, float hi) { unsigned r; asm volatile("v_cvt_pk_bf16_f32 %0, %1, %2" : "=v"(r) : "v"(lo), "v"(hi)); return r; }
; __device__ __forceinline__ unsigned dpp_xor1(unsigned v) { return (unsigned)__builtin_amdgcn_update_dpp(0, (int)v, 0xB1, 0xf, 0xf, false); }
; __device__ __forceinline__ float dpp_xor1(float v) { return __int_as_float(__builtin_amdgcn_update_dpp(0, __float_as_int(v), 0xB1, 0xf, 0xf, false)); }
; __device__ __forceinline__ int crow(int r, int hi) { return (r & 3) + 8 * (r >> 2) + 4 * hi; }
; template <int MODE, int VW>
; __device__ __forceinline__ void attn_unit_s(const AttnP& P, char* lds, const int tid) {
;     ...
;             for (int d0 = 0; d0 < 4; ++d0)
; #pragma unroll
;                 for (int rp = 0; rp < 8; ++rp) { const int r = 2 * rp;
;                     const float a = o[hv * 4 + d0][r] * rli[r], bb = o[hv * 4 + d0][r + 1] * rli[r + 1];
;                     const float t = odd ? a : bb; const float rcv = dpp_xor1(t);
;                     const unsigned w = odd ? cvt_pk_bf16(rcv, bb) : cvt_pk_bf16(a, rcv);
;                     *(unsigned*)(st + sbase + (crow(r, 0)) * 320 + d0 * 64) = w; }
.LBB0_698:
	s_or_b64 exec, exec, s[2:3]
	v_mul_f32_e32 v19, v30, v60
	v_mul_f32_e32 v21, v31, v61
	ds_write_b32 v50, v18 offset:5888
	v_cndmask_b32_e64 v18, v19, v21, s[0:1]
	s_nop 1
	v_mov_b32_dpp v20, v18 quad_perm:[1,0,3,2] row_mask:0xf bank_mask:0xf
	s_and_saveexec_b64 s[2:3], vcc
	s_xor_b64 s[2:3], exec, s[2:3]
	s_cbranch_execz .LBB0_700
	v_cvt_pk_bf16_f32 v18, v20, v21

; __device__ __forceinline__ unsigned cvt_pk_bf16(float lo, float hi) { unsigned r; asm volatile("v_cvt_pk_bf16_f32 %0, %1, %2" : "=v"(r) : "v"(lo), "v"(hi)); return r; }
; __device__ __forceinline__ unsigned dpp_xor1(unsigned v) { return (unsigned)__builtin_amdgcn_update_dpp(0, (int)v, 0xB1, 0xf, 0xf, false); }
; __device__ __forceinline__ float dpp_xor1(float v) { return __int_as_float(__builtin_amdgcn_update_dpp(0, __float_as_int(v), 0xB1, 0xf, 0xf, false)); }
; __device__ __forceinline__ int crow(int r, int hi) { return (r & 3) + 8 * (r >> 2) + 4 * hi; }
; template <int MODE, int VW>
; __device__ __forceinline__ void attn_unit_s(const AttnP& P, char* lds, const int tid) {
;     ...
;             for (int d0 = 0; d0 < 4; ++d0)
; #pragma unroll
;                 for (int rp = 0; rp < 8; ++rp) { const int r = 2 * rp;
;                     const float a = o[hv * 4 + d0][r] * rli[r], bb = o[hv * 4 + d0][r + 1] * rli[r + 1];
;                     const float t = odd ? a : bb; const float rcv = dpp_xor1(t);
;                     const unsigned w = odd ? cvt_pk_bf16(rcv, bb) : cvt_pk_bf16(a, rcv);
;                     *(unsigned*)(st + sbase + (crow(r, 0)) * 320 + d0 * 64) = w; }
.LBB0_702:
	s_or_b64 exec, exec, s[2:3]
	v_mul_f32_e32 v19, v32, v62
	v_mul_f32_e32 v21, v33, v63
	ds_write_b32 v50, v18 offset:7808
	v_cndmask_b32_e64 v18, v19, v21, s[0:1]
	s_nop 1
	v_mov_b32_dpp v20, v18 quad_perm:[1,0,3,2] row_mask:0xf bank_mask:0xf
	s_and_saveexec_b64 s[2:3], vcc
	s_xor_b64 s[2:3], exec, s[2:3]
	s_cbranch_execz .LBB0_704
	v_cvt_pk_bf16_f32 v18, v20, v21

; __device__ __forceinline__ unsigned cvt_pk_bf16(float lo, float hi) { unsigned r; asm volatile("v_cvt_pk_bf16_f32 %0, %1, %2" : "=v"(r) : "v"(lo), "v"(hi)); return r; }
; __device__ __forceinline__ unsigned dpp_xor1(unsigned v) { return (unsigned)__builtin_amdgcn_update_dpp(0, (int)v, 0xB1, 0xf, 0xf, false); }
; __device__ __forceinline__ float dpp_xor1(float v) { return __int_as_float(__builtin_amdgcn_update_dpp(0, __float_as_int(v), 0xB1, 0xf, 0xf, false)); }
; __device__ __forceinline__ int crow(int r, int hi) { return (r & 3) + 8 * (r >> 2) + 4 * hi; }
; template <int MODE, int VW>
; __device__ __forceinline__ void attn_unit_s(const AttnP& P, char* lds, const int tid) {
;     ...
;             for (int d0 = 0; d0 < 4; ++d0)
; #pragma unroll
;                 for (int rp = 0; rp < 8; ++rp) { const int r = 2 * rp;
;                     const float a = o[hv * 4 + d0][r] * rli[r], bb = o[hv * 4 + d0][r + 1] * rli[r + 1];
;                     const float t = odd ? a : bb; const float rcv = dpp_xor1(t);
;                     const unsigned w = odd ? cvt_pk_bf16(rcv, bb) : cvt_pk_bf16(a, rcv);
;                     *(unsigned*)(st + sbase + (crow(r, 0)) * 320 + d0 * 64) = w; }
.LBB0_706:
	s_or_b64 exec, exec, s[2:3]
	ds_write_b32 v50, v18 offset:8448
	v_mul_f32_e32 v2, v2, v0
	v_mul_f32_e32 v18, v3, v78
	v_cndmask_b32_e64 v0, v2, v18, s[0:1]
	s_nop 1
	v_mov_b32_dpp v3, v0 quad_perm:[1,0,3,2] row_mask:0xf bank_mask:0xf
	s_and_saveexec_b64 s[2:3], vcc
	s_xor_b64 s[2:3], exec, s[2:3]
	s_cbranch_execz .LBB0_708
	v_cvt_pk_bf16_f32 v0, v3, v18

; __device__ __forceinline__ unsigned cvt_pk_bf16(float lo, float hi) { unsigned r; asm volatile("v_cvt_pk_bf16_f32 %0, %1, %2" : "=v"(r) : "v"(lo), "v"(hi)); return r; }
; __device__ __forceinline__ unsigned dpp_xor1(unsigned v) { return (unsigned)__builtin_amdgcn_update_dpp(0, (int)v, 0xB1, 0xf, 0xf, false); }
; __device__ __forceinline__ float dpp_xor1(float v) { return __int_as_float(__builtin_amdgcn_update_dpp(0, __float_as_int(v), 0xB1, 0xf, 0xf, false)); }
; __device__ __forceinline__ int crow(int r, int hi) { return (r & 3) + 8 * (r >> 2) + 4 * hi; }
; template <int MODE, int VW>
; __device__ __forceinline__ void attn_unit_s(const AttnP& P, char* lds, const int tid) {
;     ...
;             for (int d0 = 0; d0 < 4; ++d0)
; #pragma unroll
;                 for (int rp = 0; rp < 8; ++rp) { const int r = 2 * rp;
;                     const float a = o[hv * 4 + d0][r] * rli[r], bb = o[hv * 4 + d0][r + 1] * rli[r + 1];
;                     const float t = odd ? a : bb; const float rcv = dpp_xor1(t);
;                     const unsigned w = odd ? cvt_pk_bf16(rcv, bb) : cvt_pk_bf16(a, rcv);
;                     *(unsigned*)(st + sbase + (crow(r, 0)) * 320 + d0 * 64) = w; }
.LBB0_710:
	s_or_b64 exec, exec, s[2:3]
	v_mul_f32_e32 v2, v4, v51
	v_mul_f32_e32 v4, v5, v79
	ds_write_b32 v50, v0 offset:192
	v_cndmask_b32_e64 v0, v2, v4, s[0:1]
	s_nop 1
	v_mov_b32_dpp v3, v0 quad_perm:[1,0,3,2] row_mask:0xf bank_mask:0xf
	s_and_saveexec_b64 s[2:3], vcc
	s_xor_b64 s[2:3], exec, s[2:3]
	s_cbranch_execz .LBB0_712
	v_cvt_pk_bf16_f32 v0, v3, v4

; __device__ __forceinline__ unsigned cvt_pk_bf16(float lo, float hi) { unsigned r; asm volatile("v_cvt_pk_bf16_f32 %0, %1, %2" : "=v"(r) : "v"(lo), "v"(hi)); return r; }
; __device__ __forceinline__ unsigned dpp_xor1(unsigned v) { return (unsigned)__builtin_amdgcn_update_dpp(0, (int)v, 0xB1, 0xf, 0xf, false); }
; __device__ __forceinline__ float dpp_xor1(float v) { return __int_as_float(__builtin_amdgcn_update_dpp(0, __float_as_int(v), 0xB1, 0xf, 0xf, false)); }
; __device__ __forceinline__ int crow(int r, int hi) { return (r & 3) + 8 * (r >> 2) + 4 * hi; }
; template <int MODE, int VW>
; __device__ __forceinline__ void attn_unit_s(const AttnP& P, char* lds, const int tid) {
;     ...
;             for (int d0 = 0; d0 < 4; ++d0)
; #pragma unroll
;                 for (int rp = 0; rp < 8; ++rp) { const int r = 2 * rp;
;                     const float a = o[hv * 4 + d0][r] * rli[r], bb = o[hv * 4 + d0][r + 1] * rli[r + 1];
;                     const float t = odd ? a : bb; const float rcv = dpp_xor1(t);
;                     const unsigned w = odd ? cvt_pk_bf16(rcv, bb) : cvt_pk_bf16(a, rcv);
;                     *(unsigned*)(st + sbase + (crow(r, 0)) * 320 + d0 * 64) = w; }
.LBB0_714:
	s_or_b64 exec, exec, s[2:3]
	v_mul_f32_e32 v2, v6, v52
	v_mul_f32_e32 v4, v7, v53
	ds_write_b32 v50, v0 offset:832
	v_cndmask_b32_e64 v0, v2, v4, s[0:1]
	s_nop 1
	v_mov_b32_dpp v3, v0 quad_perm:[1,0,3,2] row_mask:0xf bank_mask:0xf
	s_and_saveexec_b64 s[2:3], vcc
	s_xor_b64 s[2:3], exec, s[2:3]
	s_cbranch_execz .LBB0_716
	v_cvt_pk_bf16_f32 v0, v3, v4

; __device__ __forceinline__ unsigned cvt_pk_bf16(float lo, float hi) { unsigned r; asm volatile("v_cvt_pk_bf16_f32 %0, %1, %2" : "=v"(r) : "v"(lo), "v"(hi)); return r; }
; __device__ __forceinline__ unsigned dpp_xor1(unsigned v) { return (unsigned)__builtin_amdgcn_update_dpp(0, (int)v, 0xB1, 0xf, 0xf, false); }
; __device__ __forceinline__ float dpp_xor1(float v) { return __int_as_float(__builtin_amdgcn_update_dpp(0, __float_as_int(v), 0xB1, 0xf, 0xf, false)); }
; __device__ __forceinline__ int crow(int r, int hi) { return (r & 3) + 8 * (r >> 2) + 4 * hi; }
; template <int MODE, int VW>
; __device__ __forceinline__ void attn_unit_s(const AttnP& P, char* lds, const int tid) {
;     ...
;             for (int d0 = 0; d0 < 4; ++d0)
; #pragma unroll
;                 for (int rp = 0; rp < 8; ++rp) { const int r = 2 * rp;
;                     const float a = o[hv * 4 + d0][r] * rli[r], bb = o[hv * 4 + d0][r + 1] * rli[r + 1];
;                     const float t = odd ? a : bb; const float rcv = dpp_xor1(t);
;                     const unsigned w = odd ? cvt_pk_bf16(rcv, bb) : cvt_pk_bf16(a, rcv);
;                     *(unsigned*)(st + sbase + (crow(r, 0)) * 320 + d0 * 64) = w; }
.LBB0_718:
	s_or_b64 exec, exec, s[2:3]
	v_mul_f32_e32 v2, v8, v54
	v_mul_f32_e32 v4, v9, v55
	ds_write_b32 v50, v0 offset:2752
	v_cndmask_b32_e64 v0, v2, v4, s[0:1]
	s_nop 1
	v_mov_b32_dpp v3, v0 quad_perm:[1,0,3,2] row_mask:0xf bank_mask:0xf
	s_and_saveexec_b64 s[2:3], vcc
	s_xor_b64 s[2:3], exec, s[2:3]
	s_cbranch_execz .LBB0_720
	v_cvt_pk_bf16_f32 v0, v3, v4

; __device__ __forceinline__ unsigned cvt_pk_bf16(float lo, float hi) { unsigned r; asm volatile("v_cvt_pk_bf16_f32 %0, %1, %2" : "=v"(r) : "v"(lo), "v"(hi)); return r; }
; __device__ __forceinline__ unsigned dpp_xor1(unsigned v) { return (unsigned)__builtin_amdgcn_update_dpp(0, (int)v, 0xB1, 0xf, 0xf, false); }
; __device__ __forceinline__ float dpp_xor1(float v) { return __int_as_float(__builtin_amdgcn_update_dpp(0, __float_as_int(v), 0xB1, 0xf, 0xf, false)); }
; __device__ __forceinline__ int crow(int r, int hi) { return (r & 3) + 8 * (r >> 2) + 4 * hi; }
; template <int MODE, int VW>
; __device__ __forceinline__ void attn_unit_s(const AttnP& P, char* lds, const int tid) {
;     ...
;             for (int d0 = 0; d0 < 4; ++d0)
; #pragma unroll
;                 for (int rp = 0; rp < 8; ++rp) { const int r = 2 * rp;
;                     const float a = o[hv * 4 + d0][r] * rli[r], bb = o[hv * 4 + d0][r + 1] * rli[r + 1];
;                     const float t = odd ? a : bb; const float rcv = dpp_xor1(t);
;                     const unsigned w = odd ? cvt_pk_bf16(rcv, bb) : cvt_pk_bf16(a, rcv);
;                     *(unsigned*)(st + sbase + (crow(r, 0)) * 320 + d0 * 64) = w; }
.LBB0_722:
	s_or_b64 exec, exec, s[2:3]
	v_mul_f32_e32 v2, v10, v56
	v_mul_f32_e32 v4, v11, v57
	ds_write_b32 v50, v0 offset:3392
	v_cndmask_b32_e64 v0, v2, v4, s[0:1]
	s_nop 1
	v_mov_b32_dpp v3, v0 quad_perm:[1,0,3,2] row_mask:0xf bank_mask:0xf
	s_and_saveexec_b64 s[2:3], vcc
	s_xor_b64 s[2:3], exec, s[2:3]
	s_cbranch_execz .LBB0_724
	v_cvt_pk_bf16_f32 v0, v3, v4

; __device__ __forceinline__ unsigned cvt_pk_bf16(float lo, float hi) { unsigned r; asm volatile("v_cvt_pk_bf16_f32 %0, %1, %2" : "=v"(r) : "v"(lo), "v"(hi)); return r; }
; __device__ __forceinline__ unsigned dpp_xor1(unsigned v) { return (unsigned)__builtin_amdgcn_update_dpp(0, (int)v, 0xB1, 0xf, 0xf, false); }
; __device__ __forceinline__ float dpp_xor1(float v) { return __int_as_float(__builtin_amdgcn_update_dpp(0, __float_as_int(v), 0xB1, 0xf, 0xf, false)); }
; __device__ __forceinline__ int crow(int r, int hi) { return (r & 3) + 8 * (r >> 2) + 4 * hi; }
; template <int MODE, int VW>
; __device__ __forceinline__ void attn_unit_s(const AttnP& P, char* lds, const int tid) {
;     ...
;             for (int d0 = 0; d0 < 4; ++d0)
; #pragma unroll
;                 for (int rp = 0; rp < 8; ++rp) { const int r = 2 * rp;
;                     const float a = o[hv * 4 + d0][r] * rli[r], bb = o[hv * 4 + d0][r + 1] * rli[r + 1];
;                     const float t = odd ? a : bb; const float rcv = dpp_xor1(t);
;                     const unsigned w = odd ? cvt_pk_bf16(rcv, bb) : cvt_pk_bf16(a, rcv);
;                     *(unsigned*)(st + sbase + (crow(r, 0)) * 320 + d0 * 64) = w; }
.LBB0_726:
	s_or_b64 exec, exec, s[2:3]
	v_mul_f32_e32 v2, v12, v58
	v_mul_f32_e32 v4, v13, v59
	ds_write_b32 v50, v0 offset:5312
	v_cndmask_b32_e64 v0, v2, v4, s[0:1]
	s_nop 1
	v_mov_b32_dpp v3, v0 quad_perm:[1,0,3,2] row_mask:0xf bank_mask:0xf
	s_and_saveexec_b64 s[2:3], vcc
	s_xor_b64 s[2:3], exec, s[2:3]
	s_cbranch_execz .LBB0_728
	v_cvt_pk_bf16_f32 v0, v3, v4

; __device__ __forceinline__ unsigned cvt_pk_bf16(float lo, float hi) { unsigned r; asm volatile("v_cvt_pk_bf16_f32 %0, %1, %2" : "=v"(r) : "v"(lo), "v"(hi)); return r; }
; __device__ __forceinline__ unsigned dpp_xor1(unsigned v) { return (unsigned)__builtin_amdgcn_update_dpp(0, (int)v, 0xB1, 0xf, 0xf, false); }
; __device__ __forceinline__ float dpp_xor1(float v) { return __int_as_float(__builtin_amdgcn_update_dpp(0, __float_as_int(v), 0xB1, 0xf, 0xf, false)); }
; __device__ __forceinline__ int crow(int r, int hi) { return (r & 3) + 8 * (r >> 2) + 4 * hi; }
; template <int MODE, int VW>
; __device__ __forceinline__ void attn_unit_s(const AttnP& P, char* lds, const int tid) {
;     ...
;             for (int d0 = 0; d0 < 4; ++d0)
; #pragma unroll
;                 for (int rp = 0; rp < 8; ++rp) { const int r = 2 * rp;
;                     const float a = o[hv * 4 + d0][r] * rli[r], bb = o[hv * 4 + d0][r + 1] * rli[r + 1];
;                     const float t = odd ? a : bb; const float rcv = dpp_xor1(t);
;                     const unsigned w = odd ? cvt_pk_bf16(rcv, bb) : cvt_pk_bf16(a, rcv);
;                     *(unsigned*)(st + sbase + (crow(r, 0)) * 320 + d0 * 64) = w; }
.LBB0_730:
	s_or_b64 exec, exec, s[2:3]
	v_mul_f32_e32 v2, v14, v60
	v_mul_f32_e32 v4, v15, v61
	ds_write_b32 v50, v0 offset:5952
	v_cndmask_b32_e64 v0, v2, v4, s[0:1]
	s_nop 1
	v_mov_b32_dpp v3, v0 quad_perm:[1,0,3,2] row_mask:0xf bank_mask:0xf
	s_and_saveexec_b64 s[2:3], vcc
	s_xor_b64 s[2:3], exec, s[2:3]
	s_cbranch_execz .LBB0_732
	v_cvt_pk_bf16_f32 v0, v3, v4

; __device__ __forceinline__ unsigned cvt_pk_bf16(float lo, float hi) { unsigned r; asm volatile("v_cvt_pk_bf16_f32 %0, %1, %2" : "=v"(r) : "v"(lo), "v"(hi)); return r; }
; __device__ __forceinline__ unsigned dpp_xor1(unsigned v) { return (unsigned)__builtin_amdgcn_update_dpp(0, (int)v, 0xB1, 0xf, 0xf, false); }
; __device__ __forceinline__ float dpp_xor1(float v) { return __int_as_float(__builtin_amdgcn_update_dpp(0, __float_as_int(v), 0xB1, 0xf, 0xf, false)); }
; __device__ __forceinline__ int crow(int r, int hi) { return (r & 3) + 8 * (r >> 2) + 4 * hi; }
; template <int MODE, int VW>
; __device__ __forceinline__ void attn_unit_s(const AttnP& P, char* lds, const int tid) {
;     ...
;             for (int d0 = 0; d0 < 4; ++d0)
; #pragma unroll
;                 for (int rp = 0; rp < 8; ++rp) { const int r = 2 * rp;
;                     const float a = o[hv * 4 + d0][r] * rli[r], bb = o[hv * 4 + d0][r + 1] * rli[r + 1];
;                     const float t = odd ? a : bb; const float rcv = dpp_xor1(t);
;                     const unsigned w = odd ? cvt_pk_bf16(rcv, bb) : cvt_pk_bf16(a, rcv);
;                     *(unsigned*)(st + sbase + (crow(r, 0)) * 320 + d0 * 64) = w; }
.LBB0_734:
	s_or_b64 exec, exec, s[2:3]
	ds_write_b32 v50, v0 offset:7872
	v_mul_f32_e32 v0, v16, v62
	v_mul_f32_e32 v4, v17, v63
	v_cndmask_b32_e64 v2, v0, v4, s[0:1]
	s_nop 1
	v_mov_b32_dpp v3, v2 quad_perm:[1,0,3,2] row_mask:0xf bank_mask:0xf
	s_and_saveexec_b64 s[0:1], vcc
	s_xor_b64 s[0:1], exec, s[0:1]
	s_cbranch_execz .LBB0_736
	v_cvt_pk_bf16_f32 v2, v3, v4

; #define GAS __attribute__((address_space(1)))
;     __device__ __forceinline__ void operator()(const f32x4 (&acc)[2][2][4][2], const Unit& u, int wr, int wc, int fr, int fq) const {
;     ...
;         const int row0 = u.pm * BM + wr * 64 + fr, col0 = u.pn * BM + wc * 32 + 8 * fq; const bool odd = (fr & 1) != 0;
; #pragma unroll
;         for (int ai = 0; ai < 2; ++ai)
; #pragma unroll
;             for (int m = 0; m < 4; ++m) {
;                 const int row = row0 + ai * HALF + m * 16; float s = 0.f;
;                 const size_t off = (size_t)row * DM + col0;
;                 const size_t offp = (size_t)(row - (odd ? 1 : 0)) * DM + col0 + (odd ? 4 : 0);
; #pragma unroll
;                 for (int bj = 0; bj < 2; ++bj) {
;                     f32x4 b0, b1;
;                     if constexpr (BASE_F32) { const f32x4 la = *(const GAS f32x4*)(basef + offp + bj * HALF), lb = *(const GAS f32x4*)(basef + offp + DM + bj * HALF);
;                         const f32x4 snd = odd ? la : lb; f32x4 rcv; rcv[0] = dpp_xor1(snd[0]); rcv[1] = dpp_xor1(snd[1]); rcv[2] = dpp_xor1(snd[2]); rcv[3] = dpp_xor1(snd[3]);
;                         b0 = odd ? rcv : la; b1 = odd ? lb : rcv; }
;                     else { const u32x4 bw = *(const u32x4*)(baseb + off + bj * HALF);
;                         b0 = (f32x4){bf_lo(bw.x), bf_hi(bw.x), bf_lo(bw.y), bf_hi(bw.y)}; b1 = (f32x4){bf_lo(bw.z), bf_hi(bw.z), bf_lo(bw.w), bf_hi(bw.w)}; }
;                     const f32x4 v0 = acc[ai][bj][m][0] + b0, v1 = acc[ai][bj][m][1] + b1;
;                     if constexpr (OUT_F32) { const f32x4 snd = odd ? v0 : v1; f32x4 rcv; rcv[0] = dpp_xor1(snd[0]); rcv[1] = dpp_xor1(snd[1]); rcv[2] = dpp_xor1(snd[2]); rcv[3] = dpp_xor1(snd[3]);
;                         *(f32x4*)(H + offp + bj * HALF) = odd ? rcv : v0; *(f32x4*)(H + offp + DM + bj * HALF) = odd ? v1 : rcv; }
;                     else { u32x4 w; w.x = cvt_pk_bf16(v0[0], v0[1]); w.y = cvt_pk_bf16(v0[2], v0[3]); w.z = cvt_pk_bf16(v1[0], v1[1]); w.w = cvt_pk_bf16(v1[2], v1[3]);
;                         *(u32x4*)(HB + off + bj * HALF) = w; }
;                     s += (v0[0] * v0[0] + v0[1] * v0[1]) + (v0[2] * v0[2] + v0[3] * v0[3]) + (v1[0] * v1[0] + v1[1] * v1[1]) + (v1[2] * v1[2] + v1[3] * v1[3]);
;                 }
;                 s += __shfl_xor(s, 16); s += __shfl_xor(s, 32);
;                 if (fq == 0) unsafeAtomicAdd(ssn + row, s);
.LBB0_1005:
	v_lshl_add_u32 v148, s30, 8, v150
	v_sub_u32_e32 v158, v148, v152
	v_ashrrev_i32_e32 v159, 31, v158
	v_lshl_or_b32 v146, s34, 8, v153
	v_lshlrev_b64 v[158:159], 13, v[158:159]
	v_ashrrev_i32_e32 v147, 31, v146
	v_lshl_add_u64 v[158:159], s[8:9], 0, v[158:159]
	v_lshl_add_u64 v[158:159], v[146:147], 2, v[158:159]
	v_lshl_add_u64 v[166:167], v[158:159], 0, v[136:137]
	v_add_co_u32_e32 v168, vcc, s45, v166
	v_ashrrev_i32_e32 v149, 31, v148
	s_nop 0
	v_addc_co_u32_e32 v169, vcc, 0, v167, vcc
	global_load_dwordx4 v[158:161], v[166:167], off
	global_load_dwordx4 v[162:165], v[168:169], off
	v_readlane_b32 s24, v254, 25
	v_lshlrev_b64 v[170:171], 12, v[148:149]
	v_readlane_b32 s25, v254, 26
	s_waitcnt vmcnt(0)
	v_cndmask_b32_e64 v176, v161, v165, s[0:1]
	v_cndmask_b32_e64 v177, v160, v164, s[0:1]
	v_cndmask_b32_e64 v178, v159, v163, s[0:1]
	v_cndmask_b32_e64 v179, v158, v162, s[0:1]
	v_lshl_add_u64 v[170:171], s[24:25], 0, v[170:171]
	v_mov_b32_dpp v173, v178 quad_perm:[1,0,3,2] row_mask:0xf bank_mask:0xf
	v_mov_b32_dpp v172, v179 quad_perm:[1,0,3,2] row_mask:0xf bank_mask:0xf
	v_mov_b32_dpp v174, v177 quad_perm:[1,0,3,2] row_mask:0xf bank_mask:0xf
	v_mov_b32_dpp v175, v176 quad_perm:[1,0,3,2] row_mask:0xf bank_mask:0xf
	v_lshl_add_u64 v[170:171], v[146:147], 1, v[170:171]
	v_cndmask_b32_e64 v159, v173, v159, s[0:1]
	v_cndmask_b32_e64 v158, v172, v158, s[0:1]
	v_cndmask_b32_e64 v161, v175, v161, s[0:1]
	v_cndmask_b32_e64 v160, v174, v160, s[0:1]
	v_cndmask_b32_e64 v163, v163, v173, s[0:1]
	v_cndmask_b32_e64 v162, v162, v172, s[0:1]
	v_cndmask_b32_e64 v165, v165, v175, s[0:1]
	v_cndmask_b32_e64 v164, v164, v174, s[0:1]
	v_pk_add_f32 v[126:127], v[126:127], v[160:161]
	v_pk_add_f32 v[172:173], v[124:125], v[158:159]
	v_pk_add_f32 v[164:165], v[122:123], v[164:165]
	v_pk_add_f32 v[162:163], v[120:121], v[162:163]
	v_cvt_pk_bf16_f32 v120, v172, v173
	v_cvt_pk_bf16_f32 v121, v126, v127
	v_mul_f32_e32 v173, v173, v173
	v_cvt_pk_bf16_f32 v122, v162, v163
	v_cvt_pk_bf16_f32 v123, v164, v165
	global_store_dwordx4 v[170:171], v[120:123], off
	global_load_dwordx4 v[122:125], v[166:167], off offset:512
	s_nop 0
	global_load_dwordx4 v[158:161], v[168:169], off offset:512
	v_mul_f32_e32 v127, v127, v127
	v_mul_f32_e32 v163, v163, v163
	v_fmac_f32_e32 v173, v172, v172
	v_fmac_f32_e32 v127, v126, v126
	v_mul_f32_e32 v165, v165, v165
	v_fmac_f32_e32 v163, v162, v162
	v_add_f32_e32 v126, v173, v127
	v_fmac_f32_e32 v165, v164, v164
	v_add_f32_e32 v126, v163, v126
	v_add_f32_e32 v162, v165, v126
	v_and_b32_e32 v169, 64, v157
	v_xor_b32_e32 v120, 16, v157
	v_add_u32_e32 v169, 64, v169
	v_cmp_lt_i32_e32 vcc, v120, v169
	s_waitcnt vmcnt(0)
	v_cndmask_b32_e64 v126, v125, v161, s[0:1]
	v_cndmask_b32_e64 v127, v124, v160, s[0:1]
	v_cndmask_b32_e64 v163, v123, v159, s[0:1]
	v_cndmask_b32_e64 v164, v122, v158, s[0:1]
	v_mov_b32_dpp v167, v127 quad_perm:[1,0,3,2] row_mask:0xf bank_mask:0xf
	v_mov_b32_dpp v166, v163 quad_perm:[1,0,3,2] row_mask:0xf bank_mask:0xf
	v_mov_b32_dpp v121, v164 quad_perm:[1,0,3,2] row_mask:0xf bank_mask:0xf
	v_mov_b32_dpp v168, v126 quad_perm:[1,0,3,2] row_mask:0xf bank_mask:0xf
	v_cndmask_b32_e64 v123, v166, v123, s[0:1]
	v_cndmask_b32_e64 v122, v121, v122, s[0:1]
	v_cndmask_b32_e64 v125, v168, v125, s[0:1]
	v_cndmask_b32_e64 v124, v167, v124, s[0:1]
	v_cndmask_b32_e64 v127, v159, v166, s[0:1]
	v_cndmask_b32_e64 v126, v158, v121, s[0:1]
	v_pk_add_f32 v[118:119], v[118:119], v[124:125]
	v_pk_add_f32 v[116:117], v[116:117], v[122:123]
	v_cndmask_b32_e64 v159, v161, v168, s[0:1]
	v_cndmask_b32_e64 v158, v160, v167, s[0:1]
	v_pk_add_f32 v[124:125], v[112:113], v[126:127]
	v_mul_f32_e32 v112, v117, v117
	v_mul_f32_e32 v113, v119, v119
	v_pk_add_f32 v[122:123], v[114:115], v[158:159]
	v_mul_f32_e32 v114, v125, v125
	v_fmac_f32_e32 v112, v116, v116
	v_fmac_f32_e32 v113, v118, v118
	v_mul_f32_e32 v115, v123, v123
	v_fmac_f32_e32 v114, v124, v124
	v_add_f32_e32 v112, v112, v113
	v_fmac_f32_e32 v115, v122, v122
	v_add_f32_e32 v112, v114, v112
	v_cndmask_b32_e32 v120, v157, v120, vcc
	v_add_f32_e32 v112, v115, v112
	v_lshlrev_b32_e32 v120, 2, v120
	v_add_f32_e32 v112, v162, v112
	ds_bpermute_b32 v113, v120, v112
	v_xor_b32_e32 v114, 32, v157
	v_cmp_lt_i32_e32 vcc, v114, v169
	v_cvt_pk_bf16_f32 v116, v116, v117
	v_cvt_pk_bf16_f32 v117, v118, v119
	s_waitcnt lgkmcnt(0)
	v_add_f32_e32 v112, v112, v113
	v_cvt_pk_bf16_f32 v118, v124, v125
	v_cvt_pk_bf16_f32 v119, v122, v123
	v_cndmask_b32_e32 v114, v157, v114, vcc
	v_lshlrev_b32_e32 v114, 2, v114
	ds_bpermute_b32 v113, v114, v112
	global_store_dwordx4 v[170:171], v[116:119], off offset:256
	s_and_saveexec_b64 s[30:31], s[2:3]
	s_cbranch_execz .LBB0_1007
	v_lshl_add_u64 v[116:117], v[148:149], 2, s[12:13]
	s_waitcnt lgkmcnt(0)
	v_add_f32_e32 v112, v112, v113
	global_atomic_add_f32 v[116:117], v112, off
; #define GAS __attribute__((address_space(1)))
;     __device__ __forceinline__ void operator()(const f32x4 (&acc)[2][2][4][2], const Unit& u, int wr, int wc, int fr, int fq) const {
;     ...
;         const int row0 = u.pm * BM + wr * 64 + fr, col0 = u.pn * BM + wc * 32 + 8 * fq; const bool odd = (fr & 1) != 0;
; #pragma unroll
;         for (int ai = 0; ai < 2; ++ai)
; #pragma unroll
;             for (int m = 0; m < 4; ++m) {
;                 const int row = row0 + ai * HALF + m * 16; float s = 0.f;
;                 const size_t off = (size_t)row * DM + col0;
;                 const size_t offp = (size_t)(row - (odd ? 1 : 0)) * DM + col0 + (odd ? 4 : 0);
; #pragma unroll
;                 for (int bj = 0; bj < 2; ++bj) {
;                     f32x4 b0, b1;
;                     if constexpr (BASE_F32) { const f32x4 la = *(const GAS f32x4*)(basef + offp + bj * HALF), lb = *(const GAS f32x4*)(basef + offp + DM + bj * HALF);
;                         const f32x4 snd = odd ? la : lb; f32x4 rcv; rcv[0] = dpp_xor1(snd[0]); rcv[1] = dpp_xor1(snd[1]); rcv[2] = dpp_xor1(snd[2]); rcv[3] = dpp_xor1(snd[3]);
;                         b0 = odd ? rcv : la; b1 = odd ? lb : rcv; }
;                     else { const u32x4 bw = *(const u32x4*)(baseb + off + bj * HALF);
;                         b0 = (f32x4){bf_lo(bw.x), bf_hi(bw.x), bf_lo(bw.y), bf_hi(bw.y)}; b1 = (f32x4){bf_lo(bw.z), bf_hi(bw.z), bf_lo(bw.w), bf_hi(bw.w)}; }
;                     const f32x4 v0 = acc[ai][bj][m][0] + b0, v1 = acc[ai][bj][m][1] + b1;
;                     if constexpr (OUT_F32) { const f32x4 snd = odd ? v0 : v1; f32x4 rcv; rcv[0] = dpp_xor1(snd[0]); rcv[1] = dpp_xor1(snd[1]); rcv[2] = dpp_xor1(snd[2]); rcv[3] = dpp_xor1(snd[3]);
;                         *(f32x4*)(H + offp + bj * HALF) = odd ? rcv : v0; *(f32x4*)(H + offp + DM + bj * HALF) = odd ? v1 : rcv; }
;                     else { u32x4 w; w.x = cvt_pk_bf16(v0[0], v0[1]); w.y = cvt_pk_bf16(v0[2], v0[3]); w.z = cvt_pk_bf16(v1[0], v1[1]); w.w = cvt_pk_bf16(v1[2], v1[3]);
;                         *(u32x4*)(HB + off + bj * HALF) = w; }
;                     s += (v0[0] * v0[0] + v0[1] * v0[1]) + (v0[2] * v0[2] + v0[3] * v0[3]) + (v1[0] * v1[0] + v1[1] * v1[1]) + (v1[2] * v1[2] + v1[3] * v1[3]);
;                 }
;                 s += __shfl_xor(s, 16); s += __shfl_xor(s, 32);
;                 if (fq == 0) unsafeAtomicAdd(ssn + row, s);
.LBB0_1007:
	s_or_b64 exec, exec, s[30:31]
	v_or_b32_e32 v112, 16, v148
	v_sub_u32_e32 v116, v112, v152
	v_ashrrev_i32_e32 v117, 31, v116
	v_lshlrev_b64 v[116:117], 13, v[116:117]
	v_lshl_add_u64 v[116:117], s[8:9], 0, v[116:117]
	v_lshl_add_u64 v[116:117], v[146:147], 2, v[116:117]
	v_lshl_add_u64 v[126:127], v[116:117], 0, v[136:137]
	v_add_co_u32_e32 v158, vcc, 0x2000, v126
	s_waitcnt lgkmcnt(0)
	v_ashrrev_i32_e32 v113, 31, v112
	v_addc_co_u32_e32 v159, vcc, 0, v127, vcc
	global_load_dwordx4 v[116:119], v[126:127], off
	global_load_dwordx4 v[122:125], v[158:159], off
	v_readlane_b32 s24, v254, 25
	v_lshlrev_b64 v[160:161], 12, v[112:113]
	v_readlane_b32 s25, v254, 26
	s_waitcnt vmcnt(0)
	v_cndmask_b32_e64 v163, v119, v125, s[0:1]
	v_cndmask_b32_e64 v164, v118, v124, s[0:1]
	v_cndmask_b32_e64 v165, v117, v123, s[0:1]
	v_cndmask_b32_e64 v166, v116, v122, s[0:1]
	v_lshl_add_u64 v[160:161], s[24:25], 0, v[160:161]
	v_mov_b32_dpp v121, v165 quad_perm:[1,0,3,2] row_mask:0xf bank_mask:0xf
	v_mov_b32_dpp v115, v166 quad_perm:[1,0,3,2] row_mask:0xf bank_mask:0xf
	v_mov_b32_dpp v149, v164 quad_perm:[1,0,3,2] row_mask:0xf bank_mask:0xf
	v_mov_b32_dpp v162, v163 quad_perm:[1,0,3,2] row_mask:0xf bank_mask:0xf
	v_lshl_add_u64 v[160:161], v[146:147], 1, v[160:161]
	v_cndmask_b32_e64 v117, v121, v117, s[0:1]
	v_cndmask_b32_e64 v116, v115, v116, s[0:1]
	v_cndmask_b32_e64 v119, v162, v119, s[0:1]
	v_cndmask_b32_e64 v118, v149, v118, s[0:1]
	v_cndmask_b32_e64 v123, v123, v121, s[0:1]
	v_cndmask_b32_e64 v122, v122, v115, s[0:1]
	v_cndmask_b32_e64 v125, v125, v162, s[0:1]
	v_cndmask_b32_e64 v124, v124, v149, s[0:1]
	v_pk_add_f32 v[118:119], v[110:111], v[118:119]
	v_pk_add_f32 v[116:117], v[108:109], v[116:117]
	v_pk_add_f32 v[124:125], v[106:107], v[124:125]
	v_pk_add_f32 v[122:123], v[104:105], v[122:123]
	v_cvt_pk_bf16_f32 v104, v116, v117
	v_cvt_pk_bf16_f32 v105, v118, v119
	v_mul_f32_e32 v117, v117, v117
	v_cvt_pk_bf16_f32 v106, v122, v123
	v_cvt_pk_bf16_f32 v107, v124, v125
	global_store_dwordx4 v[160:161], v[104:107], off
	global_load_dwordx4 v[104:107], v[126:127], off offset:512
	s_nop 0
	global_load_dwordx4 v[108:111], v[158:159], off offset:512
	v_mul_f32_e32 v119, v119, v119
	v_mul_f32_e32 v123, v123, v123
	v_fmac_f32_e32 v117, v116, v116
	v_fmac_f32_e32 v119, v118, v118
	v_fmac_f32_e32 v123, v122, v122
	v_add_f32_e32 v116, v117, v119
	v_mul_f32_e32 v125, v125, v125
	v_fmac_f32_e32 v125, v124, v124
	v_add_f32_e32 v116, v123, v116
	v_add_f32_e32 v116, v125, v116
	s_waitcnt vmcnt(0)
	v_cndmask_b32_e64 v117, v107, v111, s[0:1]
	v_cndmask_b32_e64 v118, v106, v110, s[0:1]
	v_cndmask_b32_e64 v119, v105, v109, s[0:1]
	v_cndmask_b32_e64 v122, v104, v108, s[0:1]
	v_mov_b32_dpp v126, v118 quad_perm:[1,0,3,2] row_mask:0xf bank_mask:0xf
	v_mov_b32_dpp v121, v119 quad_perm:[1,0,3,2] row_mask:0xf bank_mask:0xf
	v_mov_b32_dpp v115, v122 quad_perm:[1,0,3,2] row_mask:0xf bank_mask:0xf
	v_mov_b32_dpp v127, v117 quad_perm:[1,0,3,2] row_mask:0xf bank_mask:0xf
	v_cndmask_b32_e64 v105, v121, v105, s[0:1]
	v_cndmask_b32_e64 v104, v115, v104, s[0:1]
	v_cndmask_b32_e64 v107, v127, v107, s[0:1]
	v_cndmask_b32_e64 v106, v126, v106, s[0:1]
	v_cndmask_b32_e64 v109, v109, v121, s[0:1]
	v_cndmask_b32_e64 v108, v108, v115, s[0:1]
	v_pk_add_f32 v[102:103], v[102:103], v[106:107]
	v_pk_add_f32 v[100:101], v[100:101], v[104:105]
	v_cndmask_b32_e64 v111, v111, v127, s[0:1]
	v_cndmask_b32_e64 v110, v110, v126, s[0:1]
	v_pk_add_f32 v[106:107], v[96:97], v[108:109]
	v_mul_f32_e32 v96, v101, v101
	v_mul_f32_e32 v97, v103, v103
	v_pk_add_f32 v[104:105], v[98:99], v[110:111]
	v_mul_f32_e32 v98, v107, v107
	v_fmac_f32_e32 v96, v100, v100
	v_fmac_f32_e32 v97, v102, v102
	v_mul_f32_e32 v99, v105, v105
	v_fmac_f32_e32 v98, v106, v106
	v_add_f32_e32 v96, v96, v97
	v_add_f32_e32 v96, v98, v96
	v_fmac_f32_e32 v99, v104, v104
	v_add_f32_e32 v96, v99, v96
	v_add_f32_e32 v96, v116, v96
	ds_bpermute_b32 v97, v120, v96
	v_cvt_pk_bf16_f32 v98, v100, v101
	v_cvt_pk_bf16_f32 v99, v102, v103
	v_cvt_pk_bf16_f32 v100, v106, v107
	v_cvt_pk_bf16_f32 v101, v104, v105
	s_waitcnt lgkmcnt(0)
	v_add_f32_e32 v96, v96, v97
	ds_bpermute_b32 v97, v114, v96
	global_store_dwordx4 v[160:161], v[98:101], off offset:256
	s_and_saveexec_b64 s[30:31], s[2:3]
	s_cbranch_execz .LBB0_1009
	v_lshl_add_u64 v[98:99], v[112:113], 2, s[12:13]
	s_waitcnt lgkmcnt(0)
	v_add_f32_e32 v96, v96, v97
	global_atomic_add_f32 v[98:99], v96, off
; #define GAS __attribute__((address_space(1)))
;     __device__ __forceinline__ void operator()(const f32x4 (&acc)[2][2][4][2], const Unit& u, int wr, int wc, int fr, int fq) const {
;     ...
;         const int row0 = u.pm * BM + wr * 64 + fr, col0 = u.pn * BM + wc * 32 + 8 * fq; const bool odd = (fr & 1) != 0;
; #pragma unroll
;         for (int ai = 0; ai < 2; ++ai)
; #pragma unroll
;             for (int m = 0; m < 4; ++m) {
;                 const int row = row0 + ai * HALF + m * 16; float s = 0.f;
;                 const size_t off = (size_t)row * DM + col0;
;                 const size_t offp = (size_t)(row - (odd ? 1 : 0)) * DM + col0 + (odd ? 4 : 0);
; #pragma unroll
;                 for (int bj = 0; bj < 2; ++bj) {
;                     f32x4 b0, b1;
;                     if constexpr (BASE_F32) { const f32x4 la = *(const GAS f32x4*)(basef + offp + bj * HALF), lb = *(const GAS f32x4*)(basef + offp + DM + bj * HALF);
;                         const f32x4 snd = odd ? la : lb; f32x4 rcv; rcv[0] = dpp_xor1(snd[0]); rcv[1] = dpp_xor1(snd[1]); rcv[2] = dpp_xor1(snd[2]); rcv[3] = dpp_xor1(snd[3]);
;                         b0 = odd ? rcv : la; b1 = odd ? lb : rcv; }
;                     else { const u32x4 bw = *(const u32x4*)(baseb + off + bj * HALF);
;                         b0 = (f32x4){bf_lo(bw.x), bf_hi(bw.x), bf_lo(bw.y), bf_hi(bw.y)}; b1 = (f32x4){bf_lo(bw.z), bf_hi(bw.z), bf_lo(bw.w), bf_hi(bw.w)}; }
;                     const f32x4 v0 = acc[ai][bj][m][0] + b0, v1 = acc[ai][bj][m][1] + b1;
;                     if constexpr (OUT_F32) { const f32x4 snd = odd ? v0 : v1; f32x4 rcv; rcv[0] = dpp_xor1(snd[0]); rcv[1] = dpp_xor1(snd[1]); rcv[2] = dpp_xor1(snd[2]); rcv[3] = dpp_xor1(snd[3]);
;                         *(f32x4*)(H + offp + bj * HALF) = odd ? rcv : v0; *(f32x4*)(H + offp + DM + bj * HALF) = odd ? v1 : rcv; }
;                     else { u32x4 w; w.x = cvt_pk_bf16(v0[0], v0[1]); w.y = cvt_pk_bf16(v0[2], v0[3]); w.z = cvt_pk_bf16(v1[0], v1[1]); w.w = cvt_pk_bf16(v1[2], v1[3]);
;                         *(u32x4*)(HB + off + bj * HALF) = w; }
;                     s += (v0[0] * v0[0] + v0[1] * v0[1]) + (v0[2] * v0[2] + v0[3] * v0[3]) + (v1[0] * v1[0] + v1[1] * v1[1]) + (v1[2] * v1[2] + v1[3] * v1[3]);
;                 }
;                 s += __shfl_xor(s, 16); s += __shfl_xor(s, 32);
;                 if (fq == 0) unsafeAtomicAdd(ssn + row, s);
.LBB0_1009:
	s_or_b64 exec, exec, s[30:31]
	v_or_b32_e32 v96, 32, v148
	v_sub_u32_e32 v98, v96, v152
	v_ashrrev_i32_e32 v99, 31, v98
	v_lshlrev_b64 v[98:99], 13, v[98:99]
	v_lshl_add_u64 v[98:99], s[8:9], 0, v[98:99]
	v_lshl_add_u64 v[98:99], v[146:147], 2, v[98:99]
	v_lshl_add_u64 v[106:107], v[98:99], 0, v[136:137]
	v_add_co_u32_e32 v108, vcc, 0x2000, v106
	s_waitcnt lgkmcnt(0)
	v_ashrrev_i32_e32 v97, 31, v96
	v_addc_co_u32_e32 v109, vcc, 0, v107, vcc
	global_load_dwordx4 v[98:101], v[106:107], off
	global_load_dwordx4 v[102:105], v[108:109], off
	v_readlane_b32 s24, v254, 25
	v_lshlrev_b64 v[110:111], 12, v[96:97]
	v_readlane_b32 s25, v254, 26
	s_waitcnt vmcnt(0)
	v_cndmask_b32_e64 v117, v101, v105, s[0:1]
	v_cndmask_b32_e64 v118, v100, v104, s[0:1]
	v_cndmask_b32_e64 v119, v99, v103, s[0:1]
	v_cndmask_b32_e64 v121, v98, v102, s[0:1]
	v_lshl_add_u64 v[110:111], s[24:25], 0, v[110:111]
	v_mov_b32_dpp v113, v119 quad_perm:[1,0,3,2] row_mask:0xf bank_mask:0xf
	v_mov_b32_dpp v112, v121 quad_perm:[1,0,3,2] row_mask:0xf bank_mask:0xf
	v_mov_b32_dpp v115, v118 quad_perm:[1,0,3,2] row_mask:0xf bank_mask:0xf
	v_mov_b32_dpp v116, v117 quad_perm:[1,0,3,2] row_mask:0xf bank_mask:0xf
	v_lshl_add_u64 v[110:111], v[146:147], 1, v[110:111]
	v_cndmask_b32_e64 v99, v113, v99, s[0:1]
	v_cndmask_b32_e64 v98, v112, v98, s[0:1]
	v_cndmask_b32_e64 v101, v116, v101, s[0:1]
	v_cndmask_b32_e64 v100, v115, v100, s[0:1]
	v_cndmask_b32_e64 v103, v103, v113, s[0:1]
	v_cndmask_b32_e64 v102, v102, v112, s[0:1]
	v_cndmask_b32_e64 v105, v105, v116, s[0:1]
	v_cndmask_b32_e64 v104, v104, v115, s[0:1]
	v_pk_add_f32 v[100:101], v[94:95], v[100:101]
	v_pk_add_f32 v[98:99], v[92:93], v[98:99]
	v_pk_add_f32 v[104:105], v[90:91], v[104:105]
	v_pk_add_f32 v[102:103], v[88:89], v[102:103]
	v_cvt_pk_bf16_f32 v88, v98, v99
	v_cvt_pk_bf16_f32 v89, v100, v101
	v_mul_f32_e32 v99, v99, v99
	v_cvt_pk_bf16_f32 v90, v102, v103
	v_cvt_pk_bf16_f32 v91, v104, v105
	global_store_dwordx4 v[110:111], v[88:91], off
	global_load_dwordx4 v[88:91], v[106:107], off offset:512
	s_nop 0
	global_load_dwordx4 v[92:95], v[108:109], off offset:512
	v_mul_f32_e32 v101, v101, v101
	v_mul_f32_e32 v103, v103, v103
	v_fmac_f32_e32 v99, v98, v98
	v_fmac_f32_e32 v101, v100, v100
	v_fmac_f32_e32 v103, v102, v102
	v_add_f32_e32 v98, v99, v101
	v_mul_f32_e32 v105, v105, v105
	v_fmac_f32_e32 v105, v104, v104
	v_add_f32_e32 v98, v103, v98
	v_add_f32_e32 v98, v105, v98
	s_waitcnt vmcnt(0)
	v_cndmask_b32_e64 v99, v91, v95, s[0:1]
	v_cndmask_b32_e64 v100, v90, v94, s[0:1]
	v_cndmask_b32_e64 v101, v89, v93, s[0:1]
	v_cndmask_b32_e64 v102, v88, v92, s[0:1]
	v_mov_b32_dpp v108, v100 quad_perm:[1,0,3,2] row_mask:0xf bank_mask:0xf
	v_mov_b32_dpp v107, v101 quad_perm:[1,0,3,2] row_mask:0xf bank_mask:0xf
	v_mov_b32_dpp v106, v102 quad_perm:[1,0,3,2] row_mask:0xf bank_mask:0xf
	v_mov_b32_dpp v109, v99 quad_perm:[1,0,3,2] row_mask:0xf bank_mask:0xf
	v_cndmask_b32_e64 v89, v107, v89, s[0:1]
	v_cndmask_b32_e64 v88, v106, v88, s[0:1]
	v_cndmask_b32_e64 v91, v109, v91, s[0:1]
	v_cndmask_b32_e64 v90, v108, v90, s[0:1]
	v_cndmask_b32_e64 v93, v93, v107, s[0:1]
	v_cndmask_b32_e64 v92, v92, v106, s[0:1]
	v_pk_add_f32 v[86:87], v[86:87], v[90:91]
	v_pk_add_f32 v[84:85], v[84:85], v[88:89]
	v_cndmask_b32_e64 v95, v95, v109, s[0:1]
	v_cndmask_b32_e64 v94, v94, v108, s[0:1]
	v_pk_add_f32 v[90:91], v[80:81], v[92:93]
	v_mul_f32_e32 v80, v85, v85
	v_mul_f32_e32 v81, v87, v87
	v_pk_add_f32 v[88:89], v[82:83], v[94:95]
	v_mul_f32_e32 v82, v91, v91
	v_fmac_f32_e32 v80, v84, v84
	v_fmac_f32_e32 v81, v86, v86
	v_mul_f32_e32 v83, v89, v89
	v_fmac_f32_e32 v82, v90, v90
	v_add_f32_e32 v80, v80, v81
	v_add_f32_e32 v80, v82, v80
	v_fmac_f32_e32 v83, v88, v88
	v_add_f32_e32 v80, v83, v80
	v_add_f32_e32 v80, v98, v80
	ds_bpermute_b32 v81, v120, v80
	v_cvt_pk_bf16_f32 v82, v84, v85
	v_cvt_pk_bf16_f32 v83, v86, v87
	v_cvt_pk_bf16_f32 v84, v90, v91
	v_cvt_pk_bf16_f32 v85, v88, v89
	s_waitcnt lgkmcnt(0)
	v_add_f32_e32 v80, v80, v81
	ds_bpermute_b32 v81, v114, v80
	global_store_dwordx4 v[110:111], v[82:85], off offset:256
	s_and_saveexec_b64 s[30:31], s[2:3]
	s_cbranch_execz .LBB0_1011
	v_lshl_add_u64 v[82:83], v[96:97], 2, s[12:13]
	s_waitcnt lgkmcnt(0)
	v_add_f32_e32 v80, v80, v81
	global_atomic_add_f32 v[82:83], v80, off
; #define GAS __attribute__((address_space(1)))
;     __device__ __forceinline__ void operator()(const f32x4 (&acc)[2][2][4][2], const Unit& u, int wr, int wc, int fr, int fq) const {
;     ...
;         const int row0 = u.pm * BM + wr * 64 + fr, col0 = u.pn * BM + wc * 32 + 8 * fq; const bool odd = (fr & 1) != 0;
; #pragma unroll
;         for (int ai = 0; ai < 2; ++ai)
; #pragma unroll
;             for (int m = 0; m < 4; ++m) {
;                 const int row = row0 + ai * HALF + m * 16; float s = 0.f;
;                 const size_t off = (size_t)row * DM + col0;
;                 const size_t offp = (size_t)(row - (odd ? 1 : 0)) * DM + col0 + (odd ? 4 : 0);
; #pragma unroll
;                 for (int bj = 0; bj < 2; ++bj) {
;                     f32x4 b0, b1;
;                     if constexpr (BASE_F32) { const f32x4 la = *(const GAS f32x4*)(basef + offp + bj * HALF), lb = *(const GAS f32x4*)(basef + offp + DM + bj * HALF);
;                         const f32x4 snd = odd ? la : lb; f32x4 rcv; rcv[0] = dpp_xor1(snd[0]); rcv[1] = dpp_xor1(snd[1]); rcv[2] = dpp_xor1(snd[2]); rcv[3] = dpp_xor1(snd[3]);
;                         b0 = odd ? rcv : la; b1 = odd ? lb : rcv; }
;                     else { const u32x4 bw = *(const u32x4*)(baseb + off + bj * HALF);
;                         b0 = (f32x4){bf_lo(bw.x), bf_hi(bw.x), bf_lo(bw.y), bf_hi(bw.y)}; b1 = (f32x4){bf_lo(bw.z), bf_hi(bw.z), bf_lo(bw.w), bf_hi(bw.w)}; }
;                     const f32x4 v0 = acc[ai][bj][m][0] + b0, v1 = acc[ai][bj][m][1] + b1;
;                     if constexpr (OUT_F32) { const f32x4 snd = odd ? v0 : v1; f32x4 rcv; rcv[0] = dpp_xor1(snd[0]); rcv[1] = dpp_xor1(snd[1]); rcv[2] = dpp_xor1(snd[2]); rcv[3] = dpp_xor1(snd[3]);
;                         *(f32x4*)(H + offp + bj * HALF) = odd ? rcv : v0; *(f32x4*)(H + offp + DM + bj * HALF) = odd ? v1 : rcv; }
;                     else { u32x4 w; w.x = cvt_pk_bf16(v0[0], v0[1]); w.y = cvt_pk_bf16(v0[2], v0[3]); w.z = cvt_pk_bf16(v1[0], v1[1]); w.w = cvt_pk_bf16(v1[2], v1[3]);
;                         *(u32x4*)(HB + off + bj * HALF) = w; }
;                     s += (v0[0] * v0[0] + v0[1] * v0[1]) + (v0[2] * v0[2] + v0[3] * v0[3]) + (v1[0] * v1[0] + v1[1] * v1[1]) + (v1[2] * v1[2] + v1[3] * v1[3]);
;                 }
;                 s += __shfl_xor(s, 16); s += __shfl_xor(s, 32);
;                 if (fq == 0) unsafeAtomicAdd(ssn + row, s);
.LBB0_1011:
	s_or_b64 exec, exec, s[30:31]
	v_or_b32_e32 v80, 48, v148
	v_sub_u32_e32 v82, v80, v152
	v_ashrrev_i32_e32 v83, 31, v82
	v_lshlrev_b64 v[82:83], 13, v[82:83]
	v_lshl_add_u64 v[82:83], s[8:9], 0, v[82:83]
	v_lshl_add_u64 v[82:83], v[146:147], 2, v[82:83]
	v_lshl_add_u64 v[90:91], v[82:83], 0, v[136:137]
	v_add_co_u32_e32 v92, vcc, 0x2000, v90
	s_waitcnt lgkmcnt(0)
	v_ashrrev_i32_e32 v81, 31, v80
	v_addc_co_u32_e32 v93, vcc, 0, v91, vcc
	global_load_dwordx4 v[82:85], v[90:91], off
	global_load_dwordx4 v[86:89], v[92:93], off
	v_readlane_b32 s24, v254, 25
	v_lshlrev_b64 v[94:95], 12, v[80:81]
	v_readlane_b32 s25, v254, 26
	s_waitcnt vmcnt(0)
	v_cndmask_b32_e64 v100, v85, v89, s[0:1]
	v_cndmask_b32_e64 v101, v84, v88, s[0:1]
	v_cndmask_b32_e64 v102, v83, v87, s[0:1]
	v_cndmask_b32_e64 v103, v82, v86, s[0:1]
	v_lshl_add_u64 v[94:95], s[24:25], 0, v[94:95]
	v_mov_b32_dpp v97, v102 quad_perm:[1,0,3,2] row_mask:0xf bank_mask:0xf
	v_mov_b32_dpp v96, v103 quad_perm:[1,0,3,2] row_mask:0xf bank_mask:0xf
	v_mov_b32_dpp v98, v101 quad_perm:[1,0,3,2] row_mask:0xf bank_mask:0xf
	v_mov_b32_dpp v99, v100 quad_perm:[1,0,3,2] row_mask:0xf bank_mask:0xf
	v_lshl_add_u64 v[94:95], v[146:147], 1, v[94:95]
	v_cndmask_b32_e64 v83, v97, v83, s[0:1]
	v_cndmask_b32_e64 v82, v96, v82, s[0:1]
	v_cndmask_b32_e64 v85, v99, v85, s[0:1]
	v_cndmask_b32_e64 v84, v98, v84, s[0:1]
	v_cndmask_b32_e64 v87, v87, v97, s[0:1]
	v_cndmask_b32_e64 v86, v86, v96, s[0:1]
	v_cndmask_b32_e64 v89, v89, v99, s[0:1]
	v_cndmask_b32_e64 v88, v88, v98, s[0:1]
	v_pk_add_f32 v[84:85], v[78:79], v[84:85]
	v_pk_add_f32 v[82:83], v[76:77], v[82:83]
	v_pk_add_f32 v[88:89], v[74:75], v[88:89]
	v_pk_add_f32 v[86:87], v[72:73], v[86:87]
	v_cvt_pk_bf16_f32 v72, v82, v83
	v_cvt_pk_bf16_f32 v73, v84, v85
	v_mul_f32_e32 v83, v83, v83
	v_cvt_pk_bf16_f32 v74, v86, v87
	v_cvt_pk_bf16_f32 v75, v88, v89
	global_store_dwordx4 v[94:95], v[72:75], off
	global_load_dwordx4 v[72:75], v[90:91], off offset:512
	s_nop 0
	global_load_dwordx4 v[76:79], v[92:93], off offset:512
	v_mul_f32_e32 v85, v85, v85
	v_mul_f32_e32 v87, v87, v87
	v_fmac_f32_e32 v83, v82, v82
	v_fmac_f32_e32 v85, v84, v84
	v_fmac_f32_e32 v87, v86, v86
	v_add_f32_e32 v82, v83, v85
	v_mul_f32_e32 v89, v89, v89
	v_fmac_f32_e32 v89, v88, v88
	v_add_f32_e32 v82, v87, v82
	v_add_f32_e32 v82, v89, v82
	s_waitcnt vmcnt(0)
	v_cndmask_b32_e64 v83, v75, v79, s[0:1]
	v_cndmask_b32_e64 v84, v74, v78, s[0:1]
	v_cndmask_b32_e64 v85, v73, v77, s[0:1]
	v_cndmask_b32_e64 v86, v72, v76, s[0:1]
	v_mov_b32_dpp v92, v84 quad_perm:[1,0,3,2] row_mask:0xf bank_mask:0xf
	v_mov_b32_dpp v91, v85 quad_perm:[1,0,3,2] row_mask:0xf bank_mask:0xf
	v_mov_b32_dpp v90, v86 quad_perm:[1,0,3,2] row_mask:0xf bank_mask:0xf
	v_mov_b32_dpp v93, v83 quad_perm:[1,0,3,2] row_mask:0xf bank_mask:0xf
	v_cndmask_b32_e64 v73, v91, v73, s[0:1]
	v_cndmask_b32_e64 v72, v90, v72, s[0:1]
	v_cndmask_b32_e64 v75, v93, v75, s[0:1]
	v_cndmask_b32_e64 v74, v92, v74, s[0:1]
	v_cndmask_b32_e64 v77, v77, v91, s[0:1]
	v_cndmask_b32_e64 v76, v76, v90, s[0:1]
	v_pk_add_f32 v[70:71], v[70:71], v[74:75]
	v_pk_add_f32 v[68:69], v[68:69], v[72:73]
	v_cndmask_b32_e64 v79, v79, v93, s[0:1]
	v_cndmask_b32_e64 v78, v78, v92, s[0:1]
	v_pk_add_f32 v[74:75], v[64:65], v[76:77]
	v_mul_f32_e32 v64, v69, v69
	v_mul_f32_e32 v65, v71, v71
	v_pk_add_f32 v[72:73], v[66:67], v[78:79]
	v_mul_f32_e32 v66, v75, v75
	v_fmac_f32_e32 v64, v68, v68
	v_fmac_f32_e32 v65, v70, v70
	v_mul_f32_e32 v67, v73, v73
	v_fmac_f32_e32 v66, v74, v74
	v_add_f32_e32 v64, v64, v65
	v_add_f32_e32 v64, v66, v64
	v_fmac_f32_e32 v67, v72, v72
	v_add_f32_e32 v64, v67, v64
	v_add_f32_e32 v64, v82, v64
	ds_bpermute_b32 v65, v120, v64
	v_cvt_pk_bf16_f32 v66, v68, v69
	v_cvt_pk_bf16_f32 v67, v70, v71
	v_cvt_pk_bf16_f32 v68, v74, v75
	v_cvt_pk_bf16_f32 v69, v72, v73
	s_waitcnt lgkmcnt(0)
	v_add_f32_e32 v64, v64, v65
	ds_bpermute_b32 v65, v114, v64
	global_store_dwordx4 v[94:95], v[66:69], off offset:256
	s_and_saveexec_b64 s[30:31], s[2:3]
	s_cbranch_execz .LBB0_1013
	v_lshl_add_u64 v[66:67], v[80:81], 2, s[12:13]
	s_waitcnt lgkmcnt(0)
	v_add_f32_e32 v64, v64, v65
	global_atomic_add_f32 v[66:67], v64, off
.LBB0_1013:
	s_or_b64 exec, exec, s[30:31]
	v_add_u32_e32 v64, 0x80, v148
	v_sub_u32_e32 v66, v64, v152
	v_ashrrev_i32_e32 v67, 31, v66
	v_lshlrev_b64 v[66:67], 13, v[66:67]
	v_lshl_add_u64 v[66:67], s[8:9], 0, v[66:67]
	v_lshl_add_u64 v[66:67], v[146:147], 2, v[66:67]
	v_lshl_add_u64 v[74:75], v[66:67], 0, v[136:137]
	v_add_co_u32_e32 v76, vcc, 0x2000, v74
	s_waitcnt lgkmcnt(0)
	v_ashrrev_i32_e32 v65, 31, v64
	v_addc_co_u32_e32 v77, vcc, 0, v75, vcc
	global_load_dwordx4 v[66:69], v[74:75], off
	global_load_dwordx4 v[70:73], v[76:77], off
	v_readlane_b32 s24, v254, 25
	v_lshlrev_b64 v[78:79], 12, v[64:65]
	v_readlane_b32 s25, v254, 26
	s_waitcnt vmcnt(0)
; #define GAS __attribute__((address_space(1)))
;     __device__ __forceinline__ void operator()(const f32x4 (&acc)[2][2][4][2], const Unit& u, int wr, int wc, int fr, int fq) const {
;     ...
;         const int row0 = u.pm * BM + wr * 64 + fr, col0 = u.pn * BM + wc * 32 + 8 * fq; const bool odd = (fr & 1) != 0;
; #pragma unroll
;         for (int ai = 0; ai < 2; ++ai)
; #pragma unroll
;             for (int m = 0; m < 4; ++m) {
;                 const int row = row0 + ai * HALF + m * 16; float s = 0.f;
;                 const size_t off = (size_t)row * DM + col0;
;                 const size_t offp = (size_t)(row - (odd ? 1 : 0)) * DM + col0 + (odd ? 4 : 0);
; #pragma unroll
;                 for (int bj = 0; bj < 2; ++bj) {
;                     f32x4 b0, b1;
;                     if constexpr (BASE_F32) { const f32x4 la = *(const GAS f32x4*)(basef + offp + bj * HALF), lb = *(const GAS f32x4*)(basef + offp + DM + bj * HALF);
;                         const f32x4 snd = odd ? la : lb; f32x4 rcv; rcv[0] = dpp_xor1(snd[0]); rcv[1] = dpp_xor1(snd[1]); rcv[2] = dpp_xor1(snd[2]); rcv[3] = dpp_xor1(snd[3]);
;                         b0 = odd ? rcv : la; b1 = odd ? lb : rcv; }
;                     else { const u32x4 bw = *(const u32x4*)(baseb + off + bj * HALF);
;                         b0 = (f32x4){bf_lo(bw.x), bf_hi(bw.x), bf_lo(bw.y), bf_hi(bw.y)}; b1 = (f32x4){bf_lo(bw.z), bf_hi(bw.z), bf_lo(bw.w), bf_hi(bw.w)}; }
;                     const f32x4 v0 = acc[ai][bj][m][0] + b0, v1 = acc[ai][bj][m][1] + b1;
;                     if constexpr (OUT_F32) { const f32x4 snd = odd ? v0 : v1; f32x4 rcv; rcv[0] = dpp_xor1(snd[0]); rcv[1] = dpp_xor1(snd[1]); rcv[2] = dpp_xor1(snd[2]); rcv[3] = dpp_xor1(snd[3]);
;                         *(f32x4*)(H + offp + bj * HALF) = odd ? rcv : v0; *(f32x4*)(H + offp + DM + bj * HALF) = odd ? v1 : rcv; }
;                     else { u32x4 w; w.x = cvt_pk_bf16(v0[0], v0[1]); w.y = cvt_pk_bf16(v0[2], v0[3]); w.z = cvt_pk_bf16(v1[0], v1[1]); w.w = cvt_pk_bf16(v1[2], v1[3]);
;                         *(u32x4*)(HB + off + bj * HALF) = w; }
;                     s += (v0[0] * v0[0] + v0[1] * v0[1]) + (v0[2] * v0[2] + v0[3] * v0[3]) + (v1[0] * v1[0] + v1[1] * v1[1]) + (v1[2] * v1[2] + v1[3] * v1[3]);
;                 }
;                 s += __shfl_xor(s, 16); s += __shfl_xor(s, 32);
;                 if (fq == 0) unsafeAtomicAdd(ssn + row, s);
	v_cndmask_b32_e64 v84, v69, v73, s[0:1]
	v_cndmask_b32_e64 v85, v68, v72, s[0:1]
	v_cndmask_b32_e64 v86, v67, v71, s[0:1]
	v_cndmask_b32_e64 v87, v66, v70, s[0:1]
	v_lshl_add_u64 v[78:79], s[24:25], 0, v[78:79]
	v_mov_b32_dpp v81, v86 quad_perm:[1,0,3,2] row_mask:0xf bank_mask:0xf
	v_mov_b32_dpp v80, v87 quad_perm:[1,0,3,2] row_mask:0xf bank_mask:0xf
	v_mov_b32_dpp v82, v85 quad_perm:[1,0,3,2] row_mask:0xf bank_mask:0xf
	v_mov_b32_dpp v83, v84 quad_perm:[1,0,3,2] row_mask:0xf bank_mask:0xf
	v_lshl_add_u64 v[78:79], v[146:147], 1, v[78:79]
	v_cndmask_b32_e64 v67, v81, v67, s[0:1]
	v_cndmask_b32_e64 v66, v80, v66, s[0:1]
	v_cndmask_b32_e64 v69, v83, v69, s[0:1]
	v_cndmask_b32_e64 v68, v82, v68, s[0:1]
	v_cndmask_b32_e64 v71, v71, v81, s[0:1]
	v_cndmask_b32_e64 v70, v70, v80, s[0:1]
	v_cndmask_b32_e64 v73, v73, v83, s[0:1]
	v_cndmask_b32_e64 v72, v72, v82, s[0:1]
	v_pk_add_f32 v[68:69], v[62:63], v[68:69]
	v_pk_add_f32 v[66:67], v[60:61], v[66:67]
	v_pk_add_f32 v[72:73], v[58:59], v[72:73]
	v_pk_add_f32 v[70:71], v[56:57], v[70:71]
	v_cvt_pk_bf16_f32 v56, v66, v67
	v_cvt_pk_bf16_f32 v57, v68, v69
	v_mul_f32_e32 v67, v67, v67
	v_cvt_pk_bf16_f32 v58, v70, v71
	v_cvt_pk_bf16_f32 v59, v72, v73
	global_store_dwordx4 v[78:79], v[56:59], off
	global_load_dwordx4 v[56:59], v[74:75], off offset:512
	s_nop 0
	global_load_dwordx4 v[60:63], v[76:77], off offset:512
	v_mul_f32_e32 v69, v69, v69
	v_mul_f32_e32 v71, v71, v71
	v_fmac_f32_e32 v67, v66, v66
	v_fmac_f32_e32 v69, v68, v68
	v_fmac_f32_e32 v71, v70, v70
	v_add_f32_e32 v66, v67, v69
	v_mul_f32_e32 v73, v73, v73
	v_fmac_f32_e32 v73, v72, v72
	v_add_f32_e32 v66, v71, v66
	v_add_f32_e32 v66, v73, v66
	s_waitcnt vmcnt(0)
	v_cndmask_b32_e64 v67, v59, v63, s[0:1]
	v_cndmask_b32_e64 v68, v58, v62, s[0:1]
	v_cndmask_b32_e64 v69, v57, v61, s[0:1]
	v_cndmask_b32_e64 v70, v56, v60, s[0:1]
	v_mov_b32_dpp v76, v68 quad_perm:[1,0,3,2] row_mask:0xf bank_mask:0xf
	v_mov_b32_dpp v75, v69 quad_perm:[1,0,3,2] row_mask:0xf bank_mask:0xf
	v_mov_b32_dpp v74, v70 quad_perm:[1,0,3,2] row_mask:0xf bank_mask:0xf
	v_mov_b32_dpp v77, v67 quad_perm:[1,0,3,2] row_mask:0xf bank_mask:0xf
	v_cndmask_b32_e64 v57, v75, v57, s[0:1]
	v_cndmask_b32_e64 v56, v74, v56, s[0:1]
	v_cndmask_b32_e64 v59, v77, v59, s[0:1]
	v_cndmask_b32_e64 v58, v76, v58, s[0:1]
	v_cndmask_b32_e64 v61, v61, v75, s[0:1]
	v_cndmask_b32_e64 v60, v60, v74, s[0:1]
	v_pk_add_f32 v[54:55], v[54:55], v[58:59]
	v_pk_add_f32 v[52:53], v[52:53], v[56:57]
	v_cndmask_b32_e64 v63, v63, v77, s[0:1]
	v_cndmask_b32_e64 v62, v62, v76, s[0:1]
	v_pk_add_f32 v[58:59], v[48:49], v[60:61]
	v_mul_f32_e32 v48, v53, v53
	v_mul_f32_e32 v49, v55, v55
	v_pk_add_f32 v[56:57], v[50:51], v[62:63]
	v_mul_f32_e32 v50, v59, v59
	v_fmac_f32_e32 v48, v52, v52
	v_fmac_f32_e32 v49, v54, v54
	v_mul_f32_e32 v51, v57, v57
	v_fmac_f32_e32 v50, v58, v58
	v_add_f32_e32 v48, v48, v49
	v_add_f32_e32 v48, v50, v48
	v_fmac_f32_e32 v51, v56, v56
	v_add_f32_e32 v48, v51, v48
	v_add_f32_e32 v48, v66, v48
	ds_bpermute_b32 v49, v120, v48
	v_cvt_pk_bf16_f32 v50, v52, v53
	v_cvt_pk_bf16_f32 v51, v54, v55
	v_cvt_pk_bf16_f32 v52, v58, v59
	v_cvt_pk_bf16_f32 v53, v56, v57
	s_waitcnt lgkmcnt(0)
	v_add_f32_e32 v48, v48, v49
	ds_bpermute_b32 v49, v114, v48
	global_store_dwordx4 v[78:79], v[50:53], off offset:256
	s_and_saveexec_b64 s[30:31], s[2:3]
	s_cbranch_execz .LBB0_1015
	v_lshl_add_u64 v[50:51], v[64:65], 2, s[12:13]
	s_waitcnt lgkmcnt(0)
	v_add_f32_e32 v48, v48, v49
	global_atomic_add_f32 v[50:51], v48, off
.LBB0_1015:
	s_or_b64 exec, exec, s[30:31]
	v_add_u32_e32 v48, 0x90, v148
	v_sub_u32_e32 v50, v48, v152
	v_ashrrev_i32_e32 v51, 31, v50
	v_lshlrev_b64 v[50:51], 13, v[50:51]
	v_lshl_add_u64 v[50:51], s[8:9], 0, v[50:51]
	v_lshl_add_u64 v[50:51], v[146:147], 2, v[50:51]
	v_lshl_add_u64 v[58:59], v[50:51], 0, v[136:137]
	v_add_co_u32_e32 v60, vcc, 0x2000, v58
	s_waitcnt lgkmcnt(0)
	v_ashrrev_i32_e32 v49, 31, v48
	v_addc_co_u32_e32 v61, vcc, 0, v59, vcc
	global_load_dwordx4 v[50:53], v[58:59], off
	global_load_dwordx4 v[54:57], v[60:61], off
	v_readlane_b32 s24, v254, 25
	v_lshlrev_b64 v[62:63], 12, v[48:49]
	v_readlane_b32 s25, v254, 26
	s_waitcnt vmcnt(0)
	v_cndmask_b32_e64 v68, v53, v57, s[0:1]
	v_cndmask_b32_e64 v69, v52, v56, s[0:1]
	v_cndmask_b32_e64 v70, v51, v55, s[0:1]
	v_cndmask_b32_e64 v71, v50, v54, s[0:1]
	v_lshl_add_u64 v[62:63], s[24:25], 0, v[62:63]
	v_mov_b32_dpp v65, v70 quad_perm:[1,0,3,2] row_mask:0xf bank_mask:0xf
	v_mov_b32_dpp v64, v71 quad_perm:[1,0,3,2] row_mask:0xf bank_mask:0xf
	v_mov_b32_dpp v66, v69 quad_perm:[1,0,3,2] row_mask:0xf bank_mask:0xf
	v_mov_b32_dpp v67, v68 quad_perm:[1,0,3,2] row_mask:0xf bank_mask:0xf
	v_lshl_add_u64 v[62:63], v[146:147], 1, v[62:63]
	v_cndmask_b32_e64 v51, v65, v51, s[0:1]
	v_cndmask_b32_e64 v50, v64, v50, s[0:1]
	v_cndmask_b32_e64 v53, v67, v53, s[0:1]
	v_cndmask_b32_e64 v52, v66, v52, s[0:1]
	v_cndmask_b32_e64 v55, v55, v65, s[0:1]
	v_cndmask_b32_e64 v54, v54, v64, s[0:1]
	v_cndmask_b32_e64 v57, v57, v67, s[0:1]
	v_cndmask_b32_e64 v56, v56, v66, s[0:1]
	v_pk_add_f32 v[52:53], v[46:47], v[52:53]
	v_pk_add_f32 v[50:51], v[44:45], v[50:51]
	v_pk_add_f32 v[56:57], v[42:43], v[56:57]
	v_pk_add_f32 v[54:55], v[40:41], v[54:55]
	v_cvt_pk_bf16_f32 v40, v50, v51
	v_cvt_pk_bf16_f32 v41, v52, v53
	v_mul_f32_e32 v51, v51, v51
	v_cvt_pk_bf16_f32 v42, v54, v55
	v_cvt_pk_bf16_f32 v43, v56, v57
	global_store_dwordx4 v[62:63], v[40:43], off
	global_load_dwordx4 v[40:43], v[58:59], off offset:512
	s_nop 0
	global_load_dwordx4 v[44:47], v[60:61], off offset:512
	v_mul_f32_e32 v53, v53, v53
	v_mul_f32_e32 v55, v55, v55
	v_fmac_f32_e32 v51, v50, v50
	v_fmac_f32_e32 v53, v52, v52
	v_fmac_f32_e32 v55, v54, v54
	v_add_f32_e32 v50, v51, v53
	v_mul_f32_e32 v57, v57, v57
	v_fmac_f32_e32 v57, v56, v56
	v_add_f32_e32 v50, v55, v50
	v_add_f32_e32 v50, v57, v50
	s_waitcnt vmcnt(0)
; #define GAS __attribute__((address_space(1)))
;     __device__ __forceinline__ void operator()(const f32x4 (&acc)[2][2][4][2], const Unit& u, int wr, int wc, int fr, int fq) const {
;     ...
;         const int row0 = u.pm * BM + wr * 64 + fr, col0 = u.pn * BM + wc * 32 + 8 * fq; const bool odd = (fr & 1) != 0;
; #pragma unroll
;         for (int ai = 0; ai < 2; ++ai)
; #pragma unroll
;             for (int m = 0; m < 4; ++m) {
;                 const int row = row0 + ai * HALF + m * 16; float s = 0.f;
;                 const size_t off = (size_t)row * DM + col0;
;                 const size_t offp = (size_t)(row - (odd ? 1 : 0)) * DM + col0 + (odd ? 4 : 0);
; #pragma unroll
;                 for (int bj = 0; bj < 2; ++bj) {
;                     f32x4 b0, b1;
;                     if constexpr (BASE_F32) { const f32x4 la = *(const GAS f32x4*)(basef + offp + bj * HALF), lb = *(const GAS f32x4*)(basef + offp + DM + bj * HALF);
;                         const f32x4 snd = odd ? la : lb; f32x4 rcv; rcv[0] = dpp_xor1(snd[0]); rcv[1] = dpp_xor1(snd[1]); rcv[2] = dpp_xor1(snd[2]); rcv[3] = dpp_xor1(snd[3]);
;                         b0 = odd ? rcv : la; b1 = odd ? lb : rcv; }
;                     else { const u32x4 bw = *(const u32x4*)(baseb + off + bj * HALF);
;                         b0 = (f32x4){bf_lo(bw.x), bf_hi(bw.x), bf_lo(bw.y), bf_hi(bw.y)}; b1 = (f32x4){bf_lo(bw.z), bf_hi(bw.z), bf_lo(bw.w), bf_hi(bw.w)}; }
;                     const f32x4 v0 = acc[ai][bj][m][0] + b0, v1 = acc[ai][bj][m][1] + b1;
;                     if constexpr (OUT_F32) { const f32x4 snd = odd ? v0 : v1; f32x4 rcv; rcv[0] = dpp_xor1(snd[0]); rcv[1] = dpp_xor1(snd[1]); rcv[2] = dpp_xor1(snd[2]); rcv[3] = dpp_xor1(snd[3]);
;                         *(f32x4*)(H + offp + bj * HALF) = odd ? rcv : v0; *(f32x4*)(H + offp + DM + bj * HALF) = odd ? v1 : rcv; }
;                     else { u32x4 w; w.x = cvt_pk_bf16(v0[0], v0[1]); w.y = cvt_pk_bf16(v0[2], v0[3]); w.z = cvt_pk_bf16(v1[0], v1[1]); w.w = cvt_pk_bf16(v1[2], v1[3]);
;                         *(u32x4*)(HB + off + bj * HALF) = w; }
;                     s += (v0[0] * v0[0] + v0[1] * v0[1]) + (v0[2] * v0[2] + v0[3] * v0[3]) + (v1[0] * v1[0] + v1[1] * v1[1]) + (v1[2] * v1[2] + v1[3] * v1[3]);
;                 }
;                 s += __shfl_xor(s, 16); s += __shfl_xor(s, 32);
;                 if (fq == 0) unsafeAtomicAdd(ssn + row, s);
	v_cndmask_b32_e64 v51, v43, v47, s[0:1]
	v_cndmask_b32_e64 v52, v42, v46, s[0:1]
	v_cndmask_b32_e64 v53, v41, v45, s[0:1]
	v_cndmask_b32_e64 v54, v40, v44, s[0:1]
	v_mov_b32_dpp v60, v52 quad_perm:[1,0,3,2] row_mask:0xf bank_mask:0xf
	v_mov_b32_dpp v59, v53 quad_perm:[1,0,3,2] row_mask:0xf bank_mask:0xf
	v_mov_b32_dpp v58, v54 quad_perm:[1,0,3,2] row_mask:0xf bank_mask:0xf
	v_mov_b32_dpp v61, v51 quad_perm:[1,0,3,2] row_mask:0xf bank_mask:0xf
	v_cndmask_b32_e64 v41, v59, v41, s[0:1]
	v_cndmask_b32_e64 v40, v58, v40, s[0:1]
	v_cndmask_b32_e64 v43, v61, v43, s[0:1]
	v_cndmask_b32_e64 v42, v60, v42, s[0:1]
	v_cndmask_b32_e64 v45, v45, v59, s[0:1]
	v_cndmask_b32_e64 v44, v44, v58, s[0:1]
	v_pk_add_f32 v[38:39], v[38:39], v[42:43]
	v_pk_add_f32 v[36:37], v[36:37], v[40:41]
	v_cndmask_b32_e64 v47, v47, v61, s[0:1]
	v_cndmask_b32_e64 v46, v46, v60, s[0:1]
	v_pk_add_f32 v[42:43], v[32:33], v[44:45]
	v_mul_f32_e32 v32, v37, v37
	v_mul_f32_e32 v33, v39, v39
	v_pk_add_f32 v[40:41], v[34:35], v[46:47]
	v_mul_f32_e32 v34, v43, v43
	v_fmac_f32_e32 v32, v36, v36
	v_fmac_f32_e32 v33, v38, v38
	v_mul_f32_e32 v35, v41, v41
	v_fmac_f32_e32 v34, v42, v42
	v_add_f32_e32 v32, v32, v33
	v_add_f32_e32 v32, v34, v32
	v_fmac_f32_e32 v35, v40, v40
	v_add_f32_e32 v32, v35, v32
	v_add_f32_e32 v32, v50, v32
	ds_bpermute_b32 v33, v120, v32
	v_cvt_pk_bf16_f32 v34, v36, v37
	v_cvt_pk_bf16_f32 v35, v38, v39
	v_cvt_pk_bf16_f32 v36, v42, v43
	v_cvt_pk_bf16_f32 v37, v40, v41
	s_waitcnt lgkmcnt(0)
	v_add_f32_e32 v32, v32, v33
	ds_bpermute_b32 v33, v114, v32
	global_store_dwordx4 v[62:63], v[34:37], off offset:256
	s_and_saveexec_b64 s[30:31], s[2:3]
	s_cbranch_execz .LBB0_1017
	v_lshl_add_u64 v[34:35], v[48:49], 2, s[12:13]
	s_waitcnt lgkmcnt(0)
	v_add_f32_e32 v32, v32, v33
	global_atomic_add_f32 v[34:35], v32, off
.LBB0_1017:
	s_or_b64 exec, exec, s[30:31]
	v_add_u32_e32 v32, 0xa0, v148
	v_sub_u32_e32 v34, v32, v152
	v_ashrrev_i32_e32 v35, 31, v34
	v_lshlrev_b64 v[34:35], 13, v[34:35]
	v_lshl_add_u64 v[34:35], s[8:9], 0, v[34:35]
	v_lshl_add_u64 v[34:35], v[146:147], 2, v[34:35]
	v_lshl_add_u64 v[42:43], v[34:35], 0, v[136:137]
	v_add_co_u32_e32 v44, vcc, 0x2000, v42
	s_waitcnt lgkmcnt(0)
	v_ashrrev_i32_e32 v33, 31, v32
	v_addc_co_u32_e32 v45, vcc, 0, v43, vcc
	global_load_dwordx4 v[34:37], v[42:43], off
	global_load_dwordx4 v[38:41], v[44:45], off
	v_readlane_b32 s24, v254, 25
	v_lshlrev_b64 v[46:47], 12, v[32:33]
	v_readlane_b32 s25, v254, 26
	s_waitcnt vmcnt(0)
	v_cndmask_b32_e64 v52, v37, v41, s[0:1]
	v_cndmask_b32_e64 v53, v36, v40, s[0:1]
	v_cndmask_b32_e64 v54, v35, v39, s[0:1]
	v_cndmask_b32_e64 v55, v34, v38, s[0:1]
	v_lshl_add_u64 v[46:47], s[24:25], 0, v[46:47]
	v_mov_b32_dpp v49, v54 quad_perm:[1,0,3,2] row_mask:0xf bank_mask:0xf
	v_mov_b32_dpp v48, v55 quad_perm:[1,0,3,2] row_mask:0xf bank_mask:0xf
	v_mov_b32_dpp v50, v53 quad_perm:[1,0,3,2] row_mask:0xf bank_mask:0xf
	v_mov_b32_dpp v51, v52 quad_perm:[1,0,3,2] row_mask:0xf bank_mask:0xf
	v_lshl_add_u64 v[46:47], v[146:147], 1, v[46:47]
	v_cndmask_b32_e64 v35, v49, v35, s[0:1]
	v_cndmask_b32_e64 v34, v48, v34, s[0:1]
	v_cndmask_b32_e64 v37, v51, v37, s[0:1]
	v_cndmask_b32_e64 v36, v50, v36, s[0:1]
	v_cndmask_b32_e64 v39, v39, v49, s[0:1]
	v_cndmask_b32_e64 v38, v38, v48, s[0:1]
	v_cndmask_b32_e64 v41, v41, v51, s[0:1]
	v_cndmask_b32_e64 v40, v40, v50, s[0:1]
	v_pk_add_f32 v[36:37], v[30:31], v[36:37]
	v_pk_add_f32 v[34:35], v[28:29], v[34:35]
	v_pk_add_f32 v[40:41], v[26:27], v[40:41]
	v_pk_add_f32 v[38:39], v[24:25], v[38:39]
	v_cvt_pk_bf16_f32 v24, v34, v35
	v_cvt_pk_bf16_f32 v25, v36, v37
	v_mul_f32_e32 v35, v35, v35
	v_cvt_pk_bf16_f32 v26, v38, v39
	v_cvt_pk_bf16_f32 v27, v40, v41
	global_store_dwordx4 v[46:47], v[24:27], off
	global_load_dwordx4 v[24:27], v[42:43], off offset:512
	s_nop 0
	global_load_dwordx4 v[28:31], v[44:45], off offset:512
	v_mul_f32_e32 v37, v37, v37
	v_mul_f32_e32 v39, v39, v39
	v_fmac_f32_e32 v35, v34, v34
	v_fmac_f32_e32 v37, v36, v36
	v_fmac_f32_e32 v39, v38, v38
	v_add_f32_e32 v34, v35, v37
	v_mul_f32_e32 v41, v41, v41
	v_fmac_f32_e32 v41, v40, v40
	v_add_f32_e32 v34, v39, v34
	v_add_f32_e32 v34, v41, v34
	s_waitcnt vmcnt(0)
	v_cndmask_b32_e64 v35, v27, v31, s[0:1]
	v_cndmask_b32_e64 v36, v26, v30, s[0:1]
	v_cndmask_b32_e64 v37, v25, v29, s[0:1]
	v_cndmask_b32_e64 v38, v24, v28, s[0:1]
	v_mov_b32_dpp v44, v36 quad_perm:[1,0,3,2] row_mask:0xf bank_mask:0xf
	v_mov_b32_dpp v43, v37 quad_perm:[1,0,3,2] row_mask:0xf bank_mask:0xf
	v_mov_b32_dpp v42, v38 quad_perm:[1,0,3,2] row_mask:0xf bank_mask:0xf
	v_mov_b32_dpp v45, v35 quad_perm:[1,0,3,2] row_mask:0xf bank_mask:0xf
	v_cndmask_b32_e64 v25, v43, v25, s[0:1]
	v_cndmask_b32_e64 v24, v42, v24, s[0:1]
	v_cndmask_b32_e64 v27, v45, v27, s[0:1]
	v_cndmask_b32_e64 v26, v44, v26, s[0:1]
	v_cndmask_b32_e64 v29, v29, v43, s[0:1]
	v_cndmask_b32_e64 v28, v28, v42, s[0:1]
	v_pk_add_f32 v[22:23], v[22:23], v[26:27]
	v_pk_add_f32 v[20:21], v[20:21], v[24:25]
	v_cndmask_b32_e64 v31, v31, v45, s[0:1]
	v_cndmask_b32_e64 v30, v30, v44, s[0:1]
	v_pk_add_f32 v[26:27], v[16:17], v[28:29]
	v_mul_f32_e32 v16, v21, v21
	v_mul_f32_e32 v17, v23, v23
	v_pk_add_f32 v[24:25], v[18:19], v[30:31]
	v_mul_f32_e32 v18, v27, v27
	v_fmac_f32_e32 v16, v20, v20
	v_fmac_f32_e32 v17, v22, v22
	v_mul_f32_e32 v19, v25, v25
	v_fmac_f32_e32 v18, v26, v26
	v_add_f32_e32 v16, v16, v17
	v_add_f32_e32 v16, v18, v16
	v_fmac_f32_e32 v19, v24, v24
	v_add_f32_e32 v16, v19, v16
	v_add_f32_e32 v16, v34, v16
	ds_bpermute_b32 v17, v120, v16
	v_cvt_pk_bf16_f32 v18, v20, v21
	v_cvt_pk_bf16_f32 v19, v22, v23
	v_cvt_pk_bf16_f32 v20, v26, v27
	v_cvt_pk_bf16_f32 v21, v24, v25
	s_waitcnt lgkmcnt(0)
	v_add_f32_e32 v16, v16, v17
	ds_bpermute_b32 v17, v114, v16
	global_store_dwordx4 v[46:47], v[18:21], off offset:256
	s_and_saveexec_b64 s[30:31], s[2:3]
	s_cbranch_execz .LBB0_1019
	v_lshl_add_u64 v[18:19], v[32:33], 2, s[12:13]
	s_waitcnt lgkmcnt(0)
	v_add_f32_e32 v16, v16, v17
	global_atomic_add_f32 v[18:19], v16, off
; #define GAS __attribute__((address_space(1)))
;     __device__ __forceinline__ void operator()(const f32x4 (&acc)[2][2][4][2], const Unit& u, int wr, int wc, int fr, int fq) const {
;     ...
;         const int row0 = u.pm * BM + wr * 64 + fr, col0 = u.pn * BM + wc * 32 + 8 * fq; const bool odd = (fr & 1) != 0;
; #pragma unroll
;         for (int ai = 0; ai < 2; ++ai)
; #pragma unroll
;             for (int m = 0; m < 4; ++m) {
;                 const int row = row0 + ai * HALF + m * 16; float s = 0.f;
;                 const size_t off = (size_t)row * DM + col0;
;                 const size_t offp = (size_t)(row - (odd ? 1 : 0)) * DM + col0 + (odd ? 4 : 0);
; #pragma unroll
;                 for (int bj = 0; bj < 2; ++bj) {
;                     f32x4 b0, b1;
;                     if constexpr (BASE_F32) { const f32x4 la = *(const GAS f32x4*)(basef + offp + bj * HALF), lb = *(const GAS f32x4*)(basef + offp + DM + bj * HALF);
;                         const f32x4 snd = odd ? la : lb; f32x4 rcv; rcv[0] = dpp_xor1(snd[0]); rcv[1] = dpp_xor1(snd[1]); rcv[2] = dpp_xor1(snd[2]); rcv[3] = dpp_xor1(snd[3]);
;                         b0 = odd ? rcv : la; b1 = odd ? lb : rcv; }
;                     else { const u32x4 bw = *(const u32x4*)(baseb + off + bj * HALF);
;                         b0 = (f32x4){bf_lo(bw.x), bf_hi(bw.x), bf_lo(bw.y), bf_hi(bw.y)}; b1 = (f32x4){bf_lo(bw.z), bf_hi(bw.z), bf_lo(bw.w), bf_hi(bw.w)}; }
;                     const f32x4 v0 = acc[ai][bj][m][0] + b0, v1 = acc[ai][bj][m][1] + b1;
;                     if constexpr (OUT_F32) { const f32x4 snd = odd ? v0 : v1; f32x4 rcv; rcv[0] = dpp_xor1(snd[0]); rcv[1] = dpp_xor1(snd[1]); rcv[2] = dpp_xor1(snd[2]); rcv[3] = dpp_xor1(snd[3]);
;                         *(f32x4*)(H + offp + bj * HALF) = odd ? rcv : v0; *(f32x4*)(H + offp + DM + bj * HALF) = odd ? v1 : rcv; }
;                     else { u32x4 w; w.x = cvt_pk_bf16(v0[0], v0[1]); w.y = cvt_pk_bf16(v0[2], v0[3]); w.z = cvt_pk_bf16(v1[0], v1[1]); w.w = cvt_pk_bf16(v1[2], v1[3]);
;                         *(u32x4*)(HB + off + bj * HALF) = w; }
;                     s += (v0[0] * v0[0] + v0[1] * v0[1]) + (v0[2] * v0[2] + v0[3] * v0[3]) + (v1[0] * v1[0] + v1[1] * v1[1]) + (v1[2] * v1[2] + v1[3] * v1[3]);
;                 }
;                 s += __shfl_xor(s, 16); s += __shfl_xor(s, 32);
;                 if (fq == 0) unsafeAtomicAdd(ssn + row, s);
.LBB0_1019:
	s_or_b64 exec, exec, s[30:31]
	v_add_u32_e32 v16, 0xb0, v148
	v_sub_u32_e32 v18, v16, v152
	v_ashrrev_i32_e32 v19, 31, v18
	v_lshlrev_b64 v[18:19], 13, v[18:19]
	v_lshl_add_u64 v[18:19], s[8:9], 0, v[18:19]
	v_lshl_add_u64 v[18:19], v[146:147], 2, v[18:19]
	v_lshl_add_u64 v[26:27], v[18:19], 0, v[136:137]
	v_add_co_u32_e32 v28, vcc, 0x2000, v26
	s_waitcnt lgkmcnt(0)
	v_ashrrev_i32_e32 v17, 31, v16
	v_addc_co_u32_e32 v29, vcc, 0, v27, vcc
	global_load_dwordx4 v[18:21], v[26:27], off
	global_load_dwordx4 v[22:25], v[28:29], off
	v_readlane_b32 s24, v254, 25
	v_lshlrev_b64 v[30:31], 12, v[16:17]
	v_readlane_b32 s25, v254, 26
	s_waitcnt vmcnt(0)
	v_cndmask_b32_e64 v36, v21, v25, s[0:1]
	v_cndmask_b32_e64 v37, v20, v24, s[0:1]
	v_cndmask_b32_e64 v38, v19, v23, s[0:1]
	v_cndmask_b32_e64 v39, v18, v22, s[0:1]
	v_lshl_add_u64 v[30:31], s[24:25], 0, v[30:31]
	v_mov_b32_dpp v33, v38 quad_perm:[1,0,3,2] row_mask:0xf bank_mask:0xf
	v_mov_b32_dpp v32, v39 quad_perm:[1,0,3,2] row_mask:0xf bank_mask:0xf
	v_mov_b32_dpp v34, v37 quad_perm:[1,0,3,2] row_mask:0xf bank_mask:0xf
	v_mov_b32_dpp v35, v36 quad_perm:[1,0,3,2] row_mask:0xf bank_mask:0xf
	v_lshl_add_u64 v[30:31], v[146:147], 1, v[30:31]
	v_cndmask_b32_e64 v19, v33, v19, s[0:1]
	v_cndmask_b32_e64 v18, v32, v18, s[0:1]
	v_cndmask_b32_e64 v21, v35, v21, s[0:1]
	v_cndmask_b32_e64 v20, v34, v20, s[0:1]
	v_cndmask_b32_e64 v23, v23, v33, s[0:1]
	v_cndmask_b32_e64 v22, v22, v32, s[0:1]
	v_cndmask_b32_e64 v25, v25, v35, s[0:1]
	v_cndmask_b32_e64 v24, v24, v34, s[0:1]
	v_pk_add_f32 v[20:21], v[14:15], v[20:21]
	v_pk_add_f32 v[18:19], v[12:13], v[18:19]
	v_pk_add_f32 v[24:25], v[10:11], v[24:25]
	v_pk_add_f32 v[22:23], v[8:9], v[22:23]
	v_cvt_pk_bf16_f32 v8, v18, v19
	v_cvt_pk_bf16_f32 v9, v20, v21
	v_mul_f32_e32 v19, v19, v19
	v_cvt_pk_bf16_f32 v10, v22, v23
	v_cvt_pk_bf16_f32 v11, v24, v25
	global_store_dwordx4 v[30:31], v[8:11], off
	global_load_dwordx4 v[8:11], v[26:27], off offset:512
	s_nop 0
	global_load_dwordx4 v[12:15], v[28:29], off offset:512
	v_mul_f32_e32 v21, v21, v21
	v_mul_f32_e32 v23, v23, v23
	v_fmac_f32_e32 v19, v18, v18
	v_fmac_f32_e32 v21, v20, v20
	v_fmac_f32_e32 v23, v22, v22
	v_add_f32_e32 v18, v19, v21
	v_mul_f32_e32 v25, v25, v25
	v_fmac_f32_e32 v25, v24, v24
	v_add_f32_e32 v18, v23, v18
	v_add_f32_e32 v18, v25, v18
	s_waitcnt vmcnt(0)
	v_cndmask_b32_e64 v19, v11, v15, s[0:1]
	v_cndmask_b32_e64 v20, v10, v14, s[0:1]
	v_cndmask_b32_e64 v21, v9, v13, s[0:1]
	v_cndmask_b32_e64 v22, v8, v12, s[0:1]
	v_mov_b32_dpp v28, v20 quad_perm:[1,0,3,2] row_mask:0xf bank_mask:0xf
	v_mov_b32_dpp v27, v21 quad_perm:[1,0,3,2] row_mask:0xf bank_mask:0xf
	v_mov_b32_dpp v26, v22 quad_perm:[1,0,3,2] row_mask:0xf bank_mask:0xf
	v_mov_b32_dpp v29, v19 quad_perm:[1,0,3,2] row_mask:0xf bank_mask:0xf
	v_cndmask_b32_e64 v9, v27, v9, s[0:1]
	v_cndmask_b32_e64 v8, v26, v8, s[0:1]
	v_cndmask_b32_e64 v11, v29, v11, s[0:1]
	v_cndmask_b32_e64 v10, v28, v10, s[0:1]
	v_cndmask_b32_e64 v13, v13, v27, s[0:1]
	v_cndmask_b32_e64 v12, v12, v26, s[0:1]
	v_pk_add_f32 v[6:7], v[6:7], v[10:11]
	v_pk_add_f32 v[4:5], v[4:5], v[8:9]
	v_cndmask_b32_e64 v15, v15, v29, s[0:1]
	v_cndmask_b32_e64 v14, v14, v28, s[0:1]
	v_pk_add_f32 v[10:11], v[0:1], v[12:13]
	v_mul_f32_e32 v0, v5, v5
	v_mul_f32_e32 v1, v7, v7
	v_pk_add_f32 v[8:9], v[2:3], v[14:15]
	v_mul_f32_e32 v2, v11, v11
	v_fmac_f32_e32 v0, v4, v4
	v_fmac_f32_e32 v1, v6, v6
	v_mul_f32_e32 v3, v9, v9
	v_fmac_f32_e32 v2, v10, v10
	v_add_f32_e32 v0, v0, v1
	v_add_f32_e32 v0, v2, v0
	v_fmac_f32_e32 v3, v8, v8
	v_add_f32_e32 v0, v3, v0
	v_add_f32_e32 v0, v18, v0
	ds_bpermute_b32 v1, v120, v0
	v_cvt_pk_bf16_f32 v2, v4, v5
	v_cvt_pk_bf16_f32 v3, v6, v7
	v_cvt_pk_bf16_f32 v4, v10, v11
	v_cvt_pk_bf16_f32 v5, v8, v9
	s_waitcnt lgkmcnt(0)
	v_add_f32_e32 v0, v0, v1
	ds_bpermute_b32 v1, v114, v0
	global_store_dwordx4 v[30:31], v[2:5], off offset:256
	s_and_saveexec_b64 s[30:31], s[2:3]
	s_cbranch_execz .LBB0_1021
	v_lshl_add_u64 v[2:3], v[16:17], 2, s[12:13]
	s_waitcnt lgkmcnt(0)
	v_add_f32_e32 v0, v0, v1
	global_atomic_add_f32 v[2:3], v0, off

; #define LAS __attribute__((address_space(3)))
;     __device__ __forceinline__ void operator()(f32x4 (&acc)[2][2][4][2], const Unit& u, int wr, int wc, int fr, int fq) const {
;     ...
;         for (int ai = 0; ai < 2; ++ai) {
;             const int rb = 2 * ai + wr;
;             f32x4 Sprev[2], Scur[2], Tcur[2], Tnext[2];
; #pragma unroll
;             for (int n = 0; n < 2; ++n) { Sprev[n] = (rb > 0) ? *(const LAS f32x4*)(XL + (rb - 1) * 128 + cl + 4 * n) : (f32x4){0.f, 0.f, 0.f, 0.f};
; #pragma unroll
;                 for (int j = 0; j < 4; ++j) Tcur[n][j] = dpp_rol1(acc[ai][0][0][n][j]); }
; #pragma unroll
;             for (int m = 0; m < 4; ++m) {
; #pragma unroll
;                 for (int n = 0; n < 2; ++n) {
; #pragma unroll
;                     for (int j = 0; j < 4; ++j) Scur[n][j] = dpp_ror1(acc[ai][0][m][n][j]);
;                     if (m < 3) {
; #pragma unroll
;                         for (int j = 0; j < 4; ++j) Tnext[n][j] = dpp_rol1(acc[ai][0][m < 3 ? m + 1 : 3][n][j]);
;                     } else Tnext[n] = (rb < 3) ? *(const LAS f32x4*)(XF + (rb + 1) * 128 + cl + 4 * n) : (f32x4){0.f, 0.f, 0.f, 0.f};
;                 }
;                 const int row = row0 + ai * HALF + m * 16, lrow = row & 255;
;                 const bool edge = (lrow == 0) || (lrow == 255);
;                 u32x4 ow;
; #pragma unroll
;                 for (int n = 0; n < 2; ++n) {
;                     const f32x4 up = (fr == 0) ? Sprev[n] : Scur[n], dn = (fr == 15) ? Tnext[n] : Tcur[n];
;                     const f32x4 a = w0[n] * up + w1[n] * acc[ai][0][m][n] + w2[n] * dn + bb[n];
;                     const f32x4 uu = acc[ai][1][m][n];
;                     ow[2 * n] = cvt_pk_bf16(gelu_tanh(a[0]) * uu[0], gelu_tanh(a[1]) * uu[1]);
;                     ow[2 * n + 1] = cvt_pk_bf16(gelu_tanh(a[2]) * uu[2], gelu_tanh(a[3]) * uu[3]);
;                 }
;                 if (!edge) *(u32x4*)(ACT + (size_t)row * DFF + f0) = ow;
;                 if (lrow < 2 || lrow > 253) { const int e = lrow < 2 ? lrow : lrow - 252; float* eg = EG + ((size_t)u.pm * 4 + e) * DFF + f0;
;                     *(f32x4*)eg = acc[ai][0][m][0]; *(f32x4*)(eg + 4) = acc[ai][0][m][1];
;                     if (edge) { float* eu = EU + ((size_t)u.pm * 2 + (lrow == 255 ? 1 : 0)) * DFF + f0; *(f32x4*)eu = acc[ai][1][m][0]; *(f32x4*)(eu + 4) = acc[ai][1][m][1]; } }
.LBB0_1119:
	s_or_b64 exec, exec, s[14:15]
	s_nop 1
	v_mov_b32_e32 v136, v208
	v_mov_b32_e32 v137, v208
	v_mov_b32_dpp v152, v172 row_ror:1 row_mask:0xf bank_mask:0xf
	v_mov_b32_dpp v153, v173 row_ror:1 row_mask:0xf bank_mask:0xf
	v_pk_mul_f32 v[138:139], v[118:119], v[136:137]
	v_pk_mul_f32 v[136:137], v[114:115], v[136:137]
	v_pk_mul_f32 v[124:125], v[124:125], v[206:207] op_sel_hi:[1,0]
	v_pk_mul_f32 v[114:115], v[122:123], v[206:207] op_sel_hi:[1,0]
	v_cndmask_b32_e64 v123, v153, v237, s[2:3]
	v_cndmask_b32_e64 v122, v152, v236, s[2:3]
	v_mov_b32_dpp v156, v124 row_ror:15 row_mask:0xf bank_mask:0xf
	v_mov_b32_dpp v157, v125 row_ror:15 row_mask:0xf bank_mask:0xf
	v_pk_mul_f32 v[122:123], v[84:85], v[122:123]
	v_cndmask_b32_e64 v143, v240, v157, s[4:5]
	v_cndmask_b32_e64 v142, v238, v156, s[4:5]
	v_pk_fma_f32 v[122:123], v[80:81], v[172:173], v[122:123]
	v_pk_fma_f32 v[122:123], v[68:69], v[142:143], v[122:123]
	v_pk_add_f32 v[122:123], v[76:77], v[122:123]
	v_mov_b32_e32 v209, v208
	v_mul_f32_e32 v142, v122, v122
	v_fmamk_f32 v142, v142, 0xbdd2d3e7, v232
	v_mul_f32_e32 v143, v123, v123
	v_mul_f32_e32 v142, v122, v142
	v_fmamk_f32 v143, v143, 0xbdd2d3e7, v232
	v_mov_b32_dpp v154, v170 row_ror:1 row_mask:0xf bank_mask:0xf
	v_mov_b32_dpp v155, v171 row_ror:1 row_mask:0xf bank_mask:0xf
	v_exp_f32_e32 v142, v142
	v_mul_f32_e32 v143, v123, v143
	v_pk_mul_f32 v[140:141], v[116:117], v[208:209]
	v_pk_mul_f32 v[118:119], v[126:127], v[206:207] op_sel_hi:[1,0]
	v_pk_mul_f32 v[116:117], v[120:121], v[206:207] op_sel_hi:[1,0]
	v_cndmask_b32_e64 v121, v155, v241, s[2:3]
	v_cndmask_b32_e64 v120, v154, v239, s[2:3]
	v_exp_f32_e32 v143, v143
	v_mov_b32_dpp v158, v118 row_ror:15 row_mask:0xf bank_mask:0xf
	v_mov_b32_dpp v159, v119 row_ror:15 row_mask:0xf bank_mask:0xf
	v_pk_mul_f32 v[120:121], v[86:87], v[120:121]
	v_cndmask_b32_e64 v127, v243, v159, s[4:5]
	v_cndmask_b32_e64 v126, v242, v158, s[4:5]
	v_pk_fma_f32 v[120:121], v[82:83], v[170:171], v[120:121]
	v_pk_fma_f32 v[120:121], v[70:71], v[126:127], v[120:121]
	v_add_f32_e32 v126, 1.0, v142
	v_rcp_f32_e32 v142, v126
	v_add_f32_e32 v126, 1.0, v143
	v_rcp_f32_e32 v143, v126
	v_pk_add_f32 v[126:127], v[78:79], v[120:121]
	v_mul_f32_e32 v120, v122, v142
	v_mul_f32_e32 v122, v126, v126
	v_mul_f32_e32 v121, v123, v143
	v_mul_f32_e32 v123, v127, v127
	v_fmamk_f32 v122, v122, 0xbdd2d3e7, v232
	v_fmamk_f32 v123, v123, 0xbdd2d3e7, v232
	v_mul_f32_e32 v122, v126, v122
	v_mul_f32_e32 v123, v127, v123
	v_exp_f32_e32 v122, v122
	v_exp_f32_e32 v123, v123
	v_mov_b32_dpp v160, v150 row_ror:1 row_mask:0xf bank_mask:0xf
	v_add_f32_e32 v122, 1.0, v122
	v_add_f32_e32 v123, 1.0, v123
	v_rcp_f32_e32 v122, v122
	v_rcp_f32_e32 v123, v123
	v_mov_b32_dpp v161, v151 row_ror:1 row_mask:0xf bank_mask:0xf
	v_mul_f32_e32 v120, v140, v120
	v_mul_f32_e32 v121, v141, v121
	v_cvt_pk_bf16_f32 v120, v120, v121
	v_mul_f32_e32 v121, v126, v122
	v_mul_f32_e32 v122, v127, v123
	v_cndmask_b32_e64 v127, v161, v199, s[2:3]
	v_cndmask_b32_e64 v126, v160, v175, s[2:3]
	v_mov_b32_dpp v164, v116 row_ror:15 row_mask:0xf bank_mask:0xf
	v_mov_b32_dpp v165, v117 row_ror:15 row_mask:0xf bank_mask:0xf
	v_pk_mul_f32 v[126:127], v[44:45], v[126:127]
	v_cndmask_b32_e64 v141, v210, v165, s[4:5]
	v_cndmask_b32_e64 v140, v201, v164, s[4:5]
	v_pk_fma_f32 v[126:127], v[40:41], v[150:151], v[126:127]
	v_pk_fma_f32 v[126:127], v[32:33], v[140:141], v[126:127]
	v_pk_add_f32 v[126:127], v[36:37], v[126:127]
	v_mov_b32_dpp v162, v148 row_ror:1 row_mask:0xf bank_mask:0xf
	v_mul_f32_e32 v140, v126, v126
	v_fmamk_f32 v140, v140, 0xbdd2d3e7, v232
	v_mul_f32_e32 v140, v126, v140
	v_mul_f32_e32 v141, v127, v127
	v_mov_b32_dpp v163, v149 row_ror:1 row_mask:0xf bank_mask:0xf
	v_mul_f32_e32 v121, v138, v121
	v_mul_f32_e32 v122, v139, v122
	v_exp_f32_e32 v140, v140
	v_fmamk_f32 v141, v141, 0xbdd2d3e7, v232
	v_cvt_pk_bf16_f32 v121, v121, v122
	v_cndmask_b32_e64 v123, v163, v211, s[2:3]
	v_cndmask_b32_e64 v122, v162, v207, s[2:3]
	v_mul_f32_e32 v141, v127, v141
	v_mov_b32_dpp v166, v114 row_ror:15 row_mask:0xf bank_mask:0xf
	v_mov_b32_dpp v167, v115 row_ror:15 row_mask:0xf bank_mask:0xf
	v_pk_mul_f32 v[122:123], v[46:47], v[122:123]
	v_exp_f32_e32 v141, v141
	v_cndmask_b32_e64 v139, v235, v167, s[4:5]
	v_cndmask_b32_e64 v138, v234, v166, s[4:5]
	v_pk_fma_f32 v[122:123], v[42:43], v[148:149], v[122:123]
	v_pk_mul_f32 v[112:113], v[112:113], v[208:209]
	v_pk_fma_f32 v[122:123], v[34:35], v[138:139], v[122:123]
	v_add_f32_e32 v138, 1.0, v140
	v_rcp_f32_e32 v140, v138
	v_add_f32_e32 v138, 1.0, v141
	v_rcp_f32_e32 v141, v138
	v_pk_add_f32 v[138:139], v[38:39], v[122:123]
	v_mul_f32_e32 v122, v126, v140
	v_mul_f32_e32 v123, v138, v138
	v_fmamk_f32 v123, v123, 0xbdd2d3e7, v232
	v_mul_f32_e32 v126, v139, v139
	v_mul_f32_e32 v123, v138, v123
	v_fmamk_f32 v126, v126, 0xbdd2d3e7, v232
	v_exp_f32_e32 v123, v123
	v_mul_f32_e32 v126, v139, v126
	v_exp_f32_e32 v126, v126
	v_mul_f32_e32 v112, v112, v122
	v_mul_f32_e32 v122, v127, v141
	v_mul_f32_e32 v113, v113, v122
	v_add_f32_e32 v122, 1.0, v123
	v_rcp_f32_e32 v123, v122
	v_add_f32_e32 v122, 1.0, v126
	v_rcp_f32_e32 v126, v122
	v_cvt_pk_bf16_f32 v122, v112, v113
	v_mul_f32_e32 v112, v138, v123
	v_mul_f32_e32 v113, v139, v126
	v_mov_b32_dpp v138, v124 row_ror:1 row_mask:0xf bank_mask:0xf
	v_mov_b32_dpp v139, v125 row_ror:1 row_mask:0xf bank_mask:0xf
	v_cndmask_b32_e64 v151, v139, v153, s[2:3]
	v_cndmask_b32_e64 v150, v138, v152, s[2:3]
	v_mov_b32_dpp v141, v118 row_ror:1 row_mask:0xf bank_mask:0xf
	v_mov_b32_dpp v143, v119 row_ror:1 row_mask:0xf bank_mask:0xf
	v_mov_b32_dpp v140, v128 row_ror:15 row_mask:0xf bank_mask:0xf
; #define LAS __attribute__((address_space(3)))
;     __device__ __forceinline__ void operator()(f32x4 (&acc)[2][2][4][2], const Unit& u, int wr, int wc, int fr, int fq) const {
;     ...
;         for (int ai = 0; ai < 2; ++ai) {
;             const int rb = 2 * ai + wr;
;             f32x4 Sprev[2], Scur[2], Tcur[2], Tnext[2];
; #pragma unroll
;             for (int n = 0; n < 2; ++n) { Sprev[n] = (rb > 0) ? *(const LAS f32x4*)(XL + (rb - 1) * 128 + cl + 4 * n) : (f32x4){0.f, 0.f, 0.f, 0.f};
; #pragma unroll
;                 for (int j = 0; j < 4; ++j) Tcur[n][j] = dpp_rol1(acc[ai][0][0][n][j]); }
; #pragma unroll
;             for (int m = 0; m < 4; ++m) {
; #pragma unroll
;                 for (int n = 0; n < 2; ++n) {
; #pragma unroll
;                     for (int j = 0; j < 4; ++j) Scur[n][j] = dpp_ror1(acc[ai][0][m][n][j]);
;                     if (m < 3) {
; #pragma unroll
;                         for (int j = 0; j < 4; ++j) Tnext[n][j] = dpp_rol1(acc[ai][0][m < 3 ? m + 1 : 3][n][j]);
;                     } else Tnext[n] = (rb < 3) ? *(const LAS f32x4*)(XF + (rb + 1) * 128 + cl + 4 * n) : (f32x4){0.f, 0.f, 0.f, 0.f};
;                 }
;                 const int row = row0 + ai * HALF + m * 16, lrow = row & 255;
;                 const bool edge = (lrow == 0) || (lrow == 255);
;                 u32x4 ow;
; #pragma unroll
;                 for (int n = 0; n < 2; ++n) {
;                     const f32x4 up = (fr == 0) ? Sprev[n] : Scur[n], dn = (fr == 15) ? Tnext[n] : Tcur[n];
;                     const f32x4 a = w0[n] * up + w1[n] * acc[ai][0][m][n] + w2[n] * dn + bb[n];
;                     const f32x4 uu = acc[ai][1][m][n];
;                     ow[2 * n] = cvt_pk_bf16(gelu_tanh(a[0]) * uu[0], gelu_tanh(a[1]) * uu[1]);
;                     ow[2 * n + 1] = cvt_pk_bf16(gelu_tanh(a[2]) * uu[2], gelu_tanh(a[3]) * uu[3]);
;                 }
;                 if (!edge) *(u32x4*)(ACT + (size_t)row * DFF + f0) = ow;
;                 if (lrow < 2 || lrow > 253) { const int e = lrow < 2 ? lrow : lrow - 252; float* eg = EG + ((size_t)u.pm * 4 + e) * DFF + f0;
;                     *(f32x4*)eg = acc[ai][0][m][0]; *(f32x4*)(eg + 4) = acc[ai][0][m][1];
;                     if (edge) { float* eu = EU + ((size_t)u.pm * 2 + (lrow == 255 ? 1 : 0)) * DFF + f0; *(f32x4*)eu = acc[ai][1][m][0]; *(f32x4*)(eu + 4) = acc[ai][1][m][1]; } }
	v_mov_b32_dpp v142, v129 row_ror:15 row_mask:0xf bank_mask:0xf
	v_pk_mul_f32 v[150:151], v[84:85], v[150:151]
	v_cndmask_b32_e64 v149, v143, v155, s[2:3]
	v_cndmask_b32_e64 v148, v141, v154, s[2:3]
	v_cndmask_b32_e64 v155, v157, v142, s[4:5]
	v_cndmask_b32_e64 v154, v156, v140, s[4:5]
	v_pk_fma_f32 v[124:125], v[80:81], v[124:125], v[150:151]
	v_pk_mul_f32 v[148:149], v[86:87], v[148:149]
	v_pk_fma_f32 v[124:125], v[68:69], v[154:155], v[124:125]
	v_pk_fma_f32 v[118:119], v[82:83], v[118:119], v[148:149]
	v_pk_add_f32 v[124:125], v[76:77], v[124:125]
	v_readlane_b32 s14, v254, 15
	v_mul_f32_e32 v148, v124, v124
	v_fmamk_f32 v148, v148, 0xbdd2d3e7, v232
	v_mul_f32_e32 v149, v125, v125
	v_mul_f32_e32 v148, v124, v148
	v_fmamk_f32 v149, v149, 0xbdd2d3e7, v232
	v_exp_f32_e32 v148, v148
	v_mul_f32_e32 v149, v125, v149
	v_exp_f32_e32 v149, v149
	v_readlane_b32 s15, v254, 16
	v_or_b32_e32 v144, 16, v174
	v_add_f32_e32 v148, 1.0, v148
	v_mov_b64_e32 v[146:147], s[14:15]
	v_mad_i64_i32 v[126:127], s[14:15], v144, s75, v[146:147]
	v_rcp_f32_e32 v148, v148
	v_add_f32_e32 v149, 1.0, v149
	v_mov_b32_dpp v144, v130 row_ror:15 row_mask:0xf bank_mask:0xf
	v_mov_b32_dpp v145, v131 row_ror:15 row_mask:0xf bank_mask:0xf
	v_rcp_f32_e32 v149, v149
	v_cndmask_b32_e64 v153, v159, v145, s[4:5]
	v_cndmask_b32_e64 v152, v158, v144, s[4:5]
	v_pk_fma_f32 v[118:119], v[70:71], v[152:153], v[118:119]
	v_pk_mul_f32 v[108:109], v[108:109], v[206:207] op_sel_hi:[1,0]
	v_pk_add_f32 v[118:119], v[78:79], v[118:119]
	v_mul_f32_e32 v124, v124, v148
	v_mul_f32_e32 v108, v108, v124
	v_mul_f32_e32 v124, v125, v149
	v_mul_f32_e32 v125, v118, v118
	v_fmamk_f32 v125, v125, 0xbdd2d3e7, v232
	v_mul_f32_e32 v148, v119, v119
	v_mul_f32_e32 v125, v118, v125
	v_fmamk_f32 v148, v148, 0xbdd2d3e7, v232
	v_exp_f32_e32 v125, v125
	v_mul_f32_e32 v148, v119, v148
	v_exp_f32_e32 v148, v148
	v_mul_f32_e32 v109, v109, v124
	v_add_f32_e32 v124, 1.0, v125
	v_rcp_f32_e32 v124, v124
	v_add_f32_e32 v125, 1.0, v148
	v_mul_f32_e32 v112, v136, v112
	v_mul_f32_e32 v113, v137, v113
	v_rcp_f32_e32 v125, v125
	v_cvt_pk_bf16_f32 v123, v112, v113
	v_lshlrev_b64 v[112:113], 1, v[168:169]
	v_lshl_add_u64 v[126:127], v[126:127], 0, v[112:113]
	v_pk_mul_f32 v[110:111], v[110:111], v[206:207] op_sel_hi:[1,0]
	global_store_dwordx4 v[126:127], v[120:123], off
	v_cvt_pk_bf16_f32 v108, v108, v109
	v_mul_f32_e32 v109, v118, v124
	v_mul_f32_e32 v109, v110, v109
	v_mul_f32_e32 v110, v119, v125
	v_mov_b32_dpp v120, v116 row_ror:1 row_mask:0xf bank_mask:0xf
	v_mov_b32_dpp v121, v117 row_ror:1 row_mask:0xf bank_mask:0xf
	v_mov_b32_dpp v123, v114 row_ror:1 row_mask:0xf bank_mask:0xf
	v_mov_b32_dpp v127, v115 row_ror:1 row_mask:0xf bank_mask:0xf
	v_mul_f32_e32 v110, v111, v110
	v_cvt_pk_bf16_f32 v109, v109, v110
	v_cndmask_b32_e64 v111, v127, v163, s[2:3]
	v_cndmask_b32_e64 v110, v123, v162, s[2:3]
	v_cndmask_b32_e64 v119, v121, v161, s[2:3]
	v_cndmask_b32_e64 v118, v120, v160, s[2:3]
	v_mov_b32_dpp v122, v132 row_ror:15 row_mask:0xf bank_mask:0xf
	v_mov_b32_dpp v126, v133 row_ror:15 row_mask:0xf bank_mask:0xf
	v_pk_mul_f32 v[118:119], v[44:45], v[118:119]
	v_pk_mul_f32 v[110:111], v[46:47], v[110:111]
	v_cndmask_b32_e64 v149, v165, v126, s[4:5]
	v_cndmask_b32_e64 v148, v164, v122, s[4:5]
	v_pk_fma_f32 v[110:111], v[42:43], v[114:115], v[110:111]
	v_pk_fma_f32 v[114:115], v[40:41], v[116:117], v[118:119]
	v_pk_fma_f32 v[114:115], v[32:33], v[148:149], v[114:115]
	v_pk_add_f32 v[114:115], v[36:37], v[114:115]
	v_mov_b32_dpp v136, v134 row_ror:15 row_mask:0xf bank_mask:0xf
	v_mul_f32_e32 v116, v114, v114
	v_fmamk_f32 v116, v116, 0xbdd2d3e7, v232
	v_mul_f32_e32 v116, v114, v116
	v_mul_f32_e32 v117, v115, v115
	v_exp_f32_e32 v116, v116
	v_fmamk_f32 v117, v117, 0xbdd2d3e7, v232
	v_mul_f32_e32 v117, v115, v117
	v_exp_f32_e32 v117, v117
	v_mov_b32_dpp v137, v135 row_ror:15 row_mask:0xf bank_mask:0xf
	v_add_f32_e32 v116, 1.0, v116
	v_cndmask_b32_e64 v125, v167, v137, s[4:5]
	v_cndmask_b32_e64 v124, v166, v136, s[4:5]
	v_rcp_f32_e32 v118, v116
	v_pk_fma_f32 v[110:111], v[34:35], v[124:125], v[110:111]
	v_add_f32_e32 v116, 1.0, v117
	v_rcp_f32_e32 v119, v116
	v_pk_add_f32 v[116:117], v[38:39], v[110:111]
	v_mul_f32_e32 v110, v114, v118
	v_mul_f32_e32 v111, v116, v116
	v_fmamk_f32 v111, v111, 0xbdd2d3e7, v232
	v_mul_f32_e32 v114, v117, v117
	v_mul_f32_e32 v111, v116, v111
	v_fmamk_f32 v114, v114, 0xbdd2d3e7, v232
	v_exp_f32_e32 v111, v111
	v_mul_f32_e32 v114, v117, v114
	v_exp_f32_e32 v114, v114
	v_pk_mul_f32 v[104:105], v[104:105], v[206:207] op_sel_hi:[1,0]
	v_pk_mul_f32 v[106:107], v[106:107], v[206:207] op_sel_hi:[1,0]
	v_mul_f32_e32 v104, v104, v110
	v_mul_f32_e32 v110, v115, v119
	v_mul_f32_e32 v105, v105, v110
	v_add_f32_e32 v110, 1.0, v111
	v_rcp_f32_e32 v111, v110
	v_add_f32_e32 v110, 1.0, v114
	v_rcp_f32_e32 v114, v110
	v_cvt_pk_bf16_f32 v110, v104, v105
	v_mul_f32_e32 v104, v116, v111
	v_or_b32_e32 v170, 32, v174
	v_mul_f32_e32 v105, v117, v114
	v_mul_f32_e32 v104, v106, v104
	v_mul_f32_e32 v105, v107, v105
	v_cvt_pk_bf16_f32 v111, v104, v105
	v_mad_i64_i32 v[104:105], s[14:15], v170, s75, v[146:147]
	v_lshl_add_u64 v[104:105], v[104:105], 0, v[112:113]
	global_store_dwordx4 v[104:105], v[108:111], off
	v_cndmask_b32_e64 v105, 0, 1, s[36:37]
	v_mov_b32_dpp v119, v128 row_ror:1 row_mask:0xf bank_mask:0xf
	v_mov_b32_dpp v124, v129 row_ror:1 row_mask:0xf bank_mask:0xf
	v_mov_b32_dpp v125, v130 row_ror:1 row_mask:0xf bank_mask:0xf
	v_mov_b32_dpp v146, v131 row_ror:1 row_mask:0xf bank_mask:0xf
	v_mov_b32_e32 v104, 0
	v_cmp_ne_u32_e64 s[14:15], 1, v105
	s_andn2_b64 vcc, exec, s[36:37]
	v_mov_b32_e32 v108, 0
	v_mov_b32_e32 v109, 0
	v_mov_b32_e32 v110, 0
	v_mov_b32_e32 v111, 0
	s_cbranch_vccnz .LBB0_1121
	ds_read_b128 v[108:111], v225 offset:512

; __device__ __forceinline__ void store_pair_rows(bf16_t* O, size_t ldc, int row, int col0, int fr, u32x4 p0, u32x4 p1) {
;     const bool odd = (fr & 1) != 0;
;     const u32x4 snd = odd ? p0 : p1; u32x4 rcv;
;     rcv.x = dpp_xor1(snd.x); rcv.y = dpp_xor1(snd.y); rcv.z = dpp_xor1(snd.z); rcv.w = dpp_xor1(snd.w);
;     bf16_t* pa = O + (size_t)(row - (odd ? 1 : 0)) * ldc + col0 + (odd ? 8 : 0);
;     *(u32x4*)pa = odd ? rcv : p0;
;     *(u32x4*)(pa + ldc) = odd ? p1 : rcv;
; }
;     __device__ __forceinline__ void operator()(const f32x4 (&acc)[2][2][4][2], const Unit& u, int wr, int wc, int fr, int fq) const {
;     ...
;             const int row0 = u.pm * BM + wr * 64 + fr, col0 = u.pn * BM + wc * 64 + 16 * fq; const bool odd = (fr & 1) != 0;
; #pragma unroll
;             for (int ai = 0; ai < 2; ++ai)
; #pragma unroll
;                 for (int m = 0; m < 4; ++m) {
;                     const int row = row0 + ai * HALF + m * 16; float s = 0.f;
;                     const bf16_t* pa = baseb + (size_t)(row - (odd ? 1 : 0)) * DM + col0 + (odd ? 8 : 0);
;                     const u32x4 la = *(const u32x4*)pa, lb = *(const u32x4*)(pa + DM);
;                     const u32x4 snd = odd ? la : lb; u32x4 rcv;
;                     rcv.x = dpp_xor1(snd.x); rcv.y = dpp_xor1(snd.y); rcv.z = dpp_xor1(snd.z); rcv.w = dpp_xor1(snd.w);
;                     const u32x4 bw0 = odd ? rcv : la, bw1 = odd ? lb : rcv;
;                     u32x4 pw[2];
; #pragma unroll
;                     for (int bj = 0; bj < 2; ++bj) { const u32x4 bw = bj ? bw1 : bw0;
;                         const f32x4 b0 = (f32x4){bf_lo(bw.x), bf_hi(bw.x), bf_lo(bw.y), bf_hi(bw.y)}, b1 = (f32x4){bf_lo(bw.z), bf_hi(bw.z), bf_lo(bw.w), bf_hi(bw.w)};
;                         const f32x4 v0 = acc[ai][bj][m][0] + b0, v1 = acc[ai][bj][m][1] + b1;
;                         pw[bj].x = cvt_pk_bf16(v0[0], v0[1]); pw[bj].y = cvt_pk_bf16(v0[2], v0[3]); pw[bj].z = cvt_pk_bf16(v1[0], v1[1]); pw[bj].w = cvt_pk_bf16(v1[2], v1[3]);
;                         s += (v0[0] * v0[0] + v0[1] * v0[1]) + (v0[2] * v0[2] + v0[3] * v0[3]) + (v1[0] * v1[0] + v1[1] * v1[1]) + (v1[2] * v1[2] + v1[3] * v1[3]); }
;                     store_pair_rows(HB, (size_t)DM, row, col0, fr, pw[0], pw[1]);
;                     s += __shfl_xor(s, 16); s += __shfl_xor(s, 32);
;                     if (fq == 0) unsafeAtomicAdd(ssn + row, s);
.LBB0_1253:
	v_lshl_add_u32 v152, s42, 8, v156
	v_sub_u32_e32 v154, v152, v158
	v_ashrrev_i32_e32 v155, 31, v154
	v_readlane_b32 s22, v254, 25
	v_lshl_or_b32 v150, s43, 8, v159
	v_lshlrev_b64 v[154:155], 12, v[154:155]
	v_readlane_b32 s23, v254, 26
	v_ashrrev_i32_e32 v151, 31, v150
	s_nop 0
	v_lshl_add_u64 v[154:155], s[22:23], 0, v[154:155]
	v_lshl_add_u64 v[154:155], v[150:151], 1, v[154:155]
	v_lshl_add_u64 v[172:173], v[154:155], 0, v[140:141]
	v_add_co_u32_e32 v154, vcc, 0x1000, v172
	s_nop 0
	s_nop 0
	v_addc_co_u32_e32 v155, vcc, 0, v173, vcc
	global_load_dwordx4 v[164:167], v[172:173], off
	global_load_dwordx4 v[168:171], v[154:155], off
	s_waitcnt vmcnt(0)
	v_cndmask_b32_e64 v177, v167, v171, s[0:1]
	v_cndmask_b32_e64 v179, v165, v169, s[0:1]
	v_cndmask_b32_e64 v180, v164, v168, s[0:1]
	v_cndmask_b32_e64 v178, v166, v170, s[0:1]
	v_mov_b32_dpp v174, v179 quad_perm:[1,0,3,2] row_mask:0xf bank_mask:0xf
	v_mov_b32_dpp v153, v180 quad_perm:[1,0,3,2] row_mask:0xf bank_mask:0xf
	v_mov_b32_dpp v176, v177 quad_perm:[1,0,3,2] row_mask:0xf bank_mask:0xf
	v_mov_b32_dpp v175, v178 quad_perm:[1,0,3,2] row_mask:0xf bank_mask:0xf
	v_cndmask_b32_e64 v177, v176, v167, s[0:1]
	v_cndmask_b32_e64 v167, v174, v165, s[0:1]
	v_cndmask_b32_e64 v165, v153, v164, s[0:1]
	v_cndmask_b32_e64 v180, v169, v174, s[0:1]
	v_cndmask_b32_e64 v153, v168, v153, s[0:1]
	v_cndmask_b32_e64 v178, v175, v166, s[0:1]
	v_cndmask_b32_e64 v181, v171, v176, s[0:1]
	v_cndmask_b32_e64 v179, v170, v175, s[0:1]
	v_lshlrev_b32_e32 v164, 16, v165
	v_and_b32_e32 v165, 0xffff0000, v165
	v_lshlrev_b32_e32 v166, 16, v167
	v_and_b32_e32 v167, 0xffff0000, v167
	v_lshlrev_b32_e32 v170, 16, v177
	v_and_b32_e32 v171, 0xffff0000, v177
	v_lshlrev_b32_e32 v174, 16, v153
	v_and_b32_e32 v175, 0xffff0000, v153
	v_lshlrev_b32_e32 v176, 16, v180
	v_and_b32_e32 v177, 0xffff0000, v180
	v_lshlrev_b32_e32 v168, 16, v178
	v_and_b32_e32 v169, 0xffff0000, v178
	v_lshlrev_b32_e32 v178, 16, v179
	v_and_b32_e32 v179, 0xffff0000, v179
	v_lshlrev_b32_e32 v180, 16, v181
	v_and_b32_e32 v181, 0xffff0000, v181
	v_pk_add_f32 v[126:127], v[126:127], v[166:167]
	v_pk_add_f32 v[124:125], v[124:125], v[164:165]
	v_pk_add_f32 v[118:119], v[118:119], v[176:177]
	v_pk_add_f32 v[116:117], v[116:117], v[174:175]
	v_pk_add_f32 v[122:123], v[122:123], v[170:171]
	v_pk_add_f32 v[120:121], v[120:121], v[168:169]
	v_pk_add_f32 v[114:115], v[114:115], v[180:181]
	v_pk_add_f32 v[112:113], v[112:113], v[178:179]
	v_cvt_pk_bf16_f32 v153, v124, v125
	v_cvt_pk_bf16_f32 v164, v126, v127
	v_cvt_pk_bf16_f32 v165, v120, v121
	v_cvt_pk_bf16_f32 v166, v122, v123
	v_mul_f32_e32 v125, v125, v125
	v_mul_f32_e32 v127, v127, v127
	v_cvt_pk_bf16_f32 v167, v116, v117
	v_cvt_pk_bf16_f32 v168, v118, v119
	v_mul_f32_e32 v117, v117, v117
	v_mul_f32_e32 v119, v119, v119
	v_mul_f32_e32 v121, v121, v121
	v_cvt_pk_bf16_f32 v169, v112, v113
	v_cvt_pk_bf16_f32 v170, v114, v115
	v_mul_f32_e32 v113, v113, v113
	v_mul_f32_e32 v115, v115, v115
	v_fmac_f32_e32 v125, v124, v124
	v_fmac_f32_e32 v127, v126, v126
	v_fmac_f32_e32 v117, v116, v116
	v_fmac_f32_e32 v119, v118, v118
	v_fmac_f32_e32 v121, v120, v120
	v_fmac_f32_e32 v113, v112, v112
	v_fmac_f32_e32 v115, v114, v114
	v_cndmask_b32_e64 v114, v165, v169, s[0:1]
	v_cndmask_b32_e64 v116, v164, v168, s[0:1]
	v_add_f32_e32 v120, v125, v127
	v_add_f32_e32 v117, v117, v119
	v_cndmask_b32_e64 v112, v166, v170, s[0:1]
	v_mov_b32_dpp v183, v116 quad_perm:[1,0,3,2] row_mask:0xf bank_mask:0xf
	v_add_f32_e32 v116, v121, v120
	v_add_f32_e32 v113, v113, v117
	v_mov_b32_dpp v184, v114 quad_perm:[1,0,3,2] row_mask:0xf bank_mask:0xf
	v_and_b32_e32 v114, 64, v163
	v_mul_f32_e32 v123, v123, v123
	v_add_f32_e32 v113, v115, v113
	v_mov_b32_dpp v120, v112 quad_perm:[1,0,3,2] row_mask:0xf bank_mask:0xf
	v_xor_b32_e32 v112, 16, v163
	v_add_u32_e32 v115, 64, v114
	v_fmac_f32_e32 v123, v122, v122
	v_cmp_lt_i32_e32 vcc, v112, v115
	v_add_f32_e32 v116, v123, v116
	v_add_f32_e32 v113, v116, v113
	v_cndmask_b32_e32 v112, v163, v112, vcc
	v_lshlrev_b32_e32 v114, 2, v112
	ds_bpermute_b32 v112, v114, v113
	v_cndmask_b32_e64 v118, v153, v167, s[0:1]
	v_cndmask_b32_e64 v117, v183, v164, s[0:1]
	v_cndmask_b32_e64 v119, v120, v166, s[0:1]
	v_mov_b32_dpp v182, v118 quad_perm:[1,0,3,2] row_mask:0xf bank_mask:0xf
	s_waitcnt lgkmcnt(0)
	v_add_f32_e32 v112, v113, v112
	v_xor_b32_e32 v113, 32, v163
	v_cmp_lt_i32_e32 vcc, v113, v115
	v_cndmask_b32_e64 v116, v182, v153, s[0:1]
	v_cndmask_b32_e64 v118, v184, v165, s[0:1]
	v_cndmask_b32_e32 v113, v163, v113, vcc
	v_lshlrev_b32_e32 v115, 2, v113
	ds_bpermute_b32 v113, v115, v112
	global_store_dwordx4 v[172:173], v[116:119], off
	s_nop 1
	v_cndmask_b32_e64 v116, v167, v182, s[0:1]
	v_cndmask_b32_e64 v117, v168, v183, s[0:1]
	v_cndmask_b32_e64 v118, v169, v184, s[0:1]
	v_cndmask_b32_e64 v119, v170, v120, s[0:1]
	global_store_dwordx4 v[154:155], v[116:119], off
	s_and_saveexec_b64 s[22:23], s[2:3]
	s_cbranch_execz .LBB0_1255
	v_ashrrev_i32_e32 v153, 31, v152
	v_lshl_add_u64 v[116:117], v[152:153], 2, s[12:13]
	s_waitcnt lgkmcnt(0)
	v_add_f32_e32 v112, v112, v113
	global_atomic_add_f32 v[116:117], v112, off
; __device__ __forceinline__ void store_pair_rows(bf16_t* O, size_t ldc, int row, int col0, int fr, u32x4 p0, u32x4 p1) {
;     const bool odd = (fr & 1) != 0;
;     const u32x4 snd = odd ? p0 : p1; u32x4 rcv;
;     rcv.x = dpp_xor1(snd.x); rcv.y = dpp_xor1(snd.y); rcv.z = dpp_xor1(snd.z); rcv.w = dpp_xor1(snd.w);
;     bf16_t* pa = O + (size_t)(row - (odd ? 1 : 0)) * ldc + col0 + (odd ? 8 : 0);
;     *(u32x4*)pa = odd ? rcv : p0;
;     *(u32x4*)(pa + ldc) = odd ? p1 : rcv;
; }
;     __device__ __forceinline__ void operator()(const f32x4 (&acc)[2][2][4][2], const Unit& u, int wr, int wc, int fr, int fq) const {
;     ...
;             const int row0 = u.pm * BM + wr * 64 + fr, col0 = u.pn * BM + wc * 64 + 16 * fq; const bool odd = (fr & 1) != 0;
; #pragma unroll
;             for (int ai = 0; ai < 2; ++ai)
; #pragma unroll
;                 for (int m = 0; m < 4; ++m) {
;                     const int row = row0 + ai * HALF + m * 16; float s = 0.f;
;                     const bf16_t* pa = baseb + (size_t)(row - (odd ? 1 : 0)) * DM + col0 + (odd ? 8 : 0);
;                     const u32x4 la = *(const u32x4*)pa, lb = *(const u32x4*)(pa + DM);
;                     const u32x4 snd = odd ? la : lb; u32x4 rcv;
;                     rcv.x = dpp_xor1(snd.x); rcv.y = dpp_xor1(snd.y); rcv.z = dpp_xor1(snd.z); rcv.w = dpp_xor1(snd.w);
;                     const u32x4 bw0 = odd ? rcv : la, bw1 = odd ? lb : rcv;
;                     u32x4 pw[2];
; #pragma unroll
;                     for (int bj = 0; bj < 2; ++bj) { const u32x4 bw = bj ? bw1 : bw0;
;                         const f32x4 b0 = (f32x4){bf_lo(bw.x), bf_hi(bw.x), bf_lo(bw.y), bf_hi(bw.y)}, b1 = (f32x4){bf_lo(bw.z), bf_hi(bw.z), bf_lo(bw.w), bf_hi(bw.w)};
;                         const f32x4 v0 = acc[ai][bj][m][0] + b0, v1 = acc[ai][bj][m][1] + b1;
;                         pw[bj].x = cvt_pk_bf16(v0[0], v0[1]); pw[bj].y = cvt_pk_bf16(v0[2], v0[3]); pw[bj].z = cvt_pk_bf16(v1[0], v1[1]); pw[bj].w = cvt_pk_bf16(v1[2], v1[3]);
;                         s += (v0[0] * v0[0] + v0[1] * v0[1]) + (v0[2] * v0[2] + v0[3] * v0[3]) + (v1[0] * v1[0] + v1[1] * v1[1]) + (v1[2] * v1[2] + v1[3] * v1[3]); }
;                     store_pair_rows(HB, (size_t)DM, row, col0, fr, pw[0], pw[1]);
;                     s += __shfl_xor(s, 16); s += __shfl_xor(s, 32);
;                     if (fq == 0) unsafeAtomicAdd(ssn + row, s);
.LBB0_1255:
	s_or_b64 exec, exec, s[22:23]
	v_or_b32_e32 v112, 16, v152
	v_sub_u32_e32 v116, v112, v158
	v_ashrrev_i32_e32 v117, 31, v116
	v_readlane_b32 s22, v254, 25
	v_lshlrev_b64 v[116:117], 12, v[116:117]
	v_readlane_b32 s23, v254, 26
	s_waitcnt lgkmcnt(0)
	s_nop 0
	v_lshl_add_u64 v[116:117], s[22:23], 0, v[116:117]
	v_lshl_add_u64 v[116:117], v[150:151], 1, v[116:117]
	v_lshl_add_u64 v[124:125], v[116:117], 0, v[140:141]
	v_add_co_u32_e32 v126, vcc, 0x1000, v124
	s_nop 0
	s_nop 0
	v_addc_co_u32_e32 v127, vcc, 0, v125, vcc
	global_load_dwordx4 v[116:119], v[124:125], off
	global_load_dwordx4 v[120:123], v[126:127], off
	s_waitcnt vmcnt(0)
	v_cndmask_b32_e64 v164, v119, v123, s[0:1]
	v_cndmask_b32_e64 v165, v118, v122, s[0:1]
	v_cndmask_b32_e64 v166, v117, v121, s[0:1]
	v_cndmask_b32_e64 v167, v116, v120, s[0:1]
	v_mov_b32_dpp v154, v165 quad_perm:[1,0,3,2] row_mask:0xf bank_mask:0xf
	v_mov_b32_dpp v153, v166 quad_perm:[1,0,3,2] row_mask:0xf bank_mask:0xf
	v_mov_b32_dpp v113, v167 quad_perm:[1,0,3,2] row_mask:0xf bank_mask:0xf
	v_mov_b32_dpp v155, v164 quad_perm:[1,0,3,2] row_mask:0xf bank_mask:0xf
	v_cndmask_b32_e64 v164, v155, v119, s[0:1]
	v_cndmask_b32_e64 v165, v154, v118, s[0:1]
	v_cndmask_b32_e64 v119, v153, v117, s[0:1]
	v_cndmask_b32_e64 v117, v113, v116, s[0:1]
	v_cndmask_b32_e64 v153, v121, v153, s[0:1]
	v_cndmask_b32_e64 v113, v120, v113, s[0:1]
	v_cndmask_b32_e64 v169, v123, v155, s[0:1]
	v_cndmask_b32_e64 v167, v122, v154, s[0:1]
	v_lshlrev_b32_e32 v116, 16, v117
	v_and_b32_e32 v117, 0xffff0000, v117
	v_lshlrev_b32_e32 v118, 16, v119
	v_and_b32_e32 v119, 0xffff0000, v119
	v_lshlrev_b32_e32 v120, 16, v165
	v_and_b32_e32 v121, 0xffff0000, v165
	v_lshlrev_b32_e32 v122, 16, v164
	v_and_b32_e32 v123, 0xffff0000, v164
	v_lshlrev_b32_e32 v154, 16, v113
	v_and_b32_e32 v155, 0xffff0000, v113
	v_lshlrev_b32_e32 v164, 16, v153
	v_and_b32_e32 v165, 0xffff0000, v153
	v_lshlrev_b32_e32 v166, 16, v167
	v_and_b32_e32 v167, 0xffff0000, v167
	v_lshlrev_b32_e32 v168, 16, v169
	v_and_b32_e32 v169, 0xffff0000, v169
	v_pk_add_f32 v[110:111], v[110:111], v[118:119]
	v_pk_add_f32 v[108:109], v[108:109], v[116:117]
	v_pk_add_f32 v[102:103], v[102:103], v[164:165]
	v_pk_add_f32 v[100:101], v[100:101], v[154:155]
	v_pk_add_f32 v[106:107], v[106:107], v[122:123]
	v_pk_add_f32 v[104:105], v[104:105], v[120:121]
	v_pk_add_f32 v[98:99], v[98:99], v[168:169]
	v_pk_add_f32 v[96:97], v[96:97], v[166:167]
	v_cvt_pk_bf16_f32 v113, v108, v109
	v_cvt_pk_bf16_f32 v116, v110, v111
	v_cvt_pk_bf16_f32 v117, v104, v105
	v_cvt_pk_bf16_f32 v118, v106, v107
	v_mul_f32_e32 v109, v109, v109
	v_mul_f32_e32 v111, v111, v111
	v_cvt_pk_bf16_f32 v119, v100, v101
	v_cvt_pk_bf16_f32 v120, v102, v103
	v_mul_f32_e32 v101, v101, v101
	v_mul_f32_e32 v103, v103, v103
	v_mul_f32_e32 v105, v105, v105
	v_cvt_pk_bf16_f32 v121, v96, v97
	v_cvt_pk_bf16_f32 v122, v98, v99
	v_mul_f32_e32 v97, v97, v97
	v_mul_f32_e32 v99, v99, v99
	v_fmac_f32_e32 v109, v108, v108
	v_fmac_f32_e32 v111, v110, v110
	v_fmac_f32_e32 v101, v100, v100
	v_fmac_f32_e32 v103, v102, v102
	v_mul_f32_e32 v107, v107, v107
	v_fmac_f32_e32 v105, v104, v104
	v_fmac_f32_e32 v97, v96, v96
	v_fmac_f32_e32 v99, v98, v98
	v_cndmask_b32_e64 v98, v117, v121, s[0:1]
	v_add_f32_e32 v104, v109, v111
	v_add_f32_e32 v101, v101, v103
	v_fmac_f32_e32 v107, v106, v106
	v_mov_b32_dpp v172, v98 quad_perm:[1,0,3,2] row_mask:0xf bank_mask:0xf
	v_add_f32_e32 v98, v105, v104
	v_add_f32_e32 v97, v97, v101
	v_cndmask_b32_e64 v100, v116, v120, s[0:1]
	v_add_f32_e32 v98, v107, v98
	v_add_f32_e32 v97, v99, v97
	v_mov_b32_dpp v171, v100 quad_perm:[1,0,3,2] row_mask:0xf bank_mask:0xf
	v_add_f32_e32 v100, v98, v97
	ds_bpermute_b32 v101, v114, v100
	v_cndmask_b32_e64 v96, v118, v122, s[0:1]
	v_cndmask_b32_e64 v102, v113, v119, s[0:1]
	v_cndmask_b32_e64 v97, v171, v116, s[0:1]
	v_mov_b32_dpp v173, v96 quad_perm:[1,0,3,2] row_mask:0xf bank_mask:0xf
	v_mov_b32_dpp v170, v102 quad_perm:[1,0,3,2] row_mask:0xf bank_mask:0xf
	v_cndmask_b32_e64 v96, v170, v113, s[0:1]
	v_cndmask_b32_e64 v98, v172, v117, s[0:1]
	v_cndmask_b32_e64 v99, v173, v118, s[0:1]
	global_store_dwordx4 v[124:125], v[96:99], off
	s_waitcnt lgkmcnt(0)
	s_nop 0
	v_add_f32_e32 v96, v100, v101
	ds_bpermute_b32 v97, v115, v96
	v_cndmask_b32_e64 v98, v119, v170, s[0:1]
	v_cndmask_b32_e64 v99, v120, v171, s[0:1]
	v_cndmask_b32_e64 v100, v121, v172, s[0:1]
	v_cndmask_b32_e64 v101, v122, v173, s[0:1]
	global_store_dwordx4 v[126:127], v[98:101], off
	s_and_saveexec_b64 s[22:23], s[2:3]
	s_cbranch_execz .LBB0_1257
	v_ashrrev_i32_e32 v113, 31, v112
	v_lshl_add_u64 v[98:99], v[112:113], 2, s[12:13]
	s_waitcnt lgkmcnt(0)
	v_add_f32_e32 v96, v96, v97
	global_atomic_add_f32 v[98:99], v96, off
; __device__ __forceinline__ void store_pair_rows(bf16_t* O, size_t ldc, int row, int col0, int fr, u32x4 p0, u32x4 p1) {
;     const bool odd = (fr & 1) != 0;
;     const u32x4 snd = odd ? p0 : p1; u32x4 rcv;
;     rcv.x = dpp_xor1(snd.x); rcv.y = dpp_xor1(snd.y); rcv.z = dpp_xor1(snd.z); rcv.w = dpp_xor1(snd.w);
;     bf16_t* pa = O + (size_t)(row - (odd ? 1 : 0)) * ldc + col0 + (odd ? 8 : 0);
;     *(u32x4*)pa = odd ? rcv : p0;
;     *(u32x4*)(pa + ldc) = odd ? p1 : rcv;
; }
;     __device__ __forceinline__ void operator()(const f32x4 (&acc)[2][2][4][2], const Unit& u, int wr, int wc, int fr, int fq) const {
;     ...
;             const int row0 = u.pm * BM + wr * 64 + fr, col0 = u.pn * BM + wc * 64 + 16 * fq; const bool odd = (fr & 1) != 0;
; #pragma unroll
;             for (int ai = 0; ai < 2; ++ai)
; #pragma unroll
;                 for (int m = 0; m < 4; ++m) {
;                     const int row = row0 + ai * HALF + m * 16; float s = 0.f;
;                     const bf16_t* pa = baseb + (size_t)(row - (odd ? 1 : 0)) * DM + col0 + (odd ? 8 : 0);
;                     const u32x4 la = *(const u32x4*)pa, lb = *(const u32x4*)(pa + DM);
;                     const u32x4 snd = odd ? la : lb; u32x4 rcv;
;                     rcv.x = dpp_xor1(snd.x); rcv.y = dpp_xor1(snd.y); rcv.z = dpp_xor1(snd.z); rcv.w = dpp_xor1(snd.w);
;                     const u32x4 bw0 = odd ? rcv : la, bw1 = odd ? lb : rcv;
;                     u32x4 pw[2];
; #pragma unroll
;                     for (int bj = 0; bj < 2; ++bj) { const u32x4 bw = bj ? bw1 : bw0;
;                         const f32x4 b0 = (f32x4){bf_lo(bw.x), bf_hi(bw.x), bf_lo(bw.y), bf_hi(bw.y)}, b1 = (f32x4){bf_lo(bw.z), bf_hi(bw.z), bf_lo(bw.w), bf_hi(bw.w)};
;                         const f32x4 v0 = acc[ai][bj][m][0] + b0, v1 = acc[ai][bj][m][1] + b1;
;                         pw[bj].x = cvt_pk_bf16(v0[0], v0[1]); pw[bj].y = cvt_pk_bf16(v0[2], v0[3]); pw[bj].z = cvt_pk_bf16(v1[0], v1[1]); pw[bj].w = cvt_pk_bf16(v1[2], v1[3]);
;                         s += (v0[0] * v0[0] + v0[1] * v0[1]) + (v0[2] * v0[2] + v0[3] * v0[3]) + (v1[0] * v1[0] + v1[1] * v1[1]) + (v1[2] * v1[2] + v1[3] * v1[3]); }
;                     store_pair_rows(HB, (size_t)DM, row, col0, fr, pw[0], pw[1]);
;                     s += __shfl_xor(s, 16); s += __shfl_xor(s, 32);
;                     if (fq == 0) unsafeAtomicAdd(ssn + row, s);
.LBB0_1257:
	s_or_b64 exec, exec, s[22:23]
	v_or_b32_e32 v96, 32, v152
	v_sub_u32_e32 v98, v96, v158
	v_ashrrev_i32_e32 v99, 31, v98
	v_readlane_b32 s22, v254, 25
	v_lshlrev_b64 v[98:99], 12, v[98:99]
	v_readlane_b32 s23, v254, 26
	s_waitcnt lgkmcnt(0)
	s_nop 0
	v_lshl_add_u64 v[98:99], s[22:23], 0, v[98:99]
	v_lshl_add_u64 v[98:99], v[150:151], 1, v[98:99]
	v_lshl_add_u64 v[106:107], v[98:99], 0, v[140:141]
	v_add_co_u32_e32 v108, vcc, 0x1000, v106
	s_nop 0
	s_nop 0
	v_addc_co_u32_e32 v109, vcc, 0, v107, vcc
	global_load_dwordx4 v[98:101], v[106:107], off
	global_load_dwordx4 v[102:105], v[108:109], off
	s_waitcnt vmcnt(0)
	v_cndmask_b32_e64 v113, v101, v105, s[0:1]
	v_cndmask_b32_e64 v117, v99, v103, s[0:1]
	v_cndmask_b32_e64 v118, v98, v102, s[0:1]
	v_cndmask_b32_e64 v116, v100, v104, s[0:1]
	v_mov_b32_dpp v110, v117 quad_perm:[1,0,3,2] row_mask:0xf bank_mask:0xf
	v_mov_b32_dpp v97, v118 quad_perm:[1,0,3,2] row_mask:0xf bank_mask:0xf
	v_mov_b32_dpp v112, v113 quad_perm:[1,0,3,2] row_mask:0xf bank_mask:0xf
	v_mov_b32_dpp v111, v116 quad_perm:[1,0,3,2] row_mask:0xf bank_mask:0xf
	v_cndmask_b32_e64 v113, v112, v101, s[0:1]
	v_cndmask_b32_e64 v101, v110, v99, s[0:1]
	v_cndmask_b32_e64 v99, v97, v98, s[0:1]
	v_cndmask_b32_e64 v118, v103, v110, s[0:1]
	v_cndmask_b32_e64 v97, v102, v97, s[0:1]
	v_cndmask_b32_e64 v116, v111, v100, s[0:1]
	v_cndmask_b32_e64 v119, v105, v112, s[0:1]
	v_cndmask_b32_e64 v117, v104, v111, s[0:1]
	v_lshlrev_b32_e32 v98, 16, v99
	v_and_b32_e32 v99, 0xffff0000, v99
	v_lshlrev_b32_e32 v100, 16, v101
	v_and_b32_e32 v101, 0xffff0000, v101
	v_lshlrev_b32_e32 v104, 16, v113
	v_and_b32_e32 v105, 0xffff0000, v113
	v_lshlrev_b32_e32 v110, 16, v97
	v_and_b32_e32 v111, 0xffff0000, v97
	v_lshlrev_b32_e32 v112, 16, v118
	v_and_b32_e32 v113, 0xffff0000, v118
	v_lshlrev_b32_e32 v102, 16, v116
	v_and_b32_e32 v103, 0xffff0000, v116
	v_lshlrev_b32_e32 v116, 16, v117
	v_and_b32_e32 v117, 0xffff0000, v117
	v_lshlrev_b32_e32 v118, 16, v119
	v_and_b32_e32 v119, 0xffff0000, v119
	v_pk_add_f32 v[94:95], v[94:95], v[100:101]
	v_pk_add_f32 v[92:93], v[92:93], v[98:99]
	v_pk_add_f32 v[86:87], v[86:87], v[112:113]
	v_pk_add_f32 v[84:85], v[84:85], v[110:111]
	v_pk_add_f32 v[90:91], v[90:91], v[104:105]
	v_pk_add_f32 v[88:89], v[88:89], v[102:103]
	v_pk_add_f32 v[82:83], v[82:83], v[118:119]
	v_pk_add_f32 v[80:81], v[80:81], v[116:117]
	v_cvt_pk_bf16_f32 v97, v92, v93
	v_cvt_pk_bf16_f32 v98, v94, v95
	v_cvt_pk_bf16_f32 v99, v88, v89
	v_cvt_pk_bf16_f32 v100, v90, v91
	v_mul_f32_e32 v93, v93, v93
	v_mul_f32_e32 v95, v95, v95
	v_cvt_pk_bf16_f32 v101, v84, v85
	v_cvt_pk_bf16_f32 v102, v86, v87
	v_mul_f32_e32 v85, v85, v85
	v_mul_f32_e32 v87, v87, v87
	v_mul_f32_e32 v89, v89, v89
	v_cvt_pk_bf16_f32 v103, v80, v81
	v_cvt_pk_bf16_f32 v104, v82, v83
	v_mul_f32_e32 v81, v81, v81
	v_mul_f32_e32 v83, v83, v83
	v_fmac_f32_e32 v93, v92, v92
	v_fmac_f32_e32 v95, v94, v94
	v_fmac_f32_e32 v85, v84, v84
	v_fmac_f32_e32 v87, v86, v86
	v_mul_f32_e32 v91, v91, v91
	v_fmac_f32_e32 v89, v88, v88
	v_fmac_f32_e32 v81, v80, v80
	v_fmac_f32_e32 v83, v82, v82
	v_cndmask_b32_e64 v82, v99, v103, s[0:1]
	v_add_f32_e32 v88, v93, v95
	v_add_f32_e32 v85, v85, v87
	v_fmac_f32_e32 v91, v90, v90
	v_mov_b32_dpp v122, v82 quad_perm:[1,0,3,2] row_mask:0xf bank_mask:0xf
	v_add_f32_e32 v82, v89, v88
	v_add_f32_e32 v81, v81, v85
	v_cndmask_b32_e64 v84, v98, v102, s[0:1]
	v_add_f32_e32 v82, v91, v82
	v_add_f32_e32 v81, v83, v81
	v_mov_b32_dpp v121, v84 quad_perm:[1,0,3,2] row_mask:0xf bank_mask:0xf
	v_add_f32_e32 v84, v82, v81
	ds_bpermute_b32 v85, v114, v84
	v_cndmask_b32_e64 v80, v100, v104, s[0:1]
	v_cndmask_b32_e64 v86, v97, v101, s[0:1]
	v_cndmask_b32_e64 v81, v121, v98, s[0:1]
	v_mov_b32_dpp v123, v80 quad_perm:[1,0,3,2] row_mask:0xf bank_mask:0xf
	v_mov_b32_dpp v120, v86 quad_perm:[1,0,3,2] row_mask:0xf bank_mask:0xf
	v_cndmask_b32_e64 v80, v120, v97, s[0:1]
	v_cndmask_b32_e64 v82, v122, v99, s[0:1]
	v_cndmask_b32_e64 v83, v123, v100, s[0:1]
	global_store_dwordx4 v[106:107], v[80:83], off
	s_waitcnt lgkmcnt(0)
	s_nop 0
	v_add_f32_e32 v80, v84, v85
	ds_bpermute_b32 v81, v115, v80
	v_cndmask_b32_e64 v82, v101, v120, s[0:1]
	v_cndmask_b32_e64 v83, v102, v121, s[0:1]
	v_cndmask_b32_e64 v84, v103, v122, s[0:1]
	v_cndmask_b32_e64 v85, v104, v123, s[0:1]
	global_store_dwordx4 v[108:109], v[82:85], off
	s_and_saveexec_b64 s[22:23], s[2:3]
	s_cbranch_execz .LBB0_1259
	v_ashrrev_i32_e32 v97, 31, v96
	v_lshl_add_u64 v[82:83], v[96:97], 2, s[12:13]
	s_waitcnt lgkmcnt(0)
	v_add_f32_e32 v80, v80, v81
	global_atomic_add_f32 v[82:83], v80, off
; __device__ __forceinline__ void store_pair_rows(bf16_t* O, size_t ldc, int row, int col0, int fr, u32x4 p0, u32x4 p1) {
;     const bool odd = (fr & 1) != 0;
;     const u32x4 snd = odd ? p0 : p1; u32x4 rcv;
;     rcv.x = dpp_xor1(snd.x); rcv.y = dpp_xor1(snd.y); rcv.z = dpp_xor1(snd.z); rcv.w = dpp_xor1(snd.w);
;     bf16_t* pa = O + (size_t)(row - (odd ? 1 : 0)) * ldc + col0 + (odd ? 8 : 0);
;     *(u32x4*)pa = odd ? rcv : p0;
;     *(u32x4*)(pa + ldc) = odd ? p1 : rcv;
; }
;     __device__ __forceinline__ void operator()(const f32x4 (&acc)[2][2][4][2], const Unit& u, int wr, int wc, int fr, int fq) const {
;     ...
;             const int row0 = u.pm * BM + wr * 64 + fr, col0 = u.pn * BM + wc * 64 + 16 * fq; const bool odd = (fr & 1) != 0;
; #pragma unroll
;             for (int ai = 0; ai < 2; ++ai)
; #pragma unroll
;                 for (int m = 0; m < 4; ++m) {
;                     const int row = row0 + ai * HALF + m * 16; float s = 0.f;
;                     const bf16_t* pa = baseb + (size_t)(row - (odd ? 1 : 0)) * DM + col0 + (odd ? 8 : 0);
;                     const u32x4 la = *(const u32x4*)pa, lb = *(const u32x4*)(pa + DM);
;                     const u32x4 snd = odd ? la : lb; u32x4 rcv;
;                     rcv.x = dpp_xor1(snd.x); rcv.y = dpp_xor1(snd.y); rcv.z = dpp_xor1(snd.z); rcv.w = dpp_xor1(snd.w);
;                     const u32x4 bw0 = odd ? rcv : la, bw1 = odd ? lb : rcv;
;                     u32x4 pw[2];
; #pragma unroll
;                     for (int bj = 0; bj < 2; ++bj) { const u32x4 bw = bj ? bw1 : bw0;
;                         const f32x4 b0 = (f32x4){bf_lo(bw.x), bf_hi(bw.x), bf_lo(bw.y), bf_hi(bw.y)}, b1 = (f32x4){bf_lo(bw.z), bf_hi(bw.z), bf_lo(bw.w), bf_hi(bw.w)};
;                         const f32x4 v0 = acc[ai][bj][m][0] + b0, v1 = acc[ai][bj][m][1] + b1;
;                         pw[bj].x = cvt_pk_bf16(v0[0], v0[1]); pw[bj].y = cvt_pk_bf16(v0[2], v0[3]); pw[bj].z = cvt_pk_bf16(v1[0], v1[1]); pw[bj].w = cvt_pk_bf16(v1[2], v1[3]);
;                         s += (v0[0] * v0[0] + v0[1] * v0[1]) + (v0[2] * v0[2] + v0[3] * v0[3]) + (v1[0] * v1[0] + v1[1] * v1[1]) + (v1[2] * v1[2] + v1[3] * v1[3]); }
;                     store_pair_rows(HB, (size_t)DM, row, col0, fr, pw[0], pw[1]);
;                     s += __shfl_xor(s, 16); s += __shfl_xor(s, 32);
;                     if (fq == 0) unsafeAtomicAdd(ssn + row, s);
.LBB0_1259:
	s_or_b64 exec, exec, s[22:23]
	v_or_b32_e32 v80, 48, v152
	v_sub_u32_e32 v82, v80, v158
	v_ashrrev_i32_e32 v83, 31, v82
	v_readlane_b32 s22, v254, 25
	v_lshlrev_b64 v[82:83], 12, v[82:83]
	v_readlane_b32 s23, v254, 26
	s_waitcnt lgkmcnt(0)
	s_nop 0
	v_lshl_add_u64 v[82:83], s[22:23], 0, v[82:83]
	v_lshl_add_u64 v[82:83], v[150:151], 1, v[82:83]
	v_lshl_add_u64 v[90:91], v[82:83], 0, v[140:141]
	v_add_co_u32_e32 v92, vcc, 0x1000, v90
	s_nop 0
	s_nop 0
	v_addc_co_u32_e32 v93, vcc, 0, v91, vcc
	global_load_dwordx4 v[82:85], v[90:91], off
	global_load_dwordx4 v[86:89], v[92:93], off
	s_waitcnt vmcnt(0)
	v_cndmask_b32_e64 v97, v85, v89, s[0:1]
	v_cndmask_b32_e64 v99, v83, v87, s[0:1]
	v_cndmask_b32_e64 v100, v82, v86, s[0:1]
	v_cndmask_b32_e64 v98, v84, v88, s[0:1]
	v_mov_b32_dpp v94, v99 quad_perm:[1,0,3,2] row_mask:0xf bank_mask:0xf
	v_mov_b32_dpp v81, v100 quad_perm:[1,0,3,2] row_mask:0xf bank_mask:0xf
	v_mov_b32_dpp v96, v97 quad_perm:[1,0,3,2] row_mask:0xf bank_mask:0xf
	v_mov_b32_dpp v95, v98 quad_perm:[1,0,3,2] row_mask:0xf bank_mask:0xf
	v_cndmask_b32_e64 v97, v96, v85, s[0:1]
	v_cndmask_b32_e64 v85, v94, v83, s[0:1]
	v_cndmask_b32_e64 v83, v81, v82, s[0:1]
	v_cndmask_b32_e64 v100, v87, v94, s[0:1]
	v_cndmask_b32_e64 v81, v86, v81, s[0:1]
	v_cndmask_b32_e64 v98, v95, v84, s[0:1]
	v_cndmask_b32_e64 v101, v89, v96, s[0:1]
	v_cndmask_b32_e64 v99, v88, v95, s[0:1]
	v_lshlrev_b32_e32 v82, 16, v83
	v_and_b32_e32 v83, 0xffff0000, v83
	v_lshlrev_b32_e32 v84, 16, v85
	v_and_b32_e32 v85, 0xffff0000, v85
	v_lshlrev_b32_e32 v88, 16, v97
	v_and_b32_e32 v89, 0xffff0000, v97
	v_lshlrev_b32_e32 v94, 16, v81
	v_and_b32_e32 v95, 0xffff0000, v81
	v_lshlrev_b32_e32 v96, 16, v100
	v_and_b32_e32 v97, 0xffff0000, v100
	v_lshlrev_b32_e32 v86, 16, v98
	v_and_b32_e32 v87, 0xffff0000, v98
	v_lshlrev_b32_e32 v98, 16, v99
	v_and_b32_e32 v99, 0xffff0000, v99
	v_lshlrev_b32_e32 v100, 16, v101
	v_and_b32_e32 v101, 0xffff0000, v101
	v_pk_add_f32 v[78:79], v[78:79], v[84:85]
	v_pk_add_f32 v[76:77], v[76:77], v[82:83]
	v_pk_add_f32 v[70:71], v[70:71], v[96:97]
	v_pk_add_f32 v[68:69], v[68:69], v[94:95]
	v_pk_add_f32 v[74:75], v[74:75], v[88:89]
	v_pk_add_f32 v[72:73], v[72:73], v[86:87]
	v_pk_add_f32 v[66:67], v[66:67], v[100:101]
	v_pk_add_f32 v[64:65], v[64:65], v[98:99]
	v_cvt_pk_bf16_f32 v81, v76, v77
	v_cvt_pk_bf16_f32 v82, v78, v79
	v_cvt_pk_bf16_f32 v83, v72, v73
	v_cvt_pk_bf16_f32 v84, v74, v75
	v_mul_f32_e32 v77, v77, v77
	v_mul_f32_e32 v79, v79, v79
	v_cvt_pk_bf16_f32 v85, v68, v69
	v_cvt_pk_bf16_f32 v86, v70, v71
	v_mul_f32_e32 v69, v69, v69
	v_mul_f32_e32 v71, v71, v71
	v_mul_f32_e32 v73, v73, v73
	v_cvt_pk_bf16_f32 v87, v64, v65
	v_cvt_pk_bf16_f32 v88, v66, v67
	v_mul_f32_e32 v65, v65, v65
	v_mul_f32_e32 v67, v67, v67
	v_fmac_f32_e32 v77, v76, v76
	v_fmac_f32_e32 v79, v78, v78
	v_fmac_f32_e32 v69, v68, v68
	v_fmac_f32_e32 v71, v70, v70
	v_mul_f32_e32 v75, v75, v75
	v_fmac_f32_e32 v73, v72, v72
	v_fmac_f32_e32 v65, v64, v64
	v_fmac_f32_e32 v67, v66, v66
	v_cndmask_b32_e64 v66, v83, v87, s[0:1]
	v_add_f32_e32 v72, v77, v79
	v_add_f32_e32 v69, v69, v71
	v_fmac_f32_e32 v75, v74, v74
	v_mov_b32_dpp v104, v66 quad_perm:[1,0,3,2] row_mask:0xf bank_mask:0xf
	v_add_f32_e32 v66, v73, v72
	v_add_f32_e32 v65, v65, v69
	v_cndmask_b32_e64 v68, v82, v86, s[0:1]
	v_add_f32_e32 v66, v75, v66
	v_add_f32_e32 v65, v67, v65
	v_mov_b32_dpp v103, v68 quad_perm:[1,0,3,2] row_mask:0xf bank_mask:0xf
	v_add_f32_e32 v68, v66, v65
	ds_bpermute_b32 v69, v114, v68
	v_cndmask_b32_e64 v64, v84, v88, s[0:1]
	v_cndmask_b32_e64 v70, v81, v85, s[0:1]
	v_cndmask_b32_e64 v65, v103, v82, s[0:1]
	v_mov_b32_dpp v105, v64 quad_perm:[1,0,3,2] row_mask:0xf bank_mask:0xf
	v_mov_b32_dpp v102, v70 quad_perm:[1,0,3,2] row_mask:0xf bank_mask:0xf
	v_cndmask_b32_e64 v64, v102, v81, s[0:1]
	v_cndmask_b32_e64 v66, v104, v83, s[0:1]
	v_cndmask_b32_e64 v67, v105, v84, s[0:1]
	global_store_dwordx4 v[90:91], v[64:67], off
	s_waitcnt lgkmcnt(0)
	s_nop 0
	v_add_f32_e32 v64, v68, v69
	ds_bpermute_b32 v65, v115, v64
	v_cndmask_b32_e64 v66, v85, v102, s[0:1]
	v_cndmask_b32_e64 v67, v86, v103, s[0:1]
	v_cndmask_b32_e64 v68, v87, v104, s[0:1]
	v_cndmask_b32_e64 v69, v88, v105, s[0:1]
	global_store_dwordx4 v[92:93], v[66:69], off
	s_and_saveexec_b64 s[22:23], s[2:3]
	s_cbranch_execz .LBB0_1261
	v_ashrrev_i32_e32 v81, 31, v80
	v_lshl_add_u64 v[66:67], v[80:81], 2, s[12:13]
	s_waitcnt lgkmcnt(0)
	v_add_f32_e32 v64, v64, v65
	global_atomic_add_f32 v[66:67], v64, off
; __device__ __forceinline__ void store_pair_rows(bf16_t* O, size_t ldc, int row, int col0, int fr, u32x4 p0, u32x4 p1) {
;     const bool odd = (fr & 1) != 0;
;     const u32x4 snd = odd ? p0 : p1; u32x4 rcv;
;     rcv.x = dpp_xor1(snd.x); rcv.y = dpp_xor1(snd.y); rcv.z = dpp_xor1(snd.z); rcv.w = dpp_xor1(snd.w);
;     bf16_t* pa = O + (size_t)(row - (odd ? 1 : 0)) * ldc + col0 + (odd ? 8 : 0);
;     *(u32x4*)pa = odd ? rcv : p0;
;     *(u32x4*)(pa + ldc) = odd ? p1 : rcv;
; }
;     __device__ __forceinline__ void operator()(const f32x4 (&acc)[2][2][4][2], const Unit& u, int wr, int wc, int fr, int fq) const {
;     ...
;             const int row0 = u.pm * BM + wr * 64 + fr, col0 = u.pn * BM + wc * 64 + 16 * fq; const bool odd = (fr & 1) != 0;
; #pragma unroll
;             for (int ai = 0; ai < 2; ++ai)
; #pragma unroll
;                 for (int m = 0; m < 4; ++m) {
;                     const int row = row0 + ai * HALF + m * 16; float s = 0.f;
;                     const bf16_t* pa = baseb + (size_t)(row - (odd ? 1 : 0)) * DM + col0 + (odd ? 8 : 0);
;                     const u32x4 la = *(const u32x4*)pa, lb = *(const u32x4*)(pa + DM);
;                     const u32x4 snd = odd ? la : lb; u32x4 rcv;
;                     rcv.x = dpp_xor1(snd.x); rcv.y = dpp_xor1(snd.y); rcv.z = dpp_xor1(snd.z); rcv.w = dpp_xor1(snd.w);
;                     const u32x4 bw0 = odd ? rcv : la, bw1 = odd ? lb : rcv;
;                     u32x4 pw[2];
; #pragma unroll
;                     for (int bj = 0; bj < 2; ++bj) { const u32x4 bw = bj ? bw1 : bw0;
;                         const f32x4 b0 = (f32x4){bf_lo(bw.x), bf_hi(bw.x), bf_lo(bw.y), bf_hi(bw.y)}, b1 = (f32x4){bf_lo(bw.z), bf_hi(bw.z), bf_lo(bw.w), bf_hi(bw.w)};
;                         const f32x4 v0 = acc[ai][bj][m][0] + b0, v1 = acc[ai][bj][m][1] + b1;
;                         pw[bj].x = cvt_pk_bf16(v0[0], v0[1]); pw[bj].y = cvt_pk_bf16(v0[2], v0[3]); pw[bj].z = cvt_pk_bf16(v1[0], v1[1]); pw[bj].w = cvt_pk_bf16(v1[2], v1[3]);
;                         s += (v0[0] * v0[0] + v0[1] * v0[1]) + (v0[2] * v0[2] + v0[3] * v0[3]) + (v1[0] * v1[0] + v1[1] * v1[1]) + (v1[2] * v1[2] + v1[3] * v1[3]); }
;                     store_pair_rows(HB, (size_t)DM, row, col0, fr, pw[0], pw[1]);
;                     s += __shfl_xor(s, 16); s += __shfl_xor(s, 32);
;                     if (fq == 0) unsafeAtomicAdd(ssn + row, s);
.LBB0_1261:
	s_or_b64 exec, exec, s[22:23]
	v_add_u32_e32 v64, 0x80, v152
	v_sub_u32_e32 v66, v64, v158
	v_ashrrev_i32_e32 v67, 31, v66
	v_readlane_b32 s22, v254, 25
	v_lshlrev_b64 v[66:67], 12, v[66:67]
	v_readlane_b32 s23, v254, 26
	s_waitcnt lgkmcnt(0)
	s_nop 0
	v_lshl_add_u64 v[66:67], s[22:23], 0, v[66:67]
	v_lshl_add_u64 v[66:67], v[150:151], 1, v[66:67]
	v_lshl_add_u64 v[74:75], v[66:67], 0, v[140:141]
	v_add_co_u32_e32 v76, vcc, 0x1000, v74
	s_nop 0
	s_nop 0
	v_addc_co_u32_e32 v77, vcc, 0, v75, vcc
	global_load_dwordx4 v[66:69], v[74:75], off
	global_load_dwordx4 v[70:73], v[76:77], off
	s_waitcnt vmcnt(0)
	v_cndmask_b32_e64 v81, v69, v73, s[0:1]
	v_cndmask_b32_e64 v83, v67, v71, s[0:1]
	v_cndmask_b32_e64 v84, v66, v70, s[0:1]
	v_cndmask_b32_e64 v82, v68, v72, s[0:1]
	v_mov_b32_dpp v78, v83 quad_perm:[1,0,3,2] row_mask:0xf bank_mask:0xf
	v_mov_b32_dpp v65, v84 quad_perm:[1,0,3,2] row_mask:0xf bank_mask:0xf
	v_mov_b32_dpp v80, v81 quad_perm:[1,0,3,2] row_mask:0xf bank_mask:0xf
	v_mov_b32_dpp v79, v82 quad_perm:[1,0,3,2] row_mask:0xf bank_mask:0xf
	v_cndmask_b32_e64 v81, v80, v69, s[0:1]
	v_cndmask_b32_e64 v69, v78, v67, s[0:1]
	v_cndmask_b32_e64 v67, v65, v66, s[0:1]
	v_cndmask_b32_e64 v84, v71, v78, s[0:1]
	v_cndmask_b32_e64 v65, v70, v65, s[0:1]
	v_cndmask_b32_e64 v82, v79, v68, s[0:1]
	v_cndmask_b32_e64 v85, v73, v80, s[0:1]
	v_cndmask_b32_e64 v83, v72, v79, s[0:1]
	v_lshlrev_b32_e32 v66, 16, v67
	v_and_b32_e32 v67, 0xffff0000, v67
	v_lshlrev_b32_e32 v68, 16, v69
	v_and_b32_e32 v69, 0xffff0000, v69
	v_lshlrev_b32_e32 v72, 16, v81
	v_and_b32_e32 v73, 0xffff0000, v81
	v_lshlrev_b32_e32 v78, 16, v65
	v_and_b32_e32 v79, 0xffff0000, v65
	v_lshlrev_b32_e32 v80, 16, v84
	v_and_b32_e32 v81, 0xffff0000, v84
	v_lshlrev_b32_e32 v70, 16, v82
	v_and_b32_e32 v71, 0xffff0000, v82
	v_lshlrev_b32_e32 v82, 16, v83
	v_and_b32_e32 v83, 0xffff0000, v83
	v_lshlrev_b32_e32 v84, 16, v85
	v_and_b32_e32 v85, 0xffff0000, v85
	v_pk_add_f32 v[62:63], v[62:63], v[68:69]
	v_pk_add_f32 v[60:61], v[60:61], v[66:67]
	v_pk_add_f32 v[54:55], v[54:55], v[80:81]
	v_pk_add_f32 v[52:53], v[52:53], v[78:79]
	v_pk_add_f32 v[58:59], v[58:59], v[72:73]
	v_pk_add_f32 v[56:57], v[56:57], v[70:71]
	v_pk_add_f32 v[50:51], v[50:51], v[84:85]
	v_pk_add_f32 v[48:49], v[48:49], v[82:83]
	v_cvt_pk_bf16_f32 v65, v60, v61
	v_cvt_pk_bf16_f32 v66, v62, v63
	v_cvt_pk_bf16_f32 v67, v56, v57
	v_cvt_pk_bf16_f32 v68, v58, v59
	v_mul_f32_e32 v61, v61, v61
	v_mul_f32_e32 v63, v63, v63
	v_cvt_pk_bf16_f32 v69, v52, v53
	v_cvt_pk_bf16_f32 v70, v54, v55
	v_mul_f32_e32 v53, v53, v53
	v_mul_f32_e32 v55, v55, v55
	v_mul_f32_e32 v57, v57, v57
	v_cvt_pk_bf16_f32 v71, v48, v49
	v_cvt_pk_bf16_f32 v72, v50, v51
	v_mul_f32_e32 v49, v49, v49
	v_mul_f32_e32 v51, v51, v51
	v_fmac_f32_e32 v61, v60, v60
	v_fmac_f32_e32 v63, v62, v62
	v_fmac_f32_e32 v53, v52, v52
	v_fmac_f32_e32 v55, v54, v54
	v_mul_f32_e32 v59, v59, v59
	v_fmac_f32_e32 v57, v56, v56
	v_fmac_f32_e32 v49, v48, v48
	v_fmac_f32_e32 v51, v50, v50
	v_cndmask_b32_e64 v50, v67, v71, s[0:1]
	v_add_f32_e32 v56, v61, v63
	v_add_f32_e32 v53, v53, v55
	v_fmac_f32_e32 v59, v58, v58
	v_mov_b32_dpp v88, v50 quad_perm:[1,0,3,2] row_mask:0xf bank_mask:0xf
	v_add_f32_e32 v50, v57, v56
	v_add_f32_e32 v49, v49, v53
	v_cndmask_b32_e64 v52, v66, v70, s[0:1]
	v_add_f32_e32 v50, v59, v50
	v_add_f32_e32 v49, v51, v49
	v_mov_b32_dpp v87, v52 quad_perm:[1,0,3,2] row_mask:0xf bank_mask:0xf
	v_add_f32_e32 v52, v50, v49
	ds_bpermute_b32 v53, v114, v52
	v_cndmask_b32_e64 v48, v68, v72, s[0:1]
	v_cndmask_b32_e64 v54, v65, v69, s[0:1]
	v_cndmask_b32_e64 v49, v87, v66, s[0:1]
	v_mov_b32_dpp v89, v48 quad_perm:[1,0,3,2] row_mask:0xf bank_mask:0xf
	v_mov_b32_dpp v86, v54 quad_perm:[1,0,3,2] row_mask:0xf bank_mask:0xf
	v_cndmask_b32_e64 v48, v86, v65, s[0:1]
	v_cndmask_b32_e64 v50, v88, v67, s[0:1]
	v_cndmask_b32_e64 v51, v89, v68, s[0:1]
	global_store_dwordx4 v[74:75], v[48:51], off
	s_waitcnt lgkmcnt(0)
	s_nop 0
	v_add_f32_e32 v48, v52, v53
	ds_bpermute_b32 v49, v115, v48
	v_cndmask_b32_e64 v50, v69, v86, s[0:1]
	v_cndmask_b32_e64 v51, v70, v87, s[0:1]
	v_cndmask_b32_e64 v52, v71, v88, s[0:1]
	v_cndmask_b32_e64 v53, v72, v89, s[0:1]
	global_store_dwordx4 v[76:77], v[50:53], off
	s_and_saveexec_b64 s[22:23], s[2:3]
	s_cbranch_execz .LBB0_1263
	v_ashrrev_i32_e32 v65, 31, v64
	v_lshl_add_u64 v[50:51], v[64:65], 2, s[12:13]
	s_waitcnt lgkmcnt(0)
	v_add_f32_e32 v48, v48, v49
	global_atomic_add_f32 v[50:51], v48, off
; __device__ __forceinline__ void store_pair_rows(bf16_t* O, size_t ldc, int row, int col0, int fr, u32x4 p0, u32x4 p1) {
;     const bool odd = (fr & 1) != 0;
;     const u32x4 snd = odd ? p0 : p1; u32x4 rcv;
;     rcv.x = dpp_xor1(snd.x); rcv.y = dpp_xor1(snd.y); rcv.z = dpp_xor1(snd.z); rcv.w = dpp_xor1(snd.w);
;     bf16_t* pa = O + (size_t)(row - (odd ? 1 : 0)) * ldc + col0 + (odd ? 8 : 0);
;     *(u32x4*)pa = odd ? rcv : p0;
;     *(u32x4*)(pa + ldc) = odd ? p1 : rcv;
; }
;     __device__ __forceinline__ void operator()(const f32x4 (&acc)[2][2][4][2], const Unit& u, int wr, int wc, int fr, int fq) const {
;     ...
;             const int row0 = u.pm * BM + wr * 64 + fr, col0 = u.pn * BM + wc * 64 + 16 * fq; const bool odd = (fr & 1) != 0;
; #pragma unroll
;             for (int ai = 0; ai < 2; ++ai)
; #pragma unroll
;                 for (int m = 0; m < 4; ++m) {
;                     const int row = row0 + ai * HALF + m * 16; float s = 0.f;
;                     const bf16_t* pa = baseb + (size_t)(row - (odd ? 1 : 0)) * DM + col0 + (odd ? 8 : 0);
;                     const u32x4 la = *(const u32x4*)pa, lb = *(const u32x4*)(pa + DM);
;                     const u32x4 snd = odd ? la : lb; u32x4 rcv;
;                     rcv.x = dpp_xor1(snd.x); rcv.y = dpp_xor1(snd.y); rcv.z = dpp_xor1(snd.z); rcv.w = dpp_xor1(snd.w);
;                     const u32x4 bw0 = odd ? rcv : la, bw1 = odd ? lb : rcv;
;                     u32x4 pw[2];
; #pragma unroll
;                     for (int bj = 0; bj < 2; ++bj) { const u32x4 bw = bj ? bw1 : bw0;
;                         const f32x4 b0 = (f32x4){bf_lo(bw.x), bf_hi(bw.x), bf_lo(bw.y), bf_hi(bw.y)}, b1 = (f32x4){bf_lo(bw.z), bf_hi(bw.z), bf_lo(bw.w), bf_hi(bw.w)};
;                         const f32x4 v0 = acc[ai][bj][m][0] + b0, v1 = acc[ai][bj][m][1] + b1;
;                         pw[bj].x = cvt_pk_bf16(v0[0], v0[1]); pw[bj].y = cvt_pk_bf16(v0[2], v0[3]); pw[bj].z = cvt_pk_bf16(v1[0], v1[1]); pw[bj].w = cvt_pk_bf16(v1[2], v1[3]);
;                         s += (v0[0] * v0[0] + v0[1] * v0[1]) + (v0[2] * v0[2] + v0[3] * v0[3]) + (v1[0] * v1[0] + v1[1] * v1[1]) + (v1[2] * v1[2] + v1[3] * v1[3]); }
;                     store_pair_rows(HB, (size_t)DM, row, col0, fr, pw[0], pw[1]);
;                     s += __shfl_xor(s, 16); s += __shfl_xor(s, 32);
;                     if (fq == 0) unsafeAtomicAdd(ssn + row, s);
.LBB0_1263:
	s_or_b64 exec, exec, s[22:23]
	v_add_u32_e32 v48, 0x90, v152
	v_sub_u32_e32 v50, v48, v158
	v_ashrrev_i32_e32 v51, 31, v50
	v_readlane_b32 s22, v254, 25
	v_lshlrev_b64 v[50:51], 12, v[50:51]
	v_readlane_b32 s23, v254, 26
	s_waitcnt lgkmcnt(0)
	s_nop 0
	v_lshl_add_u64 v[50:51], s[22:23], 0, v[50:51]
	v_lshl_add_u64 v[50:51], v[150:151], 1, v[50:51]
	v_lshl_add_u64 v[58:59], v[50:51], 0, v[140:141]
	v_add_co_u32_e32 v60, vcc, 0x1000, v58
	s_nop 0
	s_nop 0
	v_addc_co_u32_e32 v61, vcc, 0, v59, vcc
	global_load_dwordx4 v[50:53], v[58:59], off
	global_load_dwordx4 v[54:57], v[60:61], off
	s_waitcnt vmcnt(0)
	v_cndmask_b32_e64 v65, v53, v57, s[0:1]
	v_cndmask_b32_e64 v67, v51, v55, s[0:1]
	v_cndmask_b32_e64 v68, v50, v54, s[0:1]
	v_cndmask_b32_e64 v66, v52, v56, s[0:1]
	v_mov_b32_dpp v62, v67 quad_perm:[1,0,3,2] row_mask:0xf bank_mask:0xf
	v_mov_b32_dpp v49, v68 quad_perm:[1,0,3,2] row_mask:0xf bank_mask:0xf
	v_mov_b32_dpp v64, v65 quad_perm:[1,0,3,2] row_mask:0xf bank_mask:0xf
	v_mov_b32_dpp v63, v66 quad_perm:[1,0,3,2] row_mask:0xf bank_mask:0xf
	v_cndmask_b32_e64 v65, v64, v53, s[0:1]
	v_cndmask_b32_e64 v53, v62, v51, s[0:1]
	v_cndmask_b32_e64 v51, v49, v50, s[0:1]
	v_cndmask_b32_e64 v68, v55, v62, s[0:1]
	v_cndmask_b32_e64 v49, v54, v49, s[0:1]
	v_cndmask_b32_e64 v66, v63, v52, s[0:1]
	v_cndmask_b32_e64 v69, v57, v64, s[0:1]
	v_cndmask_b32_e64 v67, v56, v63, s[0:1]
	v_lshlrev_b32_e32 v50, 16, v51
	v_and_b32_e32 v51, 0xffff0000, v51
	v_lshlrev_b32_e32 v52, 16, v53
	v_and_b32_e32 v53, 0xffff0000, v53
	v_lshlrev_b32_e32 v56, 16, v65
	v_and_b32_e32 v57, 0xffff0000, v65
	v_lshlrev_b32_e32 v62, 16, v49
	v_and_b32_e32 v63, 0xffff0000, v49
	v_lshlrev_b32_e32 v64, 16, v68
	v_and_b32_e32 v65, 0xffff0000, v68
	v_lshlrev_b32_e32 v54, 16, v66
	v_and_b32_e32 v55, 0xffff0000, v66
	v_lshlrev_b32_e32 v66, 16, v67
	v_and_b32_e32 v67, 0xffff0000, v67
	v_lshlrev_b32_e32 v68, 16, v69
	v_and_b32_e32 v69, 0xffff0000, v69
	v_pk_add_f32 v[46:47], v[46:47], v[52:53]
	v_pk_add_f32 v[44:45], v[44:45], v[50:51]
	v_pk_add_f32 v[38:39], v[38:39], v[64:65]
	v_pk_add_f32 v[36:37], v[36:37], v[62:63]
	v_pk_add_f32 v[42:43], v[42:43], v[56:57]
	v_pk_add_f32 v[40:41], v[40:41], v[54:55]
	v_pk_add_f32 v[34:35], v[34:35], v[68:69]
	v_pk_add_f32 v[32:33], v[32:33], v[66:67]
	v_cvt_pk_bf16_f32 v49, v44, v45
	v_cvt_pk_bf16_f32 v50, v46, v47
	v_cvt_pk_bf16_f32 v51, v40, v41
	v_cvt_pk_bf16_f32 v52, v42, v43
	v_mul_f32_e32 v45, v45, v45
	v_mul_f32_e32 v47, v47, v47
	v_cvt_pk_bf16_f32 v53, v36, v37
	v_cvt_pk_bf16_f32 v54, v38, v39
	v_mul_f32_e32 v37, v37, v37
	v_mul_f32_e32 v39, v39, v39
	v_mul_f32_e32 v41, v41, v41
	v_cvt_pk_bf16_f32 v55, v32, v33
	v_cvt_pk_bf16_f32 v56, v34, v35
	v_mul_f32_e32 v33, v33, v33
	v_mul_f32_e32 v35, v35, v35
	v_fmac_f32_e32 v45, v44, v44
	v_fmac_f32_e32 v47, v46, v46
	v_fmac_f32_e32 v37, v36, v36
	v_fmac_f32_e32 v39, v38, v38
	v_mul_f32_e32 v43, v43, v43
	v_fmac_f32_e32 v41, v40, v40
	v_fmac_f32_e32 v33, v32, v32
	v_fmac_f32_e32 v35, v34, v34
	v_cndmask_b32_e64 v34, v51, v55, s[0:1]
	v_add_f32_e32 v40, v45, v47
	v_add_f32_e32 v37, v37, v39
	v_fmac_f32_e32 v43, v42, v42
	v_mov_b32_dpp v72, v34 quad_perm:[1,0,3,2] row_mask:0xf bank_mask:0xf
	v_add_f32_e32 v34, v41, v40
	v_add_f32_e32 v33, v33, v37
	v_cndmask_b32_e64 v36, v50, v54, s[0:1]
	v_add_f32_e32 v34, v43, v34
	v_add_f32_e32 v33, v35, v33
	v_mov_b32_dpp v71, v36 quad_perm:[1,0,3,2] row_mask:0xf bank_mask:0xf
	v_add_f32_e32 v36, v34, v33
	ds_bpermute_b32 v37, v114, v36
	v_cndmask_b32_e64 v32, v52, v56, s[0:1]
	v_cndmask_b32_e64 v38, v49, v53, s[0:1]
	v_cndmask_b32_e64 v33, v71, v50, s[0:1]
	v_mov_b32_dpp v73, v32 quad_perm:[1,0,3,2] row_mask:0xf bank_mask:0xf
	v_mov_b32_dpp v70, v38 quad_perm:[1,0,3,2] row_mask:0xf bank_mask:0xf
	v_cndmask_b32_e64 v32, v70, v49, s[0:1]
	v_cndmask_b32_e64 v34, v72, v51, s[0:1]
	v_cndmask_b32_e64 v35, v73, v52, s[0:1]
	global_store_dwordx4 v[58:59], v[32:35], off
	s_waitcnt lgkmcnt(0)
	s_nop 0
	v_add_f32_e32 v32, v36, v37
	ds_bpermute_b32 v33, v115, v32
	v_cndmask_b32_e64 v34, v53, v70, s[0:1]
	v_cndmask_b32_e64 v35, v54, v71, s[0:1]
	v_cndmask_b32_e64 v36, v55, v72, s[0:1]
	v_cndmask_b32_e64 v37, v56, v73, s[0:1]
	global_store_dwordx4 v[60:61], v[34:37], off
	s_and_saveexec_b64 s[22:23], s[2:3]
	s_cbranch_execz .LBB0_1265
	v_ashrrev_i32_e32 v49, 31, v48
	v_lshl_add_u64 v[34:35], v[48:49], 2, s[12:13]
	s_waitcnt lgkmcnt(0)
	v_add_f32_e32 v32, v32, v33
	global_atomic_add_f32 v[34:35], v32, off
; __device__ __forceinline__ void store_pair_rows(bf16_t* O, size_t ldc, int row, int col0, int fr, u32x4 p0, u32x4 p1) {
;     const bool odd = (fr & 1) != 0;
;     const u32x4 snd = odd ? p0 : p1; u32x4 rcv;
;     rcv.x = dpp_xor1(snd.x); rcv.y = dpp_xor1(snd.y); rcv.z = dpp_xor1(snd.z); rcv.w = dpp_xor1(snd.w);
;     bf16_t* pa = O + (size_t)(row - (odd ? 1 : 0)) * ldc + col0 + (odd ? 8 : 0);
;     *(u32x4*)pa = odd ? rcv : p0;
;     *(u32x4*)(pa + ldc) = odd ? p1 : rcv;
; }
;     __device__ __forceinline__ void operator()(const f32x4 (&acc)[2][2][4][2], const Unit& u, int wr, int wc, int fr, int fq) const {
;     ...
;             const int row0 = u.pm * BM + wr * 64 + fr, col0 = u.pn * BM + wc * 64 + 16 * fq; const bool odd = (fr & 1) != 0;
; #pragma unroll
;             for (int ai = 0; ai < 2; ++ai)
; #pragma unroll
;                 for (int m = 0; m < 4; ++m) {
;                     const int row = row0 + ai * HALF + m * 16; float s = 0.f;
;                     const bf16_t* pa = baseb + (size_t)(row - (odd ? 1 : 0)) * DM + col0 + (odd ? 8 : 0);
;                     const u32x4 la = *(const u32x4*)pa, lb = *(const u32x4*)(pa + DM);
;                     const u32x4 snd = odd ? la : lb; u32x4 rcv;
;                     rcv.x = dpp_xor1(snd.x); rcv.y = dpp_xor1(snd.y); rcv.z = dpp_xor1(snd.z); rcv.w = dpp_xor1(snd.w);
;                     const u32x4 bw0 = odd ? rcv : la, bw1 = odd ? lb : rcv;
;                     u32x4 pw[2];
; #pragma unroll
;                     for (int bj = 0; bj < 2; ++bj) { const u32x4 bw = bj ? bw1 : bw0;
;                         const f32x4 b0 = (f32x4){bf_lo(bw.x), bf_hi(bw.x), bf_lo(bw.y), bf_hi(bw.y)}, b1 = (f32x4){bf_lo(bw.z), bf_hi(bw.z), bf_lo(bw.w), bf_hi(bw.w)};
;                         const f32x4 v0 = acc[ai][bj][m][0] + b0, v1 = acc[ai][bj][m][1] + b1;
;                         pw[bj].x = cvt_pk_bf16(v0[0], v0[1]); pw[bj].y = cvt_pk_bf16(v0[2], v0[3]); pw[bj].z = cvt_pk_bf16(v1[0], v1[1]); pw[bj].w = cvt_pk_bf16(v1[2], v1[3]);
;                         s += (v0[0] * v0[0] + v0[1] * v0[1]) + (v0[2] * v0[2] + v0[3] * v0[3]) + (v1[0] * v1[0] + v1[1] * v1[1]) + (v1[2] * v1[2] + v1[3] * v1[3]); }
;                     store_pair_rows(HB, (size_t)DM, row, col0, fr, pw[0], pw[1]);
;                     s += __shfl_xor(s, 16); s += __shfl_xor(s, 32);
;                     if (fq == 0) unsafeAtomicAdd(ssn + row, s);
.LBB0_1265:
	s_or_b64 exec, exec, s[22:23]
	v_add_u32_e32 v32, 0xa0, v152
	v_sub_u32_e32 v34, v32, v158
	v_ashrrev_i32_e32 v35, 31, v34
	v_readlane_b32 s22, v254, 25
	v_lshlrev_b64 v[34:35], 12, v[34:35]
	v_readlane_b32 s23, v254, 26
	s_waitcnt lgkmcnt(0)
	s_nop 0
	v_lshl_add_u64 v[34:35], s[22:23], 0, v[34:35]
	v_lshl_add_u64 v[34:35], v[150:151], 1, v[34:35]
	v_lshl_add_u64 v[42:43], v[34:35], 0, v[140:141]
	v_add_co_u32_e32 v44, vcc, 0x1000, v42
	s_nop 0
	s_nop 0
	v_addc_co_u32_e32 v45, vcc, 0, v43, vcc
	global_load_dwordx4 v[34:37], v[42:43], off
	global_load_dwordx4 v[38:41], v[44:45], off
	s_waitcnt vmcnt(0)
	v_cndmask_b32_e64 v49, v37, v41, s[0:1]
	v_cndmask_b32_e64 v51, v35, v39, s[0:1]
	v_cndmask_b32_e64 v52, v34, v38, s[0:1]
	v_cndmask_b32_e64 v50, v36, v40, s[0:1]
	v_mov_b32_dpp v46, v51 quad_perm:[1,0,3,2] row_mask:0xf bank_mask:0xf
	v_mov_b32_dpp v33, v52 quad_perm:[1,0,3,2] row_mask:0xf bank_mask:0xf
	v_mov_b32_dpp v48, v49 quad_perm:[1,0,3,2] row_mask:0xf bank_mask:0xf
	v_mov_b32_dpp v47, v50 quad_perm:[1,0,3,2] row_mask:0xf bank_mask:0xf
	v_cndmask_b32_e64 v49, v48, v37, s[0:1]
	v_cndmask_b32_e64 v37, v46, v35, s[0:1]
	v_cndmask_b32_e64 v35, v33, v34, s[0:1]
	v_cndmask_b32_e64 v52, v39, v46, s[0:1]
	v_cndmask_b32_e64 v33, v38, v33, s[0:1]
	v_cndmask_b32_e64 v50, v47, v36, s[0:1]
	v_cndmask_b32_e64 v53, v41, v48, s[0:1]
	v_cndmask_b32_e64 v51, v40, v47, s[0:1]
	v_lshlrev_b32_e32 v34, 16, v35
	v_and_b32_e32 v35, 0xffff0000, v35
	v_lshlrev_b32_e32 v36, 16, v37
	v_and_b32_e32 v37, 0xffff0000, v37
	v_lshlrev_b32_e32 v40, 16, v49
	v_and_b32_e32 v41, 0xffff0000, v49
	v_lshlrev_b32_e32 v46, 16, v33
	v_and_b32_e32 v47, 0xffff0000, v33
	v_lshlrev_b32_e32 v48, 16, v52
	v_and_b32_e32 v49, 0xffff0000, v52
	v_lshlrev_b32_e32 v38, 16, v50
	v_and_b32_e32 v39, 0xffff0000, v50
	v_lshlrev_b32_e32 v50, 16, v51
	v_and_b32_e32 v51, 0xffff0000, v51
	v_lshlrev_b32_e32 v52, 16, v53
	v_and_b32_e32 v53, 0xffff0000, v53
	v_pk_add_f32 v[30:31], v[30:31], v[36:37]
	v_pk_add_f32 v[28:29], v[28:29], v[34:35]
	v_pk_add_f32 v[22:23], v[22:23], v[48:49]
	v_pk_add_f32 v[20:21], v[20:21], v[46:47]
	v_pk_add_f32 v[26:27], v[26:27], v[40:41]
	v_pk_add_f32 v[24:25], v[24:25], v[38:39]
	v_pk_add_f32 v[18:19], v[18:19], v[52:53]
	v_pk_add_f32 v[16:17], v[16:17], v[50:51]
	v_cvt_pk_bf16_f32 v33, v28, v29
	v_cvt_pk_bf16_f32 v34, v30, v31
	v_cvt_pk_bf16_f32 v35, v24, v25
	v_cvt_pk_bf16_f32 v36, v26, v27
	v_mul_f32_e32 v29, v29, v29
	v_mul_f32_e32 v31, v31, v31
	v_cvt_pk_bf16_f32 v37, v20, v21
	v_cvt_pk_bf16_f32 v38, v22, v23
	v_mul_f32_e32 v21, v21, v21
	v_mul_f32_e32 v23, v23, v23
	v_mul_f32_e32 v25, v25, v25
	v_cvt_pk_bf16_f32 v39, v16, v17
	v_cvt_pk_bf16_f32 v40, v18, v19
	v_mul_f32_e32 v17, v17, v17
	v_mul_f32_e32 v19, v19, v19
	v_fmac_f32_e32 v29, v28, v28
	v_fmac_f32_e32 v31, v30, v30
	v_fmac_f32_e32 v21, v20, v20
	v_fmac_f32_e32 v23, v22, v22
	v_mul_f32_e32 v27, v27, v27
	v_fmac_f32_e32 v25, v24, v24
	v_fmac_f32_e32 v17, v16, v16
	v_fmac_f32_e32 v19, v18, v18
	v_cndmask_b32_e64 v18, v35, v39, s[0:1]
	v_add_f32_e32 v24, v29, v31
	v_add_f32_e32 v21, v21, v23
	v_fmac_f32_e32 v27, v26, v26
	v_mov_b32_dpp v56, v18 quad_perm:[1,0,3,2] row_mask:0xf bank_mask:0xf
	v_add_f32_e32 v18, v25, v24
	v_add_f32_e32 v17, v17, v21
	v_cndmask_b32_e64 v20, v34, v38, s[0:1]
	v_add_f32_e32 v18, v27, v18
	v_add_f32_e32 v17, v19, v17
	v_mov_b32_dpp v55, v20 quad_perm:[1,0,3,2] row_mask:0xf bank_mask:0xf
	v_add_f32_e32 v20, v18, v17
	ds_bpermute_b32 v21, v114, v20
	v_cndmask_b32_e64 v16, v36, v40, s[0:1]
	v_cndmask_b32_e64 v22, v33, v37, s[0:1]
	v_cndmask_b32_e64 v17, v55, v34, s[0:1]
	v_mov_b32_dpp v57, v16 quad_perm:[1,0,3,2] row_mask:0xf bank_mask:0xf
	v_mov_b32_dpp v54, v22 quad_perm:[1,0,3,2] row_mask:0xf bank_mask:0xf
	v_cndmask_b32_e64 v16, v54, v33, s[0:1]
	v_cndmask_b32_e64 v18, v56, v35, s[0:1]
	v_cndmask_b32_e64 v19, v57, v36, s[0:1]
	global_store_dwordx4 v[42:43], v[16:19], off
	s_waitcnt lgkmcnt(0)
	s_nop 0
	v_add_f32_e32 v16, v20, v21
	ds_bpermute_b32 v17, v115, v16
	v_cndmask_b32_e64 v18, v37, v54, s[0:1]
	v_cndmask_b32_e64 v19, v38, v55, s[0:1]
	v_cndmask_b32_e64 v20, v39, v56, s[0:1]
	v_cndmask_b32_e64 v21, v40, v57, s[0:1]
	global_store_dwordx4 v[44:45], v[18:21], off
	s_and_saveexec_b64 s[22:23], s[2:3]
	s_cbranch_execz .LBB0_1267
	v_ashrrev_i32_e32 v33, 31, v32
	v_lshl_add_u64 v[18:19], v[32:33], 2, s[12:13]
	s_waitcnt lgkmcnt(0)
	v_add_f32_e32 v16, v16, v17
	global_atomic_add_f32 v[18:19], v16, off
; __device__ __forceinline__ void store_pair_rows(bf16_t* O, size_t ldc, int row, int col0, int fr, u32x4 p0, u32x4 p1) {
;     const bool odd = (fr & 1) != 0;
;     const u32x4 snd = odd ? p0 : p1; u32x4 rcv;
;     rcv.x = dpp_xor1(snd.x); rcv.y = dpp_xor1(snd.y); rcv.z = dpp_xor1(snd.z); rcv.w = dpp_xor1(snd.w);
;     bf16_t* pa = O + (size_t)(row - (odd ? 1 : 0)) * ldc + col0 + (odd ? 8 : 0);
;     *(u32x4*)pa = odd ? rcv : p0;
;     *(u32x4*)(pa + ldc) = odd ? p1 : rcv;
; }
;     __device__ __forceinline__ void operator()(const f32x4 (&acc)[2][2][4][2], const Unit& u, int wr, int wc, int fr, int fq) const {
;     ...
;             const int row0 = u.pm * BM + wr * 64 + fr, col0 = u.pn * BM + wc * 64 + 16 * fq; const bool odd = (fr & 1) != 0;
; #pragma unroll
;             for (int ai = 0; ai < 2; ++ai)
; #pragma unroll
;                 for (int m = 0; m < 4; ++m) {
;                     const int row = row0 + ai * HALF + m * 16; float s = 0.f;
;                     const bf16_t* pa = baseb + (size_t)(row - (odd ? 1 : 0)) * DM + col0 + (odd ? 8 : 0);
;                     const u32x4 la = *(const u32x4*)pa, lb = *(const u32x4*)(pa + DM);
;                     const u32x4 snd = odd ? la : lb; u32x4 rcv;
;                     rcv.x = dpp_xor1(snd.x); rcv.y = dpp_xor1(snd.y); rcv.z = dpp_xor1(snd.z); rcv.w = dpp_xor1(snd.w);
;                     const u32x4 bw0 = odd ? rcv : la, bw1 = odd ? lb : rcv;
;                     u32x4 pw[2];
; #pragma unroll
;                     for (int bj = 0; bj < 2; ++bj) { const u32x4 bw = bj ? bw1 : bw0;
;                         const f32x4 b0 = (f32x4){bf_lo(bw.x), bf_hi(bw.x), bf_lo(bw.y), bf_hi(bw.y)}, b1 = (f32x4){bf_lo(bw.z), bf_hi(bw.z), bf_lo(bw.w), bf_hi(bw.w)};
;                         const f32x4 v0 = acc[ai][bj][m][0] + b0, v1 = acc[ai][bj][m][1] + b1;
;                         pw[bj].x = cvt_pk_bf16(v0[0], v0[1]); pw[bj].y = cvt_pk_bf16(v0[2], v0[3]); pw[bj].z = cvt_pk_bf16(v1[0], v1[1]); pw[bj].w = cvt_pk_bf16(v1[2], v1[3]);
;                         s += (v0[0] * v0[0] + v0[1] * v0[1]) + (v0[2] * v0[2] + v0[3] * v0[3]) + (v1[0] * v1[0] + v1[1] * v1[1]) + (v1[2] * v1[2] + v1[3] * v1[3]); }
;                     store_pair_rows(HB, (size_t)DM, row, col0, fr, pw[0], pw[1]);
;                     s += __shfl_xor(s, 16); s += __shfl_xor(s, 32);
;                     if (fq == 0) unsafeAtomicAdd(ssn + row, s);
.LBB0_1267:
	s_or_b64 exec, exec, s[22:23]
	v_add_u32_e32 v16, 0xb0, v152
	v_sub_u32_e32 v18, v16, v158
	v_ashrrev_i32_e32 v19, 31, v18
	v_readlane_b32 s22, v254, 25
	v_lshlrev_b64 v[18:19], 12, v[18:19]
	v_readlane_b32 s23, v254, 26
	s_waitcnt lgkmcnt(0)
	s_nop 0
	v_lshl_add_u64 v[18:19], s[22:23], 0, v[18:19]
	v_lshl_add_u64 v[18:19], v[150:151], 1, v[18:19]
	v_lshl_add_u64 v[26:27], v[18:19], 0, v[140:141]
	v_add_co_u32_e32 v28, vcc, 0x1000, v26
	s_nop 0
	s_nop 0
	v_addc_co_u32_e32 v29, vcc, 0, v27, vcc
	global_load_dwordx4 v[18:21], v[26:27], off
	global_load_dwordx4 v[22:25], v[28:29], off
	s_waitcnt vmcnt(0)
	v_cndmask_b32_e64 v33, v21, v25, s[0:1]
	v_cndmask_b32_e64 v35, v19, v23, s[0:1]
	v_cndmask_b32_e64 v36, v18, v22, s[0:1]
	v_cndmask_b32_e64 v34, v20, v24, s[0:1]
	v_mov_b32_dpp v30, v35 quad_perm:[1,0,3,2] row_mask:0xf bank_mask:0xf
	v_mov_b32_dpp v17, v36 quad_perm:[1,0,3,2] row_mask:0xf bank_mask:0xf
	v_mov_b32_dpp v32, v33 quad_perm:[1,0,3,2] row_mask:0xf bank_mask:0xf
	v_mov_b32_dpp v31, v34 quad_perm:[1,0,3,2] row_mask:0xf bank_mask:0xf
	v_cndmask_b32_e64 v33, v32, v21, s[0:1]
	v_cndmask_b32_e64 v21, v30, v19, s[0:1]
	v_cndmask_b32_e64 v19, v17, v18, s[0:1]
	v_cndmask_b32_e64 v36, v23, v30, s[0:1]
	v_cndmask_b32_e64 v17, v22, v17, s[0:1]
	v_cndmask_b32_e64 v34, v31, v20, s[0:1]
	v_cndmask_b32_e64 v37, v25, v32, s[0:1]
	v_cndmask_b32_e64 v35, v24, v31, s[0:1]
	v_lshlrev_b32_e32 v18, 16, v19
	v_and_b32_e32 v19, 0xffff0000, v19
	v_lshlrev_b32_e32 v20, 16, v21
	v_and_b32_e32 v21, 0xffff0000, v21
	v_lshlrev_b32_e32 v24, 16, v33
	v_and_b32_e32 v25, 0xffff0000, v33
	v_lshlrev_b32_e32 v30, 16, v17
	v_and_b32_e32 v31, 0xffff0000, v17
	v_lshlrev_b32_e32 v32, 16, v36
	v_and_b32_e32 v33, 0xffff0000, v36
	v_lshlrev_b32_e32 v22, 16, v34
	v_and_b32_e32 v23, 0xffff0000, v34
	v_lshlrev_b32_e32 v34, 16, v35
	v_and_b32_e32 v35, 0xffff0000, v35
	v_lshlrev_b32_e32 v36, 16, v37
	v_and_b32_e32 v37, 0xffff0000, v37
	v_pk_add_f32 v[14:15], v[14:15], v[20:21]
	v_pk_add_f32 v[12:13], v[12:13], v[18:19]
	v_pk_add_f32 v[6:7], v[6:7], v[32:33]
	v_pk_add_f32 v[4:5], v[4:5], v[30:31]
	v_pk_add_f32 v[10:11], v[10:11], v[24:25]
	v_pk_add_f32 v[8:9], v[8:9], v[22:23]
	v_pk_add_f32 v[2:3], v[2:3], v[36:37]
	v_pk_add_f32 v[0:1], v[0:1], v[34:35]
	v_cvt_pk_bf16_f32 v17, v12, v13
	v_cvt_pk_bf16_f32 v18, v14, v15
	v_cvt_pk_bf16_f32 v19, v8, v9
	v_cvt_pk_bf16_f32 v20, v10, v11
	v_mul_f32_e32 v13, v13, v13
	v_mul_f32_e32 v15, v15, v15
	v_cvt_pk_bf16_f32 v21, v4, v5
	v_cvt_pk_bf16_f32 v22, v6, v7
	v_mul_f32_e32 v5, v5, v5
	v_mul_f32_e32 v7, v7, v7
	v_mul_f32_e32 v9, v9, v9
	v_cvt_pk_bf16_f32 v23, v0, v1
	v_cvt_pk_bf16_f32 v24, v2, v3
	v_mul_f32_e32 v1, v1, v1
	v_mul_f32_e32 v3, v3, v3
	v_fmac_f32_e32 v13, v12, v12
	v_fmac_f32_e32 v15, v14, v14
	v_fmac_f32_e32 v5, v4, v4
	v_fmac_f32_e32 v7, v6, v6
	v_mul_f32_e32 v11, v11, v11
	v_fmac_f32_e32 v9, v8, v8
	v_fmac_f32_e32 v1, v0, v0
	v_fmac_f32_e32 v3, v2, v2
	v_cndmask_b32_e64 v2, v19, v23, s[0:1]
	v_add_f32_e32 v8, v13, v15
	v_add_f32_e32 v5, v5, v7
	v_fmac_f32_e32 v11, v10, v10
	v_mov_b32_dpp v40, v2 quad_perm:[1,0,3,2] row_mask:0xf bank_mask:0xf
	v_add_f32_e32 v2, v9, v8
	v_add_f32_e32 v1, v1, v5
	v_cndmask_b32_e64 v4, v18, v22, s[0:1]
	v_add_f32_e32 v2, v11, v2
	v_add_f32_e32 v1, v3, v1
	v_mov_b32_dpp v39, v4 quad_perm:[1,0,3,2] row_mask:0xf bank_mask:0xf
	v_add_f32_e32 v4, v2, v1
	ds_bpermute_b32 v5, v114, v4
	v_cndmask_b32_e64 v0, v20, v24, s[0:1]
	v_cndmask_b32_e64 v6, v17, v21, s[0:1]
	v_cndmask_b32_e64 v1, v39, v18, s[0:1]
	v_mov_b32_dpp v41, v0 quad_perm:[1,0,3,2] row_mask:0xf bank_mask:0xf
	v_mov_b32_dpp v38, v6 quad_perm:[1,0,3,2] row_mask:0xf bank_mask:0xf
	v_cndmask_b32_e64 v0, v38, v17, s[0:1]
	v_cndmask_b32_e64 v2, v40, v19, s[0:1]
	v_cndmask_b32_e64 v3, v41, v20, s[0:1]
	global_store_dwordx4 v[26:27], v[0:3], off
	s_waitcnt lgkmcnt(0)
	s_nop 0
	v_add_f32_e32 v0, v4, v5
	ds_bpermute_b32 v1, v115, v0
	v_cndmask_b32_e64 v2, v21, v38, s[0:1]
	v_cndmask_b32_e64 v3, v22, v39, s[0:1]
	v_cndmask_b32_e64 v4, v23, v40, s[0:1]
	v_cndmask_b32_e64 v5, v24, v41, s[0:1]
	global_store_dwordx4 v[28:29], v[2:5], off
	s_and_saveexec_b64 s[22:23], s[2:3]
	s_cbranch_execz .LBB0_1269
	v_ashrrev_i32_e32 v17, 31, v16
	v_lshl_add_u64 v[2:3], v[16:17], 2, s[12:13]
	s_waitcnt lgkmcnt(0)
	v_add_f32_e32 v0, v0, v1
	global_atomic_add_f32 v[2:3], v0, off

;     __device__ __forceinline__ void operator()(f32x4 (&acc)[2][2][4][2], const Unit& u, int wr, int wc, int fr_in, int fq_in) const {
;     ...
;         const int tid = (wr * 4 + wc) * 64 + fq * 16 + fr;
;         if (tid < 256) RS[tid] = __builtin_amdgcn_rsqf(ss[u.pm * BM + tid] * (1.0f / DM) + RMS_EPS);
;         asm volatile("s_waitcnt vmcnt(0) lgkmcnt(0)" ::: "memory"); __builtin_amdgcn_s_barrier(); asm volatile("" ::: "memory");
;         const int lr0 = wr * 64 + fr, row0 = u.pm * BM + lr0, col0 = u.pn * BM + wc * 64 + 16 * fq;
; #pragma unroll
;         for (int ai = 0; ai < 2; ++ai)
; #pragma unroll
;             for (int m = 0; m < 4; ++m) { const float rs = RS[lr0 + ai * HALF + m * 16];
; #pragma unroll
;                 for (int bj = 0; bj < 2; ++bj)
; #pragma unroll
;                     for (int n = 0; n < 2; ++n) acc[ai][bj][m][n] *= rs; }
;         if (u.pn < 5) {
.LBB0_1344:
	s_or_b64 exec, exec, s[4:5]
	v_or_b32_e32 v178, s46, v176
	v_lshl_add_u32 v140, v178, 2, 0
	s_waitcnt vmcnt(0) lgkmcnt(0)
	s_barrier
	v_add_u32_e32 v140, 0x21000, v140
	ds_read2_b32 v[152:153], v140 offset1:16
	ds_read2_b32 v[166:167], v140 offset0:32 offset1:48
	s_lshl_b32 s4, s26, 8
	s_or_b32 s4, s4, s48
	v_add_u32_e32 v175, s17, v178
	s_waitcnt lgkmcnt(0)
	v_pk_mul_f32 v[150:151], v[104:105], v[152:153] op_sel_hi:[1,0]
	v_mov_b32_e32 v104, v153
	v_pk_mul_f32 v[160:161], v[126:127], v[152:153] op_sel_hi:[1,0]
	v_pk_mul_f32 v[162:163], v[124:125], v[152:153] op_sel_hi:[1,0]
	v_pk_mul_f32 v[158:159], v[122:123], v[152:153] op_sel_hi:[1,0]
	v_pk_mul_f32 v[164:165], v[120:121], v[152:153] op_sel_hi:[1,0]
	v_pk_mul_f32 v[154:155], v[110:111], v[152:153] op_sel_hi:[1,0]
	v_pk_mul_f32 v[156:157], v[108:109], v[152:153] op_sel_hi:[1,0]
	v_pk_mul_f32 v[126:127], v[106:107], v[152:153] op_sel_hi:[1,0]
	v_pk_mul_f32 v[124:125], v[118:119], v[104:105] op_sel_hi:[1,0]
	v_pk_mul_f32 v[152:153], v[116:117], v[104:105] op_sel_hi:[1,0]
	v_pk_mul_f32 v[120:121], v[114:115], v[104:105] op_sel_hi:[1,0]
	v_pk_mul_f32 v[122:123], v[112:113], v[104:105] op_sel_hi:[1,0]
	v_pk_mul_f32 v[116:117], v[94:95], v[104:105] op_sel_hi:[1,0]
	v_pk_mul_f32 v[118:119], v[92:93], v[104:105] op_sel_hi:[1,0]
	v_pk_mul_f32 v[112:113], v[90:91], v[104:105] op_sel_hi:[1,0]
	v_pk_mul_f32 v[114:115], v[88:89], v[104:105] op_sel_hi:[1,0]
	v_pk_mul_f32 v[108:109], v[102:103], v[166:167] op_sel_hi:[1,0]
	v_pk_mul_f32 v[110:111], v[100:101], v[166:167] op_sel_hi:[1,0]
	v_pk_mul_f32 v[104:105], v[98:99], v[166:167] op_sel_hi:[1,0]
	v_pk_mul_f32 v[106:107], v[96:97], v[166:167] op_sel_hi:[1,0]
	v_pk_mul_f32 v[100:101], v[78:79], v[166:167] op_sel_hi:[1,0]
	v_pk_mul_f32 v[102:103], v[76:77], v[166:167] op_sel_hi:[1,0]
	v_pk_mul_f32 v[96:97], v[74:75], v[166:167] op_sel_hi:[1,0]
	v_pk_mul_f32 v[98:99], v[72:73], v[166:167] op_sel_hi:[1,0]
	v_mov_b32_e32 v72, v167
	ds_read2_b32 v[166:167], v140 offset0:128 offset1:144
	v_pk_mul_f32 v[92:93], v[86:87], v[72:73] op_sel_hi:[1,0]
	v_pk_mul_f32 v[94:95], v[84:85], v[72:73] op_sel_hi:[1,0]
	v_pk_mul_f32 v[88:89], v[82:83], v[72:73] op_sel_hi:[1,0]
	v_pk_mul_f32 v[90:91], v[80:81], v[72:73] op_sel_hi:[1,0]
	v_pk_mul_f32 v[84:85], v[70:71], v[72:73] op_sel_hi:[1,0]
	v_pk_mul_f32 v[86:87], v[68:69], v[72:73] op_sel_hi:[1,0]
	v_pk_mul_f32 v[80:81], v[66:67], v[72:73] op_sel_hi:[1,0]
	v_pk_mul_f32 v[82:83], v[64:65], v[72:73] op_sel_hi:[1,0]
	s_waitcnt lgkmcnt(0)
	v_pk_mul_f32 v[76:77], v[62:63], v[166:167] op_sel_hi:[1,0]
	v_pk_mul_f32 v[78:79], v[60:61], v[166:167] op_sel_hi:[1,0]
	v_pk_mul_f32 v[72:73], v[58:59], v[166:167] op_sel_hi:[1,0]
	v_pk_mul_f32 v[74:75], v[56:57], v[166:167] op_sel_hi:[1,0]
	v_pk_mul_f32 v[68:69], v[46:47], v[166:167] op_sel_hi:[1,0]
	v_pk_mul_f32 v[70:71], v[44:45], v[166:167] op_sel_hi:[1,0]
	v_pk_mul_f32 v[64:65], v[42:43], v[166:167] op_sel_hi:[1,0]
	v_pk_mul_f32 v[66:67], v[40:41], v[166:167] op_sel_hi:[1,0]
	v_mov_b32_e32 v40, v167
	ds_read2_b32 v[166:167], v140 offset0:160 offset1:176
	v_pk_mul_f32 v[60:61], v[54:55], v[40:41] op_sel_hi:[1,0]
	v_pk_mul_f32 v[62:63], v[52:53], v[40:41] op_sel_hi:[1,0]
	v_pk_mul_f32 v[56:57], v[50:51], v[40:41] op_sel_hi:[1,0]
	v_pk_mul_f32 v[58:59], v[48:49], v[40:41] op_sel_hi:[1,0]
	v_pk_mul_f32 v[52:53], v[30:31], v[40:41] op_sel_hi:[1,0]
	v_pk_mul_f32 v[54:55], v[28:29], v[40:41] op_sel_hi:[1,0]
	v_pk_mul_f32 v[48:49], v[26:27], v[40:41] op_sel_hi:[1,0]
	v_pk_mul_f32 v[50:51], v[24:25], v[40:41] op_sel_hi:[1,0]
	s_waitcnt lgkmcnt(0)
	v_pk_mul_f32 v[44:45], v[38:39], v[166:167] op_sel_hi:[1,0]
	v_pk_mul_f32 v[46:47], v[36:37], v[166:167] op_sel_hi:[1,0]
	v_pk_mul_f32 v[40:41], v[34:35], v[166:167] op_sel_hi:[1,0]
	v_pk_mul_f32 v[42:43], v[32:33], v[166:167] op_sel_hi:[1,0]
	v_pk_mul_f32 v[36:37], v[14:15], v[166:167] op_sel_hi:[1,0]
	v_pk_mul_f32 v[38:39], v[12:13], v[166:167] op_sel_hi:[1,0]
	v_pk_mul_f32 v[32:33], v[10:11], v[166:167] op_sel_hi:[1,0]
	v_pk_mul_f32 v[34:35], v[8:9], v[166:167] op_sel_hi:[1,0]
	v_mov_b32_e32 v8, v167
	v_add_u32_e32 v166, s4, v177
	v_and_b32_e32 v174, 1, v179
	v_pk_mul_f32 v[28:29], v[22:23], v[8:9] op_sel_hi:[1,0]
	v_pk_mul_f32 v[30:31], v[20:21], v[8:9] op_sel_hi:[1,0]
	v_pk_mul_f32 v[24:25], v[18:19], v[8:9] op_sel_hi:[1,0]
	v_pk_mul_f32 v[26:27], v[16:17], v[8:9] op_sel_hi:[1,0]
	v_pk_mul_f32 v[20:21], v[6:7], v[8:9] op_sel_hi:[1,0]
	v_pk_mul_f32 v[22:23], v[4:5], v[8:9] op_sel_hi:[1,0]
	v_pk_mul_f32 v[16:17], v[2:3], v[8:9] op_sel_hi:[1,0]
	v_pk_mul_f32 v[18:19], v[0:1], v[8:9] op_sel_hi:[1,0]
	s_mov_b64 s[4:5], -1
	s_cmp_lt_i32 s26, 5
	v_ashrrev_i32_e32 v167, 31, v166
	v_cmp_eq_u32_e32 vcc, 0, v174
	v_sub_u32_e32 v186, v175, v174
	v_lshlrev_b32_e32 v140, 4, v174
	s_cbranch_scc1 .LBB0_1346
; __device__ __forceinline__ unsigned cvt_pk_bf16(float lo, float hi) { unsigned r; asm volatile("v_cvt_pk_bf16_f32 %0, %1, %2" : "=v"(r) : "v"(lo), "v"(hi)); return r; }
; __device__ __forceinline__ unsigned dpp_xor1(unsigned v) { return (unsigned)__builtin_amdgcn_update_dpp(0, (int)v, 0xB1, 0xf, 0xf, false); }
; __device__ __forceinline__ float dpp_xor1(float v) { return __int_as_float(__builtin_amdgcn_update_dpp(0, __float_as_int(v), 0xB1, 0xf, 0xf, false)); }
; __device__ __forceinline__ void store_pair_rows(bf16_t* O, size_t ldc, int row, int col0, int fr, u32x4 p0, u32x4 p1) {
;     const bool odd = (fr & 1) != 0;
;     const u32x4 snd = odd ? p0 : p1; u32x4 rcv;
;     rcv.x = dpp_xor1(snd.x); rcv.y = dpp_xor1(snd.y); rcv.z = dpp_xor1(snd.z); rcv.w = dpp_xor1(snd.w);
;     bf16_t* pa = O + (size_t)(row - (odd ? 1 : 0)) * ldc + col0 + (odd ? 8 : 0);
;     *(u32x4*)pa = odd ? rcv : p0;
;     *(u32x4*)(pa + ldc) = odd ? p1 : rcv;
; }
;     __device__ __forceinline__ void operator()(f32x4 (&acc)[2][2][4][2], const Unit& u, int wr, int wc, int fr_in, int fq_in) const {
;     ...
; #pragma unroll
;         for (int ai = 0; ai < 2; ++ai)
; #pragma unroll
;             for (int m = 0; m < 4; ++m) { u32x4 pw[2];
; #pragma unroll
;                 for (int bj = 0; bj < 2; ++bj) { const f32x4 v0 = acc[ai][bj][m][0], v1 = acc[ai][bj][m][1];
;                     pw[bj].x = cvt_pk_bf16(v0[0], v0[1]); pw[bj].y = cvt_pk_bf16(v0[2], v0[3]); pw[bj].z = cvt_pk_bf16(v1[0], v1[1]); pw[bj].w = cvt_pk_bf16(v1[2], v1[3]); }
;                 store_pair_rows(O, (size_t)ldc, row0 + ai * HALF + m * 16, col0, fr, pw[0], pw[1]); }
	v_readlane_b32 s4, v254, 15
	v_cvt_pk_bf16_f32 v6, v162, v163
	v_cvt_pk_bf16_f32 v7, v160, v161
	v_cvt_pk_bf16_f32 v10, v164, v165
	v_cvt_pk_bf16_f32 v11, v158, v159
	v_cvt_pk_bf16_f32 v12, v156, v157
	v_cvt_pk_bf16_f32 v13, v154, v155
	v_cvt_pk_bf16_f32 v14, v150, v151
	v_cvt_pk_bf16_f32 v15, v126, v127
	v_cndmask_b32_e32 v0, v11, v15, vcc
	v_cndmask_b32_e32 v1, v10, v14, vcc
	v_readlane_b32 s5, v254, 16
	v_cndmask_b32_e32 v2, v7, v13, vcc
	v_cndmask_b32_e32 v3, v6, v12, vcc
	v_mov_b32_dpp v182, v1 quad_perm:[1,0,3,2] row_mask:0xf bank_mask:0xf
	v_mov_b32_dpp v183, v0 quad_perm:[1,0,3,2] row_mask:0xf bank_mask:0xf
	v_mov_b64_e32 v[0:1], s[4:5]
	v_mov_b32_dpp v180, v3 quad_perm:[1,0,3,2] row_mask:0xf bank_mask:0xf
	v_mov_b32_dpp v181, v2 quad_perm:[1,0,3,2] row_mask:0xf bank_mask:0xf
	v_mad_i64_i32 v[4:5], s[4:5], v186, s61, v[0:1]
	v_lshlrev_b64 v[2:3], 1, v[166:167]
	v_lshl_add_u64 v[4:5], v[4:5], 0, v[2:3]
	v_lshl_add_u64 v[8:9], v[4:5], 0, v[140:141]
	v_cndmask_b32_e32 v4, v180, v6, vcc
	v_cndmask_b32_e32 v5, v181, v7, vcc
	v_cndmask_b32_e32 v6, v182, v10, vcc
	v_cndmask_b32_e32 v7, v183, v11, vcc
	global_store_dwordx4 v[8:9], v[4:7], off
	v_add_co_u32_e64 v8, s[4:5], s41, v8
	s_nop 0
	v_cndmask_b32_e32 v4, v12, v180, vcc
	v_cndmask_b32_e32 v5, v13, v181, vcc
	v_cndmask_b32_e32 v6, v14, v182, vcc
	v_cndmask_b32_e32 v7, v15, v183, vcc
	v_addc_co_u32_e64 v9, s[4:5], 0, v9, s[4:5]
	global_store_dwordx4 v[8:9], v[4:7], off offset:1024
	s_nop 1
	v_cvt_pk_bf16_f32 v6, v152, v153
	v_cvt_pk_bf16_f32 v7, v124, v125
	v_cvt_pk_bf16_f32 v10, v122, v123
	v_cvt_pk_bf16_f32 v11, v120, v121
	v_cvt_pk_bf16_f32 v12, v118, v119
	v_cvt_pk_bf16_f32 v13, v116, v117
	v_cvt_pk_bf16_f32 v14, v114, v115
	v_cvt_pk_bf16_f32 v15, v112, v113
	v_cndmask_b32_e32 v4, v11, v15, vcc
	v_cndmask_b32_e32 v5, v10, v14, vcc
	v_cndmask_b32_e32 v8, v7, v13, vcc
	v_mov_b32_dpp v183, v4 quad_perm:[1,0,3,2] row_mask:0xf bank_mask:0xf
	v_add_u32_e32 v4, 16, v186
	v_cndmask_b32_e32 v9, v6, v12, vcc
	v_mov_b32_dpp v182, v5 quad_perm:[1,0,3,2] row_mask:0xf bank_mask:0xf
	v_mad_i64_i32 v[4:5], s[4:5], v4, s61, v[0:1]
	v_mov_b32_dpp v180, v9 quad_perm:[1,0,3,2] row_mask:0xf bank_mask:0xf
	v_mov_b32_dpp v181, v8 quad_perm:[1,0,3,2] row_mask:0xf bank_mask:0xf
	v_lshl_add_u64 v[4:5], v[4:5], 0, v[2:3]
	v_lshl_add_u64 v[8:9], v[4:5], 0, v[140:141]
	v_cndmask_b32_e32 v4, v180, v6, vcc
	v_cndmask_b32_e32 v5, v181, v7, vcc
	v_cndmask_b32_e32 v6, v182, v10, vcc
	v_cndmask_b32_e32 v7, v183, v11, vcc
	global_store_dwordx4 v[8:9], v[4:7], off
	v_add_co_u32_e64 v8, s[4:5], s41, v8
	s_nop 0
	v_cndmask_b32_e32 v4, v12, v180, vcc
	v_cndmask_b32_e32 v5, v13, v181, vcc
	v_cndmask_b32_e32 v6, v14, v182, vcc
	v_cndmask_b32_e32 v7, v15, v183, vcc
	v_addc_co_u32_e64 v9, s[4:5], 0, v9, s[4:5]
	global_store_dwordx4 v[8:9], v[4:7], off offset:1024
	s_nop 1
	v_cvt_pk_bf16_f32 v6, v110, v111
	v_cvt_pk_bf16_f32 v7, v108, v109
	v_cvt_pk_bf16_f32 v10, v106, v107
	v_cvt_pk_bf16_f32 v11, v104, v105
	v_cvt_pk_bf16_f32 v12, v102, v103
	v_cvt_pk_bf16_f32 v13, v100, v101
	v_cvt_pk_bf16_f32 v14, v98, v99
	v_cvt_pk_bf16_f32 v15, v96, v97
	v_cndmask_b32_e32 v4, v11, v15, vcc
	v_cndmask_b32_e32 v5, v10, v14, vcc
	v_cndmask_b32_e32 v8, v7, v13, vcc
	v_mov_b32_dpp v183, v4 quad_perm:[1,0,3,2] row_mask:0xf bank_mask:0xf
	v_add_u32_e32 v4, 32, v186
	v_cndmask_b32_e32 v9, v6, v12, vcc
	v_mov_b32_dpp v182, v5 quad_perm:[1,0,3,2] row_mask:0xf bank_mask:0xf
	v_mad_i64_i32 v[4:5], s[4:5], v4, s61, v[0:1]
	v_mov_b32_dpp v180, v9 quad_perm:[1,0,3,2] row_mask:0xf bank_mask:0xf
	v_mov_b32_dpp v181, v8 quad_perm:[1,0,3,2] row_mask:0xf bank_mask:0xf
	v_lshl_add_u64 v[4:5], v[4:5], 0, v[2:3]
	v_lshl_add_u64 v[8:9], v[4:5], 0, v[140:141]
	v_cndmask_b32_e32 v4, v180, v6, vcc
	v_cndmask_b32_e32 v5, v181, v7, vcc
	v_cndmask_b32_e32 v6, v182, v10, vcc
	v_cndmask_b32_e32 v7, v183, v11, vcc
	global_store_dwordx4 v[8:9], v[4:7], off
	v_add_co_u32_e64 v8, s[4:5], s41, v8
	s_nop 0
	v_cndmask_b32_e32 v4, v12, v180, vcc
	v_cndmask_b32_e32 v5, v13, v181, vcc
	v_cndmask_b32_e32 v6, v14, v182, vcc
	v_cndmask_b32_e32 v7, v15, v183, vcc
	v_addc_co_u32_e64 v9, s[4:5], 0, v9, s[4:5]
	global_store_dwordx4 v[8:9], v[4:7], off offset:1024
	s_nop 1
	v_cvt_pk_bf16_f32 v6, v94, v95
	v_cvt_pk_bf16_f32 v7, v92, v93
	v_cvt_pk_bf16_f32 v10, v90, v91
	v_cvt_pk_bf16_f32 v11, v88, v89
	v_cvt_pk_bf16_f32 v12, v86, v87
	v_cvt_pk_bf16_f32 v13, v84, v85
	v_cvt_pk_bf16_f32 v14, v82, v83
	v_cvt_pk_bf16_f32 v15, v80, v81
	v_cndmask_b32_e32 v4, v11, v15, vcc
	v_cndmask_b32_e32 v5, v10, v14, vcc
	v_cndmask_b32_e32 v8, v7, v13, vcc
	v_mov_b32_dpp v183, v4 quad_perm:[1,0,3,2] row_mask:0xf bank_mask:0xf
	v_add_u32_e32 v4, 48, v186
	v_cndmask_b32_e32 v9, v6, v12, vcc
	v_mov_b32_dpp v182, v5 quad_perm:[1,0,3,2] row_mask:0xf bank_mask:0xf
	v_mad_i64_i32 v[4:5], s[4:5], v4, s61, v[0:1]
	v_mov_b32_dpp v180, v9 quad_perm:[1,0,3,2] row_mask:0xf bank_mask:0xf
	v_mov_b32_dpp v181, v8 quad_perm:[1,0,3,2] row_mask:0xf bank_mask:0xf
	v_lshl_add_u64 v[4:5], v[4:5], 0, v[2:3]
	v_lshl_add_u64 v[8:9], v[4:5], 0, v[140:141]
	v_cndmask_b32_e32 v4, v180, v6, vcc
	v_cndmask_b32_e32 v5, v181, v7, vcc
	v_cndmask_b32_e32 v6, v182, v10, vcc
	v_cndmask_b32_e32 v7, v183, v11, vcc
	global_store_dwordx4 v[8:9], v[4:7], off
	v_add_co_u32_e64 v8, s[4:5], s41, v8
	s_nop 0
	v_cndmask_b32_e32 v4, v12, v180, vcc
	v_cndmask_b32_e32 v5, v13, v181, vcc
	v_cndmask_b32_e32 v6, v14, v182, vcc
	v_cndmask_b32_e32 v7, v15, v183, vcc
	v_addc_co_u32_e64 v9, s[4:5], 0, v9, s[4:5]
; __device__ __forceinline__ unsigned cvt_pk_bf16(float lo, float hi) { unsigned r; asm volatile("v_cvt_pk_bf16_f32 %0, %1, %2" : "=v"(r) : "v"(lo), "v"(hi)); return r; }
; __device__ __forceinline__ unsigned dpp_xor1(unsigned v) { return (unsigned)__builtin_amdgcn_update_dpp(0, (int)v, 0xB1, 0xf, 0xf, false); }
; __device__ __forceinline__ float dpp_xor1(float v) { return __int_as_float(__builtin_amdgcn_update_dpp(0, __float_as_int(v), 0xB1, 0xf, 0xf, false)); }
; __device__ __forceinline__ void store_pair_rows(bf16_t* O, size_t ldc, int row, int col0, int fr, u32x4 p0, u32x4 p1) {
;     const bool odd = (fr & 1) != 0;
;     const u32x4 snd = odd ? p0 : p1; u32x4 rcv;
;     rcv.x = dpp_xor1(snd.x); rcv.y = dpp_xor1(snd.y); rcv.z = dpp_xor1(snd.z); rcv.w = dpp_xor1(snd.w);
;     bf16_t* pa = O + (size_t)(row - (odd ? 1 : 0)) * ldc + col0 + (odd ? 8 : 0);
;     *(u32x4*)pa = odd ? rcv : p0;
;     *(u32x4*)(pa + ldc) = odd ? p1 : rcv;
;     __device__ __forceinline__ void operator()(f32x4 (&acc)[2][2][4][2], const Unit& u, int wr, int wc, int fr_in, int fq_in) const {
;     ...
; #pragma unroll
;         for (int ai = 0; ai < 2; ++ai)
; #pragma unroll
;             for (int m = 0; m < 4; ++m) { u32x4 pw[2];
; #pragma unroll
;                 for (int bj = 0; bj < 2; ++bj) { const f32x4 v0 = acc[ai][bj][m][0], v1 = acc[ai][bj][m][1];
;                     pw[bj].x = cvt_pk_bf16(v0[0], v0[1]); pw[bj].y = cvt_pk_bf16(v0[2], v0[3]); pw[bj].z = cvt_pk_bf16(v1[0], v1[1]); pw[bj].w = cvt_pk_bf16(v1[2], v1[3]); }
;                 store_pair_rows(O, (size_t)ldc, row0 + ai * HALF + m * 16, col0, fr, pw[0], pw[1]); }
	global_store_dwordx4 v[8:9], v[4:7], off offset:1024
	s_nop 1
	v_add_u32_e32 v4, 0x80, v186
	v_cvt_pk_bf16_f32 v6, v78, v79
	v_cvt_pk_bf16_f32 v7, v76, v77
	v_cvt_pk_bf16_f32 v10, v74, v75
	v_cvt_pk_bf16_f32 v11, v72, v73
	v_cvt_pk_bf16_f32 v12, v70, v71
	v_cvt_pk_bf16_f32 v13, v68, v69
	v_cvt_pk_bf16_f32 v14, v66, v67
	v_cvt_pk_bf16_f32 v15, v64, v65
	v_cndmask_b32_e32 v5, v11, v15, vcc
	v_cndmask_b32_e32 v180, v6, v12, vcc
	v_cndmask_b32_e32 v8, v10, v14, vcc
	v_cndmask_b32_e32 v9, v7, v13, vcc
	v_mov_b32_dpp v181, v180 quad_perm:[1,0,3,2] row_mask:0xf bank_mask:0xf
	v_mov_b32_dpp v183, v5 quad_perm:[1,0,3,2] row_mask:0xf bank_mask:0xf
	v_mad_i64_i32 v[4:5], s[4:5], v4, s61, v[0:1]
	v_mov_b32_dpp v180, v9 quad_perm:[1,0,3,2] row_mask:0xf bank_mask:0xf
	v_mov_b32_dpp v182, v8 quad_perm:[1,0,3,2] row_mask:0xf bank_mask:0xf
	v_lshl_add_u64 v[4:5], v[4:5], 0, v[2:3]
	v_lshl_add_u64 v[8:9], v[4:5], 0, v[140:141]
	v_cndmask_b32_e32 v4, v181, v6, vcc
	v_cndmask_b32_e32 v5, v180, v7, vcc
	v_cndmask_b32_e32 v6, v182, v10, vcc
	v_cndmask_b32_e32 v7, v183, v11, vcc
	global_store_dwordx4 v[8:9], v[4:7], off
	v_add_co_u32_e64 v8, s[4:5], s41, v8
	s_nop 0
	v_cndmask_b32_e32 v4, v12, v181, vcc
	v_cndmask_b32_e32 v5, v13, v180, vcc
	v_cndmask_b32_e32 v6, v14, v182, vcc
	v_cndmask_b32_e32 v7, v15, v183, vcc
	v_addc_co_u32_e64 v9, s[4:5], 0, v9, s[4:5]
	global_store_dwordx4 v[8:9], v[4:7], off offset:1024
	s_nop 1
	v_cvt_pk_bf16_f32 v6, v62, v63
	v_cvt_pk_bf16_f32 v7, v60, v61
	v_cvt_pk_bf16_f32 v10, v58, v59
	v_cvt_pk_bf16_f32 v11, v56, v57
	v_cvt_pk_bf16_f32 v12, v54, v55
	v_cvt_pk_bf16_f32 v13, v52, v53
	v_cvt_pk_bf16_f32 v14, v50, v51
	v_cvt_pk_bf16_f32 v15, v48, v49
	v_cndmask_b32_e32 v4, v11, v15, vcc
	v_cndmask_b32_e32 v5, v10, v14, vcc
	v_cndmask_b32_e32 v8, v7, v13, vcc
	v_mov_b32_dpp v183, v4 quad_perm:[1,0,3,2] row_mask:0xf bank_mask:0xf
	v_add_u32_e32 v4, 0x90, v186
	v_cndmask_b32_e32 v9, v6, v12, vcc
	v_mov_b32_dpp v182, v5 quad_perm:[1,0,3,2] row_mask:0xf bank_mask:0xf
	v_mad_i64_i32 v[4:5], s[4:5], v4, s61, v[0:1]
	v_mov_b32_dpp v180, v9 quad_perm:[1,0,3,2] row_mask:0xf bank_mask:0xf
	v_mov_b32_dpp v181, v8 quad_perm:[1,0,3,2] row_mask:0xf bank_mask:0xf
	v_lshl_add_u64 v[4:5], v[4:5], 0, v[2:3]
	v_lshl_add_u64 v[8:9], v[4:5], 0, v[140:141]
	v_cndmask_b32_e32 v4, v180, v6, vcc
	v_cndmask_b32_e32 v5, v181, v7, vcc
	v_cndmask_b32_e32 v6, v182, v10, vcc
	v_cndmask_b32_e32 v7, v183, v11, vcc
	global_store_dwordx4 v[8:9], v[4:7], off
	v_add_co_u32_e64 v8, s[4:5], s41, v8
	s_nop 0
	v_cndmask_b32_e32 v4, v12, v180, vcc
	v_cndmask_b32_e32 v5, v13, v181, vcc
	v_cndmask_b32_e32 v6, v14, v182, vcc
	v_cndmask_b32_e32 v7, v15, v183, vcc
	v_addc_co_u32_e64 v9, s[4:5], 0, v9, s[4:5]
	global_store_dwordx4 v[8:9], v[4:7], off offset:1024
	s_nop 1
	v_cvt_pk_bf16_f32 v6, v46, v47
	v_cvt_pk_bf16_f32 v7, v44, v45
	v_cvt_pk_bf16_f32 v10, v42, v43
	v_cvt_pk_bf16_f32 v11, v40, v41
	v_cvt_pk_bf16_f32 v12, v38, v39
	v_cvt_pk_bf16_f32 v13, v36, v37
	v_cvt_pk_bf16_f32 v14, v34, v35
	v_cvt_pk_bf16_f32 v15, v32, v33
	v_cndmask_b32_e32 v4, v11, v15, vcc
	v_cndmask_b32_e32 v5, v10, v14, vcc
	v_cndmask_b32_e32 v8, v7, v13, vcc
	v_mov_b32_dpp v183, v4 quad_perm:[1,0,3,2] row_mask:0xf bank_mask:0xf
	v_add_u32_e32 v4, 0xa0, v186
	v_cndmask_b32_e32 v9, v6, v12, vcc
	v_mov_b32_dpp v182, v5 quad_perm:[1,0,3,2] row_mask:0xf bank_mask:0xf
	v_mad_i64_i32 v[4:5], s[4:5], v4, s61, v[0:1]
	v_mov_b32_dpp v180, v9 quad_perm:[1,0,3,2] row_mask:0xf bank_mask:0xf
	v_mov_b32_dpp v181, v8 quad_perm:[1,0,3,2] row_mask:0xf bank_mask:0xf
	v_lshl_add_u64 v[4:5], v[4:5], 0, v[2:3]
	v_lshl_add_u64 v[8:9], v[4:5], 0, v[140:141]
	v_cndmask_b32_e32 v4, v180, v6, vcc
	v_cndmask_b32_e32 v5, v181, v7, vcc
	v_cndmask_b32_e32 v6, v182, v10, vcc
	v_cndmask_b32_e32 v7, v183, v11, vcc
	global_store_dwordx4 v[8:9], v[4:7], off
	v_add_co_u32_e64 v8, s[4:5], s41, v8
	s_nop 0
	v_cndmask_b32_e32 v4, v12, v180, vcc
	v_cndmask_b32_e32 v5, v13, v181, vcc
	v_cndmask_b32_e32 v6, v14, v182, vcc
	v_cndmask_b32_e32 v7, v15, v183, vcc
	v_addc_co_u32_e64 v9, s[4:5], 0, v9, s[4:5]
	global_store_dwordx4 v[8:9], v[4:7], off offset:1024
	s_nop 1
	v_cvt_pk_bf16_f32 v6, v30, v31
	v_cvt_pk_bf16_f32 v7, v28, v29
	v_cvt_pk_bf16_f32 v8, v26, v27
	v_cvt_pk_bf16_f32 v9, v24, v25
	v_cvt_pk_bf16_f32 v10, v22, v23
	v_cvt_pk_bf16_f32 v11, v20, v21
	v_cvt_pk_bf16_f32 v12, v18, v19
	v_cvt_pk_bf16_f32 v13, v16, v17
	s_nop 0
	v_cndmask_b32_e32 v4, v9, v13, vcc
	v_cndmask_b32_e32 v15, v6, v10, vcc
	v_cndmask_b32_e32 v14, v7, v11, vcc
	v_mov_b32_dpp v181, v4 quad_perm:[1,0,3,2] row_mask:0xf bank_mask:0xf
	v_mov_b32_dpp v180, v15 quad_perm:[1,0,3,2] row_mask:0xf bank_mask:0xf
	v_add_u32_e32 v4, 0xb0, v186
	v_cndmask_b32_e32 v5, v8, v12, vcc
	v_mov_b32_dpp v15, v14 quad_perm:[1,0,3,2] row_mask:0xf bank_mask:0xf
	v_mad_i64_i32 v[0:1], s[4:5], v4, s61, v[0:1]
	s_nop 0
	v_mov_b32_dpp v14, v5 quad_perm:[1,0,3,2] row_mask:0xf bank_mask:0xf
	v_lshl_add_u64 v[0:1], v[0:1], 0, v[2:3]
	v_lshl_add_u64 v[4:5], v[0:1], 0, v[140:141]
	v_cndmask_b32_e32 v0, v180, v6, vcc
	v_cndmask_b32_e32 v1, v15, v7, vcc
	v_cndmask_b32_e32 v2, v14, v8, vcc
	v_cndmask_b32_e32 v3, v181, v9, vcc
	global_store_dwordx4 v[4:5], v[0:3], off
	s_mov_b64 s[4:5], 0
	s_nop 0
	v_cndmask_b32_e32 v0, v10, v180, vcc
	v_cndmask_b32_e32 v1, v11, v15, vcc
	v_cndmask_b32_e32 v2, v12, v14, vcc
	v_cndmask_b32_e32 v3, v13, v181, vcc
	v_add_co_u32_e32 v4, vcc, 0x2000, v4
	s_nop 1
	v_addc_co_u32_e32 v5, vcc, 0, v5, vcc
	global_store_dwordx4 v[4:5], v[0:3], off offset:1024

; #define GAS __attribute__((address_space(1)))
; __device__ __forceinline__ unsigned cvt_pk_bf16(float lo, float hi) { unsigned r; asm volatile("v_cvt_pk_bf16_f32 %0, %1, %2" : "=v"(r) : "v"(lo), "v"(hi)); return r; }
;     __device__ __forceinline__ void operator()(f32x4 (&acc)[2][2][4][2], const Unit& u, int wr, int wc, int fr_in, int fq_in) const {
;     ...
;             asm volatile("s_waitcnt lgkmcnt(0)" ::: "memory"); __builtin_amdgcn_s_barrier(); asm volatile("" ::: "memory");
;             const gfp gsrc = (u.pn < 4) ? qn : kn; const int dbase = 64 * (wc & 1) + 16 * fq;
;             f32x4 gg[2][2]; float invf[2][2][2];
; #pragma unroll
;             for (int bj = 0; bj < 2; ++bj)
; #pragma unroll
;                 for (int n = 0; n < 2; ++n) { gg[bj][n] = *(const GAS f32x4*)(gsrc + dbase + 8 * bj + 4 * n);
; #pragma unroll
;                     for (int h = 0; h < 2; ++h) invf[bj][n][h] = __builtin_amdgcn_exp2f(-(float)(2 * (8 * fq + 4 * bj + 2 * n + h)) * (13.287712379549449f / 64.0f)); }
;             const bool colaxis = (wc & 1) != 0;
; #pragma unroll
;             for (int ai = 0; ai < 2; ++ai)
; #pragma unroll
;                 for (int m = 0; m < 4; ++m) { const int lr = lr0 + ai * HALF + m * 16;
;                     const float tot = PS[lr * 4 + wc] + PS[lr * 4 + (wc ^ 1)]; const float r2 = __builtin_amdgcn_rsqf(tot * (1.0f / 128.0f) + RMS_EPS);
;                     const int t = (row0 + ai * HALF + m * 16) & (SEQ - 1); const float pos = colaxis ? (float)(t & 63) : (float)(t >> 6);
;                     u32x4 pw[2];
; #pragma unroll
;                     for (int bj = 0; bj < 2; ++bj) {
; #pragma unroll
;                         for (int n = 0; n < 2; ++n) { f32x4 v = acc[ai][bj][m][n] * r2 * gg[bj][n];
; #pragma unroll
;                             for (int h = 0; h < 2; ++h) { const float rev = pos * invf[bj][n][h] * 0.15915494309189535f; const float sn = __builtin_amdgcn_sinf(rev), cs = __builtin_amdgcn_cosf(rev); const float x0 = v[2 * h], x1 = v[2 * h + 1];
;                                 pw[bj][2 * n + h] = cvt_pk_bf16(x0 * cs - x1 * sn, x0 * sn + x1 * cs); } } }
.LBB0_1363:
	s_or_b64 exec, exec, s[4:5]
	s_cmp_eq_u32 s26, 4
	s_cselect_b32 s4, s35, s33
	s_cselect_b32 s5, s36, s34
	v_add_u32_e32 v2, s50, v177
	v_mov_b32_e32 v0, s5
	s_waitcnt lgkmcnt(0)
	v_mov_b32_e32 v1, s4
	v_ashrrev_i32_e32 v3, 31, v2
	s_waitcnt lgkmcnt(0)
	s_barrier
	v_lshl_add_u64 v[8:9], v[2:3], 2, v[0:1]
	global_load_dwordx4 v[12:15], v[8:9], off
	global_load_dwordx4 v[4:7], v[8:9], off offset:16
	v_or_b32_e32 v0, 2, v177
	v_or_b32_e32 v1, 4, v177
	v_lshlrev_b32_e32 v187, 2, v178
	v_lshl_add_u32 v183, v178, 4, s53
	v_bfe_u32 v178, v175, 6, 6
	v_or_b32_e32 v2, 6, v177
	v_or_b32_e32 v3, 8, v177
	v_or_b32_e32 v10, 10, v177
	v_or_b32_e32 v11, 12, v177
	v_cvt_f32_i32_e32 v180, v0
	v_cvt_f32_i32_e32 v181, v1
	v_bitop3_b32 v0, v187, 1, s45 bitop3:0x36
	s_add_i32 s17, 0, 0x20000
	v_cndmask_b32_e64 v1, v176, v178, s[0:1]
	v_cvt_f32_i32_e32 v182, v2
	v_cvt_f32_i32_e32 v184, v3
	v_cvt_f32_i32_e32 v188, v10
	v_cvt_f32_i32_e32 v189, v11
	v_lshl_add_u32 v178, v0, 2, s17
	v_cvt_f32_ubyte0_e32 v198, v1
	global_load_dwordx4 v[0:3], v[8:9], off offset:48
	s_nop 0
	global_load_dwordx4 v[8:11], v[8:9], off offset:32
	v_cvt_f32_i32_e32 v179, v177
	ds_read_b32 v190, v183
	ds_read_b32 v191, v178
	v_mul_f32_e32 v192, 0xbe549a78, v184
	v_mul_f32_e32 v188, 0xbe549a78, v188
	v_mul_f32_e32 v178, 0xbe549a78, v179
	v_exp_f32_e32 v185, v178
	v_mul_f32_e32 v178, 0xbe549a78, v180
	v_mul_f32_e32 v179, 0xbe549a78, v181
	v_exp_f32_e32 v184, v178
	v_mul_f32_e32 v180, 0xbe549a78, v182
	v_exp_f32_e32 v182, v179
	v_mul_f32_e32 v189, 0xbe549a78, v189
	v_exp_f32_e32 v179, v188
	v_exp_f32_e32 v178, v189
	s_waitcnt lgkmcnt(0)
	v_add_f32_e32 v188, v190, v191
	v_mul_f32_e32 v189, v185, v198
	v_exp_f32_e32 v181, v180
	v_exp_f32_e32 v180, v192
	v_fmamk_f32 v188, v188, 0x3c000000, v172
	v_mul_f32_e32 v189, 0.15915494, v189
	v_mul_f32_e32 v192, v184, v198
	v_rsq_f32_e32 v188, v188
	v_mul_f32_e32 v193, v182, v198
	v_sin_f32_e32 v191, v189
	v_cos_f32_e32 v190, v189
	v_mul_f32_e32 v189, 0.15915494, v192
	v_mul_f32_e32 v199, 0.15915494, v193
	v_sin_f32_e32 v193, v189
	v_cos_f32_e32 v192, v189
	v_pk_mul_f32 v[162:163], v[162:163], v[188:189] op_sel_hi:[1,0]
	v_pk_mul_f32 v[160:161], v[160:161], v[188:189] op_sel_hi:[1,0]
	v_mov_b32_e32 v196, v193
	v_mov_b32_e32 v197, v192
	v_mov_b32_e32 v194, v191
	v_mov_b32_e32 v195, v190
	v_pk_mul_f32 v[164:165], v[164:165], v[188:189] op_sel_hi:[1,0]
	v_or_b32_e32 v177, 14, v177
	v_cvt_f32_i32_e32 v177, v177
	v_cmp_eq_u32_e32 vcc, 0, v174
	v_readlane_b32 s4, v254, 15
	v_readlane_b32 s5, v254, 16
	v_mul_f32_e32 v177, 0xbe549a78, v177
	v_exp_f32_e32 v177, v177
	s_waitcnt vmcnt(0)
	v_pk_mul_f32 v[160:161], v[14:15], v[160:161]
	v_pk_mul_f32 v[162:163], v[12:13], v[162:163]
	v_pk_mul_f32 v[192:193], v[192:193], v[160:161]
	v_pk_mul_f32 v[190:191], v[190:191], v[162:163]
	v_pk_mul_f32 v[160:161], v[196:197], v[160:161]
	v_pk_mul_f32 v[162:163], v[194:195], v[162:163]
	v_sub_f32_e32 v189, v190, v191
	v_add_f32_e32 v160, v160, v161
	v_add_f32_e32 v162, v162, v163
	v_sub_f32_e32 v163, v192, v193
	v_cvt_pk_bf16_f32 v189, v189, v162
	v_cvt_pk_bf16_f32 v190, v163, v160
	v_sin_f32_e32 v161, v199
	v_cos_f32_e32 v160, v199
	v_pk_mul_f32 v[162:163], v[4:5], v[164:165]
	v_pk_mul_f32 v[158:159], v[158:159], v[188:189] op_sel_hi:[1,0]
	v_pk_mul_f32 v[156:157], v[156:157], v[188:189] op_sel_hi:[1,0]
	v_pk_mul_f32 v[164:165], v[160:161], v[162:163]
	v_pk_mul_f32 v[158:159], v[6:7], v[158:159]
	v_sub_f32_e32 v191, v164, v165
	v_mov_b32_e32 v165, v160
	v_mul_f32_e32 v160, v181, v198
	v_mul_f32_e32 v160, 0.15915494, v160
	v_mov_b32_e32 v164, v161
	v_sin_f32_e32 v161, v160
	v_cos_f32_e32 v160, v160
	v_pk_mul_f32 v[162:163], v[164:165], v[162:163]
	v_pk_mul_f32 v[156:157], v[8:9], v[156:157]
	v_add_f32_e32 v162, v162, v163
	v_cvt_pk_bf16_f32 v164, v191, v162
	v_pk_mul_f32 v[162:163], v[160:161], v[158:159]
	v_pk_mul_f32 v[154:155], v[154:155], v[188:189] op_sel_hi:[1,0]
	v_sub_f32_e32 v165, v162, v163
	v_mov_b32_e32 v162, v161
	v_mov_b32_e32 v163, v160
	v_pk_mul_f32 v[158:159], v[162:163], v[158:159]
	v_pk_mul_f32 v[154:155], v[10:11], v[154:155]
	v_add_f32_e32 v158, v158, v159
	v_cvt_pk_bf16_f32 v162, v165, v158
	v_mul_f32_e32 v158, v180, v198
	v_mul_f32_e32 v158, 0.15915494, v158
	v_sin_f32_e32 v159, v158
	v_cos_f32_e32 v158, v158
	v_pk_mul_f32 v[150:151], v[150:151], v[188:189] op_sel_hi:[1,0]
	v_pk_mul_f32 v[126:127], v[126:127], v[188:189] op_sel_hi:[1,0]
	v_pk_mul_f32 v[150:151], v[0:1], v[150:151]
	v_pk_mul_f32 v[160:161], v[158:159], v[156:157]
	v_pk_mul_f32 v[126:127], v[2:3], v[126:127]
	v_sub_f32_e32 v163, v160, v161
	v_mov_b32_e32 v161, v158
	v_mul_f32_e32 v158, v179, v198
	v_mul_f32_e32 v158, 0.15915494, v158
	v_mov_b32_e32 v160, v159
	v_sin_f32_e32 v159, v158
	v_cos_f32_e32 v158, v158
	v_pk_mul_f32 v[156:157], v[160:161], v[156:157]
	v_add_f32_e32 v156, v156, v157
	v_cvt_pk_bf16_f32 v160, v163, v156
	v_pk_mul_f32 v[156:157], v[158:159], v[154:155]
	v_sub_f32_e32 v161, v156, v157
	v_mov_b32_e32 v156, v159
	v_mov_b32_e32 v157, v158
	v_pk_mul_f32 v[154:155], v[156:157], v[154:155]
	v_add_f32_e32 v154, v154, v155
	v_cvt_pk_bf16_f32 v161, v161, v154
	v_mul_f32_e32 v154, v178, v198
	v_mul_f32_e32 v154, 0.15915494, v154
	v_sin_f32_e32 v155, v154
	v_cos_f32_e32 v154, v154
	s_nop 0
	v_pk_mul_f32 v[156:157], v[154:155], v[150:151]
	s_nop 0
	v_sub_f32_e32 v158, v156, v157
	v_mov_b32_e32 v157, v154
	v_mul_f32_e32 v154, v177, v198
	v_mul_f32_e32 v154, 0.15915494, v154
	v_mov_b32_e32 v156, v155
	v_sin_f32_e32 v155, v154
	v_cos_f32_e32 v154, v154
	v_pk_mul_f32 v[150:151], v[156:157], v[150:151]
	s_nop 0
	v_add_f32_e32 v150, v150, v151
	v_cvt_pk_bf16_f32 v163, v158, v150
; __device__ __forceinline__ unsigned cvt_pk_bf16(float lo, float hi) { unsigned r; asm volatile("v_cvt_pk_bf16_f32 %0, %1, %2" : "=v"(r) : "v"(lo), "v"(hi)); return r; }
; __device__ __forceinline__ unsigned dpp_xor1(unsigned v) { return (unsigned)__builtin_amdgcn_update_dpp(0, (int)v, 0xB1, 0xf, 0xf, false); }
; __device__ __forceinline__ float dpp_xor1(float v) { return __int_as_float(__builtin_amdgcn_update_dpp(0, __float_as_int(v), 0xB1, 0xf, 0xf, false)); }
; __device__ __forceinline__ void store_pair_rows(bf16_t* O, size_t ldc, int row, int col0, int fr, u32x4 p0, u32x4 p1) {
;     const bool odd = (fr & 1) != 0;
;     const u32x4 snd = odd ? p0 : p1; u32x4 rcv;
;     rcv.x = dpp_xor1(snd.x); rcv.y = dpp_xor1(snd.y); rcv.z = dpp_xor1(snd.z); rcv.w = dpp_xor1(snd.w);
;     bf16_t* pa = O + (size_t)(row - (odd ? 1 : 0)) * ldc + col0 + (odd ? 8 : 0);
;     *(u32x4*)pa = odd ? rcv : p0;
;     *(u32x4*)(pa + ldc) = odd ? p1 : rcv;
;     __device__ __forceinline__ void operator()(f32x4 (&acc)[2][2][4][2], const Unit& u, int wr, int wc, int fr_in, int fq_in) const {
;     ...
;             for (int ai = 0; ai < 2; ++ai)
; #pragma unroll
;                 for (int m = 0; m < 4; ++m) { const int lr = lr0 + ai * HALF + m * 16;
;                     const float tot = PS[lr * 4 + wc] + PS[lr * 4 + (wc ^ 1)]; const float r2 = __builtin_amdgcn_rsqf(tot * (1.0f / 128.0f) + RMS_EPS);
;                     const int t = (row0 + ai * HALF + m * 16) & (SEQ - 1); const float pos = colaxis ? (float)(t & 63) : (float)(t >> 6);
;                     u32x4 pw[2];
; #pragma unroll
;                     for (int bj = 0; bj < 2; ++bj) {
; #pragma unroll
;                         for (int n = 0; n < 2; ++n) { f32x4 v = acc[ai][bj][m][n] * r2 * gg[bj][n];
; #pragma unroll
;                             for (int h = 0; h < 2; ++h) { const float rev = pos * invf[bj][n][h] * 0.15915494309189535f; const float sn = __builtin_amdgcn_sinf(rev), cs = __builtin_amdgcn_cosf(rev); const float x0 = v[2 * h], x1 = v[2 * h + 1];
;                                 pw[bj][2 * n + h] = cvt_pk_bf16(x0 * cs - x1 * sn, x0 * sn + x1 * cs); } } }
;                     store_pair_rows(O, (size_t)ldc, row0 + ai * HALF + m * 16, col0, fr, pw[0], pw[1]);
	v_pk_mul_f32 v[150:151], v[154:155], v[126:127]
	s_nop 0
	v_sub_f32_e32 v156, v150, v151
	v_mov_b32_e32 v150, v155
	v_mov_b32_e32 v151, v154
	v_pk_mul_f32 v[126:127], v[150:151], v[126:127]
	v_cndmask_b32_e32 v150, v190, v161, vcc
	v_add_f32_e32 v126, v126, v127
	v_cvt_pk_bf16_f32 v165, v156, v126
	v_cndmask_b32_e32 v127, v164, v163, vcc
	v_cndmask_b32_e32 v126, v162, v165, vcc
	v_cndmask_b32_e32 v151, v189, v160, vcc
	v_mov_b32_dpp v192, v127 quad_perm:[1,0,3,2] row_mask:0xf bank_mask:0xf
	v_mov_b32_dpp v193, v126 quad_perm:[1,0,3,2] row_mask:0xf bank_mask:0xf
	v_mov_b64_e32 v[126:127], s[4:5]
	v_mov_b32_dpp v188, v151 quad_perm:[1,0,3,2] row_mask:0xf bank_mask:0xf
	v_mov_b32_dpp v191, v150 quad_perm:[1,0,3,2] row_mask:0xf bank_mask:0xf
	v_mad_i64_i32 v[154:155], s[4:5], v186, s61, v[126:127]
	v_lshlrev_b64 v[150:151], 1, v[166:167]
	v_lshl_add_u64 v[154:155], v[154:155], 0, v[150:151]
	v_lshl_add_u64 v[158:159], v[154:155], 0, v[140:141]
	v_cndmask_b32_e32 v154, v188, v189, vcc
	v_cndmask_b32_e32 v155, v191, v190, vcc
	v_cndmask_b32_e32 v156, v192, v164, vcc
	v_cndmask_b32_e32 v157, v193, v162, vcc
	global_store_dwordx4 v[158:159], v[154:157], off
	v_add_co_u32_e64 v158, s[4:5], s41, v158
	s_nop 0
	v_cndmask_b32_e32 v154, v160, v188, vcc
	v_cndmask_b32_e32 v155, v161, v191, vcc
	v_cndmask_b32_e32 v156, v163, v192, vcc
	v_cndmask_b32_e32 v157, v165, v193, vcc
	v_addc_co_u32_e64 v159, s[4:5], 0, v159, s[4:5]
	global_store_dwordx4 v[158:159], v[154:157], off offset:1024
	v_lshrrev_b32_e32 v160, 6, v175
	s_nop 0
	v_bitop3_b32 v154, v187, 1, s55 bitop3:0x36
	v_lshl_add_u32 v154, v154, 2, s17
	ds_read_b32 v155, v183 offset:256
	ds_read_b32 v154, v154
	s_waitcnt lgkmcnt(0)
	v_add_f32_e32 v154, v155, v154
	v_or_b32_e32 v155, 16, v175
	v_cndmask_b32_e64 v156, v155, v160, s[0:1]
	v_and_b32_e32 v156, 63, v156
	v_fmamk_f32 v154, v154, 0x3c000000, v172
	v_cvt_f32_ubyte0_e32 v161, v156
	v_rsq_f32_e32 v154, v154
	v_mul_f32_e32 v156, v185, v161
	v_mul_f32_e32 v156, 0.15915494, v156
	v_sin_f32_e32 v157, v156
	v_cos_f32_e32 v156, v156
	v_pk_mul_f32 v[152:153], v[152:153], v[154:155] op_sel_hi:[1,0]
	v_pk_mul_f32 v[124:125], v[124:125], v[154:155] op_sel_hi:[1,0]
	v_pk_mul_f32 v[152:153], v[12:13], v[152:153]
	v_pk_mul_f32 v[124:125], v[14:15], v[124:125]
	v_pk_mul_f32 v[158:159], v[156:157], v[152:153]
	v_pk_mul_f32 v[122:123], v[122:123], v[154:155] op_sel_hi:[1,0]
	v_sub_f32_e32 v162, v158, v159
	v_mov_b32_e32 v159, v156
	v_mul_f32_e32 v156, v184, v161
	v_mul_f32_e32 v156, 0.15915494, v156
	v_mov_b32_e32 v158, v157
	v_sin_f32_e32 v157, v156
	v_cos_f32_e32 v156, v156
	v_pk_mul_f32 v[152:153], v[158:159], v[152:153]
	v_pk_mul_f32 v[122:123], v[4:5], v[122:123]
	v_add_f32_e32 v152, v152, v153
	v_cvt_pk_bf16_f32 v158, v162, v152
	v_pk_mul_f32 v[152:153], v[156:157], v[124:125]
	v_pk_mul_f32 v[120:121], v[120:121], v[154:155] op_sel_hi:[1,0]
	v_sub_f32_e32 v159, v152, v153
	v_mov_b32_e32 v152, v157
	v_mov_b32_e32 v153, v156
	v_pk_mul_f32 v[124:125], v[152:153], v[124:125]
	v_pk_mul_f32 v[120:121], v[6:7], v[120:121]
	v_add_f32_e32 v124, v124, v125
	v_cvt_pk_bf16_f32 v156, v159, v124
	v_mul_f32_e32 v124, v182, v161
	v_mul_f32_e32 v124, 0.15915494, v124
	v_sin_f32_e32 v125, v124
	v_cos_f32_e32 v124, v124
	v_pk_mul_f32 v[118:119], v[118:119], v[154:155] op_sel_hi:[1,0]
	v_pk_mul_f32 v[116:117], v[116:117], v[154:155] op_sel_hi:[1,0]
	v_pk_mul_f32 v[118:119], v[8:9], v[118:119]
	v_pk_mul_f32 v[152:153], v[124:125], v[122:123]
	v_pk_mul_f32 v[116:117], v[10:11], v[116:117]
	v_sub_f32_e32 v157, v152, v153
	v_mov_b32_e32 v153, v124
	v_mul_f32_e32 v124, v181, v161
	v_mul_f32_e32 v124, 0.15915494, v124
	v_mov_b32_e32 v152, v125
	v_sin_f32_e32 v125, v124
	v_cos_f32_e32 v124, v124
	v_pk_mul_f32 v[122:123], v[152:153], v[122:123]
	v_pk_mul_f32 v[114:115], v[114:115], v[154:155] op_sel_hi:[1,0]
	v_add_f32_e32 v122, v122, v123
	v_cvt_pk_bf16_f32 v152, v157, v122
	v_pk_mul_f32 v[122:123], v[124:125], v[120:121]
	v_pk_mul_f32 v[114:115], v[0:1], v[114:115]
	v_sub_f32_e32 v153, v122, v123
	v_mov_b32_e32 v122, v125
	v_mov_b32_e32 v123, v124
	v_pk_mul_f32 v[120:121], v[122:123], v[120:121]
	v_pk_mul_f32 v[112:113], v[112:113], v[154:155] op_sel_hi:[1,0]
	v_add_f32_e32 v120, v120, v121
	v_cvt_pk_bf16_f32 v124, v153, v120
	v_mul_f32_e32 v120, v180, v161
	v_mul_f32_e32 v120, 0.15915494, v120
	v_sin_f32_e32 v121, v120
	v_cos_f32_e32 v120, v120
	v_pk_mul_f32 v[112:113], v[2:3], v[112:113]
	v_pk_mul_f32 v[122:123], v[120:121], v[118:119]
	s_nop 0
	v_sub_f32_e32 v125, v122, v123
	v_mov_b32_e32 v123, v120
	v_mul_f32_e32 v120, v179, v161
	v_mul_f32_e32 v120, 0.15915494, v120
	v_mov_b32_e32 v122, v121
	v_sin_f32_e32 v121, v120
	v_cos_f32_e32 v120, v120
	v_pk_mul_f32 v[118:119], v[122:123], v[118:119]
	s_nop 0
	v_add_f32_e32 v118, v118, v119
	v_cvt_pk_bf16_f32 v122, v125, v118
	v_pk_mul_f32 v[118:119], v[120:121], v[116:117]
	v_sub_f32_e32 v123, v118, v119
	v_mov_b32_e32 v118, v121
	v_mov_b32_e32 v119, v120
	v_pk_mul_f32 v[116:117], v[118:119], v[116:117]
	s_nop 0
	v_add_f32_e32 v116, v116, v117
	v_cvt_pk_bf16_f32 v120, v123, v116
	v_mul_f32_e32 v116, v178, v161
	v_mul_f32_e32 v116, 0.15915494, v116
	v_sin_f32_e32 v117, v116
	v_cos_f32_e32 v116, v116
	s_nop 0
	v_pk_mul_f32 v[118:119], v[116:117], v[114:115]
	s_nop 0
	v_sub_f32_e32 v121, v118, v119
	v_mov_b32_e32 v119, v116
	v_mul_f32_e32 v116, v177, v161
	v_mul_f32_e32 v116, 0.15915494, v116
	v_mov_b32_e32 v118, v117
	v_sin_f32_e32 v117, v116
	v_cos_f32_e32 v116, v116
	v_pk_mul_f32 v[114:115], v[118:119], v[114:115]
	s_nop 0
	v_add_f32_e32 v114, v114, v115
	v_cvt_pk_bf16_f32 v118, v121, v114
	v_pk_mul_f32 v[114:115], v[116:117], v[112:113]
; __device__ __forceinline__ unsigned cvt_pk_bf16(float lo, float hi) { unsigned r; asm volatile("v_cvt_pk_bf16_f32 %0, %1, %2" : "=v"(r) : "v"(lo), "v"(hi)); return r; }
; __device__ __forceinline__ unsigned dpp_xor1(unsigned v) { return (unsigned)__builtin_amdgcn_update_dpp(0, (int)v, 0xB1, 0xf, 0xf, false); }
; __device__ __forceinline__ float dpp_xor1(float v) { return __int_as_float(__builtin_amdgcn_update_dpp(0, __float_as_int(v), 0xB1, 0xf, 0xf, false)); }
; __device__ __forceinline__ void store_pair_rows(bf16_t* O, size_t ldc, int row, int col0, int fr, u32x4 p0, u32x4 p1) {
;     const bool odd = (fr & 1) != 0;
;     const u32x4 snd = odd ? p0 : p1; u32x4 rcv;
;     rcv.x = dpp_xor1(snd.x); rcv.y = dpp_xor1(snd.y); rcv.z = dpp_xor1(snd.z); rcv.w = dpp_xor1(snd.w);
;     bf16_t* pa = O + (size_t)(row - (odd ? 1 : 0)) * ldc + col0 + (odd ? 8 : 0);
;     *(u32x4*)pa = odd ? rcv : p0;
;     *(u32x4*)(pa + ldc) = odd ? p1 : rcv;
;     __device__ __forceinline__ void operator()(f32x4 (&acc)[2][2][4][2], const Unit& u, int wr, int wc, int fr_in, int fq_in) const {
;     ...
;             for (int ai = 0; ai < 2; ++ai)
; #pragma unroll
;                 for (int m = 0; m < 4; ++m) { const int lr = lr0 + ai * HALF + m * 16;
;                     const float tot = PS[lr * 4 + wc] + PS[lr * 4 + (wc ^ 1)]; const float r2 = __builtin_amdgcn_rsqf(tot * (1.0f / 128.0f) + RMS_EPS);
;                     const int t = (row0 + ai * HALF + m * 16) & (SEQ - 1); const float pos = colaxis ? (float)(t & 63) : (float)(t >> 6);
;                     u32x4 pw[2];
; #pragma unroll
;                     for (int bj = 0; bj < 2; ++bj) {
; #pragma unroll
;                         for (int n = 0; n < 2; ++n) { f32x4 v = acc[ai][bj][m][n] * r2 * gg[bj][n];
; #pragma unroll
;                             for (int h = 0; h < 2; ++h) { const float rev = pos * invf[bj][n][h] * 0.15915494309189535f; const float sn = __builtin_amdgcn_sinf(rev), cs = __builtin_amdgcn_cosf(rev); const float x0 = v[2 * h], x1 = v[2 * h + 1];
;                                 pw[bj][2 * n + h] = cvt_pk_bf16(x0 * cs - x1 * sn, x0 * sn + x1 * cs); } } }
;                     store_pair_rows(O, (size_t)ldc, row0 + ai * HALF + m * 16, col0, fr, pw[0], pw[1]);
	v_sub_f32_e32 v119, v114, v115
	v_mov_b32_e32 v114, v117
	v_mov_b32_e32 v115, v116
	v_pk_mul_f32 v[112:113], v[114:115], v[112:113]
	v_cndmask_b32_e32 v114, v156, v120, vcc
	v_add_f32_e32 v112, v112, v113
	v_cvt_pk_bf16_f32 v119, v119, v112
	v_cndmask_b32_e32 v113, v152, v118, vcc
	v_cndmask_b32_e32 v112, v124, v119, vcc
	v_cndmask_b32_e32 v115, v158, v122, vcc
	v_mov_b32_dpp v125, v113 quad_perm:[1,0,3,2] row_mask:0xf bank_mask:0xf
	v_mov_b32_dpp v153, v112 quad_perm:[1,0,3,2] row_mask:0xf bank_mask:0xf
	v_sub_u32_e32 v112, v155, v174
	v_mad_i64_i32 v[112:113], s[4:5], v112, s61, v[126:127]
	v_mov_b32_dpp v121, v115 quad_perm:[1,0,3,2] row_mask:0xf bank_mask:0xf
	v_mov_b32_dpp v123, v114 quad_perm:[1,0,3,2] row_mask:0xf bank_mask:0xf
	v_lshl_add_u64 v[112:113], v[112:113], 0, v[150:151]
	v_lshl_add_u64 v[116:117], v[112:113], 0, v[140:141]
	v_cndmask_b32_e32 v112, v121, v158, vcc
	v_cndmask_b32_e32 v113, v123, v156, vcc
	v_cndmask_b32_e32 v114, v125, v152, vcc
	v_cndmask_b32_e32 v115, v153, v124, vcc
	global_store_dwordx4 v[116:117], v[112:115], off
	v_add_co_u32_e64 v116, s[4:5], s41, v116
	s_nop 0
	v_cndmask_b32_e32 v112, v122, v121, vcc
	v_cndmask_b32_e32 v113, v120, v123, vcc
	v_cndmask_b32_e32 v114, v118, v125, vcc
	v_cndmask_b32_e32 v115, v119, v153, vcc
	v_addc_co_u32_e64 v117, s[4:5], 0, v117, s[4:5]
	global_store_dwordx4 v[116:117], v[112:115], off offset:1024
	s_nop 1
	v_bitop3_b32 v112, v187, 1, s56 bitop3:0x36
	v_lshl_add_u32 v112, v112, 2, s17
	ds_read_b32 v113, v183 offset:512
	ds_read_b32 v112, v112
	s_waitcnt lgkmcnt(0)
	v_add_f32_e32 v112, v113, v112
	v_or_b32_e32 v113, 32, v175
	v_cndmask_b32_e64 v114, v113, v160, s[0:1]
	v_and_b32_e32 v114, 63, v114
	v_fmamk_f32 v112, v112, 0x3c000000, v172
	v_cvt_f32_ubyte0_e32 v118, v114
	v_rsq_f32_e32 v112, v112
	v_mul_f32_e32 v114, v185, v118
	v_mul_f32_e32 v114, 0.15915494, v114
	v_sin_f32_e32 v115, v114
	v_cos_f32_e32 v114, v114
	v_pk_mul_f32 v[110:111], v[110:111], v[112:113] op_sel_hi:[1,0]
	v_pk_mul_f32 v[108:109], v[108:109], v[112:113] op_sel_hi:[1,0]
	v_pk_mul_f32 v[110:111], v[12:13], v[110:111]
	v_pk_mul_f32 v[108:109], v[14:15], v[108:109]
	v_pk_mul_f32 v[116:117], v[114:115], v[110:111]
	v_pk_mul_f32 v[106:107], v[106:107], v[112:113] op_sel_hi:[1,0]
	v_sub_f32_e32 v119, v116, v117
	v_mov_b32_e32 v117, v114
	v_mul_f32_e32 v114, v184, v118
	v_mul_f32_e32 v114, 0.15915494, v114
	v_mov_b32_e32 v116, v115
	v_sin_f32_e32 v115, v114
	v_cos_f32_e32 v114, v114
	v_pk_mul_f32 v[110:111], v[116:117], v[110:111]
	v_pk_mul_f32 v[106:107], v[4:5], v[106:107]
	v_add_f32_e32 v110, v110, v111
	v_cvt_pk_bf16_f32 v116, v119, v110
	v_pk_mul_f32 v[110:111], v[114:115], v[108:109]
	v_pk_mul_f32 v[104:105], v[104:105], v[112:113] op_sel_hi:[1,0]
	v_sub_f32_e32 v117, v110, v111
	v_mov_b32_e32 v110, v115
	v_mov_b32_e32 v111, v114
	v_pk_mul_f32 v[108:109], v[110:111], v[108:109]
	v_pk_mul_f32 v[104:105], v[6:7], v[104:105]
	v_add_f32_e32 v108, v108, v109
	v_cvt_pk_bf16_f32 v114, v117, v108
	v_mul_f32_e32 v108, v182, v118
	v_mul_f32_e32 v108, 0.15915494, v108
	v_sin_f32_e32 v109, v108
	v_cos_f32_e32 v108, v108
	v_pk_mul_f32 v[102:103], v[102:103], v[112:113] op_sel_hi:[1,0]
	v_pk_mul_f32 v[100:101], v[100:101], v[112:113] op_sel_hi:[1,0]
	v_pk_mul_f32 v[102:103], v[8:9], v[102:103]
	v_pk_mul_f32 v[110:111], v[108:109], v[106:107]
	v_pk_mul_f32 v[100:101], v[10:11], v[100:101]
	v_sub_f32_e32 v115, v110, v111
	v_mov_b32_e32 v111, v108
	v_mul_f32_e32 v108, v181, v118
	v_mul_f32_e32 v108, 0.15915494, v108
	v_mov_b32_e32 v110, v109
	v_sin_f32_e32 v109, v108
	v_cos_f32_e32 v108, v108
	v_pk_mul_f32 v[106:107], v[110:111], v[106:107]
	v_pk_mul_f32 v[98:99], v[98:99], v[112:113] op_sel_hi:[1,0]
	v_add_f32_e32 v106, v106, v107
	v_cvt_pk_bf16_f32 v110, v115, v106
	v_pk_mul_f32 v[106:107], v[108:109], v[104:105]
	v_pk_mul_f32 v[98:99], v[0:1], v[98:99]
	v_sub_f32_e32 v111, v106, v107
	v_mov_b32_e32 v106, v109
	v_mov_b32_e32 v107, v108
	v_pk_mul_f32 v[104:105], v[106:107], v[104:105]
	v_pk_mul_f32 v[96:97], v[96:97], v[112:113] op_sel_hi:[1,0]
	v_add_f32_e32 v104, v104, v105
	v_cvt_pk_bf16_f32 v108, v111, v104
	v_mul_f32_e32 v104, v180, v118
	v_mul_f32_e32 v104, 0.15915494, v104
	v_sin_f32_e32 v105, v104
	v_cos_f32_e32 v104, v104
	v_pk_mul_f32 v[96:97], v[2:3], v[96:97]
	v_pk_mul_f32 v[106:107], v[104:105], v[102:103]
	s_nop 0
	v_sub_f32_e32 v109, v106, v107
	v_mov_b32_e32 v107, v104
	v_mul_f32_e32 v104, v179, v118
	v_mul_f32_e32 v104, 0.15915494, v104
	v_mov_b32_e32 v106, v105
	v_sin_f32_e32 v105, v104
	v_cos_f32_e32 v104, v104
	v_pk_mul_f32 v[102:103], v[106:107], v[102:103]
	s_nop 0
	v_add_f32_e32 v102, v102, v103
	v_cvt_pk_bf16_f32 v106, v109, v102
	v_pk_mul_f32 v[102:103], v[104:105], v[100:101]
	v_sub_f32_e32 v107, v102, v103
	v_mov_b32_e32 v102, v105
	v_mov_b32_e32 v103, v104
	v_pk_mul_f32 v[100:101], v[102:103], v[100:101]
	s_nop 0
	v_add_f32_e32 v100, v100, v101
	v_cvt_pk_bf16_f32 v104, v107, v100
	v_mul_f32_e32 v100, v178, v118
	v_mul_f32_e32 v100, 0.15915494, v100
	v_sin_f32_e32 v101, v100
	v_cos_f32_e32 v100, v100
	s_nop 0
	v_pk_mul_f32 v[102:103], v[100:101], v[98:99]
	s_nop 0
	v_sub_f32_e32 v105, v102, v103
	v_mov_b32_e32 v103, v100
	v_mul_f32_e32 v100, v177, v118
	v_mul_f32_e32 v100, 0.15915494, v100
	v_mov_b32_e32 v102, v101
	v_sin_f32_e32 v101, v100
	v_cos_f32_e32 v100, v100
	v_pk_mul_f32 v[98:99], v[102:103], v[98:99]
	s_nop 0
	v_add_f32_e32 v98, v98, v99
	v_cvt_pk_bf16_f32 v102, v105, v98
	v_pk_mul_f32 v[98:99], v[100:101], v[96:97]
	v_sub_f32_e32 v103, v98, v99
	v_mov_b32_e32 v98, v101
	v_mov_b32_e32 v99, v100
	v_pk_mul_f32 v[96:97], v[98:99], v[96:97]
	v_cndmask_b32_e32 v98, v114, v104, vcc
	v_add_f32_e32 v96, v96, v97
	v_cvt_pk_bf16_f32 v103, v103, v96
	v_cndmask_b32_e32 v97, v110, v102, vcc
	v_cndmask_b32_e32 v96, v108, v103, vcc
	v_cndmask_b32_e32 v99, v116, v106, vcc
	v_mov_b32_dpp v109, v97 quad_perm:[1,0,3,2] row_mask:0xf bank_mask:0xf
	v_mov_b32_dpp v111, v96 quad_perm:[1,0,3,2] row_mask:0xf bank_mask:0xf
	v_sub_u32_e32 v96, v113, v174
	v_mad_i64_i32 v[96:97], s[4:5], v96, s61, v[126:127]
	v_mov_b32_dpp v105, v99 quad_perm:[1,0,3,2] row_mask:0xf bank_mask:0xf
	v_mov_b32_dpp v107, v98 quad_perm:[1,0,3,2] row_mask:0xf bank_mask:0xf
	v_lshl_add_u64 v[96:97], v[96:97], 0, v[150:151]
	v_lshl_add_u64 v[100:101], v[96:97], 0, v[140:141]
	v_cndmask_b32_e32 v96, v105, v116, vcc
	v_cndmask_b32_e32 v97, v107, v114, vcc
	v_cndmask_b32_e32 v98, v109, v110, vcc
	v_cndmask_b32_e32 v99, v111, v108, vcc
	global_store_dwordx4 v[100:101], v[96:99], off
	v_add_co_u32_e64 v100, s[4:5], s41, v100
	s_nop 0
	v_cndmask_b32_e32 v96, v106, v105, vcc
	v_cndmask_b32_e32 v97, v104, v107, vcc
	v_cndmask_b32_e32 v98, v102, v109, vcc
	v_cndmask_b32_e32 v99, v103, v111, vcc
	v_addc_co_u32_e64 v101, s[4:5], 0, v101, s[4:5]
	global_store_dwordx4 v[100:101], v[96:99], off offset:1024
	s_nop 1
	v_bitop3_b32 v96, v187, 1, s57 bitop3:0x36
	v_lshl_add_u32 v96, v96, 2, s17
	ds_read_b32 v97, v183 offset:768
	ds_read_b32 v98, v96
	v_or_b32_e32 v96, s45, v187
	s_waitcnt lgkmcnt(0)
; __device__ __forceinline__ unsigned cvt_pk_bf16(float lo, float hi) { unsigned r; asm volatile("v_cvt_pk_bf16_f32 %0, %1, %2" : "=v"(r) : "v"(lo), "v"(hi)); return r; }
; __device__ __forceinline__ unsigned dpp_xor1(unsigned v) { return (unsigned)__builtin_amdgcn_update_dpp(0, (int)v, 0xB1, 0xf, 0xf, false); }
; __device__ __forceinline__ float dpp_xor1(float v) { return __int_as_float(__builtin_amdgcn_update_dpp(0, __float_as_int(v), 0xB1, 0xf, 0xf, false)); }
; __device__ __forceinline__ void store_pair_rows(bf16_t* O, size_t ldc, int row, int col0, int fr, u32x4 p0, u32x4 p1) {
;     const bool odd = (fr & 1) != 0;
;     const u32x4 snd = odd ? p0 : p1; u32x4 rcv;
;     rcv.x = dpp_xor1(snd.x); rcv.y = dpp_xor1(snd.y); rcv.z = dpp_xor1(snd.z); rcv.w = dpp_xor1(snd.w);
;     bf16_t* pa = O + (size_t)(row - (odd ? 1 : 0)) * ldc + col0 + (odd ? 8 : 0);
;     *(u32x4*)pa = odd ? rcv : p0;
;     *(u32x4*)(pa + ldc) = odd ? p1 : rcv;
;     __device__ __forceinline__ void operator()(f32x4 (&acc)[2][2][4][2], const Unit& u, int wr, int wc, int fr_in, int fq_in) const {
;     ...
;             for (int ai = 0; ai < 2; ++ai)
; #pragma unroll
;                 for (int m = 0; m < 4; ++m) { const int lr = lr0 + ai * HALF + m * 16;
;                     const float tot = PS[lr * 4 + wc] + PS[lr * 4 + (wc ^ 1)]; const float r2 = __builtin_amdgcn_rsqf(tot * (1.0f / 128.0f) + RMS_EPS);
;                     const int t = (row0 + ai * HALF + m * 16) & (SEQ - 1); const float pos = colaxis ? (float)(t & 63) : (float)(t >> 6);
;                     u32x4 pw[2];
; #pragma unroll
;                     for (int bj = 0; bj < 2; ++bj) {
; #pragma unroll
;                         for (int n = 0; n < 2; ++n) { f32x4 v = acc[ai][bj][m][n] * r2 * gg[bj][n];
; #pragma unroll
;                             for (int h = 0; h < 2; ++h) { const float rev = pos * invf[bj][n][h] * 0.15915494309189535f; const float sn = __builtin_amdgcn_sinf(rev), cs = __builtin_amdgcn_cosf(rev); const float x0 = v[2 * h], x1 = v[2 * h + 1];
;                                 pw[bj][2 * n + h] = cvt_pk_bf16(x0 * cs - x1 * sn, x0 * sn + x1 * cs); } } }
;                     store_pair_rows(O, (size_t)ldc, row0 + ai * HALF + m * 16, col0, fr, pw[0], pw[1]);
	v_add_f32_e32 v97, v97, v98
	v_fmamk_f32 v97, v97, 0x3c000000, v172
	v_rsq_f32_e32 v98, v97
	v_or_b32_e32 v97, 48, v175
	v_cndmask_b32_e64 v99, v97, v160, s[0:1]
	v_and_b32_e32 v99, 63, v99
	v_cvt_f32_ubyte0_e32 v99, v99
	v_mul_f32_e32 v100, v185, v99
	v_mul_f32_e32 v100, 0.15915494, v100
	v_sin_f32_e32 v101, v100
	v_cos_f32_e32 v100, v100
	v_pk_mul_f32 v[94:95], v[94:95], v[98:99] op_sel_hi:[1,0]
	v_pk_mul_f32 v[92:93], v[92:93], v[98:99] op_sel_hi:[1,0]
	v_pk_mul_f32 v[94:95], v[12:13], v[94:95]
	v_pk_mul_f32 v[92:93], v[14:15], v[92:93]
	v_pk_mul_f32 v[102:103], v[100:101], v[94:95]
	v_pk_mul_f32 v[90:91], v[90:91], v[98:99] op_sel_hi:[1,0]
	v_sub_f32_e32 v104, v102, v103
	v_mov_b32_e32 v103, v100
	v_mul_f32_e32 v100, v184, v99
	v_mul_f32_e32 v100, 0.15915494, v100
	v_mov_b32_e32 v102, v101
	v_sin_f32_e32 v101, v100
	v_cos_f32_e32 v100, v100
	v_pk_mul_f32 v[94:95], v[102:103], v[94:95]
	v_pk_mul_f32 v[90:91], v[4:5], v[90:91]
	v_add_f32_e32 v94, v94, v95
	v_cvt_pk_bf16_f32 v102, v104, v94
	v_pk_mul_f32 v[94:95], v[100:101], v[92:93]
	v_pk_mul_f32 v[88:89], v[88:89], v[98:99] op_sel_hi:[1,0]
	v_sub_f32_e32 v103, v94, v95
	v_mov_b32_e32 v94, v101
	v_mov_b32_e32 v95, v100
	v_pk_mul_f32 v[92:93], v[94:95], v[92:93]
	v_pk_mul_f32 v[88:89], v[6:7], v[88:89]
	v_add_f32_e32 v92, v92, v93
	v_cvt_pk_bf16_f32 v100, v103, v92
	v_mul_f32_e32 v92, v182, v99
	v_mul_f32_e32 v92, 0.15915494, v92
	v_sin_f32_e32 v93, v92
	v_cos_f32_e32 v92, v92
	v_pk_mul_f32 v[86:87], v[86:87], v[98:99] op_sel_hi:[1,0]
	v_pk_mul_f32 v[84:85], v[84:85], v[98:99] op_sel_hi:[1,0]
	v_pk_mul_f32 v[86:87], v[8:9], v[86:87]
	v_pk_mul_f32 v[94:95], v[92:93], v[90:91]
	v_pk_mul_f32 v[84:85], v[10:11], v[84:85]
	v_sub_f32_e32 v101, v94, v95
	v_mov_b32_e32 v95, v92
	v_mul_f32_e32 v92, v181, v99
	v_mul_f32_e32 v92, 0.15915494, v92
	v_mov_b32_e32 v94, v93
	v_sin_f32_e32 v93, v92
	v_cos_f32_e32 v92, v92
	v_pk_mul_f32 v[90:91], v[94:95], v[90:91]
	v_pk_mul_f32 v[82:83], v[82:83], v[98:99] op_sel_hi:[1,0]
	v_add_f32_e32 v90, v90, v91
	v_cvt_pk_bf16_f32 v94, v101, v90
	v_pk_mul_f32 v[90:91], v[92:93], v[88:89]
	v_pk_mul_f32 v[82:83], v[0:1], v[82:83]
	v_sub_f32_e32 v95, v90, v91
	v_mov_b32_e32 v90, v93
	v_mov_b32_e32 v91, v92
	v_pk_mul_f32 v[88:89], v[90:91], v[88:89]
	v_pk_mul_f32 v[80:81], v[80:81], v[98:99] op_sel_hi:[1,0]
	v_add_f32_e32 v88, v88, v89
	v_cvt_pk_bf16_f32 v92, v95, v88
	v_mul_f32_e32 v88, v180, v99
	v_mul_f32_e32 v88, 0.15915494, v88
	v_sin_f32_e32 v89, v88
	v_cos_f32_e32 v88, v88
	v_pk_mul_f32 v[80:81], v[2:3], v[80:81]
	v_pk_mul_f32 v[90:91], v[88:89], v[86:87]
	s_nop 0
	v_sub_f32_e32 v93, v90, v91
	v_mov_b32_e32 v91, v88
	v_mul_f32_e32 v88, v179, v99
	v_mul_f32_e32 v88, 0.15915494, v88
	v_mov_b32_e32 v90, v89
	v_sin_f32_e32 v89, v88
	v_cos_f32_e32 v88, v88
	v_pk_mul_f32 v[86:87], v[90:91], v[86:87]
	s_nop 0
	v_add_f32_e32 v86, v86, v87
	v_cvt_pk_bf16_f32 v90, v93, v86
	v_pk_mul_f32 v[86:87], v[88:89], v[84:85]
	v_sub_f32_e32 v91, v86, v87
	v_mov_b32_e32 v86, v89
	v_mov_b32_e32 v87, v88
	v_pk_mul_f32 v[84:85], v[86:87], v[84:85]
	s_nop 0
	v_add_f32_e32 v84, v84, v85
	v_cvt_pk_bf16_f32 v88, v91, v84
	v_mul_f32_e32 v84, v178, v99
	v_mul_f32_e32 v84, 0.15915494, v84
	v_sin_f32_e32 v85, v84
	v_cos_f32_e32 v84, v84
	s_nop 0
	v_pk_mul_f32 v[86:87], v[84:85], v[82:83]
	s_nop 0
	v_sub_f32_e32 v89, v86, v87
	v_mov_b32_e32 v87, v84
	v_mul_f32_e32 v84, v177, v99
	v_mul_f32_e32 v84, 0.15915494, v84
	v_mov_b32_e32 v86, v85
	v_sin_f32_e32 v85, v84
	v_cos_f32_e32 v84, v84
	v_pk_mul_f32 v[82:83], v[86:87], v[82:83]
	s_nop 0
	v_add_f32_e32 v82, v82, v83
	v_cvt_pk_bf16_f32 v86, v89, v82
	v_pk_mul_f32 v[82:83], v[84:85], v[80:81]
	v_sub_f32_e32 v87, v82, v83
	v_mov_b32_e32 v82, v85
	v_mov_b32_e32 v83, v84
	v_pk_mul_f32 v[80:81], v[82:83], v[80:81]
	v_cndmask_b32_e32 v82, v100, v88, vcc
	v_add_f32_e32 v80, v80, v81
	v_cvt_pk_bf16_f32 v87, v87, v80
	v_cndmask_b32_e32 v81, v94, v86, vcc
	v_cndmask_b32_e32 v80, v92, v87, vcc
	v_cndmask_b32_e32 v83, v102, v90, vcc
	v_mov_b32_dpp v93, v81 quad_perm:[1,0,3,2] row_mask:0xf bank_mask:0xf
	v_mov_b32_dpp v95, v80 quad_perm:[1,0,3,2] row_mask:0xf bank_mask:0xf
	v_sub_u32_e32 v80, v97, v174
	v_mad_i64_i32 v[80:81], s[4:5], v80, s61, v[126:127]
	v_mov_b32_dpp v89, v83 quad_perm:[1,0,3,2] row_mask:0xf bank_mask:0xf
	v_mov_b32_dpp v91, v82 quad_perm:[1,0,3,2] row_mask:0xf bank_mask:0xf
	v_lshl_add_u64 v[80:81], v[80:81], 0, v[150:151]
	v_lshl_add_u64 v[84:85], v[80:81], 0, v[140:141]
	v_cndmask_b32_e32 v80, v89, v102, vcc
	v_cndmask_b32_e32 v81, v91, v100, vcc
	v_cndmask_b32_e32 v82, v93, v94, vcc
	v_cndmask_b32_e32 v83, v95, v92, vcc
	global_store_dwordx4 v[84:85], v[80:83], off
	v_add_co_u32_e64 v84, s[4:5], s41, v84
	s_nop 0
	v_cndmask_b32_e32 v80, v90, v89, vcc
	v_cndmask_b32_e32 v81, v88, v91, vcc
	v_cndmask_b32_e32 v82, v86, v93, vcc
	v_cndmask_b32_e32 v83, v87, v95, vcc
	v_addc_co_u32_e64 v85, s[4:5], 0, v85, s[4:5]
	global_store_dwordx4 v[84:85], v[80:83], off offset:1024
	v_add_u32_e32 v86, 0x80, v175
	s_nop 0
	v_add_u32_e32 v80, 0x200, v96
	v_xor_b32_e32 v80, 1, v80
	v_lshl_add_u32 v80, v80, 2, s17
	ds_read_b32 v81, v183 offset:2048
	ds_read_b32 v80, v80
	s_waitcnt lgkmcnt(0)
; __device__ __forceinline__ unsigned cvt_pk_bf16(float lo, float hi) { unsigned r; asm volatile("v_cvt_pk_bf16_f32 %0, %1, %2" : "=v"(r) : "v"(lo), "v"(hi)); return r; }
; __device__ __forceinline__ unsigned dpp_xor1(unsigned v) { return (unsigned)__builtin_amdgcn_update_dpp(0, (int)v, 0xB1, 0xf, 0xf, false); }
; __device__ __forceinline__ float dpp_xor1(float v) { return __int_as_float(__builtin_amdgcn_update_dpp(0, __float_as_int(v), 0xB1, 0xf, 0xf, false)); }
; __device__ __forceinline__ void store_pair_rows(bf16_t* O, size_t ldc, int row, int col0, int fr, u32x4 p0, u32x4 p1) {
;     const bool odd = (fr & 1) != 0;
;     const u32x4 snd = odd ? p0 : p1; u32x4 rcv;
;     rcv.x = dpp_xor1(snd.x); rcv.y = dpp_xor1(snd.y); rcv.z = dpp_xor1(snd.z); rcv.w = dpp_xor1(snd.w);
;     bf16_t* pa = O + (size_t)(row - (odd ? 1 : 0)) * ldc + col0 + (odd ? 8 : 0);
;     *(u32x4*)pa = odd ? rcv : p0;
;     *(u32x4*)(pa + ldc) = odd ? p1 : rcv;
;     __device__ __forceinline__ void operator()(f32x4 (&acc)[2][2][4][2], const Unit& u, int wr, int wc, int fr_in, int fq_in) const {
;     ...
;             for (int ai = 0; ai < 2; ++ai)
; #pragma unroll
;                 for (int m = 0; m < 4; ++m) { const int lr = lr0 + ai * HALF + m * 16;
;                     const float tot = PS[lr * 4 + wc] + PS[lr * 4 + (wc ^ 1)]; const float r2 = __builtin_amdgcn_rsqf(tot * (1.0f / 128.0f) + RMS_EPS);
;                     const int t = (row0 + ai * HALF + m * 16) & (SEQ - 1); const float pos = colaxis ? (float)(t & 63) : (float)(t >> 6);
;                     u32x4 pw[2];
; #pragma unroll
;                     for (int bj = 0; bj < 2; ++bj) {
; #pragma unroll
;                         for (int n = 0; n < 2; ++n) { f32x4 v = acc[ai][bj][m][n] * r2 * gg[bj][n];
; #pragma unroll
;                             for (int h = 0; h < 2; ++h) { const float rev = pos * invf[bj][n][h] * 0.15915494309189535f; const float sn = __builtin_amdgcn_sinf(rev), cs = __builtin_amdgcn_cosf(rev); const float x0 = v[2 * h], x1 = v[2 * h + 1];
;                                 pw[bj][2 * n + h] = cvt_pk_bf16(x0 * cs - x1 * sn, x0 * sn + x1 * cs); } } }
;                     store_pair_rows(O, (size_t)ldc, row0 + ai * HALF + m * 16, col0, fr, pw[0], pw[1]);
	v_add_f32_e32 v80, v81, v80
	v_bfe_u32 v81, v86, 6, 6
	v_cndmask_b32_e64 v81, v176, v81, s[0:1]
	v_fmamk_f32 v80, v80, 0x3c000000, v172
	v_cvt_f32_ubyte0_e32 v81, v81
	v_rsq_f32_e32 v80, v80
	v_mul_f32_e32 v82, v185, v81
	v_mul_f32_e32 v82, 0.15915494, v82
	v_sin_f32_e32 v83, v82
	v_cos_f32_e32 v82, v82
	v_pk_mul_f32 v[78:79], v[78:79], v[80:81] op_sel_hi:[1,0]
	v_pk_mul_f32 v[76:77], v[76:77], v[80:81] op_sel_hi:[1,0]
	v_pk_mul_f32 v[78:79], v[12:13], v[78:79]
	v_pk_mul_f32 v[76:77], v[14:15], v[76:77]
	v_pk_mul_f32 v[84:85], v[82:83], v[78:79]
	v_pk_mul_f32 v[74:75], v[74:75], v[80:81] op_sel_hi:[1,0]
	v_sub_f32_e32 v87, v84, v85
	v_mov_b32_e32 v85, v82
	v_mul_f32_e32 v82, v184, v81
	v_mul_f32_e32 v82, 0.15915494, v82
	v_mov_b32_e32 v84, v83
	v_sin_f32_e32 v83, v82
	v_cos_f32_e32 v82, v82
	v_pk_mul_f32 v[78:79], v[84:85], v[78:79]
	v_pk_mul_f32 v[74:75], v[4:5], v[74:75]
	v_add_f32_e32 v78, v78, v79
	v_cvt_pk_bf16_f32 v84, v87, v78
	v_pk_mul_f32 v[78:79], v[82:83], v[76:77]
	v_pk_mul_f32 v[72:73], v[72:73], v[80:81] op_sel_hi:[1,0]
	v_sub_f32_e32 v85, v78, v79
	v_mov_b32_e32 v78, v83
	v_mov_b32_e32 v79, v82
	v_pk_mul_f32 v[76:77], v[78:79], v[76:77]
	v_pk_mul_f32 v[72:73], v[6:7], v[72:73]
	v_add_f32_e32 v76, v76, v77
	v_cvt_pk_bf16_f32 v82, v85, v76
	v_mul_f32_e32 v76, v182, v81
	v_mul_f32_e32 v76, 0.15915494, v76
	v_sin_f32_e32 v77, v76
	v_cos_f32_e32 v76, v76
	v_pk_mul_f32 v[70:71], v[70:71], v[80:81] op_sel_hi:[1,0]
	v_pk_mul_f32 v[68:69], v[68:69], v[80:81] op_sel_hi:[1,0]
	v_pk_mul_f32 v[70:71], v[8:9], v[70:71]
	v_pk_mul_f32 v[78:79], v[76:77], v[74:75]
	v_pk_mul_f32 v[68:69], v[10:11], v[68:69]
	v_sub_f32_e32 v83, v78, v79
	v_mov_b32_e32 v79, v76
	v_mul_f32_e32 v76, v181, v81
	v_mul_f32_e32 v76, 0.15915494, v76
	v_mov_b32_e32 v78, v77
	v_sin_f32_e32 v77, v76
	v_cos_f32_e32 v76, v76
	v_pk_mul_f32 v[74:75], v[78:79], v[74:75]
	v_pk_mul_f32 v[66:67], v[66:67], v[80:81] op_sel_hi:[1,0]
	v_add_f32_e32 v74, v74, v75
	v_cvt_pk_bf16_f32 v78, v83, v74
	v_pk_mul_f32 v[74:75], v[76:77], v[72:73]
	v_pk_mul_f32 v[66:67], v[0:1], v[66:67]
	v_sub_f32_e32 v79, v74, v75
	v_mov_b32_e32 v74, v77
	v_mov_b32_e32 v75, v76
	v_pk_mul_f32 v[72:73], v[74:75], v[72:73]
	v_pk_mul_f32 v[64:65], v[64:65], v[80:81] op_sel_hi:[1,0]
	v_add_f32_e32 v72, v72, v73
	v_cvt_pk_bf16_f32 v76, v79, v72
	v_mul_f32_e32 v72, v180, v81
	v_mul_f32_e32 v72, 0.15915494, v72
	v_sin_f32_e32 v73, v72
	v_cos_f32_e32 v72, v72
	v_pk_mul_f32 v[64:65], v[2:3], v[64:65]
	v_pk_mul_f32 v[74:75], v[72:73], v[70:71]
	s_nop 0
	v_sub_f32_e32 v77, v74, v75
	v_mov_b32_e32 v75, v72
	v_mul_f32_e32 v72, v179, v81
	v_mul_f32_e32 v72, 0.15915494, v72
	v_mov_b32_e32 v74, v73
	v_sin_f32_e32 v73, v72
	v_cos_f32_e32 v72, v72
	v_pk_mul_f32 v[70:71], v[74:75], v[70:71]
	s_nop 0
	v_add_f32_e32 v70, v70, v71
	v_cvt_pk_bf16_f32 v74, v77, v70
	v_pk_mul_f32 v[70:71], v[72:73], v[68:69]
	v_sub_f32_e32 v75, v70, v71
	v_mov_b32_e32 v70, v73
	v_mov_b32_e32 v71, v72
	v_pk_mul_f32 v[68:69], v[70:71], v[68:69]
	s_nop 0
	v_add_f32_e32 v68, v68, v69
	v_cvt_pk_bf16_f32 v72, v75, v68
	v_mul_f32_e32 v68, v178, v81
	v_mul_f32_e32 v68, 0.15915494, v68
	v_sin_f32_e32 v69, v68
	v_cos_f32_e32 v68, v68
	s_nop 0
	v_pk_mul_f32 v[70:71], v[68:69], v[66:67]
	s_nop 0
	v_sub_f32_e32 v73, v70, v71
	v_mov_b32_e32 v71, v68
	v_mul_f32_e32 v68, v177, v81
	v_mul_f32_e32 v68, 0.15915494, v68
	v_mov_b32_e32 v70, v69
	v_sin_f32_e32 v69, v68
	v_cos_f32_e32 v68, v68
	v_pk_mul_f32 v[66:67], v[70:71], v[66:67]
	s_nop 0
	v_add_f32_e32 v66, v66, v67
	v_cvt_pk_bf16_f32 v70, v73, v66
	v_pk_mul_f32 v[66:67], v[68:69], v[64:65]
	v_sub_f32_e32 v71, v66, v67
	v_mov_b32_e32 v66, v69
	v_mov_b32_e32 v67, v68
	v_pk_mul_f32 v[64:65], v[66:67], v[64:65]
	v_cndmask_b32_e32 v66, v82, v72, vcc
	v_add_f32_e32 v64, v64, v65
	v_cvt_pk_bf16_f32 v71, v71, v64
	v_cndmask_b32_e32 v65, v78, v70, vcc
	v_cndmask_b32_e32 v64, v76, v71, vcc
	v_cndmask_b32_e32 v67, v84, v74, vcc
	v_mov_b32_dpp v77, v65 quad_perm:[1,0,3,2] row_mask:0xf bank_mask:0xf
	v_mov_b32_dpp v79, v64 quad_perm:[1,0,3,2] row_mask:0xf bank_mask:0xf
	v_sub_u32_e32 v64, v86, v174
	v_mad_i64_i32 v[64:65], s[4:5], v64, s61, v[126:127]
	v_mov_b32_dpp v73, v67 quad_perm:[1,0,3,2] row_mask:0xf bank_mask:0xf
	v_mov_b32_dpp v75, v66 quad_perm:[1,0,3,2] row_mask:0xf bank_mask:0xf
	v_lshl_add_u64 v[64:65], v[64:65], 0, v[150:151]
	v_lshl_add_u64 v[68:69], v[64:65], 0, v[140:141]
	v_cndmask_b32_e32 v64, v73, v84, vcc
	v_cndmask_b32_e32 v65, v75, v82, vcc
	v_cndmask_b32_e32 v66, v77, v78, vcc
	v_cndmask_b32_e32 v67, v79, v76, vcc
	global_store_dwordx4 v[68:69], v[64:67], off
	v_add_co_u32_e64 v68, s[4:5], s41, v68
	s_nop 0
	v_cndmask_b32_e32 v64, v74, v73, vcc
	v_cndmask_b32_e32 v65, v72, v75, vcc
	v_cndmask_b32_e32 v66, v70, v77, vcc
	v_cndmask_b32_e32 v67, v71, v79, vcc
	v_addc_co_u32_e64 v69, s[4:5], 0, v69, s[4:5]
	global_store_dwordx4 v[68:69], v[64:67], off offset:1024
	v_lshrrev_b32_e32 v70, 6, v86
	s_nop 0
	v_add_u32_e32 v64, 0x240, v96
	v_xor_b32_e32 v64, 1, v64
	v_lshl_add_u32 v64, v64, 2, s17
	ds_read_b32 v65, v183 offset:2304
	ds_read_b32 v64, v64
	s_waitcnt lgkmcnt(0)
; __device__ __forceinline__ unsigned cvt_pk_bf16(float lo, float hi) { unsigned r; asm volatile("v_cvt_pk_bf16_f32 %0, %1, %2" : "=v"(r) : "v"(lo), "v"(hi)); return r; }
; __device__ __forceinline__ unsigned dpp_xor1(unsigned v) { return (unsigned)__builtin_amdgcn_update_dpp(0, (int)v, 0xB1, 0xf, 0xf, false); }
; __device__ __forceinline__ float dpp_xor1(float v) { return __int_as_float(__builtin_amdgcn_update_dpp(0, __float_as_int(v), 0xB1, 0xf, 0xf, false)); }
; __device__ __forceinline__ void store_pair_rows(bf16_t* O, size_t ldc, int row, int col0, int fr, u32x4 p0, u32x4 p1) {
;     const bool odd = (fr & 1) != 0;
;     const u32x4 snd = odd ? p0 : p1; u32x4 rcv;
;     rcv.x = dpp_xor1(snd.x); rcv.y = dpp_xor1(snd.y); rcv.z = dpp_xor1(snd.z); rcv.w = dpp_xor1(snd.w);
;     bf16_t* pa = O + (size_t)(row - (odd ? 1 : 0)) * ldc + col0 + (odd ? 8 : 0);
;     *(u32x4*)pa = odd ? rcv : p0;
;     *(u32x4*)(pa + ldc) = odd ? p1 : rcv;
;     __device__ __forceinline__ void operator()(f32x4 (&acc)[2][2][4][2], const Unit& u, int wr, int wc, int fr_in, int fq_in) const {
;     ...
;             for (int ai = 0; ai < 2; ++ai)
; #pragma unroll
;                 for (int m = 0; m < 4; ++m) { const int lr = lr0 + ai * HALF + m * 16;
;                     const float tot = PS[lr * 4 + wc] + PS[lr * 4 + (wc ^ 1)]; const float r2 = __builtin_amdgcn_rsqf(tot * (1.0f / 128.0f) + RMS_EPS);
;                     const int t = (row0 + ai * HALF + m * 16) & (SEQ - 1); const float pos = colaxis ? (float)(t & 63) : (float)(t >> 6);
;                     u32x4 pw[2];
; #pragma unroll
;                     for (int bj = 0; bj < 2; ++bj) {
; #pragma unroll
;                         for (int n = 0; n < 2; ++n) { f32x4 v = acc[ai][bj][m][n] * r2 * gg[bj][n];
; #pragma unroll
;                             for (int h = 0; h < 2; ++h) { const float rev = pos * invf[bj][n][h] * 0.15915494309189535f; const float sn = __builtin_amdgcn_sinf(rev), cs = __builtin_amdgcn_cosf(rev); const float x0 = v[2 * h], x1 = v[2 * h + 1];
;                                 pw[bj][2 * n + h] = cvt_pk_bf16(x0 * cs - x1 * sn, x0 * sn + x1 * cs); } } }
;                     store_pair_rows(O, (size_t)ldc, row0 + ai * HALF + m * 16, col0, fr, pw[0], pw[1]);
	v_add_f32_e32 v64, v65, v64
	v_add_u32_e32 v65, 0x90, v175
	v_cndmask_b32_e64 v66, v65, v70, s[0:1]
	v_and_b32_e32 v66, 63, v66
	v_fmamk_f32 v64, v64, 0x3c000000, v172
	v_cvt_f32_ubyte0_e32 v71, v66
	v_rsq_f32_e32 v64, v64
	v_mul_f32_e32 v66, v185, v71
	v_mul_f32_e32 v66, 0.15915494, v66
	v_sin_f32_e32 v67, v66
	v_cos_f32_e32 v66, v66
	v_pk_mul_f32 v[62:63], v[62:63], v[64:65] op_sel_hi:[1,0]
	v_pk_mul_f32 v[60:61], v[60:61], v[64:65] op_sel_hi:[1,0]
	v_pk_mul_f32 v[62:63], v[12:13], v[62:63]
	v_pk_mul_f32 v[60:61], v[14:15], v[60:61]
	v_pk_mul_f32 v[68:69], v[66:67], v[62:63]
	v_pk_mul_f32 v[58:59], v[58:59], v[64:65] op_sel_hi:[1,0]
	v_sub_f32_e32 v72, v68, v69
	v_mov_b32_e32 v69, v66
	v_mul_f32_e32 v66, v184, v71
	v_mul_f32_e32 v66, 0.15915494, v66
	v_mov_b32_e32 v68, v67
	v_sin_f32_e32 v67, v66
	v_cos_f32_e32 v66, v66
	v_pk_mul_f32 v[62:63], v[68:69], v[62:63]
	v_pk_mul_f32 v[58:59], v[4:5], v[58:59]
	v_add_f32_e32 v62, v62, v63
	v_cvt_pk_bf16_f32 v68, v72, v62
	v_pk_mul_f32 v[62:63], v[66:67], v[60:61]
	v_pk_mul_f32 v[56:57], v[56:57], v[64:65] op_sel_hi:[1,0]
	v_sub_f32_e32 v69, v62, v63
	v_mov_b32_e32 v62, v67
	v_mov_b32_e32 v63, v66
	v_pk_mul_f32 v[60:61], v[62:63], v[60:61]
	v_pk_mul_f32 v[56:57], v[6:7], v[56:57]
	v_add_f32_e32 v60, v60, v61
	v_cvt_pk_bf16_f32 v66, v69, v60
	v_mul_f32_e32 v60, v182, v71
	v_mul_f32_e32 v60, 0.15915494, v60
	v_sin_f32_e32 v61, v60
	v_cos_f32_e32 v60, v60
	v_pk_mul_f32 v[54:55], v[54:55], v[64:65] op_sel_hi:[1,0]
	v_pk_mul_f32 v[52:53], v[52:53], v[64:65] op_sel_hi:[1,0]
	v_pk_mul_f32 v[54:55], v[8:9], v[54:55]
	v_pk_mul_f32 v[62:63], v[60:61], v[58:59]
	v_pk_mul_f32 v[52:53], v[10:11], v[52:53]
	v_sub_f32_e32 v67, v62, v63
	v_mov_b32_e32 v63, v60
	v_mul_f32_e32 v60, v181, v71
	v_mul_f32_e32 v60, 0.15915494, v60
	v_mov_b32_e32 v62, v61
	v_sin_f32_e32 v61, v60
	v_cos_f32_e32 v60, v60
	v_pk_mul_f32 v[58:59], v[62:63], v[58:59]
	v_pk_mul_f32 v[50:51], v[50:51], v[64:65] op_sel_hi:[1,0]
	v_add_f32_e32 v58, v58, v59
	v_cvt_pk_bf16_f32 v62, v67, v58
	v_pk_mul_f32 v[58:59], v[60:61], v[56:57]
	v_pk_mul_f32 v[50:51], v[0:1], v[50:51]
	v_sub_f32_e32 v63, v58, v59
	v_mov_b32_e32 v58, v61
	v_mov_b32_e32 v59, v60
	v_pk_mul_f32 v[56:57], v[58:59], v[56:57]
	v_pk_mul_f32 v[48:49], v[48:49], v[64:65] op_sel_hi:[1,0]
	v_add_f32_e32 v56, v56, v57
	v_cvt_pk_bf16_f32 v60, v63, v56
	v_mul_f32_e32 v56, v180, v71
	v_mul_f32_e32 v56, 0.15915494, v56
	v_sin_f32_e32 v57, v56
	v_cos_f32_e32 v56, v56
	v_pk_mul_f32 v[48:49], v[2:3], v[48:49]
	v_pk_mul_f32 v[58:59], v[56:57], v[54:55]
	s_nop 0
	v_sub_f32_e32 v61, v58, v59
	v_mov_b32_e32 v59, v56
	v_mul_f32_e32 v56, v179, v71
	v_mul_f32_e32 v56, 0.15915494, v56
	v_mov_b32_e32 v58, v57
	v_sin_f32_e32 v57, v56
	v_cos_f32_e32 v56, v56
	v_pk_mul_f32 v[54:55], v[58:59], v[54:55]
	s_nop 0
	v_add_f32_e32 v54, v54, v55
	v_cvt_pk_bf16_f32 v58, v61, v54
	v_pk_mul_f32 v[54:55], v[56:57], v[52:53]
	v_sub_f32_e32 v59, v54, v55
	v_mov_b32_e32 v54, v57
	v_mov_b32_e32 v55, v56
	v_pk_mul_f32 v[52:53], v[54:55], v[52:53]
	s_nop 0
	v_add_f32_e32 v52, v52, v53
	v_cvt_pk_bf16_f32 v56, v59, v52
	v_mul_f32_e32 v52, v178, v71
	v_mul_f32_e32 v52, 0.15915494, v52
	v_sin_f32_e32 v53, v52
	v_cos_f32_e32 v52, v52
	s_nop 0
	v_pk_mul_f32 v[54:55], v[52:53], v[50:51]
	s_nop 0
	v_sub_f32_e32 v57, v54, v55
	v_mov_b32_e32 v55, v52
	v_mul_f32_e32 v52, v177, v71
	v_mul_f32_e32 v52, 0.15915494, v52
	v_mov_b32_e32 v54, v53
	v_sin_f32_e32 v53, v52
	v_cos_f32_e32 v52, v52
	v_pk_mul_f32 v[50:51], v[54:55], v[50:51]
	s_nop 0
	v_add_f32_e32 v50, v50, v51
	v_cvt_pk_bf16_f32 v54, v57, v50
	v_pk_mul_f32 v[50:51], v[52:53], v[48:49]
	v_sub_f32_e32 v55, v50, v51
	v_mov_b32_e32 v50, v53
	v_mov_b32_e32 v51, v52
	v_pk_mul_f32 v[48:49], v[50:51], v[48:49]
	v_cndmask_b32_e32 v50, v66, v56, vcc
	v_add_f32_e32 v48, v48, v49
	v_cvt_pk_bf16_f32 v55, v55, v48
	v_cndmask_b32_e32 v49, v62, v54, vcc
	v_cndmask_b32_e32 v48, v60, v55, vcc
	v_cndmask_b32_e32 v51, v68, v58, vcc
	v_mov_b32_dpp v61, v49 quad_perm:[1,0,3,2] row_mask:0xf bank_mask:0xf
	v_mov_b32_dpp v63, v48 quad_perm:[1,0,3,2] row_mask:0xf bank_mask:0xf
	v_sub_u32_e32 v48, v65, v174
	v_mad_i64_i32 v[48:49], s[4:5], v48, s61, v[126:127]
	v_mov_b32_dpp v57, v51 quad_perm:[1,0,3,2] row_mask:0xf bank_mask:0xf
	v_mov_b32_dpp v59, v50 quad_perm:[1,0,3,2] row_mask:0xf bank_mask:0xf
	v_lshl_add_u64 v[48:49], v[48:49], 0, v[150:151]
	v_lshl_add_u64 v[52:53], v[48:49], 0, v[140:141]
	v_cndmask_b32_e32 v48, v57, v68, vcc
	v_cndmask_b32_e32 v49, v59, v66, vcc
	v_cndmask_b32_e32 v50, v61, v62, vcc
	v_cndmask_b32_e32 v51, v63, v60, vcc
	global_store_dwordx4 v[52:53], v[48:51], off
	v_add_co_u32_e64 v52, s[4:5], s41, v52
	s_nop 0
	v_cndmask_b32_e32 v48, v58, v57, vcc
	v_cndmask_b32_e32 v49, v56, v59, vcc
	v_cndmask_b32_e32 v50, v54, v61, vcc
	v_cndmask_b32_e32 v51, v55, v63, vcc
	v_addc_co_u32_e64 v53, s[4:5], 0, v53, s[4:5]
	global_store_dwordx4 v[52:53], v[48:51], off offset:1024
	s_nop 1
	v_add_u32_e32 v48, 0x280, v96
	v_xor_b32_e32 v48, 1, v48
	v_lshl_add_u32 v48, v48, 2, s17
	ds_read_b32 v49, v183 offset:2560
	ds_read_b32 v48, v48
	s_waitcnt lgkmcnt(0)
; __device__ __forceinline__ unsigned cvt_pk_bf16(float lo, float hi) { unsigned r; asm volatile("v_cvt_pk_bf16_f32 %0, %1, %2" : "=v"(r) : "v"(lo), "v"(hi)); return r; }
; __device__ __forceinline__ unsigned dpp_xor1(unsigned v) { return (unsigned)__builtin_amdgcn_update_dpp(0, (int)v, 0xB1, 0xf, 0xf, false); }
; __device__ __forceinline__ float dpp_xor1(float v) { return __int_as_float(__builtin_amdgcn_update_dpp(0, __float_as_int(v), 0xB1, 0xf, 0xf, false)); }
; __device__ __forceinline__ void store_pair_rows(bf16_t* O, size_t ldc, int row, int col0, int fr, u32x4 p0, u32x4 p1) {
;     const bool odd = (fr & 1) != 0;
;     const u32x4 snd = odd ? p0 : p1; u32x4 rcv;
;     rcv.x = dpp_xor1(snd.x); rcv.y = dpp_xor1(snd.y); rcv.z = dpp_xor1(snd.z); rcv.w = dpp_xor1(snd.w);
;     bf16_t* pa = O + (size_t)(row - (odd ? 1 : 0)) * ldc + col0 + (odd ? 8 : 0);
;     *(u32x4*)pa = odd ? rcv : p0;
;     *(u32x4*)(pa + ldc) = odd ? p1 : rcv;
;     __device__ __forceinline__ void operator()(f32x4 (&acc)[2][2][4][2], const Unit& u, int wr, int wc, int fr_in, int fq_in) const {
;     ...
;             for (int ai = 0; ai < 2; ++ai)
; #pragma unroll
;                 for (int m = 0; m < 4; ++m) { const int lr = lr0 + ai * HALF + m * 16;
;                     const float tot = PS[lr * 4 + wc] + PS[lr * 4 + (wc ^ 1)]; const float r2 = __builtin_amdgcn_rsqf(tot * (1.0f / 128.0f) + RMS_EPS);
;                     const int t = (row0 + ai * HALF + m * 16) & (SEQ - 1); const float pos = colaxis ? (float)(t & 63) : (float)(t >> 6);
;                     u32x4 pw[2];
; #pragma unroll
;                     for (int bj = 0; bj < 2; ++bj) {
; #pragma unroll
;                         for (int n = 0; n < 2; ++n) { f32x4 v = acc[ai][bj][m][n] * r2 * gg[bj][n];
; #pragma unroll
;                             for (int h = 0; h < 2; ++h) { const float rev = pos * invf[bj][n][h] * 0.15915494309189535f; const float sn = __builtin_amdgcn_sinf(rev), cs = __builtin_amdgcn_cosf(rev); const float x0 = v[2 * h], x1 = v[2 * h + 1];
;                                 pw[bj][2 * n + h] = cvt_pk_bf16(x0 * cs - x1 * sn, x0 * sn + x1 * cs); } } }
;                     store_pair_rows(O, (size_t)ldc, row0 + ai * HALF + m * 16, col0, fr, pw[0], pw[1]);
	v_add_f32_e32 v48, v49, v48
	v_add_u32_e32 v49, 0xa0, v175
	v_cndmask_b32_e64 v50, v49, v70, s[0:1]
	v_and_b32_e32 v50, 63, v50
	v_fmamk_f32 v48, v48, 0x3c000000, v172
	v_cvt_f32_ubyte0_e32 v54, v50
	v_rsq_f32_e32 v48, v48
	v_mul_f32_e32 v50, v185, v54
	v_mul_f32_e32 v50, 0.15915494, v50
	v_sin_f32_e32 v51, v50
	v_cos_f32_e32 v50, v50
	v_pk_mul_f32 v[46:47], v[46:47], v[48:49] op_sel_hi:[1,0]
	v_pk_mul_f32 v[44:45], v[44:45], v[48:49] op_sel_hi:[1,0]
	v_pk_mul_f32 v[46:47], v[12:13], v[46:47]
	v_pk_mul_f32 v[44:45], v[14:15], v[44:45]
	v_pk_mul_f32 v[52:53], v[50:51], v[46:47]
	v_pk_mul_f32 v[42:43], v[42:43], v[48:49] op_sel_hi:[1,0]
	v_sub_f32_e32 v55, v52, v53
	v_mov_b32_e32 v53, v50
	v_mul_f32_e32 v50, v184, v54
	v_mul_f32_e32 v50, 0.15915494, v50
	v_mov_b32_e32 v52, v51
	v_sin_f32_e32 v51, v50
	v_cos_f32_e32 v50, v50
	v_pk_mul_f32 v[46:47], v[52:53], v[46:47]
	v_pk_mul_f32 v[42:43], v[4:5], v[42:43]
	v_add_f32_e32 v46, v46, v47
	v_cvt_pk_bf16_f32 v52, v55, v46
	v_pk_mul_f32 v[46:47], v[50:51], v[44:45]
	v_pk_mul_f32 v[40:41], v[40:41], v[48:49] op_sel_hi:[1,0]
	v_sub_f32_e32 v53, v46, v47
	v_mov_b32_e32 v46, v51
	v_mov_b32_e32 v47, v50
	v_pk_mul_f32 v[44:45], v[46:47], v[44:45]
	v_pk_mul_f32 v[40:41], v[6:7], v[40:41]
	v_add_f32_e32 v44, v44, v45
	v_cvt_pk_bf16_f32 v50, v53, v44
	v_mul_f32_e32 v44, v182, v54
	v_mul_f32_e32 v44, 0.15915494, v44
	v_sin_f32_e32 v45, v44
	v_cos_f32_e32 v44, v44
	v_pk_mul_f32 v[38:39], v[38:39], v[48:49] op_sel_hi:[1,0]
	v_pk_mul_f32 v[36:37], v[36:37], v[48:49] op_sel_hi:[1,0]
	v_pk_mul_f32 v[38:39], v[8:9], v[38:39]
	v_pk_mul_f32 v[46:47], v[44:45], v[42:43]
	v_pk_mul_f32 v[36:37], v[10:11], v[36:37]
	v_sub_f32_e32 v51, v46, v47
	v_mov_b32_e32 v47, v44
	v_mul_f32_e32 v44, v181, v54
	v_mul_f32_e32 v44, 0.15915494, v44
	v_mov_b32_e32 v46, v45
	v_sin_f32_e32 v45, v44
	v_cos_f32_e32 v44, v44
	v_pk_mul_f32 v[42:43], v[46:47], v[42:43]
	v_pk_mul_f32 v[34:35], v[34:35], v[48:49] op_sel_hi:[1,0]
	v_add_f32_e32 v42, v42, v43
	v_cvt_pk_bf16_f32 v46, v51, v42
	v_pk_mul_f32 v[42:43], v[44:45], v[40:41]
	v_pk_mul_f32 v[34:35], v[0:1], v[34:35]
	v_sub_f32_e32 v47, v42, v43
	v_mov_b32_e32 v42, v45
	v_mov_b32_e32 v43, v44
	v_pk_mul_f32 v[40:41], v[42:43], v[40:41]
	v_pk_mul_f32 v[32:33], v[32:33], v[48:49] op_sel_hi:[1,0]
	v_add_f32_e32 v40, v40, v41
	v_cvt_pk_bf16_f32 v44, v47, v40
	v_mul_f32_e32 v40, v180, v54
	v_mul_f32_e32 v40, 0.15915494, v40
	v_sin_f32_e32 v41, v40
	v_cos_f32_e32 v40, v40
	v_pk_mul_f32 v[32:33], v[2:3], v[32:33]
	v_pk_mul_f32 v[42:43], v[40:41], v[38:39]
	s_nop 0
	v_sub_f32_e32 v45, v42, v43
	v_mov_b32_e32 v43, v40
	v_mul_f32_e32 v40, v179, v54
	v_mul_f32_e32 v40, 0.15915494, v40
	v_mov_b32_e32 v42, v41
	v_sin_f32_e32 v41, v40
	v_cos_f32_e32 v40, v40
	v_pk_mul_f32 v[38:39], v[42:43], v[38:39]
	s_nop 0
	v_add_f32_e32 v38, v38, v39
	v_cvt_pk_bf16_f32 v42, v45, v38
	v_pk_mul_f32 v[38:39], v[40:41], v[36:37]
	v_sub_f32_e32 v43, v38, v39
	v_mov_b32_e32 v38, v41
	v_mov_b32_e32 v39, v40
	v_pk_mul_f32 v[36:37], v[38:39], v[36:37]
	s_nop 0
	v_add_f32_e32 v36, v36, v37
	v_cvt_pk_bf16_f32 v40, v43, v36
	v_mul_f32_e32 v36, v178, v54
	v_mul_f32_e32 v36, 0.15915494, v36
	v_sin_f32_e32 v37, v36
	v_cos_f32_e32 v36, v36
	s_nop 0
	v_pk_mul_f32 v[38:39], v[36:37], v[34:35]
	s_nop 0
	v_sub_f32_e32 v41, v38, v39
	v_mov_b32_e32 v39, v36
	v_mul_f32_e32 v36, v177, v54
	v_mul_f32_e32 v36, 0.15915494, v36
	v_mov_b32_e32 v38, v37
	v_sin_f32_e32 v37, v36
	v_cos_f32_e32 v36, v36
	v_pk_mul_f32 v[34:35], v[38:39], v[34:35]
	s_nop 0
	v_add_f32_e32 v34, v34, v35
	v_cvt_pk_bf16_f32 v38, v41, v34
	v_pk_mul_f32 v[34:35], v[36:37], v[32:33]
	v_sub_f32_e32 v39, v34, v35
	v_mov_b32_e32 v34, v37
	v_mov_b32_e32 v35, v36
	v_pk_mul_f32 v[32:33], v[34:35], v[32:33]
	v_cndmask_b32_e32 v34, v50, v40, vcc
	v_add_f32_e32 v32, v32, v33
	v_cvt_pk_bf16_f32 v39, v39, v32
	v_cndmask_b32_e32 v33, v46, v38, vcc
	v_cndmask_b32_e32 v32, v44, v39, vcc
	v_cndmask_b32_e32 v35, v52, v42, vcc
	v_mov_b32_dpp v45, v33 quad_perm:[1,0,3,2] row_mask:0xf bank_mask:0xf
	v_mov_b32_dpp v47, v32 quad_perm:[1,0,3,2] row_mask:0xf bank_mask:0xf
	v_sub_u32_e32 v32, v49, v174
	v_mad_i64_i32 v[32:33], s[4:5], v32, s61, v[126:127]
	v_mov_b32_dpp v41, v35 quad_perm:[1,0,3,2] row_mask:0xf bank_mask:0xf
	v_mov_b32_dpp v43, v34 quad_perm:[1,0,3,2] row_mask:0xf bank_mask:0xf
	v_lshl_add_u64 v[32:33], v[32:33], 0, v[150:151]
	v_lshl_add_u64 v[36:37], v[32:33], 0, v[140:141]
	v_cndmask_b32_e32 v32, v41, v52, vcc
	v_cndmask_b32_e32 v33, v43, v50, vcc
	v_cndmask_b32_e32 v34, v45, v46, vcc
	v_cndmask_b32_e32 v35, v47, v44, vcc
	global_store_dwordx4 v[36:37], v[32:35], off
	v_add_co_u32_e64 v36, s[4:5], s41, v36
	s_nop 0
	v_cndmask_b32_e32 v32, v42, v41, vcc
	v_cndmask_b32_e32 v33, v40, v43, vcc
	v_cndmask_b32_e32 v34, v38, v45, vcc
	v_cndmask_b32_e32 v35, v39, v47, vcc
	v_addc_co_u32_e64 v37, s[4:5], 0, v37, s[4:5]
	global_store_dwordx4 v[36:37], v[32:35], off offset:1024
	s_nop 1
	v_add_u32_e32 v32, 0x2c0, v96
	v_xor_b32_e32 v32, 1, v32
	v_lshl_add_u32 v32, v32, 2, s17
	ds_read_b32 v33, v183 offset:2816
	ds_read_b32 v32, v32
	s_waitcnt lgkmcnt(0)
; __device__ __forceinline__ unsigned cvt_pk_bf16(float lo, float hi) { unsigned r; asm volatile("v_cvt_pk_bf16_f32 %0, %1, %2" : "=v"(r) : "v"(lo), "v"(hi)); return r; }
; __device__ __forceinline__ unsigned dpp_xor1(unsigned v) { return (unsigned)__builtin_amdgcn_update_dpp(0, (int)v, 0xB1, 0xf, 0xf, false); }
; __device__ __forceinline__ float dpp_xor1(float v) { return __int_as_float(__builtin_amdgcn_update_dpp(0, __float_as_int(v), 0xB1, 0xf, 0xf, false)); }
; __device__ __forceinline__ void store_pair_rows(bf16_t* O, size_t ldc, int row, int col0, int fr, u32x4 p0, u32x4 p1) {
;     const bool odd = (fr & 1) != 0;
;     const u32x4 snd = odd ? p0 : p1; u32x4 rcv;
;     rcv.x = dpp_xor1(snd.x); rcv.y = dpp_xor1(snd.y); rcv.z = dpp_xor1(snd.z); rcv.w = dpp_xor1(snd.w);
;     bf16_t* pa = O + (size_t)(row - (odd ? 1 : 0)) * ldc + col0 + (odd ? 8 : 0);
;     *(u32x4*)pa = odd ? rcv : p0;
;     *(u32x4*)(pa + ldc) = odd ? p1 : rcv;
;     __device__ __forceinline__ void operator()(f32x4 (&acc)[2][2][4][2], const Unit& u, int wr, int wc, int fr_in, int fq_in) const {
;     ...
;             for (int ai = 0; ai < 2; ++ai)
; #pragma unroll
;                 for (int m = 0; m < 4; ++m) { const int lr = lr0 + ai * HALF + m * 16;
;                     const float tot = PS[lr * 4 + wc] + PS[lr * 4 + (wc ^ 1)]; const float r2 = __builtin_amdgcn_rsqf(tot * (1.0f / 128.0f) + RMS_EPS);
;                     const int t = (row0 + ai * HALF + m * 16) & (SEQ - 1); const float pos = colaxis ? (float)(t & 63) : (float)(t >> 6);
;                     u32x4 pw[2];
; #pragma unroll
;                     for (int bj = 0; bj < 2; ++bj) {
; #pragma unroll
;                         for (int n = 0; n < 2; ++n) { f32x4 v = acc[ai][bj][m][n] * r2 * gg[bj][n];
; #pragma unroll
;                             for (int h = 0; h < 2; ++h) { const float rev = pos * invf[bj][n][h] * 0.15915494309189535f; const float sn = __builtin_amdgcn_sinf(rev), cs = __builtin_amdgcn_cosf(rev); const float x0 = v[2 * h], x1 = v[2 * h + 1];
;                                 pw[bj][2 * n + h] = cvt_pk_bf16(x0 * cs - x1 * sn, x0 * sn + x1 * cs); } } }
;                     store_pair_rows(O, (size_t)ldc, row0 + ai * HALF + m * 16, col0, fr, pw[0], pw[1]);
	v_add_f32_e32 v32, v33, v32
	v_add_u32_e32 v33, 0xb0, v175
	v_cndmask_b32_e64 v34, v33, v70, s[0:1]
	v_fmamk_f32 v32, v32, 0x3c000000, v172
	v_and_b32_e32 v34, 63, v34
	v_rsq_f32_e32 v32, v32
	v_cvt_f32_ubyte0_e32 v36, v34
	v_mul_f32_e32 v34, v185, v36
	v_mul_f32_e32 v34, 0.15915494, v34
	v_sin_f32_e32 v35, v34
	v_cos_f32_e32 v34, v34
	v_pk_mul_f32 v[30:31], v[30:31], v[32:33] op_sel_hi:[1,0]
	v_pk_mul_f32 v[28:29], v[28:29], v[32:33] op_sel_hi:[1,0]
	v_pk_mul_f32 v[12:13], v[12:13], v[30:31]
	v_mul_f32_e32 v30, v184, v36
	v_mul_f32_e32 v30, 0.15915494, v30
	v_pk_mul_f32 v[14:15], v[14:15], v[28:29]
	v_pk_mul_f32 v[28:29], v[34:35], v[12:13]
	v_sin_f32_e32 v31, v30
	v_cos_f32_e32 v30, v30
	v_sub_f32_e32 v37, v28, v29
	v_mov_b32_e32 v28, v35
	v_mov_b32_e32 v29, v34
	v_pk_mul_f32 v[12:13], v[28:29], v[12:13]
	v_pk_mul_f32 v[24:25], v[24:25], v[32:33] op_sel_hi:[1,0]
	v_add_f32_e32 v12, v12, v13
	v_cvt_pk_bf16_f32 v28, v37, v12
	v_pk_mul_f32 v[12:13], v[30:31], v[14:15]
	v_pk_mul_f32 v[6:7], v[6:7], v[24:25]
	v_sub_f32_e32 v29, v12, v13
	v_mov_b32_e32 v12, v31
	v_mov_b32_e32 v13, v30
	v_pk_mul_f32 v[12:13], v[12:13], v[14:15]
	v_mul_f32_e32 v14, v182, v36
	v_mul_f32_e32 v14, 0.15915494, v14
	v_sin_f32_e32 v15, v14
	v_cos_f32_e32 v14, v14
	v_add_f32_e32 v12, v12, v13
	v_cvt_pk_bf16_f32 v29, v29, v12
	v_pk_mul_f32 v[12:13], v[26:27], v[32:33] op_sel_hi:[1,0]
	s_nop 0
	v_pk_mul_f32 v[4:5], v[4:5], v[12:13]
	s_nop 0
	v_pk_mul_f32 v[12:13], v[14:15], v[4:5]
	s_nop 0
	v_sub_f32_e32 v24, v12, v13
	v_mov_b32_e32 v13, v14
	v_mul_f32_e32 v14, v181, v36
	v_mul_f32_e32 v14, 0.15915494, v14
	v_mov_b32_e32 v12, v15
	v_sin_f32_e32 v15, v14
	v_cos_f32_e32 v14, v14
	v_pk_mul_f32 v[4:5], v[12:13], v[4:5]
	s_nop 0
	v_add_f32_e32 v4, v4, v5
	v_cvt_pk_bf16_f32 v24, v24, v4
	v_pk_mul_f32 v[4:5], v[14:15], v[6:7]
	s_nop 0
	v_sub_f32_e32 v12, v4, v5
	v_mov_b32_e32 v4, v15
	v_mov_b32_e32 v5, v14
	v_pk_mul_f32 v[4:5], v[4:5], v[6:7]
	v_mul_f32_e32 v6, v180, v36
	v_mul_f32_e32 v6, 0.15915494, v6
	v_sin_f32_e32 v7, v6
	v_cos_f32_e32 v6, v6
	v_add_f32_e32 v4, v4, v5
	v_cvt_pk_bf16_f32 v14, v12, v4
	v_pk_mul_f32 v[4:5], v[22:23], v[32:33] op_sel_hi:[1,0]
	v_pk_mul_f32 v[12:13], v[20:21], v[32:33] op_sel_hi:[1,0]
	v_pk_mul_f32 v[4:5], v[8:9], v[4:5]
	v_pk_mul_f32 v[10:11], v[10:11], v[12:13]
	v_pk_mul_f32 v[8:9], v[6:7], v[4:5]
	v_sub_f32_e32 v12, v8, v9
	v_mov_b32_e32 v9, v6
	v_mul_f32_e32 v6, v179, v36
	v_mul_f32_e32 v6, 0.15915494, v6
	v_mov_b32_e32 v8, v7
	v_sin_f32_e32 v7, v6
	v_cos_f32_e32 v6, v6
	v_pk_mul_f32 v[4:5], v[8:9], v[4:5]
	s_nop 0
	v_add_f32_e32 v4, v4, v5
	v_cvt_pk_bf16_f32 v12, v12, v4
	v_pk_mul_f32 v[4:5], v[6:7], v[10:11]
	s_nop 0
	v_sub_f32_e32 v8, v4, v5
	v_mov_b32_e32 v5, v6
	v_mul_f32_e32 v6, v178, v36
	v_mov_b32_e32 v4, v7
	v_mul_f32_e32 v6, 0.15915494, v6
	v_pk_mul_f32 v[4:5], v[4:5], v[10:11]
	v_sin_f32_e32 v7, v6
	v_cos_f32_e32 v6, v6
	v_add_f32_e32 v4, v4, v5
	v_cvt_pk_bf16_f32 v10, v8, v4
	v_pk_mul_f32 v[4:5], v[18:19], v[32:33] op_sel_hi:[1,0]
	v_pk_mul_f32 v[8:9], v[16:17], v[32:33] op_sel_hi:[1,0]
	v_pk_mul_f32 v[0:1], v[0:1], v[4:5]
	v_pk_mul_f32 v[2:3], v[2:3], v[8:9]
	v_pk_mul_f32 v[4:5], v[6:7], v[0:1]
	v_sub_f32_e32 v8, v4, v5
	v_mov_b32_e32 v5, v6
	v_mul_f32_e32 v6, v177, v36
	v_mul_f32_e32 v6, 0.15915494, v6
	v_mov_b32_e32 v4, v7
	v_sin_f32_e32 v7, v6
	v_cos_f32_e32 v6, v6
	v_pk_mul_f32 v[0:1], v[4:5], v[0:1]
	v_add_f32_e32 v0, v0, v1
	v_cvt_pk_bf16_f32 v8, v8, v0
	v_pk_mul_f32 v[0:1], v[6:7], v[2:3]
	s_nop 0
	v_sub_f32_e32 v4, v0, v1
	v_mov_b32_e32 v0, v7
	v_mov_b32_e32 v1, v6
	v_pk_mul_f32 v[0:1], v[0:1], v[2:3]
	v_cndmask_b32_e32 v2, v29, v10, vcc
	v_add_f32_e32 v0, v0, v1
	v_cvt_pk_bf16_f32 v6, v4, v0
	v_cndmask_b32_e32 v1, v24, v8, vcc
	v_cndmask_b32_e32 v0, v14, v6, vcc
	v_cndmask_b32_e32 v3, v28, v12, vcc
	s_nop 1
	v_mov_b32_dpp v13, v0 quad_perm:[1,0,3,2] row_mask:0xf bank_mask:0xf
	v_sub_u32_e32 v0, v33, v174
	v_mov_b32_dpp v11, v1 quad_perm:[1,0,3,2] row_mask:0xf bank_mask:0xf
	v_mad_i64_i32 v[0:1], s[4:5], v0, s61, v[126:127]
	v_mov_b32_dpp v7, v3 quad_perm:[1,0,3,2] row_mask:0xf bank_mask:0xf
	v_mov_b32_dpp v9, v2 quad_perm:[1,0,3,2] row_mask:0xf bank_mask:0xf
	v_lshl_add_u64 v[0:1], v[0:1], 0, v[150:151]
	v_lshl_add_u64 v[4:5], v[0:1], 0, v[140:141]
	v_cndmask_b32_e32 v0, v7, v28, vcc
	v_cndmask_b32_e32 v1, v9, v29, vcc
	v_cndmask_b32_e32 v2, v11, v24, vcc
	v_cndmask_b32_e32 v3, v13, v14, vcc
	global_store_dwordx4 v[4:5], v[0:3], off
	s_nop 1
	v_cndmask_b32_e32 v0, v12, v7, vcc
	v_cndmask_b32_e32 v1, v10, v9, vcc
	v_cndmask_b32_e32 v2, v8, v11, vcc
	v_cndmask_b32_e32 v3, v6, v13, vcc
	v_add_co_u32_e32 v4, vcc, 0x2000, v4
	s_nop 1
	v_addc_co_u32_e32 v5, vcc, 0, v5, vcc
	global_store_dwordx4 v[4:5], v[0:3], off offset:1024

; #define ltid() ltid_(wave0)
; #define P10_WEIGHTS() do { if (ucnt10++ == wslot10) { __syncthreads(); PH_IDS gfp w_up = TAB(17); gfp w_down = TAB(20); gfp ln_ffn = TAB(2); \
;             transpose_weight(w_up + (size_t)DM * DFF2, DM, DFF2, Wup, ln_ffn + DM, scr, gw, ngw, lane, true); \
;             transpose_weight(w_down + (size_t)DFF * DM, DFF, DM, Wdn, nullptr, scr, gw, ngw, lane); __syncthreads(); } } while (0)
; __global__ void __launch_bounds__(NTHREADS, 2) mk_fwd(Args args) {
;     ...
;         for (int idx = vcu; idx < NC_UNITS; idx += G) {
;             att::AttnP P; P.lse = nullptr; P.lse_ld = 0; P.ldq = OD_IN; P.ldk = OD_IN; P.ldo = DM; P.lbase = 0; P.krow0 = 0; P.qtok0 = 0; P.lut = nullptr; P.lut_n = 0; P.far_thr = 1 << 30; P.q0abs = 0; P.cidx = 0;
;             {
;                 const int qblk = idx & 15, hq = (idx >> 4) & 7, b = idx >> 7;
;                 const bf16_t* base = BIG + (size_t)b * SEQ * OD_IN;
;                 P.Q = base + (size_t)(qblk * 256) * OD_IN + hq * 128; P.K = base + 1024 + (hq >> 2) * 128; P.V = base + 1280 + (hq >> 2) * 128;
;                 P.O = R1 + ((size_t)b * SEQ + qblk * 256) * DM + hq * 128; P.NT = SEQ / 64;
;                 if (ATT_EN & 1) att::attn_unit<0, 2, false>(P, (char*)lds, ltid());
;                 P10_WEIGHTS();
;             }
;         }
.LBB0_1427:
	v_readlane_b32 s0, v254, 48
	s_add_i32 s0, s0, 1
	s_add_i32 s61, s61, s68
	s_nop 1
	v_writelane_b32 v254, s0, 48
	s_cmpk_gt_i32 s61, 0x1ff
	s_cbranch_scc1 .LBB0_1594

; __device__ __forceinline__ unsigned cvt_pk_bf16(float lo, float hi) { unsigned r; asm volatile("v_cvt_pk_bf16_f32 %0, %1, %2" : "=v"(r) : "v"(lo), "v"(hi)); return r; }
; __device__ __forceinline__ unsigned dpp_xor1(unsigned v) { return (unsigned)__builtin_amdgcn_update_dpp(0, (int)v, 0xB1, 0xf, 0xf, false); }
; __device__ __forceinline__ float dpp_xor1(float v) { return __int_as_float(__builtin_amdgcn_update_dpp(0, __float_as_int(v), 0xB1, 0xf, 0xf, false)); }
; __device__ __forceinline__ int crow(int r, int hi) { return (r & 3) + 8 * (r >> 2) + 4 * hi; }
; template <int MODE, int SDEPTH, bool QL>
; __device__ __forceinline__ void attn_unit(const AttnP& P, char* lds, const int tid) {
;     ...
;     float rli[16];
; #pragma unroll
;     for (int r = 0; r < 16; ++r) rli[r] = __builtin_amdgcn_rcpf(li_l[crow(r, hi)]);
;     __syncthreads();
;     {
;         char* st = lds + wid * 10240;
;         const bool odd = (r32 & 1) != 0;
;         const int sbase = (crow(0, hi) + (odd ? 1 : 0)) * 320 + (r32 & ~1) * 2;
; #pragma unroll
;         for (int d0 = 0; d0 < 4; ++d0)
; #pragma unroll
;             for (int rp = 0; rp < 8; ++rp) { const int r = 2 * rp;
;                 const float a = o[d0][r] * rli[r], b = o[d0][r + 1] * rli[r + 1];
;                 const float t = odd ? a : b; const float rcv = dpp_xor1(t);
;                 const unsigned w = odd ? cvt_pk_bf16(rcv, b) : cvt_pk_bf16(a, rcv);
;                 *(unsigned*)(st + sbase + (crow(r, 0)) * 320 + d0 * 64) = w; }
.LBB0_1451:
	s_or_b64 exec, exec, s[2:3]
	s_movk_i32 s2, 0x2800
	v_rcp_f32_e32 v78, v78
	v_rcp_f32_e32 v79, v79
	v_mul_lo_u32 v48, v202, s2
	v_add_u32_e32 v48, 0, v48
	v_lshl_or_b32 v49, v203, 2, v80
	v_and_b32_e32 v80, 60, v204
	v_mad_u32_u24 v49, v49, s46, v48
	v_add_u32_e32 v49, v49, v80
	ds_write_b32 v49, v81
	v_mul_f32_e32 v50, v50, v78
	v_mul_f32_e32 v81, v51, v79
	v_cndmask_b32_e64 v80, v50, v81, s[0:1]
	s_nop 1
	v_mov_b32_dpp v51, v80 quad_perm:[1,0,3,2] row_mask:0xf bank_mask:0xf
	s_and_saveexec_b64 s[2:3], vcc
	s_xor_b64 s[2:3], exec, s[2:3]
	s_cbranch_execz .LBB0_1453
	v_cvt_pk_bf16_f32 v80, v51, v81

; __device__ __forceinline__ unsigned cvt_pk_bf16(float lo, float hi) { unsigned r; asm volatile("v_cvt_pk_bf16_f32 %0, %1, %2" : "=v"(r) : "v"(lo), "v"(hi)); return r; }
; __device__ __forceinline__ unsigned dpp_xor1(unsigned v) { return (unsigned)__builtin_amdgcn_update_dpp(0, (int)v, 0xB1, 0xf, 0xf, false); }
; __device__ __forceinline__ float dpp_xor1(float v) { return __int_as_float(__builtin_amdgcn_update_dpp(0, __float_as_int(v), 0xB1, 0xf, 0xf, false)); }
; __device__ __forceinline__ int crow(int r, int hi) { return (r & 3) + 8 * (r >> 2) + 4 * hi; }
; template <int MODE, int SDEPTH, bool QL>
; __device__ __forceinline__ void attn_unit(const AttnP& P, char* lds, const int tid) {
;     ...
;     float rli[16];
; #pragma unroll
;     for (int r = 0; r < 16; ++r) rli[r] = __builtin_amdgcn_rcpf(li_l[crow(r, hi)]);
;     __syncthreads();
;     {
;         char* st = lds + wid * 10240;
;         const bool odd = (r32 & 1) != 0;
;         const int sbase = (crow(0, hi) + (odd ? 1 : 0)) * 320 + (r32 & ~1) * 2;
; #pragma unroll
;         for (int d0 = 0; d0 < 4; ++d0)
; #pragma unroll
;             for (int rp = 0; rp < 8; ++rp) { const int r = 2 * rp;
;                 const float a = o[d0][r] * rli[r], b = o[d0][r + 1] * rli[r + 1];
;                 const float t = odd ? a : b; const float rcv = dpp_xor1(t);
;                 const unsigned w = odd ? cvt_pk_bf16(rcv, b) : cvt_pk_bf16(a, rcv);
;                 *(unsigned*)(st + sbase + (crow(r, 0)) * 320 + d0 * 64) = w; }
.LBB0_1455:
	s_or_b64 exec, exec, s[2:3]
	v_rcp_f32_e32 v50, v72
	v_rcp_f32_e32 v51, v73
	ds_write_b32 v49, v80 offset:640
	v_mul_f32_e32 v52, v52, v50
	v_mul_f32_e32 v73, v53, v51
	v_cndmask_b32_e64 v72, v52, v73, s[0:1]
	s_nop 1
	v_mov_b32_dpp v53, v72 quad_perm:[1,0,3,2] row_mask:0xf bank_mask:0xf
	s_and_saveexec_b64 s[2:3], vcc
	s_xor_b64 s[2:3], exec, s[2:3]
	s_cbranch_execz .LBB0_1457
	v_cvt_pk_bf16_f32 v72, v53, v73

; __device__ __forceinline__ unsigned cvt_pk_bf16(float lo, float hi) { unsigned r; asm volatile("v_cvt_pk_bf16_f32 %0, %1, %2" : "=v"(r) : "v"(lo), "v"(hi)); return r; }
; __device__ __forceinline__ unsigned dpp_xor1(unsigned v) { return (unsigned)__builtin_amdgcn_update_dpp(0, (int)v, 0xB1, 0xf, 0xf, false); }
; __device__ __forceinline__ float dpp_xor1(float v) { return __int_as_float(__builtin_amdgcn_update_dpp(0, __float_as_int(v), 0xB1, 0xf, 0xf, false)); }
; __device__ __forceinline__ int crow(int r, int hi) { return (r & 3) + 8 * (r >> 2) + 4 * hi; }
; template <int MODE, int SDEPTH, bool QL>
; __device__ __forceinline__ void attn_unit(const AttnP& P, char* lds, const int tid) {
;     ...
;     float rli[16];
; #pragma unroll
;     for (int r = 0; r < 16; ++r) rli[r] = __builtin_amdgcn_rcpf(li_l[crow(r, hi)]);
;     __syncthreads();
;     {
;         char* st = lds + wid * 10240;
;         const bool odd = (r32 & 1) != 0;
;         const int sbase = (crow(0, hi) + (odd ? 1 : 0)) * 320 + (r32 & ~1) * 2;
; #pragma unroll
;         for (int d0 = 0; d0 < 4; ++d0)
; #pragma unroll
;             for (int rp = 0; rp < 8; ++rp) { const int r = 2 * rp;
;                 const float a = o[d0][r] * rli[r], b = o[d0][r + 1] * rli[r + 1];
;                 const float t = odd ? a : b; const float rcv = dpp_xor1(t);
;                 const unsigned w = odd ? cvt_pk_bf16(rcv, b) : cvt_pk_bf16(a, rcv);
;                 *(unsigned*)(st + sbase + (crow(r, 0)) * 320 + d0 * 64) = w; }
.LBB0_1459:
	s_or_b64 exec, exec, s[2:3]
	v_rcp_f32_e32 v52, v74
	v_rcp_f32_e32 v53, v75
	ds_write_b32 v49, v72 offset:2560
	v_mul_f32_e32 v54, v54, v52
	v_mul_f32_e32 v73, v55, v53
	v_cndmask_b32_e64 v72, v54, v73, s[0:1]
	s_nop 1
	v_mov_b32_dpp v55, v72 quad_perm:[1,0,3,2] row_mask:0xf bank_mask:0xf
	s_and_saveexec_b64 s[2:3], vcc
	s_xor_b64 s[2:3], exec, s[2:3]
	s_cbranch_execz .LBB0_1461
	v_cvt_pk_bf16_f32 v72, v55, v73

; __device__ __forceinline__ unsigned cvt_pk_bf16(float lo, float hi) { unsigned r; asm volatile("v_cvt_pk_bf16_f32 %0, %1, %2" : "=v"(r) : "v"(lo), "v"(hi)); return r; }
; __device__ __forceinline__ unsigned dpp_xor1(unsigned v) { return (unsigned)__builtin_amdgcn_update_dpp(0, (int)v, 0xB1, 0xf, 0xf, false); }
; __device__ __forceinline__ float dpp_xor1(float v) { return __int_as_float(__builtin_amdgcn_update_dpp(0, __float_as_int(v), 0xB1, 0xf, 0xf, false)); }
; __device__ __forceinline__ int crow(int r, int hi) { return (r & 3) + 8 * (r >> 2) + 4 * hi; }
; template <int MODE, int SDEPTH, bool QL>
; __device__ __forceinline__ void attn_unit(const AttnP& P, char* lds, const int tid) {
;     ...
;     float rli[16];
; #pragma unroll
;     for (int r = 0; r < 16; ++r) rli[r] = __builtin_amdgcn_rcpf(li_l[crow(r, hi)]);
;     __syncthreads();
;     {
;         char* st = lds + wid * 10240;
;         const bool odd = (r32 & 1) != 0;
;         const int sbase = (crow(0, hi) + (odd ? 1 : 0)) * 320 + (r32 & ~1) * 2;
; #pragma unroll
;         for (int d0 = 0; d0 < 4; ++d0)
; #pragma unroll
;             for (int rp = 0; rp < 8; ++rp) { const int r = 2 * rp;
;                 const float a = o[d0][r] * rli[r], b = o[d0][r + 1] * rli[r + 1];
;                 const float t = odd ? a : b; const float rcv = dpp_xor1(t);
;                 const unsigned w = odd ? cvt_pk_bf16(rcv, b) : cvt_pk_bf16(a, rcv);
;                 *(unsigned*)(st + sbase + (crow(r, 0)) * 320 + d0 * 64) = w; }
.LBB0_1463:
	s_or_b64 exec, exec, s[2:3]
	v_rcp_f32_e32 v54, v68
	v_rcp_f32_e32 v55, v69
	ds_write_b32 v49, v72 offset:3200
	v_mul_f32_e32 v56, v56, v54
	v_mul_f32_e32 v69, v57, v55
	v_cndmask_b32_e64 v68, v56, v69, s[0:1]
	s_nop 1
	v_mov_b32_dpp v57, v68 quad_perm:[1,0,3,2] row_mask:0xf bank_mask:0xf
	s_and_saveexec_b64 s[2:3], vcc
	s_xor_b64 s[2:3], exec, s[2:3]
	s_cbranch_execz .LBB0_1465
	v_cvt_pk_bf16_f32 v68, v57, v69

; __device__ __forceinline__ unsigned cvt_pk_bf16(float lo, float hi) { unsigned r; asm volatile("v_cvt_pk_bf16_f32 %0, %1, %2" : "=v"(r) : "v"(lo), "v"(hi)); return r; }
; __device__ __forceinline__ unsigned dpp_xor1(unsigned v) { return (unsigned)__builtin_amdgcn_update_dpp(0, (int)v, 0xB1, 0xf, 0xf, false); }
; __device__ __forceinline__ float dpp_xor1(float v) { return __int_as_float(__builtin_amdgcn_update_dpp(0, __float_as_int(v), 0xB1, 0xf, 0xf, false)); }
; __device__ __forceinline__ int crow(int r, int hi) { return (r & 3) + 8 * (r >> 2) + 4 * hi; }
; template <int MODE, int SDEPTH, bool QL>
; __device__ __forceinline__ void attn_unit(const AttnP& P, char* lds, const int tid) {
;     ...
;     float rli[16];
; #pragma unroll
;     for (int r = 0; r < 16; ++r) rli[r] = __builtin_amdgcn_rcpf(li_l[crow(r, hi)]);
;     __syncthreads();
;     {
;         char* st = lds + wid * 10240;
;         const bool odd = (r32 & 1) != 0;
;         const int sbase = (crow(0, hi) + (odd ? 1 : 0)) * 320 + (r32 & ~1) * 2;
; #pragma unroll
;         for (int d0 = 0; d0 < 4; ++d0)
; #pragma unroll
;             for (int rp = 0; rp < 8; ++rp) { const int r = 2 * rp;
;                 const float a = o[d0][r] * rli[r], b = o[d0][r + 1] * rli[r + 1];
;                 const float t = odd ? a : b; const float rcv = dpp_xor1(t);
;                 const unsigned w = odd ? cvt_pk_bf16(rcv, b) : cvt_pk_bf16(a, rcv);
;                 *(unsigned*)(st + sbase + (crow(r, 0)) * 320 + d0 * 64) = w; }
.LBB0_1467:
	s_or_b64 exec, exec, s[2:3]
	v_rcp_f32_e32 v56, v70
	v_rcp_f32_e32 v57, v71
	ds_write_b32 v49, v68 offset:5120
	v_mul_f32_e32 v58, v58, v56
	v_mul_f32_e32 v69, v59, v57
	v_cndmask_b32_e64 v68, v58, v69, s[0:1]
	s_nop 1
	v_mov_b32_dpp v59, v68 quad_perm:[1,0,3,2] row_mask:0xf bank_mask:0xf
	s_and_saveexec_b64 s[2:3], vcc
	s_xor_b64 s[2:3], exec, s[2:3]
	s_cbranch_execz .LBB0_1469
	v_cvt_pk_bf16_f32 v68, v59, v69

; __device__ __forceinline__ unsigned cvt_pk_bf16(float lo, float hi) { unsigned r; asm volatile("v_cvt_pk_bf16_f32 %0, %1, %2" : "=v"(r) : "v"(lo), "v"(hi)); return r; }
; __device__ __forceinline__ unsigned dpp_xor1(unsigned v) { return (unsigned)__builtin_amdgcn_update_dpp(0, (int)v, 0xB1, 0xf, 0xf, false); }
; __device__ __forceinline__ float dpp_xor1(float v) { return __int_as_float(__builtin_amdgcn_update_dpp(0, __float_as_int(v), 0xB1, 0xf, 0xf, false)); }
; __device__ __forceinline__ int crow(int r, int hi) { return (r & 3) + 8 * (r >> 2) + 4 * hi; }
; template <int MODE, int SDEPTH, bool QL>
; __device__ __forceinline__ void attn_unit(const AttnP& P, char* lds, const int tid) {
;     ...
;     float rli[16];
; #pragma unroll
;     for (int r = 0; r < 16; ++r) rli[r] = __builtin_amdgcn_rcpf(li_l[crow(r, hi)]);
;     __syncthreads();
;     {
;         char* st = lds + wid * 10240;
;         const bool odd = (r32 & 1) != 0;
;         const int sbase = (crow(0, hi) + (odd ? 1 : 0)) * 320 + (r32 & ~1) * 2;
; #pragma unroll
;         for (int d0 = 0; d0 < 4; ++d0)
; #pragma unroll
;             for (int rp = 0; rp < 8; ++rp) { const int r = 2 * rp;
;                 const float a = o[d0][r] * rli[r], b = o[d0][r + 1] * rli[r + 1];
;                 const float t = odd ? a : b; const float rcv = dpp_xor1(t);
;                 const unsigned w = odd ? cvt_pk_bf16(rcv, b) : cvt_pk_bf16(a, rcv);
;                 *(unsigned*)(st + sbase + (crow(r, 0)) * 320 + d0 * 64) = w; }
.LBB0_1471:
	s_or_b64 exec, exec, s[2:3]
	v_rcp_f32_e32 v58, v64
	v_rcp_f32_e32 v59, v65
	ds_write_b32 v49, v68 offset:5760
	v_mul_f32_e32 v60, v60, v58
	v_mul_f32_e32 v65, v61, v59
	v_cndmask_b32_e64 v64, v60, v65, s[0:1]
	s_nop 1
	v_mov_b32_dpp v61, v64 quad_perm:[1,0,3,2] row_mask:0xf bank_mask:0xf
	s_and_saveexec_b64 s[2:3], vcc
	s_xor_b64 s[2:3], exec, s[2:3]
	s_cbranch_execz .LBB0_1473
	v_cvt_pk_bf16_f32 v64, v61, v65

; __device__ __forceinline__ unsigned cvt_pk_bf16(float lo, float hi) { unsigned r; asm volatile("v_cvt_pk_bf16_f32 %0, %1, %2" : "=v"(r) : "v"(lo), "v"(hi)); return r; }
; __device__ __forceinline__ unsigned dpp_xor1(unsigned v) { return (unsigned)__builtin_amdgcn_update_dpp(0, (int)v, 0xB1, 0xf, 0xf, false); }
; __device__ __forceinline__ float dpp_xor1(float v) { return __int_as_float(__builtin_amdgcn_update_dpp(0, __float_as_int(v), 0xB1, 0xf, 0xf, false)); }
; __device__ __forceinline__ int crow(int r, int hi) { return (r & 3) + 8 * (r >> 2) + 4 * hi; }
; template <int MODE, int SDEPTH, bool QL>
; __device__ __forceinline__ void attn_unit(const AttnP& P, char* lds, const int tid) {
;     ...
;     float rli[16];
; #pragma unroll
;     for (int r = 0; r < 16; ++r) rli[r] = __builtin_amdgcn_rcpf(li_l[crow(r, hi)]);
;     __syncthreads();
;     {
;         char* st = lds + wid * 10240;
;         const bool odd = (r32 & 1) != 0;
;         const int sbase = (crow(0, hi) + (odd ? 1 : 0)) * 320 + (r32 & ~1) * 2;
; #pragma unroll
;         for (int d0 = 0; d0 < 4; ++d0)
; #pragma unroll
;             for (int rp = 0; rp < 8; ++rp) { const int r = 2 * rp;
;                 const float a = o[d0][r] * rli[r], b = o[d0][r + 1] * rli[r + 1];
;                 const float t = odd ? a : b; const float rcv = dpp_xor1(t);
;                 const unsigned w = odd ? cvt_pk_bf16(rcv, b) : cvt_pk_bf16(a, rcv);
;                 *(unsigned*)(st + sbase + (crow(r, 0)) * 320 + d0 * 64) = w; }
.LBB0_1475:
	s_or_b64 exec, exec, s[2:3]
	v_rcp_f32_e32 v60, v66
	v_rcp_f32_e32 v61, v67
	ds_write_b32 v49, v64 offset:7680
	v_mul_f32_e32 v64, v62, v60
	v_mul_f32_e32 v65, v63, v61
	v_cndmask_b32_e64 v62, v64, v65, s[0:1]
	s_nop 1
	v_mov_b32_dpp v63, v62 quad_perm:[1,0,3,2] row_mask:0xf bank_mask:0xf
	s_and_saveexec_b64 s[2:3], vcc
	s_xor_b64 s[2:3], exec, s[2:3]
	s_cbranch_execz .LBB0_1477
	v_cvt_pk_bf16_f32 v62, v63, v65

; __device__ __forceinline__ unsigned cvt_pk_bf16(float lo, float hi) { unsigned r; asm volatile("v_cvt_pk_bf16_f32 %0, %1, %2" : "=v"(r) : "v"(lo), "v"(hi)); return r; }
; __device__ __forceinline__ unsigned dpp_xor1(unsigned v) { return (unsigned)__builtin_amdgcn_update_dpp(0, (int)v, 0xB1, 0xf, 0xf, false); }
; __device__ __forceinline__ float dpp_xor1(float v) { return __int_as_float(__builtin_amdgcn_update_dpp(0, __float_as_int(v), 0xB1, 0xf, 0xf, false)); }
; __device__ __forceinline__ int crow(int r, int hi) { return (r & 3) + 8 * (r >> 2) + 4 * hi; }
; template <int MODE, int SDEPTH, bool QL>
; __device__ __forceinline__ void attn_unit(const AttnP& P, char* lds, const int tid) {
;     ...
;     float rli[16];
; #pragma unroll
;     for (int r = 0; r < 16; ++r) rli[r] = __builtin_amdgcn_rcpf(li_l[crow(r, hi)]);
;     __syncthreads();
;     {
;         char* st = lds + wid * 10240;
;         const bool odd = (r32 & 1) != 0;
;         const int sbase = (crow(0, hi) + (odd ? 1 : 0)) * 320 + (r32 & ~1) * 2;
; #pragma unroll
;         for (int d0 = 0; d0 < 4; ++d0)
; #pragma unroll
;             for (int rp = 0; rp < 8; ++rp) { const int r = 2 * rp;
;                 const float a = o[d0][r] * rli[r], b = o[d0][r + 1] * rli[r + 1];
;                 const float t = odd ? a : b; const float rcv = dpp_xor1(t);
;                 const unsigned w = odd ? cvt_pk_bf16(rcv, b) : cvt_pk_bf16(a, rcv);
;                 *(unsigned*)(st + sbase + (crow(r, 0)) * 320 + d0 * 64) = w; }
.LBB0_1479:
	s_or_b64 exec, exec, s[2:3]
	ds_write_b32 v49, v62 offset:8320
	v_mul_f32_e32 v62, v32, v76
	v_mul_f32_e32 v63, v33, v77
	v_cndmask_b32_e64 v32, v62, v63, s[0:1]
	s_nop 1
	v_mov_b32_dpp v33, v32 quad_perm:[1,0,3,2] row_mask:0xf bank_mask:0xf
	s_and_saveexec_b64 s[2:3], vcc
	s_xor_b64 s[2:3], exec, s[2:3]
	s_cbranch_execz .LBB0_1481
	v_cvt_pk_bf16_f32 v32, v33, v63

; __device__ __forceinline__ unsigned cvt_pk_bf16(float lo, float hi) { unsigned r; asm volatile("v_cvt_pk_bf16_f32 %0, %1, %2" : "=v"(r) : "v"(lo), "v"(hi)); return r; }
; __device__ __forceinline__ unsigned dpp_xor1(unsigned v) { return (unsigned)__builtin_amdgcn_update_dpp(0, (int)v, 0xB1, 0xf, 0xf, false); }
; __device__ __forceinline__ float dpp_xor1(float v) { return __int_as_float(__builtin_amdgcn_update_dpp(0, __float_as_int(v), 0xB1, 0xf, 0xf, false)); }
; __device__ __forceinline__ int crow(int r, int hi) { return (r & 3) + 8 * (r >> 2) + 4 * hi; }
; template <int MODE, int SDEPTH, bool QL>
; __device__ __forceinline__ void attn_unit(const AttnP& P, char* lds, const int tid) {
;     ...
;     float rli[16];
; #pragma unroll
;     for (int r = 0; r < 16; ++r) rli[r] = __builtin_amdgcn_rcpf(li_l[crow(r, hi)]);
;     __syncthreads();
;     {
;         char* st = lds + wid * 10240;
;         const bool odd = (r32 & 1) != 0;
;         const int sbase = (crow(0, hi) + (odd ? 1 : 0)) * 320 + (r32 & ~1) * 2;
; #pragma unroll
;         for (int d0 = 0; d0 < 4; ++d0)
; #pragma unroll
;             for (int rp = 0; rp < 8; ++rp) { const int r = 2 * rp;
;                 const float a = o[d0][r] * rli[r], b = o[d0][r + 1] * rli[r + 1];
;                 const float t = odd ? a : b; const float rcv = dpp_xor1(t);
;                 const unsigned w = odd ? cvt_pk_bf16(rcv, b) : cvt_pk_bf16(a, rcv);
;                 *(unsigned*)(st + sbase + (crow(r, 0)) * 320 + d0 * 64) = w; }
.LBB0_1483:
	s_or_b64 exec, exec, s[2:3]
	v_mul_f32_e32 v33, v34, v78
	v_mul_f32_e32 v35, v35, v79
	ds_write_b32 v49, v32 offset:64
	v_cndmask_b32_e64 v32, v33, v35, s[0:1]
	s_nop 1
	v_mov_b32_dpp v34, v32 quad_perm:[1,0,3,2] row_mask:0xf bank_mask:0xf
	s_and_saveexec_b64 s[2:3], vcc
	s_xor_b64 s[2:3], exec, s[2:3]
	s_cbranch_execz .LBB0_1485
	v_cvt_pk_bf16_f32 v32, v34, v35

; __device__ __forceinline__ unsigned cvt_pk_bf16(float lo, float hi) { unsigned r; asm volatile("v_cvt_pk_bf16_f32 %0, %1, %2" : "=v"(r) : "v"(lo), "v"(hi)); return r; }
; __device__ __forceinline__ unsigned dpp_xor1(unsigned v) { return (unsigned)__builtin_amdgcn_update_dpp(0, (int)v, 0xB1, 0xf, 0xf, false); }
; __device__ __forceinline__ float dpp_xor1(float v) { return __int_as_float(__builtin_amdgcn_update_dpp(0, __float_as_int(v), 0xB1, 0xf, 0xf, false)); }
; __device__ __forceinline__ int crow(int r, int hi) { return (r & 3) + 8 * (r >> 2) + 4 * hi; }
; template <int MODE, int SDEPTH, bool QL>
; __device__ __forceinline__ void attn_unit(const AttnP& P, char* lds, const int tid) {
;     ...
;     float rli[16];
; #pragma unroll
;     for (int r = 0; r < 16; ++r) rli[r] = __builtin_amdgcn_rcpf(li_l[crow(r, hi)]);
;     __syncthreads();
;     {
;         char* st = lds + wid * 10240;
;         const bool odd = (r32 & 1) != 0;
;         const int sbase = (crow(0, hi) + (odd ? 1 : 0)) * 320 + (r32 & ~1) * 2;
; #pragma unroll
;         for (int d0 = 0; d0 < 4; ++d0)
; #pragma unroll
;             for (int rp = 0; rp < 8; ++rp) { const int r = 2 * rp;
;                 const float a = o[d0][r] * rli[r], b = o[d0][r + 1] * rli[r + 1];
;                 const float t = odd ? a : b; const float rcv = dpp_xor1(t);
;                 const unsigned w = odd ? cvt_pk_bf16(rcv, b) : cvt_pk_bf16(a, rcv);
;                 *(unsigned*)(st + sbase + (crow(r, 0)) * 320 + d0 * 64) = w; }
.LBB0_1487:
	s_or_b64 exec, exec, s[2:3]
	v_mul_f32_e32 v33, v36, v50
	v_mul_f32_e32 v35, v37, v51
	ds_write_b32 v49, v32 offset:704
	v_cndmask_b32_e64 v32, v33, v35, s[0:1]
	s_nop 1
	v_mov_b32_dpp v34, v32 quad_perm:[1,0,3,2] row_mask:0xf bank_mask:0xf
	s_and_saveexec_b64 s[2:3], vcc
	s_xor_b64 s[2:3], exec, s[2:3]
	s_cbranch_execz .LBB0_1489
	v_cvt_pk_bf16_f32 v32, v34, v35

; __device__ __forceinline__ unsigned cvt_pk_bf16(float lo, float hi) { unsigned r; asm volatile("v_cvt_pk_bf16_f32 %0, %1, %2" : "=v"(r) : "v"(lo), "v"(hi)); return r; }
; __device__ __forceinline__ unsigned dpp_xor1(unsigned v) { return (unsigned)__builtin_amdgcn_update_dpp(0, (int)v, 0xB1, 0xf, 0xf, false); }
; __device__ __forceinline__ float dpp_xor1(float v) { return __int_as_float(__builtin_amdgcn_update_dpp(0, __float_as_int(v), 0xB1, 0xf, 0xf, false)); }
; __device__ __forceinline__ int crow(int r, int hi) { return (r & 3) + 8 * (r >> 2) + 4 * hi; }
; template <int MODE, int SDEPTH, bool QL>
; __device__ __forceinline__ void attn_unit(const AttnP& P, char* lds, const int tid) {
;     ...
;     float rli[16];
; #pragma unroll
;     for (int r = 0; r < 16; ++r) rli[r] = __builtin_amdgcn_rcpf(li_l[crow(r, hi)]);
;     __syncthreads();
;     {
;         char* st = lds + wid * 10240;
;         const bool odd = (r32 & 1) != 0;
;         const int sbase = (crow(0, hi) + (odd ? 1 : 0)) * 320 + (r32 & ~1) * 2;
; #pragma unroll
;         for (int d0 = 0; d0 < 4; ++d0)
; #pragma unroll
;             for (int rp = 0; rp < 8; ++rp) { const int r = 2 * rp;
;                 const float a = o[d0][r] * rli[r], b = o[d0][r + 1] * rli[r + 1];
;                 const float t = odd ? a : b; const float rcv = dpp_xor1(t);
;                 const unsigned w = odd ? cvt_pk_bf16(rcv, b) : cvt_pk_bf16(a, rcv);
;                 *(unsigned*)(st + sbase + (crow(r, 0)) * 320 + d0 * 64) = w; }
.LBB0_1491:
	s_or_b64 exec, exec, s[2:3]
	v_mul_f32_e32 v33, v38, v52
	v_mul_f32_e32 v35, v39, v53
	ds_write_b32 v49, v32 offset:2624
	v_cndmask_b32_e64 v32, v33, v35, s[0:1]
	s_nop 1
	v_mov_b32_dpp v34, v32 quad_perm:[1,0,3,2] row_mask:0xf bank_mask:0xf
	s_and_saveexec_b64 s[2:3], vcc
	s_xor_b64 s[2:3], exec, s[2:3]
	s_cbranch_execz .LBB0_1493
	v_cvt_pk_bf16_f32 v32, v34, v35

; __device__ __forceinline__ unsigned cvt_pk_bf16(float lo, float hi) { unsigned r; asm volatile("v_cvt_pk_bf16_f32 %0, %1, %2" : "=v"(r) : "v"(lo), "v"(hi)); return r; }
; __device__ __forceinline__ unsigned dpp_xor1(unsigned v) { return (unsigned)__builtin_amdgcn_update_dpp(0, (int)v, 0xB1, 0xf, 0xf, false); }
; __device__ __forceinline__ float dpp_xor1(float v) { return __int_as_float(__builtin_amdgcn_update_dpp(0, __float_as_int(v), 0xB1, 0xf, 0xf, false)); }
; __device__ __forceinline__ int crow(int r, int hi) { return (r & 3) + 8 * (r >> 2) + 4 * hi; }
; template <int MODE, int SDEPTH, bool QL>
; __device__ __forceinline__ void attn_unit(const AttnP& P, char* lds, const int tid) {
;     ...
;     float rli[16];
; #pragma unroll
;     for (int r = 0; r < 16; ++r) rli[r] = __builtin_amdgcn_rcpf(li_l[crow(r, hi)]);
;     __syncthreads();
;     {
;         char* st = lds + wid * 10240;
;         const bool odd = (r32 & 1) != 0;
;         const int sbase = (crow(0, hi) + (odd ? 1 : 0)) * 320 + (r32 & ~1) * 2;
; #pragma unroll
;         for (int d0 = 0; d0 < 4; ++d0)
; #pragma unroll
;             for (int rp = 0; rp < 8; ++rp) { const int r = 2 * rp;
;                 const float a = o[d0][r] * rli[r], b = o[d0][r + 1] * rli[r + 1];
;                 const float t = odd ? a : b; const float rcv = dpp_xor1(t);
;                 const unsigned w = odd ? cvt_pk_bf16(rcv, b) : cvt_pk_bf16(a, rcv);
;                 *(unsigned*)(st + sbase + (crow(r, 0)) * 320 + d0 * 64) = w; }
.LBB0_1495:
	s_or_b64 exec, exec, s[2:3]
	v_mul_f32_e32 v33, v40, v54
	v_mul_f32_e32 v35, v41, v55
	ds_write_b32 v49, v32 offset:3264
	v_cndmask_b32_e64 v32, v33, v35, s[0:1]
	s_nop 1
	v_mov_b32_dpp v34, v32 quad_perm:[1,0,3,2] row_mask:0xf bank_mask:0xf
	s_and_saveexec_b64 s[2:3], vcc
	s_xor_b64 s[2:3], exec, s[2:3]
	s_cbranch_execz .LBB0_1497
	v_cvt_pk_bf16_f32 v32, v34, v35

; __device__ __forceinline__ unsigned cvt_pk_bf16(float lo, float hi) { unsigned r; asm volatile("v_cvt_pk_bf16_f32 %0, %1, %2" : "=v"(r) : "v"(lo), "v"(hi)); return r; }
; __device__ __forceinline__ unsigned dpp_xor1(unsigned v) { return (unsigned)__builtin_amdgcn_update_dpp(0, (int)v, 0xB1, 0xf, 0xf, false); }
; __device__ __forceinline__ float dpp_xor1(float v) { return __int_as_float(__builtin_amdgcn_update_dpp(0, __float_as_int(v), 0xB1, 0xf, 0xf, false)); }
; __device__ __forceinline__ int crow(int r, int hi) { return (r & 3) + 8 * (r >> 2) + 4 * hi; }
; template <int MODE, int SDEPTH, bool QL>
; __device__ __forceinline__ void attn_unit(const AttnP& P, char* lds, const int tid) {
;     ...
;     float rli[16];
; #pragma unroll
;     for (int r = 0; r < 16; ++r) rli[r] = __builtin_amdgcn_rcpf(li_l[crow(r, hi)]);
;     __syncthreads();
;     {
;         char* st = lds + wid * 10240;
;         const bool odd = (r32 & 1) != 0;
;         const int sbase = (crow(0, hi) + (odd ? 1 : 0)) * 320 + (r32 & ~1) * 2;
; #pragma unroll
;         for (int d0 = 0; d0 < 4; ++d0)
; #pragma unroll
;             for (int rp = 0; rp < 8; ++rp) { const int r = 2 * rp;
;                 const float a = o[d0][r] * rli[r], b = o[d0][r + 1] * rli[r + 1];
;                 const float t = odd ? a : b; const float rcv = dpp_xor1(t);
;                 const unsigned w = odd ? cvt_pk_bf16(rcv, b) : cvt_pk_bf16(a, rcv);
;                 *(unsigned*)(st + sbase + (crow(r, 0)) * 320 + d0 * 64) = w; }
.LBB0_1499:
	s_or_b64 exec, exec, s[2:3]
	v_mul_f32_e32 v33, v42, v56
	v_mul_f32_e32 v35, v43, v57
	ds_write_b32 v49, v32 offset:5184
	v_cndmask_b32_e64 v32, v33, v35, s[0:1]
	s_nop 1
	v_mov_b32_dpp v34, v32 quad_perm:[1,0,3,2] row_mask:0xf bank_mask:0xf
	s_and_saveexec_b64 s[2:3], vcc
	s_xor_b64 s[2:3], exec, s[2:3]
	s_cbranch_execz .LBB0_1501
	v_cvt_pk_bf16_f32 v32, v34, v35

; __device__ __forceinline__ unsigned cvt_pk_bf16(float lo, float hi) { unsigned r; asm volatile("v_cvt_pk_bf16_f32 %0, %1, %2" : "=v"(r) : "v"(lo), "v"(hi)); return r; }
; __device__ __forceinline__ unsigned dpp_xor1(unsigned v) { return (unsigned)__builtin_amdgcn_update_dpp(0, (int)v, 0xB1, 0xf, 0xf, false); }
; __device__ __forceinline__ float dpp_xor1(float v) { return __int_as_float(__builtin_amdgcn_update_dpp(0, __float_as_int(v), 0xB1, 0xf, 0xf, false)); }
; __device__ __forceinline__ int crow(int r, int hi) { return (r & 3) + 8 * (r >> 2) + 4 * hi; }
; template <int MODE, int SDEPTH, bool QL>
; __device__ __forceinline__ void attn_unit(const AttnP& P, char* lds, const int tid) {
;     ...
;     float rli[16];
; #pragma unroll
;     for (int r = 0; r < 16; ++r) rli[r] = __builtin_amdgcn_rcpf(li_l[crow(r, hi)]);
;     __syncthreads();
;     {
;         char* st = lds + wid * 10240;
;         const bool odd = (r32 & 1) != 0;
;         const int sbase = (crow(0, hi) + (odd ? 1 : 0)) * 320 + (r32 & ~1) * 2;
; #pragma unroll
;         for (int d0 = 0; d0 < 4; ++d0)
; #pragma unroll
;             for (int rp = 0; rp < 8; ++rp) { const int r = 2 * rp;
;                 const float a = o[d0][r] * rli[r], b = o[d0][r + 1] * rli[r + 1];
;                 const float t = odd ? a : b; const float rcv = dpp_xor1(t);
;                 const unsigned w = odd ? cvt_pk_bf16(rcv, b) : cvt_pk_bf16(a, rcv);
;                 *(unsigned*)(st + sbase + (crow(r, 0)) * 320 + d0 * 64) = w; }
.LBB0_1503:
	s_or_b64 exec, exec, s[2:3]
	v_mul_f32_e32 v33, v44, v58
	v_mul_f32_e32 v35, v45, v59
	ds_write_b32 v49, v32 offset:5824
	v_cndmask_b32_e64 v32, v33, v35, s[0:1]
	s_nop 1
	v_mov_b32_dpp v34, v32 quad_perm:[1,0,3,2] row_mask:0xf bank_mask:0xf
	s_and_saveexec_b64 s[2:3], vcc
	s_xor_b64 s[2:3], exec, s[2:3]
	s_cbranch_execz .LBB0_1505
	v_cvt_pk_bf16_f32 v32, v34, v35

; __device__ __forceinline__ unsigned cvt_pk_bf16(float lo, float hi) { unsigned r; asm volatile("v_cvt_pk_bf16_f32 %0, %1, %2" : "=v"(r) : "v"(lo), "v"(hi)); return r; }
; __device__ __forceinline__ unsigned dpp_xor1(unsigned v) { return (unsigned)__builtin_amdgcn_update_dpp(0, (int)v, 0xB1, 0xf, 0xf, false); }
; __device__ __forceinline__ float dpp_xor1(float v) { return __int_as_float(__builtin_amdgcn_update_dpp(0, __float_as_int(v), 0xB1, 0xf, 0xf, false)); }
; __device__ __forceinline__ int crow(int r, int hi) { return (r & 3) + 8 * (r >> 2) + 4 * hi; }
; template <int MODE, int SDEPTH, bool QL>
; __device__ __forceinline__ void attn_unit(const AttnP& P, char* lds, const int tid) {
;     ...
;     float rli[16];
; #pragma unroll
;     for (int r = 0; r < 16; ++r) rli[r] = __builtin_amdgcn_rcpf(li_l[crow(r, hi)]);
;     __syncthreads();
;     {
;         char* st = lds + wid * 10240;
;         const bool odd = (r32 & 1) != 0;
;         const int sbase = (crow(0, hi) + (odd ? 1 : 0)) * 320 + (r32 & ~1) * 2;
; #pragma unroll
;         for (int d0 = 0; d0 < 4; ++d0)
; #pragma unroll
;             for (int rp = 0; rp < 8; ++rp) { const int r = 2 * rp;
;                 const float a = o[d0][r] * rli[r], b = o[d0][r + 1] * rli[r + 1];
;                 const float t = odd ? a : b; const float rcv = dpp_xor1(t);
;                 const unsigned w = odd ? cvt_pk_bf16(rcv, b) : cvt_pk_bf16(a, rcv);
;                 *(unsigned*)(st + sbase + (crow(r, 0)) * 320 + d0 * 64) = w; }
.LBB0_1507:
	s_or_b64 exec, exec, s[2:3]
	v_mul_f32_e32 v33, v46, v60
	v_mul_f32_e32 v35, v47, v61
	ds_write_b32 v49, v32 offset:7744
	v_cndmask_b32_e64 v32, v33, v35, s[0:1]
	s_nop 1
	v_mov_b32_dpp v34, v32 quad_perm:[1,0,3,2] row_mask:0xf bank_mask:0xf
	s_and_saveexec_b64 s[2:3], vcc
	s_xor_b64 s[2:3], exec, s[2:3]
	s_cbranch_execz .LBB0_1509
	v_cvt_pk_bf16_f32 v32, v34, v35

; __device__ __forceinline__ unsigned cvt_pk_bf16(float lo, float hi) { unsigned r; asm volatile("v_cvt_pk_bf16_f32 %0, %1, %2" : "=v"(r) : "v"(lo), "v"(hi)); return r; }
; __device__ __forceinline__ unsigned dpp_xor1(unsigned v) { return (unsigned)__builtin_amdgcn_update_dpp(0, (int)v, 0xB1, 0xf, 0xf, false); }
; __device__ __forceinline__ float dpp_xor1(float v) { return __int_as_float(__builtin_amdgcn_update_dpp(0, __float_as_int(v), 0xB1, 0xf, 0xf, false)); }
; __device__ __forceinline__ int crow(int r, int hi) { return (r & 3) + 8 * (r >> 2) + 4 * hi; }
; template <int MODE, int SDEPTH, bool QL>
; __device__ __forceinline__ void attn_unit(const AttnP& P, char* lds, const int tid) {
;     ...
;     float rli[16];
; #pragma unroll
;     for (int r = 0; r < 16; ++r) rli[r] = __builtin_amdgcn_rcpf(li_l[crow(r, hi)]);
;     __syncthreads();
;     {
;         char* st = lds + wid * 10240;
;         const bool odd = (r32 & 1) != 0;
;         const int sbase = (crow(0, hi) + (odd ? 1 : 0)) * 320 + (r32 & ~1) * 2;
; #pragma unroll
;         for (int d0 = 0; d0 < 4; ++d0)
; #pragma unroll
;             for (int rp = 0; rp < 8; ++rp) { const int r = 2 * rp;
;                 const float a = o[d0][r] * rli[r], b = o[d0][r + 1] * rli[r + 1];
;                 const float t = odd ? a : b; const float rcv = dpp_xor1(t);
;                 const unsigned w = odd ? cvt_pk_bf16(rcv, b) : cvt_pk_bf16(a, rcv);
;                 *(unsigned*)(st + sbase + (crow(r, 0)) * 320 + d0 * 64) = w; }
.LBB0_1511:
	s_or_b64 exec, exec, s[2:3]
	ds_write_b32 v49, v32 offset:8384
	v_mul_f32_e32 v32, v16, v76
	v_mul_f32_e32 v33, v17, v77
	v_cndmask_b32_e64 v16, v32, v33, s[0:1]
	s_nop 1
	v_mov_b32_dpp v17, v16 quad_perm:[1,0,3,2] row_mask:0xf bank_mask:0xf
	s_and_saveexec_b64 s[2:3], vcc
	s_xor_b64 s[2:3], exec, s[2:3]
	s_cbranch_execz .LBB0_1513
	v_cvt_pk_bf16_f32 v16, v17, v33

; __device__ __forceinline__ unsigned cvt_pk_bf16(float lo, float hi) { unsigned r; asm volatile("v_cvt_pk_bf16_f32 %0, %1, %2" : "=v"(r) : "v"(lo), "v"(hi)); return r; }
; __device__ __forceinline__ unsigned dpp_xor1(unsigned v) { return (unsigned)__builtin_amdgcn_update_dpp(0, (int)v, 0xB1, 0xf, 0xf, false); }
; __device__ __forceinline__ float dpp_xor1(float v) { return __int_as_float(__builtin_amdgcn_update_dpp(0, __float_as_int(v), 0xB1, 0xf, 0xf, false)); }
; __device__ __forceinline__ int crow(int r, int hi) { return (r & 3) + 8 * (r >> 2) + 4 * hi; }
; template <int MODE, int SDEPTH, bool QL>
; __device__ __forceinline__ void attn_unit(const AttnP& P, char* lds, const int tid) {
;     ...
;     float rli[16];
; #pragma unroll
;     for (int r = 0; r < 16; ++r) rli[r] = __builtin_amdgcn_rcpf(li_l[crow(r, hi)]);
;     __syncthreads();
;     {
;         char* st = lds + wid * 10240;
;         const bool odd = (r32 & 1) != 0;
;         const int sbase = (crow(0, hi) + (odd ? 1 : 0)) * 320 + (r32 & ~1) * 2;
; #pragma unroll
;         for (int d0 = 0; d0 < 4; ++d0)
; #pragma unroll
;             for (int rp = 0; rp < 8; ++rp) { const int r = 2 * rp;
;                 const float a = o[d0][r] * rli[r], b = o[d0][r + 1] * rli[r + 1];
;                 const float t = odd ? a : b; const float rcv = dpp_xor1(t);
;                 const unsigned w = odd ? cvt_pk_bf16(rcv, b) : cvt_pk_bf16(a, rcv);
;                 *(unsigned*)(st + sbase + (crow(r, 0)) * 320 + d0 * 64) = w; }
.LBB0_1515:
	s_or_b64 exec, exec, s[2:3]
	v_mul_f32_e32 v17, v18, v78
	v_mul_f32_e32 v19, v19, v79
	ds_write_b32 v49, v16 offset:128
	v_cndmask_b32_e64 v16, v17, v19, s[0:1]
	s_nop 1
	v_mov_b32_dpp v18, v16 quad_perm:[1,0,3,2] row_mask:0xf bank_mask:0xf
	s_and_saveexec_b64 s[2:3], vcc
	s_xor_b64 s[2:3], exec, s[2:3]
	s_cbranch_execz .LBB0_1517
	v_cvt_pk_bf16_f32 v16, v18, v19

; __device__ __forceinline__ unsigned cvt_pk_bf16(float lo, float hi) { unsigned r; asm volatile("v_cvt_pk_bf16_f32 %0, %1, %2" : "=v"(r) : "v"(lo), "v"(hi)); return r; }
; __device__ __forceinline__ unsigned dpp_xor1(unsigned v) { return (unsigned)__builtin_amdgcn_update_dpp(0, (int)v, 0xB1, 0xf, 0xf, false); }
; __device__ __forceinline__ float dpp_xor1(float v) { return __int_as_float(__builtin_amdgcn_update_dpp(0, __float_as_int(v), 0xB1, 0xf, 0xf, false)); }
; __device__ __forceinline__ int crow(int r, int hi) { return (r & 3) + 8 * (r >> 2) + 4 * hi; }
; template <int MODE, int SDEPTH, bool QL>
; __device__ __forceinline__ void attn_unit(const AttnP& P, char* lds, const int tid) {
;     ...
;     float rli[16];
; #pragma unroll
;     for (int r = 0; r < 16; ++r) rli[r] = __builtin_amdgcn_rcpf(li_l[crow(r, hi)]);
;     __syncthreads();
;     {
;         char* st = lds + wid * 10240;
;         const bool odd = (r32 & 1) != 0;
;         const int sbase = (crow(0, hi) + (odd ? 1 : 0)) * 320 + (r32 & ~1) * 2;
; #pragma unroll
;         for (int d0 = 0; d0 < 4; ++d0)
; #pragma unroll
;             for (int rp = 0; rp < 8; ++rp) { const int r = 2 * rp;
;                 const float a = o[d0][r] * rli[r], b = o[d0][r + 1] * rli[r + 1];
;                 const float t = odd ? a : b; const float rcv = dpp_xor1(t);
;                 const unsigned w = odd ? cvt_pk_bf16(rcv, b) : cvt_pk_bf16(a, rcv);
;                 *(unsigned*)(st + sbase + (crow(r, 0)) * 320 + d0 * 64) = w; }
.LBB0_1519:
	s_or_b64 exec, exec, s[2:3]
	v_mul_f32_e32 v17, v20, v50
	v_mul_f32_e32 v19, v21, v51
	ds_write_b32 v49, v16 offset:768
	v_cndmask_b32_e64 v16, v17, v19, s[0:1]
	s_nop 1
	v_mov_b32_dpp v18, v16 quad_perm:[1,0,3,2] row_mask:0xf bank_mask:0xf
	s_and_saveexec_b64 s[2:3], vcc
	s_xor_b64 s[2:3], exec, s[2:3]
	s_cbranch_execz .LBB0_1521
	v_cvt_pk_bf16_f32 v16, v18, v19

; __device__ __forceinline__ unsigned cvt_pk_bf16(float lo, float hi) { unsigned r; asm volatile("v_cvt_pk_bf16_f32 %0, %1, %2" : "=v"(r) : "v"(lo), "v"(hi)); return r; }
; __device__ __forceinline__ unsigned dpp_xor1(unsigned v) { return (unsigned)__builtin_amdgcn_update_dpp(0, (int)v, 0xB1, 0xf, 0xf, false); }
; __device__ __forceinline__ float dpp_xor1(float v) { return __int_as_float(__builtin_amdgcn_update_dpp(0, __float_as_int(v), 0xB1, 0xf, 0xf, false)); }
; __device__ __forceinline__ int crow(int r, int hi) { return (r & 3) + 8 * (r >> 2) + 4 * hi; }
; template <int MODE, int SDEPTH, bool QL>
; __device__ __forceinline__ void attn_unit(const AttnP& P, char* lds, const int tid) {
;     ...
;     float rli[16];
; #pragma unroll
;     for (int r = 0; r < 16; ++r) rli[r] = __builtin_amdgcn_rcpf(li_l[crow(r, hi)]);
;     __syncthreads();
;     {
;         char* st = lds + wid * 10240;
;         const bool odd = (r32 & 1) != 0;
;         const int sbase = (crow(0, hi) + (odd ? 1 : 0)) * 320 + (r32 & ~1) * 2;
; #pragma unroll
;         for (int d0 = 0; d0 < 4; ++d0)
; #pragma unroll
;             for (int rp = 0; rp < 8; ++rp) { const int r = 2 * rp;
;                 const float a = o[d0][r] * rli[r], b = o[d0][r + 1] * rli[r + 1];
;                 const float t = odd ? a : b; const float rcv = dpp_xor1(t);
;                 const unsigned w = odd ? cvt_pk_bf16(rcv, b) : cvt_pk_bf16(a, rcv);
;                 *(unsigned*)(st + sbase + (crow(r, 0)) * 320 + d0 * 64) = w; }
.LBB0_1523:
	s_or_b64 exec, exec, s[2:3]
	v_mul_f32_e32 v17, v22, v52
	v_mul_f32_e32 v19, v23, v53
	ds_write_b32 v49, v16 offset:2688
	v_cndmask_b32_e64 v16, v17, v19, s[0:1]
	s_nop 1
	v_mov_b32_dpp v18, v16 quad_perm:[1,0,3,2] row_mask:0xf bank_mask:0xf
	s_and_saveexec_b64 s[2:3], vcc
	s_xor_b64 s[2:3], exec, s[2:3]
	s_cbranch_execz .LBB0_1525
	v_cvt_pk_bf16_f32 v16, v18, v19

; __device__ __forceinline__ unsigned cvt_pk_bf16(float lo, float hi) { unsigned r; asm volatile("v_cvt_pk_bf16_f32 %0, %1, %2" : "=v"(r) : "v"(lo), "v"(hi)); return r; }
; __device__ __forceinline__ unsigned dpp_xor1(unsigned v) { return (unsigned)__builtin_amdgcn_update_dpp(0, (int)v, 0xB1, 0xf, 0xf, false); }
; __device__ __forceinline__ float dpp_xor1(float v) { return __int_as_float(__builtin_amdgcn_update_dpp(0, __float_as_int(v), 0xB1, 0xf, 0xf, false)); }
; __device__ __forceinline__ int crow(int r, int hi) { return (r & 3) + 8 * (r >> 2) + 4 * hi; }
; template <int MODE, int SDEPTH, bool QL>
; __device__ __forceinline__ void attn_unit(const AttnP& P, char* lds, const int tid) {
;     ...
;     float rli[16];
; #pragma unroll
;     for (int r = 0; r < 16; ++r) rli[r] = __builtin_amdgcn_rcpf(li_l[crow(r, hi)]);
;     __syncthreads();
;     {
;         char* st = lds + wid * 10240;
;         const bool odd = (r32 & 1) != 0;
;         const int sbase = (crow(0, hi) + (odd ? 1 : 0)) * 320 + (r32 & ~1) * 2;
; #pragma unroll
;         for (int d0 = 0; d0 < 4; ++d0)
; #pragma unroll
;             for (int rp = 0; rp < 8; ++rp) { const int r = 2 * rp;
;                 const float a = o[d0][r] * rli[r], b = o[d0][r + 1] * rli[r + 1];
;                 const float t = odd ? a : b; const float rcv = dpp_xor1(t);
;                 const unsigned w = odd ? cvt_pk_bf16(rcv, b) : cvt_pk_bf16(a, rcv);
;                 *(unsigned*)(st + sbase + (crow(r, 0)) * 320 + d0 * 64) = w; }
.LBB0_1527:
	s_or_b64 exec, exec, s[2:3]
	v_mul_f32_e32 v17, v24, v54
	v_mul_f32_e32 v19, v25, v55
	ds_write_b32 v49, v16 offset:3328
	v_cndmask_b32_e64 v16, v17, v19, s[0:1]
	s_nop 1
	v_mov_b32_dpp v18, v16 quad_perm:[1,0,3,2] row_mask:0xf bank_mask:0xf
	s_and_saveexec_b64 s[2:3], vcc
	s_xor_b64 s[2:3], exec, s[2:3]
	s_cbranch_execz .LBB0_1529
	v_cvt_pk_bf16_f32 v16, v18, v19

; __device__ __forceinline__ unsigned cvt_pk_bf16(float lo, float hi) { unsigned r; asm volatile("v_cvt_pk_bf16_f32 %0, %1, %2" : "=v"(r) : "v"(lo), "v"(hi)); return r; }
; __device__ __forceinline__ unsigned dpp_xor1(unsigned v) { return (unsigned)__builtin_amdgcn_update_dpp(0, (int)v, 0xB1, 0xf, 0xf, false); }
; __device__ __forceinline__ float dpp_xor1(float v) { return __int_as_float(__builtin_amdgcn_update_dpp(0, __float_as_int(v), 0xB1, 0xf, 0xf, false)); }
; __device__ __forceinline__ int crow(int r, int hi) { return (r & 3) + 8 * (r >> 2) + 4 * hi; }
; template <int MODE, int SDEPTH, bool QL>
; __device__ __forceinline__ void attn_unit(const AttnP& P, char* lds, const int tid) {
;     ...
;     float rli[16];
; #pragma unroll
;     for (int r = 0; r < 16; ++r) rli[r] = __builtin_amdgcn_rcpf(li_l[crow(r, hi)]);
;     __syncthreads();
;     {
;         char* st = lds + wid * 10240;
;         const bool odd = (r32 & 1) != 0;
;         const int sbase = (crow(0, hi) + (odd ? 1 : 0)) * 320 + (r32 & ~1) * 2;
; #pragma unroll
;         for (int d0 = 0; d0 < 4; ++d0)
; #pragma unroll
;             for (int rp = 0; rp < 8; ++rp) { const int r = 2 * rp;
;                 const float a = o[d0][r] * rli[r], b = o[d0][r + 1] * rli[r + 1];
;                 const float t = odd ? a : b; const float rcv = dpp_xor1(t);
;                 const unsigned w = odd ? cvt_pk_bf16(rcv, b) : cvt_pk_bf16(a, rcv);
;                 *(unsigned*)(st + sbase + (crow(r, 0)) * 320 + d0 * 64) = w; }
.LBB0_1531:
	s_or_b64 exec, exec, s[2:3]
	v_mul_f32_e32 v17, v26, v56
	v_mul_f32_e32 v19, v27, v57
	ds_write_b32 v49, v16 offset:5248
	v_cndmask_b32_e64 v16, v17, v19, s[0:1]
	s_nop 1
	v_mov_b32_dpp v18, v16 quad_perm:[1,0,3,2] row_mask:0xf bank_mask:0xf
	s_and_saveexec_b64 s[2:3], vcc
	s_xor_b64 s[2:3], exec, s[2:3]
	s_cbranch_execz .LBB0_1533
	v_cvt_pk_bf16_f32 v16, v18, v19

; __device__ __forceinline__ unsigned cvt_pk_bf16(float lo, float hi) { unsigned r; asm volatile("v_cvt_pk_bf16_f32 %0, %1, %2" : "=v"(r) : "v"(lo), "v"(hi)); return r; }
; __device__ __forceinline__ unsigned dpp_xor1(unsigned v) { return (unsigned)__builtin_amdgcn_update_dpp(0, (int)v, 0xB1, 0xf, 0xf, false); }
; __device__ __forceinline__ float dpp_xor1(float v) { return __int_as_float(__builtin_amdgcn_update_dpp(0, __float_as_int(v), 0xB1, 0xf, 0xf, false)); }
; __device__ __forceinline__ int crow(int r, int hi) { return (r & 3) + 8 * (r >> 2) + 4 * hi; }
; template <int MODE, int SDEPTH, bool QL>
; __device__ __forceinline__ void attn_unit(const AttnP& P, char* lds, const int tid) {
;     ...
;     float rli[16];
; #pragma unroll
;     for (int r = 0; r < 16; ++r) rli[r] = __builtin_amdgcn_rcpf(li_l[crow(r, hi)]);
;     __syncthreads();
;     {
;         char* st = lds + wid * 10240;
;         const bool odd = (r32 & 1) != 0;
;         const int sbase = (crow(0, hi) + (odd ? 1 : 0)) * 320 + (r32 & ~1) * 2;
; #pragma unroll
;         for (int d0 = 0; d0 < 4; ++d0)
; #pragma unroll
;             for (int rp = 0; rp < 8; ++rp) { const int r = 2 * rp;
;                 const float a = o[d0][r] * rli[r], b = o[d0][r + 1] * rli[r + 1];
;                 const float t = odd ? a : b; const float rcv = dpp_xor1(t);
;                 const unsigned w = odd ? cvt_pk_bf16(rcv, b) : cvt_pk_bf16(a, rcv);
;                 *(unsigned*)(st + sbase + (crow(r, 0)) * 320 + d0 * 64) = w; }
.LBB0_1535:
	s_or_b64 exec, exec, s[2:3]
	v_mul_f32_e32 v17, v28, v58
	v_mul_f32_e32 v19, v29, v59
	ds_write_b32 v49, v16 offset:5888
	v_cndmask_b32_e64 v16, v17, v19, s[0:1]
	s_nop 1
	v_mov_b32_dpp v18, v16 quad_perm:[1,0,3,2] row_mask:0xf bank_mask:0xf
	s_and_saveexec_b64 s[2:3], vcc
	s_xor_b64 s[2:3], exec, s[2:3]
	s_cbranch_execz .LBB0_1537
	v_cvt_pk_bf16_f32 v16, v18, v19

; __device__ __forceinline__ unsigned cvt_pk_bf16(float lo, float hi) { unsigned r; asm volatile("v_cvt_pk_bf16_f32 %0, %1, %2" : "=v"(r) : "v"(lo), "v"(hi)); return r; }
; __device__ __forceinline__ unsigned dpp_xor1(unsigned v) { return (unsigned)__builtin_amdgcn_update_dpp(0, (int)v, 0xB1, 0xf, 0xf, false); }
; __device__ __forceinline__ float dpp_xor1(float v) { return __int_as_float(__builtin_amdgcn_update_dpp(0, __float_as_int(v), 0xB1, 0xf, 0xf, false)); }
; __device__ __forceinline__ int crow(int r, int hi) { return (r & 3) + 8 * (r >> 2) + 4 * hi; }
; template <int MODE, int SDEPTH, bool QL>
; __device__ __forceinline__ void attn_unit(const AttnP& P, char* lds, const int tid) {
;     ...
;     float rli[16];
; #pragma unroll
;     for (int r = 0; r < 16; ++r) rli[r] = __builtin_amdgcn_rcpf(li_l[crow(r, hi)]);
;     __syncthreads();
;     {
;         char* st = lds + wid * 10240;
;         const bool odd = (r32 & 1) != 0;
;         const int sbase = (crow(0, hi) + (odd ? 1 : 0)) * 320 + (r32 & ~1) * 2;
; #pragma unroll
;         for (int d0 = 0; d0 < 4; ++d0)
; #pragma unroll
;             for (int rp = 0; rp < 8; ++rp) { const int r = 2 * rp;
;                 const float a = o[d0][r] * rli[r], b = o[d0][r + 1] * rli[r + 1];
;                 const float t = odd ? a : b; const float rcv = dpp_xor1(t);
;                 const unsigned w = odd ? cvt_pk_bf16(rcv, b) : cvt_pk_bf16(a, rcv);
;                 *(unsigned*)(st + sbase + (crow(r, 0)) * 320 + d0 * 64) = w; }
.LBB0_1539:
	s_or_b64 exec, exec, s[2:3]
	v_mul_f32_e32 v17, v30, v60
	v_mul_f32_e32 v19, v31, v61
	ds_write_b32 v49, v16 offset:7808
	v_cndmask_b32_e64 v16, v17, v19, s[0:1]
	s_nop 1
	v_mov_b32_dpp v18, v16 quad_perm:[1,0,3,2] row_mask:0xf bank_mask:0xf
	s_and_saveexec_b64 s[2:3], vcc
	s_xor_b64 s[2:3], exec, s[2:3]
	s_cbranch_execz .LBB0_1541
	v_cvt_pk_bf16_f32 v16, v18, v19

; __device__ __forceinline__ unsigned cvt_pk_bf16(float lo, float hi) { unsigned r; asm volatile("v_cvt_pk_bf16_f32 %0, %1, %2" : "=v"(r) : "v"(lo), "v"(hi)); return r; }
; __device__ __forceinline__ unsigned dpp_xor1(unsigned v) { return (unsigned)__builtin_amdgcn_update_dpp(0, (int)v, 0xB1, 0xf, 0xf, false); }
; __device__ __forceinline__ float dpp_xor1(float v) { return __int_as_float(__builtin_amdgcn_update_dpp(0, __float_as_int(v), 0xB1, 0xf, 0xf, false)); }
; __device__ __forceinline__ int crow(int r, int hi) { return (r & 3) + 8 * (r >> 2) + 4 * hi; }
; template <int MODE, int SDEPTH, bool QL>
; __device__ __forceinline__ void attn_unit(const AttnP& P, char* lds, const int tid) {
;     ...
;     float rli[16];
; #pragma unroll
;     for (int r = 0; r < 16; ++r) rli[r] = __builtin_amdgcn_rcpf(li_l[crow(r, hi)]);
;     __syncthreads();
;     {
;         char* st = lds + wid * 10240;
;         const bool odd = (r32 & 1) != 0;
;         const int sbase = (crow(0, hi) + (odd ? 1 : 0)) * 320 + (r32 & ~1) * 2;
; #pragma unroll
;         for (int d0 = 0; d0 < 4; ++d0)
; #pragma unroll
;             for (int rp = 0; rp < 8; ++rp) { const int r = 2 * rp;
;                 const float a = o[d0][r] * rli[r], b = o[d0][r + 1] * rli[r + 1];
;                 const float t = odd ? a : b; const float rcv = dpp_xor1(t);
;                 const unsigned w = odd ? cvt_pk_bf16(rcv, b) : cvt_pk_bf16(a, rcv);
;                 *(unsigned*)(st + sbase + (crow(r, 0)) * 320 + d0 * 64) = w; }
.LBB0_1543:
	s_or_b64 exec, exec, s[2:3]
	ds_write_b32 v49, v16 offset:8448
	v_mul_f32_e32 v16, v0, v76
	v_mul_f32_e32 v17, v1, v77
	v_cndmask_b32_e64 v0, v16, v17, s[0:1]
	s_nop 1
	v_mov_b32_dpp v1, v0 quad_perm:[1,0,3,2] row_mask:0xf bank_mask:0xf
	s_and_saveexec_b64 s[2:3], vcc
	s_xor_b64 s[2:3], exec, s[2:3]
	s_cbranch_execz .LBB0_1545
	v_cvt_pk_bf16_f32 v0, v1, v17

; __device__ __forceinline__ unsigned cvt_pk_bf16(float lo, float hi) { unsigned r; asm volatile("v_cvt_pk_bf16_f32 %0, %1, %2" : "=v"(r) : "v"(lo), "v"(hi)); return r; }
; __device__ __forceinline__ unsigned dpp_xor1(unsigned v) { return (unsigned)__builtin_amdgcn_update_dpp(0, (int)v, 0xB1, 0xf, 0xf, false); }
; __device__ __forceinline__ float dpp_xor1(float v) { return __int_as_float(__builtin_amdgcn_update_dpp(0, __float_as_int(v), 0xB1, 0xf, 0xf, false)); }
; __device__ __forceinline__ int crow(int r, int hi) { return (r & 3) + 8 * (r >> 2) + 4 * hi; }
; template <int MODE, int SDEPTH, bool QL>
; __device__ __forceinline__ void attn_unit(const AttnP& P, char* lds, const int tid) {
;     ...
;     float rli[16];
; #pragma unroll
;     for (int r = 0; r < 16; ++r) rli[r] = __builtin_amdgcn_rcpf(li_l[crow(r, hi)]);
;     __syncthreads();
;     {
;         char* st = lds + wid * 10240;
;         const bool odd = (r32 & 1) != 0;
;         const int sbase = (crow(0, hi) + (odd ? 1 : 0)) * 320 + (r32 & ~1) * 2;
; #pragma unroll
;         for (int d0 = 0; d0 < 4; ++d0)
; #pragma unroll
;             for (int rp = 0; rp < 8; ++rp) { const int r = 2 * rp;
;                 const float a = o[d0][r] * rli[r], b = o[d0][r + 1] * rli[r + 1];
;                 const float t = odd ? a : b; const float rcv = dpp_xor1(t);
;                 const unsigned w = odd ? cvt_pk_bf16(rcv, b) : cvt_pk_bf16(a, rcv);
;                 *(unsigned*)(st + sbase + (crow(r, 0)) * 320 + d0 * 64) = w; }
.LBB0_1547:
	s_or_b64 exec, exec, s[2:3]
	v_mul_f32_e32 v1, v2, v78
	v_mul_f32_e32 v3, v3, v79
	ds_write_b32 v49, v0 offset:192
	v_cndmask_b32_e64 v0, v1, v3, s[0:1]
	s_nop 1
	v_mov_b32_dpp v2, v0 quad_perm:[1,0,3,2] row_mask:0xf bank_mask:0xf
	s_and_saveexec_b64 s[2:3], vcc
	s_xor_b64 s[2:3], exec, s[2:3]
	s_cbranch_execz .LBB0_1549
	v_cvt_pk_bf16_f32 v0, v2, v3

; __device__ __forceinline__ unsigned cvt_pk_bf16(float lo, float hi) { unsigned r; asm volatile("v_cvt_pk_bf16_f32 %0, %1, %2" : "=v"(r) : "v"(lo), "v"(hi)); return r; }
; __device__ __forceinline__ unsigned dpp_xor1(unsigned v) { return (unsigned)__builtin_amdgcn_update_dpp(0, (int)v, 0xB1, 0xf, 0xf, false); }
; __device__ __forceinline__ float dpp_xor1(float v) { return __int_as_float(__builtin_amdgcn_update_dpp(0, __float_as_int(v), 0xB1, 0xf, 0xf, false)); }
; __device__ __forceinline__ int crow(int r, int hi) { return (r & 3) + 8 * (r >> 2) + 4 * hi; }
; template <int MODE, int SDEPTH, bool QL>
; __device__ __forceinline__ void attn_unit(const AttnP& P, char* lds, const int tid) {
;     ...
;     float rli[16];
; #pragma unroll
;     for (int r = 0; r < 16; ++r) rli[r] = __builtin_amdgcn_rcpf(li_l[crow(r, hi)]);
;     __syncthreads();
;     {
;         char* st = lds + wid * 10240;
;         const bool odd = (r32 & 1) != 0;
;         const int sbase = (crow(0, hi) + (odd ? 1 : 0)) * 320 + (r32 & ~1) * 2;
; #pragma unroll
;         for (int d0 = 0; d0 < 4; ++d0)
; #pragma unroll
;             for (int rp = 0; rp < 8; ++rp) { const int r = 2 * rp;
;                 const float a = o[d0][r] * rli[r], b = o[d0][r + 1] * rli[r + 1];
;                 const float t = odd ? a : b; const float rcv = dpp_xor1(t);
;                 const unsigned w = odd ? cvt_pk_bf16(rcv, b) : cvt_pk_bf16(a, rcv);
;                 *(unsigned*)(st + sbase + (crow(r, 0)) * 320 + d0 * 64) = w; }
.LBB0_1551:
	s_or_b64 exec, exec, s[2:3]
	v_mul_f32_e32 v1, v4, v50
	v_mul_f32_e32 v3, v5, v51
	ds_write_b32 v49, v0 offset:832
	v_cndmask_b32_e64 v0, v1, v3, s[0:1]
	s_nop 1
	v_mov_b32_dpp v2, v0 quad_perm:[1,0,3,2] row_mask:0xf bank_mask:0xf
	s_and_saveexec_b64 s[2:3], vcc
	s_xor_b64 s[2:3], exec, s[2:3]
	s_cbranch_execz .LBB0_1553
	v_cvt_pk_bf16_f32 v0, v2, v3

; __device__ __forceinline__ unsigned cvt_pk_bf16(float lo, float hi) { unsigned r; asm volatile("v_cvt_pk_bf16_f32 %0, %1, %2" : "=v"(r) : "v"(lo), "v"(hi)); return r; }
; __device__ __forceinline__ unsigned dpp_xor1(unsigned v) { return (unsigned)__builtin_amdgcn_update_dpp(0, (int)v, 0xB1, 0xf, 0xf, false); }
; __device__ __forceinline__ float dpp_xor1(float v) { return __int_as_float(__builtin_amdgcn_update_dpp(0, __float_as_int(v), 0xB1, 0xf, 0xf, false)); }
; __device__ __forceinline__ int crow(int r, int hi) { return (r & 3) + 8 * (r >> 2) + 4 * hi; }
; template <int MODE, int SDEPTH, bool QL>
; __device__ __forceinline__ void attn_unit(const AttnP& P, char* lds, const int tid) {
;     ...
;     float rli[16];
; #pragma unroll
;     for (int r = 0; r < 16; ++r) rli[r] = __builtin_amdgcn_rcpf(li_l[crow(r, hi)]);
;     __syncthreads();
;     {
;         char* st = lds + wid * 10240;
;         const bool odd = (r32 & 1) != 0;
;         const int sbase = (crow(0, hi) + (odd ? 1 : 0)) * 320 + (r32 & ~1) * 2;
; #pragma unroll
;         for (int d0 = 0; d0 < 4; ++d0)
; #pragma unroll
;             for (int rp = 0; rp < 8; ++rp) { const int r = 2 * rp;
;                 const float a = o[d0][r] * rli[r], b = o[d0][r + 1] * rli[r + 1];
;                 const float t = odd ? a : b; const float rcv = dpp_xor1(t);
;                 const unsigned w = odd ? cvt_pk_bf16(rcv, b) : cvt_pk_bf16(a, rcv);
;                 *(unsigned*)(st + sbase + (crow(r, 0)) * 320 + d0 * 64) = w; }
.LBB0_1555:
	s_or_b64 exec, exec, s[2:3]
	v_mul_f32_e32 v1, v6, v52
	v_mul_f32_e32 v3, v7, v53
	ds_write_b32 v49, v0 offset:2752
	v_cndmask_b32_e64 v0, v1, v3, s[0:1]
	s_nop 1
	v_mov_b32_dpp v2, v0 quad_perm:[1,0,3,2] row_mask:0xf bank_mask:0xf
	s_and_saveexec_b64 s[2:3], vcc
	s_xor_b64 s[2:3], exec, s[2:3]
	s_cbranch_execz .LBB0_1557
	v_cvt_pk_bf16_f32 v0, v2, v3

; __device__ __forceinline__ unsigned cvt_pk_bf16(float lo, float hi) { unsigned r; asm volatile("v_cvt_pk_bf16_f32 %0, %1, %2" : "=v"(r) : "v"(lo), "v"(hi)); return r; }
; __device__ __forceinline__ unsigned dpp_xor1(unsigned v) { return (unsigned)__builtin_amdgcn_update_dpp(0, (int)v, 0xB1, 0xf, 0xf, false); }
; __device__ __forceinline__ float dpp_xor1(float v) { return __int_as_float(__builtin_amdgcn_update_dpp(0, __float_as_int(v), 0xB1, 0xf, 0xf, false)); }
; __device__ __forceinline__ int crow(int r, int hi) { return (r & 3) + 8 * (r >> 2) + 4 * hi; }
; template <int MODE, int SDEPTH, bool QL>
; __device__ __forceinline__ void attn_unit(const AttnP& P, char* lds, const int tid) {
;     ...
;     float rli[16];
; #pragma unroll
;     for (int r = 0; r < 16; ++r) rli[r] = __builtin_amdgcn_rcpf(li_l[crow(r, hi)]);
;     __syncthreads();
;     {
;         char* st = lds + wid * 10240;
;         const bool odd = (r32 & 1) != 0;
;         const int sbase = (crow(0, hi) + (odd ? 1 : 0)) * 320 + (r32 & ~1) * 2;
; #pragma unroll
;         for (int d0 = 0; d0 < 4; ++d0)
; #pragma unroll
;             for (int rp = 0; rp < 8; ++rp) { const int r = 2 * rp;
;                 const float a = o[d0][r] * rli[r], b = o[d0][r + 1] * rli[r + 1];
;                 const float t = odd ? a : b; const float rcv = dpp_xor1(t);
;                 const unsigned w = odd ? cvt_pk_bf16(rcv, b) : cvt_pk_bf16(a, rcv);
;                 *(unsigned*)(st + sbase + (crow(r, 0)) * 320 + d0 * 64) = w; }
.LBB0_1559:
	s_or_b64 exec, exec, s[2:3]
	v_mul_f32_e32 v1, v8, v54
	v_mul_f32_e32 v3, v9, v55
	ds_write_b32 v49, v0 offset:3392
	v_cndmask_b32_e64 v0, v1, v3, s[0:1]
	s_nop 1
	v_mov_b32_dpp v2, v0 quad_perm:[1,0,3,2] row_mask:0xf bank_mask:0xf
	s_and_saveexec_b64 s[2:3], vcc
	s_xor_b64 s[2:3], exec, s[2:3]
	s_cbranch_execz .LBB0_1561
	v_cvt_pk_bf16_f32 v0, v2, v3

; __device__ __forceinline__ unsigned cvt_pk_bf16(float lo, float hi) { unsigned r; asm volatile("v_cvt_pk_bf16_f32 %0, %1, %2" : "=v"(r) : "v"(lo), "v"(hi)); return r; }
; __device__ __forceinline__ unsigned dpp_xor1(unsigned v) { return (unsigned)__builtin_amdgcn_update_dpp(0, (int)v, 0xB1, 0xf, 0xf, false); }
; __device__ __forceinline__ float dpp_xor1(float v) { return __int_as_float(__builtin_amdgcn_update_dpp(0, __float_as_int(v), 0xB1, 0xf, 0xf, false)); }
; __device__ __forceinline__ int crow(int r, int hi) { return (r & 3) + 8 * (r >> 2) + 4 * hi; }
; template <int MODE, int SDEPTH, bool QL>
; __device__ __forceinline__ void attn_unit(const AttnP& P, char* lds, const int tid) {
;     ...
;     float rli[16];
; #pragma unroll
;     for (int r = 0; r < 16; ++r) rli[r] = __builtin_amdgcn_rcpf(li_l[crow(r, hi)]);
;     __syncthreads();
;     {
;         char* st = lds + wid * 10240;
;         const bool odd = (r32 & 1) != 0;
;         const int sbase = (crow(0, hi) + (odd ? 1 : 0)) * 320 + (r32 & ~1) * 2;
; #pragma unroll
;         for (int d0 = 0; d0 < 4; ++d0)
; #pragma unroll
;             for (int rp = 0; rp < 8; ++rp) { const int r = 2 * rp;
;                 const float a = o[d0][r] * rli[r], b = o[d0][r + 1] * rli[r + 1];
;                 const float t = odd ? a : b; const float rcv = dpp_xor1(t);
;                 const unsigned w = odd ? cvt_pk_bf16(rcv, b) : cvt_pk_bf16(a, rcv);
;                 *(unsigned*)(st + sbase + (crow(r, 0)) * 320 + d0 * 64) = w; }
.LBB0_1563:
	s_or_b64 exec, exec, s[2:3]
	v_mul_f32_e32 v1, v10, v56
	v_mul_f32_e32 v3, v11, v57
	ds_write_b32 v49, v0 offset:5312
	v_cndmask_b32_e64 v0, v1, v3, s[0:1]
	s_nop 1
	v_mov_b32_dpp v2, v0 quad_perm:[1,0,3,2] row_mask:0xf bank_mask:0xf
	s_and_saveexec_b64 s[2:3], vcc
	s_xor_b64 s[2:3], exec, s[2:3]
	s_cbranch_execz .LBB0_1565
	v_cvt_pk_bf16_f32 v0, v2, v3

; __device__ __forceinline__ unsigned cvt_pk_bf16(float lo, float hi) { unsigned r; asm volatile("v_cvt_pk_bf16_f32 %0, %1, %2" : "=v"(r) : "v"(lo), "v"(hi)); return r; }
; __device__ __forceinline__ unsigned dpp_xor1(unsigned v) { return (unsigned)__builtin_amdgcn_update_dpp(0, (int)v, 0xB1, 0xf, 0xf, false); }
; __device__ __forceinline__ float dpp_xor1(float v) { return __int_as_float(__builtin_amdgcn_update_dpp(0, __float_as_int(v), 0xB1, 0xf, 0xf, false)); }
; __device__ __forceinline__ int crow(int r, int hi) { return (r & 3) + 8 * (r >> 2) + 4 * hi; }
; template <int MODE, int SDEPTH, bool QL>
; __device__ __forceinline__ void attn_unit(const AttnP& P, char* lds, const int tid) {
;     ...
;     float rli[16];
; #pragma unroll
;     for (int r = 0; r < 16; ++r) rli[r] = __builtin_amdgcn_rcpf(li_l[crow(r, hi)]);
;     __syncthreads();
;     {
;         char* st = lds + wid * 10240;
;         const bool odd = (r32 & 1) != 0;
;         const int sbase = (crow(0, hi) + (odd ? 1 : 0)) * 320 + (r32 & ~1) * 2;
; #pragma unroll
;         for (int d0 = 0; d0 < 4; ++d0)
; #pragma unroll
;             for (int rp = 0; rp < 8; ++rp) { const int r = 2 * rp;
;                 const float a = o[d0][r] * rli[r], b = o[d0][r + 1] * rli[r + 1];
;                 const float t = odd ? a : b; const float rcv = dpp_xor1(t);
;                 const unsigned w = odd ? cvt_pk_bf16(rcv, b) : cvt_pk_bf16(a, rcv);
;                 *(unsigned*)(st + sbase + (crow(r, 0)) * 320 + d0 * 64) = w; }
.LBB0_1567:
	s_or_b64 exec, exec, s[2:3]
	v_mul_f32_e32 v1, v12, v58
	v_mul_f32_e32 v3, v13, v59
	ds_write_b32 v49, v0 offset:5952
	v_cndmask_b32_e64 v0, v1, v3, s[0:1]
	s_nop 1
	v_mov_b32_dpp v2, v0 quad_perm:[1,0,3,2] row_mask:0xf bank_mask:0xf
	s_and_saveexec_b64 s[2:3], vcc
	s_xor_b64 s[2:3], exec, s[2:3]
	s_cbranch_execz .LBB0_1569
	v_cvt_pk_bf16_f32 v0, v2, v3

; __device__ __forceinline__ unsigned cvt_pk_bf16(float lo, float hi) { unsigned r; asm volatile("v_cvt_pk_bf16_f32 %0, %1, %2" : "=v"(r) : "v"(lo), "v"(hi)); return r; }
; __device__ __forceinline__ unsigned dpp_xor1(unsigned v) { return (unsigned)__builtin_amdgcn_update_dpp(0, (int)v, 0xB1, 0xf, 0xf, false); }
; __device__ __forceinline__ float dpp_xor1(float v) { return __int_as_float(__builtin_amdgcn_update_dpp(0, __float_as_int(v), 0xB1, 0xf, 0xf, false)); }
; __device__ __forceinline__ int crow(int r, int hi) { return (r & 3) + 8 * (r >> 2) + 4 * hi; }
; template <int MODE, int SDEPTH, bool QL>
; __device__ __forceinline__ void attn_unit(const AttnP& P, char* lds, const int tid) {
;     ...
;     float rli[16];
; #pragma unroll
;     for (int r = 0; r < 16; ++r) rli[r] = __builtin_amdgcn_rcpf(li_l[crow(r, hi)]);
;     __syncthreads();
;     {
;         char* st = lds + wid * 10240;
;         const bool odd = (r32 & 1) != 0;
;         const int sbase = (crow(0, hi) + (odd ? 1 : 0)) * 320 + (r32 & ~1) * 2;
; #pragma unroll
;         for (int d0 = 0; d0 < 4; ++d0)
; #pragma unroll
;             for (int rp = 0; rp < 8; ++rp) { const int r = 2 * rp;
;                 const float a = o[d0][r] * rli[r], b = o[d0][r + 1] * rli[r + 1];
;                 const float t = odd ? a : b; const float rcv = dpp_xor1(t);
;                 const unsigned w = odd ? cvt_pk_bf16(rcv, b) : cvt_pk_bf16(a, rcv);
;                 *(unsigned*)(st + sbase + (crow(r, 0)) * 320 + d0 * 64) = w; }
.LBB0_1571:
	s_or_b64 exec, exec, s[2:3]
	v_mul_f32_e32 v1, v14, v60
	v_mul_f32_e32 v3, v15, v61
	ds_write_b32 v49, v0 offset:7872
	v_cndmask_b32_e64 v0, v1, v3, s[0:1]
	s_nop 1
	v_mov_b32_dpp v2, v0 quad_perm:[1,0,3,2] row_mask:0xf bank_mask:0xf
	s_and_saveexec_b64 s[0:1], vcc
	s_xor_b64 s[0:1], exec, s[0:1]
	s_cbranch_execz .LBB0_1573
	v_cvt_pk_bf16_f32 v0, v2, v3

; __global__ void __launch_bounds__(NTHREADS, 2) mk_fwd(Args args) {
;     ...
;         for (int i2 = vcu; i2 < ND_UNITS; i2 += G) {
;             att::AttnP P; P.lse = nullptr; P.lse_ld = 0; P.ldq = OD_IN; P.ldk = OD_IN; P.ldo = DM; P.lbase = 0; P.krow0 = 0; P.qtok0 = 0; P.lut = nullptr; P.lut_n = 0; P.far_thr = 1 << 30; P.q0abs = 0; P.cidx = 0;
;             {
;                 const int u = i2 & 15, h = (i2 >> 4) & 7, b = i2 >> 7;
;                 const int krow0 = min(max(4 * u - 4, 0), 56), nt = (u == 0 || u == 15) ? 8 : 12;
;                 const bf16_t* base = BIG + (size_t)b * SEQ * OD_IN + 1536 + h * 128;
;                 P.Q = base + (size_t)(u * 256) * OD_IN; P.K = base + 1024 + (size_t)(krow0 * 64) * OD_IN; P.V = base + 2048 + (size_t)(krow0 * 64) * OD_IN;
;                 P.O = R1 + ((size_t)b * SEQ + u * 256) * DM + 1024 + h * 128; P.NT = nt;
;                 P.lut = lut3 + h * 512; P.lut_n = 512; P.krow0 = krow0; P.qtok0 = u * 256;
.LBB0_1594:
	s_andn2_b64 vcc, exec, s[24:25]
	s_cbranch_vccnz .LBB0_1841
	v_readlane_b32 s20, v254, 7
	v_readlane_b32 s22, v254, 9
	v_readlane_b32 s23, v254, 10
	s_add_u32 s0, s22, 0x338000
	v_readlane_b32 s21, v254, 8
	v_writelane_b32 v254, s0, 50
	s_addc_u32 s0, s23, 0
	v_writelane_b32 v254, s0, 51
	s_lshl_b32 s0, s69, 3
	v_writelane_b32 v254, s0, 52
	s_add_u32 s0, s22, 0x80088
	s_addc_u32 s1, s23, 0
	v_writelane_b32 v254, s0, 53
	s_mov_b32 s57, 0
	s_waitcnt vmcnt(0) lgkmcnt(0)
	v_mov_b32_e32 v1, 0
	v_writelane_b32 v254, s1, 54
	s_add_u32 s0, s22, 0x800a0
	s_addc_u32 s1, s23, 0
	v_writelane_b32 v254, s0, 55
	s_mov_b64 s[60:61], 0x800
	v_mov_b32_e32 v143, 0xff800000
	v_writelane_b32 v254, s1, 56
	s_add_u32 s0, s22, 0x80010
	s_addc_u32 s1, s23, 0
	v_writelane_b32 v254, s0, 57
	s_nop 1
	v_writelane_b32 v254, s1, 58
	s_lshl_b32 s0, s82, 2
	s_and_b32 s0, s0, 0xffffff00
	s_add_i32 s0, s0, 0
	s_add_i32 s0, s0, 0x20800
	v_writelane_b32 v254, s0, 59
	s_lshl_b32 s0, s68, 4
	v_writelane_b32 v254, s0, 37
	s_add_i32 s0, 0, 0x21000
	v_writelane_b32 v254, s0, 60
	s_mov_b32 s0, 1.0
	v_writelane_b32 v254, s0, 61
	s_nop 1
	v_writelane_b32 v254, s1, 62
	v_writelane_b32 v254, s2, 63
	v_writelane_b32 v255, s3, 0
	v_readlane_b32 s16, v254, 0
	s_nop 1
	s_nop 1
	v_writelane_b32 v255, s16, 1

; #define LAS __attribute__((address_space(3)))
; __device__ __forceinline__ int v_rd_base(int lane) { return ((lane & 3) << 3) | (((lane >> 2) & 3) << 6) | (((lane >> 4) & 1) << 5) | (((lane >> 5) & 1) << 8); }
; template <int MODE, int VW>
; __device__ __forceinline__ void attn_unit_s(const AttnP& P, char* lds, const int tid) {
;     ...
;     const bf16_t* Qw = P.Q + (long)(wid * QBLK + r32) * P.ldq + hi * 8;
; #pragma unroll
;     for (int d0 = 0; d0 < 8; ++d0) { const bf16x8 qv = *reinterpret_cast<const bf16x8*>(Qw + d0 * 16);
;         if (QLD && d0 >= 4) *(LAS bf16x8*)((LAS char*)qlds + (d0 - 4) * 1024) = qv; else qr[d0 < (QLD ? 4 : 8) ? d0 : 0] = qv; }
;     const int vb0 = (int)(uintptr_t)V_lds + v_rd_base(lane);
;     const long LDK = P.ldk;
;     unsigned offK[2], offV[2];
; #pragma unroll
;     for (int i = 0; i < 2; ++i) { const int sl = tid + 512 * i, row = sl >> 4, ch = (sl & 15) ^ (row & 7); offK[i] = (unsigned)((row * LDK + ch * 8) * 2); }
; #pragma unroll
;     for (int i = 0; i < 2; ++i) { const int sl = tid + 512 * i, sub = sl >> 5, rowk = (sl >> 2) & 7, cch = sl & 3, kk = (sub >> 2) * 8 + rowk;
;         const int k = (kk & ~0xC) | ((kk & 4) << 1) | ((kk & 8) >> 1), col = (sub & 3) * 32 + cch * 8; offV[i] = (unsigned)((k * LDK + col) * 2); }
;     LAS unsigned char* ldsw = (LAS unsigned char*)lds + wid * 1024;
;     ...
;     BDMA(0, 0); asm volatile("s_waitcnt vmcnt(0)" ::: "memory"); __syncthreads();
; __global__ void __launch_bounds__(NTHREADS, 2) mk_fwd(Args args) {
;     ...
;                 const int u = i2 & 15, h = (i2 >> 4) & 7, b = i2 >> 7;
;                 const int krow0 = min(max(4 * u - 4, 0), 56), nt = (u == 0 || u == 15) ? 8 : 12;
;                 const bf16_t* base = BIG + (size_t)b * SEQ * OD_IN + 1536 + h * 128;
;                 P.Q = base + (size_t)(u * 256) * OD_IN; P.K = base + 1024 + (size_t)(krow0 * 64) * OD_IN; P.V = base + 2048 + (size_t)(krow0 * 64) * OD_IN;
;                 P.O = R1 + ((size_t)b * SEQ + u * 256) * DM + 1024 + h * 128; P.NT = nt;
;                 P.lut = lut3 + h * 512; P.lut_n = 512; P.krow0 = krow0; P.qtok0 = u * 256;
.LBB0_1609:
	s_or_b64 exec, exec, s[0:1]
	s_mul_i32 s9, s14, 0x1f0
	s_mul_i32 s14, s14, 0x120000
	s_mul_i32 s0, s20, 0x48000
	s_mov_b32 s1, s57
	s_sub_i32 s56, s14, s0
	v_writelane_b32 v255, s0, 2
	s_lshl_b32 s2, s13, 8
	s_ashr_i32 s14, s16, 7
	v_writelane_b32 v255, s1, 3
	s_lshl_b64 s[0:1], s[56:57], 1
	s_cmp_eq_u32 s12, 0
	s_cselect_b64 s[4:5], -1, 0
	s_cmp_eq_u32 s12, 15
	s_cselect_b64 s[6:7], -1, 0
	s_or_b64 s[4:5], s[4:5], s[6:7]
	s_and_b64 s[4:5], s[4:5], exec
	s_movk_i32 s3, 0xd9
	v_writelane_b32 v254, s16, 0
	s_cselect_b32 s4, s3, 0x155
	s_ashr_i32 s15, s14, 31
	s_mul_hi_i32 s3, s14, 0x2400000
	v_writelane_b32 v255, s14, 4
	s_mul_i32 s21, s14, 0x2400000
	v_readlane_b32 s6, v254, 15
	v_readlane_b32 s7, v254, 16
	s_add_u32 s5, s6, s21
	s_addc_u32 s6, s7, s3
	s_lshl_b32 s7, s13, 7
	s_add_u32 s5, s5, s2
	s_addc_u32 s8, s6, 0
	s_lshl_b32 s16, s12, 8
	s_mul_i32 s12, s12, 0x240000
	v_writelane_b32 v255, s15, 5
	s_add_u32 s6, s5, s12
	v_writelane_b32 v255, s7, 6
	s_addc_u32 s7, s8, 0
	s_mul_i32 s12, s17, 0x90000
	s_add_u32 s5, s5, s12
	s_addc_u32 s8, s8, 0
	s_add_u32 s12, s5, 0xc00
	s_addc_u32 s13, s8, 0
	s_add_u32 s14, s5, 0x1c00
	s_addc_u32 s15, s8, 0
	s_ashr_i32 s24, s10, 6
	s_waitcnt vmcnt(10)
	v_and_b32_e32 v8, 31, v154
	s_lshl_b32 s18, s24, 5
	v_bfe_u32 v9, v154, 5, 1
	v_or_b32_e32 v0, s18, v8
	v_mov_b64_e32 v[4:5], s[6:7]
	s_movk_i32 s8, 0x2400
	v_mad_i64_i32 v[4:5], s[6:7], v0, s8, v[4:5]
	v_lshlrev_b32_e32 v0, 4, v9
	v_lshl_add_u64 v[4:5], v[4:5], 0, v[0:1]
	v_and_b32_e32 v153, 15, v154
	v_ashrrev_i32_e32 v3, 4, v2
	global_load_dwordx4 v[134:137], v[4:5], off offset:3072
	global_load_dwordx4 v[130:133], v[4:5], off offset:3104
	global_load_dwordx4 v[126:129], v[4:5], off offset:3136
	global_load_dwordx4 v[122:125], v[4:5], off offset:3168
	global_load_dwordx4 v[118:121], v[4:5], off offset:3200
	global_load_dwordx4 v[114:117], v[4:5], off offset:3232
	global_load_dwordx4 v[110:113], v[4:5], off offset:3264
	global_load_dwordx4 v[106:109], v[4:5], off offset:3296
	v_bitop3_b32 v4, v3, v153, 7 bitop3:0x6c
	v_mul_lo_u32 v5, v3, s8
	v_lshl_or_b32 v4, v4, 4, v5
	v_add_u32_e32 v5, 0x200, v2
	v_ashrrev_i32_e32 v5, 4, v5
	v_bitop3_b32 v6, v5, v153, 7 bitop3:0x6c
	v_mul_lo_u32 v7, v5, s8
	v_lshl_or_b32 v6, v6, 4, v7
	v_bfe_u32 v7, v2, 2, 2
	s_waitcnt vmcnt(17)
	v_lshrrev_b32_e32 v10, 1, v2
	v_and_b32_e32 v13, 0x7ffff0, v3
	v_lshrrev_b32_e32 v3, 1, v3
	v_and_or_b32 v7, v10, 8, v7
	v_lshlrev_b32_e32 v11, 3, v154
	v_and_b32_e32 v3, 4, v3
	v_and_b32_e32 v10, 0x60, v2
	v_and_b32_e32 v12, 24, v11
	v_or3_b32 v3, v13, v3, v7
	v_or_b32_e32 v2, v12, v10
	v_mul_u32_u24_e32 v13, 0x1200, v3
	v_or_b32_e32 v3, v13, v2
	s_waitcnt vmcnt(16)
	v_lshlrev_b32_e32 v14, 1, v3
	v_and_b32_e32 v3, 0x7ffff0, v5
	v_lshrrev_b32_e32 v5, 1, v5
	v_and_b32_e32 v5, 4, v5
	v_or3_b32 v3, v3, v5, v7
	v_mul_u32_u24_e32 v15, 0x1200, v3
	s_lshl_b32 s7, s24, 10
	v_or_b32_e32 v2, v15, v2
	s_add_i32 s7, s7, 0
	v_mov_b32_e32 v5, v1
	v_lshlrev_b32_e32 v16, 1, v2
	s_add_i32 s8, s7, 0x10000
	v_lshl_add_u64 v[2:3], s[12:13], 0, v[4:5]
	v_lshl_add_u64 v[2:3], v[2:3], 0, s[60:61]
	s_mov_b32 m0, s8
	v_mov_b32_e32 v7, v1
	global_load_lds_dwordx4 v[2:3], off
	v_lshl_add_u64 v[2:3], s[12:13], 0, v[6:7]
	v_lshl_add_u64 v[2:3], v[2:3], 0, s[60:61]
	s_add_i32 m0, s7, 0x12000
	v_writelane_b32 v255, s16, 7
	global_load_lds_dwordx4 v[2:3], off
	s_mov_b32 m0, s7
	v_writelane_b32 v255, s17, 8
	global_load_lds_dwordx4 v14, s[14:15]
	s_add_i32 m0, s7, 0x2000
	s_mov_b32 s12, s18
	global_load_lds_dwordx4 v16, s[14:15]
	v_writelane_b32 v255, s12, 9
	v_lshlrev_b32_e32 v2, 4, v154
	v_and_b32_e32 v14, 0x70, v2
	v_writelane_b32 v255, s13, 10
	s_movk_i32 s13, 0x70
	s_and_b32 s12, s18, 32
	v_bitop3_b32 v170, v0, v2, s13 bitop3:0x78
	s_movk_i32 s13, 0x60
	v_or_b32_e32 v169, s12, v8
	v_bitop3_b32 v166, v0, v14, s13 bitop3:0x36
	s_movk_i32 s13, 0x80
	v_lshlrev_b32_e32 v142, 2, v9
	v_sub_u32_e64 v9, v169, 8 clamp
	v_bitop3_b32 v165, v0, v14, s13 bitop3:0x36
	s_movk_i32 s13, 0xa0
	v_min_u32_e32 v9, 48, v9
	v_bitop3_b32 v164, v0, v14, s13 bitop3:0x36
	s_movk_i32 s13, 0xc0
	v_bitop3_b32 v163, v0, v14, s13 bitop3:0x36
	s_movk_i32 s13, 0xe0
	v_sub_u32_e32 v9, v142, v9
	v_bitop3_b32 v168, v0, v14, 32 bitop3:0x36
	v_bitop3_b32 v167, v0, v14, 64 bitop3:0x36
	v_bitop3_b32 v162, v0, v14, s13 bitop3:0x36
	v_add_u32_e32 v14, 1, v9
	s_movk_i32 s68, 0xffe0
	v_cmp_gt_u32_e64 s[60:61], 16, v14
	v_and_b32_e32 v14, -16, v14
	v_cmp_eq_u32_e64 s[62:63], s68, v14
	v_add_u32_e32 v14, 2, v9
	v_cmp_gt_u32_e64 s[56:57], 16, v14
	v_and_b32_e32 v14, -16, v14
	s_and_b32 s5, s10, 0x3fffffc0
	v_cmp_eq_u32_e64 s[58:59], s68, v14
	v_add_u32_e32 v14, 3, v9
	s_lshl_b32 s5, s5, 2
	v_cmp_gt_u32_e64 s[52:53], 16, v14
	v_and_b32_e32 v14, -16, v14
	s_add_i32 s5, s5, 0
	v_cmp_eq_u32_e64 s[54:55], s68, v14
	v_add_u32_e32 v14, 8, v9
	s_add_i32 s10, s5, 0x18000
	s_add_i32 s5, s18, s16
	v_cmp_gt_u32_e64 s[48:49], 16, v14
	v_and_b32_e32 v14, -16, v14
	s_ashr_i32 s28, s5, 6
	v_cmp_eq_u32_e64 s[50:51], s68, v14
; template <int MODE> __device__ __forceinline__ float apply_mode(f32x16& p0, f32x16& p1, int t, const ModeCtx& c, const LAS float* lut, int hi) {
;     ...
;         const int ki = c.krow0 + t;
;         const bool rowok = (unsigned)(ki - c.rs) < 8u;
;         const int base = (ki - c.qi + 7) * 31 + 15 - c.qj + 4 * hi;
;         const int kjb = 4 * hi - c.cs;
; #pragma unroll
;         for (int r = 0; r < 16; ++r) {
;             const int kj0 = (r & 3) + 8 * (r >> 2);
;             const bool ok0 = rowok && ((unsigned)(kjb + kj0) < 16u), ok1 = rowok && ((unsigned)(kjb + kj0 + 32) < 16u);
;             const float v0 = lut[ok0 ? base + kj0 : 0], v1 = lut[ok1 ? base + kj0 + 32 : 0];
; template <int MODE, int VW>
; __device__ __forceinline__ void attn_unit_s(const AttnP& P, char* lds, const int tid) {
;     ...
;     ModeCtx mc; mc.rs = mc.cs = mc.qi = mc.qj = 0; mc.krow0 = P.krow0; mc.far_thr = P.far_thr; mc.qlo = P.q0abs + wid * QBLK; mc.cpos = 0.f; mc.cneg = 0.f;
;     mc.lidx = P.lbase - (wid * QBLK + r32) + 4 * hi;
;     if constexpr (MODE == 3) { const int tq = P.qtok0 + wid * QBLK + r32; mc.qi = tq >> 6; mc.qj = tq & 63; mc.rs = min(max(mc.qi - 4, 0), 56); mc.cs = min(max(mc.qj - 8, 0), 48); }
;     int t_lo = 0, t_hi = P.NT;
;     if constexpr (MODE == 1) { if (P.far_thr >= (1 << 20)) { const int qlo = 512 - P.lbase + wid * QBLK; t_lo = max(0, (qlo - 64) >> 6); t_hi = min(P.NT, ((qlo + 31 + 64) >> 6) + 1); } }
;     if constexpr (MODE == 3) { const int qi0 = (P.qtok0 + wid * QBLK) >> 6, rs0 = min(max(qi0 - 4, 0), 56); t_lo = rs0 - P.krow0; t_hi = t_lo + 8; }
;     constexpr bool QLD = (VW == 2);
;     float m_reg = -1e30f, l_reg = 0; f32x16 o[4 * VW] = {}; bf16x8 qr[QLD ? 4 : 8];
	v_add_u32_e32 v14, 9, v9
	s_max_i32 s5, s28, 4
	v_cmp_gt_u32_e64 s[42:43], 16, v14
	v_and_b32_e32 v14, -16, v14
	s_add_i32 s5, s5, -4
	v_cmp_eq_u32_e64 s[46:47], s68, v14
	v_add_u32_e32 v14, 10, v9
	s_min_u32 s29, s5, 56
	v_cmp_gt_u32_e64 s[38:39], 16, v14
	v_and_b32_e32 v14, -16, v14
	s_sub_i32 s5, s29, s17
	v_cmp_eq_u32_e64 s[40:41], s68, v14
	v_add_u32_e32 v14, 11, v9
	s_add_i32 s6, s5, 8
	v_cmp_gt_u32_e64 s[26:27], 16, v14
	v_and_b32_e32 v14, -16, v14
	v_cmp_eq_u32_e64 s[30:31], s68, v14
	s_movk_i32 s13, 0xffef
	v_lshlrev_b32_e32 v14, 2, v8
	s_cmp_lg_u32 0, -1
	v_and_b32_e32 v3, 0xc0, v2
	v_and_b32_e32 v2, -16, v9
	v_cmp_lt_u32_e64 s[14:15], s13, v9
	s_movk_i32 s13, 0xffd0
	v_add_u32_e32 v157, s10, v14
	v_add_u32_e32 v156, s10, v0
	s_cselect_b32 s10, 0, 0
	v_add_u32_e32 v0, s9, v0
	s_add_i32 s9, s28, s20
	v_cmp_eq_u32_e64 s[64:65], s68, v2
	v_cmp_eq_u32_e64 s[18:19], s13, v2
	v_add_u32_e32 v2, 17, v9
	v_sub_u32_e32 v0, v0, v14
	s_mulk_i32 s9, 0x7c
	v_cmp_gt_u32_e64 s[16:17], 16, v2
	v_subrev_u32_e32 v0, s9, v0
	s_lshl_b32 s9, s24, 7
	s_nop 1
	v_writelane_b32 v254, s16, 31
	v_and_b32_e32 v2, -16, v2
	s_and_b32 s9, s9, 0x80
	v_writelane_b32 v254, s17, 32
	v_cmp_eq_u32_e64 s[16:17], s68, v2
	v_subrev_u32_e32 v0, s9, v0
	s_add_i32 s9, 0, 0x20ba0
	s_or_b32 s2, s21, s2
	s_nop 0
	v_writelane_b32 v254, s16, 33
	v_add_u32_e32 v2, 18, v9
	s_add_u32 s0, s2, s0
	v_writelane_b32 v254, s17, 34
	v_cmp_gt_u32_e64 s[16:17], 16, v2
	s_addc_u32 s1, s3, s1
	v_lshlrev_b32_e32 v155, 1, v154
	v_and_b32_e32 v11, 0x118, v11
	s_nop 0
	v_writelane_b32 v254, s16, 17
	v_and_b32_e32 v2, -16, v2
	s_add_u32 s0, s22, s0
	v_writelane_b32 v254, s17, 18
	v_and_or_b32 v11, v155, 32, v11
	v_cmp_eq_u32_e64 s[16:17], s68, v2
	v_add_u32_e32 v2, 19, v9
	v_writelane_b32 v255, s24, 11
	s_addc_u32 s1, s23, s1
	s_sub_i32 s2, s11, s29
	v_add3_u32 v158, v3, s10, v11
	v_add_u32_e32 v171, s9, v0
	v_and_b32_e32 v0, -16, v2
	v_writelane_b32 v255, s29, 12
	s_sub_i32 s10, s2, s20
	s_sub_i32 s2, s11, s28
	v_writelane_b32 v255, s28, 13
	s_sub_i32 s2, s2, s20
	v_cmp_eq_u32_e64 s[28:29], s68, v0
	v_add_u32_e32 v0, 24, v9
	v_cmp_gt_u32_e64 s[24:25], 16, v2
	v_mad_u64_u32 v[2:3], s[2:3], s2, 31, v[142:143]
	v_cmp_gt_u32_e64 s[20:21], 16, v0
	v_and_b32_e32 v66, -16, v0
	v_or3_b32 v0, v15, v10, v12
	v_lshlrev_b32_e32 v0, 1, v0
	s_mov_b64 s[2:3], 0xfe91c00
	v_lshl_add_u64 v[144:145], v[0:1], 0, s[2:3]
	v_or3_b32 v0, v13, v10, v12
	v_lshlrev_b32_e32 v0, 1, v0
	v_writelane_b32 v254, s24, 5
	v_add_u32_e32 v71, 27, v9
	v_lshl_add_u64 v[146:147], v[0:1], 0, s[2:3]
	s_mov_b64 s[2:3], 0xfe91400
	v_writelane_b32 v254, s25, 6
	v_lshl_add_u64 v[148:149], v[4:5], 0, s[2:3]
	v_lshl_add_u64 v[150:151], v[6:7], 0, s[2:3]
	v_cmp_gt_u32_e64 s[2:3], 16, v71
	v_and_b32_e32 v72, -16, v71
	v_and_b32_e32 v152, 63, v154
	s_nop 1
	v_writelane_b32 v254, s2, 35
	v_sub_u32_e32 v2, v2, v8
	v_mov_b32_e32 v14, v1
	v_writelane_b32 v254, s3, 36
	v_cmp_eq_u32_e64 s[2:3], s68, v72
	v_mov_b32_e32 v15, v1
	s_waitcnt vmcnt(0)
	v_lshlrev_b32_e32 v161, 8, v8
	s_nop 0
	v_writelane_b32 v254, s2, 27
	v_cmp_gt_u32_e64 s[66:67], 16, v9
	v_subrev_u32_e32 v172, s12, v2
	v_add_u32_e32 v67, 25, v9
	v_add_u32_e32 v69, 26, v9
	v_mov_b32_e32 v0, v1
	v_mov_b32_e32 v2, v1
	v_mov_b32_e32 v3, v1
	v_mov_b32_e32 v4, v1
	v_mov_b32_e32 v6, v1
	v_mov_b32_e32 v8, v1
	v_mov_b32_e32 v9, v1
	v_mov_b32_e32 v10, v1
	v_mov_b32_e32 v11, v1
	v_mov_b32_e32 v12, v1
	v_mov_b32_e32 v13, v1
	s_waitcnt vmcnt(0)
	v_mov_b64_e32 v[64:65], v[14:15]
	v_mov_b64_e32 v[48:49], v[14:15]
	v_mov_b64_e32 v[32:33], v[14:15]
	v_writelane_b32 v254, s3, 28
	v_cmp_gt_u32_e64 s[2:3], 32, v152
	v_and_b32_e32 v68, -16, v67
	v_and_b32_e32 v70, -16, v69
	v_mov_b64_e32 v[62:63], v[12:13]
	v_mov_b64_e32 v[60:61], v[10:11]
	v_mov_b64_e32 v[58:59], v[8:9]
	v_mov_b64_e32 v[56:57], v[6:7]
	v_mov_b64_e32 v[54:55], v[4:5]
	v_mov_b64_e32 v[52:53], v[2:3]
	v_mov_b64_e32 v[50:51], v[0:1]
	v_mov_b64_e32 v[46:47], v[12:13]
	v_mov_b64_e32 v[44:45], v[10:11]
	v_mov_b64_e32 v[42:43], v[8:9]
	v_mov_b64_e32 v[40:41], v[6:7]
	v_mov_b64_e32 v[38:39], v[4:5]
	v_mov_b64_e32 v[36:37], v[2:3]
	v_mov_b64_e32 v[34:35], v[0:1]
	v_mov_b64_e32 v[30:31], v[12:13]
	v_mov_b64_e32 v[28:29], v[10:11]
	v_mov_b64_e32 v[26:27], v[8:9]
	v_mov_b64_e32 v[24:25], v[6:7]
	v_mov_b64_e32 v[22:23], v[4:5]
	v_mov_b64_e32 v[20:21], v[2:3]
	v_mov_b64_e32 v[18:19], v[0:1]
	v_mov_b64_e32 v[16:17], v[14:15]
	v_writelane_b32 v254, s2, 38
	s_mov_b32 s33, 0
	v_mov_b32_e32 v159, 0xf149f2ca
	v_mov_b32_e32 v160, 0
	v_mov_b64_e32 v[14:15], v[12:13]
	v_mov_b64_e32 v[12:13], v[10:11]
	v_mov_b64_e32 v[10:11], v[8:9]
	v_mov_b64_e32 v[8:9], v[6:7]
	v_mov_b64_e32 v[6:7], v[4:5]
	v_mov_b64_e32 v[4:5], v[2:3]
	v_mov_b64_e32 v[2:3], v[0:1]
	s_mov_b32 s9, 0
	v_cmp_eq_u32_e64 s[44:45], s68, v66
	v_cmp_gt_u32_e64 s[34:35], 16, v67
	v_cmp_eq_u32_e64 s[36:37], s68, v68
	v_cmp_gt_u32_e64 s[22:23], 16, v69
	v_cmp_eq_u32_e64 s[24:25], s68, v70
	v_writelane_b32 v254, s3, 39
	s_waitcnt vmcnt(0) lgkmcnt(0)
	s_barrier
	s_branch .LBB0_1613

; __device__ __forceinline__ unsigned cvt_pk_bf16(float lo, float hi) { unsigned r; asm volatile("v_cvt_pk_bf16_f32 %0, %1, %2" : "=v"(r) : "v"(lo), "v"(hi)); return r; }
; __device__ __forceinline__ unsigned dpp_xor1(unsigned v) { return (unsigned)__builtin_amdgcn_update_dpp(0, (int)v, 0xB1, 0xf, 0xf, false); }
; __device__ __forceinline__ float dpp_xor1(float v) { return __int_as_float(__builtin_amdgcn_update_dpp(0, __float_as_int(v), 0xB1, 0xf, 0xf, false)); }
; __device__ __forceinline__ int crow(int r, int hi) { return (r & 3) + 8 * (r >> 2) + 4 * hi; }
; template <int MODE, int VW>
; __device__ __forceinline__ void attn_unit_s(const AttnP& P, char* lds, const int tid) {
;     ...
;     if (hi == 0) li_l[r32] = l_reg; asm volatile("s_waitcnt lgkmcnt(0)" ::: "memory");
;     if (P.lse != nullptr && hi == 0) P.lse[(long)(wid * QBLK + r32) * P.lse_ld] = m_reg * SCALE + __logf(l_reg);
;     float rli[16];
; #pragma unroll
;     for (int r = 0; r < 16; ++r) rli[r] = __builtin_amdgcn_rcpf(li_l[crow(r, hi)]);
;     {
;         char* st = lds + wid * 10240;
;         const bool odd = (r32 & 1) != 0;
;         const int sbase = (crow(0, hi) + (odd ? 1 : 0)) * 320 + (r32 & ~1) * 2;
;         bf16_t* Ow = P.O + (long)(wid * QBLK) * P.ldo;
; #pragma unroll
;         for (int hv = 0; hv < VW; ++hv) {
; #pragma unroll
;             for (int d0 = 0; d0 < 4; ++d0)
; #pragma unroll
;                 for (int rp = 0; rp < 8; ++rp) { const int r = 2 * rp;
;                     const float a = o[hv * 4 + d0][r] * rli[r], bb = o[hv * 4 + d0][r + 1] * rli[r + 1];
;                     const float t = odd ? a : bb; const float rcv = dpp_xor1(t);
;                     const unsigned w = odd ? cvt_pk_bf16(rcv, bb) : cvt_pk_bf16(a, rcv);
;                     *(unsigned*)(st + sbase + (crow(r, 0)) * 320 + d0 * 64) = w; }
.LBB0_1688:
	s_waitcnt vmcnt(0)
	s_barrier
	s_mov_b64 s[0:1], exec
	v_readlane_b32 s2, v254, 38
	v_readlane_b32 s3, v254, 39
	s_and_b64 s[2:3], s[0:1], s[2:3]
	s_mov_b64 exec, s[2:3]
	ds_write_b32 v157, v160
	s_or_b64 exec, exec, s[0:1]
	s_waitcnt lgkmcnt(0)
	ds_read_b128 v[78:81], v156
	ds_read_b128 v[74:77], v156 offset:32
	ds_read_b128 v[70:73], v156 offset:64
	ds_read_b128 v[66:69], v156 offset:96
	v_and_b32_e32 v82, 1, v154
	v_cmp_eq_u32_e64 s[0:1], 0, v82
	s_waitcnt lgkmcnt(3)
	v_rcp_f32_e32 v0, v78
	v_rcp_f32_e32 v78, v79
	v_cmp_eq_u32_e32 vcc, 1, v82
	v_mul_f32_e32 v50, v50, v0
	v_mul_f32_e32 v79, v51, v78
	v_cndmask_b32_e64 v83, v50, v79, s[0:1]
	s_nop 1
	v_mov_b32_dpp v51, v83 quad_perm:[1,0,3,2] row_mask:0xf bank_mask:0xf
	s_and_saveexec_b64 s[2:3], vcc
	s_xor_b64 s[2:3], exec, s[2:3]
	s_cbranch_execz .LBB0_1692
	v_cvt_pk_bf16_f32 v83, v51, v79

; __device__ __forceinline__ unsigned cvt_pk_bf16(float lo, float hi) { unsigned r; asm volatile("v_cvt_pk_bf16_f32 %0, %1, %2" : "=v"(r) : "v"(lo), "v"(hi)); return r; }
; __device__ __forceinline__ unsigned dpp_xor1(unsigned v) { return (unsigned)__builtin_amdgcn_update_dpp(0, (int)v, 0xB1, 0xf, 0xf, false); }
; __device__ __forceinline__ float dpp_xor1(float v) { return __int_as_float(__builtin_amdgcn_update_dpp(0, __float_as_int(v), 0xB1, 0xf, 0xf, false)); }
; __device__ __forceinline__ int crow(int r, int hi) { return (r & 3) + 8 * (r >> 2) + 4 * hi; }
; template <int MODE, int VW>
; __device__ __forceinline__ void attn_unit_s(const AttnP& P, char* lds, const int tid) {
;     ...
;     for (int r = 0; r < 16; ++r) rli[r] = __builtin_amdgcn_rcpf(li_l[crow(r, hi)]);
;     {
;         char* st = lds + wid * 10240;
;         const bool odd = (r32 & 1) != 0;
;         const int sbase = (crow(0, hi) + (odd ? 1 : 0)) * 320 + (r32 & ~1) * 2;
;         bf16_t* Ow = P.O + (long)(wid * QBLK) * P.ldo;
; #pragma unroll
;         for (int hv = 0; hv < VW; ++hv) {
; #pragma unroll
;             for (int d0 = 0; d0 < 4; ++d0)
; #pragma unroll
;                 for (int rp = 0; rp < 8; ++rp) { const int r = 2 * rp;
;                     const float a = o[hv * 4 + d0][r] * rli[r], bb = o[hv * 4 + d0][r + 1] * rli[r + 1];
;                     const float t = odd ? a : bb; const float rcv = dpp_xor1(t);
;                     const unsigned w = odd ? cvt_pk_bf16(rcv, bb) : cvt_pk_bf16(a, rcv);
;                     *(unsigned*)(st + sbase + (crow(r, 0)) * 320 + d0 * 64) = w; }
.LBB0_1694:
	s_or_b64 exec, exec, s[2:3]
	v_rcp_f32_e32 v51, v80
	v_rcp_f32_e32 v79, v81
	v_readlane_b32 s2, v255, 11
	s_mulk_i32 s2, 0x2800
	s_add_i32 s4, s2, 0
	v_or_b32_e32 v50, v142, v82
	v_mov_b32_e32 v81, s4
	s_movk_i32 s2, 0x140
	v_and_b32_e32 v80, 60, v155
	v_mad_u32_u24 v50, v50, s2, v81
	v_mul_f32_e32 v52, v52, v51
	v_mul_f32_e32 v81, v53, v79
	v_add_u32_e32 v50, v50, v80
	v_cndmask_b32_e64 v80, v52, v81, s[0:1]
	ds_write_b32 v50, v83
	s_nop 0
	v_mov_b32_dpp v53, v80 quad_perm:[1,0,3,2] row_mask:0xf bank_mask:0xf
	s_and_saveexec_b64 s[2:3], vcc
	s_xor_b64 s[2:3], exec, s[2:3]
	s_cbranch_execz .LBB0_1696
	v_cvt_pk_bf16_f32 v80, v53, v81

; #define ltid() ltid_(wave0)
; #define P10_WEIGHTS() do { if (ucnt10++ == wslot10) { __syncthreads(); PH_IDS gfp w_up = TAB(17); gfp w_down = TAB(20); gfp ln_ffn = TAB(2); \
;             transpose_weight(w_up + (size_t)DM * DFF2, DM, DFF2, Wup, ln_ffn + DM, scr, gw, ngw, lane, true); \
;             transpose_weight(w_down + (size_t)DFF * DM, DFF, DM, Wdn, nullptr, scr, gw, ngw, lane); __syncthreads(); } } while (0)
; __global__ void __launch_bounds__(NTHREADS, 2) mk_fwd(Args args) {
;     ...
;         for (int i2 = vcu; i2 < ND_UNITS; i2 += G) {
;             att::AttnP P; P.lse = nullptr; P.lse_ld = 0; P.ldq = OD_IN; P.ldk = OD_IN; P.ldo = DM; P.lbase = 0; P.krow0 = 0; P.qtok0 = 0; P.lut = nullptr; P.lut_n = 0; P.far_thr = 1 << 30; P.q0abs = 0; P.cidx = 0;
;             {
;                 const int u = i2 & 15, h = (i2 >> 4) & 7, b = i2 >> 7;
;                 const int krow0 = min(max(4 * u - 4, 0), 56), nt = (u == 0 || u == 15) ? 8 : 12;
;                 const bf16_t* base = BIG + (size_t)b * SEQ * OD_IN + 1536 + h * 128;
;                 P.Q = base + (size_t)(u * 256) * OD_IN; P.K = base + 1024 + (size_t)(krow0 * 64) * OD_IN; P.V = base + 2048 + (size_t)(krow0 * 64) * OD_IN;
;                 P.O = R1 + ((size_t)b * SEQ + u * 256) * DM + 1024 + h * 128; P.NT = nt;
;                 P.lut = lut3 + h * 512; P.lut_n = 512; P.krow0 = krow0; P.qtok0 = u * 256;
;                 att::attn_unit_s<3, 1>(P, (char*)lds, ltid());
;                 P10_WEIGHTS();
;             }
;         }
;         while (ucnt10 <= wslot10) P10_WEIGHTS();
.LBB0_1839:
	v_readlane_b32 s0, v254, 48
	s_add_i32 s0, s0, 1
	v_readlane_b32 s2, v255, 1
	s_nop 1
	v_writelane_b32 v254, s0, 48
	s_add_i32 s2, s2, s68
	v_readlane_b32 s0, v254, 0
	s_add_i32 s0, s0, s68
	v_writelane_b32 v255, s2, 1
	s_cmpk_gt_i32 s0, 0x1ff
	s_cbranch_scc1 .LBB0_1841
	v_readlane_b32 s20, v254, 7
	v_readlane_b32 s21, v254, 8
	v_readlane_b32 s22, v254, 9
	v_readlane_b32 s23, v254, 10
	s_mov_b32 s16, s0
	s_branch .LBB0_1596

; __device__ __forceinline__ unsigned cvt_pk_bf16(float lo, float hi) { unsigned r; asm volatile("v_cvt_pk_bf16_f32 %0, %1, %2" : "=v"(r) : "v"(lo), "v"(hi)); return r; }
; __device__ __forceinline__ unsigned dpp_xor1(unsigned v) { return (unsigned)__builtin_amdgcn_update_dpp(0, (int)v, 0xB1, 0xf, 0xf, false); }
; __device__ __forceinline__ float dpp_xor1(float v) { return __int_as_float(__builtin_amdgcn_update_dpp(0, __float_as_int(v), 0xB1, 0xf, 0xf, false)); }
;     __device__ __forceinline__ void operator()(const f32x4 (&acc)[2][2][4][2], const Unit& u, int wr, int wc, int fr, int fq) const {
;     ...
;             const int row0 = u.pm * BM + wr * 64 + fr, col0 = u.pn * BM + wc * 64 + 16 * fq; const bool odd = (fr & 1) != 0;
; #pragma unroll
;             for (int ai = 0; ai < 2; ++ai)
; #pragma unroll
;                 for (int m = 0; m < 4; ++m) {
;                     const int row = row0 + ai * HALF + m * 16; float s = 0.f;
;                     const bf16_t* pa = baseb + (size_t)(row - (odd ? 1 : 0)) * DM + col0 + (odd ? 8 : 0);
;                     const u32x4 la = *(const u32x4*)pa, lb = *(const u32x4*)(pa + DM);
;                     const u32x4 snd = odd ? la : lb; u32x4 rcv;
;                     rcv.x = dpp_xor1(snd.x); rcv.y = dpp_xor1(snd.y); rcv.z = dpp_xor1(snd.z); rcv.w = dpp_xor1(snd.w);
;                     const u32x4 bw0 = odd ? rcv : la, bw1 = odd ? lb : rcv;
;                     u32x4 pw[2];
; #pragma unroll
;                     for (int bj = 0; bj < 2; ++bj) { const u32x4 bw = bj ? bw1 : bw0;
;                         const f32x4 b0 = (f32x4){bf_lo(bw.x), bf_hi(bw.x), bf_lo(bw.y), bf_hi(bw.y)}, b1 = (f32x4){bf_lo(bw.z), bf_hi(bw.z), bf_lo(bw.w), bf_hi(bw.w)};
;                         const f32x4 v0 = acc[ai][bj][m][0] + b0, v1 = acc[ai][bj][m][1] + b1;
;                         pw[bj].x = cvt_pk_bf16(v0[0], v0[1]); pw[bj].y = cvt_pk_bf16(v0[2], v0[3]); pw[bj].z = cvt_pk_bf16(v1[0], v1[1]); pw[bj].w = cvt_pk_bf16(v1[2], v1[3]);
;                         s += (v0[0] * v0[0] + v0[1] * v0[1]) + (v0[2] * v0[2] + v0[3] * v0[3]) + (v1[0] * v1[0] + v1[1] * v1[1]) + (v1[2] * v1[2] + v1[3] * v1[3]); }
;                     store_pair_rows(HB, (size_t)DM, row, col0, fr, pw[0], pw[1]);
;                     s += __shfl_xor(s, 16); s += __shfl_xor(s, 32);
;                     if (fq == 0) unsafeAtomicAdd(ssn + row, s);
.LBB0_1942:
	v_lshl_add_u32 v152, s24, 8, v156
	v_sub_u32_e32 v154, v152, v158
	v_ashrrev_i32_e32 v155, 31, v154
	v_readlane_b32 s24, v254, 25
	v_lshl_or_b32 v150, s26, 8, v159
	v_lshlrev_b64 v[154:155], 12, v[154:155]
	v_readlane_b32 s25, v254, 26
	v_ashrrev_i32_e32 v151, 31, v150
	s_nop 0
	v_lshl_add_u64 v[154:155], s[24:25], 0, v[154:155]
	v_lshl_add_u64 v[154:155], v[150:151], 1, v[154:155]
	v_lshl_add_u64 v[172:173], v[154:155], 0, v[140:141]
	v_add_co_u32_e32 v154, vcc, 0x1000, v172
	s_nop 0
	s_nop 0
	v_addc_co_u32_e32 v155, vcc, 0, v173, vcc
	global_load_dwordx4 v[164:167], v[172:173], off
	global_load_dwordx4 v[168:171], v[154:155], off
	s_waitcnt vmcnt(0)
	v_cndmask_b32_e64 v177, v167, v171, s[0:1]
	v_cndmask_b32_e64 v179, v165, v169, s[0:1]
	v_cndmask_b32_e64 v180, v164, v168, s[0:1]
	v_cndmask_b32_e64 v178, v166, v170, s[0:1]
	v_mov_b32_dpp v174, v179 quad_perm:[1,0,3,2] row_mask:0xf bank_mask:0xf
	v_mov_b32_dpp v153, v180 quad_perm:[1,0,3,2] row_mask:0xf bank_mask:0xf
	v_mov_b32_dpp v176, v177 quad_perm:[1,0,3,2] row_mask:0xf bank_mask:0xf
	v_mov_b32_dpp v175, v178 quad_perm:[1,0,3,2] row_mask:0xf bank_mask:0xf
	v_cndmask_b32_e64 v177, v176, v167, s[0:1]
	v_cndmask_b32_e64 v167, v174, v165, s[0:1]
	v_cndmask_b32_e64 v165, v153, v164, s[0:1]
	v_cndmask_b32_e64 v180, v169, v174, s[0:1]
	v_cndmask_b32_e64 v153, v168, v153, s[0:1]
	v_cndmask_b32_e64 v178, v175, v166, s[0:1]
	v_cndmask_b32_e64 v181, v171, v176, s[0:1]
	v_cndmask_b32_e64 v179, v170, v175, s[0:1]
	v_lshlrev_b32_e32 v164, 16, v165
	v_and_b32_e32 v165, 0xffff0000, v165
	v_lshlrev_b32_e32 v166, 16, v167
	v_and_b32_e32 v167, 0xffff0000, v167
	v_lshlrev_b32_e32 v170, 16, v177
	v_and_b32_e32 v171, 0xffff0000, v177
	v_lshlrev_b32_e32 v174, 16, v153
	v_and_b32_e32 v175, 0xffff0000, v153
	v_lshlrev_b32_e32 v176, 16, v180
	v_and_b32_e32 v177, 0xffff0000, v180
	v_lshlrev_b32_e32 v168, 16, v178
	v_and_b32_e32 v169, 0xffff0000, v178
	v_lshlrev_b32_e32 v178, 16, v179
	v_and_b32_e32 v179, 0xffff0000, v179
	v_lshlrev_b32_e32 v180, 16, v181
	v_and_b32_e32 v181, 0xffff0000, v181
	v_pk_add_f32 v[126:127], v[126:127], v[166:167]
	v_pk_add_f32 v[124:125], v[124:125], v[164:165]
	v_pk_add_f32 v[118:119], v[118:119], v[176:177]
	v_pk_add_f32 v[116:117], v[116:117], v[174:175]
	v_pk_add_f32 v[122:123], v[122:123], v[170:171]
	v_pk_add_f32 v[120:121], v[120:121], v[168:169]
	v_pk_add_f32 v[114:115], v[114:115], v[180:181]
	v_pk_add_f32 v[112:113], v[112:113], v[178:179]
	v_cvt_pk_bf16_f32 v153, v124, v125
	v_cvt_pk_bf16_f32 v164, v126, v127
	v_cvt_pk_bf16_f32 v165, v120, v121
	v_cvt_pk_bf16_f32 v166, v122, v123
	v_mul_f32_e32 v125, v125, v125
	v_mul_f32_e32 v127, v127, v127
	v_cvt_pk_bf16_f32 v167, v116, v117
	v_cvt_pk_bf16_f32 v168, v118, v119
	v_mul_f32_e32 v117, v117, v117
	v_mul_f32_e32 v119, v119, v119
	v_mul_f32_e32 v121, v121, v121
	v_cvt_pk_bf16_f32 v169, v112, v113
	v_cvt_pk_bf16_f32 v170, v114, v115
	v_mul_f32_e32 v113, v113, v113
	v_mul_f32_e32 v115, v115, v115
	v_fmac_f32_e32 v125, v124, v124
	v_fmac_f32_e32 v127, v126, v126
	v_fmac_f32_e32 v117, v116, v116
	v_fmac_f32_e32 v119, v118, v118
	v_fmac_f32_e32 v121, v120, v120
	v_fmac_f32_e32 v113, v112, v112
	v_fmac_f32_e32 v115, v114, v114
	v_cndmask_b32_e64 v114, v165, v169, s[0:1]
	v_cndmask_b32_e64 v116, v164, v168, s[0:1]
	v_add_f32_e32 v120, v125, v127
	v_add_f32_e32 v117, v117, v119
	v_cndmask_b32_e64 v112, v166, v170, s[0:1]
	v_mov_b32_dpp v183, v116 quad_perm:[1,0,3,2] row_mask:0xf bank_mask:0xf
	v_add_f32_e32 v116, v121, v120
	v_add_f32_e32 v113, v113, v117
	v_mov_b32_dpp v184, v114 quad_perm:[1,0,3,2] row_mask:0xf bank_mask:0xf
	v_and_b32_e32 v114, 64, v163
	v_mul_f32_e32 v123, v123, v123
	v_add_f32_e32 v113, v115, v113
	v_mov_b32_dpp v120, v112 quad_perm:[1,0,3,2] row_mask:0xf bank_mask:0xf
	v_xor_b32_e32 v112, 16, v163
	v_add_u32_e32 v115, 64, v114
	v_fmac_f32_e32 v123, v122, v122
	v_cmp_lt_i32_e32 vcc, v112, v115
	v_add_f32_e32 v116, v123, v116
	v_add_f32_e32 v113, v116, v113
	v_cndmask_b32_e32 v112, v163, v112, vcc
	v_lshlrev_b32_e32 v114, 2, v112
	ds_bpermute_b32 v112, v114, v113
	v_cndmask_b32_e64 v118, v153, v167, s[0:1]
	v_cndmask_b32_e64 v117, v183, v164, s[0:1]
	v_cndmask_b32_e64 v119, v120, v166, s[0:1]
	v_mov_b32_dpp v182, v118 quad_perm:[1,0,3,2] row_mask:0xf bank_mask:0xf
	s_waitcnt lgkmcnt(0)
	v_add_f32_e32 v112, v113, v112
	v_xor_b32_e32 v113, 32, v163
	v_cmp_lt_i32_e32 vcc, v113, v115
	v_cndmask_b32_e64 v116, v182, v153, s[0:1]
	v_cndmask_b32_e64 v118, v184, v165, s[0:1]
	v_cndmask_b32_e32 v113, v163, v113, vcc
	v_lshlrev_b32_e32 v115, 2, v113
	ds_bpermute_b32 v113, v115, v112
	global_store_dwordx4 v[172:173], v[116:119], off
	s_nop 1
	v_cndmask_b32_e64 v116, v167, v182, s[0:1]
	v_cndmask_b32_e64 v117, v168, v183, s[0:1]
	v_cndmask_b32_e64 v118, v169, v184, s[0:1]
	v_cndmask_b32_e64 v119, v170, v120, s[0:1]
	global_store_dwordx4 v[154:155], v[116:119], off
	s_and_saveexec_b64 s[24:25], s[2:3]
	s_cbranch_execz .LBB0_1944
	v_ashrrev_i32_e32 v153, 31, v152
	v_lshl_add_u64 v[116:117], v[152:153], 2, s[10:11]
	s_waitcnt lgkmcnt(0)
	v_add_f32_e32 v112, v112, v113
	global_atomic_add_f32 v[116:117], v112, off
; __device__ __forceinline__ unsigned cvt_pk_bf16(float lo, float hi) { unsigned r; asm volatile("v_cvt_pk_bf16_f32 %0, %1, %2" : "=v"(r) : "v"(lo), "v"(hi)); return r; }
; __device__ __forceinline__ unsigned dpp_xor1(unsigned v) { return (unsigned)__builtin_amdgcn_update_dpp(0, (int)v, 0xB1, 0xf, 0xf, false); }
; __device__ __forceinline__ float dpp_xor1(float v) { return __int_as_float(__builtin_amdgcn_update_dpp(0, __float_as_int(v), 0xB1, 0xf, 0xf, false)); }
;     __device__ __forceinline__ void operator()(const f32x4 (&acc)[2][2][4][2], const Unit& u, int wr, int wc, int fr, int fq) const {
;     ...
;             const int row0 = u.pm * BM + wr * 64 + fr, col0 = u.pn * BM + wc * 64 + 16 * fq; const bool odd = (fr & 1) != 0;
; #pragma unroll
;             for (int ai = 0; ai < 2; ++ai)
; #pragma unroll
;                 for (int m = 0; m < 4; ++m) {
;                     const int row = row0 + ai * HALF + m * 16; float s = 0.f;
;                     const bf16_t* pa = baseb + (size_t)(row - (odd ? 1 : 0)) * DM + col0 + (odd ? 8 : 0);
;                     const u32x4 la = *(const u32x4*)pa, lb = *(const u32x4*)(pa + DM);
;                     const u32x4 snd = odd ? la : lb; u32x4 rcv;
;                     rcv.x = dpp_xor1(snd.x); rcv.y = dpp_xor1(snd.y); rcv.z = dpp_xor1(snd.z); rcv.w = dpp_xor1(snd.w);
;                     const u32x4 bw0 = odd ? rcv : la, bw1 = odd ? lb : rcv;
;                     u32x4 pw[2];
; #pragma unroll
;                     for (int bj = 0; bj < 2; ++bj) { const u32x4 bw = bj ? bw1 : bw0;
;                         const f32x4 b0 = (f32x4){bf_lo(bw.x), bf_hi(bw.x), bf_lo(bw.y), bf_hi(bw.y)}, b1 = (f32x4){bf_lo(bw.z), bf_hi(bw.z), bf_lo(bw.w), bf_hi(bw.w)};
;                         const f32x4 v0 = acc[ai][bj][m][0] + b0, v1 = acc[ai][bj][m][1] + b1;
;                         pw[bj].x = cvt_pk_bf16(v0[0], v0[1]); pw[bj].y = cvt_pk_bf16(v0[2], v0[3]); pw[bj].z = cvt_pk_bf16(v1[0], v1[1]); pw[bj].w = cvt_pk_bf16(v1[2], v1[3]);
;                         s += (v0[0] * v0[0] + v0[1] * v0[1]) + (v0[2] * v0[2] + v0[3] * v0[3]) + (v1[0] * v1[0] + v1[1] * v1[1]) + (v1[2] * v1[2] + v1[3] * v1[3]); }
;                     store_pair_rows(HB, (size_t)DM, row, col0, fr, pw[0], pw[1]);
;                     s += __shfl_xor(s, 16); s += __shfl_xor(s, 32);
;                     if (fq == 0) unsafeAtomicAdd(ssn + row, s);
.LBB0_1944:
	s_or_b64 exec, exec, s[24:25]
	v_or_b32_e32 v112, 16, v152
	v_sub_u32_e32 v116, v112, v158
	v_ashrrev_i32_e32 v117, 31, v116
	v_readlane_b32 s24, v254, 25
	v_lshlrev_b64 v[116:117], 12, v[116:117]
	v_readlane_b32 s25, v254, 26
	s_waitcnt lgkmcnt(0)
	s_nop 0
	v_lshl_add_u64 v[116:117], s[24:25], 0, v[116:117]
	v_lshl_add_u64 v[116:117], v[150:151], 1, v[116:117]
	v_lshl_add_u64 v[124:125], v[116:117], 0, v[140:141]
	v_add_co_u32_e32 v126, vcc, 0x1000, v124
	s_nop 0
	s_nop 0
	v_addc_co_u32_e32 v127, vcc, 0, v125, vcc
	global_load_dwordx4 v[116:119], v[124:125], off
	global_load_dwordx4 v[120:123], v[126:127], off
	s_waitcnt vmcnt(0)
	v_cndmask_b32_e64 v164, v119, v123, s[0:1]
	v_cndmask_b32_e64 v165, v118, v122, s[0:1]
	v_cndmask_b32_e64 v166, v117, v121, s[0:1]
	v_cndmask_b32_e64 v167, v116, v120, s[0:1]
	v_mov_b32_dpp v154, v165 quad_perm:[1,0,3,2] row_mask:0xf bank_mask:0xf
	v_mov_b32_dpp v153, v166 quad_perm:[1,0,3,2] row_mask:0xf bank_mask:0xf
	v_mov_b32_dpp v113, v167 quad_perm:[1,0,3,2] row_mask:0xf bank_mask:0xf
	v_mov_b32_dpp v155, v164 quad_perm:[1,0,3,2] row_mask:0xf bank_mask:0xf
	v_cndmask_b32_e64 v164, v155, v119, s[0:1]
	v_cndmask_b32_e64 v165, v154, v118, s[0:1]
	v_cndmask_b32_e64 v119, v153, v117, s[0:1]
	v_cndmask_b32_e64 v117, v113, v116, s[0:1]
	v_cndmask_b32_e64 v153, v121, v153, s[0:1]
	v_cndmask_b32_e64 v113, v120, v113, s[0:1]
	v_cndmask_b32_e64 v169, v123, v155, s[0:1]
	v_cndmask_b32_e64 v167, v122, v154, s[0:1]
	v_lshlrev_b32_e32 v116, 16, v117
	v_and_b32_e32 v117, 0xffff0000, v117
	v_lshlrev_b32_e32 v118, 16, v119
	v_and_b32_e32 v119, 0xffff0000, v119
	v_lshlrev_b32_e32 v120, 16, v165
	v_and_b32_e32 v121, 0xffff0000, v165
	v_lshlrev_b32_e32 v122, 16, v164
	v_and_b32_e32 v123, 0xffff0000, v164
	v_lshlrev_b32_e32 v154, 16, v113
	v_and_b32_e32 v155, 0xffff0000, v113
	v_lshlrev_b32_e32 v164, 16, v153
	v_and_b32_e32 v165, 0xffff0000, v153
	v_lshlrev_b32_e32 v166, 16, v167
	v_and_b32_e32 v167, 0xffff0000, v167
	v_lshlrev_b32_e32 v168, 16, v169
	v_and_b32_e32 v169, 0xffff0000, v169
	v_pk_add_f32 v[110:111], v[110:111], v[118:119]
	v_pk_add_f32 v[108:109], v[108:109], v[116:117]
	v_pk_add_f32 v[102:103], v[102:103], v[164:165]
	v_pk_add_f32 v[100:101], v[100:101], v[154:155]
	v_pk_add_f32 v[106:107], v[106:107], v[122:123]
	v_pk_add_f32 v[104:105], v[104:105], v[120:121]
	v_pk_add_f32 v[98:99], v[98:99], v[168:169]
	v_pk_add_f32 v[96:97], v[96:97], v[166:167]
	v_cvt_pk_bf16_f32 v113, v108, v109
	v_cvt_pk_bf16_f32 v116, v110, v111
	v_cvt_pk_bf16_f32 v117, v104, v105
	v_cvt_pk_bf16_f32 v118, v106, v107
	v_mul_f32_e32 v109, v109, v109
	v_mul_f32_e32 v111, v111, v111
	v_cvt_pk_bf16_f32 v119, v100, v101
	v_cvt_pk_bf16_f32 v120, v102, v103
	v_mul_f32_e32 v101, v101, v101
	v_mul_f32_e32 v103, v103, v103
	v_mul_f32_e32 v105, v105, v105
	v_cvt_pk_bf16_f32 v121, v96, v97
	v_cvt_pk_bf16_f32 v122, v98, v99
	v_mul_f32_e32 v97, v97, v97
	v_mul_f32_e32 v99, v99, v99
	v_fmac_f32_e32 v109, v108, v108
	v_fmac_f32_e32 v111, v110, v110
	v_fmac_f32_e32 v101, v100, v100
	v_fmac_f32_e32 v103, v102, v102
	v_mul_f32_e32 v107, v107, v107
	v_fmac_f32_e32 v105, v104, v104
	v_fmac_f32_e32 v97, v96, v96
	v_fmac_f32_e32 v99, v98, v98
	v_cndmask_b32_e64 v98, v117, v121, s[0:1]
	v_add_f32_e32 v104, v109, v111
	v_add_f32_e32 v101, v101, v103
	v_fmac_f32_e32 v107, v106, v106
	v_mov_b32_dpp v172, v98 quad_perm:[1,0,3,2] row_mask:0xf bank_mask:0xf
	v_add_f32_e32 v98, v105, v104
	v_add_f32_e32 v97, v97, v101
	v_cndmask_b32_e64 v100, v116, v120, s[0:1]
	v_add_f32_e32 v98, v107, v98
	v_add_f32_e32 v97, v99, v97
	v_mov_b32_dpp v171, v100 quad_perm:[1,0,3,2] row_mask:0xf bank_mask:0xf
	v_add_f32_e32 v100, v98, v97
	ds_bpermute_b32 v101, v114, v100
	v_cndmask_b32_e64 v96, v118, v122, s[0:1]
	v_cndmask_b32_e64 v102, v113, v119, s[0:1]
	v_cndmask_b32_e64 v97, v171, v116, s[0:1]
	v_mov_b32_dpp v173, v96 quad_perm:[1,0,3,2] row_mask:0xf bank_mask:0xf
	v_mov_b32_dpp v170, v102 quad_perm:[1,0,3,2] row_mask:0xf bank_mask:0xf
	v_cndmask_b32_e64 v96, v170, v113, s[0:1]
	v_cndmask_b32_e64 v98, v172, v117, s[0:1]
	v_cndmask_b32_e64 v99, v173, v118, s[0:1]
	global_store_dwordx4 v[124:125], v[96:99], off
	s_waitcnt lgkmcnt(0)
	s_nop 0
	v_add_f32_e32 v96, v100, v101
	ds_bpermute_b32 v97, v115, v96
	v_cndmask_b32_e64 v98, v119, v170, s[0:1]
	v_cndmask_b32_e64 v99, v120, v171, s[0:1]
	v_cndmask_b32_e64 v100, v121, v172, s[0:1]
	v_cndmask_b32_e64 v101, v122, v173, s[0:1]
	global_store_dwordx4 v[126:127], v[98:101], off
	s_and_saveexec_b64 s[24:25], s[2:3]
	s_cbranch_execz .LBB0_1946
	v_ashrrev_i32_e32 v113, 31, v112
	v_lshl_add_u64 v[98:99], v[112:113], 2, s[10:11]
	s_waitcnt lgkmcnt(0)
	v_add_f32_e32 v96, v96, v97
	global_atomic_add_f32 v[98:99], v96, off
; __device__ __forceinline__ unsigned cvt_pk_bf16(float lo, float hi) { unsigned r; asm volatile("v_cvt_pk_bf16_f32 %0, %1, %2" : "=v"(r) : "v"(lo), "v"(hi)); return r; }
; __device__ __forceinline__ unsigned dpp_xor1(unsigned v) { return (unsigned)__builtin_amdgcn_update_dpp(0, (int)v, 0xB1, 0xf, 0xf, false); }
; __device__ __forceinline__ float dpp_xor1(float v) { return __int_as_float(__builtin_amdgcn_update_dpp(0, __float_as_int(v), 0xB1, 0xf, 0xf, false)); }
;     __device__ __forceinline__ void operator()(const f32x4 (&acc)[2][2][4][2], const Unit& u, int wr, int wc, int fr, int fq) const {
;     ...
;             const int row0 = u.pm * BM + wr * 64 + fr, col0 = u.pn * BM + wc * 64 + 16 * fq; const bool odd = (fr & 1) != 0;
; #pragma unroll
;             for (int ai = 0; ai < 2; ++ai)
; #pragma unroll
;                 for (int m = 0; m < 4; ++m) {
;                     const int row = row0 + ai * HALF + m * 16; float s = 0.f;
;                     const bf16_t* pa = baseb + (size_t)(row - (odd ? 1 : 0)) * DM + col0 + (odd ? 8 : 0);
;                     const u32x4 la = *(const u32x4*)pa, lb = *(const u32x4*)(pa + DM);
;                     const u32x4 snd = odd ? la : lb; u32x4 rcv;
;                     rcv.x = dpp_xor1(snd.x); rcv.y = dpp_xor1(snd.y); rcv.z = dpp_xor1(snd.z); rcv.w = dpp_xor1(snd.w);
;                     const u32x4 bw0 = odd ? rcv : la, bw1 = odd ? lb : rcv;
;                     u32x4 pw[2];
; #pragma unroll
;                     for (int bj = 0; bj < 2; ++bj) { const u32x4 bw = bj ? bw1 : bw0;
;                         const f32x4 b0 = (f32x4){bf_lo(bw.x), bf_hi(bw.x), bf_lo(bw.y), bf_hi(bw.y)}, b1 = (f32x4){bf_lo(bw.z), bf_hi(bw.z), bf_lo(bw.w), bf_hi(bw.w)};
;                         const f32x4 v0 = acc[ai][bj][m][0] + b0, v1 = acc[ai][bj][m][1] + b1;
;                         pw[bj].x = cvt_pk_bf16(v0[0], v0[1]); pw[bj].y = cvt_pk_bf16(v0[2], v0[3]); pw[bj].z = cvt_pk_bf16(v1[0], v1[1]); pw[bj].w = cvt_pk_bf16(v1[2], v1[3]);
;                         s += (v0[0] * v0[0] + v0[1] * v0[1]) + (v0[2] * v0[2] + v0[3] * v0[3]) + (v1[0] * v1[0] + v1[1] * v1[1]) + (v1[2] * v1[2] + v1[3] * v1[3]); }
;                     store_pair_rows(HB, (size_t)DM, row, col0, fr, pw[0], pw[1]);
;                     s += __shfl_xor(s, 16); s += __shfl_xor(s, 32);
;                     if (fq == 0) unsafeAtomicAdd(ssn + row, s);
.LBB0_1946:
	s_or_b64 exec, exec, s[24:25]
	v_or_b32_e32 v96, 32, v152
	v_sub_u32_e32 v98, v96, v158
	v_ashrrev_i32_e32 v99, 31, v98
	v_readlane_b32 s24, v254, 25
	v_lshlrev_b64 v[98:99], 12, v[98:99]
	v_readlane_b32 s25, v254, 26
	s_waitcnt lgkmcnt(0)
	s_nop 0
	v_lshl_add_u64 v[98:99], s[24:25], 0, v[98:99]
	v_lshl_add_u64 v[98:99], v[150:151], 1, v[98:99]
	v_lshl_add_u64 v[106:107], v[98:99], 0, v[140:141]
	v_add_co_u32_e32 v108, vcc, 0x1000, v106
	s_nop 0
	s_nop 0
	v_addc_co_u32_e32 v109, vcc, 0, v107, vcc
	global_load_dwordx4 v[98:101], v[106:107], off
	global_load_dwordx4 v[102:105], v[108:109], off
	s_waitcnt vmcnt(0)
	v_cndmask_b32_e64 v113, v101, v105, s[0:1]
	v_cndmask_b32_e64 v117, v99, v103, s[0:1]
	v_cndmask_b32_e64 v118, v98, v102, s[0:1]
	v_cndmask_b32_e64 v116, v100, v104, s[0:1]
	v_mov_b32_dpp v110, v117 quad_perm:[1,0,3,2] row_mask:0xf bank_mask:0xf
	v_mov_b32_dpp v97, v118 quad_perm:[1,0,3,2] row_mask:0xf bank_mask:0xf
	v_mov_b32_dpp v112, v113 quad_perm:[1,0,3,2] row_mask:0xf bank_mask:0xf
	v_mov_b32_dpp v111, v116 quad_perm:[1,0,3,2] row_mask:0xf bank_mask:0xf
	v_cndmask_b32_e64 v113, v112, v101, s[0:1]
	v_cndmask_b32_e64 v101, v110, v99, s[0:1]
	v_cndmask_b32_e64 v99, v97, v98, s[0:1]
	v_cndmask_b32_e64 v118, v103, v110, s[0:1]
	v_cndmask_b32_e64 v97, v102, v97, s[0:1]
	v_cndmask_b32_e64 v116, v111, v100, s[0:1]
	v_cndmask_b32_e64 v119, v105, v112, s[0:1]
	v_cndmask_b32_e64 v117, v104, v111, s[0:1]
	v_lshlrev_b32_e32 v98, 16, v99
	v_and_b32_e32 v99, 0xffff0000, v99
	v_lshlrev_b32_e32 v100, 16, v101
	v_and_b32_e32 v101, 0xffff0000, v101
	v_lshlrev_b32_e32 v104, 16, v113
	v_and_b32_e32 v105, 0xffff0000, v113
	v_lshlrev_b32_e32 v110, 16, v97
	v_and_b32_e32 v111, 0xffff0000, v97
	v_lshlrev_b32_e32 v112, 16, v118
	v_and_b32_e32 v113, 0xffff0000, v118
	v_lshlrev_b32_e32 v102, 16, v116
	v_and_b32_e32 v103, 0xffff0000, v116
	v_lshlrev_b32_e32 v116, 16, v117
	v_and_b32_e32 v117, 0xffff0000, v117
	v_lshlrev_b32_e32 v118, 16, v119
	v_and_b32_e32 v119, 0xffff0000, v119
	v_pk_add_f32 v[94:95], v[94:95], v[100:101]
	v_pk_add_f32 v[92:93], v[92:93], v[98:99]
	v_pk_add_f32 v[86:87], v[86:87], v[112:113]
	v_pk_add_f32 v[84:85], v[84:85], v[110:111]
	v_pk_add_f32 v[90:91], v[90:91], v[104:105]
	v_pk_add_f32 v[88:89], v[88:89], v[102:103]
	v_pk_add_f32 v[82:83], v[82:83], v[118:119]
	v_pk_add_f32 v[80:81], v[80:81], v[116:117]
	v_cvt_pk_bf16_f32 v97, v92, v93
	v_cvt_pk_bf16_f32 v98, v94, v95
	v_cvt_pk_bf16_f32 v99, v88, v89
	v_cvt_pk_bf16_f32 v100, v90, v91
	v_mul_f32_e32 v93, v93, v93
	v_mul_f32_e32 v95, v95, v95
	v_cvt_pk_bf16_f32 v101, v84, v85
	v_cvt_pk_bf16_f32 v102, v86, v87
	v_mul_f32_e32 v85, v85, v85
	v_mul_f32_e32 v87, v87, v87
	v_mul_f32_e32 v89, v89, v89
	v_cvt_pk_bf16_f32 v103, v80, v81
	v_cvt_pk_bf16_f32 v104, v82, v83
	v_mul_f32_e32 v81, v81, v81
	v_mul_f32_e32 v83, v83, v83
	v_fmac_f32_e32 v93, v92, v92
	v_fmac_f32_e32 v95, v94, v94
	v_fmac_f32_e32 v85, v84, v84
	v_fmac_f32_e32 v87, v86, v86
	v_mul_f32_e32 v91, v91, v91
	v_fmac_f32_e32 v89, v88, v88
	v_fmac_f32_e32 v81, v80, v80
	v_fmac_f32_e32 v83, v82, v82
	v_cndmask_b32_e64 v82, v99, v103, s[0:1]
	v_add_f32_e32 v88, v93, v95
	v_add_f32_e32 v85, v85, v87
	v_fmac_f32_e32 v91, v90, v90
	v_mov_b32_dpp v122, v82 quad_perm:[1,0,3,2] row_mask:0xf bank_mask:0xf
	v_add_f32_e32 v82, v89, v88
	v_add_f32_e32 v81, v81, v85
	v_cndmask_b32_e64 v84, v98, v102, s[0:1]
	v_add_f32_e32 v82, v91, v82
	v_add_f32_e32 v81, v83, v81
	v_mov_b32_dpp v121, v84 quad_perm:[1,0,3,2] row_mask:0xf bank_mask:0xf
	v_add_f32_e32 v84, v82, v81
	ds_bpermute_b32 v85, v114, v84
	v_cndmask_b32_e64 v80, v100, v104, s[0:1]
	v_cndmask_b32_e64 v86, v97, v101, s[0:1]
	v_cndmask_b32_e64 v81, v121, v98, s[0:1]
	v_mov_b32_dpp v123, v80 quad_perm:[1,0,3,2] row_mask:0xf bank_mask:0xf
	v_mov_b32_dpp v120, v86 quad_perm:[1,0,3,2] row_mask:0xf bank_mask:0xf
	v_cndmask_b32_e64 v80, v120, v97, s[0:1]
	v_cndmask_b32_e64 v82, v122, v99, s[0:1]
	v_cndmask_b32_e64 v83, v123, v100, s[0:1]
	global_store_dwordx4 v[106:107], v[80:83], off
	s_waitcnt lgkmcnt(0)
	s_nop 0
	v_add_f32_e32 v80, v84, v85
	ds_bpermute_b32 v81, v115, v80
	v_cndmask_b32_e64 v82, v101, v120, s[0:1]
	v_cndmask_b32_e64 v83, v102, v121, s[0:1]
	v_cndmask_b32_e64 v84, v103, v122, s[0:1]
	v_cndmask_b32_e64 v85, v104, v123, s[0:1]
	global_store_dwordx4 v[108:109], v[82:85], off
	s_and_saveexec_b64 s[24:25], s[2:3]
	s_cbranch_execz .LBB0_1948
	v_ashrrev_i32_e32 v97, 31, v96
	v_lshl_add_u64 v[82:83], v[96:97], 2, s[10:11]
	s_waitcnt lgkmcnt(0)
	v_add_f32_e32 v80, v80, v81
	global_atomic_add_f32 v[82:83], v80, off
; __device__ __forceinline__ unsigned cvt_pk_bf16(float lo, float hi) { unsigned r; asm volatile("v_cvt_pk_bf16_f32 %0, %1, %2" : "=v"(r) : "v"(lo), "v"(hi)); return r; }
; __device__ __forceinline__ unsigned dpp_xor1(unsigned v) { return (unsigned)__builtin_amdgcn_update_dpp(0, (int)v, 0xB1, 0xf, 0xf, false); }
; __device__ __forceinline__ float dpp_xor1(float v) { return __int_as_float(__builtin_amdgcn_update_dpp(0, __float_as_int(v), 0xB1, 0xf, 0xf, false)); }
;     __device__ __forceinline__ void operator()(const f32x4 (&acc)[2][2][4][2], const Unit& u, int wr, int wc, int fr, int fq) const {
;     ...
;             const int row0 = u.pm * BM + wr * 64 + fr, col0 = u.pn * BM + wc * 64 + 16 * fq; const bool odd = (fr & 1) != 0;
; #pragma unroll
;             for (int ai = 0; ai < 2; ++ai)
; #pragma unroll
;                 for (int m = 0; m < 4; ++m) {
;                     const int row = row0 + ai * HALF + m * 16; float s = 0.f;
;                     const bf16_t* pa = baseb + (size_t)(row - (odd ? 1 : 0)) * DM + col0 + (odd ? 8 : 0);
;                     const u32x4 la = *(const u32x4*)pa, lb = *(const u32x4*)(pa + DM);
;                     const u32x4 snd = odd ? la : lb; u32x4 rcv;
;                     rcv.x = dpp_xor1(snd.x); rcv.y = dpp_xor1(snd.y); rcv.z = dpp_xor1(snd.z); rcv.w = dpp_xor1(snd.w);
;                     const u32x4 bw0 = odd ? rcv : la, bw1 = odd ? lb : rcv;
;                     u32x4 pw[2];
; #pragma unroll
;                     for (int bj = 0; bj < 2; ++bj) { const u32x4 bw = bj ? bw1 : bw0;
;                         const f32x4 b0 = (f32x4){bf_lo(bw.x), bf_hi(bw.x), bf_lo(bw.y), bf_hi(bw.y)}, b1 = (f32x4){bf_lo(bw.z), bf_hi(bw.z), bf_lo(bw.w), bf_hi(bw.w)};
;                         const f32x4 v0 = acc[ai][bj][m][0] + b0, v1 = acc[ai][bj][m][1] + b1;
;                         pw[bj].x = cvt_pk_bf16(v0[0], v0[1]); pw[bj].y = cvt_pk_bf16(v0[2], v0[3]); pw[bj].z = cvt_pk_bf16(v1[0], v1[1]); pw[bj].w = cvt_pk_bf16(v1[2], v1[3]);
;                         s += (v0[0] * v0[0] + v0[1] * v0[1]) + (v0[2] * v0[2] + v0[3] * v0[3]) + (v1[0] * v1[0] + v1[1] * v1[1]) + (v1[2] * v1[2] + v1[3] * v1[3]); }
;                     store_pair_rows(HB, (size_t)DM, row, col0, fr, pw[0], pw[1]);
;                     s += __shfl_xor(s, 16); s += __shfl_xor(s, 32);
;                     if (fq == 0) unsafeAtomicAdd(ssn + row, s);
.LBB0_1948:
	s_or_b64 exec, exec, s[24:25]
	v_or_b32_e32 v80, 48, v152
	v_sub_u32_e32 v82, v80, v158
	v_ashrrev_i32_e32 v83, 31, v82
	v_readlane_b32 s24, v254, 25
	v_lshlrev_b64 v[82:83], 12, v[82:83]
	v_readlane_b32 s25, v254, 26
	s_waitcnt lgkmcnt(0)
	s_nop 0
	v_lshl_add_u64 v[82:83], s[24:25], 0, v[82:83]
	v_lshl_add_u64 v[82:83], v[150:151], 1, v[82:83]
	v_lshl_add_u64 v[90:91], v[82:83], 0, v[140:141]
	v_add_co_u32_e32 v92, vcc, 0x1000, v90
	s_nop 0
	s_nop 0
	v_addc_co_u32_e32 v93, vcc, 0, v91, vcc
	global_load_dwordx4 v[82:85], v[90:91], off
	global_load_dwordx4 v[86:89], v[92:93], off
	s_waitcnt vmcnt(0)
	v_cndmask_b32_e64 v97, v85, v89, s[0:1]
	v_cndmask_b32_e64 v99, v83, v87, s[0:1]
	v_cndmask_b32_e64 v100, v82, v86, s[0:1]
	v_cndmask_b32_e64 v98, v84, v88, s[0:1]
	v_mov_b32_dpp v94, v99 quad_perm:[1,0,3,2] row_mask:0xf bank_mask:0xf
	v_mov_b32_dpp v81, v100 quad_perm:[1,0,3,2] row_mask:0xf bank_mask:0xf
	v_mov_b32_dpp v96, v97 quad_perm:[1,0,3,2] row_mask:0xf bank_mask:0xf
	v_mov_b32_dpp v95, v98 quad_perm:[1,0,3,2] row_mask:0xf bank_mask:0xf
	v_cndmask_b32_e64 v97, v96, v85, s[0:1]
	v_cndmask_b32_e64 v85, v94, v83, s[0:1]
	v_cndmask_b32_e64 v83, v81, v82, s[0:1]
	v_cndmask_b32_e64 v100, v87, v94, s[0:1]
	v_cndmask_b32_e64 v81, v86, v81, s[0:1]
	v_cndmask_b32_e64 v98, v95, v84, s[0:1]
	v_cndmask_b32_e64 v101, v89, v96, s[0:1]
	v_cndmask_b32_e64 v99, v88, v95, s[0:1]
	v_lshlrev_b32_e32 v82, 16, v83
	v_and_b32_e32 v83, 0xffff0000, v83
	v_lshlrev_b32_e32 v84, 16, v85
	v_and_b32_e32 v85, 0xffff0000, v85
	v_lshlrev_b32_e32 v88, 16, v97
	v_and_b32_e32 v89, 0xffff0000, v97
	v_lshlrev_b32_e32 v94, 16, v81
	v_and_b32_e32 v95, 0xffff0000, v81
	v_lshlrev_b32_e32 v96, 16, v100
	v_and_b32_e32 v97, 0xffff0000, v100
	v_lshlrev_b32_e32 v86, 16, v98
	v_and_b32_e32 v87, 0xffff0000, v98
	v_lshlrev_b32_e32 v98, 16, v99
	v_and_b32_e32 v99, 0xffff0000, v99
	v_lshlrev_b32_e32 v100, 16, v101
	v_and_b32_e32 v101, 0xffff0000, v101
	v_pk_add_f32 v[78:79], v[78:79], v[84:85]
	v_pk_add_f32 v[76:77], v[76:77], v[82:83]
	v_pk_add_f32 v[70:71], v[70:71], v[96:97]
	v_pk_add_f32 v[68:69], v[68:69], v[94:95]
	v_pk_add_f32 v[74:75], v[74:75], v[88:89]
	v_pk_add_f32 v[72:73], v[72:73], v[86:87]
	v_pk_add_f32 v[66:67], v[66:67], v[100:101]
	v_pk_add_f32 v[64:65], v[64:65], v[98:99]
	v_cvt_pk_bf16_f32 v81, v76, v77
	v_cvt_pk_bf16_f32 v82, v78, v79
	v_cvt_pk_bf16_f32 v83, v72, v73
	v_cvt_pk_bf16_f32 v84, v74, v75
	v_mul_f32_e32 v77, v77, v77
	v_mul_f32_e32 v79, v79, v79
	v_cvt_pk_bf16_f32 v85, v68, v69
	v_cvt_pk_bf16_f32 v86, v70, v71
	v_mul_f32_e32 v69, v69, v69
	v_mul_f32_e32 v71, v71, v71
	v_mul_f32_e32 v73, v73, v73
	v_cvt_pk_bf16_f32 v87, v64, v65
	v_cvt_pk_bf16_f32 v88, v66, v67
	v_mul_f32_e32 v65, v65, v65
	v_mul_f32_e32 v67, v67, v67
	v_fmac_f32_e32 v77, v76, v76
	v_fmac_f32_e32 v79, v78, v78
	v_fmac_f32_e32 v69, v68, v68
	v_fmac_f32_e32 v71, v70, v70
	v_mul_f32_e32 v75, v75, v75
	v_fmac_f32_e32 v73, v72, v72
	v_fmac_f32_e32 v65, v64, v64
	v_fmac_f32_e32 v67, v66, v66
	v_cndmask_b32_e64 v66, v83, v87, s[0:1]
	v_add_f32_e32 v72, v77, v79
	v_add_f32_e32 v69, v69, v71
	v_fmac_f32_e32 v75, v74, v74
	v_mov_b32_dpp v104, v66 quad_perm:[1,0,3,2] row_mask:0xf bank_mask:0xf
	v_add_f32_e32 v66, v73, v72
	v_add_f32_e32 v65, v65, v69
	v_cndmask_b32_e64 v68, v82, v86, s[0:1]
	v_add_f32_e32 v66, v75, v66
	v_add_f32_e32 v65, v67, v65
	v_mov_b32_dpp v103, v68 quad_perm:[1,0,3,2] row_mask:0xf bank_mask:0xf
	v_add_f32_e32 v68, v66, v65
	ds_bpermute_b32 v69, v114, v68
	v_cndmask_b32_e64 v64, v84, v88, s[0:1]
	v_cndmask_b32_e64 v70, v81, v85, s[0:1]
	v_cndmask_b32_e64 v65, v103, v82, s[0:1]
	v_mov_b32_dpp v105, v64 quad_perm:[1,0,3,2] row_mask:0xf bank_mask:0xf
	v_mov_b32_dpp v102, v70 quad_perm:[1,0,3,2] row_mask:0xf bank_mask:0xf
	v_cndmask_b32_e64 v64, v102, v81, s[0:1]
	v_cndmask_b32_e64 v66, v104, v83, s[0:1]
	v_cndmask_b32_e64 v67, v105, v84, s[0:1]
	global_store_dwordx4 v[90:91], v[64:67], off
	s_waitcnt lgkmcnt(0)
	s_nop 0
	v_add_f32_e32 v64, v68, v69
	ds_bpermute_b32 v65, v115, v64
	v_cndmask_b32_e64 v66, v85, v102, s[0:1]
	v_cndmask_b32_e64 v67, v86, v103, s[0:1]
	v_cndmask_b32_e64 v68, v87, v104, s[0:1]
	v_cndmask_b32_e64 v69, v88, v105, s[0:1]
	global_store_dwordx4 v[92:93], v[66:69], off
	s_and_saveexec_b64 s[24:25], s[2:3]
	s_cbranch_execz .LBB0_1950
	v_ashrrev_i32_e32 v81, 31, v80
	v_lshl_add_u64 v[66:67], v[80:81], 2, s[10:11]
	s_waitcnt lgkmcnt(0)
	v_add_f32_e32 v64, v64, v65
	global_atomic_add_f32 v[66:67], v64, off
; __device__ __forceinline__ unsigned cvt_pk_bf16(float lo, float hi) { unsigned r; asm volatile("v_cvt_pk_bf16_f32 %0, %1, %2" : "=v"(r) : "v"(lo), "v"(hi)); return r; }
; __device__ __forceinline__ unsigned dpp_xor1(unsigned v) { return (unsigned)__builtin_amdgcn_update_dpp(0, (int)v, 0xB1, 0xf, 0xf, false); }
; __device__ __forceinline__ float dpp_xor1(float v) { return __int_as_float(__builtin_amdgcn_update_dpp(0, __float_as_int(v), 0xB1, 0xf, 0xf, false)); }
;     __device__ __forceinline__ void operator()(const f32x4 (&acc)[2][2][4][2], const Unit& u, int wr, int wc, int fr, int fq) const {
;     ...
;             const int row0 = u.pm * BM + wr * 64 + fr, col0 = u.pn * BM + wc * 64 + 16 * fq; const bool odd = (fr & 1) != 0;
; #pragma unroll
;             for (int ai = 0; ai < 2; ++ai)
; #pragma unroll
;                 for (int m = 0; m < 4; ++m) {
;                     const int row = row0 + ai * HALF + m * 16; float s = 0.f;
;                     const bf16_t* pa = baseb + (size_t)(row - (odd ? 1 : 0)) * DM + col0 + (odd ? 8 : 0);
;                     const u32x4 la = *(const u32x4*)pa, lb = *(const u32x4*)(pa + DM);
;                     const u32x4 snd = odd ? la : lb; u32x4 rcv;
;                     rcv.x = dpp_xor1(snd.x); rcv.y = dpp_xor1(snd.y); rcv.z = dpp_xor1(snd.z); rcv.w = dpp_xor1(snd.w);
;                     const u32x4 bw0 = odd ? rcv : la, bw1 = odd ? lb : rcv;
;                     u32x4 pw[2];
; #pragma unroll
;                     for (int bj = 0; bj < 2; ++bj) { const u32x4 bw = bj ? bw1 : bw0;
;                         const f32x4 b0 = (f32x4){bf_lo(bw.x), bf_hi(bw.x), bf_lo(bw.y), bf_hi(bw.y)}, b1 = (f32x4){bf_lo(bw.z), bf_hi(bw.z), bf_lo(bw.w), bf_hi(bw.w)};
;                         const f32x4 v0 = acc[ai][bj][m][0] + b0, v1 = acc[ai][bj][m][1] + b1;
;                         pw[bj].x = cvt_pk_bf16(v0[0], v0[1]); pw[bj].y = cvt_pk_bf16(v0[2], v0[3]); pw[bj].z = cvt_pk_bf16(v1[0], v1[1]); pw[bj].w = cvt_pk_bf16(v1[2], v1[3]);
;                         s += (v0[0] * v0[0] + v0[1] * v0[1]) + (v0[2] * v0[2] + v0[3] * v0[3]) + (v1[0] * v1[0] + v1[1] * v1[1]) + (v1[2] * v1[2] + v1[3] * v1[3]); }
;                     store_pair_rows(HB, (size_t)DM, row, col0, fr, pw[0], pw[1]);
;                     s += __shfl_xor(s, 16); s += __shfl_xor(s, 32);
;                     if (fq == 0) unsafeAtomicAdd(ssn + row, s);
.LBB0_1950:
	s_or_b64 exec, exec, s[24:25]
	v_add_u32_e32 v64, 0x80, v152
	v_sub_u32_e32 v66, v64, v158
	v_ashrrev_i32_e32 v67, 31, v66
	v_readlane_b32 s24, v254, 25
	v_lshlrev_b64 v[66:67], 12, v[66:67]
	v_readlane_b32 s25, v254, 26
	s_waitcnt lgkmcnt(0)
	s_nop 0
	v_lshl_add_u64 v[66:67], s[24:25], 0, v[66:67]
	v_lshl_add_u64 v[66:67], v[150:151], 1, v[66:67]
	v_lshl_add_u64 v[74:75], v[66:67], 0, v[140:141]
	v_add_co_u32_e32 v76, vcc, 0x1000, v74
	s_nop 0
	s_nop 0
	v_addc_co_u32_e32 v77, vcc, 0, v75, vcc
	global_load_dwordx4 v[66:69], v[74:75], off
	global_load_dwordx4 v[70:73], v[76:77], off
	s_waitcnt vmcnt(0)
	v_cndmask_b32_e64 v81, v69, v73, s[0:1]
	v_cndmask_b32_e64 v83, v67, v71, s[0:1]
	v_cndmask_b32_e64 v84, v66, v70, s[0:1]
	v_cndmask_b32_e64 v82, v68, v72, s[0:1]
	v_mov_b32_dpp v78, v83 quad_perm:[1,0,3,2] row_mask:0xf bank_mask:0xf
	v_mov_b32_dpp v65, v84 quad_perm:[1,0,3,2] row_mask:0xf bank_mask:0xf
	v_mov_b32_dpp v80, v81 quad_perm:[1,0,3,2] row_mask:0xf bank_mask:0xf
	v_mov_b32_dpp v79, v82 quad_perm:[1,0,3,2] row_mask:0xf bank_mask:0xf
	v_cndmask_b32_e64 v81, v80, v69, s[0:1]
	v_cndmask_b32_e64 v69, v78, v67, s[0:1]
	v_cndmask_b32_e64 v67, v65, v66, s[0:1]
	v_cndmask_b32_e64 v84, v71, v78, s[0:1]
	v_cndmask_b32_e64 v65, v70, v65, s[0:1]
	v_cndmask_b32_e64 v82, v79, v68, s[0:1]
	v_cndmask_b32_e64 v85, v73, v80, s[0:1]
	v_cndmask_b32_e64 v83, v72, v79, s[0:1]
	v_lshlrev_b32_e32 v66, 16, v67
	v_and_b32_e32 v67, 0xffff0000, v67
	v_lshlrev_b32_e32 v68, 16, v69
	v_and_b32_e32 v69, 0xffff0000, v69
	v_lshlrev_b32_e32 v72, 16, v81
	v_and_b32_e32 v73, 0xffff0000, v81
	v_lshlrev_b32_e32 v78, 16, v65
	v_and_b32_e32 v79, 0xffff0000, v65
	v_lshlrev_b32_e32 v80, 16, v84
	v_and_b32_e32 v81, 0xffff0000, v84
	v_lshlrev_b32_e32 v70, 16, v82
	v_and_b32_e32 v71, 0xffff0000, v82
	v_lshlrev_b32_e32 v82, 16, v83
	v_and_b32_e32 v83, 0xffff0000, v83
	v_lshlrev_b32_e32 v84, 16, v85
	v_and_b32_e32 v85, 0xffff0000, v85
	v_pk_add_f32 v[62:63], v[62:63], v[68:69]
	v_pk_add_f32 v[60:61], v[60:61], v[66:67]
	v_pk_add_f32 v[54:55], v[54:55], v[80:81]
	v_pk_add_f32 v[52:53], v[52:53], v[78:79]
	v_pk_add_f32 v[58:59], v[58:59], v[72:73]
	v_pk_add_f32 v[56:57], v[56:57], v[70:71]
	v_pk_add_f32 v[50:51], v[50:51], v[84:85]
	v_pk_add_f32 v[48:49], v[48:49], v[82:83]
	v_cvt_pk_bf16_f32 v65, v60, v61
	v_cvt_pk_bf16_f32 v66, v62, v63
	v_cvt_pk_bf16_f32 v67, v56, v57
	v_cvt_pk_bf16_f32 v68, v58, v59
	v_mul_f32_e32 v61, v61, v61
	v_mul_f32_e32 v63, v63, v63
	v_cvt_pk_bf16_f32 v69, v52, v53
	v_cvt_pk_bf16_f32 v70, v54, v55
	v_mul_f32_e32 v53, v53, v53
	v_mul_f32_e32 v55, v55, v55
	v_mul_f32_e32 v57, v57, v57
	v_cvt_pk_bf16_f32 v71, v48, v49
	v_cvt_pk_bf16_f32 v72, v50, v51
	v_mul_f32_e32 v49, v49, v49
	v_mul_f32_e32 v51, v51, v51
	v_fmac_f32_e32 v61, v60, v60
	v_fmac_f32_e32 v63, v62, v62
	v_fmac_f32_e32 v53, v52, v52
	v_fmac_f32_e32 v55, v54, v54
	v_mul_f32_e32 v59, v59, v59
	v_fmac_f32_e32 v57, v56, v56
	v_fmac_f32_e32 v49, v48, v48
	v_fmac_f32_e32 v51, v50, v50
	v_cndmask_b32_e64 v50, v67, v71, s[0:1]
	v_add_f32_e32 v56, v61, v63
	v_add_f32_e32 v53, v53, v55
	v_fmac_f32_e32 v59, v58, v58
	v_mov_b32_dpp v88, v50 quad_perm:[1,0,3,2] row_mask:0xf bank_mask:0xf
	v_add_f32_e32 v50, v57, v56
	v_add_f32_e32 v49, v49, v53
	v_cndmask_b32_e64 v52, v66, v70, s[0:1]
	v_add_f32_e32 v50, v59, v50
	v_add_f32_e32 v49, v51, v49
	v_mov_b32_dpp v87, v52 quad_perm:[1,0,3,2] row_mask:0xf bank_mask:0xf
	v_add_f32_e32 v52, v50, v49
	ds_bpermute_b32 v53, v114, v52
	v_cndmask_b32_e64 v48, v68, v72, s[0:1]
	v_cndmask_b32_e64 v54, v65, v69, s[0:1]
	v_cndmask_b32_e64 v49, v87, v66, s[0:1]
	v_mov_b32_dpp v89, v48 quad_perm:[1,0,3,2] row_mask:0xf bank_mask:0xf
	v_mov_b32_dpp v86, v54 quad_perm:[1,0,3,2] row_mask:0xf bank_mask:0xf
	v_cndmask_b32_e64 v48, v86, v65, s[0:1]
	v_cndmask_b32_e64 v50, v88, v67, s[0:1]
	v_cndmask_b32_e64 v51, v89, v68, s[0:1]
	global_store_dwordx4 v[74:75], v[48:51], off
	s_waitcnt lgkmcnt(0)
	s_nop 0
	v_add_f32_e32 v48, v52, v53
	ds_bpermute_b32 v49, v115, v48
	v_cndmask_b32_e64 v50, v69, v86, s[0:1]
	v_cndmask_b32_e64 v51, v70, v87, s[0:1]
	v_cndmask_b32_e64 v52, v71, v88, s[0:1]
	v_cndmask_b32_e64 v53, v72, v89, s[0:1]
	global_store_dwordx4 v[76:77], v[50:53], off
	s_and_saveexec_b64 s[24:25], s[2:3]
	s_cbranch_execz .LBB0_1952
	v_ashrrev_i32_e32 v65, 31, v64
	v_lshl_add_u64 v[50:51], v[64:65], 2, s[10:11]
	s_waitcnt lgkmcnt(0)
	v_add_f32_e32 v48, v48, v49
	global_atomic_add_f32 v[50:51], v48, off
; __device__ __forceinline__ unsigned cvt_pk_bf16(float lo, float hi) { unsigned r; asm volatile("v_cvt_pk_bf16_f32 %0, %1, %2" : "=v"(r) : "v"(lo), "v"(hi)); return r; }
; __device__ __forceinline__ unsigned dpp_xor1(unsigned v) { return (unsigned)__builtin_amdgcn_update_dpp(0, (int)v, 0xB1, 0xf, 0xf, false); }
; __device__ __forceinline__ float dpp_xor1(float v) { return __int_as_float(__builtin_amdgcn_update_dpp(0, __float_as_int(v), 0xB1, 0xf, 0xf, false)); }
;     __device__ __forceinline__ void operator()(const f32x4 (&acc)[2][2][4][2], const Unit& u, int wr, int wc, int fr, int fq) const {
;     ...
;             const int row0 = u.pm * BM + wr * 64 + fr, col0 = u.pn * BM + wc * 64 + 16 * fq; const bool odd = (fr & 1) != 0;
; #pragma unroll
;             for (int ai = 0; ai < 2; ++ai)
; #pragma unroll
;                 for (int m = 0; m < 4; ++m) {
;                     const int row = row0 + ai * HALF + m * 16; float s = 0.f;
;                     const bf16_t* pa = baseb + (size_t)(row - (odd ? 1 : 0)) * DM + col0 + (odd ? 8 : 0);
;                     const u32x4 la = *(const u32x4*)pa, lb = *(const u32x4*)(pa + DM);
;                     const u32x4 snd = odd ? la : lb; u32x4 rcv;
;                     rcv.x = dpp_xor1(snd.x); rcv.y = dpp_xor1(snd.y); rcv.z = dpp_xor1(snd.z); rcv.w = dpp_xor1(snd.w);
;                     const u32x4 bw0 = odd ? rcv : la, bw1 = odd ? lb : rcv;
;                     u32x4 pw[2];
; #pragma unroll
;                     for (int bj = 0; bj < 2; ++bj) { const u32x4 bw = bj ? bw1 : bw0;
;                         const f32x4 b0 = (f32x4){bf_lo(bw.x), bf_hi(bw.x), bf_lo(bw.y), bf_hi(bw.y)}, b1 = (f32x4){bf_lo(bw.z), bf_hi(bw.z), bf_lo(bw.w), bf_hi(bw.w)};
;                         const f32x4 v0 = acc[ai][bj][m][0] + b0, v1 = acc[ai][bj][m][1] + b1;
;                         pw[bj].x = cvt_pk_bf16(v0[0], v0[1]); pw[bj].y = cvt_pk_bf16(v0[2], v0[3]); pw[bj].z = cvt_pk_bf16(v1[0], v1[1]); pw[bj].w = cvt_pk_bf16(v1[2], v1[3]);
;                         s += (v0[0] * v0[0] + v0[1] * v0[1]) + (v0[2] * v0[2] + v0[3] * v0[3]) + (v1[0] * v1[0] + v1[1] * v1[1]) + (v1[2] * v1[2] + v1[3] * v1[3]); }
;                     store_pair_rows(HB, (size_t)DM, row, col0, fr, pw[0], pw[1]);
;                     s += __shfl_xor(s, 16); s += __shfl_xor(s, 32);
;                     if (fq == 0) unsafeAtomicAdd(ssn + row, s);
.LBB0_1952:
	s_or_b64 exec, exec, s[24:25]
	v_add_u32_e32 v48, 0x90, v152
	v_sub_u32_e32 v50, v48, v158
	v_ashrrev_i32_e32 v51, 31, v50
	v_readlane_b32 s24, v254, 25
	v_lshlrev_b64 v[50:51], 12, v[50:51]
	v_readlane_b32 s25, v254, 26
	s_waitcnt lgkmcnt(0)
	s_nop 0
	v_lshl_add_u64 v[50:51], s[24:25], 0, v[50:51]
	v_lshl_add_u64 v[50:51], v[150:151], 1, v[50:51]
	v_lshl_add_u64 v[58:59], v[50:51], 0, v[140:141]
	v_add_co_u32_e32 v60, vcc, 0x1000, v58
	s_nop 0
	s_nop 0
	v_addc_co_u32_e32 v61, vcc, 0, v59, vcc
	global_load_dwordx4 v[50:53], v[58:59], off
	global_load_dwordx4 v[54:57], v[60:61], off
	s_waitcnt vmcnt(0)
	v_cndmask_b32_e64 v65, v53, v57, s[0:1]
	v_cndmask_b32_e64 v67, v51, v55, s[0:1]
	v_cndmask_b32_e64 v68, v50, v54, s[0:1]
	v_cndmask_b32_e64 v66, v52, v56, s[0:1]
	v_mov_b32_dpp v62, v67 quad_perm:[1,0,3,2] row_mask:0xf bank_mask:0xf
	v_mov_b32_dpp v49, v68 quad_perm:[1,0,3,2] row_mask:0xf bank_mask:0xf
	v_mov_b32_dpp v64, v65 quad_perm:[1,0,3,2] row_mask:0xf bank_mask:0xf
	v_mov_b32_dpp v63, v66 quad_perm:[1,0,3,2] row_mask:0xf bank_mask:0xf
	v_cndmask_b32_e64 v65, v64, v53, s[0:1]
	v_cndmask_b32_e64 v53, v62, v51, s[0:1]
	v_cndmask_b32_e64 v51, v49, v50, s[0:1]
	v_cndmask_b32_e64 v68, v55, v62, s[0:1]
	v_cndmask_b32_e64 v49, v54, v49, s[0:1]
	v_cndmask_b32_e64 v66, v63, v52, s[0:1]
	v_cndmask_b32_e64 v69, v57, v64, s[0:1]
	v_cndmask_b32_e64 v67, v56, v63, s[0:1]
	v_lshlrev_b32_e32 v50, 16, v51
	v_and_b32_e32 v51, 0xffff0000, v51
	v_lshlrev_b32_e32 v52, 16, v53
	v_and_b32_e32 v53, 0xffff0000, v53
	v_lshlrev_b32_e32 v56, 16, v65
	v_and_b32_e32 v57, 0xffff0000, v65
	v_lshlrev_b32_e32 v62, 16, v49
	v_and_b32_e32 v63, 0xffff0000, v49
	v_lshlrev_b32_e32 v64, 16, v68
	v_and_b32_e32 v65, 0xffff0000, v68
	v_lshlrev_b32_e32 v54, 16, v66
	v_and_b32_e32 v55, 0xffff0000, v66
	v_lshlrev_b32_e32 v66, 16, v67
	v_and_b32_e32 v67, 0xffff0000, v67
	v_lshlrev_b32_e32 v68, 16, v69
	v_and_b32_e32 v69, 0xffff0000, v69
	v_pk_add_f32 v[46:47], v[46:47], v[52:53]
	v_pk_add_f32 v[44:45], v[44:45], v[50:51]
	v_pk_add_f32 v[38:39], v[38:39], v[64:65]
	v_pk_add_f32 v[36:37], v[36:37], v[62:63]
	v_pk_add_f32 v[42:43], v[42:43], v[56:57]
	v_pk_add_f32 v[40:41], v[40:41], v[54:55]
	v_pk_add_f32 v[34:35], v[34:35], v[68:69]
	v_pk_add_f32 v[32:33], v[32:33], v[66:67]
	v_cvt_pk_bf16_f32 v49, v44, v45
	v_cvt_pk_bf16_f32 v50, v46, v47
	v_cvt_pk_bf16_f32 v51, v40, v41
	v_cvt_pk_bf16_f32 v52, v42, v43
	v_mul_f32_e32 v45, v45, v45
	v_mul_f32_e32 v47, v47, v47
	v_cvt_pk_bf16_f32 v53, v36, v37
	v_cvt_pk_bf16_f32 v54, v38, v39
	v_mul_f32_e32 v37, v37, v37
	v_mul_f32_e32 v39, v39, v39
	v_mul_f32_e32 v41, v41, v41
	v_cvt_pk_bf16_f32 v55, v32, v33
	v_cvt_pk_bf16_f32 v56, v34, v35
	v_mul_f32_e32 v33, v33, v33
	v_mul_f32_e32 v35, v35, v35
	v_fmac_f32_e32 v45, v44, v44
	v_fmac_f32_e32 v47, v46, v46
	v_fmac_f32_e32 v37, v36, v36
	v_fmac_f32_e32 v39, v38, v38
	v_mul_f32_e32 v43, v43, v43
	v_fmac_f32_e32 v41, v40, v40
	v_fmac_f32_e32 v33, v32, v32
	v_fmac_f32_e32 v35, v34, v34
	v_cndmask_b32_e64 v34, v51, v55, s[0:1]
	v_add_f32_e32 v40, v45, v47
	v_add_f32_e32 v37, v37, v39
	v_fmac_f32_e32 v43, v42, v42
	v_mov_b32_dpp v72, v34 quad_perm:[1,0,3,2] row_mask:0xf bank_mask:0xf
	v_add_f32_e32 v34, v41, v40
	v_add_f32_e32 v33, v33, v37
	v_cndmask_b32_e64 v36, v50, v54, s[0:1]
	v_add_f32_e32 v34, v43, v34
	v_add_f32_e32 v33, v35, v33
	v_mov_b32_dpp v71, v36 quad_perm:[1,0,3,2] row_mask:0xf bank_mask:0xf
	v_add_f32_e32 v36, v34, v33
	ds_bpermute_b32 v37, v114, v36
	v_cndmask_b32_e64 v32, v52, v56, s[0:1]
	v_cndmask_b32_e64 v38, v49, v53, s[0:1]
	v_cndmask_b32_e64 v33, v71, v50, s[0:1]
	v_mov_b32_dpp v73, v32 quad_perm:[1,0,3,2] row_mask:0xf bank_mask:0xf
	v_mov_b32_dpp v70, v38 quad_perm:[1,0,3,2] row_mask:0xf bank_mask:0xf
	v_cndmask_b32_e64 v32, v70, v49, s[0:1]
	v_cndmask_b32_e64 v34, v72, v51, s[0:1]
	v_cndmask_b32_e64 v35, v73, v52, s[0:1]
	global_store_dwordx4 v[58:59], v[32:35], off
	s_waitcnt lgkmcnt(0)
	s_nop 0
	v_add_f32_e32 v32, v36, v37
	ds_bpermute_b32 v33, v115, v32
	v_cndmask_b32_e64 v34, v53, v70, s[0:1]
	v_cndmask_b32_e64 v35, v54, v71, s[0:1]
	v_cndmask_b32_e64 v36, v55, v72, s[0:1]
	v_cndmask_b32_e64 v37, v56, v73, s[0:1]
	global_store_dwordx4 v[60:61], v[34:37], off
	s_and_saveexec_b64 s[24:25], s[2:3]
	s_cbranch_execz .LBB0_1954
	v_ashrrev_i32_e32 v49, 31, v48
	v_lshl_add_u64 v[34:35], v[48:49], 2, s[10:11]
	s_waitcnt lgkmcnt(0)
	v_add_f32_e32 v32, v32, v33
	global_atomic_add_f32 v[34:35], v32, off
; __device__ __forceinline__ unsigned cvt_pk_bf16(float lo, float hi) { unsigned r; asm volatile("v_cvt_pk_bf16_f32 %0, %1, %2" : "=v"(r) : "v"(lo), "v"(hi)); return r; }
; __device__ __forceinline__ unsigned dpp_xor1(unsigned v) { return (unsigned)__builtin_amdgcn_update_dpp(0, (int)v, 0xB1, 0xf, 0xf, false); }
; __device__ __forceinline__ float dpp_xor1(float v) { return __int_as_float(__builtin_amdgcn_update_dpp(0, __float_as_int(v), 0xB1, 0xf, 0xf, false)); }
;     __device__ __forceinline__ void operator()(const f32x4 (&acc)[2][2][4][2], const Unit& u, int wr, int wc, int fr, int fq) const {
;     ...
;             const int row0 = u.pm * BM + wr * 64 + fr, col0 = u.pn * BM + wc * 64 + 16 * fq; const bool odd = (fr & 1) != 0;
; #pragma unroll
;             for (int ai = 0; ai < 2; ++ai)
; #pragma unroll
;                 for (int m = 0; m < 4; ++m) {
;                     const int row = row0 + ai * HALF + m * 16; float s = 0.f;
;                     const bf16_t* pa = baseb + (size_t)(row - (odd ? 1 : 0)) * DM + col0 + (odd ? 8 : 0);
;                     const u32x4 la = *(const u32x4*)pa, lb = *(const u32x4*)(pa + DM);
;                     const u32x4 snd = odd ? la : lb; u32x4 rcv;
;                     rcv.x = dpp_xor1(snd.x); rcv.y = dpp_xor1(snd.y); rcv.z = dpp_xor1(snd.z); rcv.w = dpp_xor1(snd.w);
;                     const u32x4 bw0 = odd ? rcv : la, bw1 = odd ? lb : rcv;
;                     u32x4 pw[2];
; #pragma unroll
;                     for (int bj = 0; bj < 2; ++bj) { const u32x4 bw = bj ? bw1 : bw0;
;                         const f32x4 b0 = (f32x4){bf_lo(bw.x), bf_hi(bw.x), bf_lo(bw.y), bf_hi(bw.y)}, b1 = (f32x4){bf_lo(bw.z), bf_hi(bw.z), bf_lo(bw.w), bf_hi(bw.w)};
;                         const f32x4 v0 = acc[ai][bj][m][0] + b0, v1 = acc[ai][bj][m][1] + b1;
;                         pw[bj].x = cvt_pk_bf16(v0[0], v0[1]); pw[bj].y = cvt_pk_bf16(v0[2], v0[3]); pw[bj].z = cvt_pk_bf16(v1[0], v1[1]); pw[bj].w = cvt_pk_bf16(v1[2], v1[3]);
;                         s += (v0[0] * v0[0] + v0[1] * v0[1]) + (v0[2] * v0[2] + v0[3] * v0[3]) + (v1[0] * v1[0] + v1[1] * v1[1]) + (v1[2] * v1[2] + v1[3] * v1[3]); }
;                     store_pair_rows(HB, (size_t)DM, row, col0, fr, pw[0], pw[1]);
;                     s += __shfl_xor(s, 16); s += __shfl_xor(s, 32);
;                     if (fq == 0) unsafeAtomicAdd(ssn + row, s);
.LBB0_1954:
	s_or_b64 exec, exec, s[24:25]
	v_add_u32_e32 v32, 0xa0, v152
	v_sub_u32_e32 v34, v32, v158
	v_ashrrev_i32_e32 v35, 31, v34
	v_readlane_b32 s24, v254, 25
	v_lshlrev_b64 v[34:35], 12, v[34:35]
	v_readlane_b32 s25, v254, 26
	s_waitcnt lgkmcnt(0)
	s_nop 0
	v_lshl_add_u64 v[34:35], s[24:25], 0, v[34:35]
	v_lshl_add_u64 v[34:35], v[150:151], 1, v[34:35]
	v_lshl_add_u64 v[42:43], v[34:35], 0, v[140:141]
	v_add_co_u32_e32 v44, vcc, 0x1000, v42
	s_nop 0
	s_nop 0
	v_addc_co_u32_e32 v45, vcc, 0, v43, vcc
	global_load_dwordx4 v[34:37], v[42:43], off
	global_load_dwordx4 v[38:41], v[44:45], off
	s_waitcnt vmcnt(0)
	v_cndmask_b32_e64 v49, v37, v41, s[0:1]
	v_cndmask_b32_e64 v51, v35, v39, s[0:1]
	v_cndmask_b32_e64 v52, v34, v38, s[0:1]
	v_cndmask_b32_e64 v50, v36, v40, s[0:1]
	v_mov_b32_dpp v46, v51 quad_perm:[1,0,3,2] row_mask:0xf bank_mask:0xf
	v_mov_b32_dpp v33, v52 quad_perm:[1,0,3,2] row_mask:0xf bank_mask:0xf
	v_mov_b32_dpp v48, v49 quad_perm:[1,0,3,2] row_mask:0xf bank_mask:0xf
	v_mov_b32_dpp v47, v50 quad_perm:[1,0,3,2] row_mask:0xf bank_mask:0xf
	v_cndmask_b32_e64 v49, v48, v37, s[0:1]
	v_cndmask_b32_e64 v37, v46, v35, s[0:1]
	v_cndmask_b32_e64 v35, v33, v34, s[0:1]
	v_cndmask_b32_e64 v52, v39, v46, s[0:1]
	v_cndmask_b32_e64 v33, v38, v33, s[0:1]
	v_cndmask_b32_e64 v50, v47, v36, s[0:1]
	v_cndmask_b32_e64 v53, v41, v48, s[0:1]
	v_cndmask_b32_e64 v51, v40, v47, s[0:1]
	v_lshlrev_b32_e32 v34, 16, v35
	v_and_b32_e32 v35, 0xffff0000, v35
	v_lshlrev_b32_e32 v36, 16, v37
	v_and_b32_e32 v37, 0xffff0000, v37
	v_lshlrev_b32_e32 v40, 16, v49
	v_and_b32_e32 v41, 0xffff0000, v49
	v_lshlrev_b32_e32 v46, 16, v33
	v_and_b32_e32 v47, 0xffff0000, v33
	v_lshlrev_b32_e32 v48, 16, v52
	v_and_b32_e32 v49, 0xffff0000, v52
	v_lshlrev_b32_e32 v38, 16, v50
	v_and_b32_e32 v39, 0xffff0000, v50
	v_lshlrev_b32_e32 v50, 16, v51
	v_and_b32_e32 v51, 0xffff0000, v51
	v_lshlrev_b32_e32 v52, 16, v53
	v_and_b32_e32 v53, 0xffff0000, v53
	v_pk_add_f32 v[30:31], v[30:31], v[36:37]
	v_pk_add_f32 v[28:29], v[28:29], v[34:35]
	v_pk_add_f32 v[22:23], v[22:23], v[48:49]
	v_pk_add_f32 v[20:21], v[20:21], v[46:47]
	v_pk_add_f32 v[26:27], v[26:27], v[40:41]
	v_pk_add_f32 v[24:25], v[24:25], v[38:39]
	v_pk_add_f32 v[18:19], v[18:19], v[52:53]
	v_pk_add_f32 v[16:17], v[16:17], v[50:51]
	v_cvt_pk_bf16_f32 v33, v28, v29
	v_cvt_pk_bf16_f32 v34, v30, v31
	v_cvt_pk_bf16_f32 v35, v24, v25
	v_cvt_pk_bf16_f32 v36, v26, v27
	v_mul_f32_e32 v29, v29, v29
	v_mul_f32_e32 v31, v31, v31
	v_cvt_pk_bf16_f32 v37, v20, v21
	v_cvt_pk_bf16_f32 v38, v22, v23
	v_mul_f32_e32 v21, v21, v21
	v_mul_f32_e32 v23, v23, v23
	v_mul_f32_e32 v25, v25, v25
	v_cvt_pk_bf16_f32 v39, v16, v17
	v_cvt_pk_bf16_f32 v40, v18, v19
	v_mul_f32_e32 v17, v17, v17
	v_mul_f32_e32 v19, v19, v19
	v_fmac_f32_e32 v29, v28, v28
	v_fmac_f32_e32 v31, v30, v30
	v_fmac_f32_e32 v21, v20, v20
	v_fmac_f32_e32 v23, v22, v22
	v_mul_f32_e32 v27, v27, v27
	v_fmac_f32_e32 v25, v24, v24
	v_fmac_f32_e32 v17, v16, v16
	v_fmac_f32_e32 v19, v18, v18
	v_cndmask_b32_e64 v18, v35, v39, s[0:1]
	v_add_f32_e32 v24, v29, v31
	v_add_f32_e32 v21, v21, v23
	v_fmac_f32_e32 v27, v26, v26
	v_mov_b32_dpp v56, v18 quad_perm:[1,0,3,2] row_mask:0xf bank_mask:0xf
	v_add_f32_e32 v18, v25, v24
	v_add_f32_e32 v17, v17, v21
	v_cndmask_b32_e64 v20, v34, v38, s[0:1]
	v_add_f32_e32 v18, v27, v18
	v_add_f32_e32 v17, v19, v17
	v_mov_b32_dpp v55, v20 quad_perm:[1,0,3,2] row_mask:0xf bank_mask:0xf
	v_add_f32_e32 v20, v18, v17
	ds_bpermute_b32 v21, v114, v20
	v_cndmask_b32_e64 v16, v36, v40, s[0:1]
	v_cndmask_b32_e64 v22, v33, v37, s[0:1]
	v_cndmask_b32_e64 v17, v55, v34, s[0:1]
	v_mov_b32_dpp v57, v16 quad_perm:[1,0,3,2] row_mask:0xf bank_mask:0xf
	v_mov_b32_dpp v54, v22 quad_perm:[1,0,3,2] row_mask:0xf bank_mask:0xf
	v_cndmask_b32_e64 v16, v54, v33, s[0:1]
	v_cndmask_b32_e64 v18, v56, v35, s[0:1]
	v_cndmask_b32_e64 v19, v57, v36, s[0:1]
	global_store_dwordx4 v[42:43], v[16:19], off
	s_waitcnt lgkmcnt(0)
	s_nop 0
	v_add_f32_e32 v16, v20, v21
	ds_bpermute_b32 v17, v115, v16
	v_cndmask_b32_e64 v18, v37, v54, s[0:1]
	v_cndmask_b32_e64 v19, v38, v55, s[0:1]
	v_cndmask_b32_e64 v20, v39, v56, s[0:1]
	v_cndmask_b32_e64 v21, v40, v57, s[0:1]
	global_store_dwordx4 v[44:45], v[18:21], off
	s_and_saveexec_b64 s[24:25], s[2:3]
	s_cbranch_execz .LBB0_1956
	v_ashrrev_i32_e32 v33, 31, v32
	v_lshl_add_u64 v[18:19], v[32:33], 2, s[10:11]
	s_waitcnt lgkmcnt(0)
	v_add_f32_e32 v16, v16, v17
	global_atomic_add_f32 v[18:19], v16, off
; __device__ __forceinline__ unsigned cvt_pk_bf16(float lo, float hi) { unsigned r; asm volatile("v_cvt_pk_bf16_f32 %0, %1, %2" : "=v"(r) : "v"(lo), "v"(hi)); return r; }
; __device__ __forceinline__ unsigned dpp_xor1(unsigned v) { return (unsigned)__builtin_amdgcn_update_dpp(0, (int)v, 0xB1, 0xf, 0xf, false); }
; __device__ __forceinline__ float dpp_xor1(float v) { return __int_as_float(__builtin_amdgcn_update_dpp(0, __float_as_int(v), 0xB1, 0xf, 0xf, false)); }
;     __device__ __forceinline__ void operator()(const f32x4 (&acc)[2][2][4][2], const Unit& u, int wr, int wc, int fr, int fq) const {
;     ...
;             const int row0 = u.pm * BM + wr * 64 + fr, col0 = u.pn * BM + wc * 64 + 16 * fq; const bool odd = (fr & 1) != 0;
; #pragma unroll
;             for (int ai = 0; ai < 2; ++ai)
; #pragma unroll
;                 for (int m = 0; m < 4; ++m) {
;                     const int row = row0 + ai * HALF + m * 16; float s = 0.f;
;                     const bf16_t* pa = baseb + (size_t)(row - (odd ? 1 : 0)) * DM + col0 + (odd ? 8 : 0);
;                     const u32x4 la = *(const u32x4*)pa, lb = *(const u32x4*)(pa + DM);
;                     const u32x4 snd = odd ? la : lb; u32x4 rcv;
;                     rcv.x = dpp_xor1(snd.x); rcv.y = dpp_xor1(snd.y); rcv.z = dpp_xor1(snd.z); rcv.w = dpp_xor1(snd.w);
;                     const u32x4 bw0 = odd ? rcv : la, bw1 = odd ? lb : rcv;
;                     u32x4 pw[2];
; #pragma unroll
;                     for (int bj = 0; bj < 2; ++bj) { const u32x4 bw = bj ? bw1 : bw0;
;                         const f32x4 b0 = (f32x4){bf_lo(bw.x), bf_hi(bw.x), bf_lo(bw.y), bf_hi(bw.y)}, b1 = (f32x4){bf_lo(bw.z), bf_hi(bw.z), bf_lo(bw.w), bf_hi(bw.w)};
;                         const f32x4 v0 = acc[ai][bj][m][0] + b0, v1 = acc[ai][bj][m][1] + b1;
;                         pw[bj].x = cvt_pk_bf16(v0[0], v0[1]); pw[bj].y = cvt_pk_bf16(v0[2], v0[3]); pw[bj].z = cvt_pk_bf16(v1[0], v1[1]); pw[bj].w = cvt_pk_bf16(v1[2], v1[3]);
;                         s += (v0[0] * v0[0] + v0[1] * v0[1]) + (v0[2] * v0[2] + v0[3] * v0[3]) + (v1[0] * v1[0] + v1[1] * v1[1]) + (v1[2] * v1[2] + v1[3] * v1[3]); }
;                     store_pair_rows(HB, (size_t)DM, row, col0, fr, pw[0], pw[1]);
;                     s += __shfl_xor(s, 16); s += __shfl_xor(s, 32);
;                     if (fq == 0) unsafeAtomicAdd(ssn + row, s);
.LBB0_1956:
	s_or_b64 exec, exec, s[24:25]
	v_add_u32_e32 v16, 0xb0, v152
	v_sub_u32_e32 v18, v16, v158
	v_ashrrev_i32_e32 v19, 31, v18
	v_readlane_b32 s24, v254, 25
	v_lshlrev_b64 v[18:19], 12, v[18:19]
	v_readlane_b32 s25, v254, 26
	s_waitcnt lgkmcnt(0)
	s_nop 0
	v_lshl_add_u64 v[18:19], s[24:25], 0, v[18:19]
	v_lshl_add_u64 v[18:19], v[150:151], 1, v[18:19]
	v_lshl_add_u64 v[26:27], v[18:19], 0, v[140:141]
	v_add_co_u32_e32 v28, vcc, 0x1000, v26
	s_nop 0
	s_nop 0
	v_addc_co_u32_e32 v29, vcc, 0, v27, vcc
	global_load_dwordx4 v[18:21], v[26:27], off
	global_load_dwordx4 v[22:25], v[28:29], off
	s_waitcnt vmcnt(0)
	v_cndmask_b32_e64 v33, v21, v25, s[0:1]
	v_cndmask_b32_e64 v35, v19, v23, s[0:1]
	v_cndmask_b32_e64 v36, v18, v22, s[0:1]
	v_cndmask_b32_e64 v34, v20, v24, s[0:1]
	v_mov_b32_dpp v30, v35 quad_perm:[1,0,3,2] row_mask:0xf bank_mask:0xf
	v_mov_b32_dpp v17, v36 quad_perm:[1,0,3,2] row_mask:0xf bank_mask:0xf
	v_mov_b32_dpp v32, v33 quad_perm:[1,0,3,2] row_mask:0xf bank_mask:0xf
	v_mov_b32_dpp v31, v34 quad_perm:[1,0,3,2] row_mask:0xf bank_mask:0xf
	v_cndmask_b32_e64 v33, v32, v21, s[0:1]
	v_cndmask_b32_e64 v21, v30, v19, s[0:1]
	v_cndmask_b32_e64 v19, v17, v18, s[0:1]
	v_cndmask_b32_e64 v36, v23, v30, s[0:1]
	v_cndmask_b32_e64 v17, v22, v17, s[0:1]
	v_cndmask_b32_e64 v34, v31, v20, s[0:1]
	v_cndmask_b32_e64 v37, v25, v32, s[0:1]
	v_cndmask_b32_e64 v35, v24, v31, s[0:1]
	v_lshlrev_b32_e32 v18, 16, v19
	v_and_b32_e32 v19, 0xffff0000, v19
	v_lshlrev_b32_e32 v20, 16, v21
	v_and_b32_e32 v21, 0xffff0000, v21
	v_lshlrev_b32_e32 v24, 16, v33
	v_and_b32_e32 v25, 0xffff0000, v33
	v_lshlrev_b32_e32 v30, 16, v17
	v_and_b32_e32 v31, 0xffff0000, v17
	v_lshlrev_b32_e32 v32, 16, v36
	v_and_b32_e32 v33, 0xffff0000, v36
	v_lshlrev_b32_e32 v22, 16, v34
	v_and_b32_e32 v23, 0xffff0000, v34
	v_lshlrev_b32_e32 v34, 16, v35
	v_and_b32_e32 v35, 0xffff0000, v35
	v_lshlrev_b32_e32 v36, 16, v37
	v_and_b32_e32 v37, 0xffff0000, v37
	v_pk_add_f32 v[14:15], v[14:15], v[20:21]
	v_pk_add_f32 v[12:13], v[12:13], v[18:19]
	v_pk_add_f32 v[6:7], v[6:7], v[32:33]
	v_pk_add_f32 v[4:5], v[4:5], v[30:31]
	v_pk_add_f32 v[10:11], v[10:11], v[24:25]
	v_pk_add_f32 v[8:9], v[8:9], v[22:23]
	v_pk_add_f32 v[2:3], v[2:3], v[36:37]
	v_pk_add_f32 v[0:1], v[0:1], v[34:35]
	v_cvt_pk_bf16_f32 v17, v12, v13
	v_cvt_pk_bf16_f32 v18, v14, v15
	v_cvt_pk_bf16_f32 v19, v8, v9
	v_cvt_pk_bf16_f32 v20, v10, v11
	v_mul_f32_e32 v13, v13, v13
	v_mul_f32_e32 v15, v15, v15
	v_cvt_pk_bf16_f32 v21, v4, v5
	v_cvt_pk_bf16_f32 v22, v6, v7
	v_mul_f32_e32 v5, v5, v5
	v_mul_f32_e32 v7, v7, v7
	v_mul_f32_e32 v9, v9, v9
	v_cvt_pk_bf16_f32 v23, v0, v1
	v_cvt_pk_bf16_f32 v24, v2, v3
	v_mul_f32_e32 v1, v1, v1
	v_mul_f32_e32 v3, v3, v3
	v_fmac_f32_e32 v13, v12, v12
	v_fmac_f32_e32 v15, v14, v14
	v_fmac_f32_e32 v5, v4, v4
	v_fmac_f32_e32 v7, v6, v6
	v_mul_f32_e32 v11, v11, v11
	v_fmac_f32_e32 v9, v8, v8
	v_fmac_f32_e32 v1, v0, v0
	v_fmac_f32_e32 v3, v2, v2
	v_cndmask_b32_e64 v2, v19, v23, s[0:1]
	v_add_f32_e32 v8, v13, v15
	v_add_f32_e32 v5, v5, v7
	v_fmac_f32_e32 v11, v10, v10
	v_mov_b32_dpp v40, v2 quad_perm:[1,0,3,2] row_mask:0xf bank_mask:0xf
	v_add_f32_e32 v2, v9, v8
	v_add_f32_e32 v1, v1, v5
	v_cndmask_b32_e64 v4, v18, v22, s[0:1]
	v_add_f32_e32 v2, v11, v2
	v_add_f32_e32 v1, v3, v1
	v_mov_b32_dpp v39, v4 quad_perm:[1,0,3,2] row_mask:0xf bank_mask:0xf
	v_add_f32_e32 v4, v2, v1
	ds_bpermute_b32 v5, v114, v4
	v_cndmask_b32_e64 v0, v20, v24, s[0:1]
	v_cndmask_b32_e64 v6, v17, v21, s[0:1]
	v_cndmask_b32_e64 v1, v39, v18, s[0:1]
	v_mov_b32_dpp v41, v0 quad_perm:[1,0,3,2] row_mask:0xf bank_mask:0xf
	v_mov_b32_dpp v38, v6 quad_perm:[1,0,3,2] row_mask:0xf bank_mask:0xf
	v_cndmask_b32_e64 v0, v38, v17, s[0:1]
	v_cndmask_b32_e64 v2, v40, v19, s[0:1]
	v_cndmask_b32_e64 v3, v41, v20, s[0:1]
	global_store_dwordx4 v[26:27], v[0:3], off
	s_waitcnt lgkmcnt(0)
	s_nop 0
	v_add_f32_e32 v0, v4, v5
	ds_bpermute_b32 v1, v115, v0
	v_cndmask_b32_e64 v2, v21, v38, s[0:1]
	v_cndmask_b32_e64 v3, v22, v39, s[0:1]
	v_cndmask_b32_e64 v4, v23, v40, s[0:1]
	v_cndmask_b32_e64 v5, v24, v41, s[0:1]
	global_store_dwordx4 v[28:29], v[2:5], off
	s_and_saveexec_b64 s[24:25], s[2:3]
	s_cbranch_execz .LBB0_1958
	v_ashrrev_i32_e32 v17, 31, v16
	v_lshl_add_u64 v[2:3], v[16:17], 2, s[10:11]
	s_waitcnt lgkmcnt(0)
	v_add_f32_e32 v0, v0, v1
	global_atomic_add_f32 v[2:3], v0, off

; #define LAS __attribute__((address_space(3)))
; __device__ __forceinline__ unsigned cvt_pk_bf16(float lo, float hi) { unsigned r; asm volatile("v_cvt_pk_bf16_f32 %0, %1, %2" : "=v"(r) : "v"(lo), "v"(hi)); return r; }
; __device__ __forceinline__ float dpp_ror1(float v) { return __int_as_float(__builtin_amdgcn_update_dpp(0, __float_as_int(v), 0x121, 0xf, 0xf, false)); }
; __device__ __forceinline__ float dpp_rol1(float v) { return __int_as_float(__builtin_amdgcn_update_dpp(0, __float_as_int(v), 0x12F, 0xf, 0xf, false)); }
;     __device__ __forceinline__ void operator()(f32x4 (&acc)[2][2][4][2], const Unit& u, int wr, int wc, int fr, int fq) const {
;     ...
;         for (int ai = 0; ai < 2; ++ai) {
;             const int rb = 2 * ai + wr;
;             f32x4 Sprev[2], Scur[2], Tcur[2], Tnext[2];
; #pragma unroll
;             for (int n = 0; n < 2; ++n) { Sprev[n] = (rb > 0) ? *(const LAS f32x4*)(XL + (rb - 1) * 128 + cl + 4 * n) : (f32x4){0.f, 0.f, 0.f, 0.f};
; #pragma unroll
;                 for (int j = 0; j < 4; ++j) Tcur[n][j] = dpp_rol1(acc[ai][0][0][n][j]); }
; #pragma unroll
;             for (int m = 0; m < 4; ++m) {
; #pragma unroll
;                 for (int n = 0; n < 2; ++n) {
; #pragma unroll
;                     for (int j = 0; j < 4; ++j) Scur[n][j] = dpp_ror1(acc[ai][0][m][n][j]);
;                     if (m < 3) {
; #pragma unroll
;                         for (int j = 0; j < 4; ++j) Tnext[n][j] = dpp_rol1(acc[ai][0][m < 3 ? m + 1 : 3][n][j]);
;                     } else Tnext[n] = (rb < 3) ? *(const LAS f32x4*)(XF + (rb + 1) * 128 + cl + 4 * n) : (f32x4){0.f, 0.f, 0.f, 0.f};
;                 }
;                 const int row = row0 + ai * HALF + m * 16, lrow = row & 255;
;                 const bool edge = (lrow == 0) || (lrow == 255);
;                 u32x4 ow;
; #pragma unroll
;                 for (int n = 0; n < 2; ++n) {
;                     const f32x4 up = (fr == 0) ? Sprev[n] : Scur[n], dn = (fr == 15) ? Tnext[n] : Tcur[n];
;                     const f32x4 a = w0[n] * up + w1[n] * acc[ai][0][m][n] + w2[n] * dn + bb[n];
;                     const f32x4 uu = acc[ai][1][m][n];
;                     ow[2 * n] = cvt_pk_bf16(gelu_tanh(a[0]) * uu[0], gelu_tanh(a[1]) * uu[1]);
;                     ow[2 * n + 1] = cvt_pk_bf16(gelu_tanh(a[2]) * uu[2], gelu_tanh(a[3]) * uu[3]);
;                 }
.LBB0_2056:
	s_or_b64 exec, exec, s[14:15]
	s_nop 1
	v_mov_b32_e32 v136, v208
	v_mov_b32_e32 v137, v208
	v_mov_b32_dpp v152, v172 row_ror:1 row_mask:0xf bank_mask:0xf
	v_mov_b32_dpp v153, v173 row_ror:1 row_mask:0xf bank_mask:0xf
	v_pk_mul_f32 v[138:139], v[118:119], v[136:137]
	v_pk_mul_f32 v[136:137], v[114:115], v[136:137]
	v_pk_mul_f32 v[124:125], v[124:125], v[206:207] op_sel_hi:[1,0]
	v_pk_mul_f32 v[114:115], v[122:123], v[206:207] op_sel_hi:[1,0]
	v_cndmask_b32_e64 v123, v153, v237, s[2:3]
	v_cndmask_b32_e64 v122, v152, v236, s[2:3]
	v_mov_b32_dpp v156, v124 row_ror:15 row_mask:0xf bank_mask:0xf
	v_mov_b32_dpp v157, v125 row_ror:15 row_mask:0xf bank_mask:0xf
	v_pk_mul_f32 v[122:123], v[84:85], v[122:123]
	v_cndmask_b32_e64 v143, v240, v157, s[4:5]
	v_cndmask_b32_e64 v142, v238, v156, s[4:5]
	v_pk_fma_f32 v[122:123], v[80:81], v[172:173], v[122:123]
	v_pk_fma_f32 v[122:123], v[68:69], v[142:143], v[122:123]
	v_pk_add_f32 v[122:123], v[76:77], v[122:123]
	v_mov_b32_e32 v209, v208
	v_mul_f32_e32 v142, v122, v122
	v_fmamk_f32 v142, v142, 0xbdd2d3e7, v232
	v_mul_f32_e32 v143, v123, v123
	v_mul_f32_e32 v142, v122, v142
	v_fmamk_f32 v143, v143, 0xbdd2d3e7, v232
	v_mov_b32_dpp v154, v170 row_ror:1 row_mask:0xf bank_mask:0xf
	v_mov_b32_dpp v155, v171 row_ror:1 row_mask:0xf bank_mask:0xf
	v_exp_f32_e32 v142, v142
	v_mul_f32_e32 v143, v123, v143
	v_pk_mul_f32 v[140:141], v[116:117], v[208:209]
	v_pk_mul_f32 v[118:119], v[126:127], v[206:207] op_sel_hi:[1,0]
	v_pk_mul_f32 v[116:117], v[120:121], v[206:207] op_sel_hi:[1,0]
	v_cndmask_b32_e64 v121, v155, v241, s[2:3]
	v_cndmask_b32_e64 v120, v154, v239, s[2:3]
	v_exp_f32_e32 v143, v143
	v_mov_b32_dpp v158, v118 row_ror:15 row_mask:0xf bank_mask:0xf
	v_mov_b32_dpp v159, v119 row_ror:15 row_mask:0xf bank_mask:0xf
	v_pk_mul_f32 v[120:121], v[86:87], v[120:121]
	v_cndmask_b32_e64 v127, v243, v159, s[4:5]
	v_cndmask_b32_e64 v126, v242, v158, s[4:5]
	v_pk_fma_f32 v[120:121], v[82:83], v[170:171], v[120:121]
	v_pk_fma_f32 v[120:121], v[70:71], v[126:127], v[120:121]
	v_add_f32_e32 v126, 1.0, v142
	v_rcp_f32_e32 v142, v126
	v_add_f32_e32 v126, 1.0, v143
	v_rcp_f32_e32 v143, v126
	v_pk_add_f32 v[126:127], v[78:79], v[120:121]
	v_mul_f32_e32 v120, v122, v142
	v_mul_f32_e32 v122, v126, v126
	v_mul_f32_e32 v121, v123, v143
	v_mul_f32_e32 v123, v127, v127
	v_fmamk_f32 v122, v122, 0xbdd2d3e7, v232
	v_fmamk_f32 v123, v123, 0xbdd2d3e7, v232
	v_mul_f32_e32 v122, v126, v122
	v_mul_f32_e32 v123, v127, v123
	v_exp_f32_e32 v122, v122
	v_exp_f32_e32 v123, v123
	v_mov_b32_dpp v160, v150 row_ror:1 row_mask:0xf bank_mask:0xf
	v_add_f32_e32 v122, 1.0, v122
	v_add_f32_e32 v123, 1.0, v123
	v_rcp_f32_e32 v122, v122
	v_rcp_f32_e32 v123, v123
	v_mov_b32_dpp v161, v151 row_ror:1 row_mask:0xf bank_mask:0xf
	v_mul_f32_e32 v120, v140, v120
	v_mul_f32_e32 v121, v141, v121
	v_cvt_pk_bf16_f32 v120, v120, v121
	v_mul_f32_e32 v121, v126, v122
	v_mul_f32_e32 v122, v127, v123
	v_cndmask_b32_e64 v127, v161, v199, s[2:3]
	v_cndmask_b32_e64 v126, v160, v175, s[2:3]
	v_mov_b32_dpp v164, v116 row_ror:15 row_mask:0xf bank_mask:0xf
	v_mov_b32_dpp v165, v117 row_ror:15 row_mask:0xf bank_mask:0xf
	v_pk_mul_f32 v[126:127], v[44:45], v[126:127]
	v_cndmask_b32_e64 v141, v210, v165, s[4:5]
	v_cndmask_b32_e64 v140, v201, v164, s[4:5]
	v_pk_fma_f32 v[126:127], v[40:41], v[150:151], v[126:127]
	v_pk_fma_f32 v[126:127], v[32:33], v[140:141], v[126:127]
	v_pk_add_f32 v[126:127], v[36:37], v[126:127]
	v_mov_b32_dpp v162, v148 row_ror:1 row_mask:0xf bank_mask:0xf
	v_mul_f32_e32 v140, v126, v126
	v_fmamk_f32 v140, v140, 0xbdd2d3e7, v232
	v_mul_f32_e32 v140, v126, v140
	v_mul_f32_e32 v141, v127, v127
	v_mov_b32_dpp v163, v149 row_ror:1 row_mask:0xf bank_mask:0xf
	v_mul_f32_e32 v121, v138, v121
	v_mul_f32_e32 v122, v139, v122
	v_exp_f32_e32 v140, v140
	v_fmamk_f32 v141, v141, 0xbdd2d3e7, v232
	v_cvt_pk_bf16_f32 v121, v121, v122
	v_cndmask_b32_e64 v123, v163, v211, s[2:3]
	v_cndmask_b32_e64 v122, v162, v207, s[2:3]
	v_mul_f32_e32 v141, v127, v141
	v_mov_b32_dpp v166, v114 row_ror:15 row_mask:0xf bank_mask:0xf
	v_mov_b32_dpp v167, v115 row_ror:15 row_mask:0xf bank_mask:0xf
	v_pk_mul_f32 v[122:123], v[46:47], v[122:123]
	v_exp_f32_e32 v141, v141
	v_cndmask_b32_e64 v139, v235, v167, s[4:5]
	v_cndmask_b32_e64 v138, v234, v166, s[4:5]
	v_pk_fma_f32 v[122:123], v[42:43], v[148:149], v[122:123]
	v_pk_mul_f32 v[112:113], v[112:113], v[208:209]
	v_pk_fma_f32 v[122:123], v[34:35], v[138:139], v[122:123]
	v_add_f32_e32 v138, 1.0, v140
	v_rcp_f32_e32 v140, v138
	v_add_f32_e32 v138, 1.0, v141
	v_rcp_f32_e32 v141, v138
	v_pk_add_f32 v[138:139], v[38:39], v[122:123]
	v_mul_f32_e32 v122, v126, v140
	v_mul_f32_e32 v123, v138, v138
	v_fmamk_f32 v123, v123, 0xbdd2d3e7, v232
	v_mul_f32_e32 v126, v139, v139
	v_mul_f32_e32 v123, v138, v123
	v_fmamk_f32 v126, v126, 0xbdd2d3e7, v232
	v_exp_f32_e32 v123, v123
	v_mul_f32_e32 v126, v139, v126
	v_exp_f32_e32 v126, v126
	v_mul_f32_e32 v112, v112, v122
	v_mul_f32_e32 v122, v127, v141
	v_mul_f32_e32 v113, v113, v122
	v_add_f32_e32 v122, 1.0, v123
	v_rcp_f32_e32 v123, v122
	v_add_f32_e32 v122, 1.0, v126
	v_rcp_f32_e32 v126, v122
	v_cvt_pk_bf16_f32 v122, v112, v113
	v_mul_f32_e32 v112, v138, v123
	v_mul_f32_e32 v113, v139, v126
	v_mov_b32_dpp v138, v124 row_ror:1 row_mask:0xf bank_mask:0xf
	v_mov_b32_dpp v139, v125 row_ror:1 row_mask:0xf bank_mask:0xf
	v_cndmask_b32_e64 v151, v139, v153, s[2:3]
	v_cndmask_b32_e64 v150, v138, v152, s[2:3]
	v_mov_b32_dpp v141, v118 row_ror:1 row_mask:0xf bank_mask:0xf
	v_mov_b32_dpp v143, v119 row_ror:1 row_mask:0xf bank_mask:0xf
	v_mov_b32_dpp v140, v128 row_ror:15 row_mask:0xf bank_mask:0xf
; #define LAS __attribute__((address_space(3)))
;     __device__ __forceinline__ void operator()(f32x4 (&acc)[2][2][4][2], const Unit& u, int wr, int wc, int fr, int fq) const {
;     ...
;         for (int ai = 0; ai < 2; ++ai) {
;             const int rb = 2 * ai + wr;
;             f32x4 Sprev[2], Scur[2], Tcur[2], Tnext[2];
; #pragma unroll
;             for (int n = 0; n < 2; ++n) { Sprev[n] = (rb > 0) ? *(const LAS f32x4*)(XL + (rb - 1) * 128 + cl + 4 * n) : (f32x4){0.f, 0.f, 0.f, 0.f};
; #pragma unroll
;                 for (int j = 0; j < 4; ++j) Tcur[n][j] = dpp_rol1(acc[ai][0][0][n][j]); }
; #pragma unroll
;             for (int m = 0; m < 4; ++m) {
; #pragma unroll
;                 for (int n = 0; n < 2; ++n) {
; #pragma unroll
;                     for (int j = 0; j < 4; ++j) Scur[n][j] = dpp_ror1(acc[ai][0][m][n][j]);
;                     if (m < 3) {
; #pragma unroll
;                         for (int j = 0; j < 4; ++j) Tnext[n][j] = dpp_rol1(acc[ai][0][m < 3 ? m + 1 : 3][n][j]);
;                     } else Tnext[n] = (rb < 3) ? *(const LAS f32x4*)(XF + (rb + 1) * 128 + cl + 4 * n) : (f32x4){0.f, 0.f, 0.f, 0.f};
;                 }
;                 const int row = row0 + ai * HALF + m * 16, lrow = row & 255;
;                 const bool edge = (lrow == 0) || (lrow == 255);
;                 u32x4 ow;
; #pragma unroll
;                 for (int n = 0; n < 2; ++n) {
;                     const f32x4 up = (fr == 0) ? Sprev[n] : Scur[n], dn = (fr == 15) ? Tnext[n] : Tcur[n];
;                     const f32x4 a = w0[n] * up + w1[n] * acc[ai][0][m][n] + w2[n] * dn + bb[n];
;                     const f32x4 uu = acc[ai][1][m][n];
;                     ow[2 * n] = cvt_pk_bf16(gelu_tanh(a[0]) * uu[0], gelu_tanh(a[1]) * uu[1]);
;                     ow[2 * n + 1] = cvt_pk_bf16(gelu_tanh(a[2]) * uu[2], gelu_tanh(a[3]) * uu[3]);
;                 }
;                 if (!edge) *(u32x4*)(ACT + (size_t)row * DFF + f0) = ow;
;                 if (lrow < 2 || lrow > 253) { const int e = lrow < 2 ? lrow : lrow - 252; float* eg = EG + ((size_t)u.pm * 4 + e) * DFF + f0;
;                     *(f32x4*)eg = acc[ai][0][m][0]; *(f32x4*)(eg + 4) = acc[ai][0][m][1];
;                     if (edge) { float* eu = EU + ((size_t)u.pm * 2 + (lrow == 255 ? 1 : 0)) * DFF + f0; *(f32x4*)eu = acc[ai][1][m][0]; *(f32x4*)(eu + 4) = acc[ai][1][m][1]; } }
; #pragma unroll
	v_mov_b32_dpp v142, v129 row_ror:15 row_mask:0xf bank_mask:0xf
	v_pk_mul_f32 v[150:151], v[84:85], v[150:151]
	v_cndmask_b32_e64 v149, v143, v155, s[2:3]
	v_cndmask_b32_e64 v148, v141, v154, s[2:3]
	v_cndmask_b32_e64 v155, v157, v142, s[4:5]
	v_cndmask_b32_e64 v154, v156, v140, s[4:5]
	v_pk_fma_f32 v[124:125], v[80:81], v[124:125], v[150:151]
	v_pk_mul_f32 v[148:149], v[86:87], v[148:149]
	v_pk_fma_f32 v[124:125], v[68:69], v[154:155], v[124:125]
	v_pk_fma_f32 v[118:119], v[82:83], v[118:119], v[148:149]
	v_pk_add_f32 v[124:125], v[76:77], v[124:125]
	v_readlane_b32 s14, v254, 15
	v_mul_f32_e32 v148, v124, v124
	v_fmamk_f32 v148, v148, 0xbdd2d3e7, v232
	v_mul_f32_e32 v149, v125, v125
	v_mul_f32_e32 v148, v124, v148
	v_fmamk_f32 v149, v149, 0xbdd2d3e7, v232
	v_exp_f32_e32 v148, v148
	v_mul_f32_e32 v149, v125, v149
	v_exp_f32_e32 v149, v149
	v_readlane_b32 s15, v254, 16
	v_or_b32_e32 v144, 16, v174
	v_add_f32_e32 v148, 1.0, v148
	v_mov_b64_e32 v[146:147], s[14:15]
	v_mad_i64_i32 v[126:127], s[14:15], v144, s73, v[146:147]
	v_rcp_f32_e32 v148, v148
	v_add_f32_e32 v149, 1.0, v149
	v_mov_b32_dpp v144, v130 row_ror:15 row_mask:0xf bank_mask:0xf
	v_mov_b32_dpp v145, v131 row_ror:15 row_mask:0xf bank_mask:0xf
	v_rcp_f32_e32 v149, v149
	v_cndmask_b32_e64 v153, v159, v145, s[4:5]
	v_cndmask_b32_e64 v152, v158, v144, s[4:5]
	v_pk_fma_f32 v[118:119], v[70:71], v[152:153], v[118:119]
	v_pk_mul_f32 v[108:109], v[108:109], v[206:207] op_sel_hi:[1,0]
	v_pk_add_f32 v[118:119], v[78:79], v[118:119]
	v_mul_f32_e32 v124, v124, v148
	v_mul_f32_e32 v108, v108, v124
	v_mul_f32_e32 v124, v125, v149
	v_mul_f32_e32 v125, v118, v118
	v_fmamk_f32 v125, v125, 0xbdd2d3e7, v232
	v_mul_f32_e32 v148, v119, v119
	v_mul_f32_e32 v125, v118, v125
	v_fmamk_f32 v148, v148, 0xbdd2d3e7, v232
	v_exp_f32_e32 v125, v125
	v_mul_f32_e32 v148, v119, v148
	v_exp_f32_e32 v148, v148
	v_mul_f32_e32 v109, v109, v124
	v_add_f32_e32 v124, 1.0, v125
	v_rcp_f32_e32 v124, v124
	v_add_f32_e32 v125, 1.0, v148
	v_mul_f32_e32 v112, v136, v112
	v_mul_f32_e32 v113, v137, v113
	v_rcp_f32_e32 v125, v125
	v_cvt_pk_bf16_f32 v123, v112, v113
	v_lshlrev_b64 v[112:113], 1, v[168:169]
	v_lshl_add_u64 v[126:127], v[126:127], 0, v[112:113]
	v_pk_mul_f32 v[110:111], v[110:111], v[206:207] op_sel_hi:[1,0]
	global_store_dwordx4 v[126:127], v[120:123], off
	v_cvt_pk_bf16_f32 v108, v108, v109
	v_mul_f32_e32 v109, v118, v124
	v_mul_f32_e32 v109, v110, v109
	v_mul_f32_e32 v110, v119, v125
	v_mov_b32_dpp v120, v116 row_ror:1 row_mask:0xf bank_mask:0xf
	v_mov_b32_dpp v121, v117 row_ror:1 row_mask:0xf bank_mask:0xf
	v_mov_b32_dpp v123, v114 row_ror:1 row_mask:0xf bank_mask:0xf
	v_mov_b32_dpp v127, v115 row_ror:1 row_mask:0xf bank_mask:0xf
	v_mul_f32_e32 v110, v111, v110
	v_cvt_pk_bf16_f32 v109, v109, v110
	v_cndmask_b32_e64 v111, v127, v163, s[2:3]
	v_cndmask_b32_e64 v110, v123, v162, s[2:3]
	v_cndmask_b32_e64 v119, v121, v161, s[2:3]
	v_cndmask_b32_e64 v118, v120, v160, s[2:3]
	v_mov_b32_dpp v122, v132 row_ror:15 row_mask:0xf bank_mask:0xf
	v_mov_b32_dpp v126, v133 row_ror:15 row_mask:0xf bank_mask:0xf
	v_pk_mul_f32 v[118:119], v[44:45], v[118:119]
	v_pk_mul_f32 v[110:111], v[46:47], v[110:111]
	v_cndmask_b32_e64 v149, v165, v126, s[4:5]
	v_cndmask_b32_e64 v148, v164, v122, s[4:5]
	v_pk_fma_f32 v[110:111], v[42:43], v[114:115], v[110:111]
	v_pk_fma_f32 v[114:115], v[40:41], v[116:117], v[118:119]
	v_pk_fma_f32 v[114:115], v[32:33], v[148:149], v[114:115]
	v_pk_add_f32 v[114:115], v[36:37], v[114:115]
	v_mov_b32_dpp v136, v134 row_ror:15 row_mask:0xf bank_mask:0xf
	v_mul_f32_e32 v116, v114, v114
	v_fmamk_f32 v116, v116, 0xbdd2d3e7, v232
	v_mul_f32_e32 v116, v114, v116
	v_mul_f32_e32 v117, v115, v115
	v_exp_f32_e32 v116, v116
	v_fmamk_f32 v117, v117, 0xbdd2d3e7, v232
	v_mul_f32_e32 v117, v115, v117
	v_exp_f32_e32 v117, v117
	v_mov_b32_dpp v137, v135 row_ror:15 row_mask:0xf bank_mask:0xf
	v_add_f32_e32 v116, 1.0, v116
	v_cndmask_b32_e64 v125, v167, v137, s[4:5]
	v_cndmask_b32_e64 v124, v166, v136, s[4:5]
	v_rcp_f32_e32 v118, v116
	v_pk_fma_f32 v[110:111], v[34:35], v[124:125], v[110:111]
	v_add_f32_e32 v116, 1.0, v117
	v_rcp_f32_e32 v119, v116
	v_pk_add_f32 v[116:117], v[38:39], v[110:111]
	v_mul_f32_e32 v110, v114, v118
	v_mul_f32_e32 v111, v116, v116
	v_fmamk_f32 v111, v111, 0xbdd2d3e7, v232
	v_mul_f32_e32 v114, v117, v117
	v_mul_f32_e32 v111, v116, v111
	v_fmamk_f32 v114, v114, 0xbdd2d3e7, v232
	v_exp_f32_e32 v111, v111
	v_mul_f32_e32 v114, v117, v114
	v_exp_f32_e32 v114, v114
	v_pk_mul_f32 v[104:105], v[104:105], v[206:207] op_sel_hi:[1,0]
	v_pk_mul_f32 v[106:107], v[106:107], v[206:207] op_sel_hi:[1,0]
	v_mul_f32_e32 v104, v104, v110
	v_mul_f32_e32 v110, v115, v119
	v_mul_f32_e32 v105, v105, v110
	v_add_f32_e32 v110, 1.0, v111
	v_rcp_f32_e32 v111, v110
	v_add_f32_e32 v110, 1.0, v114
	v_rcp_f32_e32 v114, v110
	v_cvt_pk_bf16_f32 v110, v104, v105
	v_mul_f32_e32 v104, v116, v111
	v_or_b32_e32 v170, 32, v174
	v_mul_f32_e32 v105, v117, v114
	v_mul_f32_e32 v104, v106, v104
	v_mul_f32_e32 v105, v107, v105
	v_cvt_pk_bf16_f32 v111, v104, v105
	v_mad_i64_i32 v[104:105], s[14:15], v170, s73, v[146:147]
	v_lshl_add_u64 v[104:105], v[104:105], 0, v[112:113]
	global_store_dwordx4 v[104:105], v[108:111], off
	v_cndmask_b32_e64 v105, 0, 1, s[36:37]
	v_mov_b32_dpp v119, v128 row_ror:1 row_mask:0xf bank_mask:0xf
	v_mov_b32_dpp v124, v129 row_ror:1 row_mask:0xf bank_mask:0xf
	v_mov_b32_dpp v125, v130 row_ror:1 row_mask:0xf bank_mask:0xf
	v_mov_b32_dpp v146, v131 row_ror:1 row_mask:0xf bank_mask:0xf
	v_mov_b32_e32 v104, 0
	v_cmp_ne_u32_e64 s[14:15], 1, v105
	s_andn2_b64 vcc, exec, s[36:37]
	v_mov_b32_e32 v108, 0
	v_mov_b32_e32 v109, 0
	v_mov_b32_e32 v110, 0
	v_mov_b32_e32 v111, 0
	s_cbranch_vccnz .LBB0_2058
	ds_read_b128 v[108:111], v225 offset:512

;     __device__ __forceinline__ void operator()(const f32x4 (&acc)[2][2][4][2], const Unit& u, int wr, int wc, int fr, int fq) const {
;     ...
;         const int row0 = u.pm * BM + wr * 64 + fr, col0 = u.pn * BM + wc * 32 + 8 * fq; const bool odd = (fr & 1) != 0;
; #pragma unroll
;         for (int ai = 0; ai < 2; ++ai)
; #pragma unroll
;             for (int m = 0; m < 4; ++m) {
;                 const int row = row0 + ai * HALF + m * 16; float s = 0.f;
;                 const size_t off = (size_t)row * DM + col0;
;                 const size_t offp = (size_t)(row - (odd ? 1 : 0)) * DM + col0 + (odd ? 4 : 0);
; #pragma unroll
;                 for (int bj = 0; bj < 2; ++bj) {
;                     f32x4 b0, b1;
;                     if constexpr (BASE_F32) { const f32x4 la = *(const GAS f32x4*)(basef + offp + bj * HALF), lb = *(const GAS f32x4*)(basef + offp + DM + bj * HALF);
;                         const f32x4 snd = odd ? la : lb; f32x4 rcv; rcv[0] = dpp_xor1(snd[0]); rcv[1] = dpp_xor1(snd[1]); rcv[2] = dpp_xor1(snd[2]); rcv[3] = dpp_xor1(snd[3]);
;                         b0 = odd ? rcv : la; b1 = odd ? lb : rcv; }
;                     else { const u32x4 bw = *(const u32x4*)(baseb + off + bj * HALF);
;                         b0 = (f32x4){bf_lo(bw.x), bf_hi(bw.x), bf_lo(bw.y), bf_hi(bw.y)}; b1 = (f32x4){bf_lo(bw.z), bf_hi(bw.z), bf_lo(bw.w), bf_hi(bw.w)}; }
;                     const f32x4 v0 = acc[ai][bj][m][0] + b0, v1 = acc[ai][bj][m][1] + b1;
;                     if constexpr (OUT_F32) { const f32x4 snd = odd ? v0 : v1; f32x4 rcv; rcv[0] = dpp_xor1(snd[0]); rcv[1] = dpp_xor1(snd[1]); rcv[2] = dpp_xor1(snd[2]); rcv[3] = dpp_xor1(snd[3]);
;                         *(f32x4*)(H + offp + bj * HALF) = odd ? rcv : v0; *(f32x4*)(H + offp + DM + bj * HALF) = odd ? v1 : rcv; }
;                     else { u32x4 w; w.x = cvt_pk_bf16(v0[0], v0[1]); w.y = cvt_pk_bf16(v0[2], v0[3]); w.z = cvt_pk_bf16(v1[0], v1[1]); w.w = cvt_pk_bf16(v1[2], v1[3]);
;                         *(u32x4*)(HB + off + bj * HALF) = w; }
;                     s += (v0[0] * v0[0] + v0[1] * v0[1]) + (v0[2] * v0[2] + v0[3] * v0[3]) + (v1[0] * v1[0] + v1[1] * v1[1]) + (v1[2] * v1[2] + v1[3] * v1[3]);
;                 }
;                 s += __shfl_xor(s, 16); s += __shfl_xor(s, 32);
;                 if (fq == 0) unsafeAtomicAdd(ssn + row, s);
;             }
.LBB0_2190:
	v_lshl_add_u32 v148, s44, 8, v137
	v_ashrrev_i32_e32 v149, 31, v148
	v_readlane_b32 s20, v254, 25
	v_lshl_or_b32 v146, s45, 8, v154
	v_lshlrev_b64 v[150:151], 12, v[148:149]
	v_readlane_b32 s21, v254, 26
	v_ashrrev_i32_e32 v147, 31, v146
	v_sub_u32_e32 v166, v148, v153
	v_lshl_add_u64 v[150:151], s[20:21], 0, v[150:151]
	v_lshl_add_u64 v[164:165], v[146:147], 1, v[150:151]
	global_load_dwordx4 v[160:163], v[164:165], off
	v_ashrrev_i32_e32 v167, 31, v166
	v_readlane_b32 s20, v254, 7
	v_lshlrev_b64 v[166:167], 13, v[166:167]
	v_readlane_b32 s21, v254, 8
	v_or_b32_e32 v150, v146, v136
	v_mov_b32_e32 v151, v147
	v_lshl_add_u64 v[166:167], s[20:21], 0, v[166:167]
	v_lshl_add_u64 v[166:167], v[150:151], 2, v[166:167]
	v_add_co_u32_e32 v168, vcc, s35, v166
	v_readlane_b32 s22, v254, 9
	s_nop 0
	v_addc_co_u32_e32 v169, vcc, 0, v167, vcc
	v_readlane_b32 s23, v254, 10
	s_waitcnt vmcnt(0)
	v_lshlrev_b32_e32 v170, 16, v160
	v_and_b32_e32 v171, 0xffff0000, v160
	v_lshlrev_b32_e32 v160, 16, v161
	v_and_b32_e32 v161, 0xffff0000, v161
	v_lshlrev_b32_e32 v172, 16, v162
	v_and_b32_e32 v173, 0xffff0000, v162
	v_lshlrev_b32_e32 v162, 16, v163
	v_and_b32_e32 v163, 0xffff0000, v163
	v_pk_add_f32 v[170:171], v[124:125], v[170:171]
	v_pk_add_f32 v[160:161], v[126:127], v[160:161]
	v_pk_add_f32 v[172:173], v[120:121], v[172:173]
	v_pk_add_f32 v[162:163], v[122:123], v[162:163]
	v_cndmask_b32_e64 v122, v171, v173, s[0:1]
	v_cndmask_b32_e64 v120, v161, v163, s[0:1]
	v_cndmask_b32_e64 v121, v160, v162, s[0:1]
	v_cndmask_b32_e64 v123, v170, v172, s[0:1]
	v_mov_b32_dpp v174, v122 quad_perm:[1,0,3,2] row_mask:0xf bank_mask:0xf
	v_mov_b32_dpp v175, v121 quad_perm:[1,0,3,2] row_mask:0xf bank_mask:0xf
	v_mov_b32_dpp v159, v123 quad_perm:[1,0,3,2] row_mask:0xf bank_mask:0xf
	v_mov_b32_dpp v176, v120 quad_perm:[1,0,3,2] row_mask:0xf bank_mask:0xf
	v_cndmask_b32_e64 v123, v176, v161, s[0:1]
	v_cndmask_b32_e64 v122, v175, v160, s[0:1]
	v_cndmask_b32_e64 v121, v174, v171, s[0:1]
	v_cndmask_b32_e64 v120, v159, v170, s[0:1]
	v_cndmask_b32_e64 v127, v163, v176, s[0:1]
	v_cndmask_b32_e64 v126, v162, v175, s[0:1]
	v_cndmask_b32_e64 v125, v173, v174, s[0:1]
	v_cndmask_b32_e64 v124, v172, v159, s[0:1]
	global_store_dwordx4 v[166:167], v[120:123], off
	global_store_dwordx4 v[168:169], v[124:127], off
	global_load_dwordx4 v[122:125], v[164:165], off offset:256
	v_and_b32_e32 v121, 64, v158
	v_xor_b32_e32 v120, 16, v158
	v_add_u32_e32 v121, 64, v121
	v_xor_b32_e32 v126, 32, v158
	v_cmp_lt_i32_e32 vcc, v120, v121
	v_mul_f32_e32 v127, v161, v161
	v_mul_f32_e32 v161, v173, v173
	v_cndmask_b32_e32 v120, v158, v120, vcc
	v_cmp_lt_i32_e32 vcc, v126, v121
	v_lshlrev_b32_e32 v121, 2, v120
	v_fmac_f32_e32 v127, v160, v160
	v_cndmask_b32_e32 v126, v158, v126, vcc
	v_lshlrev_b32_e32 v120, 2, v126
	v_mul_f32_e32 v126, v171, v171
	v_fmac_f32_e32 v126, v170, v170
	v_mul_f32_e32 v163, v163, v163
	v_fmac_f32_e32 v161, v172, v172
	v_add_f32_e32 v126, v126, v127
	v_fmac_f32_e32 v163, v162, v162
	v_add_f32_e32 v126, v161, v126
	v_add_f32_e32 v162, v163, v126
	s_waitcnt vmcnt(0)
	v_lshlrev_b32_e32 v126, 16, v122
	v_and_b32_e32 v127, 0xffff0000, v122
	v_lshlrev_b32_e32 v122, 16, v123
	v_and_b32_e32 v123, 0xffff0000, v123
	v_lshlrev_b32_e32 v160, 16, v124
	v_and_b32_e32 v161, 0xffff0000, v124
	v_lshlrev_b32_e32 v124, 16, v125
	v_and_b32_e32 v125, 0xffff0000, v125
	v_pk_add_f32 v[116:117], v[116:117], v[126:127]
	v_pk_add_f32 v[118:119], v[118:119], v[122:123]
	v_pk_add_f32 v[122:123], v[112:113], v[160:161]
	v_pk_add_f32 v[124:125], v[114:115], v[124:125]
	v_mul_f32_e32 v126, v117, v117
	v_mul_f32_e32 v127, v119, v119
	v_cndmask_b32_e64 v112, v119, v125, s[0:1]
	v_mul_f32_e32 v160, v123, v123
	v_fmac_f32_e32 v126, v116, v116
	v_fmac_f32_e32 v127, v118, v118
	v_mul_f32_e32 v161, v125, v125
	v_mov_b32_dpp v174, v112 quad_perm:[1,0,3,2] row_mask:0xf bank_mask:0xf
	v_fmac_f32_e32 v160, v122, v122
	v_add_f32_e32 v112, v126, v127
	v_cndmask_b32_e64 v113, v118, v124, s[0:1]
	v_add_f32_e32 v112, v160, v112
	v_fmac_f32_e32 v161, v124, v124
	v_cndmask_b32_e64 v114, v117, v123, s[0:1]
	v_mov_b32_dpp v165, v113 quad_perm:[1,0,3,2] row_mask:0xf bank_mask:0xf
	v_add_f32_e32 v112, v161, v112
	v_cndmask_b32_e64 v115, v116, v122, s[0:1]
	v_mov_b32_dpp v164, v114 quad_perm:[1,0,3,2] row_mask:0xf bank_mask:0xf
	v_cndmask_b32_e64 v114, v165, v118, s[0:1]
	v_add_f32_e32 v118, v162, v112
	v_mov_b32_dpp v159, v115 quad_perm:[1,0,3,2] row_mask:0xf bank_mask:0xf
	v_cndmask_b32_e64 v115, v174, v119, s[0:1]
	ds_bpermute_b32 v119, v121, v118
	v_cndmask_b32_e64 v113, v164, v117, s[0:1]
	v_cndmask_b32_e64 v112, v159, v116, s[0:1]
	global_store_dwordx4 v[166:167], v[112:115], off offset:512
	v_cndmask_b32_e64 v117, v125, v174, s[0:1]
	v_cndmask_b32_e64 v116, v124, v165, s[0:1]
	s_waitcnt lgkmcnt(0)
	v_add_f32_e32 v112, v118, v119
	ds_bpermute_b32 v113, v120, v112
	v_cndmask_b32_e64 v115, v123, v164, s[0:1]
	v_cndmask_b32_e64 v114, v122, v159, s[0:1]
	global_store_dwordx4 v[168:169], v[114:117], off offset:512
	s_and_saveexec_b64 s[20:21], s[2:3]
	s_cbranch_execz .LBB0_2192
	v_lshl_add_u64 v[114:115], v[148:149], 2, s[12:13]
	s_waitcnt lgkmcnt(0)
	v_add_f32_e32 v112, v112, v113
	global_atomic_add_f32 v[114:115], v112, off
;     __device__ __forceinline__ void operator()(const f32x4 (&acc)[2][2][4][2], const Unit& u, int wr, int wc, int fr, int fq) const {
;     ...
;         const int row0 = u.pm * BM + wr * 64 + fr, col0 = u.pn * BM + wc * 32 + 8 * fq; const bool odd = (fr & 1) != 0;
; #pragma unroll
;         for (int ai = 0; ai < 2; ++ai)
; #pragma unroll
;             for (int m = 0; m < 4; ++m) {
;                 const int row = row0 + ai * HALF + m * 16; float s = 0.f;
;                 const size_t off = (size_t)row * DM + col0;
;                 const size_t offp = (size_t)(row - (odd ? 1 : 0)) * DM + col0 + (odd ? 4 : 0);
; #pragma unroll
;                 for (int bj = 0; bj < 2; ++bj) {
;                     f32x4 b0, b1;
;                     if constexpr (BASE_F32) { const f32x4 la = *(const GAS f32x4*)(basef + offp + bj * HALF), lb = *(const GAS f32x4*)(basef + offp + DM + bj * HALF);
;                         const f32x4 snd = odd ? la : lb; f32x4 rcv; rcv[0] = dpp_xor1(snd[0]); rcv[1] = dpp_xor1(snd[1]); rcv[2] = dpp_xor1(snd[2]); rcv[3] = dpp_xor1(snd[3]);
;                         b0 = odd ? rcv : la; b1 = odd ? lb : rcv; }
;                     else { const u32x4 bw = *(const u32x4*)(baseb + off + bj * HALF);
;                         b0 = (f32x4){bf_lo(bw.x), bf_hi(bw.x), bf_lo(bw.y), bf_hi(bw.y)}; b1 = (f32x4){bf_lo(bw.z), bf_hi(bw.z), bf_lo(bw.w), bf_hi(bw.w)}; }
;                     const f32x4 v0 = acc[ai][bj][m][0] + b0, v1 = acc[ai][bj][m][1] + b1;
;                     if constexpr (OUT_F32) { const f32x4 snd = odd ? v0 : v1; f32x4 rcv; rcv[0] = dpp_xor1(snd[0]); rcv[1] = dpp_xor1(snd[1]); rcv[2] = dpp_xor1(snd[2]); rcv[3] = dpp_xor1(snd[3]);
;                         *(f32x4*)(H + offp + bj * HALF) = odd ? rcv : v0; *(f32x4*)(H + offp + DM + bj * HALF) = odd ? v1 : rcv; }
;                     else { u32x4 w; w.x = cvt_pk_bf16(v0[0], v0[1]); w.y = cvt_pk_bf16(v0[2], v0[3]); w.z = cvt_pk_bf16(v1[0], v1[1]); w.w = cvt_pk_bf16(v1[2], v1[3]);
;                         *(u32x4*)(HB + off + bj * HALF) = w; }
;                     s += (v0[0] * v0[0] + v0[1] * v0[1]) + (v0[2] * v0[2] + v0[3] * v0[3]) + (v1[0] * v1[0] + v1[1] * v1[1]) + (v1[2] * v1[2] + v1[3] * v1[3]);
;                 }
;                 s += __shfl_xor(s, 16); s += __shfl_xor(s, 32);
;                 if (fq == 0) unsafeAtomicAdd(ssn + row, s);
;             }
.LBB0_2192:
	s_or_b64 exec, exec, s[20:21]
	v_or_b32_e32 v112, 16, v148
	s_waitcnt lgkmcnt(0)
	v_ashrrev_i32_e32 v113, 31, v112
	v_readlane_b32 s20, v254, 25
	v_lshlrev_b64 v[114:115], 12, v[112:113]
	v_readlane_b32 s21, v254, 26
	v_sub_u32_e32 v122, v112, v153
	v_ashrrev_i32_e32 v123, 31, v122
	v_lshl_add_u64 v[114:115], s[20:21], 0, v[114:115]
	v_lshl_add_u64 v[118:119], v[146:147], 1, v[114:115]
	global_load_dwordx4 v[114:117], v[118:119], off
	v_readlane_b32 s20, v254, 7
	v_lshlrev_b64 v[122:123], 13, v[122:123]
	v_readlane_b32 s21, v254, 8
	s_nop 1
	v_lshl_add_u64 v[122:123], s[20:21], 0, v[122:123]
	v_lshl_add_u64 v[122:123], v[150:151], 2, v[122:123]
	v_add_co_u32_e32 v124, vcc, s35, v122
	v_readlane_b32 s22, v254, 9
	s_nop 0
	v_addc_co_u32_e32 v125, vcc, 0, v123, vcc
	v_readlane_b32 s23, v254, 10
	s_waitcnt vmcnt(0)
	v_lshlrev_b32_e32 v126, 16, v114
	v_and_b32_e32 v127, 0xffff0000, v114
	v_lshlrev_b32_e32 v114, 16, v115
	v_and_b32_e32 v115, 0xffff0000, v115
	v_lshlrev_b32_e32 v160, 16, v116
	v_and_b32_e32 v161, 0xffff0000, v116
	v_lshlrev_b32_e32 v116, 16, v117
	v_and_b32_e32 v117, 0xffff0000, v117
	v_pk_add_f32 v[126:127], v[108:109], v[126:127]
	v_pk_add_f32 v[114:115], v[110:111], v[114:115]
	v_pk_add_f32 v[160:161], v[104:105], v[160:161]
	v_pk_add_f32 v[116:117], v[106:107], v[116:117]
	v_cndmask_b32_e64 v106, v127, v161, s[0:1]
	v_cndmask_b32_e64 v104, v115, v117, s[0:1]
	v_cndmask_b32_e64 v105, v114, v116, s[0:1]
	v_cndmask_b32_e64 v107, v126, v160, s[0:1]
	v_mov_b32_dpp v159, v106 quad_perm:[1,0,3,2] row_mask:0xf bank_mask:0xf
	v_mov_b32_dpp v162, v105 quad_perm:[1,0,3,2] row_mask:0xf bank_mask:0xf
	v_mov_b32_dpp v149, v107 quad_perm:[1,0,3,2] row_mask:0xf bank_mask:0xf
	v_mov_b32_dpp v163, v104 quad_perm:[1,0,3,2] row_mask:0xf bank_mask:0xf
	v_cndmask_b32_e64 v107, v163, v115, s[0:1]
	v_cndmask_b32_e64 v106, v162, v114, s[0:1]
	v_cndmask_b32_e64 v105, v159, v127, s[0:1]
	v_cndmask_b32_e64 v104, v149, v126, s[0:1]
	v_cndmask_b32_e64 v111, v117, v163, s[0:1]
	v_cndmask_b32_e64 v110, v116, v162, s[0:1]
	v_cndmask_b32_e64 v109, v161, v159, s[0:1]
	v_cndmask_b32_e64 v108, v160, v149, s[0:1]
	global_store_dwordx4 v[122:123], v[104:107], off
	global_store_dwordx4 v[124:125], v[108:111], off
	global_load_dwordx4 v[104:107], v[118:119], off offset:256
	s_nop 1
	v_mul_f32_e32 v108, v127, v127
	v_mul_f32_e32 v109, v115, v115
	v_mul_f32_e32 v110, v161, v161
	v_fmac_f32_e32 v108, v126, v126
	v_fmac_f32_e32 v109, v114, v114
	v_mul_f32_e32 v111, v117, v117
	v_fmac_f32_e32 v110, v160, v160
	v_add_f32_e32 v108, v108, v109
	v_fmac_f32_e32 v111, v116, v116
	v_add_f32_e32 v108, v110, v108
	v_add_f32_e32 v114, v111, v108
	s_waitcnt vmcnt(0)
	v_lshlrev_b32_e32 v108, 16, v104
	v_and_b32_e32 v109, 0xffff0000, v104
	v_lshlrev_b32_e32 v104, 16, v105
	v_and_b32_e32 v105, 0xffff0000, v105
	v_lshlrev_b32_e32 v110, 16, v106
	v_and_b32_e32 v111, 0xffff0000, v106
	v_lshlrev_b32_e32 v106, 16, v107
	v_and_b32_e32 v107, 0xffff0000, v107
	v_pk_add_f32 v[100:101], v[100:101], v[108:109]
	v_pk_add_f32 v[102:103], v[102:103], v[104:105]
	v_pk_add_f32 v[104:105], v[96:97], v[110:111]
	v_pk_add_f32 v[106:107], v[98:99], v[106:107]
	v_mul_f32_e32 v108, v101, v101
	v_mul_f32_e32 v109, v103, v103
	v_cndmask_b32_e64 v96, v103, v107, s[0:1]
	v_mul_f32_e32 v110, v105, v105
	v_fmac_f32_e32 v108, v100, v100
	v_fmac_f32_e32 v109, v102, v102
	v_mul_f32_e32 v111, v107, v107
	v_mov_b32_dpp v159, v96 quad_perm:[1,0,3,2] row_mask:0xf bank_mask:0xf
	v_fmac_f32_e32 v110, v104, v104
	v_add_f32_e32 v96, v108, v109
	v_cndmask_b32_e64 v97, v102, v106, s[0:1]
	v_add_f32_e32 v96, v110, v96
	v_fmac_f32_e32 v111, v106, v106
	v_cndmask_b32_e64 v98, v101, v105, s[0:1]
	v_mov_b32_dpp v149, v97 quad_perm:[1,0,3,2] row_mask:0xf bank_mask:0xf
	v_add_f32_e32 v96, v111, v96
	v_cndmask_b32_e64 v99, v100, v104, s[0:1]
	v_mov_b32_dpp v119, v98 quad_perm:[1,0,3,2] row_mask:0xf bank_mask:0xf
	v_cndmask_b32_e64 v98, v149, v102, s[0:1]
	v_add_f32_e32 v102, v114, v96
	v_mov_b32_dpp v118, v99 quad_perm:[1,0,3,2] row_mask:0xf bank_mask:0xf
	v_cndmask_b32_e64 v99, v159, v103, s[0:1]
	ds_bpermute_b32 v103, v121, v102
	v_cndmask_b32_e64 v97, v119, v101, s[0:1]
	v_cndmask_b32_e64 v96, v118, v100, s[0:1]
	global_store_dwordx4 v[122:123], v[96:99], off offset:512
	v_cndmask_b32_e64 v101, v107, v159, s[0:1]
	v_cndmask_b32_e64 v100, v106, v149, s[0:1]
	s_waitcnt lgkmcnt(0)
	v_add_f32_e32 v96, v102, v103
	ds_bpermute_b32 v97, v120, v96
	v_cndmask_b32_e64 v99, v105, v119, s[0:1]
	v_cndmask_b32_e64 v98, v104, v118, s[0:1]
	global_store_dwordx4 v[124:125], v[98:101], off offset:512
	s_and_saveexec_b64 s[20:21], s[2:3]
	s_cbranch_execz .LBB0_2194
	v_lshl_add_u64 v[98:99], v[112:113], 2, s[12:13]
	s_waitcnt lgkmcnt(0)
	v_add_f32_e32 v96, v96, v97
	global_atomic_add_f32 v[98:99], v96, off
;     __device__ __forceinline__ void operator()(const f32x4 (&acc)[2][2][4][2], const Unit& u, int wr, int wc, int fr, int fq) const {
;     ...
;         const int row0 = u.pm * BM + wr * 64 + fr, col0 = u.pn * BM + wc * 32 + 8 * fq; const bool odd = (fr & 1) != 0;
; #pragma unroll
;         for (int ai = 0; ai < 2; ++ai)
; #pragma unroll
;             for (int m = 0; m < 4; ++m) {
;                 const int row = row0 + ai * HALF + m * 16; float s = 0.f;
;                 const size_t off = (size_t)row * DM + col0;
;                 const size_t offp = (size_t)(row - (odd ? 1 : 0)) * DM + col0 + (odd ? 4 : 0);
; #pragma unroll
;                 for (int bj = 0; bj < 2; ++bj) {
;                     f32x4 b0, b1;
;                     if constexpr (BASE_F32) { const f32x4 la = *(const GAS f32x4*)(basef + offp + bj * HALF), lb = *(const GAS f32x4*)(basef + offp + DM + bj * HALF);
;                         const f32x4 snd = odd ? la : lb; f32x4 rcv; rcv[0] = dpp_xor1(snd[0]); rcv[1] = dpp_xor1(snd[1]); rcv[2] = dpp_xor1(snd[2]); rcv[3] = dpp_xor1(snd[3]);
;                         b0 = odd ? rcv : la; b1 = odd ? lb : rcv; }
;                     else { const u32x4 bw = *(const u32x4*)(baseb + off + bj * HALF);
;                         b0 = (f32x4){bf_lo(bw.x), bf_hi(bw.x), bf_lo(bw.y), bf_hi(bw.y)}; b1 = (f32x4){bf_lo(bw.z), bf_hi(bw.z), bf_lo(bw.w), bf_hi(bw.w)}; }
;                     const f32x4 v0 = acc[ai][bj][m][0] + b0, v1 = acc[ai][bj][m][1] + b1;
;                     if constexpr (OUT_F32) { const f32x4 snd = odd ? v0 : v1; f32x4 rcv; rcv[0] = dpp_xor1(snd[0]); rcv[1] = dpp_xor1(snd[1]); rcv[2] = dpp_xor1(snd[2]); rcv[3] = dpp_xor1(snd[3]);
;                         *(f32x4*)(H + offp + bj * HALF) = odd ? rcv : v0; *(f32x4*)(H + offp + DM + bj * HALF) = odd ? v1 : rcv; }
;                     else { u32x4 w; w.x = cvt_pk_bf16(v0[0], v0[1]); w.y = cvt_pk_bf16(v0[2], v0[3]); w.z = cvt_pk_bf16(v1[0], v1[1]); w.w = cvt_pk_bf16(v1[2], v1[3]);
;                         *(u32x4*)(HB + off + bj * HALF) = w; }
;                     s += (v0[0] * v0[0] + v0[1] * v0[1]) + (v0[2] * v0[2] + v0[3] * v0[3]) + (v1[0] * v1[0] + v1[1] * v1[1]) + (v1[2] * v1[2] + v1[3] * v1[3]);
;                 }
;                 s += __shfl_xor(s, 16); s += __shfl_xor(s, 32);
;                 if (fq == 0) unsafeAtomicAdd(ssn + row, s);
;             }
.LBB0_2194:
	s_or_b64 exec, exec, s[20:21]
	v_or_b32_e32 v96, 32, v148
	s_waitcnt lgkmcnt(0)
	v_ashrrev_i32_e32 v97, 31, v96
	v_readlane_b32 s20, v254, 25
	v_lshlrev_b64 v[98:99], 12, v[96:97]
	v_readlane_b32 s21, v254, 26
	v_sub_u32_e32 v104, v96, v153
	v_ashrrev_i32_e32 v105, 31, v104
	v_lshl_add_u64 v[98:99], s[20:21], 0, v[98:99]
	v_lshl_add_u64 v[102:103], v[146:147], 1, v[98:99]
	global_load_dwordx4 v[98:101], v[102:103], off
	v_readlane_b32 s20, v254, 7
	v_lshlrev_b64 v[104:105], 13, v[104:105]
	v_readlane_b32 s21, v254, 8
	s_nop 1
	v_lshl_add_u64 v[104:105], s[20:21], 0, v[104:105]
	v_lshl_add_u64 v[104:105], v[150:151], 2, v[104:105]
	v_add_co_u32_e32 v106, vcc, s35, v104
	v_readlane_b32 s22, v254, 9
	s_nop 0
	v_addc_co_u32_e32 v107, vcc, 0, v105, vcc
	v_readlane_b32 s23, v254, 10
	s_waitcnt vmcnt(0)
	v_lshlrev_b32_e32 v108, 16, v98
	v_and_b32_e32 v109, 0xffff0000, v98
	v_lshlrev_b32_e32 v98, 16, v99
	v_and_b32_e32 v99, 0xffff0000, v99
	v_lshlrev_b32_e32 v110, 16, v100
	v_and_b32_e32 v111, 0xffff0000, v100
	v_lshlrev_b32_e32 v100, 16, v101
	v_and_b32_e32 v101, 0xffff0000, v101
	v_pk_add_f32 v[108:109], v[92:93], v[108:109]
	v_pk_add_f32 v[98:99], v[94:95], v[98:99]
	v_pk_add_f32 v[110:111], v[88:89], v[110:111]
	v_pk_add_f32 v[100:101], v[90:91], v[100:101]
	v_cndmask_b32_e64 v90, v109, v111, s[0:1]
	v_cndmask_b32_e64 v88, v99, v101, s[0:1]
	v_cndmask_b32_e64 v89, v98, v100, s[0:1]
	v_cndmask_b32_e64 v91, v108, v110, s[0:1]
	v_mov_b32_dpp v113, v90 quad_perm:[1,0,3,2] row_mask:0xf bank_mask:0xf
	v_mov_b32_dpp v114, v89 quad_perm:[1,0,3,2] row_mask:0xf bank_mask:0xf
	v_mov_b32_dpp v112, v91 quad_perm:[1,0,3,2] row_mask:0xf bank_mask:0xf
	v_mov_b32_dpp v115, v88 quad_perm:[1,0,3,2] row_mask:0xf bank_mask:0xf
	v_cndmask_b32_e64 v91, v115, v99, s[0:1]
	v_cndmask_b32_e64 v90, v114, v98, s[0:1]
	v_cndmask_b32_e64 v89, v113, v109, s[0:1]
	v_cndmask_b32_e64 v88, v112, v108, s[0:1]
	v_cndmask_b32_e64 v95, v101, v115, s[0:1]
	v_cndmask_b32_e64 v94, v100, v114, s[0:1]
	v_cndmask_b32_e64 v93, v111, v113, s[0:1]
	v_cndmask_b32_e64 v92, v110, v112, s[0:1]
	global_store_dwordx4 v[104:105], v[88:91], off
	global_store_dwordx4 v[106:107], v[92:95], off
	global_load_dwordx4 v[88:91], v[102:103], off offset:256
	s_nop 1
	v_mul_f32_e32 v92, v109, v109
	v_mul_f32_e32 v93, v99, v99
	v_mul_f32_e32 v94, v111, v111
	v_fmac_f32_e32 v92, v108, v108
	v_fmac_f32_e32 v93, v98, v98
	v_mul_f32_e32 v95, v101, v101
	v_fmac_f32_e32 v94, v110, v110
	v_add_f32_e32 v92, v92, v93
	v_fmac_f32_e32 v95, v100, v100
	v_add_f32_e32 v92, v94, v92
	v_add_f32_e32 v98, v95, v92
	s_waitcnt vmcnt(0)
	v_lshlrev_b32_e32 v92, 16, v88
	v_and_b32_e32 v93, 0xffff0000, v88
	v_lshlrev_b32_e32 v88, 16, v89
	v_and_b32_e32 v89, 0xffff0000, v89
	v_lshlrev_b32_e32 v94, 16, v90
	v_and_b32_e32 v95, 0xffff0000, v90
	v_lshlrev_b32_e32 v90, 16, v91
	v_and_b32_e32 v91, 0xffff0000, v91
	v_pk_add_f32 v[84:85], v[84:85], v[92:93]
	v_pk_add_f32 v[86:87], v[86:87], v[88:89]
	v_pk_add_f32 v[88:89], v[80:81], v[94:95]
	v_pk_add_f32 v[90:91], v[82:83], v[90:91]
	v_mul_f32_e32 v92, v85, v85
	v_mul_f32_e32 v93, v87, v87
	v_cndmask_b32_e64 v80, v87, v91, s[0:1]
	v_mul_f32_e32 v94, v89, v89
	v_fmac_f32_e32 v92, v84, v84
	v_fmac_f32_e32 v93, v86, v86
	v_mul_f32_e32 v95, v91, v91
	v_mov_b32_dpp v113, v80 quad_perm:[1,0,3,2] row_mask:0xf bank_mask:0xf
	v_fmac_f32_e32 v94, v88, v88
	v_add_f32_e32 v80, v92, v93
	v_cndmask_b32_e64 v81, v86, v90, s[0:1]
	v_add_f32_e32 v80, v94, v80
	v_fmac_f32_e32 v95, v90, v90
	v_cndmask_b32_e64 v82, v85, v89, s[0:1]
	v_mov_b32_dpp v112, v81 quad_perm:[1,0,3,2] row_mask:0xf bank_mask:0xf
	v_add_f32_e32 v80, v95, v80
	v_cndmask_b32_e64 v83, v84, v88, s[0:1]
	v_mov_b32_dpp v103, v82 quad_perm:[1,0,3,2] row_mask:0xf bank_mask:0xf
	v_cndmask_b32_e64 v82, v112, v86, s[0:1]
	v_add_f32_e32 v86, v98, v80
	v_mov_b32_dpp v102, v83 quad_perm:[1,0,3,2] row_mask:0xf bank_mask:0xf
	v_cndmask_b32_e64 v83, v113, v87, s[0:1]
	ds_bpermute_b32 v87, v121, v86
	v_cndmask_b32_e64 v81, v103, v85, s[0:1]
	v_cndmask_b32_e64 v80, v102, v84, s[0:1]
	global_store_dwordx4 v[104:105], v[80:83], off offset:512
	v_cndmask_b32_e64 v85, v91, v113, s[0:1]
	v_cndmask_b32_e64 v84, v90, v112, s[0:1]
	s_waitcnt lgkmcnt(0)
	v_add_f32_e32 v80, v86, v87
	ds_bpermute_b32 v81, v120, v80
	v_cndmask_b32_e64 v83, v89, v103, s[0:1]
	v_cndmask_b32_e64 v82, v88, v102, s[0:1]
	global_store_dwordx4 v[106:107], v[82:85], off offset:512
	s_and_saveexec_b64 s[20:21], s[2:3]
	s_cbranch_execz .LBB0_2196
	v_lshl_add_u64 v[82:83], v[96:97], 2, s[12:13]
	s_waitcnt lgkmcnt(0)
	v_add_f32_e32 v80, v80, v81
	global_atomic_add_f32 v[82:83], v80, off
;     __device__ __forceinline__ void operator()(const f32x4 (&acc)[2][2][4][2], const Unit& u, int wr, int wc, int fr, int fq) const {
;     ...
;         const int row0 = u.pm * BM + wr * 64 + fr, col0 = u.pn * BM + wc * 32 + 8 * fq; const bool odd = (fr & 1) != 0;
; #pragma unroll
;         for (int ai = 0; ai < 2; ++ai)
; #pragma unroll
;             for (int m = 0; m < 4; ++m) {
;                 const int row = row0 + ai * HALF + m * 16; float s = 0.f;
;                 const size_t off = (size_t)row * DM + col0;
;                 const size_t offp = (size_t)(row - (odd ? 1 : 0)) * DM + col0 + (odd ? 4 : 0);
; #pragma unroll
;                 for (int bj = 0; bj < 2; ++bj) {
;                     f32x4 b0, b1;
;                     if constexpr (BASE_F32) { const f32x4 la = *(const GAS f32x4*)(basef + offp + bj * HALF), lb = *(const GAS f32x4*)(basef + offp + DM + bj * HALF);
;                         const f32x4 snd = odd ? la : lb; f32x4 rcv; rcv[0] = dpp_xor1(snd[0]); rcv[1] = dpp_xor1(snd[1]); rcv[2] = dpp_xor1(snd[2]); rcv[3] = dpp_xor1(snd[3]);
;                         b0 = odd ? rcv : la; b1 = odd ? lb : rcv; }
;                     else { const u32x4 bw = *(const u32x4*)(baseb + off + bj * HALF);
;                         b0 = (f32x4){bf_lo(bw.x), bf_hi(bw.x), bf_lo(bw.y), bf_hi(bw.y)}; b1 = (f32x4){bf_lo(bw.z), bf_hi(bw.z), bf_lo(bw.w), bf_hi(bw.w)}; }
;                     const f32x4 v0 = acc[ai][bj][m][0] + b0, v1 = acc[ai][bj][m][1] + b1;
;                     if constexpr (OUT_F32) { const f32x4 snd = odd ? v0 : v1; f32x4 rcv; rcv[0] = dpp_xor1(snd[0]); rcv[1] = dpp_xor1(snd[1]); rcv[2] = dpp_xor1(snd[2]); rcv[3] = dpp_xor1(snd[3]);
;                         *(f32x4*)(H + offp + bj * HALF) = odd ? rcv : v0; *(f32x4*)(H + offp + DM + bj * HALF) = odd ? v1 : rcv; }
;                     else { u32x4 w; w.x = cvt_pk_bf16(v0[0], v0[1]); w.y = cvt_pk_bf16(v0[2], v0[3]); w.z = cvt_pk_bf16(v1[0], v1[1]); w.w = cvt_pk_bf16(v1[2], v1[3]);
;                         *(u32x4*)(HB + off + bj * HALF) = w; }
;                     s += (v0[0] * v0[0] + v0[1] * v0[1]) + (v0[2] * v0[2] + v0[3] * v0[3]) + (v1[0] * v1[0] + v1[1] * v1[1]) + (v1[2] * v1[2] + v1[3] * v1[3]);
;                 }
;                 s += __shfl_xor(s, 16); s += __shfl_xor(s, 32);
;                 if (fq == 0) unsafeAtomicAdd(ssn + row, s);
;             }
.LBB0_2196:
	s_or_b64 exec, exec, s[20:21]
	v_or_b32_e32 v80, 48, v148
	s_waitcnt lgkmcnt(0)
	v_ashrrev_i32_e32 v81, 31, v80
	v_readlane_b32 s20, v254, 25
	v_lshlrev_b64 v[82:83], 12, v[80:81]
	v_readlane_b32 s21, v254, 26
	v_sub_u32_e32 v88, v80, v153
	v_ashrrev_i32_e32 v89, 31, v88
	v_lshl_add_u64 v[82:83], s[20:21], 0, v[82:83]
	v_lshl_add_u64 v[86:87], v[146:147], 1, v[82:83]
	global_load_dwordx4 v[82:85], v[86:87], off
	v_readlane_b32 s20, v254, 7
	v_lshlrev_b64 v[88:89], 13, v[88:89]
	v_readlane_b32 s21, v254, 8
	s_nop 1
	v_lshl_add_u64 v[88:89], s[20:21], 0, v[88:89]
	v_lshl_add_u64 v[88:89], v[150:151], 2, v[88:89]
	v_add_co_u32_e32 v90, vcc, s35, v88
	v_readlane_b32 s22, v254, 9
	s_nop 0
	v_addc_co_u32_e32 v91, vcc, 0, v89, vcc
	v_readlane_b32 s23, v254, 10
	s_waitcnt vmcnt(0)
	v_lshlrev_b32_e32 v92, 16, v82
	v_and_b32_e32 v93, 0xffff0000, v82
	v_lshlrev_b32_e32 v82, 16, v83
	v_and_b32_e32 v83, 0xffff0000, v83
	v_lshlrev_b32_e32 v94, 16, v84
	v_and_b32_e32 v95, 0xffff0000, v84
	v_lshlrev_b32_e32 v84, 16, v85
	v_and_b32_e32 v85, 0xffff0000, v85
	v_pk_add_f32 v[92:93], v[76:77], v[92:93]
	v_pk_add_f32 v[82:83], v[78:79], v[82:83]
	v_pk_add_f32 v[94:95], v[72:73], v[94:95]
	v_pk_add_f32 v[84:85], v[74:75], v[84:85]
	v_cndmask_b32_e64 v74, v93, v95, s[0:1]
	v_cndmask_b32_e64 v72, v83, v85, s[0:1]
	v_cndmask_b32_e64 v73, v82, v84, s[0:1]
	v_cndmask_b32_e64 v75, v92, v94, s[0:1]
	v_mov_b32_dpp v97, v74 quad_perm:[1,0,3,2] row_mask:0xf bank_mask:0xf
	v_mov_b32_dpp v98, v73 quad_perm:[1,0,3,2] row_mask:0xf bank_mask:0xf
	v_mov_b32_dpp v96, v75 quad_perm:[1,0,3,2] row_mask:0xf bank_mask:0xf
	v_mov_b32_dpp v99, v72 quad_perm:[1,0,3,2] row_mask:0xf bank_mask:0xf
	v_cndmask_b32_e64 v75, v99, v83, s[0:1]
	v_cndmask_b32_e64 v74, v98, v82, s[0:1]
	v_cndmask_b32_e64 v73, v97, v93, s[0:1]
	v_cndmask_b32_e64 v72, v96, v92, s[0:1]
	v_cndmask_b32_e64 v79, v85, v99, s[0:1]
	v_cndmask_b32_e64 v78, v84, v98, s[0:1]
	v_cndmask_b32_e64 v77, v95, v97, s[0:1]
	v_cndmask_b32_e64 v76, v94, v96, s[0:1]
	global_store_dwordx4 v[88:89], v[72:75], off
	global_store_dwordx4 v[90:91], v[76:79], off
	global_load_dwordx4 v[72:75], v[86:87], off offset:256
	s_nop 1
	v_mul_f32_e32 v76, v93, v93
	v_mul_f32_e32 v77, v83, v83
	v_mul_f32_e32 v78, v95, v95
	v_fmac_f32_e32 v76, v92, v92
	v_fmac_f32_e32 v77, v82, v82
	v_mul_f32_e32 v79, v85, v85
	v_fmac_f32_e32 v78, v94, v94
	v_add_f32_e32 v76, v76, v77
	v_fmac_f32_e32 v79, v84, v84
	v_add_f32_e32 v76, v78, v76
	v_add_f32_e32 v82, v79, v76
	s_waitcnt vmcnt(0)
	v_lshlrev_b32_e32 v76, 16, v72
	v_and_b32_e32 v77, 0xffff0000, v72
	v_lshlrev_b32_e32 v72, 16, v73
	v_and_b32_e32 v73, 0xffff0000, v73
	v_lshlrev_b32_e32 v78, 16, v74
	v_and_b32_e32 v79, 0xffff0000, v74
	v_lshlrev_b32_e32 v74, 16, v75
	v_and_b32_e32 v75, 0xffff0000, v75
	v_pk_add_f32 v[68:69], v[68:69], v[76:77]
	v_pk_add_f32 v[70:71], v[70:71], v[72:73]
	v_pk_add_f32 v[72:73], v[64:65], v[78:79]
	v_pk_add_f32 v[74:75], v[66:67], v[74:75]
	v_mul_f32_e32 v76, v69, v69
	v_mul_f32_e32 v77, v71, v71
	v_cndmask_b32_e64 v64, v71, v75, s[0:1]
	v_mul_f32_e32 v78, v73, v73
	v_fmac_f32_e32 v76, v68, v68
	v_fmac_f32_e32 v77, v70, v70
	v_mul_f32_e32 v79, v75, v75
	v_mov_b32_dpp v97, v64 quad_perm:[1,0,3,2] row_mask:0xf bank_mask:0xf
	v_fmac_f32_e32 v78, v72, v72
	v_add_f32_e32 v64, v76, v77
	v_cndmask_b32_e64 v65, v70, v74, s[0:1]
	v_add_f32_e32 v64, v78, v64
	v_fmac_f32_e32 v79, v74, v74
	v_cndmask_b32_e64 v66, v69, v73, s[0:1]
	v_mov_b32_dpp v96, v65 quad_perm:[1,0,3,2] row_mask:0xf bank_mask:0xf
	v_add_f32_e32 v64, v79, v64
	v_cndmask_b32_e64 v67, v68, v72, s[0:1]
	v_mov_b32_dpp v87, v66 quad_perm:[1,0,3,2] row_mask:0xf bank_mask:0xf
	v_cndmask_b32_e64 v66, v96, v70, s[0:1]
	v_add_f32_e32 v70, v82, v64
	v_mov_b32_dpp v86, v67 quad_perm:[1,0,3,2] row_mask:0xf bank_mask:0xf
	v_cndmask_b32_e64 v67, v97, v71, s[0:1]
	ds_bpermute_b32 v71, v121, v70
	v_cndmask_b32_e64 v65, v87, v69, s[0:1]
	v_cndmask_b32_e64 v64, v86, v68, s[0:1]
	global_store_dwordx4 v[88:89], v[64:67], off offset:512
	v_cndmask_b32_e64 v69, v75, v97, s[0:1]
	v_cndmask_b32_e64 v68, v74, v96, s[0:1]
	s_waitcnt lgkmcnt(0)
	v_add_f32_e32 v64, v70, v71
	ds_bpermute_b32 v65, v120, v64
	v_cndmask_b32_e64 v67, v73, v87, s[0:1]
	v_cndmask_b32_e64 v66, v72, v86, s[0:1]
	global_store_dwordx4 v[90:91], v[66:69], off offset:512
	s_and_saveexec_b64 s[20:21], s[2:3]
	s_cbranch_execz .LBB0_2198
	v_lshl_add_u64 v[66:67], v[80:81], 2, s[12:13]
	s_waitcnt lgkmcnt(0)
	v_add_f32_e32 v64, v64, v65
	global_atomic_add_f32 v[66:67], v64, off
;     __device__ __forceinline__ void operator()(const f32x4 (&acc)[2][2][4][2], const Unit& u, int wr, int wc, int fr, int fq) const {
;     ...
;         const int row0 = u.pm * BM + wr * 64 + fr, col0 = u.pn * BM + wc * 32 + 8 * fq; const bool odd = (fr & 1) != 0;
; #pragma unroll
;         for (int ai = 0; ai < 2; ++ai)
; #pragma unroll
;             for (int m = 0; m < 4; ++m) {
;                 const int row = row0 + ai * HALF + m * 16; float s = 0.f;
;                 const size_t off = (size_t)row * DM + col0;
;                 const size_t offp = (size_t)(row - (odd ? 1 : 0)) * DM + col0 + (odd ? 4 : 0);
; #pragma unroll
;                 for (int bj = 0; bj < 2; ++bj) {
;                     f32x4 b0, b1;
;                     if constexpr (BASE_F32) { const f32x4 la = *(const GAS f32x4*)(basef + offp + bj * HALF), lb = *(const GAS f32x4*)(basef + offp + DM + bj * HALF);
;                         const f32x4 snd = odd ? la : lb; f32x4 rcv; rcv[0] = dpp_xor1(snd[0]); rcv[1] = dpp_xor1(snd[1]); rcv[2] = dpp_xor1(snd[2]); rcv[3] = dpp_xor1(snd[3]);
;                         b0 = odd ? rcv : la; b1 = odd ? lb : rcv; }
;                     else { const u32x4 bw = *(const u32x4*)(baseb + off + bj * HALF);
;                         b0 = (f32x4){bf_lo(bw.x), bf_hi(bw.x), bf_lo(bw.y), bf_hi(bw.y)}; b1 = (f32x4){bf_lo(bw.z), bf_hi(bw.z), bf_lo(bw.w), bf_hi(bw.w)}; }
;                     const f32x4 v0 = acc[ai][bj][m][0] + b0, v1 = acc[ai][bj][m][1] + b1;
;                     if constexpr (OUT_F32) { const f32x4 snd = odd ? v0 : v1; f32x4 rcv; rcv[0] = dpp_xor1(snd[0]); rcv[1] = dpp_xor1(snd[1]); rcv[2] = dpp_xor1(snd[2]); rcv[3] = dpp_xor1(snd[3]);
;                         *(f32x4*)(H + offp + bj * HALF) = odd ? rcv : v0; *(f32x4*)(H + offp + DM + bj * HALF) = odd ? v1 : rcv; }
;                     else { u32x4 w; w.x = cvt_pk_bf16(v0[0], v0[1]); w.y = cvt_pk_bf16(v0[2], v0[3]); w.z = cvt_pk_bf16(v1[0], v1[1]); w.w = cvt_pk_bf16(v1[2], v1[3]);
;                         *(u32x4*)(HB + off + bj * HALF) = w; }
;                     s += (v0[0] * v0[0] + v0[1] * v0[1]) + (v0[2] * v0[2] + v0[3] * v0[3]) + (v1[0] * v1[0] + v1[1] * v1[1]) + (v1[2] * v1[2] + v1[3] * v1[3]);
;                 }
;                 s += __shfl_xor(s, 16); s += __shfl_xor(s, 32);
;                 if (fq == 0) unsafeAtomicAdd(ssn + row, s);
;             }
.LBB0_2198:
	s_or_b64 exec, exec, s[20:21]
	v_add_u32_e32 v64, 0x80, v148
	s_waitcnt lgkmcnt(0)
	v_ashrrev_i32_e32 v65, 31, v64
	v_readlane_b32 s20, v254, 25
	v_lshlrev_b64 v[66:67], 12, v[64:65]
	v_readlane_b32 s21, v254, 26
	v_sub_u32_e32 v72, v64, v153
	v_ashrrev_i32_e32 v73, 31, v72
	v_lshl_add_u64 v[66:67], s[20:21], 0, v[66:67]
	v_lshl_add_u64 v[70:71], v[146:147], 1, v[66:67]
	global_load_dwordx4 v[66:69], v[70:71], off
	v_readlane_b32 s20, v254, 7
	v_lshlrev_b64 v[72:73], 13, v[72:73]
	v_readlane_b32 s21, v254, 8
	s_nop 1
	v_lshl_add_u64 v[72:73], s[20:21], 0, v[72:73]
	v_lshl_add_u64 v[72:73], v[150:151], 2, v[72:73]
	v_add_co_u32_e32 v74, vcc, s35, v72
	v_readlane_b32 s22, v254, 9
	s_nop 0
	v_addc_co_u32_e32 v75, vcc, 0, v73, vcc
	v_readlane_b32 s23, v254, 10
	s_waitcnt vmcnt(0)
	v_lshlrev_b32_e32 v76, 16, v66
	v_and_b32_e32 v77, 0xffff0000, v66
	v_lshlrev_b32_e32 v66, 16, v67
	v_and_b32_e32 v67, 0xffff0000, v67
	v_lshlrev_b32_e32 v78, 16, v68
	v_and_b32_e32 v79, 0xffff0000, v68
	v_lshlrev_b32_e32 v68, 16, v69
	v_and_b32_e32 v69, 0xffff0000, v69
	v_pk_add_f32 v[76:77], v[60:61], v[76:77]
	v_pk_add_f32 v[66:67], v[62:63], v[66:67]
	v_pk_add_f32 v[78:79], v[56:57], v[78:79]
	v_pk_add_f32 v[68:69], v[58:59], v[68:69]
	v_cndmask_b32_e64 v58, v77, v79, s[0:1]
	v_cndmask_b32_e64 v56, v67, v69, s[0:1]
	v_cndmask_b32_e64 v57, v66, v68, s[0:1]
	v_cndmask_b32_e64 v59, v76, v78, s[0:1]
	v_mov_b32_dpp v81, v58 quad_perm:[1,0,3,2] row_mask:0xf bank_mask:0xf
	v_mov_b32_dpp v82, v57 quad_perm:[1,0,3,2] row_mask:0xf bank_mask:0xf
	v_mov_b32_dpp v80, v59 quad_perm:[1,0,3,2] row_mask:0xf bank_mask:0xf
	v_mov_b32_dpp v83, v56 quad_perm:[1,0,3,2] row_mask:0xf bank_mask:0xf
	v_cndmask_b32_e64 v59, v83, v67, s[0:1]
	v_cndmask_b32_e64 v58, v82, v66, s[0:1]
	v_cndmask_b32_e64 v57, v81, v77, s[0:1]
	v_cndmask_b32_e64 v56, v80, v76, s[0:1]
	v_cndmask_b32_e64 v63, v69, v83, s[0:1]
	v_cndmask_b32_e64 v62, v68, v82, s[0:1]
	v_cndmask_b32_e64 v61, v79, v81, s[0:1]
	v_cndmask_b32_e64 v60, v78, v80, s[0:1]
	global_store_dwordx4 v[72:73], v[56:59], off
	global_store_dwordx4 v[74:75], v[60:63], off
	global_load_dwordx4 v[56:59], v[70:71], off offset:256
	s_nop 1
	v_mul_f32_e32 v60, v77, v77
	v_mul_f32_e32 v61, v67, v67
	v_mul_f32_e32 v62, v79, v79
	v_fmac_f32_e32 v60, v76, v76
	v_fmac_f32_e32 v61, v66, v66
	v_mul_f32_e32 v63, v69, v69
	v_fmac_f32_e32 v62, v78, v78
	v_add_f32_e32 v60, v60, v61
	v_fmac_f32_e32 v63, v68, v68
	v_add_f32_e32 v60, v62, v60
	v_add_f32_e32 v66, v63, v60
	s_waitcnt vmcnt(0)
	v_lshlrev_b32_e32 v60, 16, v56
	v_and_b32_e32 v61, 0xffff0000, v56
	v_lshlrev_b32_e32 v56, 16, v57
	v_and_b32_e32 v57, 0xffff0000, v57
	v_lshlrev_b32_e32 v62, 16, v58
	v_and_b32_e32 v63, 0xffff0000, v58
	v_lshlrev_b32_e32 v58, 16, v59
	v_and_b32_e32 v59, 0xffff0000, v59
	v_pk_add_f32 v[52:53], v[52:53], v[60:61]
	v_pk_add_f32 v[54:55], v[54:55], v[56:57]
	v_pk_add_f32 v[56:57], v[48:49], v[62:63]
	v_pk_add_f32 v[58:59], v[50:51], v[58:59]
	v_mul_f32_e32 v60, v53, v53
	v_mul_f32_e32 v61, v55, v55
	v_cndmask_b32_e64 v48, v55, v59, s[0:1]
	v_mul_f32_e32 v62, v57, v57
	v_fmac_f32_e32 v60, v52, v52
	v_fmac_f32_e32 v61, v54, v54
	v_mul_f32_e32 v63, v59, v59
	v_mov_b32_dpp v81, v48 quad_perm:[1,0,3,2] row_mask:0xf bank_mask:0xf
	v_fmac_f32_e32 v62, v56, v56
	v_add_f32_e32 v48, v60, v61
	v_cndmask_b32_e64 v49, v54, v58, s[0:1]
	v_add_f32_e32 v48, v62, v48
	v_fmac_f32_e32 v63, v58, v58
	v_cndmask_b32_e64 v50, v53, v57, s[0:1]
	v_mov_b32_dpp v80, v49 quad_perm:[1,0,3,2] row_mask:0xf bank_mask:0xf
	v_add_f32_e32 v48, v63, v48
	v_cndmask_b32_e64 v51, v52, v56, s[0:1]
	v_mov_b32_dpp v71, v50 quad_perm:[1,0,3,2] row_mask:0xf bank_mask:0xf
	v_cndmask_b32_e64 v50, v80, v54, s[0:1]
	v_add_f32_e32 v54, v66, v48
	v_mov_b32_dpp v70, v51 quad_perm:[1,0,3,2] row_mask:0xf bank_mask:0xf
	v_cndmask_b32_e64 v51, v81, v55, s[0:1]
	ds_bpermute_b32 v55, v121, v54
	v_cndmask_b32_e64 v49, v71, v53, s[0:1]
	v_cndmask_b32_e64 v48, v70, v52, s[0:1]
	global_store_dwordx4 v[72:73], v[48:51], off offset:512
	v_cndmask_b32_e64 v53, v59, v81, s[0:1]
	v_cndmask_b32_e64 v52, v58, v80, s[0:1]
	s_waitcnt lgkmcnt(0)
	v_add_f32_e32 v48, v54, v55
	ds_bpermute_b32 v49, v120, v48
	v_cndmask_b32_e64 v51, v57, v71, s[0:1]
	v_cndmask_b32_e64 v50, v56, v70, s[0:1]
	global_store_dwordx4 v[74:75], v[50:53], off offset:512
	s_and_saveexec_b64 s[20:21], s[2:3]
	s_cbranch_execz .LBB0_2200
	v_lshl_add_u64 v[50:51], v[64:65], 2, s[12:13]
	s_waitcnt lgkmcnt(0)
	v_add_f32_e32 v48, v48, v49
	global_atomic_add_f32 v[50:51], v48, off
;     __device__ __forceinline__ void operator()(const f32x4 (&acc)[2][2][4][2], const Unit& u, int wr, int wc, int fr, int fq) const {
;     ...
;         const int row0 = u.pm * BM + wr * 64 + fr, col0 = u.pn * BM + wc * 32 + 8 * fq; const bool odd = (fr & 1) != 0;
; #pragma unroll
;         for (int ai = 0; ai < 2; ++ai)
; #pragma unroll
;             for (int m = 0; m < 4; ++m) {
;                 const int row = row0 + ai * HALF + m * 16; float s = 0.f;
;                 const size_t off = (size_t)row * DM + col0;
;                 const size_t offp = (size_t)(row - (odd ? 1 : 0)) * DM + col0 + (odd ? 4 : 0);
; #pragma unroll
;                 for (int bj = 0; bj < 2; ++bj) {
;                     f32x4 b0, b1;
;                     if constexpr (BASE_F32) { const f32x4 la = *(const GAS f32x4*)(basef + offp + bj * HALF), lb = *(const GAS f32x4*)(basef + offp + DM + bj * HALF);
;                         const f32x4 snd = odd ? la : lb; f32x4 rcv; rcv[0] = dpp_xor1(snd[0]); rcv[1] = dpp_xor1(snd[1]); rcv[2] = dpp_xor1(snd[2]); rcv[3] = dpp_xor1(snd[3]);
;                         b0 = odd ? rcv : la; b1 = odd ? lb : rcv; }
;                     else { const u32x4 bw = *(const u32x4*)(baseb + off + bj * HALF);
;                         b0 = (f32x4){bf_lo(bw.x), bf_hi(bw.x), bf_lo(bw.y), bf_hi(bw.y)}; b1 = (f32x4){bf_lo(bw.z), bf_hi(bw.z), bf_lo(bw.w), bf_hi(bw.w)}; }
;                     const f32x4 v0 = acc[ai][bj][m][0] + b0, v1 = acc[ai][bj][m][1] + b1;
;                     if constexpr (OUT_F32) { const f32x4 snd = odd ? v0 : v1; f32x4 rcv; rcv[0] = dpp_xor1(snd[0]); rcv[1] = dpp_xor1(snd[1]); rcv[2] = dpp_xor1(snd[2]); rcv[3] = dpp_xor1(snd[3]);
;                         *(f32x4*)(H + offp + bj * HALF) = odd ? rcv : v0; *(f32x4*)(H + offp + DM + bj * HALF) = odd ? v1 : rcv; }
;                     else { u32x4 w; w.x = cvt_pk_bf16(v0[0], v0[1]); w.y = cvt_pk_bf16(v0[2], v0[3]); w.z = cvt_pk_bf16(v1[0], v1[1]); w.w = cvt_pk_bf16(v1[2], v1[3]);
;                         *(u32x4*)(HB + off + bj * HALF) = w; }
;                     s += (v0[0] * v0[0] + v0[1] * v0[1]) + (v0[2] * v0[2] + v0[3] * v0[3]) + (v1[0] * v1[0] + v1[1] * v1[1]) + (v1[2] * v1[2] + v1[3] * v1[3]);
;                 }
;                 s += __shfl_xor(s, 16); s += __shfl_xor(s, 32);
;                 if (fq == 0) unsafeAtomicAdd(ssn + row, s);
;             }
.LBB0_2200:
	s_or_b64 exec, exec, s[20:21]
	v_add_u32_e32 v48, 0x90, v148
	s_waitcnt lgkmcnt(0)
	v_ashrrev_i32_e32 v49, 31, v48
	v_readlane_b32 s20, v254, 25
	v_lshlrev_b64 v[50:51], 12, v[48:49]
	v_readlane_b32 s21, v254, 26
	v_sub_u32_e32 v56, v48, v153
	v_ashrrev_i32_e32 v57, 31, v56
	v_lshl_add_u64 v[50:51], s[20:21], 0, v[50:51]
	v_lshl_add_u64 v[54:55], v[146:147], 1, v[50:51]
	global_load_dwordx4 v[50:53], v[54:55], off
	v_readlane_b32 s20, v254, 7
	v_lshlrev_b64 v[56:57], 13, v[56:57]
	v_readlane_b32 s21, v254, 8
	s_nop 1
	v_lshl_add_u64 v[56:57], s[20:21], 0, v[56:57]
	v_lshl_add_u64 v[56:57], v[150:151], 2, v[56:57]
	v_add_co_u32_e32 v58, vcc, s35, v56
	v_readlane_b32 s22, v254, 9
	s_nop 0
	v_addc_co_u32_e32 v59, vcc, 0, v57, vcc
	v_readlane_b32 s23, v254, 10
	s_waitcnt vmcnt(0)
	v_lshlrev_b32_e32 v60, 16, v50
	v_and_b32_e32 v61, 0xffff0000, v50
	v_lshlrev_b32_e32 v50, 16, v51
	v_and_b32_e32 v51, 0xffff0000, v51
	v_lshlrev_b32_e32 v62, 16, v52
	v_and_b32_e32 v63, 0xffff0000, v52
	v_lshlrev_b32_e32 v52, 16, v53
	v_and_b32_e32 v53, 0xffff0000, v53
	v_pk_add_f32 v[60:61], v[44:45], v[60:61]
	v_pk_add_f32 v[50:51], v[46:47], v[50:51]
	v_pk_add_f32 v[62:63], v[40:41], v[62:63]
	v_pk_add_f32 v[52:53], v[42:43], v[52:53]
	v_cndmask_b32_e64 v42, v61, v63, s[0:1]
	v_cndmask_b32_e64 v40, v51, v53, s[0:1]
	v_cndmask_b32_e64 v41, v50, v52, s[0:1]
	v_cndmask_b32_e64 v43, v60, v62, s[0:1]
	v_mov_b32_dpp v65, v42 quad_perm:[1,0,3,2] row_mask:0xf bank_mask:0xf
	v_mov_b32_dpp v66, v41 quad_perm:[1,0,3,2] row_mask:0xf bank_mask:0xf
	v_mov_b32_dpp v64, v43 quad_perm:[1,0,3,2] row_mask:0xf bank_mask:0xf
	v_mov_b32_dpp v67, v40 quad_perm:[1,0,3,2] row_mask:0xf bank_mask:0xf
	v_cndmask_b32_e64 v43, v67, v51, s[0:1]
	v_cndmask_b32_e64 v42, v66, v50, s[0:1]
	v_cndmask_b32_e64 v41, v65, v61, s[0:1]
	v_cndmask_b32_e64 v40, v64, v60, s[0:1]
	v_cndmask_b32_e64 v47, v53, v67, s[0:1]
	v_cndmask_b32_e64 v46, v52, v66, s[0:1]
	v_cndmask_b32_e64 v45, v63, v65, s[0:1]
	v_cndmask_b32_e64 v44, v62, v64, s[0:1]
	global_store_dwordx4 v[56:57], v[40:43], off
	global_store_dwordx4 v[58:59], v[44:47], off
	global_load_dwordx4 v[40:43], v[54:55], off offset:256
	s_nop 1
	v_mul_f32_e32 v44, v61, v61
	v_mul_f32_e32 v45, v51, v51
	v_mul_f32_e32 v46, v63, v63
	v_fmac_f32_e32 v44, v60, v60
	v_fmac_f32_e32 v45, v50, v50
	v_mul_f32_e32 v47, v53, v53
	v_fmac_f32_e32 v46, v62, v62
	v_add_f32_e32 v44, v44, v45
	v_fmac_f32_e32 v47, v52, v52
	v_add_f32_e32 v44, v46, v44
	v_add_f32_e32 v50, v47, v44
	s_waitcnt vmcnt(0)
	v_lshlrev_b32_e32 v44, 16, v40
	v_and_b32_e32 v45, 0xffff0000, v40
	v_lshlrev_b32_e32 v40, 16, v41
	v_and_b32_e32 v41, 0xffff0000, v41
	v_lshlrev_b32_e32 v46, 16, v42
	v_and_b32_e32 v47, 0xffff0000, v42
	v_lshlrev_b32_e32 v42, 16, v43
	v_and_b32_e32 v43, 0xffff0000, v43
	v_pk_add_f32 v[36:37], v[36:37], v[44:45]
	v_pk_add_f32 v[38:39], v[38:39], v[40:41]
	v_pk_add_f32 v[40:41], v[32:33], v[46:47]
	v_pk_add_f32 v[42:43], v[34:35], v[42:43]
	v_mul_f32_e32 v44, v37, v37
	v_mul_f32_e32 v45, v39, v39
	v_cndmask_b32_e64 v32, v39, v43, s[0:1]
	v_mul_f32_e32 v46, v41, v41
	v_fmac_f32_e32 v44, v36, v36
	v_fmac_f32_e32 v45, v38, v38
	v_mul_f32_e32 v47, v43, v43
	v_mov_b32_dpp v65, v32 quad_perm:[1,0,3,2] row_mask:0xf bank_mask:0xf
	v_fmac_f32_e32 v46, v40, v40
	v_add_f32_e32 v32, v44, v45
	v_cndmask_b32_e64 v33, v38, v42, s[0:1]
	v_add_f32_e32 v32, v46, v32
	v_fmac_f32_e32 v47, v42, v42
	v_cndmask_b32_e64 v34, v37, v41, s[0:1]
	v_mov_b32_dpp v64, v33 quad_perm:[1,0,3,2] row_mask:0xf bank_mask:0xf
	v_add_f32_e32 v32, v47, v32
	v_cndmask_b32_e64 v35, v36, v40, s[0:1]
	v_mov_b32_dpp v55, v34 quad_perm:[1,0,3,2] row_mask:0xf bank_mask:0xf
	v_cndmask_b32_e64 v34, v64, v38, s[0:1]
	v_add_f32_e32 v38, v50, v32
	v_mov_b32_dpp v54, v35 quad_perm:[1,0,3,2] row_mask:0xf bank_mask:0xf
	v_cndmask_b32_e64 v35, v65, v39, s[0:1]
	ds_bpermute_b32 v39, v121, v38
	v_cndmask_b32_e64 v33, v55, v37, s[0:1]
	v_cndmask_b32_e64 v32, v54, v36, s[0:1]
	global_store_dwordx4 v[56:57], v[32:35], off offset:512
	v_cndmask_b32_e64 v37, v43, v65, s[0:1]
	v_cndmask_b32_e64 v36, v42, v64, s[0:1]
	s_waitcnt lgkmcnt(0)
	v_add_f32_e32 v32, v38, v39
	ds_bpermute_b32 v33, v120, v32
	v_cndmask_b32_e64 v35, v41, v55, s[0:1]
	v_cndmask_b32_e64 v34, v40, v54, s[0:1]
	global_store_dwordx4 v[58:59], v[34:37], off offset:512
	s_and_saveexec_b64 s[20:21], s[2:3]
	s_cbranch_execz .LBB0_2202
	v_lshl_add_u64 v[34:35], v[48:49], 2, s[12:13]
	s_waitcnt lgkmcnt(0)
	v_add_f32_e32 v32, v32, v33
	global_atomic_add_f32 v[34:35], v32, off
;     __device__ __forceinline__ void operator()(const f32x4 (&acc)[2][2][4][2], const Unit& u, int wr, int wc, int fr, int fq) const {
;     ...
;         const int row0 = u.pm * BM + wr * 64 + fr, col0 = u.pn * BM + wc * 32 + 8 * fq; const bool odd = (fr & 1) != 0;
; #pragma unroll
;         for (int ai = 0; ai < 2; ++ai)
; #pragma unroll
;             for (int m = 0; m < 4; ++m) {
;                 const int row = row0 + ai * HALF + m * 16; float s = 0.f;
;                 const size_t off = (size_t)row * DM + col0;
;                 const size_t offp = (size_t)(row - (odd ? 1 : 0)) * DM + col0 + (odd ? 4 : 0);
; #pragma unroll
;                 for (int bj = 0; bj < 2; ++bj) {
;                     f32x4 b0, b1;
;                     if constexpr (BASE_F32) { const f32x4 la = *(const GAS f32x4*)(basef + offp + bj * HALF), lb = *(const GAS f32x4*)(basef + offp + DM + bj * HALF);
;                         const f32x4 snd = odd ? la : lb; f32x4 rcv; rcv[0] = dpp_xor1(snd[0]); rcv[1] = dpp_xor1(snd[1]); rcv[2] = dpp_xor1(snd[2]); rcv[3] = dpp_xor1(snd[3]);
;                         b0 = odd ? rcv : la; b1 = odd ? lb : rcv; }
;                     else { const u32x4 bw = *(const u32x4*)(baseb + off + bj * HALF);
;                         b0 = (f32x4){bf_lo(bw.x), bf_hi(bw.x), bf_lo(bw.y), bf_hi(bw.y)}; b1 = (f32x4){bf_lo(bw.z), bf_hi(bw.z), bf_lo(bw.w), bf_hi(bw.w)}; }
;                     const f32x4 v0 = acc[ai][bj][m][0] + b0, v1 = acc[ai][bj][m][1] + b1;
;                     if constexpr (OUT_F32) { const f32x4 snd = odd ? v0 : v1; f32x4 rcv; rcv[0] = dpp_xor1(snd[0]); rcv[1] = dpp_xor1(snd[1]); rcv[2] = dpp_xor1(snd[2]); rcv[3] = dpp_xor1(snd[3]);
;                         *(f32x4*)(H + offp + bj * HALF) = odd ? rcv : v0; *(f32x4*)(H + offp + DM + bj * HALF) = odd ? v1 : rcv; }
;                     else { u32x4 w; w.x = cvt_pk_bf16(v0[0], v0[1]); w.y = cvt_pk_bf16(v0[2], v0[3]); w.z = cvt_pk_bf16(v1[0], v1[1]); w.w = cvt_pk_bf16(v1[2], v1[3]);
;                         *(u32x4*)(HB + off + bj * HALF) = w; }
;                     s += (v0[0] * v0[0] + v0[1] * v0[1]) + (v0[2] * v0[2] + v0[3] * v0[3]) + (v1[0] * v1[0] + v1[1] * v1[1]) + (v1[2] * v1[2] + v1[3] * v1[3]);
;                 }
;                 s += __shfl_xor(s, 16); s += __shfl_xor(s, 32);
;                 if (fq == 0) unsafeAtomicAdd(ssn + row, s);
;             }
.LBB0_2202:
	s_or_b64 exec, exec, s[20:21]
	v_add_u32_e32 v32, 0xa0, v148
	s_waitcnt lgkmcnt(0)
	v_ashrrev_i32_e32 v33, 31, v32
	v_readlane_b32 s20, v254, 25
	v_lshlrev_b64 v[34:35], 12, v[32:33]
	v_readlane_b32 s21, v254, 26
	v_sub_u32_e32 v40, v32, v153
	v_ashrrev_i32_e32 v41, 31, v40
	v_lshl_add_u64 v[34:35], s[20:21], 0, v[34:35]
	v_lshl_add_u64 v[38:39], v[146:147], 1, v[34:35]
	global_load_dwordx4 v[34:37], v[38:39], off
	v_readlane_b32 s20, v254, 7
	v_lshlrev_b64 v[40:41], 13, v[40:41]
	v_readlane_b32 s21, v254, 8
	s_nop 1
	v_lshl_add_u64 v[40:41], s[20:21], 0, v[40:41]
	v_lshl_add_u64 v[40:41], v[150:151], 2, v[40:41]
	v_add_co_u32_e32 v42, vcc, s35, v40
	v_readlane_b32 s22, v254, 9
	s_nop 0
	v_addc_co_u32_e32 v43, vcc, 0, v41, vcc
	v_readlane_b32 s23, v254, 10
	s_waitcnt vmcnt(0)
	v_lshlrev_b32_e32 v44, 16, v34
	v_and_b32_e32 v45, 0xffff0000, v34
	v_lshlrev_b32_e32 v34, 16, v35
	v_and_b32_e32 v35, 0xffff0000, v35
	v_lshlrev_b32_e32 v46, 16, v36
	v_and_b32_e32 v47, 0xffff0000, v36
	v_lshlrev_b32_e32 v36, 16, v37
	v_and_b32_e32 v37, 0xffff0000, v37
	v_pk_add_f32 v[44:45], v[28:29], v[44:45]
	v_pk_add_f32 v[34:35], v[30:31], v[34:35]
	v_pk_add_f32 v[46:47], v[24:25], v[46:47]
	v_pk_add_f32 v[36:37], v[26:27], v[36:37]
	v_cndmask_b32_e64 v26, v45, v47, s[0:1]
	v_cndmask_b32_e64 v24, v35, v37, s[0:1]
	v_cndmask_b32_e64 v25, v34, v36, s[0:1]
	v_cndmask_b32_e64 v27, v44, v46, s[0:1]
	v_mov_b32_dpp v49, v26 quad_perm:[1,0,3,2] row_mask:0xf bank_mask:0xf
	v_mov_b32_dpp v50, v25 quad_perm:[1,0,3,2] row_mask:0xf bank_mask:0xf
	v_mov_b32_dpp v48, v27 quad_perm:[1,0,3,2] row_mask:0xf bank_mask:0xf
	v_mov_b32_dpp v51, v24 quad_perm:[1,0,3,2] row_mask:0xf bank_mask:0xf
	v_cndmask_b32_e64 v27, v51, v35, s[0:1]
	v_cndmask_b32_e64 v26, v50, v34, s[0:1]
	v_cndmask_b32_e64 v25, v49, v45, s[0:1]
	v_cndmask_b32_e64 v24, v48, v44, s[0:1]
	v_cndmask_b32_e64 v31, v37, v51, s[0:1]
	v_cndmask_b32_e64 v30, v36, v50, s[0:1]
	v_cndmask_b32_e64 v29, v47, v49, s[0:1]
	v_cndmask_b32_e64 v28, v46, v48, s[0:1]
	global_store_dwordx4 v[40:41], v[24:27], off
	global_store_dwordx4 v[42:43], v[28:31], off
	global_load_dwordx4 v[24:27], v[38:39], off offset:256
	s_nop 1
	v_mul_f32_e32 v28, v45, v45
	v_mul_f32_e32 v29, v35, v35
	v_mul_f32_e32 v30, v47, v47
	v_fmac_f32_e32 v28, v44, v44
	v_fmac_f32_e32 v29, v34, v34
	v_mul_f32_e32 v31, v37, v37
	v_fmac_f32_e32 v30, v46, v46
	v_add_f32_e32 v28, v28, v29
	v_fmac_f32_e32 v31, v36, v36
	v_add_f32_e32 v28, v30, v28
	v_add_f32_e32 v34, v31, v28
	s_waitcnt vmcnt(0)
	v_lshlrev_b32_e32 v28, 16, v24
	v_and_b32_e32 v29, 0xffff0000, v24
	v_lshlrev_b32_e32 v24, 16, v25
	v_and_b32_e32 v25, 0xffff0000, v25
	v_lshlrev_b32_e32 v30, 16, v26
	v_and_b32_e32 v31, 0xffff0000, v26
	v_lshlrev_b32_e32 v26, 16, v27
	v_and_b32_e32 v27, 0xffff0000, v27
	v_pk_add_f32 v[20:21], v[20:21], v[28:29]
	v_pk_add_f32 v[22:23], v[22:23], v[24:25]
	v_pk_add_f32 v[24:25], v[16:17], v[30:31]
	v_pk_add_f32 v[26:27], v[18:19], v[26:27]
	v_mul_f32_e32 v28, v21, v21
	v_mul_f32_e32 v29, v23, v23
	v_cndmask_b32_e64 v16, v23, v27, s[0:1]
	v_mul_f32_e32 v30, v25, v25
	v_fmac_f32_e32 v28, v20, v20
	v_fmac_f32_e32 v29, v22, v22
	v_mul_f32_e32 v31, v27, v27
	v_mov_b32_dpp v49, v16 quad_perm:[1,0,3,2] row_mask:0xf bank_mask:0xf
	v_fmac_f32_e32 v30, v24, v24
	v_add_f32_e32 v16, v28, v29
	v_cndmask_b32_e64 v17, v22, v26, s[0:1]
	v_add_f32_e32 v16, v30, v16
	v_fmac_f32_e32 v31, v26, v26
	v_cndmask_b32_e64 v18, v21, v25, s[0:1]
	v_mov_b32_dpp v48, v17 quad_perm:[1,0,3,2] row_mask:0xf bank_mask:0xf
	v_add_f32_e32 v16, v31, v16
	v_cndmask_b32_e64 v19, v20, v24, s[0:1]
	v_mov_b32_dpp v39, v18 quad_perm:[1,0,3,2] row_mask:0xf bank_mask:0xf
	v_cndmask_b32_e64 v18, v48, v22, s[0:1]
	v_add_f32_e32 v22, v34, v16
	v_mov_b32_dpp v38, v19 quad_perm:[1,0,3,2] row_mask:0xf bank_mask:0xf
	v_cndmask_b32_e64 v19, v49, v23, s[0:1]
	ds_bpermute_b32 v23, v121, v22
	v_cndmask_b32_e64 v17, v39, v21, s[0:1]
	v_cndmask_b32_e64 v16, v38, v20, s[0:1]
	global_store_dwordx4 v[40:41], v[16:19], off offset:512
	v_cndmask_b32_e64 v21, v27, v49, s[0:1]
	v_cndmask_b32_e64 v20, v26, v48, s[0:1]
	s_waitcnt lgkmcnt(0)
	v_add_f32_e32 v16, v22, v23
	ds_bpermute_b32 v17, v120, v16
	v_cndmask_b32_e64 v19, v25, v39, s[0:1]
	v_cndmask_b32_e64 v18, v24, v38, s[0:1]
	global_store_dwordx4 v[42:43], v[18:21], off offset:512
	s_and_saveexec_b64 s[20:21], s[2:3]
	s_cbranch_execz .LBB0_2204
	v_lshl_add_u64 v[18:19], v[32:33], 2, s[12:13]
	s_waitcnt lgkmcnt(0)
	v_add_f32_e32 v16, v16, v17
	global_atomic_add_f32 v[18:19], v16, off
;     __device__ __forceinline__ void operator()(const f32x4 (&acc)[2][2][4][2], const Unit& u, int wr, int wc, int fr, int fq) const {
;     ...
;         const int row0 = u.pm * BM + wr * 64 + fr, col0 = u.pn * BM + wc * 32 + 8 * fq; const bool odd = (fr & 1) != 0;
; #pragma unroll
;         for (int ai = 0; ai < 2; ++ai)
; #pragma unroll
;             for (int m = 0; m < 4; ++m) {
;                 const int row = row0 + ai * HALF + m * 16; float s = 0.f;
;                 const size_t off = (size_t)row * DM + col0;
;                 const size_t offp = (size_t)(row - (odd ? 1 : 0)) * DM + col0 + (odd ? 4 : 0);
; #pragma unroll
;                 for (int bj = 0; bj < 2; ++bj) {
;                     f32x4 b0, b1;
;                     if constexpr (BASE_F32) { const f32x4 la = *(const GAS f32x4*)(basef + offp + bj * HALF), lb = *(const GAS f32x4*)(basef + offp + DM + bj * HALF);
;                         const f32x4 snd = odd ? la : lb; f32x4 rcv; rcv[0] = dpp_xor1(snd[0]); rcv[1] = dpp_xor1(snd[1]); rcv[2] = dpp_xor1(snd[2]); rcv[3] = dpp_xor1(snd[3]);
;                         b0 = odd ? rcv : la; b1 = odd ? lb : rcv; }
;                     else { const u32x4 bw = *(const u32x4*)(baseb + off + bj * HALF);
;                         b0 = (f32x4){bf_lo(bw.x), bf_hi(bw.x), bf_lo(bw.y), bf_hi(bw.y)}; b1 = (f32x4){bf_lo(bw.z), bf_hi(bw.z), bf_lo(bw.w), bf_hi(bw.w)}; }
;                     const f32x4 v0 = acc[ai][bj][m][0] + b0, v1 = acc[ai][bj][m][1] + b1;
;                     if constexpr (OUT_F32) { const f32x4 snd = odd ? v0 : v1; f32x4 rcv; rcv[0] = dpp_xor1(snd[0]); rcv[1] = dpp_xor1(snd[1]); rcv[2] = dpp_xor1(snd[2]); rcv[3] = dpp_xor1(snd[3]);
;                         *(f32x4*)(H + offp + bj * HALF) = odd ? rcv : v0; *(f32x4*)(H + offp + DM + bj * HALF) = odd ? v1 : rcv; }
;                     else { u32x4 w; w.x = cvt_pk_bf16(v0[0], v0[1]); w.y = cvt_pk_bf16(v0[2], v0[3]); w.z = cvt_pk_bf16(v1[0], v1[1]); w.w = cvt_pk_bf16(v1[2], v1[3]);
;                         *(u32x4*)(HB + off + bj * HALF) = w; }
;                     s += (v0[0] * v0[0] + v0[1] * v0[1]) + (v0[2] * v0[2] + v0[3] * v0[3]) + (v1[0] * v1[0] + v1[1] * v1[1]) + (v1[2] * v1[2] + v1[3] * v1[3]);
;                 }
;                 s += __shfl_xor(s, 16); s += __shfl_xor(s, 32);
;                 if (fq == 0) unsafeAtomicAdd(ssn + row, s);
;             }
.LBB0_2204:
	s_or_b64 exec, exec, s[20:21]
	v_add_u32_e32 v16, 0xb0, v148
	s_waitcnt lgkmcnt(0)
	v_ashrrev_i32_e32 v17, 31, v16
	v_readlane_b32 s20, v254, 25
	v_lshlrev_b64 v[18:19], 12, v[16:17]
	v_readlane_b32 s21, v254, 26
	v_sub_u32_e32 v24, v16, v153
	v_ashrrev_i32_e32 v25, 31, v24
	v_lshl_add_u64 v[18:19], s[20:21], 0, v[18:19]
	v_lshl_add_u64 v[22:23], v[146:147], 1, v[18:19]
	global_load_dwordx4 v[18:21], v[22:23], off
	v_readlane_b32 s20, v254, 7
	v_lshlrev_b64 v[24:25], 13, v[24:25]
	v_readlane_b32 s21, v254, 8
	s_nop 1
	v_lshl_add_u64 v[24:25], s[20:21], 0, v[24:25]
	v_lshl_add_u64 v[24:25], v[150:151], 2, v[24:25]
	v_add_co_u32_e32 v26, vcc, s35, v24
	v_readlane_b32 s22, v254, 9
	s_nop 0
	v_addc_co_u32_e32 v27, vcc, 0, v25, vcc
	v_readlane_b32 s23, v254, 10
	s_waitcnt vmcnt(0)
	v_lshlrev_b32_e32 v28, 16, v18
	v_and_b32_e32 v29, 0xffff0000, v18
	v_lshlrev_b32_e32 v18, 16, v19
	v_and_b32_e32 v19, 0xffff0000, v19
	v_lshlrev_b32_e32 v30, 16, v20
	v_and_b32_e32 v31, 0xffff0000, v20
	v_lshlrev_b32_e32 v20, 16, v21
	v_and_b32_e32 v21, 0xffff0000, v21
	v_pk_add_f32 v[28:29], v[12:13], v[28:29]
	v_pk_add_f32 v[18:19], v[14:15], v[18:19]
	v_pk_add_f32 v[30:31], v[8:9], v[30:31]
	v_pk_add_f32 v[20:21], v[10:11], v[20:21]
	v_cndmask_b32_e64 v10, v29, v31, s[0:1]
	v_cndmask_b32_e64 v8, v19, v21, s[0:1]
	v_cndmask_b32_e64 v9, v18, v20, s[0:1]
	v_cndmask_b32_e64 v11, v28, v30, s[0:1]
	v_mov_b32_dpp v33, v10 quad_perm:[1,0,3,2] row_mask:0xf bank_mask:0xf
	v_mov_b32_dpp v34, v9 quad_perm:[1,0,3,2] row_mask:0xf bank_mask:0xf
	v_mov_b32_dpp v32, v11 quad_perm:[1,0,3,2] row_mask:0xf bank_mask:0xf
	v_mov_b32_dpp v35, v8 quad_perm:[1,0,3,2] row_mask:0xf bank_mask:0xf
	v_cndmask_b32_e64 v11, v35, v19, s[0:1]
	v_cndmask_b32_e64 v10, v34, v18, s[0:1]
	v_cndmask_b32_e64 v9, v33, v29, s[0:1]
	v_cndmask_b32_e64 v8, v32, v28, s[0:1]
	v_cndmask_b32_e64 v15, v21, v35, s[0:1]
	v_cndmask_b32_e64 v14, v20, v34, s[0:1]
	v_cndmask_b32_e64 v13, v31, v33, s[0:1]
	v_cndmask_b32_e64 v12, v30, v32, s[0:1]
	global_store_dwordx4 v[24:25], v[8:11], off
	global_store_dwordx4 v[26:27], v[12:15], off
	global_load_dwordx4 v[8:11], v[22:23], off offset:256
	s_nop 1
	v_mul_f32_e32 v12, v29, v29
	v_mul_f32_e32 v13, v19, v19
	v_mul_f32_e32 v14, v31, v31
	v_fmac_f32_e32 v12, v28, v28
	v_fmac_f32_e32 v13, v18, v18
	v_mul_f32_e32 v15, v21, v21
	v_fmac_f32_e32 v14, v30, v30
	v_add_f32_e32 v12, v12, v13
	v_fmac_f32_e32 v15, v20, v20
	v_add_f32_e32 v12, v14, v12
	v_add_f32_e32 v18, v15, v12
	s_waitcnt vmcnt(0)
	v_lshlrev_b32_e32 v12, 16, v8
	v_and_b32_e32 v13, 0xffff0000, v8
	v_lshlrev_b32_e32 v8, 16, v9
	v_and_b32_e32 v9, 0xffff0000, v9
	v_lshlrev_b32_e32 v14, 16, v10
	v_and_b32_e32 v15, 0xffff0000, v10
	v_lshlrev_b32_e32 v10, 16, v11
	v_and_b32_e32 v11, 0xffff0000, v11
	v_pk_add_f32 v[4:5], v[4:5], v[12:13]
	v_pk_add_f32 v[6:7], v[6:7], v[8:9]
	v_pk_add_f32 v[8:9], v[0:1], v[14:15]
	v_pk_add_f32 v[10:11], v[2:3], v[10:11]
	v_mul_f32_e32 v12, v5, v5
	v_mul_f32_e32 v13, v7, v7
	v_cndmask_b32_e64 v0, v7, v11, s[0:1]
	v_mul_f32_e32 v14, v9, v9
	v_fmac_f32_e32 v12, v4, v4
	v_fmac_f32_e32 v13, v6, v6
	v_mul_f32_e32 v15, v11, v11
	v_mov_b32_dpp v33, v0 quad_perm:[1,0,3,2] row_mask:0xf bank_mask:0xf
	v_fmac_f32_e32 v14, v8, v8
	v_add_f32_e32 v0, v12, v13
	v_cndmask_b32_e64 v1, v6, v10, s[0:1]
	v_add_f32_e32 v0, v14, v0
	v_fmac_f32_e32 v15, v10, v10
	v_cndmask_b32_e64 v2, v5, v9, s[0:1]
	v_mov_b32_dpp v32, v1 quad_perm:[1,0,3,2] row_mask:0xf bank_mask:0xf
	v_add_f32_e32 v0, v15, v0
	v_cndmask_b32_e64 v3, v4, v8, s[0:1]
	v_mov_b32_dpp v23, v2 quad_perm:[1,0,3,2] row_mask:0xf bank_mask:0xf
	v_cndmask_b32_e64 v2, v32, v6, s[0:1]
	v_add_f32_e32 v6, v18, v0
	v_mov_b32_dpp v22, v3 quad_perm:[1,0,3,2] row_mask:0xf bank_mask:0xf
	v_cndmask_b32_e64 v3, v33, v7, s[0:1]
	ds_bpermute_b32 v7, v121, v6
	v_cndmask_b32_e64 v1, v23, v5, s[0:1]
	v_cndmask_b32_e64 v0, v22, v4, s[0:1]
	global_store_dwordx4 v[24:25], v[0:3], off offset:512
	v_cndmask_b32_e64 v5, v11, v33, s[0:1]
	v_cndmask_b32_e64 v4, v10, v32, s[0:1]
	s_waitcnt lgkmcnt(0)
	v_add_f32_e32 v0, v6, v7
	ds_bpermute_b32 v1, v120, v0
	v_cndmask_b32_e64 v3, v9, v23, s[0:1]
	v_cndmask_b32_e64 v2, v8, v22, s[0:1]
	global_store_dwordx4 v[26:27], v[2:5], off offset:512
	s_and_saveexec_b64 s[20:21], s[2:3]
	s_cbranch_execz .LBB0_2206
	v_lshl_add_u64 v[2:3], v[16:17], 2, s[12:13]
	s_waitcnt lgkmcnt(0)
	v_add_f32_e32 v0, v0, v1
	global_atomic_add_f32 v[2:3], v0, off
